# GEMM K-loops: leading wave half skips the pre-barrier lgkmcnt(0) of its load segments (its post-barrier wait already orders those reads before any restage)
# baseline (speedup 1.0000x reference)
; #define PG8_STAGE(bufoff, gbase, voff) do { _Pragma("unroll") for (int _i = 0; _i < 2; ++_i) \
;         __builtin_amdgcn_global_load_lds((const unsigned*)((const char*)(gbase) + (voff)[_i]), (PG8_LAS unsigned*)(lds + (bufoff) + ldsw + _i * 8192), 16, 0, 0); } while (0)
; #define PG8_LDA(dst, b, h) do { _Pragma("unroll") for (int m = 0; m < 4; ++m) _Pragma("unroll") for (int k = 0; k < 2; ++k) dst[m][k] = *(const PG8_LAS bf16x8*)(lds + PG8_SA(b, h) + aoff + m * 2048 + k * 1024); } while (0)
; #define PG8_LDB(dst, b, h) do { _Pragma("unroll") for (int n = 0; n < 2; ++n) _Pragma("unroll") for (int k = 0; k < 2; ++k) dst[n][k] = *(const PG8_LAS bf16x8*)(lds + PG8_SB(b, h) + boff + n * 2048 + k * 1024); } while (0)
; #define PG8_MMA(ai, bj, At, Bt) do { __builtin_amdgcn_s_setprio(1); _Pragma("unroll") for (int m = 0; m < 4; ++m) _Pragma("unroll") for (int n = 0; n < 2; ++n) _Pragma("unroll") for (int k = 0; k < 2; ++k) \
;         acc[ai][bj][m][n] = mma16<F16>(Bt[n][k], At[m][k], acc[ai][bj][m][n]); __builtin_amdgcn_s_setprio(0); } while (0)
; #define PG8_WAIT_V(n) asm volatile("s_waitcnt vmcnt(" #n ")" ::: "memory")
; #define PG8_WAIT_L(n) asm volatile("s_waitcnt lgkmcnt(" #n ")" ::: "memory")
; #define PG8_BAR __builtin_amdgcn_s_barrier()
; #define PG8_SCHED __builtin_amdgcn_sched_barrier(0)
; template <class Epi, class Sched, bool ALIGN_EPI = false, bool SP2 = false, bool F16 = false>
; __device__ __forceinline__ void gemm_phase(PG8_LAS unsigned char* lds, const Gemm g, const Sched& S, const Epi& E, const int wid_in) {
;     ...
;             PG8_LDB(B0, 0, 0); PG8_LDB(B1, 0, 1); PG8_SCHED; PG8_LDA(At, 0, 0); PG8_STAGE(PG8_SA(1, 1), a1 + hstep, voffA);
;             PG8_WAIT_V(8); PG8_WAIT_L(0); PG8_BAR; PG8_MMA(0, 0, At, B0); PG8_MMA(0, 1, At, B1); PG8_BAR; PG8_SCHED;
;             PG8_LDA(At, 0, 1); PG8_STAGE(PG8_SB(0, 0), b2, voffB); PG8_STAGE(PG8_SB(0, 1), b2 + hstep, voffB); PG8_STAGE(PG8_SA(0, 0), a2, voffA);
;             PG8_WAIT_V(8); PG8_WAIT_L(0); PG8_BAR; PG8_MMA(1, 0, At, B0); PG8_MMA(1, 1, At, B1); PG8_BAR; PG8_SCHED;
.LBB0_224:
	ds_read_b128 v[128:131], v184
	ds_read_b128 v[132:135], v184 offset:1024
	ds_read_b128 v[136:139], v184 offset:2048
	ds_read_b128 v[140:143], v184 offset:3072
	ds_read_b128 v[144:147], v185
	ds_read_b128 v[148:151], v185 offset:1024
	ds_read_b128 v[152:155], v185 offset:2048
	ds_read_b128 v[174:177], v185 offset:3072
	s_add_u32 s58, s56, 0xfffc0080
	s_addc_u32 s59, s57, -1
	s_cmp_eq_u32 s62, 12
	s_cselect_b32 s61, s9, s59
	s_cselect_b32 s60, s21, s58
	s_cselect_b32 s59, s42, s51
	s_cselect_b32 s58, s43, s49
	v_lshl_add_u64 v[178:179], s[56:57], 0, v[166:167]
	s_add_i32 m0, s83, 0xc000
	ds_read_b128 v[190:193], v186
	ds_read_b128 v[194:197], v186 offset:1024
	ds_read_b128 v[198:201], v186 offset:2048
	ds_read_b128 v[202:205], v186 offset:3072
	ds_read_b128 v[206:209], v186 offset:4096
	ds_read_b128 v[210:213], v186 offset:5120
	ds_read_b128 v[214:217], v186 offset:6144
	ds_read_b128 v[218:221], v186 offset:7168
	global_load_lds_dwordx4 v[178:179], off
	v_lshl_add_u64 v[178:179], s[56:57], 0, v[168:169]
	s_add_i32 m0, s83, 0xe000
	s_nop 0
	global_load_lds_dwordx4 v[178:179], off
	s_waitcnt vmcnt(8)
	s_cmp_lt_u32 s3, 4
	s_cbranch_scc1 .Lgls_0
	s_waitcnt lgkmcnt(0)
.Lgls_0:
	s_barrier
	s_setprio 1
	s_waitcnt lgkmcnt(0)
	v_mfma_f32_16x16x32_f16 v[124:127], v[128:131], v[190:193], v[124:127]
	v_mfma_f32_16x16x32_f16 v[120:123], v[136:139], v[190:193], v[120:123]
	v_mfma_f32_16x16x32_f16 v[108:111], v[128:131], v[198:201], v[108:111]
	v_mfma_f32_16x16x32_f16 v[104:107], v[136:139], v[198:201], v[104:107]
	v_mfma_f32_16x16x32_f16 v[92:95], v[128:131], v[206:209], v[92:95]
	v_mfma_f32_16x16x32_f16 v[88:91], v[136:139], v[206:209], v[88:91]
	v_mfma_f32_16x16x32_f16 v[76:79], v[128:131], v[214:217], v[76:79]
	v_mfma_f32_16x16x32_f16 v[72:75], v[136:139], v[214:217], v[72:75]
	v_mfma_f32_16x16x32_f16 v[124:127], v[132:135], v[194:197], v[124:127]
	v_mfma_f32_16x16x32_f16 v[120:123], v[140:143], v[194:197], v[120:123]
	v_mfma_f32_16x16x32_f16 v[108:111], v[132:135], v[202:205], v[108:111]
	v_mfma_f32_16x16x32_f16 v[104:107], v[140:143], v[202:205], v[104:107]
	v_mfma_f32_16x16x32_f16 v[92:95], v[132:135], v[210:213], v[92:95]
	v_mfma_f32_16x16x32_f16 v[88:91], v[140:143], v[210:213], v[88:91]
	v_mfma_f32_16x16x32_f16 v[76:79], v[132:135], v[218:221], v[76:79]
	v_mfma_f32_16x16x32_f16 v[72:75], v[140:143], v[218:221], v[72:75]
	s_setprio 0
	s_setprio 1
	v_mfma_f32_16x16x32_f16 v[116:119], v[144:147], v[190:193], v[116:119]
	v_mfma_f32_16x16x32_f16 v[112:115], v[152:155], v[190:193], v[112:115]
	v_mfma_f32_16x16x32_f16 v[100:103], v[144:147], v[198:201], v[100:103]
	v_mfma_f32_16x16x32_f16 v[96:99], v[152:155], v[198:201], v[96:99]
	v_mfma_f32_16x16x32_f16 v[84:87], v[144:147], v[206:209], v[84:87]
	v_mfma_f32_16x16x32_f16 v[80:83], v[152:155], v[206:209], v[80:83]
	v_mfma_f32_16x16x32_f16 v[68:71], v[144:147], v[214:217], v[68:71]
	v_mfma_f32_16x16x32_f16 v[64:67], v[152:155], v[214:217], v[64:67]
	v_mfma_f32_16x16x32_f16 v[116:119], v[148:151], v[194:197], v[116:119]
	v_mfma_f32_16x16x32_f16 v[112:115], v[174:177], v[194:197], v[112:115]
	v_mfma_f32_16x16x32_f16 v[100:103], v[148:151], v[202:205], v[100:103]
	v_mfma_f32_16x16x32_f16 v[96:99], v[174:177], v[202:205], v[96:99]
	v_mfma_f32_16x16x32_f16 v[84:87], v[148:151], v[210:213], v[84:87]
	v_mfma_f32_16x16x32_f16 v[80:83], v[174:177], v[210:213], v[80:83]
	v_mfma_f32_16x16x32_f16 v[68:71], v[148:151], v[218:221], v[68:71]
	v_mfma_f32_16x16x32_f16 v[64:67], v[174:177], v[218:221], v[64:67]
	s_setprio 0
	s_barrier
	s_add_i32 s63, s40, s68
	v_lshl_add_u64 v[178:179], s[58:59], 0, v[158:159]
	s_mov_b32 m0, s63
	ds_read_b128 v[190:193], v186 offset:16384
	ds_read_b128 v[194:197], v186 offset:17408
	ds_read_b128 v[198:201], v186 offset:18432
	ds_read_b128 v[202:205], v186 offset:19456
	ds_read_b128 v[206:209], v186 offset:20480
	ds_read_b128 v[210:213], v186 offset:21504
	ds_read_b128 v[214:217], v186 offset:22528
	ds_read_b128 v[218:221], v186 offset:23552
	global_load_lds_dwordx4 v[178:179], off
	s_add_i32 m0, s63, 0x2000
	s_add_u32 s64, s58, 0x40000
	v_lshl_add_u64 v[222:223], s[58:59], 0, v[162:163]
	s_addc_u32 s65, s59, 0
	s_add_i32 s63, s41, s68
	global_load_lds_dwordx4 v[222:223], off
	v_lshl_add_u64 v[224:225], s[64:65], 0, v[158:159]
	s_mov_b32 m0, s63
	v_lshl_add_u64 v[226:227], s[60:61], 0, v[160:161]
	global_load_lds_dwordx4 v[224:225], off
	v_lshl_add_u64 v[224:225], s[64:65], 0, v[162:163]
	s_add_i32 m0, s63, 0x2000
	s_nop 0
	global_load_lds_dwordx4 v[224:225], off
	v_lshl_add_u64 v[224:225], s[60:61], 0, v[156:157]
	s_mov_b32 m0, s83
	s_nop 0
	global_load_lds_dwordx4 v[224:225], off
	s_mov_b32 m0, s84
	s_nop 0
	global_load_lds_dwordx4 v[226:227], off
	s_waitcnt vmcnt(8)
	s_cmp_lt_u32 s3, 4
	s_cbranch_scc1 .Lgls_1
	s_waitcnt lgkmcnt(0)
; #define PG8_STAGE(bufoff, gbase, voff) do { _Pragma("unroll") for (int _i = 0; _i < 2; ++_i) \
;         __builtin_amdgcn_global_load_lds((const unsigned*)((const char*)(gbase) + (voff)[_i]), (PG8_LAS unsigned*)(lds + (bufoff) + ldsw + _i * 8192), 16, 0, 0); } while (0)
; #define PG8_LDA(dst, b, h) do { _Pragma("unroll") for (int m = 0; m < 4; ++m) _Pragma("unroll") for (int k = 0; k < 2; ++k) dst[m][k] = *(const PG8_LAS bf16x8*)(lds + PG8_SA(b, h) + aoff + m * 2048 + k * 1024); } while (0)
; #define PG8_LDB(dst, b, h) do { _Pragma("unroll") for (int n = 0; n < 2; ++n) _Pragma("unroll") for (int k = 0; k < 2; ++k) dst[n][k] = *(const PG8_LAS bf16x8*)(lds + PG8_SB(b, h) + boff + n * 2048 + k * 1024); } while (0)
; #define PG8_MMA(ai, bj, At, Bt) do { __builtin_amdgcn_s_setprio(1); _Pragma("unroll") for (int m = 0; m < 4; ++m) _Pragma("unroll") for (int n = 0; n < 2; ++n) _Pragma("unroll") for (int k = 0; k < 2; ++k) \
;         acc[ai][bj][m][n] = mma16<F16>(Bt[n][k], At[m][k], acc[ai][bj][m][n]); __builtin_amdgcn_s_setprio(0); } while (0)
; #define PG8_WAIT_V(n) asm volatile("s_waitcnt vmcnt(" #n ")" ::: "memory")
; #define PG8_WAIT_L(n) asm volatile("s_waitcnt lgkmcnt(" #n ")" ::: "memory")
; #define PG8_BAR __builtin_amdgcn_s_barrier()
; #define PG8_SCHED __builtin_amdgcn_sched_barrier(0)
; template <class Epi, class Sched, bool ALIGN_EPI = false, bool SP2 = false, bool F16 = false>
; __device__ __forceinline__ void gemm_phase(PG8_LAS unsigned char* lds, const Gemm g, const Sched& S, const Epi& E, const int wid_in) {
;     ...
;             PG8_WAIT_V(8); PG8_WAIT_L(0); PG8_BAR; PG8_MMA(1, 0, At, B0); PG8_MMA(1, 1, At, B1); PG8_BAR; PG8_SCHED;
;             PG8_LDB(B0, 1, 0); PG8_LDB(B1, 1, 1); PG8_SCHED; PG8_LDA(At, 1, 0); PG8_STAGE(PG8_SA(0, 1), a2 + hstep, voffA);
;             PG8_WAIT_V(8); PG8_WAIT_L(0); PG8_BAR; PG8_MMA(0, 0, At, B0); PG8_MMA(0, 1, At, B1); PG8_BAR; PG8_SCHED;
.Lgls_1:
	s_barrier
	s_setprio 1
	s_waitcnt lgkmcnt(0)
	v_mfma_f32_16x16x32_f16 v[60:63], v[128:131], v[190:193], v[60:63]
	v_mfma_f32_16x16x32_f16 v[56:59], v[136:139], v[190:193], v[56:59]
	v_mfma_f32_16x16x32_f16 v[44:47], v[128:131], v[198:201], v[44:47]
	v_mfma_f32_16x16x32_f16 v[40:43], v[136:139], v[198:201], v[40:43]
	v_mfma_f32_16x16x32_f16 v[28:31], v[128:131], v[206:209], v[28:31]
	v_mfma_f32_16x16x32_f16 v[24:27], v[136:139], v[206:209], v[24:27]
	v_mfma_f32_16x16x32_f16 v[12:15], v[128:131], v[214:217], v[12:15]
	v_mfma_f32_16x16x32_f16 v[8:11], v[136:139], v[214:217], v[8:11]
	v_mfma_f32_16x16x32_f16 v[60:63], v[132:135], v[194:197], v[60:63]
	v_mfma_f32_16x16x32_f16 v[56:59], v[140:143], v[194:197], v[56:59]
	v_mfma_f32_16x16x32_f16 v[44:47], v[132:135], v[202:205], v[44:47]
	v_mfma_f32_16x16x32_f16 v[40:43], v[140:143], v[202:205], v[40:43]
	v_mfma_f32_16x16x32_f16 v[28:31], v[132:135], v[210:213], v[28:31]
	v_mfma_f32_16x16x32_f16 v[24:27], v[140:143], v[210:213], v[24:27]
	v_mfma_f32_16x16x32_f16 v[12:15], v[132:135], v[218:221], v[12:15]
	v_mfma_f32_16x16x32_f16 v[8:11], v[140:143], v[218:221], v[8:11]
	s_setprio 0
	s_setprio 1
	v_mfma_f32_16x16x32_f16 v[52:55], v[144:147], v[190:193], v[52:55]
	v_mfma_f32_16x16x32_f16 v[48:51], v[152:155], v[190:193], v[48:51]
	v_mfma_f32_16x16x32_f16 v[36:39], v[144:147], v[198:201], v[36:39]
	v_mfma_f32_16x16x32_f16 v[32:35], v[152:155], v[198:201], v[32:35]
	v_mfma_f32_16x16x32_f16 v[20:23], v[144:147], v[206:209], v[20:23]
	v_mfma_f32_16x16x32_f16 v[16:19], v[152:155], v[206:209], v[16:19]
	v_mfma_f32_16x16x32_f16 v[4:7], v[144:147], v[214:217], v[4:7]
	v_mfma_f32_16x16x32_f16 v[0:3], v[152:155], v[214:217], v[0:3]
	v_mfma_f32_16x16x32_f16 v[52:55], v[148:151], v[194:197], v[52:55]
	v_mfma_f32_16x16x32_f16 v[48:51], v[174:177], v[194:197], v[48:51]
	v_mfma_f32_16x16x32_f16 v[36:39], v[148:151], v[202:205], v[36:39]
	v_mfma_f32_16x16x32_f16 v[32:35], v[174:177], v[202:205], v[32:35]
	v_mfma_f32_16x16x32_f16 v[20:23], v[148:151], v[210:213], v[20:23]
	v_mfma_f32_16x16x32_f16 v[16:19], v[174:177], v[210:213], v[16:19]
	v_mfma_f32_16x16x32_f16 v[4:7], v[148:151], v[218:221], v[4:7]
	v_mfma_f32_16x16x32_f16 v[0:3], v[174:177], v[218:221], v[0:3]
	s_setprio 0
	s_barrier
	s_add_i32 s63, 0, 0x18000
	s_add_i32 s64, 0, 0x1c000
	v_add_u32_e32 v140, s63, v183
	v_add_u32_e32 v165, s64, v183
	ds_read_b128 v[128:131], v140
	ds_read_b128 v[132:135], v140 offset:1024
	ds_read_b128 v[136:139], v140 offset:2048
	ds_read_b128 v[140:143], v140 offset:3072
	ds_read_b128 v[144:147], v165
	ds_read_b128 v[148:151], v165 offset:1024
	ds_read_b128 v[152:155], v165 offset:2048
	ds_read_b128 v[174:177], v165 offset:3072
	s_add_u32 s60, s60, 0x40000
	s_addc_u32 s61, s61, 0
	s_mov_b32 m0, s85
	v_lshl_add_u64 v[228:229], s[60:61], 0, v[156:157]
	ds_read_b128 v[190:193], v186 offset:32768
	ds_read_b128 v[194:197], v186 offset:33792
	ds_read_b128 v[198:201], v186 offset:34816
	ds_read_b128 v[202:205], v186 offset:35840
	ds_read_b128 v[206:209], v186 offset:36864
	ds_read_b128 v[210:213], v186 offset:37888
	ds_read_b128 v[214:217], v186 offset:38912
	ds_read_b128 v[218:221], v186 offset:39936
	global_load_lds_dwordx4 v[228:229], off
	v_lshl_add_u64 v[228:229], s[60:61], 0, v[160:161]
	s_mov_b32 m0, s86
	s_nop 0
	global_load_lds_dwordx4 v[228:229], off
	s_waitcnt vmcnt(8)
	s_cmp_lt_u32 s3, 4
	s_cbranch_scc1 .Lgls_2
	s_waitcnt lgkmcnt(0)
; #define PG8_STAGE(bufoff, gbase, voff) do { _Pragma("unroll") for (int _i = 0; _i < 2; ++_i) \
;         __builtin_amdgcn_global_load_lds((const unsigned*)((const char*)(gbase) + (voff)[_i]), (PG8_LAS unsigned*)(lds + (bufoff) + ldsw + _i * 8192), 16, 0, 0); } while (0)
; #define PG8_LDA(dst, b, h) do { _Pragma("unroll") for (int m = 0; m < 4; ++m) _Pragma("unroll") for (int k = 0; k < 2; ++k) dst[m][k] = *(const PG8_LAS bf16x8*)(lds + PG8_SA(b, h) + aoff + m * 2048 + k * 1024); } while (0)
; #define PG8_MMA(ai, bj, At, Bt) do { __builtin_amdgcn_s_setprio(1); _Pragma("unroll") for (int m = 0; m < 4; ++m) _Pragma("unroll") for (int n = 0; n < 2; ++n) _Pragma("unroll") for (int k = 0; k < 2; ++k) \
;         acc[ai][bj][m][n] = mma16<F16>(Bt[n][k], At[m][k], acc[ai][bj][m][n]); __builtin_amdgcn_s_setprio(0); } while (0)
; #define PG8_WAIT_V(n) asm volatile("s_waitcnt vmcnt(" #n ")" ::: "memory")
; #define PG8_WAIT_L(n) asm volatile("s_waitcnt lgkmcnt(" #n ")" ::: "memory")
; #define PG8_BAR __builtin_amdgcn_s_barrier()
; #define PG8_SCHED __builtin_amdgcn_sched_barrier(0)
; template <class Epi, class Sched, bool ALIGN_EPI = false, bool SP2 = false, bool F16 = false>
; __device__ __forceinline__ void gemm_phase(PG8_LAS unsigned char* lds, const Gemm g, const Sched& S, const Epi& E, const int wid_in) {
;     ...
;             PG8_WAIT_V(8); PG8_WAIT_L(0); PG8_BAR; PG8_MMA(0, 0, At, B0); PG8_MMA(0, 1, At, B1); PG8_BAR; PG8_SCHED;
;             PG8_LDA(At, 1, 1); PG8_STAGE(PG8_SB(1, 0), b3, voffB); PG8_STAGE(PG8_SB(1, 1), b3 + hstep, voffB); PG8_STAGE(PG8_SA(1, 0), a3, voffA);
;             PG8_WAIT_V(8); PG8_WAIT_L(0); PG8_BAR; PG8_MMA(1, 0, At, B0); PG8_MMA(1, 1, At, B1); PG8_BAR; PG8_SCHED;
.Lgls_2:
	s_barrier
	s_setprio 1
	s_waitcnt lgkmcnt(0)
	v_mfma_f32_16x16x32_f16 v[124:127], v[128:131], v[190:193], v[124:127]
	v_mfma_f32_16x16x32_f16 v[120:123], v[136:139], v[190:193], v[120:123]
	v_mfma_f32_16x16x32_f16 v[108:111], v[128:131], v[198:201], v[108:111]
	v_mfma_f32_16x16x32_f16 v[104:107], v[136:139], v[198:201], v[104:107]
	v_mfma_f32_16x16x32_f16 v[92:95], v[128:131], v[206:209], v[92:95]
	v_mfma_f32_16x16x32_f16 v[88:91], v[136:139], v[206:209], v[88:91]
	v_mfma_f32_16x16x32_f16 v[76:79], v[128:131], v[214:217], v[76:79]
	v_mfma_f32_16x16x32_f16 v[72:75], v[136:139], v[214:217], v[72:75]
	v_mfma_f32_16x16x32_f16 v[124:127], v[132:135], v[194:197], v[124:127]
	v_mfma_f32_16x16x32_f16 v[120:123], v[140:143], v[194:197], v[120:123]
	v_mfma_f32_16x16x32_f16 v[108:111], v[132:135], v[202:205], v[108:111]
	v_mfma_f32_16x16x32_f16 v[104:107], v[140:143], v[202:205], v[104:107]
	v_mfma_f32_16x16x32_f16 v[92:95], v[132:135], v[210:213], v[92:95]
	v_mfma_f32_16x16x32_f16 v[88:91], v[140:143], v[210:213], v[88:91]
	v_mfma_f32_16x16x32_f16 v[76:79], v[132:135], v[218:221], v[76:79]
	v_mfma_f32_16x16x32_f16 v[72:75], v[140:143], v[218:221], v[72:75]
	s_setprio 0
	s_setprio 1
	v_mfma_f32_16x16x32_f16 v[116:119], v[144:147], v[190:193], v[116:119]
	v_mfma_f32_16x16x32_f16 v[112:115], v[152:155], v[190:193], v[112:115]
	v_mfma_f32_16x16x32_f16 v[100:103], v[144:147], v[198:201], v[100:103]
	v_mfma_f32_16x16x32_f16 v[96:99], v[152:155], v[198:201], v[96:99]
	v_mfma_f32_16x16x32_f16 v[84:87], v[144:147], v[206:209], v[84:87]
	v_mfma_f32_16x16x32_f16 v[80:83], v[152:155], v[206:209], v[80:83]
	v_mfma_f32_16x16x32_f16 v[68:71], v[144:147], v[214:217], v[68:71]
	v_mfma_f32_16x16x32_f16 v[64:67], v[152:155], v[214:217], v[64:67]
	v_mfma_f32_16x16x32_f16 v[116:119], v[148:151], v[194:197], v[116:119]
	v_mfma_f32_16x16x32_f16 v[112:115], v[174:177], v[194:197], v[112:115]
	v_mfma_f32_16x16x32_f16 v[100:103], v[148:151], v[202:205], v[100:103]
	v_mfma_f32_16x16x32_f16 v[96:99], v[174:177], v[202:205], v[96:99]
	v_mfma_f32_16x16x32_f16 v[84:87], v[148:151], v[210:213], v[84:87]
	v_mfma_f32_16x16x32_f16 v[80:83], v[174:177], v[210:213], v[80:83]
	v_mfma_f32_16x16x32_f16 v[68:71], v[148:151], v[218:221], v[68:71]
	v_mfma_f32_16x16x32_f16 v[64:67], v[174:177], v[218:221], v[64:67]
	s_setprio 0
	s_barrier
	s_add_i32 s60, s63, s68
	v_lshl_add_u64 v[178:179], v[178:179], 0, s[24:25]
	s_mov_b32 m0, s60
	ds_read_b128 v[190:193], v186 offset:49152
	ds_read_b128 v[194:197], v186 offset:50176
	ds_read_b128 v[198:201], v186 offset:51200
	ds_read_b128 v[202:205], v186 offset:52224
	ds_read_b128 v[206:209], v186 offset:53248
	ds_read_b128 v[210:213], v186 offset:54272
	ds_read_b128 v[214:217], v186 offset:55296
	ds_read_b128 v[218:221], v186 offset:56320
	global_load_lds_dwordx4 v[178:179], off
	s_add_i32 m0, s60, 0x2000
	s_add_u32 s58, s58, 0x40080
	v_lshl_add_u64 v[178:179], v[222:223], 0, s[24:25]
	s_addc_u32 s59, s59, 0
	s_add_i32 s60, s64, s68
	global_load_lds_dwordx4 v[178:179], off
	v_lshl_add_u64 v[178:179], s[58:59], 0, v[158:159]
	s_mov_b32 m0, s60
	s_nop 0
	global_load_lds_dwordx4 v[178:179], off
	v_lshl_add_u64 v[178:179], s[58:59], 0, v[162:163]
	s_add_i32 m0, s60, 0x2000
	s_nop 0
	global_load_lds_dwordx4 v[178:179], off
	v_lshl_add_u64 v[178:179], v[224:225], 0, s[24:25]
	s_mov_b32 m0, s90
	s_nop 0
	global_load_lds_dwordx4 v[178:179], off
	v_lshl_add_u64 v[178:179], v[226:227], 0, s[24:25]
	s_mov_b32 m0, s91
	s_nop 0
	global_load_lds_dwordx4 v[178:179], off
	s_waitcnt vmcnt(8)
	s_cmp_lt_u32 s3, 4
	s_cbranch_scc1 .Lgls_3
	s_waitcnt lgkmcnt(0)
.Lgls_3:
	s_barrier
	s_setprio 1
	s_waitcnt lgkmcnt(0)
	v_mfma_f32_16x16x32_f16 v[60:63], v[128:131], v[190:193], v[60:63]
	v_mfma_f32_16x16x32_f16 v[56:59], v[136:139], v[190:193], v[56:59]
	v_mfma_f32_16x16x32_f16 v[44:47], v[128:131], v[198:201], v[44:47]
	v_mfma_f32_16x16x32_f16 v[40:43], v[136:139], v[198:201], v[40:43]
	v_mfma_f32_16x16x32_f16 v[28:31], v[128:131], v[206:209], v[28:31]
	v_mfma_f32_16x16x32_f16 v[24:27], v[136:139], v[206:209], v[24:27]
	v_mfma_f32_16x16x32_f16 v[12:15], v[128:131], v[214:217], v[12:15]
	v_mfma_f32_16x16x32_f16 v[8:11], v[136:139], v[214:217], v[8:11]
	v_mfma_f32_16x16x32_f16 v[60:63], v[132:135], v[194:197], v[60:63]
	v_mfma_f32_16x16x32_f16 v[56:59], v[140:143], v[194:197], v[56:59]
	v_mfma_f32_16x16x32_f16 v[44:47], v[132:135], v[202:205], v[44:47]
	v_mfma_f32_16x16x32_f16 v[40:43], v[140:143], v[202:205], v[40:43]
	v_mfma_f32_16x16x32_f16 v[28:31], v[132:135], v[210:213], v[28:31]
	v_mfma_f32_16x16x32_f16 v[24:27], v[140:143], v[210:213], v[24:27]
	v_mfma_f32_16x16x32_f16 v[12:15], v[132:135], v[218:221], v[12:15]
	v_mfma_f32_16x16x32_f16 v[8:11], v[140:143], v[218:221], v[8:11]
	s_setprio 0
	s_setprio 1
	v_mfma_f32_16x16x32_f16 v[52:55], v[144:147], v[190:193], v[52:55]
	v_mfma_f32_16x16x32_f16 v[48:51], v[152:155], v[190:193], v[48:51]
	v_mfma_f32_16x16x32_f16 v[36:39], v[144:147], v[198:201], v[36:39]
	v_mfma_f32_16x16x32_f16 v[32:35], v[152:155], v[198:201], v[32:35]
	v_mfma_f32_16x16x32_f16 v[20:23], v[144:147], v[206:209], v[20:23]
	v_mfma_f32_16x16x32_f16 v[16:19], v[152:155], v[206:209], v[16:19]
	v_mfma_f32_16x16x32_f16 v[4:7], v[144:147], v[214:217], v[4:7]
	v_mfma_f32_16x16x32_f16 v[0:3], v[152:155], v[214:217], v[0:3]
	v_mfma_f32_16x16x32_f16 v[52:55], v[148:151], v[194:197], v[52:55]
	v_mfma_f32_16x16x32_f16 v[48:51], v[174:177], v[194:197], v[48:51]
	v_mfma_f32_16x16x32_f16 v[36:39], v[148:151], v[202:205], v[36:39]
	v_mfma_f32_16x16x32_f16 v[32:35], v[174:177], v[202:205], v[32:35]
	v_mfma_f32_16x16x32_f16 v[20:23], v[148:151], v[210:213], v[20:23]
	v_mfma_f32_16x16x32_f16 v[16:19], v[174:177], v[210:213], v[16:19]
	v_mfma_f32_16x16x32_f16 v[4:7], v[148:151], v[218:221], v[4:7]
	v_mfma_f32_16x16x32_f16 v[0:3], v[174:177], v[218:221], v[0:3]
	s_setprio 0
	s_barrier
	s_add_i32 s62, s62, 2
	s_add_u32 s56, s56, 0x100
	s_addc_u32 s57, s57, 0
	s_add_u32 s49, s49, 0x100
	s_addc_u32 s51, s51, 0
	s_cmp_gt_u32 s62, 13
	s_cbranch_scc0 .LBB0_224
	s_and_b64 vcc, exec, s[26:27]
	s_cbranch_vccz .LBB0_227
	s_barrier

; #define PG8_STAGE(bufoff, gbase, voff) do { _Pragma("unroll") for (int _i = 0; _i < 2; ++_i) \
;         __builtin_amdgcn_global_load_lds((const unsigned*)((const char*)(gbase) + (voff)[_i]), (PG8_LAS unsigned*)(lds + (bufoff) + ldsw + _i * 8192), 16, 0, 0); } while (0)
; #define PG8_LDA(dst, b, h) do { _Pragma("unroll") for (int m = 0; m < 4; ++m) _Pragma("unroll") for (int k = 0; k < 2; ++k) dst[m][k] = *(const PG8_LAS bf16x8*)(lds + PG8_SA(b, h) + aoff + m * 2048 + k * 1024); } while (0)
; #define PG8_LDB(dst, b, h) do { _Pragma("unroll") for (int n = 0; n < 2; ++n) _Pragma("unroll") for (int k = 0; k < 2; ++k) dst[n][k] = *(const PG8_LAS bf16x8*)(lds + PG8_SB(b, h) + boff + n * 2048 + k * 1024); } while (0)
; #define PG8_MMA(ai, bj, At, Bt) do { __builtin_amdgcn_s_setprio(1); _Pragma("unroll") for (int m = 0; m < 4; ++m) _Pragma("unroll") for (int n = 0; n < 2; ++n) _Pragma("unroll") for (int k = 0; k < 2; ++k) \
;         acc[ai][bj][m][n] = mma16<F16>(Bt[n][k], At[m][k], acc[ai][bj][m][n]); __builtin_amdgcn_s_setprio(0); } while (0)
; #define PG8_WAIT_V(n) asm volatile("s_waitcnt vmcnt(" #n ")" ::: "memory")
; #define PG8_WAIT_L(n) asm volatile("s_waitcnt lgkmcnt(" #n ")" ::: "memory")
; #define PG8_BAR __builtin_amdgcn_s_barrier()
; #define PG8_SCHED __builtin_amdgcn_sched_barrier(0)
; template <class Epi, class Sched, bool ALIGN_EPI = false, bool SP2 = false, bool F16 = false>
; __device__ __forceinline__ void gemm_phase(PG8_LAS unsigned char* lds, const Gemm g, const Sched& S, const Epi& E, const int wid_in) {
;     ...
;             PG8_LDB(B0, 0, 0); PG8_LDB(B1, 0, 1); PG8_SCHED; PG8_LDA(At, 0, 0); PG8_STAGE(PG8_SA(1, 1), a1 + hstep, voffA);
;             PG8_WAIT_V(8); PG8_WAIT_L(0); PG8_BAR; PG8_MMA(0, 0, At, B0); PG8_MMA(0, 1, At, B1); PG8_BAR; PG8_SCHED;
;             PG8_LDA(At, 0, 1); PG8_STAGE(PG8_SB(0, 0), b2, voffB); PG8_STAGE(PG8_SB(0, 1), b2 + hstep, voffB); PG8_STAGE(PG8_SA(0, 0), a2, voffA);
;             PG8_WAIT_V(8); PG8_WAIT_L(0); PG8_BAR; PG8_MMA(1, 0, At, B0); PG8_MMA(1, 1, At, B1); PG8_BAR; PG8_SCHED;
.LBB0_508:
	ds_read_b128 v[128:131], v189
	ds_read_b128 v[132:135], v189 offset:1024
	ds_read_b128 v[136:139], v189 offset:2048
	ds_read_b128 v[140:143], v189 offset:3072
	ds_read_b128 v[144:147], v190
	ds_read_b128 v[148:151], v190 offset:1024
	ds_read_b128 v[168:171], v190 offset:2048
	ds_read_b128 v[172:175], v190 offset:3072
	s_add_u32 s46, s44, 0xfffc0080
	s_addc_u32 s47, s45, -1
	s_cmp_eq_u32 s43, 12
	s_cselect_b32 s49, s10, s47
	s_cselect_b32 s48, s27, s46
	s_cselect_b32 s47, s25, s42
	s_cselect_b32 s46, s35, s37
	v_lshl_add_u64 v[184:185], s[44:45], 0, v[160:161]
	s_add_i32 m0, s74, 0xc000
	ds_read_b128 v[176:179], v191
	ds_read_b128 v[180:183], v191 offset:1024
	ds_read_b128 v[192:195], v191 offset:2048
	ds_read_b128 v[196:199], v191 offset:3072
	ds_read_b128 v[200:203], v191 offset:4096
	ds_read_b128 v[204:207], v191 offset:5120
	ds_read_b128 v[208:211], v191 offset:6144
	ds_read_b128 v[212:215], v191 offset:7168
	global_load_lds_dwordx4 v[184:185], off
	v_lshl_add_u64 v[184:185], s[44:45], 0, v[162:163]
	s_add_i32 m0, s74, 0xe000
	s_nop 0
	global_load_lds_dwordx4 v[184:185], off
	s_waitcnt vmcnt(8)
	s_cmp_lt_u32 s3, 4
	s_cbranch_scc1 .Lgls_4
	s_waitcnt lgkmcnt(0)
.Lgls_4:
	s_barrier
	s_setprio 1
	s_waitcnt lgkmcnt(0)
	v_mfma_f32_16x16x32_bf16 v[124:127], v[128:131], v[176:179], v[124:127]
	v_mfma_f32_16x16x32_bf16 v[120:123], v[136:139], v[176:179], v[120:123]
	v_mfma_f32_16x16x32_bf16 v[108:111], v[128:131], v[192:195], v[108:111]
	v_mfma_f32_16x16x32_bf16 v[104:107], v[136:139], v[192:195], v[104:107]
	v_mfma_f32_16x16x32_bf16 v[92:95], v[128:131], v[200:203], v[92:95]
	v_mfma_f32_16x16x32_bf16 v[88:91], v[136:139], v[200:203], v[88:91]
	v_mfma_f32_16x16x32_bf16 v[76:79], v[128:131], v[208:211], v[76:79]
	v_mfma_f32_16x16x32_bf16 v[72:75], v[136:139], v[208:211], v[72:75]
	v_mfma_f32_16x16x32_bf16 v[124:127], v[132:135], v[180:183], v[124:127]
	v_mfma_f32_16x16x32_bf16 v[120:123], v[140:143], v[180:183], v[120:123]
	v_mfma_f32_16x16x32_bf16 v[108:111], v[132:135], v[196:199], v[108:111]
	v_mfma_f32_16x16x32_bf16 v[104:107], v[140:143], v[196:199], v[104:107]
	v_mfma_f32_16x16x32_bf16 v[92:95], v[132:135], v[204:207], v[92:95]
	v_mfma_f32_16x16x32_bf16 v[88:91], v[140:143], v[204:207], v[88:91]
	v_mfma_f32_16x16x32_bf16 v[76:79], v[132:135], v[212:215], v[76:79]
	v_mfma_f32_16x16x32_bf16 v[72:75], v[140:143], v[212:215], v[72:75]
	s_setprio 0
	s_setprio 1
	v_mfma_f32_16x16x32_bf16 v[116:119], v[144:147], v[176:179], v[116:119]
	v_mfma_f32_16x16x32_bf16 v[112:115], v[168:171], v[176:179], v[112:115]
	v_mfma_f32_16x16x32_bf16 v[100:103], v[144:147], v[192:195], v[100:103]
	v_mfma_f32_16x16x32_bf16 v[96:99], v[168:171], v[192:195], v[96:99]
	v_mfma_f32_16x16x32_bf16 v[84:87], v[144:147], v[200:203], v[84:87]
	v_mfma_f32_16x16x32_bf16 v[80:83], v[168:171], v[200:203], v[80:83]
	v_mfma_f32_16x16x32_bf16 v[68:71], v[144:147], v[208:211], v[68:71]
	v_mfma_f32_16x16x32_bf16 v[64:67], v[168:171], v[208:211], v[64:67]
	v_mfma_f32_16x16x32_bf16 v[116:119], v[148:151], v[180:183], v[116:119]
	v_mfma_f32_16x16x32_bf16 v[112:115], v[172:175], v[180:183], v[112:115]
	v_mfma_f32_16x16x32_bf16 v[100:103], v[148:151], v[196:199], v[100:103]
	v_mfma_f32_16x16x32_bf16 v[96:99], v[172:175], v[196:199], v[96:99]
	v_mfma_f32_16x16x32_bf16 v[84:87], v[148:151], v[204:207], v[84:87]
	v_mfma_f32_16x16x32_bf16 v[80:83], v[172:175], v[204:207], v[80:83]
	v_mfma_f32_16x16x32_bf16 v[68:71], v[148:151], v[212:215], v[68:71]
	v_mfma_f32_16x16x32_bf16 v[64:67], v[172:175], v[212:215], v[64:67]
	s_setprio 0
	s_barrier
	s_add_i32 s63, s60, s68
	v_lshl_add_u64 v[184:185], s[46:47], 0, v[154:155]
	s_mov_b32 m0, s63
	ds_read_b128 v[176:179], v191 offset:16384
	ds_read_b128 v[180:183], v191 offset:17408
	ds_read_b128 v[192:195], v191 offset:18432
	ds_read_b128 v[196:199], v191 offset:19456
	ds_read_b128 v[200:203], v191 offset:20480
	ds_read_b128 v[204:207], v191 offset:21504
	ds_read_b128 v[208:211], v191 offset:22528
	ds_read_b128 v[212:215], v191 offset:23552
	global_load_lds_dwordx4 v[184:185], off
	s_add_i32 m0, s63, 0x2000
	s_add_u32 s64, s46, 0x40000
	v_lshl_add_u64 v[216:217], s[46:47], 0, v[158:159]
	s_addc_u32 s65, s47, 0
	s_add_i32 s63, s61, s68
	global_load_lds_dwordx4 v[216:217], off
	v_lshl_add_u64 v[218:219], s[64:65], 0, v[154:155]
	s_mov_b32 m0, s63
	v_lshl_add_u64 v[220:221], s[48:49], 0, v[156:157]
	global_load_lds_dwordx4 v[218:219], off
	v_lshl_add_u64 v[218:219], s[64:65], 0, v[158:159]
	s_add_i32 m0, s63, 0x2000
	s_nop 0
	global_load_lds_dwordx4 v[218:219], off
	v_lshl_add_u64 v[218:219], s[48:49], 0, v[152:153]
	s_mov_b32 m0, s74
	s_nop 0
	global_load_lds_dwordx4 v[218:219], off
	s_mov_b32 m0, s51
	s_nop 0
	global_load_lds_dwordx4 v[220:221], off
	s_waitcnt vmcnt(8)
	s_cmp_lt_u32 s3, 4
	s_cbranch_scc1 .Lgls_5
	s_waitcnt lgkmcnt(0)
; #define PG8_STAGE(bufoff, gbase, voff) do { _Pragma("unroll") for (int _i = 0; _i < 2; ++_i) \
;         __builtin_amdgcn_global_load_lds((const unsigned*)((const char*)(gbase) + (voff)[_i]), (PG8_LAS unsigned*)(lds + (bufoff) + ldsw + _i * 8192), 16, 0, 0); } while (0)
; #define PG8_LDA(dst, b, h) do { _Pragma("unroll") for (int m = 0; m < 4; ++m) _Pragma("unroll") for (int k = 0; k < 2; ++k) dst[m][k] = *(const PG8_LAS bf16x8*)(lds + PG8_SA(b, h) + aoff + m * 2048 + k * 1024); } while (0)
; #define PG8_LDB(dst, b, h) do { _Pragma("unroll") for (int n = 0; n < 2; ++n) _Pragma("unroll") for (int k = 0; k < 2; ++k) dst[n][k] = *(const PG8_LAS bf16x8*)(lds + PG8_SB(b, h) + boff + n * 2048 + k * 1024); } while (0)
; #define PG8_MMA(ai, bj, At, Bt) do { __builtin_amdgcn_s_setprio(1); _Pragma("unroll") for (int m = 0; m < 4; ++m) _Pragma("unroll") for (int n = 0; n < 2; ++n) _Pragma("unroll") for (int k = 0; k < 2; ++k) \
;         acc[ai][bj][m][n] = mma16<F16>(Bt[n][k], At[m][k], acc[ai][bj][m][n]); __builtin_amdgcn_s_setprio(0); } while (0)
; #define PG8_WAIT_V(n) asm volatile("s_waitcnt vmcnt(" #n ")" ::: "memory")
; #define PG8_WAIT_L(n) asm volatile("s_waitcnt lgkmcnt(" #n ")" ::: "memory")
; #define PG8_BAR __builtin_amdgcn_s_barrier()
; #define PG8_SCHED __builtin_amdgcn_sched_barrier(0)
; template <class Epi, class Sched, bool ALIGN_EPI = false, bool SP2 = false, bool F16 = false>
; __device__ __forceinline__ void gemm_phase(PG8_LAS unsigned char* lds, const Gemm g, const Sched& S, const Epi& E, const int wid_in) {
;     ...
;             PG8_WAIT_V(8); PG8_WAIT_L(0); PG8_BAR; PG8_MMA(1, 0, At, B0); PG8_MMA(1, 1, At, B1); PG8_BAR; PG8_SCHED;
;             PG8_LDB(B0, 1, 0); PG8_LDB(B1, 1, 1); PG8_SCHED; PG8_LDA(At, 1, 0); PG8_STAGE(PG8_SA(0, 1), a2 + hstep, voffA);
;             PG8_WAIT_V(8); PG8_WAIT_L(0); PG8_BAR; PG8_MMA(0, 0, At, B0); PG8_MMA(0, 1, At, B1); PG8_BAR; PG8_SCHED;
.Lgls_5:
	s_barrier
	s_setprio 1
	s_waitcnt lgkmcnt(0)
	v_mfma_f32_16x16x32_bf16 v[60:63], v[128:131], v[176:179], v[60:63]
	v_mfma_f32_16x16x32_bf16 v[56:59], v[136:139], v[176:179], v[56:59]
	v_mfma_f32_16x16x32_bf16 v[44:47], v[128:131], v[192:195], v[44:47]
	v_mfma_f32_16x16x32_bf16 v[40:43], v[136:139], v[192:195], v[40:43]
	v_mfma_f32_16x16x32_bf16 v[28:31], v[128:131], v[200:203], v[28:31]
	v_mfma_f32_16x16x32_bf16 v[24:27], v[136:139], v[200:203], v[24:27]
	v_mfma_f32_16x16x32_bf16 v[12:15], v[128:131], v[208:211], v[12:15]
	v_mfma_f32_16x16x32_bf16 v[8:11], v[136:139], v[208:211], v[8:11]
	v_mfma_f32_16x16x32_bf16 v[60:63], v[132:135], v[180:183], v[60:63]
	v_mfma_f32_16x16x32_bf16 v[56:59], v[140:143], v[180:183], v[56:59]
	v_mfma_f32_16x16x32_bf16 v[44:47], v[132:135], v[196:199], v[44:47]
	v_mfma_f32_16x16x32_bf16 v[40:43], v[140:143], v[196:199], v[40:43]
	v_mfma_f32_16x16x32_bf16 v[28:31], v[132:135], v[204:207], v[28:31]
	v_mfma_f32_16x16x32_bf16 v[24:27], v[140:143], v[204:207], v[24:27]
	v_mfma_f32_16x16x32_bf16 v[12:15], v[132:135], v[212:215], v[12:15]
	v_mfma_f32_16x16x32_bf16 v[8:11], v[140:143], v[212:215], v[8:11]
	s_setprio 0
	s_setprio 1
	v_mfma_f32_16x16x32_bf16 v[52:55], v[144:147], v[176:179], v[52:55]
	v_mfma_f32_16x16x32_bf16 v[48:51], v[168:171], v[176:179], v[48:51]
	v_mfma_f32_16x16x32_bf16 v[36:39], v[144:147], v[192:195], v[36:39]
	v_mfma_f32_16x16x32_bf16 v[32:35], v[168:171], v[192:195], v[32:35]
	v_mfma_f32_16x16x32_bf16 v[20:23], v[144:147], v[200:203], v[20:23]
	v_mfma_f32_16x16x32_bf16 v[16:19], v[168:171], v[200:203], v[16:19]
	v_mfma_f32_16x16x32_bf16 v[4:7], v[144:147], v[208:211], v[4:7]
	v_mfma_f32_16x16x32_bf16 v[0:3], v[168:171], v[208:211], v[0:3]
	v_mfma_f32_16x16x32_bf16 v[52:55], v[148:151], v[180:183], v[52:55]
	v_mfma_f32_16x16x32_bf16 v[48:51], v[172:175], v[180:183], v[48:51]
	v_mfma_f32_16x16x32_bf16 v[36:39], v[148:151], v[196:199], v[36:39]
	v_mfma_f32_16x16x32_bf16 v[32:35], v[172:175], v[196:199], v[32:35]
	v_mfma_f32_16x16x32_bf16 v[20:23], v[148:151], v[204:207], v[20:23]
	v_mfma_f32_16x16x32_bf16 v[16:19], v[172:175], v[204:207], v[16:19]
	v_mfma_f32_16x16x32_bf16 v[4:7], v[148:151], v[212:215], v[4:7]
	v_mfma_f32_16x16x32_bf16 v[0:3], v[172:175], v[212:215], v[0:3]
	s_setprio 0
	s_barrier
	s_add_i32 s63, 0, 0x18000
	s_add_i32 s64, 0, 0x1c000
	v_add_u32_e32 v140, s63, v188
	v_add_u32_e32 v172, s64, v188
	ds_read_b128 v[128:131], v140
	ds_read_b128 v[132:135], v140 offset:1024
	ds_read_b128 v[136:139], v140 offset:2048
	ds_read_b128 v[140:143], v140 offset:3072
	ds_read_b128 v[144:147], v172
	ds_read_b128 v[148:151], v172 offset:1024
	ds_read_b128 v[168:171], v172 offset:2048
	ds_read_b128 v[172:175], v172 offset:3072
	s_add_u32 s48, s48, 0x40000
	s_addc_u32 s49, s49, 0
	s_mov_b32 m0, s52
	v_lshl_add_u64 v[222:223], s[48:49], 0, v[152:153]
	ds_read_b128 v[176:179], v191 offset:32768
	ds_read_b128 v[180:183], v191 offset:33792
	ds_read_b128 v[192:195], v191 offset:34816
	ds_read_b128 v[196:199], v191 offset:35840
	ds_read_b128 v[200:203], v191 offset:36864
	ds_read_b128 v[204:207], v191 offset:37888
	ds_read_b128 v[208:211], v191 offset:38912
	ds_read_b128 v[212:215], v191 offset:39936
	global_load_lds_dwordx4 v[222:223], off
	v_lshl_add_u64 v[222:223], s[48:49], 0, v[156:157]
	s_mov_b32 m0, s53
	s_nop 0
	global_load_lds_dwordx4 v[222:223], off
	s_waitcnt vmcnt(8)
	s_cmp_lt_u32 s3, 4
	s_cbranch_scc1 .Lgls_6
	s_waitcnt lgkmcnt(0)
; #define PG8_STAGE(bufoff, gbase, voff) do { _Pragma("unroll") for (int _i = 0; _i < 2; ++_i) \
;         __builtin_amdgcn_global_load_lds((const unsigned*)((const char*)(gbase) + (voff)[_i]), (PG8_LAS unsigned*)(lds + (bufoff) + ldsw + _i * 8192), 16, 0, 0); } while (0)
; #define PG8_LDA(dst, b, h) do { _Pragma("unroll") for (int m = 0; m < 4; ++m) _Pragma("unroll") for (int k = 0; k < 2; ++k) dst[m][k] = *(const PG8_LAS bf16x8*)(lds + PG8_SA(b, h) + aoff + m * 2048 + k * 1024); } while (0)
; #define PG8_MMA(ai, bj, At, Bt) do { __builtin_amdgcn_s_setprio(1); _Pragma("unroll") for (int m = 0; m < 4; ++m) _Pragma("unroll") for (int n = 0; n < 2; ++n) _Pragma("unroll") for (int k = 0; k < 2; ++k) \
;         acc[ai][bj][m][n] = mma16<F16>(Bt[n][k], At[m][k], acc[ai][bj][m][n]); __builtin_amdgcn_s_setprio(0); } while (0)
; #define PG8_WAIT_V(n) asm volatile("s_waitcnt vmcnt(" #n ")" ::: "memory")
; #define PG8_WAIT_L(n) asm volatile("s_waitcnt lgkmcnt(" #n ")" ::: "memory")
; #define PG8_BAR __builtin_amdgcn_s_barrier()
; #define PG8_SCHED __builtin_amdgcn_sched_barrier(0)
; template <class Epi, class Sched, bool ALIGN_EPI = false, bool SP2 = false, bool F16 = false>
; __device__ __forceinline__ void gemm_phase(PG8_LAS unsigned char* lds, const Gemm g, const Sched& S, const Epi& E, const int wid_in) {
;     ...
;             PG8_WAIT_V(8); PG8_WAIT_L(0); PG8_BAR; PG8_MMA(0, 0, At, B0); PG8_MMA(0, 1, At, B1); PG8_BAR; PG8_SCHED;
;             PG8_LDA(At, 1, 1); PG8_STAGE(PG8_SB(1, 0), b3, voffB); PG8_STAGE(PG8_SB(1, 1), b3 + hstep, voffB); PG8_STAGE(PG8_SA(1, 0), a3, voffA);
;             PG8_WAIT_V(8); PG8_WAIT_L(0); PG8_BAR; PG8_MMA(1, 0, At, B0); PG8_MMA(1, 1, At, B1); PG8_BAR; PG8_SCHED;
.Lgls_6:
	s_barrier
	s_setprio 1
	s_waitcnt lgkmcnt(0)
	v_mfma_f32_16x16x32_bf16 v[124:127], v[128:131], v[176:179], v[124:127]
	v_mfma_f32_16x16x32_bf16 v[120:123], v[136:139], v[176:179], v[120:123]
	v_mfma_f32_16x16x32_bf16 v[108:111], v[128:131], v[192:195], v[108:111]
	v_mfma_f32_16x16x32_bf16 v[104:107], v[136:139], v[192:195], v[104:107]
	v_mfma_f32_16x16x32_bf16 v[92:95], v[128:131], v[200:203], v[92:95]
	v_mfma_f32_16x16x32_bf16 v[88:91], v[136:139], v[200:203], v[88:91]
	v_mfma_f32_16x16x32_bf16 v[76:79], v[128:131], v[208:211], v[76:79]
	v_mfma_f32_16x16x32_bf16 v[72:75], v[136:139], v[208:211], v[72:75]
	v_mfma_f32_16x16x32_bf16 v[124:127], v[132:135], v[180:183], v[124:127]
	v_mfma_f32_16x16x32_bf16 v[120:123], v[140:143], v[180:183], v[120:123]
	v_mfma_f32_16x16x32_bf16 v[108:111], v[132:135], v[196:199], v[108:111]
	v_mfma_f32_16x16x32_bf16 v[104:107], v[140:143], v[196:199], v[104:107]
	v_mfma_f32_16x16x32_bf16 v[92:95], v[132:135], v[204:207], v[92:95]
	v_mfma_f32_16x16x32_bf16 v[88:91], v[140:143], v[204:207], v[88:91]
	v_mfma_f32_16x16x32_bf16 v[76:79], v[132:135], v[212:215], v[76:79]
	v_mfma_f32_16x16x32_bf16 v[72:75], v[140:143], v[212:215], v[72:75]
	s_setprio 0
	s_setprio 1
	v_mfma_f32_16x16x32_bf16 v[116:119], v[144:147], v[176:179], v[116:119]
	v_mfma_f32_16x16x32_bf16 v[112:115], v[168:171], v[176:179], v[112:115]
	v_mfma_f32_16x16x32_bf16 v[100:103], v[144:147], v[192:195], v[100:103]
	v_mfma_f32_16x16x32_bf16 v[96:99], v[168:171], v[192:195], v[96:99]
	v_mfma_f32_16x16x32_bf16 v[84:87], v[144:147], v[200:203], v[84:87]
	v_mfma_f32_16x16x32_bf16 v[80:83], v[168:171], v[200:203], v[80:83]
	v_mfma_f32_16x16x32_bf16 v[68:71], v[144:147], v[208:211], v[68:71]
	v_mfma_f32_16x16x32_bf16 v[64:67], v[168:171], v[208:211], v[64:67]
	v_mfma_f32_16x16x32_bf16 v[116:119], v[148:151], v[180:183], v[116:119]
	v_mfma_f32_16x16x32_bf16 v[112:115], v[172:175], v[180:183], v[112:115]
	v_mfma_f32_16x16x32_bf16 v[100:103], v[148:151], v[196:199], v[100:103]
	v_mfma_f32_16x16x32_bf16 v[96:99], v[172:175], v[196:199], v[96:99]
	v_mfma_f32_16x16x32_bf16 v[84:87], v[148:151], v[204:207], v[84:87]
	v_mfma_f32_16x16x32_bf16 v[80:83], v[172:175], v[204:207], v[80:83]
	v_mfma_f32_16x16x32_bf16 v[68:71], v[148:151], v[212:215], v[68:71]
	v_mfma_f32_16x16x32_bf16 v[64:67], v[172:175], v[212:215], v[64:67]
	s_setprio 0
	s_barrier
	s_add_i32 s48, s63, s68
	v_lshl_add_u64 v[184:185], v[184:185], 0, s[22:23]
	s_mov_b32 m0, s48
	ds_read_b128 v[176:179], v191 offset:49152
	ds_read_b128 v[180:183], v191 offset:50176
	ds_read_b128 v[192:195], v191 offset:51200
	ds_read_b128 v[196:199], v191 offset:52224
	ds_read_b128 v[200:203], v191 offset:53248
	ds_read_b128 v[204:207], v191 offset:54272
	ds_read_b128 v[208:211], v191 offset:55296
	ds_read_b128 v[212:215], v191 offset:56320
	global_load_lds_dwordx4 v[184:185], off
	s_add_i32 m0, s48, 0x2000
	s_add_u32 s46, s46, 0x40080
	v_lshl_add_u64 v[184:185], v[216:217], 0, s[22:23]
	s_addc_u32 s47, s47, 0
	s_add_i32 s48, s64, s68
	global_load_lds_dwordx4 v[184:185], off
	v_lshl_add_u64 v[184:185], s[46:47], 0, v[154:155]
	s_mov_b32 m0, s48
	s_nop 0
	global_load_lds_dwordx4 v[184:185], off
	v_lshl_add_u64 v[184:185], s[46:47], 0, v[158:159]
	s_add_i32 m0, s48, 0x2000
	s_nop 0
	global_load_lds_dwordx4 v[184:185], off
	v_lshl_add_u64 v[184:185], v[218:219], 0, s[22:23]
	s_mov_b32 m0, s75
	s_nop 0
	global_load_lds_dwordx4 v[184:185], off
	v_lshl_add_u64 v[184:185], v[220:221], 0, s[22:23]
	s_mov_b32 m0, s54
	s_nop 0
	global_load_lds_dwordx4 v[184:185], off
	s_waitcnt vmcnt(8)
	s_cmp_lt_u32 s3, 4
	s_cbranch_scc1 .Lgls_7
	s_waitcnt lgkmcnt(0)
.Lgls_7:
	s_barrier
	s_setprio 1
	s_waitcnt lgkmcnt(0)
	v_mfma_f32_16x16x32_bf16 v[60:63], v[128:131], v[176:179], v[60:63]
	v_mfma_f32_16x16x32_bf16 v[56:59], v[136:139], v[176:179], v[56:59]
	v_mfma_f32_16x16x32_bf16 v[44:47], v[128:131], v[192:195], v[44:47]
	v_mfma_f32_16x16x32_bf16 v[40:43], v[136:139], v[192:195], v[40:43]
	v_mfma_f32_16x16x32_bf16 v[28:31], v[128:131], v[200:203], v[28:31]
	v_mfma_f32_16x16x32_bf16 v[24:27], v[136:139], v[200:203], v[24:27]
	v_mfma_f32_16x16x32_bf16 v[12:15], v[128:131], v[208:211], v[12:15]
	v_mfma_f32_16x16x32_bf16 v[8:11], v[136:139], v[208:211], v[8:11]
	v_mfma_f32_16x16x32_bf16 v[60:63], v[132:135], v[180:183], v[60:63]
	v_mfma_f32_16x16x32_bf16 v[56:59], v[140:143], v[180:183], v[56:59]
	v_mfma_f32_16x16x32_bf16 v[44:47], v[132:135], v[196:199], v[44:47]
	v_mfma_f32_16x16x32_bf16 v[40:43], v[140:143], v[196:199], v[40:43]
	v_mfma_f32_16x16x32_bf16 v[28:31], v[132:135], v[204:207], v[28:31]
	v_mfma_f32_16x16x32_bf16 v[24:27], v[140:143], v[204:207], v[24:27]
	v_mfma_f32_16x16x32_bf16 v[12:15], v[132:135], v[212:215], v[12:15]
	v_mfma_f32_16x16x32_bf16 v[8:11], v[140:143], v[212:215], v[8:11]
	s_setprio 0
	s_setprio 1
	v_mfma_f32_16x16x32_bf16 v[52:55], v[144:147], v[176:179], v[52:55]
	v_mfma_f32_16x16x32_bf16 v[48:51], v[168:171], v[176:179], v[48:51]
	v_mfma_f32_16x16x32_bf16 v[36:39], v[144:147], v[192:195], v[36:39]
	v_mfma_f32_16x16x32_bf16 v[32:35], v[168:171], v[192:195], v[32:35]
	v_mfma_f32_16x16x32_bf16 v[20:23], v[144:147], v[200:203], v[20:23]
	v_mfma_f32_16x16x32_bf16 v[16:19], v[168:171], v[200:203], v[16:19]
	v_mfma_f32_16x16x32_bf16 v[4:7], v[144:147], v[208:211], v[4:7]
	v_mfma_f32_16x16x32_bf16 v[0:3], v[168:171], v[208:211], v[0:3]
	v_mfma_f32_16x16x32_bf16 v[52:55], v[148:151], v[180:183], v[52:55]
	v_mfma_f32_16x16x32_bf16 v[48:51], v[172:175], v[180:183], v[48:51]
	v_mfma_f32_16x16x32_bf16 v[36:39], v[148:151], v[196:199], v[36:39]
	v_mfma_f32_16x16x32_bf16 v[32:35], v[172:175], v[196:199], v[32:35]
	v_mfma_f32_16x16x32_bf16 v[20:23], v[148:151], v[204:207], v[20:23]
	v_mfma_f32_16x16x32_bf16 v[16:19], v[172:175], v[204:207], v[16:19]
	v_mfma_f32_16x16x32_bf16 v[4:7], v[148:151], v[212:215], v[4:7]
	v_mfma_f32_16x16x32_bf16 v[0:3], v[172:175], v[212:215], v[0:3]
	s_setprio 0
	s_barrier
	s_add_i32 s43, s43, 2
	s_add_u32 s44, s44, 0x100
	s_addc_u32 s45, s45, 0
	s_add_u32 s37, s37, 0x100
	s_addc_u32 s42, s42, 0
	s_cmp_gt_u32 s43, 13
	s_cbranch_scc0 .LBB0_508
	s_and_b64 vcc, exec, s[16:17]
	s_cbranch_vccz .LBB0_511
	s_barrier

; #define PG8_STAGE(bufoff, gbase, voff) do { _Pragma("unroll") for (int _i = 0; _i < 2; ++_i) \
;         __builtin_amdgcn_global_load_lds((const unsigned*)((const char*)(gbase) + (voff)[_i]), (PG8_LAS unsigned*)(lds + (bufoff) + ldsw + _i * 8192), 16, 0, 0); } while (0)
; #define PG8_LDA(dst, b, h) do { _Pragma("unroll") for (int m = 0; m < 4; ++m) _Pragma("unroll") for (int k = 0; k < 2; ++k) dst[m][k] = *(const PG8_LAS bf16x8*)(lds + PG8_SA(b, h) + aoff + m * 2048 + k * 1024); } while (0)
; #define PG8_LDB(dst, b, h) do { _Pragma("unroll") for (int n = 0; n < 2; ++n) _Pragma("unroll") for (int k = 0; k < 2; ++k) dst[n][k] = *(const PG8_LAS bf16x8*)(lds + PG8_SB(b, h) + boff + n * 2048 + k * 1024); } while (0)
; #define PG8_MMA(ai, bj, At, Bt) do { __builtin_amdgcn_s_setprio(1); _Pragma("unroll") for (int m = 0; m < 4; ++m) _Pragma("unroll") for (int n = 0; n < 2; ++n) _Pragma("unroll") for (int k = 0; k < 2; ++k) \
;         acc[ai][bj][m][n] = mma16<F16>(Bt[n][k], At[m][k], acc[ai][bj][m][n]); __builtin_amdgcn_s_setprio(0); } while (0)
; #define PG8_WAIT_V(n) asm volatile("s_waitcnt vmcnt(" #n ")" ::: "memory")
; #define PG8_WAIT_L(n) asm volatile("s_waitcnt lgkmcnt(" #n ")" ::: "memory")
; #define PG8_BAR __builtin_amdgcn_s_barrier()
; #define PG8_SCHED __builtin_amdgcn_sched_barrier(0)
; template <class Epi, class Sched, bool ALIGN_EPI = false, bool SP2 = false, bool F16 = false>
; __device__ __forceinline__ void gemm_phase(PG8_LAS unsigned char* lds, const Gemm g, const Sched& S, const Epi& E, const int wid_in) {
;     ...
;             PG8_LDB(B0, 0, 0); PG8_LDB(B1, 0, 1); PG8_SCHED; PG8_LDA(At, 0, 0); PG8_STAGE(PG8_SA(1, 1), a1 + hstep, voffA);
;             PG8_WAIT_V(8); PG8_WAIT_L(0); PG8_BAR; PG8_MMA(0, 0, At, B0); PG8_MMA(0, 1, At, B1); PG8_BAR; PG8_SCHED;
;             PG8_LDA(At, 0, 1); PG8_STAGE(PG8_SB(0, 0), b2, voffB); PG8_STAGE(PG8_SB(0, 1), b2 + hstep, voffB); PG8_STAGE(PG8_SA(0, 0), a2, voffA);
;             PG8_WAIT_V(8); PG8_WAIT_L(0); PG8_BAR; PG8_MMA(1, 0, At, B0); PG8_MMA(1, 1, At, B1); PG8_BAR; PG8_SCHED;
.LBB0_585:
	ds_read_b128 v[0:3], v193
	ds_read_b128 v[4:7], v193 offset:1024
	ds_read_b128 v[136:139], v193 offset:2048
	ds_read_b128 v[140:143], v193 offset:3072
	ds_read_b128 v[144:147], v194
	ds_read_b128 v[148:151], v194 offset:1024
	ds_read_b128 v[152:155], v194 offset:2048
	ds_read_b128 v[156:159], v194 offset:3072
	s_add_u32 s36, s34, 0xfffc0080
	s_addc_u32 s37, s35, -1
	s_cmp_eq_u32 s65, 12
	s_cselect_b32 s45, s23, s37
	s_cselect_b32 s44, s31, s36
	s_cselect_b32 s37, s21, s64
	s_cselect_b32 s36, s42, s43
	v_lshl_add_u64 v[188:189], s[34:35], 0, v[168:169]
	s_add_i32 m0, s74, 0xc000
	ds_read_b128 v[176:179], v195
	ds_read_b128 v[180:183], v195 offset:1024
	ds_read_b128 v[184:187], v195 offset:2048
	ds_read_b128 v[198:201], v195 offset:3072
	ds_read_b128 v[202:205], v195 offset:4096
	ds_read_b128 v[206:209], v195 offset:5120
	ds_read_b128 v[210:213], v195 offset:6144
	ds_read_b128 v[214:217], v195 offset:7168
	global_load_lds_dwordx4 v[188:189], off
	v_lshl_add_u64 v[188:189], s[34:35], 0, v[170:171]
	s_add_i32 m0, s74, 0xe000
	s_nop 0
	global_load_lds_dwordx4 v[188:189], off
	s_waitcnt vmcnt(8)
	s_cmp_lt_u32 s3, 4
	s_cbranch_scc1 .Lgls_8
	s_waitcnt lgkmcnt(0)
.Lgls_8:
	s_barrier
	s_setprio 1
	s_waitcnt lgkmcnt(0)
	v_mfma_f32_16x16x32_f16 v[132:135], v[0:3], v[176:179], v[132:135]
	v_mfma_f32_16x16x32_f16 v[128:131], v[136:139], v[176:179], v[128:131]
	v_mfma_f32_16x16x32_f16 v[116:119], v[0:3], v[184:187], v[116:119]
	v_mfma_f32_16x16x32_f16 v[112:115], v[136:139], v[184:187], v[112:115]
	v_mfma_f32_16x16x32_f16 v[100:103], v[0:3], v[202:205], v[100:103]
	v_mfma_f32_16x16x32_f16 v[96:99], v[136:139], v[202:205], v[96:99]
	v_mfma_f32_16x16x32_f16 v[84:87], v[0:3], v[210:213], v[84:87]
	v_mfma_f32_16x16x32_f16 v[80:83], v[136:139], v[210:213], v[80:83]
	v_mfma_f32_16x16x32_f16 v[132:135], v[4:7], v[180:183], v[132:135]
	v_mfma_f32_16x16x32_f16 v[128:131], v[140:143], v[180:183], v[128:131]
	v_mfma_f32_16x16x32_f16 v[116:119], v[4:7], v[198:201], v[116:119]
	v_mfma_f32_16x16x32_f16 v[112:115], v[140:143], v[198:201], v[112:115]
	v_mfma_f32_16x16x32_f16 v[100:103], v[4:7], v[206:209], v[100:103]
	v_mfma_f32_16x16x32_f16 v[96:99], v[140:143], v[206:209], v[96:99]
	v_mfma_f32_16x16x32_f16 v[84:87], v[4:7], v[214:217], v[84:87]
	v_mfma_f32_16x16x32_f16 v[80:83], v[140:143], v[214:217], v[80:83]
	s_setprio 0
	s_setprio 1
	v_mfma_f32_16x16x32_f16 v[124:127], v[144:147], v[176:179], v[124:127]
	v_mfma_f32_16x16x32_f16 v[120:123], v[152:155], v[176:179], v[120:123]
	v_mfma_f32_16x16x32_f16 v[108:111], v[144:147], v[184:187], v[108:111]
	v_mfma_f32_16x16x32_f16 v[104:107], v[152:155], v[184:187], v[104:107]
	v_mfma_f32_16x16x32_f16 v[92:95], v[144:147], v[202:205], v[92:95]
	v_mfma_f32_16x16x32_f16 v[88:91], v[152:155], v[202:205], v[88:91]
	v_mfma_f32_16x16x32_f16 v[76:79], v[144:147], v[210:213], v[76:79]
	v_mfma_f32_16x16x32_f16 v[72:75], v[152:155], v[210:213], v[72:75]
	v_mfma_f32_16x16x32_f16 v[124:127], v[148:151], v[180:183], v[124:127]
	v_mfma_f32_16x16x32_f16 v[120:123], v[156:159], v[180:183], v[120:123]
	v_mfma_f32_16x16x32_f16 v[108:111], v[148:151], v[198:201], v[108:111]
	v_mfma_f32_16x16x32_f16 v[104:107], v[156:159], v[198:201], v[104:107]
	v_mfma_f32_16x16x32_f16 v[92:95], v[148:151], v[206:209], v[92:95]
	v_mfma_f32_16x16x32_f16 v[88:91], v[156:159], v[206:209], v[88:91]
	v_mfma_f32_16x16x32_f16 v[76:79], v[148:151], v[214:217], v[76:79]
	v_mfma_f32_16x16x32_f16 v[72:75], v[156:159], v[214:217], v[72:75]
	s_setprio 0
	s_barrier
	s_add_i32 s66, s61, s68
	v_lshl_add_u64 v[188:189], s[36:37], 0, v[162:163]
	s_mov_b32 m0, s66
	ds_read_b128 v[176:179], v195 offset:16384
	ds_read_b128 v[180:183], v195 offset:17408
	ds_read_b128 v[184:187], v195 offset:18432
	ds_read_b128 v[198:201], v195 offset:19456
	ds_read_b128 v[202:205], v195 offset:20480
	ds_read_b128 v[206:209], v195 offset:21504
	ds_read_b128 v[210:213], v195 offset:22528
	ds_read_b128 v[214:217], v195 offset:23552
	global_load_lds_dwordx4 v[188:189], off
	s_add_i32 m0, s66, 0x2000
	s_add_u32 s66, s36, 0x40000
	v_lshl_add_u64 v[218:219], s[36:37], 0, v[166:167]
	s_addc_u32 s67, s37, 0
	s_add_i32 s76, s62, s68
	global_load_lds_dwordx4 v[218:219], off
	v_lshl_add_u64 v[220:221], s[66:67], 0, v[162:163]
	s_mov_b32 m0, s76
	v_lshl_add_u64 v[222:223], s[44:45], 0, v[164:165]
	global_load_lds_dwordx4 v[220:221], off
	v_lshl_add_u64 v[220:221], s[66:67], 0, v[166:167]
	s_add_i32 m0, s76, 0x2000
	s_nop 0
	global_load_lds_dwordx4 v[220:221], off
	v_lshl_add_u64 v[220:221], s[44:45], 0, v[160:161]
	s_mov_b32 m0, s74
	s_nop 0
	global_load_lds_dwordx4 v[220:221], off
	s_mov_b32 m0, s29
	s_nop 0
	global_load_lds_dwordx4 v[222:223], off
	s_waitcnt vmcnt(8)
	s_cmp_lt_u32 s3, 4
	s_cbranch_scc1 .Lgls_9
	s_waitcnt lgkmcnt(0)
; #define PG8_STAGE(bufoff, gbase, voff) do { _Pragma("unroll") for (int _i = 0; _i < 2; ++_i) \
;         __builtin_amdgcn_global_load_lds((const unsigned*)((const char*)(gbase) + (voff)[_i]), (PG8_LAS unsigned*)(lds + (bufoff) + ldsw + _i * 8192), 16, 0, 0); } while (0)
; #define PG8_LDA(dst, b, h) do { _Pragma("unroll") for (int m = 0; m < 4; ++m) _Pragma("unroll") for (int k = 0; k < 2; ++k) dst[m][k] = *(const PG8_LAS bf16x8*)(lds + PG8_SA(b, h) + aoff + m * 2048 + k * 1024); } while (0)
; #define PG8_LDB(dst, b, h) do { _Pragma("unroll") for (int n = 0; n < 2; ++n) _Pragma("unroll") for (int k = 0; k < 2; ++k) dst[n][k] = *(const PG8_LAS bf16x8*)(lds + PG8_SB(b, h) + boff + n * 2048 + k * 1024); } while (0)
; #define PG8_MMA(ai, bj, At, Bt) do { __builtin_amdgcn_s_setprio(1); _Pragma("unroll") for (int m = 0; m < 4; ++m) _Pragma("unroll") for (int n = 0; n < 2; ++n) _Pragma("unroll") for (int k = 0; k < 2; ++k) \
;         acc[ai][bj][m][n] = mma16<F16>(Bt[n][k], At[m][k], acc[ai][bj][m][n]); __builtin_amdgcn_s_setprio(0); } while (0)
; #define PG8_WAIT_V(n) asm volatile("s_waitcnt vmcnt(" #n ")" ::: "memory")
; #define PG8_WAIT_L(n) asm volatile("s_waitcnt lgkmcnt(" #n ")" ::: "memory")
; #define PG8_BAR __builtin_amdgcn_s_barrier()
; #define PG8_SCHED __builtin_amdgcn_sched_barrier(0)
; template <class Epi, class Sched, bool ALIGN_EPI = false, bool SP2 = false, bool F16 = false>
; __device__ __forceinline__ void gemm_phase(PG8_LAS unsigned char* lds, const Gemm g, const Sched& S, const Epi& E, const int wid_in) {
;     ...
;             PG8_WAIT_V(8); PG8_WAIT_L(0); PG8_BAR; PG8_MMA(1, 0, At, B0); PG8_MMA(1, 1, At, B1); PG8_BAR; PG8_SCHED;
;             PG8_LDB(B0, 1, 0); PG8_LDB(B1, 1, 1); PG8_SCHED; PG8_LDA(At, 1, 0); PG8_STAGE(PG8_SA(0, 1), a2 + hstep, voffA);
;             PG8_WAIT_V(8); PG8_WAIT_L(0); PG8_BAR; PG8_MMA(0, 0, At, B0); PG8_MMA(0, 1, At, B1); PG8_BAR; PG8_SCHED;
.Lgls_9:
	s_barrier
	s_setprio 1
	s_waitcnt lgkmcnt(0)
	v_mfma_f32_16x16x32_f16 v[68:71], v[0:3], v[176:179], v[68:71]
	v_mfma_f32_16x16x32_f16 v[64:67], v[136:139], v[176:179], v[64:67]
	v_mfma_f32_16x16x32_f16 v[52:55], v[0:3], v[184:187], v[52:55]
	v_mfma_f32_16x16x32_f16 v[48:51], v[136:139], v[184:187], v[48:51]
	v_mfma_f32_16x16x32_f16 v[36:39], v[0:3], v[202:205], v[36:39]
	v_mfma_f32_16x16x32_f16 v[32:35], v[136:139], v[202:205], v[32:35]
	v_mfma_f32_16x16x32_f16 v[0:3], v[0:3], v[210:213], v[20:23]
	v_mfma_f32_16x16x32_f16 v[68:71], v[4:7], v[180:183], v[68:71]
	v_mfma_f32_16x16x32_f16 v[64:67], v[140:143], v[180:183], v[64:67]
	v_mfma_f32_16x16x32_f16 v[52:55], v[4:7], v[198:201], v[52:55]
	v_mfma_f32_16x16x32_f16 v[48:51], v[140:143], v[198:201], v[48:51]
	v_mfma_f32_16x16x32_f16 v[36:39], v[4:7], v[206:209], v[36:39]
	v_mfma_f32_16x16x32_f16 v[32:35], v[140:143], v[206:209], v[32:35]
	v_mfma_f32_16x16x32_f16 v[0:3], v[4:7], v[214:217], v[0:3]
	v_mfma_f32_16x16x32_f16 v[4:7], v[136:139], v[210:213], v[16:19]
	v_mfma_f32_16x16x32_f16 v[4:7], v[140:143], v[214:217], v[4:7]
	s_setprio 0
	s_setprio 1
	v_mfma_f32_16x16x32_f16 v[16:19], v[144:147], v[176:179], v[60:63]
	v_mfma_f32_16x16x32_f16 v[60:63], v[148:151], v[180:183], v[16:19]
	v_mfma_f32_16x16x32_f16 v[16:19], v[152:155], v[176:179], v[56:59]
	v_mfma_f32_16x16x32_f16 v[56:59], v[156:159], v[180:183], v[16:19]
	v_mfma_f32_16x16x32_f16 v[16:19], v[144:147], v[184:187], v[44:47]
	v_mfma_f32_16x16x32_f16 v[44:47], v[148:151], v[198:201], v[16:19]
	v_mfma_f32_16x16x32_f16 v[16:19], v[152:155], v[184:187], v[40:43]
	v_mfma_f32_16x16x32_f16 v[40:43], v[156:159], v[198:201], v[16:19]
	v_mfma_f32_16x16x32_f16 v[16:19], v[144:147], v[202:205], v[28:31]
	v_mfma_f32_16x16x32_f16 v[28:31], v[148:151], v[206:209], v[16:19]
	v_mfma_f32_16x16x32_f16 v[16:19], v[152:155], v[202:205], v[24:27]
	v_mfma_f32_16x16x32_f16 v[12:15], v[144:147], v[210:213], v[12:15]
	v_mfma_f32_16x16x32_f16 v[8:11], v[152:155], v[210:213], v[8:11]
	v_mfma_f32_16x16x32_f16 v[24:27], v[156:159], v[206:209], v[16:19]
	v_mfma_f32_16x16x32_f16 v[12:15], v[148:151], v[214:217], v[12:15]
	v_mfma_f32_16x16x32_f16 v[8:11], v[156:159], v[214:217], v[8:11]
	s_setprio 0
	s_barrier
	s_add_i32 s66, 0, 0x18000
	s_add_i32 s67, 0, 0x1c000
	v_add_u32_e32 v140, s66, v192
	v_add_u32_e32 v156, s67, v192
	ds_read_b128 v[16:19], v140
	ds_read_b128 v[20:23], v140 offset:1024
	ds_read_b128 v[136:139], v140 offset:2048
	ds_read_b128 v[140:143], v140 offset:3072
	ds_read_b128 v[144:147], v156
	ds_read_b128 v[148:151], v156 offset:1024
	ds_read_b128 v[152:155], v156 offset:2048
	ds_read_b128 v[156:159], v156 offset:3072
	s_add_u32 s44, s44, 0x40000
	s_addc_u32 s45, s45, 0
	s_mov_b32 m0, s49
	v_lshl_add_u64 v[224:225], s[44:45], 0, v[160:161]
	ds_read_b128 v[176:179], v195 offset:32768
	ds_read_b128 v[180:183], v195 offset:33792
	ds_read_b128 v[184:187], v195 offset:34816
	ds_read_b128 v[198:201], v195 offset:35840
	ds_read_b128 v[202:205], v195 offset:36864
	ds_read_b128 v[206:209], v195 offset:37888
	ds_read_b128 v[210:213], v195 offset:38912
	ds_read_b128 v[214:217], v195 offset:39936
	global_load_lds_dwordx4 v[224:225], off
	v_lshl_add_u64 v[224:225], s[44:45], 0, v[164:165]
	s_mov_b32 m0, s50
	s_nop 0
	global_load_lds_dwordx4 v[224:225], off
	s_waitcnt vmcnt(8)
	s_cmp_lt_u32 s3, 4
	s_cbranch_scc1 .Lgls_10
	s_waitcnt lgkmcnt(0)
; #define PG8_STAGE(bufoff, gbase, voff) do { _Pragma("unroll") for (int _i = 0; _i < 2; ++_i) \
;         __builtin_amdgcn_global_load_lds((const unsigned*)((const char*)(gbase) + (voff)[_i]), (PG8_LAS unsigned*)(lds + (bufoff) + ldsw + _i * 8192), 16, 0, 0); } while (0)
; #define PG8_LDA(dst, b, h) do { _Pragma("unroll") for (int m = 0; m < 4; ++m) _Pragma("unroll") for (int k = 0; k < 2; ++k) dst[m][k] = *(const PG8_LAS bf16x8*)(lds + PG8_SA(b, h) + aoff + m * 2048 + k * 1024); } while (0)
; #define PG8_MMA(ai, bj, At, Bt) do { __builtin_amdgcn_s_setprio(1); _Pragma("unroll") for (int m = 0; m < 4; ++m) _Pragma("unroll") for (int n = 0; n < 2; ++n) _Pragma("unroll") for (int k = 0; k < 2; ++k) \
;         acc[ai][bj][m][n] = mma16<F16>(Bt[n][k], At[m][k], acc[ai][bj][m][n]); __builtin_amdgcn_s_setprio(0); } while (0)
; #define PG8_WAIT_V(n) asm volatile("s_waitcnt vmcnt(" #n ")" ::: "memory")
; #define PG8_WAIT_L(n) asm volatile("s_waitcnt lgkmcnt(" #n ")" ::: "memory")
; #define PG8_BAR __builtin_amdgcn_s_barrier()
; #define PG8_SCHED __builtin_amdgcn_sched_barrier(0)
; template <class Epi, class Sched, bool ALIGN_EPI = false, bool SP2 = false, bool F16 = false>
; __device__ __forceinline__ void gemm_phase(PG8_LAS unsigned char* lds, const Gemm g, const Sched& S, const Epi& E, const int wid_in) {
;     ...
;             PG8_WAIT_V(8); PG8_WAIT_L(0); PG8_BAR; PG8_MMA(0, 0, At, B0); PG8_MMA(0, 1, At, B1); PG8_BAR; PG8_SCHED;
;             PG8_LDA(At, 1, 1); PG8_STAGE(PG8_SB(1, 0), b3, voffB); PG8_STAGE(PG8_SB(1, 1), b3 + hstep, voffB); PG8_STAGE(PG8_SA(1, 0), a3, voffA);
;             PG8_WAIT_V(8); PG8_WAIT_L(0); PG8_BAR; PG8_MMA(1, 0, At, B0); PG8_MMA(1, 1, At, B1); PG8_BAR; PG8_SCHED;
;     ...
;         if constexpr (ALIGN_EPI) { if (wr == 0) PG8_BAR; }
.Lgls_10:
	s_barrier
	s_setprio 1
	s_waitcnt lgkmcnt(0)
	v_mfma_f32_16x16x32_f16 v[132:135], v[16:19], v[176:179], v[132:135]
	v_mfma_f32_16x16x32_f16 v[128:131], v[136:139], v[176:179], v[128:131]
	v_mfma_f32_16x16x32_f16 v[116:119], v[16:19], v[184:187], v[116:119]
	v_mfma_f32_16x16x32_f16 v[112:115], v[136:139], v[184:187], v[112:115]
	v_mfma_f32_16x16x32_f16 v[100:103], v[16:19], v[202:205], v[100:103]
	v_mfma_f32_16x16x32_f16 v[96:99], v[136:139], v[202:205], v[96:99]
	v_mfma_f32_16x16x32_f16 v[84:87], v[16:19], v[210:213], v[84:87]
	v_mfma_f32_16x16x32_f16 v[80:83], v[136:139], v[210:213], v[80:83]
	v_mfma_f32_16x16x32_f16 v[132:135], v[20:23], v[180:183], v[132:135]
	v_mfma_f32_16x16x32_f16 v[128:131], v[140:143], v[180:183], v[128:131]
	v_mfma_f32_16x16x32_f16 v[116:119], v[20:23], v[198:201], v[116:119]
	v_mfma_f32_16x16x32_f16 v[112:115], v[140:143], v[198:201], v[112:115]
	v_mfma_f32_16x16x32_f16 v[100:103], v[20:23], v[206:209], v[100:103]
	v_mfma_f32_16x16x32_f16 v[96:99], v[140:143], v[206:209], v[96:99]
	v_mfma_f32_16x16x32_f16 v[84:87], v[20:23], v[214:217], v[84:87]
	v_mfma_f32_16x16x32_f16 v[80:83], v[140:143], v[214:217], v[80:83]
	s_setprio 0
	s_setprio 1
	v_mfma_f32_16x16x32_f16 v[124:127], v[144:147], v[176:179], v[124:127]
	v_mfma_f32_16x16x32_f16 v[120:123], v[152:155], v[176:179], v[120:123]
	v_mfma_f32_16x16x32_f16 v[108:111], v[144:147], v[184:187], v[108:111]
	v_mfma_f32_16x16x32_f16 v[104:107], v[152:155], v[184:187], v[104:107]
	v_mfma_f32_16x16x32_f16 v[92:95], v[144:147], v[202:205], v[92:95]
	v_mfma_f32_16x16x32_f16 v[88:91], v[152:155], v[202:205], v[88:91]
	v_mfma_f32_16x16x32_f16 v[76:79], v[144:147], v[210:213], v[76:79]
	v_mfma_f32_16x16x32_f16 v[72:75], v[152:155], v[210:213], v[72:75]
	v_mfma_f32_16x16x32_f16 v[124:127], v[148:151], v[180:183], v[124:127]
	v_mfma_f32_16x16x32_f16 v[120:123], v[156:159], v[180:183], v[120:123]
	v_mfma_f32_16x16x32_f16 v[108:111], v[148:151], v[198:201], v[108:111]
	v_mfma_f32_16x16x32_f16 v[104:107], v[156:159], v[198:201], v[104:107]
	v_mfma_f32_16x16x32_f16 v[92:95], v[148:151], v[206:209], v[92:95]
	v_mfma_f32_16x16x32_f16 v[88:91], v[156:159], v[206:209], v[88:91]
	v_mfma_f32_16x16x32_f16 v[76:79], v[148:151], v[214:217], v[76:79]
	v_mfma_f32_16x16x32_f16 v[72:75], v[156:159], v[214:217], v[72:75]
	s_setprio 0
	s_barrier
	s_add_i32 s44, s66, s68
	v_lshl_add_u64 v[188:189], v[188:189], 0, s[18:19]
	s_mov_b32 m0, s44
	ds_read_b128 v[176:179], v195 offset:49152
	ds_read_b128 v[180:183], v195 offset:50176
	ds_read_b128 v[184:187], v195 offset:51200
	ds_read_b128 v[198:201], v195 offset:52224
	ds_read_b128 v[202:205], v195 offset:53248
	ds_read_b128 v[206:209], v195 offset:54272
	ds_read_b128 v[210:213], v195 offset:55296
	ds_read_b128 v[214:217], v195 offset:56320
	global_load_lds_dwordx4 v[188:189], off
	s_add_i32 m0, s44, 0x2000
	s_add_u32 s36, s36, 0x40080
	v_lshl_add_u64 v[188:189], v[218:219], 0, s[18:19]
	s_addc_u32 s37, s37, 0
	s_add_i32 s44, s67, s68
	global_load_lds_dwordx4 v[188:189], off
	v_lshl_add_u64 v[188:189], s[36:37], 0, v[162:163]
	s_mov_b32 m0, s44
	s_nop 0
	global_load_lds_dwordx4 v[188:189], off
	v_lshl_add_u64 v[188:189], s[36:37], 0, v[166:167]
	s_add_i32 m0, s44, 0x2000
	s_nop 0
	global_load_lds_dwordx4 v[188:189], off
	v_lshl_add_u64 v[188:189], v[220:221], 0, s[18:19]
	s_mov_b32 m0, s75
	s_nop 0
	global_load_lds_dwordx4 v[188:189], off
	v_lshl_add_u64 v[188:189], v[222:223], 0, s[18:19]
	s_mov_b32 m0, s53
	s_nop 0
	global_load_lds_dwordx4 v[188:189], off
	s_waitcnt vmcnt(8)
	s_cmp_lt_u32 s3, 4
	s_cbranch_scc1 .Lgls_11
	s_waitcnt lgkmcnt(0)
.Lgls_11:
	s_barrier
	s_setprio 1
	s_waitcnt lgkmcnt(0)
	v_mfma_f32_16x16x32_f16 v[68:71], v[16:19], v[176:179], v[68:71]
	v_mfma_f32_16x16x32_f16 v[52:55], v[16:19], v[184:187], v[52:55]
	v_mfma_f32_16x16x32_f16 v[36:39], v[16:19], v[202:205], v[36:39]
	v_mfma_f32_16x16x32_f16 v[0:3], v[16:19], v[210:213], v[0:3]
	v_mfma_f32_16x16x32_f16 v[68:71], v[20:23], v[180:183], v[68:71]
	v_mfma_f32_16x16x32_f16 v[64:67], v[136:139], v[176:179], v[64:67]
	v_mfma_f32_16x16x32_f16 v[52:55], v[20:23], v[198:201], v[52:55]
	v_mfma_f32_16x16x32_f16 v[48:51], v[136:139], v[184:187], v[48:51]
	v_mfma_f32_16x16x32_f16 v[36:39], v[20:23], v[206:209], v[36:39]
	v_mfma_f32_16x16x32_f16 v[32:35], v[136:139], v[202:205], v[32:35]
	v_mfma_f32_16x16x32_f16 v[20:23], v[20:23], v[214:217], v[0:3]
	v_mfma_f32_16x16x32_f16 v[0:3], v[136:139], v[210:213], v[4:7]
	v_mfma_f32_16x16x32_f16 v[64:67], v[140:143], v[180:183], v[64:67]
	v_mfma_f32_16x16x32_f16 v[48:51], v[140:143], v[198:201], v[48:51]
	v_mfma_f32_16x16x32_f16 v[32:35], v[140:143], v[206:209], v[32:35]
	v_mfma_f32_16x16x32_f16 v[16:19], v[140:143], v[214:217], v[0:3]
	s_setprio 0
	s_setprio 1
	v_mfma_f32_16x16x32_f16 v[0:3], v[144:147], v[176:179], v[60:63]
	v_mfma_f32_16x16x32_f16 v[60:63], v[148:151], v[180:183], v[0:3]
	v_mfma_f32_16x16x32_f16 v[0:3], v[152:155], v[176:179], v[56:59]
	v_mfma_f32_16x16x32_f16 v[56:59], v[156:159], v[180:183], v[0:3]
	v_mfma_f32_16x16x32_f16 v[0:3], v[144:147], v[184:187], v[44:47]
	v_mfma_f32_16x16x32_f16 v[44:47], v[148:151], v[198:201], v[0:3]
	v_mfma_f32_16x16x32_f16 v[0:3], v[152:155], v[184:187], v[40:43]
	v_mfma_f32_16x16x32_f16 v[40:43], v[156:159], v[198:201], v[0:3]
	v_mfma_f32_16x16x32_f16 v[0:3], v[144:147], v[202:205], v[28:31]
	v_mfma_f32_16x16x32_f16 v[28:31], v[148:151], v[206:209], v[0:3]
	v_mfma_f32_16x16x32_f16 v[0:3], v[152:155], v[202:205], v[24:27]
	v_mfma_f32_16x16x32_f16 v[24:27], v[156:159], v[206:209], v[0:3]
	v_mfma_f32_16x16x32_f16 v[0:3], v[144:147], v[210:213], v[12:15]
	v_mfma_f32_16x16x32_f16 v[12:15], v[148:151], v[214:217], v[0:3]
	v_mfma_f32_16x16x32_f16 v[0:3], v[152:155], v[210:213], v[8:11]
	v_mfma_f32_16x16x32_f16 v[8:11], v[156:159], v[214:217], v[0:3]
	s_setprio 0
	s_barrier
	s_add_i32 s65, s65, 2
	s_add_u32 s34, s34, 0x100
	s_addc_u32 s35, s35, 0
	s_add_u32 s43, s43, 0x100
	s_addc_u32 s64, s64, 0
	s_cmp_gt_u32 s65, 13
	s_cbranch_scc0 .LBB0_585
	s_and_b64 vcc, exec, s[16:17]
	s_cbranch_vccz .LBB0_588
	s_barrier

; #define PG8_STAGE(bufoff, gbase, voff) do { _Pragma("unroll") for (int _i = 0; _i < 2; ++_i) \
;         __builtin_amdgcn_global_load_lds((const unsigned*)((const char*)(gbase) + (voff)[_i]), (PG8_LAS unsigned*)(lds + (bufoff) + ldsw + _i * 8192), 16, 0, 0); } while (0)
; #define PG8_LDA(dst, b, h) do { _Pragma("unroll") for (int m = 0; m < 4; ++m) _Pragma("unroll") for (int k = 0; k < 2; ++k) dst[m][k] = *(const PG8_LAS bf16x8*)(lds + PG8_SA(b, h) + aoff + m * 2048 + k * 1024); } while (0)
; #define PG8_LDB(dst, b, h) do { _Pragma("unroll") for (int n = 0; n < 2; ++n) _Pragma("unroll") for (int k = 0; k < 2; ++k) dst[n][k] = *(const PG8_LAS bf16x8*)(lds + PG8_SB(b, h) + boff + n * 2048 + k * 1024); } while (0)
; #define PG8_WAIT_V(n) asm volatile("s_waitcnt vmcnt(" #n ")" ::: "memory")
; #define PG8_WAIT_L(n) asm volatile("s_waitcnt lgkmcnt(" #n ")" ::: "memory")
; #define PG8_BAR __builtin_amdgcn_s_barrier()
; #define PG8_SCHED __builtin_amdgcn_sched_barrier(0)
; template <class Epi, class Sched, bool ALIGN_EPI = false, bool SP2 = false, bool F16 = false>
; __device__ __forceinline__ void gemm_phase(PG8_LAS unsigned char* lds, const Gemm g, const Sched& S, const Epi& E, const int wid_in) {
;     ...
;         const bool has_next = S.next(ui + 1, nxt);
;         const char* nA = has_next ? (const char*)g.A + (size_t)nxt.pm * tstep : cA; const char* nB = has_next ? (const char*)g.Bt + (size_t)nxt.pn * tstep : cB;
;         for (int t = 0; t < nt; t += 2) {
;             const bool last = (t == nt - 2);
;             const char* a1 = cA + (size_t)(t + 1) * kstep;
;             const char* a2 = last ? nA : cA + (size_t)(t + 2) * kstep; const char* b2 = last ? nB : cB + (size_t)(t + 2) * kstep;
;             const char* a3 = a2 + kstep; const char* b3 = b2 + kstep;
;             if (last && has_next) S.a_ready(nxt);
;             if constexpr (SP2) {
;             PG8_LDB(B0, 0, 0); PG8_LDB(B1, 0, 1); PG8_SCHED; PG8_LDA(At, 0, 0); PG8_STAGE(PG8_SA(1, 1), a1 + hstep, voffA);
;             PG8_WAIT_V(8); PG8_WAIT_L(0); PG8_BAR; PG8_MMA(0, 0, At, B0); PG8_MMA(0, 1, At, B1); PG8_BAR; PG8_SCHED;
;             PG8_LDA(At, 0, 1); PG8_STAGE(PG8_SB(0, 0), b2, voffB); PG8_STAGE(PG8_SB(0, 1), b2 + hstep, voffB); PG8_STAGE(PG8_SA(0, 0), a2, voffA);
;             PG8_WAIT_V(8); PG8_WAIT_L(0); PG8_BAR; PG8_MMA(1, 0, At, B0); PG8_MMA(1, 1, At, B1); PG8_BAR; PG8_SCHED;
.LBB0_620:
	s_mov_b64 s[44:45], s[10:11]
	s_add_i32 s10, s30, s40
	s_mov_b64 s[36:37], s[12:13]
	s_mov_b32 s12, s62
	s_mov_b32 s13, s61
	s_and_b32 s61, s10, 3
	s_ashr_i32 s62, s10, 2
	s_and_b64 s[10:11], s[26:27], exec
	s_cselect_b32 s12, s62, s12
	ds_read_b128 v[0:3], v134
	ds_read_b128 v[4:7], v134 offset:1024
	ds_read_b128 v[8:11], v134 offset:2048
	ds_read_b128 v[12:15], v134 offset:3072
	ds_read_b128 v[16:19], v135
	ds_read_b128 v[20:23], v135 offset:1024
	ds_read_b128 v[24:27], v135 offset:2048
	ds_read_b128 v[28:31], v135 offset:3072
	s_cselect_b32 s10, s61, s13
	s_ashr_i32 s13, s12, 31
	s_lshl_b64 s[12:13], s[12:13], 17
	s_add_u32 s12, s43, s12
	s_addc_u32 s13, s46, s13
	s_and_b64 s[30:31], s[26:27], exec
	s_cselect_b32 s35, s13, s37
	s_cselect_b32 s34, s12, s36
	s_ashr_i32 s11, s10, 31
	s_lshl_b64 s[10:11], s[10:11], 17
	s_add_u32 s10, s41, s10
	s_addc_u32 s11, s42, s11
	s_and_b64 s[30:31], s[26:27], exec
	s_cselect_b32 s31, s11, s45
	s_cselect_b32 s30, s10, s44
	s_add_u32 s64, s36, 0x10080
	s_addc_u32 s65, s37, 0
	s_mov_b32 m0, s15
	v_lshl_add_u64 v[64:65], s[64:65], 0, v[130:131]
	ds_read_b128 v[32:35], v136
	ds_read_b128 v[36:39], v136 offset:1024
	ds_read_b128 v[40:43], v136 offset:2048
	ds_read_b128 v[44:47], v136 offset:3072
	ds_read_b128 v[48:51], v136 offset:4096
	ds_read_b128 v[52:55], v136 offset:5120
	ds_read_b128 v[56:59], v136 offset:6144
	ds_read_b128 v[60:63], v136 offset:7168
	global_load_lds_dwordx4 v[64:65], off
	v_lshl_add_u64 v[64:65], s[64:65], 0, v[128:129]
	s_mov_b32 m0, s50
	s_nop 0
	global_load_lds_dwordx4 v[64:65], off
	s_waitcnt vmcnt(8)
	s_cmp_lt_u32 s3, 4
	s_cbranch_scc1 .Lgls_12
	s_waitcnt lgkmcnt(0)
.Lgls_12:
	s_barrier
	s_setprio 1
	s_waitcnt lgkmcnt(0)
	v_mfma_f32_16x16x32_bf16 v[64:67], v[0:3], v[32:35], 0
	v_mfma_f32_16x16x32_bf16 v[68:71], v[8:11], v[32:35], 0
	v_mfma_f32_16x16x32_bf16 v[72:75], v[0:3], v[40:43], 0
	v_mfma_f32_16x16x32_bf16 v[76:79], v[8:11], v[40:43], 0
	v_mfma_f32_16x16x32_bf16 v[80:83], v[0:3], v[48:51], 0
	v_mfma_f32_16x16x32_bf16 v[84:87], v[8:11], v[48:51], 0
	v_mfma_f32_16x16x32_bf16 v[88:91], v[0:3], v[56:59], 0
	v_mfma_f32_16x16x32_bf16 v[92:95], v[8:11], v[56:59], 0
	v_mfma_f32_16x16x32_bf16 v[64:67], v[4:7], v[36:39], v[64:67]
	v_mfma_f32_16x16x32_bf16 v[68:71], v[12:15], v[36:39], v[68:71]
	v_mfma_f32_16x16x32_bf16 v[72:75], v[4:7], v[44:47], v[72:75]
	v_mfma_f32_16x16x32_bf16 v[76:79], v[12:15], v[44:47], v[76:79]
	v_mfma_f32_16x16x32_bf16 v[80:83], v[4:7], v[52:55], v[80:83]
	v_mfma_f32_16x16x32_bf16 v[84:87], v[12:15], v[52:55], v[84:87]
	v_mfma_f32_16x16x32_bf16 v[88:91], v[4:7], v[60:63], v[88:91]
	v_mfma_f32_16x16x32_bf16 v[92:95], v[12:15], v[60:63], v[92:95]
	s_setprio 0
	s_setprio 1
	v_mfma_f32_16x16x32_bf16 v[96:99], v[16:19], v[32:35], 0
	v_mfma_f32_16x16x32_bf16 v[32:35], v[24:27], v[32:35], 0
	v_mfma_f32_16x16x32_bf16 v[96:99], v[20:23], v[36:39], v[96:99]
	v_mfma_f32_16x16x32_bf16 v[32:35], v[28:31], v[36:39], v[32:35]
	v_mfma_f32_16x16x32_bf16 v[36:39], v[16:19], v[40:43], 0
	v_mfma_f32_16x16x32_bf16 v[40:43], v[24:27], v[40:43], 0
	v_mfma_f32_16x16x32_bf16 v[36:39], v[20:23], v[44:47], v[36:39]
	v_mfma_f32_16x16x32_bf16 v[40:43], v[28:31], v[44:47], v[40:43]
	v_mfma_f32_16x16x32_bf16 v[44:47], v[16:19], v[48:51], 0
	v_mfma_f32_16x16x32_bf16 v[48:51], v[24:27], v[48:51], 0
	v_mfma_f32_16x16x32_bf16 v[44:47], v[20:23], v[52:55], v[44:47]
	v_mfma_f32_16x16x32_bf16 v[48:51], v[28:31], v[52:55], v[48:51]
	v_mfma_f32_16x16x32_bf16 v[52:55], v[16:19], v[56:59], 0
	v_mfma_f32_16x16x32_bf16 v[56:59], v[24:27], v[56:59], 0
	v_mfma_f32_16x16x32_bf16 v[52:55], v[20:23], v[60:63], v[52:55]
	v_mfma_f32_16x16x32_bf16 v[56:59], v[28:31], v[60:63], v[56:59]
	s_setprio 0
	s_barrier
	v_lshl_add_u64 v[204:205], s[44:45], 0, v[130:131]
	s_mov_b32 m0, s51
	v_lshl_add_u64 v[140:141], v[204:205], 0, s[22:23]
	v_lshl_add_u64 v[206:207], s[44:45], 0, v[128:129]
	s_add_u32 s64, s44, 0x10100
	ds_read_b128 v[60:63], v136 offset:16384
	ds_read_b128 v[100:103], v136 offset:17408
	ds_read_b128 v[104:107], v136 offset:18432
	ds_read_b128 v[108:111], v136 offset:19456
	ds_read_b128 v[112:115], v136 offset:20480
	ds_read_b128 v[116:119], v136 offset:21504
	ds_read_b128 v[120:123], v136 offset:22528
	ds_read_b128 v[124:127], v136 offset:23552
	global_load_lds_dwordx4 v[140:141], off
	v_lshl_add_u64 v[140:141], v[206:207], 0, s[22:23]
	s_mov_b32 m0, s52
	s_addc_u32 s65, s45, 0
	global_load_lds_dwordx4 v[140:141], off
	v_lshl_add_u64 v[140:141], s[64:65], 0, v[130:131]
	s_mov_b32 m0, s53
	v_lshl_add_u64 v[208:209], s[36:37], 0, v[130:131]
	global_load_lds_dwordx4 v[140:141], off
	v_lshl_add_u64 v[140:141], s[64:65], 0, v[128:129]
	s_mov_b32 m0, s54
	v_lshl_add_u64 v[210:211], s[36:37], 0, v[128:129]
	global_load_lds_dwordx4 v[140:141], off
	v_lshl_add_u64 v[140:141], v[208:209], 0, s[22:23]
	s_mov_b32 m0, s74
	s_nop 0
	global_load_lds_dwordx4 v[140:141], off
	v_lshl_add_u64 v[140:141], v[210:211], 0, s[22:23]
	s_mov_b32 m0, s47
	s_nop 0
	global_load_lds_dwordx4 v[140:141], off
	s_waitcnt vmcnt(8)
	s_cmp_lt_u32 s3, 4
	s_cbranch_scc1 .Lgls_13
	s_waitcnt lgkmcnt(0)
; #define PG8_STAGE(bufoff, gbase, voff) do { _Pragma("unroll") for (int _i = 0; _i < 2; ++_i) \
;         __builtin_amdgcn_global_load_lds((const unsigned*)((const char*)(gbase) + (voff)[_i]), (PG8_LAS unsigned*)(lds + (bufoff) + ldsw + _i * 8192), 16, 0, 0); } while (0)
; #define PG8_LDA(dst, b, h) do { _Pragma("unroll") for (int m = 0; m < 4; ++m) _Pragma("unroll") for (int k = 0; k < 2; ++k) dst[m][k] = *(const PG8_LAS bf16x8*)(lds + PG8_SA(b, h) + aoff + m * 2048 + k * 1024); } while (0)
; #define PG8_LDB(dst, b, h) do { _Pragma("unroll") for (int n = 0; n < 2; ++n) _Pragma("unroll") for (int k = 0; k < 2; ++k) dst[n][k] = *(const PG8_LAS bf16x8*)(lds + PG8_SB(b, h) + boff + n * 2048 + k * 1024); } while (0)
; #define PG8_MMA(ai, bj, At, Bt) do { __builtin_amdgcn_s_setprio(1); _Pragma("unroll") for (int m = 0; m < 4; ++m) _Pragma("unroll") for (int n = 0; n < 2; ++n) _Pragma("unroll") for (int k = 0; k < 2; ++k) \
;         acc[ai][bj][m][n] = mma16<F16>(Bt[n][k], At[m][k], acc[ai][bj][m][n]); __builtin_amdgcn_s_setprio(0); } while (0)
; #define PG8_WAIT_V(n) asm volatile("s_waitcnt vmcnt(" #n ")" ::: "memory")
; #define PG8_WAIT_L(n) asm volatile("s_waitcnt lgkmcnt(" #n ")" ::: "memory")
; #define PG8_BAR __builtin_amdgcn_s_barrier()
; #define PG8_SCHED __builtin_amdgcn_sched_barrier(0)
; template <class Epi, class Sched, bool ALIGN_EPI = false, bool SP2 = false, bool F16 = false>
; __device__ __forceinline__ void gemm_phase(PG8_LAS unsigned char* lds, const Gemm g, const Sched& S, const Epi& E, const int wid_in) {
;     ...
;             PG8_WAIT_V(8); PG8_WAIT_L(0); PG8_BAR; PG8_MMA(1, 0, At, B0); PG8_MMA(1, 1, At, B1); PG8_BAR; PG8_SCHED;
;             PG8_LDB(B0, 1, 0); PG8_LDB(B1, 1, 1); PG8_SCHED; PG8_LDA(At, 1, 0); PG8_STAGE(PG8_SA(0, 1), a2 + hstep, voffA);
;             PG8_WAIT_V(8); PG8_WAIT_L(0); PG8_BAR; PG8_MMA(0, 0, At, B0); PG8_MMA(0, 1, At, B1); PG8_BAR; PG8_SCHED;
;             PG8_LDA(At, 1, 1); PG8_STAGE(PG8_SB(1, 0), b3, voffB); PG8_STAGE(PG8_SB(1, 1), b3 + hstep, voffB); PG8_STAGE(PG8_SA(1, 0), a3, voffA);
;             PG8_WAIT_V(8); PG8_WAIT_L(0); PG8_BAR; PG8_MMA(1, 0, At, B0); PG8_MMA(1, 1, At, B1); PG8_BAR; PG8_SCHED;
.Lgls_13:
	s_barrier
	s_setprio 1
	s_waitcnt lgkmcnt(0)
	v_mfma_f32_16x16x32_bf16 v[140:143], v[0:3], v[60:63], 0
	v_mfma_f32_16x16x32_bf16 v[148:151], v[0:3], v[104:107], 0
	v_mfma_f32_16x16x32_bf16 v[156:159], v[0:3], v[112:115], 0
	v_mfma_f32_16x16x32_bf16 v[0:3], v[0:3], v[120:123], 0
	v_mfma_f32_16x16x32_bf16 v[140:143], v[4:7], v[100:103], v[140:143]
	v_mfma_f32_16x16x32_bf16 v[148:151], v[4:7], v[108:111], v[148:151]
	v_mfma_f32_16x16x32_bf16 v[156:159], v[4:7], v[116:119], v[156:159]
	v_mfma_f32_16x16x32_bf16 v[0:3], v[4:7], v[124:127], v[0:3]
	v_mfma_f32_16x16x32_bf16 v[4:7], v[8:11], v[120:123], 0
	v_mfma_f32_16x16x32_bf16 v[144:147], v[8:11], v[60:63], 0
	v_mfma_f32_16x16x32_bf16 v[152:155], v[8:11], v[104:107], 0
	v_mfma_f32_16x16x32_bf16 v[160:163], v[8:11], v[112:115], 0
	v_mfma_f32_16x16x32_bf16 v[4:7], v[12:15], v[124:127], v[4:7]
	v_mfma_f32_16x16x32_bf16 v[144:147], v[12:15], v[100:103], v[144:147]
	v_mfma_f32_16x16x32_bf16 v[152:155], v[12:15], v[108:111], v[152:155]
	v_mfma_f32_16x16x32_bf16 v[160:163], v[12:15], v[116:119], v[160:163]
	s_setprio 0
	s_setprio 1
	v_mfma_f32_16x16x32_bf16 v[8:11], v[16:19], v[60:63], 0
	v_mfma_f32_16x16x32_bf16 v[12:15], v[24:27], v[60:63], 0
	v_mfma_f32_16x16x32_bf16 v[8:11], v[20:23], v[100:103], v[8:11]
	v_mfma_f32_16x16x32_bf16 v[12:15], v[28:31], v[100:103], v[12:15]
	v_mfma_f32_16x16x32_bf16 v[60:63], v[16:19], v[104:107], 0
	v_mfma_f32_16x16x32_bf16 v[100:103], v[24:27], v[104:107], 0
	v_mfma_f32_16x16x32_bf16 v[104:107], v[16:19], v[112:115], 0
	v_mfma_f32_16x16x32_bf16 v[16:19], v[16:19], v[120:123], 0
	v_mfma_f32_16x16x32_bf16 v[60:63], v[20:23], v[108:111], v[60:63]
	v_mfma_f32_16x16x32_bf16 v[100:103], v[28:31], v[108:111], v[100:103]
	v_mfma_f32_16x16x32_bf16 v[104:107], v[20:23], v[116:119], v[104:107]
	v_mfma_f32_16x16x32_bf16 v[108:111], v[24:27], v[112:115], 0
	v_mfma_f32_16x16x32_bf16 v[16:19], v[20:23], v[124:127], v[16:19]
	v_mfma_f32_16x16x32_bf16 v[20:23], v[24:27], v[120:123], 0
	v_mfma_f32_16x16x32_bf16 v[108:111], v[28:31], v[116:119], v[108:111]
	v_mfma_f32_16x16x32_bf16 v[20:23], v[28:31], v[124:127], v[20:23]
	s_setprio 0
	s_barrier
	ds_read_b128 v[24:27], v137
	ds_read_b128 v[28:31], v137 offset:1024
	ds_read_b128 v[112:115], v137 offset:2048
	ds_read_b128 v[116:119], v137 offset:3072
	ds_read_b128 v[120:123], v138
	ds_read_b128 v[124:127], v138 offset:1024
	ds_read_b128 v[164:167], v138 offset:2048
	ds_read_b128 v[168:171], v138 offset:3072
	s_add_u32 s64, s36, 0x10100
	s_addc_u32 s65, s37, 0
	s_mov_b32 m0, s48
	v_lshl_add_u64 v[212:213], s[64:65], 0, v[130:131]
	ds_read_b128 v[172:175], v136 offset:32768
	ds_read_b128 v[176:179], v136 offset:33792
	ds_read_b128 v[180:183], v136 offset:34816
	ds_read_b128 v[184:187], v136 offset:35840
	ds_read_b128 v[188:191], v136 offset:36864
	ds_read_b128 v[192:195], v136 offset:37888
	ds_read_b128 v[196:199], v136 offset:38912
	ds_read_b128 v[200:203], v136 offset:39936
	global_load_lds_dwordx4 v[212:213], off
	v_lshl_add_u64 v[212:213], s[64:65], 0, v[128:129]
	s_mov_b32 m0, s49
	s_nop 0
	global_load_lds_dwordx4 v[212:213], off
	s_waitcnt vmcnt(8)
	s_cmp_lt_u32 s3, 4
	s_cbranch_scc1 .Lgls_14
	s_waitcnt lgkmcnt(0)
.Lgls_14:
	s_barrier
	s_setprio 1
	s_waitcnt lgkmcnt(0)
	v_mfma_f32_16x16x32_bf16 v[64:67], v[24:27], v[172:175], v[64:67]
	v_mfma_f32_16x16x32_bf16 v[68:71], v[112:115], v[172:175], v[68:71]
	v_mfma_f32_16x16x32_bf16 v[72:75], v[24:27], v[180:183], v[72:75]
	v_mfma_f32_16x16x32_bf16 v[76:79], v[112:115], v[180:183], v[76:79]
	v_mfma_f32_16x16x32_bf16 v[80:83], v[24:27], v[188:191], v[80:83]
	v_mfma_f32_16x16x32_bf16 v[84:87], v[112:115], v[188:191], v[84:87]
	v_mfma_f32_16x16x32_bf16 v[88:91], v[24:27], v[196:199], v[88:91]
	v_mfma_f32_16x16x32_bf16 v[92:95], v[112:115], v[196:199], v[92:95]
	v_mfma_f32_16x16x32_bf16 v[64:67], v[28:31], v[176:179], v[64:67]
	v_mfma_f32_16x16x32_bf16 v[68:71], v[116:119], v[176:179], v[68:71]
	v_mfma_f32_16x16x32_bf16 v[72:75], v[28:31], v[184:187], v[72:75]
	v_mfma_f32_16x16x32_bf16 v[76:79], v[116:119], v[184:187], v[76:79]
	v_mfma_f32_16x16x32_bf16 v[80:83], v[28:31], v[192:195], v[80:83]
	v_mfma_f32_16x16x32_bf16 v[84:87], v[116:119], v[192:195], v[84:87]
	v_mfma_f32_16x16x32_bf16 v[88:91], v[28:31], v[200:203], v[88:91]
	v_mfma_f32_16x16x32_bf16 v[92:95], v[116:119], v[200:203], v[92:95]
	s_setprio 0
	s_setprio 1
	v_mfma_f32_16x16x32_bf16 v[96:99], v[120:123], v[172:175], v[96:99]
	v_mfma_f32_16x16x32_bf16 v[32:35], v[164:167], v[172:175], v[32:35]
	v_mfma_f32_16x16x32_bf16 v[36:39], v[120:123], v[180:183], v[36:39]
	v_mfma_f32_16x16x32_bf16 v[40:43], v[164:167], v[180:183], v[40:43]
	v_mfma_f32_16x16x32_bf16 v[44:47], v[120:123], v[188:191], v[44:47]
	v_mfma_f32_16x16x32_bf16 v[48:51], v[164:167], v[188:191], v[48:51]
	v_mfma_f32_16x16x32_bf16 v[52:55], v[120:123], v[196:199], v[52:55]
	v_mfma_f32_16x16x32_bf16 v[56:59], v[164:167], v[196:199], v[56:59]
	v_mfma_f32_16x16x32_bf16 v[96:99], v[124:127], v[176:179], v[96:99]
	v_mfma_f32_16x16x32_bf16 v[32:35], v[168:171], v[176:179], v[32:35]
	v_mfma_f32_16x16x32_bf16 v[36:39], v[124:127], v[184:187], v[36:39]
	v_mfma_f32_16x16x32_bf16 v[40:43], v[168:171], v[184:187], v[40:43]
	v_mfma_f32_16x16x32_bf16 v[44:47], v[124:127], v[192:195], v[44:47]
	v_mfma_f32_16x16x32_bf16 v[48:51], v[168:171], v[192:195], v[48:51]
	v_mfma_f32_16x16x32_bf16 v[52:55], v[124:127], v[200:203], v[52:55]
	v_mfma_f32_16x16x32_bf16 v[56:59], v[168:171], v[200:203], v[56:59]
	s_setprio 0
	s_barrier
	s_mov_b32 m0, s55
	v_lshl_add_u64 v[204:205], v[204:205], 0, s[24:25]
	s_add_u32 s44, s44, 0x10180
	ds_read_b128 v[172:175], v136 offset:49152
	ds_read_b128 v[176:179], v136 offset:50176
	ds_read_b128 v[180:183], v136 offset:51200
	ds_read_b128 v[184:187], v136 offset:52224
	ds_read_b128 v[188:191], v136 offset:53248
	ds_read_b128 v[192:195], v136 offset:54272
	ds_read_b128 v[196:199], v136 offset:55296
	ds_read_b128 v[200:203], v136 offset:56320
	global_load_lds_dwordx4 v[204:205], off
	v_lshl_add_u64 v[204:205], v[206:207], 0, s[24:25]
	s_mov_b32 m0, s58
	s_addc_u32 s45, s45, 0
	global_load_lds_dwordx4 v[204:205], off
	v_lshl_add_u64 v[204:205], s[44:45], 0, v[130:131]
	s_mov_b32 m0, s59
	s_nop 0
	global_load_lds_dwordx4 v[204:205], off
	v_lshl_add_u64 v[204:205], s[44:45], 0, v[128:129]
	s_mov_b32 m0, s60
	s_nop 0
	global_load_lds_dwordx4 v[204:205], off
	v_lshl_add_u64 v[204:205], v[208:209], 0, s[24:25]
	s_mov_b32 m0, s75
	s_nop 0
	global_load_lds_dwordx4 v[204:205], off
	v_lshl_add_u64 v[204:205], v[210:211], 0, s[24:25]
	s_mov_b32 m0, s14
	s_nop 0
	global_load_lds_dwordx4 v[204:205], off
	s_waitcnt vmcnt(8)
	s_cmp_lt_u32 s3, 4
	s_cbranch_scc1 .Lgls_15
	s_waitcnt lgkmcnt(0)
; #define PG8_STAGE(bufoff, gbase, voff) do { _Pragma("unroll") for (int _i = 0; _i < 2; ++_i) \
;         __builtin_amdgcn_global_load_lds((const unsigned*)((const char*)(gbase) + (voff)[_i]), (PG8_LAS unsigned*)(lds + (bufoff) + ldsw + _i * 8192), 16, 0, 0); } while (0)
; #define PG8_LDA(dst, b, h) do { _Pragma("unroll") for (int m = 0; m < 4; ++m) _Pragma("unroll") for (int k = 0; k < 2; ++k) dst[m][k] = *(const PG8_LAS bf16x8*)(lds + PG8_SA(b, h) + aoff + m * 2048 + k * 1024); } while (0)
; #define PG8_LDB(dst, b, h) do { _Pragma("unroll") for (int n = 0; n < 2; ++n) _Pragma("unroll") for (int k = 0; k < 2; ++k) dst[n][k] = *(const PG8_LAS bf16x8*)(lds + PG8_SB(b, h) + boff + n * 2048 + k * 1024); } while (0)
; #define PG8_MMA(ai, bj, At, Bt) do { __builtin_amdgcn_s_setprio(1); _Pragma("unroll") for (int m = 0; m < 4; ++m) _Pragma("unroll") for (int n = 0; n < 2; ++n) _Pragma("unroll") for (int k = 0; k < 2; ++k) \
;         acc[ai][bj][m][n] = mma16<F16>(Bt[n][k], At[m][k], acc[ai][bj][m][n]); __builtin_amdgcn_s_setprio(0); } while (0)
; #define PG8_WAIT_V(n) asm volatile("s_waitcnt vmcnt(" #n ")" ::: "memory")
; template <class Epi, class Sched, bool ALIGN_EPI = false, bool SP2 = false, bool F16 = false>
; __device__ __forceinline__ void gemm_phase(PG8_LAS unsigned char* lds, const Gemm g, const Sched& S, const Epi& E, const int wid_in) {
;     ...
;             PG8_LDB(B0, 0, 0); PG8_LDB(B1, 0, 1); PG8_SCHED; PG8_LDA(At, 0, 0); PG8_STAGE(PG8_SA(1, 1), a1 + hstep, voffA);
;             PG8_WAIT_V(8); PG8_WAIT_L(0); PG8_BAR; PG8_MMA(0, 0, At, B0); PG8_MMA(0, 1, At, B1); PG8_BAR; PG8_SCHED;
;             PG8_LDA(At, 0, 1); PG8_STAGE(PG8_SB(0, 0), b2, voffB); PG8_STAGE(PG8_SB(0, 1), b2 + hstep, voffB); PG8_STAGE(PG8_SA(0, 0), a2, voffA);
;             PG8_WAIT_V(8); PG8_WAIT_L(0); PG8_BAR; PG8_MMA(1, 0, At, B0); PG8_MMA(1, 1, At, B1); PG8_BAR; PG8_SCHED;
;             PG8_LDB(B0, 1, 0); PG8_LDB(B1, 1, 1); PG8_SCHED; PG8_LDA(At, 1, 0); PG8_STAGE(PG8_SA(0, 1), a2 + hstep, voffA);
;             PG8_WAIT_V(8); PG8_WAIT_L(0); PG8_BAR; PG8_MMA(0, 0, At, B0); PG8_MMA(0, 1, At, B1); PG8_BAR; PG8_SCHED;
;             PG8_LDA(At, 1, 1); PG8_STAGE(PG8_SB(1, 0), b3, voffB); PG8_STAGE(PG8_SB(1, 1), b3 + hstep, voffB); PG8_STAGE(PG8_SA(1, 0), a3, voffA);
;             PG8_WAIT_V(8); PG8_WAIT_L(0); PG8_BAR; PG8_MMA(1, 0, At, B0); PG8_MMA(1, 1, At, B1); PG8_BAR; PG8_SCHED;
.Lgls_15:
	s_barrier
	s_setprio 1
	s_waitcnt lgkmcnt(0)
	v_mfma_f32_16x16x32_bf16 v[0:3], v[24:27], v[196:199], v[0:3]
	v_mfma_f32_16x16x32_bf16 v[4:7], v[112:115], v[196:199], v[4:7]
	v_mfma_f32_16x16x32_bf16 v[140:143], v[24:27], v[172:175], v[140:143]
	v_mfma_f32_16x16x32_bf16 v[144:147], v[112:115], v[172:175], v[144:147]
	v_mfma_f32_16x16x32_bf16 v[148:151], v[24:27], v[180:183], v[148:151]
	v_mfma_f32_16x16x32_bf16 v[152:155], v[112:115], v[180:183], v[152:155]
	v_mfma_f32_16x16x32_bf16 v[156:159], v[24:27], v[188:191], v[156:159]
	v_mfma_f32_16x16x32_bf16 v[160:163], v[112:115], v[188:191], v[160:163]
	v_mfma_f32_16x16x32_bf16 v[0:3], v[28:31], v[200:203], v[0:3]
	v_mfma_f32_16x16x32_bf16 v[4:7], v[116:119], v[200:203], v[4:7]
	v_mfma_f32_16x16x32_bf16 v[140:143], v[28:31], v[176:179], v[140:143]
	v_mfma_f32_16x16x32_bf16 v[144:147], v[116:119], v[176:179], v[144:147]
	v_mfma_f32_16x16x32_bf16 v[148:151], v[28:31], v[184:187], v[148:151]
	v_mfma_f32_16x16x32_bf16 v[152:155], v[116:119], v[184:187], v[152:155]
	v_mfma_f32_16x16x32_bf16 v[156:159], v[28:31], v[192:195], v[156:159]
	v_mfma_f32_16x16x32_bf16 v[160:163], v[116:119], v[192:195], v[160:163]
	s_setprio 0
	s_setprio 1
	v_mfma_f32_16x16x32_bf16 v[8:11], v[120:123], v[172:175], v[8:11]
	v_mfma_f32_16x16x32_bf16 v[12:15], v[164:167], v[172:175], v[12:15]
	v_mfma_f32_16x16x32_bf16 v[24:27], v[120:123], v[180:183], v[60:63]
	v_mfma_f32_16x16x32_bf16 v[28:31], v[164:167], v[180:183], v[100:103]
	v_mfma_f32_16x16x32_bf16 v[60:63], v[120:123], v[188:191], v[104:107]
	v_mfma_f32_16x16x32_bf16 v[100:103], v[164:167], v[188:191], v[108:111]
	v_mfma_f32_16x16x32_bf16 v[16:19], v[120:123], v[196:199], v[16:19]
	v_mfma_f32_16x16x32_bf16 v[20:23], v[164:167], v[196:199], v[20:23]
	v_mfma_f32_16x16x32_bf16 v[8:11], v[124:127], v[176:179], v[8:11]
	v_mfma_f32_16x16x32_bf16 v[12:15], v[168:171], v[176:179], v[12:15]
	v_mfma_f32_16x16x32_bf16 v[24:27], v[124:127], v[184:187], v[24:27]
	v_mfma_f32_16x16x32_bf16 v[28:31], v[168:171], v[184:187], v[28:31]
	v_mfma_f32_16x16x32_bf16 v[60:63], v[124:127], v[192:195], v[60:63]
	v_mfma_f32_16x16x32_bf16 v[100:103], v[168:171], v[192:195], v[100:103]
	v_mfma_f32_16x16x32_bf16 v[16:19], v[124:127], v[200:203], v[16:19]
	v_mfma_f32_16x16x32_bf16 v[20:23], v[168:171], v[200:203], v[20:23]
	s_setprio 0
	s_barrier
	ds_read_b128 v[104:107], v134
	ds_read_b128 v[108:111], v134 offset:1024
	ds_read_b128 v[112:115], v134 offset:2048
	ds_read_b128 v[116:119], v134 offset:3072
	ds_read_b128 v[120:123], v135
	ds_read_b128 v[124:127], v135 offset:1024
	ds_read_b128 v[164:167], v135 offset:2048
	ds_read_b128 v[168:171], v135 offset:3072
	s_add_u32 s36, s36, 0x10180
	s_addc_u32 s37, s37, 0
	s_mov_b32 m0, s15
	v_lshl_add_u64 v[204:205], s[36:37], 0, v[130:131]
	ds_read_b128 v[172:175], v136
	ds_read_b128 v[176:179], v136 offset:1024
	ds_read_b128 v[180:183], v136 offset:2048
	ds_read_b128 v[184:187], v136 offset:3072
	ds_read_b128 v[188:191], v136 offset:4096
	ds_read_b128 v[192:195], v136 offset:5120
	ds_read_b128 v[196:199], v136 offset:6144
	ds_read_b128 v[200:203], v136 offset:7168
	global_load_lds_dwordx4 v[204:205], off
	v_lshl_add_u64 v[204:205], s[36:37], 0, v[128:129]
	s_mov_b32 m0, s50
	s_nop 0
	global_load_lds_dwordx4 v[204:205], off
	s_waitcnt vmcnt(8)
	s_cmp_lt_u32 s3, 4
	s_cbranch_scc1 .Lgls_16
	s_waitcnt lgkmcnt(0)
.Lgls_16:
	s_barrier
	s_setprio 1
	s_waitcnt lgkmcnt(0)
	v_mfma_f32_16x16x32_bf16 v[64:67], v[104:107], v[172:175], v[64:67]
	v_mfma_f32_16x16x32_bf16 v[68:71], v[112:115], v[172:175], v[68:71]
	v_mfma_f32_16x16x32_bf16 v[72:75], v[104:107], v[180:183], v[72:75]
	v_mfma_f32_16x16x32_bf16 v[76:79], v[112:115], v[180:183], v[76:79]
	v_mfma_f32_16x16x32_bf16 v[80:83], v[104:107], v[188:191], v[80:83]
	v_mfma_f32_16x16x32_bf16 v[84:87], v[112:115], v[188:191], v[84:87]
	v_mfma_f32_16x16x32_bf16 v[88:91], v[104:107], v[196:199], v[88:91]
	v_mfma_f32_16x16x32_bf16 v[92:95], v[112:115], v[196:199], v[92:95]
	v_mfma_f32_16x16x32_bf16 v[64:67], v[108:111], v[176:179], v[64:67]
	v_mfma_f32_16x16x32_bf16 v[68:71], v[116:119], v[176:179], v[68:71]
	v_mfma_f32_16x16x32_bf16 v[72:75], v[108:111], v[184:187], v[72:75]
	v_mfma_f32_16x16x32_bf16 v[76:79], v[116:119], v[184:187], v[76:79]
	v_mfma_f32_16x16x32_bf16 v[80:83], v[108:111], v[192:195], v[80:83]
	v_mfma_f32_16x16x32_bf16 v[84:87], v[116:119], v[192:195], v[84:87]
	v_mfma_f32_16x16x32_bf16 v[88:91], v[108:111], v[200:203], v[88:91]
	v_mfma_f32_16x16x32_bf16 v[92:95], v[116:119], v[200:203], v[92:95]
	s_setprio 0
	s_setprio 1
	v_mfma_f32_16x16x32_bf16 v[32:35], v[164:167], v[172:175], v[32:35]
	v_mfma_f32_16x16x32_bf16 v[96:99], v[120:123], v[172:175], v[96:99]
	v_mfma_f32_16x16x32_bf16 v[172:175], v[168:171], v[176:179], v[32:35]
	v_mfma_f32_16x16x32_bf16 v[32:35], v[120:123], v[180:183], v[36:39]
	v_mfma_f32_16x16x32_bf16 v[204:207], v[124:127], v[176:179], v[96:99]
	v_mfma_f32_16x16x32_bf16 v[176:179], v[124:127], v[184:187], v[32:35]
	v_mfma_f32_16x16x32_bf16 v[32:35], v[164:167], v[180:183], v[40:43]
	v_mfma_f32_16x16x32_bf16 v[40:43], v[168:171], v[184:187], v[32:35]
	v_mfma_f32_16x16x32_bf16 v[32:35], v[120:123], v[188:191], v[44:47]
	v_mfma_f32_16x16x32_bf16 v[44:47], v[124:127], v[192:195], v[32:35]
	v_mfma_f32_16x16x32_bf16 v[32:35], v[164:167], v[188:191], v[48:51]
	v_mfma_f32_16x16x32_bf16 v[48:51], v[168:171], v[192:195], v[32:35]
	v_mfma_f32_16x16x32_bf16 v[32:35], v[120:123], v[196:199], v[52:55]
	v_mfma_f32_16x16x32_bf16 v[52:55], v[124:127], v[200:203], v[32:35]
	v_mfma_f32_16x16x32_bf16 v[32:35], v[164:167], v[196:199], v[56:59]
	v_mfma_f32_16x16x32_bf16 v[56:59], v[168:171], v[200:203], v[32:35]
	s_setprio 0
	s_barrier
	s_mov_b32 m0, s51
	v_lshl_add_u64 v[240:241], s[30:31], 0, v[130:131]
	s_add_u32 s36, s30, 0x10000
	s_nop 1
	ds_read_b128 v[32:35], v136 offset:16384
	ds_read_b128 v[36:39], v136 offset:17408
	ds_read_b128 v[96:99], v136 offset:18432
	ds_read_b128 v[180:183], v136 offset:19456
	ds_read_b128 v[184:187], v136 offset:20480
	ds_read_b128 v[188:191], v136 offset:21504
	ds_read_b128 v[192:195], v136 offset:22528
	ds_read_b128 v[196:199], v136 offset:23552
	global_load_lds_dwordx4 v[240:241], off
	v_lshl_add_u64 v[242:243], s[30:31], 0, v[128:129]
	s_mov_b32 m0, s52
	s_addc_u32 s37, s31, 0
	global_load_lds_dwordx4 v[242:243], off
	v_lshl_add_u64 v[200:201], s[36:37], 0, v[130:131]
	s_mov_b32 m0, s53
	v_lshl_add_u64 v[244:245], s[34:35], 0, v[130:131]
	global_load_lds_dwordx4 v[200:201], off
	v_lshl_add_u64 v[200:201], s[36:37], 0, v[128:129]
	s_mov_b32 m0, s54
	v_lshl_add_u64 v[246:247], s[34:35], 0, v[128:129]
	global_load_lds_dwordx4 v[200:201], off
	s_mov_b32 m0, s74
	s_nop 0
	global_load_lds_dwordx4 v[244:245], off
	s_mov_b32 m0, s47
	s_nop 0
	global_load_lds_dwordx4 v[246:247], off
	s_waitcnt vmcnt(8)
	s_cmp_lt_u32 s3, 4
	s_cbranch_scc1 .Lgls_17
	s_waitcnt lgkmcnt(0)
; #define PG8_STAGE(bufoff, gbase, voff) do { _Pragma("unroll") for (int _i = 0; _i < 2; ++_i) \
;         __builtin_amdgcn_global_load_lds((const unsigned*)((const char*)(gbase) + (voff)[_i]), (PG8_LAS unsigned*)(lds + (bufoff) + ldsw + _i * 8192), 16, 0, 0); } while (0)
; #define PG8_LDA(dst, b, h) do { _Pragma("unroll") for (int m = 0; m < 4; ++m) _Pragma("unroll") for (int k = 0; k < 2; ++k) dst[m][k] = *(const PG8_LAS bf16x8*)(lds + PG8_SA(b, h) + aoff + m * 2048 + k * 1024); } while (0)
; #define PG8_LDB(dst, b, h) do { _Pragma("unroll") for (int n = 0; n < 2; ++n) _Pragma("unroll") for (int k = 0; k < 2; ++k) dst[n][k] = *(const PG8_LAS bf16x8*)(lds + PG8_SB(b, h) + boff + n * 2048 + k * 1024); } while (0)
; #define PG8_MMA(ai, bj, At, Bt) do { __builtin_amdgcn_s_setprio(1); _Pragma("unroll") for (int m = 0; m < 4; ++m) _Pragma("unroll") for (int n = 0; n < 2; ++n) _Pragma("unroll") for (int k = 0; k < 2; ++k) \
;         acc[ai][bj][m][n] = mma16<F16>(Bt[n][k], At[m][k], acc[ai][bj][m][n]); __builtin_amdgcn_s_setprio(0); } while (0)
; #define PG8_WAIT_V(n) asm volatile("s_waitcnt vmcnt(" #n ")" ::: "memory")
; #define PG8_WAIT_L(n) asm volatile("s_waitcnt lgkmcnt(" #n ")" ::: "memory")
; #define PG8_BAR __builtin_amdgcn_s_barrier()
; #define PG8_SCHED __builtin_amdgcn_sched_barrier(0)
; template <class Epi, class Sched, bool ALIGN_EPI = false, bool SP2 = false, bool F16 = false>
; __device__ __forceinline__ void gemm_phase(PG8_LAS unsigned char* lds, const Gemm g, const Sched& S, const Epi& E, const int wid_in) {
;     ...
;             PG8_WAIT_V(8); PG8_WAIT_L(0); PG8_BAR; PG8_MMA(1, 0, At, B0); PG8_MMA(1, 1, At, B1); PG8_BAR; PG8_SCHED;
;             PG8_LDB(B0, 1, 0); PG8_LDB(B1, 1, 1); PG8_SCHED; PG8_LDA(At, 1, 0); PG8_STAGE(PG8_SA(0, 1), a2 + hstep, voffA);
;             PG8_WAIT_V(8); PG8_WAIT_L(0); PG8_BAR; PG8_MMA(0, 0, At, B0); PG8_MMA(0, 1, At, B1); PG8_BAR; PG8_SCHED;
.Lgls_17:
	s_barrier
	s_setprio 1
	s_waitcnt lgkmcnt(0)
	v_mfma_f32_16x16x32_bf16 v[0:3], v[104:107], v[192:195], v[0:3]
	v_mfma_f32_16x16x32_bf16 v[140:143], v[104:107], v[32:35], v[140:143]
	v_mfma_f32_16x16x32_bf16 v[144:147], v[112:115], v[32:35], v[144:147]
	v_mfma_f32_16x16x32_bf16 v[148:151], v[104:107], v[96:99], v[148:151]
	v_mfma_f32_16x16x32_bf16 v[152:155], v[112:115], v[96:99], v[152:155]
	v_mfma_f32_16x16x32_bf16 v[156:159], v[104:107], v[184:187], v[156:159]
	v_mfma_f32_16x16x32_bf16 v[160:163], v[112:115], v[184:187], v[160:163]
	v_mfma_f32_16x16x32_bf16 v[0:3], v[108:111], v[196:199], v[0:3]
	v_mfma_f32_16x16x32_bf16 v[4:7], v[112:115], v[192:195], v[4:7]
	v_mfma_f32_16x16x32_bf16 v[140:143], v[108:111], v[36:39], v[140:143]
	v_mfma_f32_16x16x32_bf16 v[144:147], v[116:119], v[36:39], v[144:147]
	v_mfma_f32_16x16x32_bf16 v[148:151], v[108:111], v[180:183], v[148:151]
	v_mfma_f32_16x16x32_bf16 v[152:155], v[116:119], v[180:183], v[152:155]
	v_mfma_f32_16x16x32_bf16 v[156:159], v[108:111], v[188:191], v[156:159]
	v_mfma_f32_16x16x32_bf16 v[160:163], v[116:119], v[188:191], v[160:163]
	v_mfma_f32_16x16x32_bf16 v[200:203], v[116:119], v[196:199], v[4:7]
	s_setprio 0
	s_setprio 1
	v_mfma_f32_16x16x32_bf16 v[4:7], v[120:123], v[32:35], v[8:11]
	v_mfma_f32_16x16x32_bf16 v[8:11], v[124:127], v[36:39], v[4:7]
	v_mfma_f32_16x16x32_bf16 v[4:7], v[164:167], v[32:35], v[12:15]
	v_mfma_f32_16x16x32_bf16 v[12:15], v[168:171], v[36:39], v[4:7]
	v_mfma_f32_16x16x32_bf16 v[4:7], v[120:123], v[96:99], v[24:27]
	v_mfma_f32_16x16x32_bf16 v[24:27], v[124:127], v[180:183], v[4:7]
	v_mfma_f32_16x16x32_bf16 v[4:7], v[164:167], v[96:99], v[28:31]
	v_mfma_f32_16x16x32_bf16 v[28:31], v[168:171], v[180:183], v[4:7]
	v_mfma_f32_16x16x32_bf16 v[4:7], v[120:123], v[184:187], v[60:63]
	v_mfma_f32_16x16x32_bf16 v[180:183], v[124:127], v[188:191], v[4:7]
	v_mfma_f32_16x16x32_bf16 v[4:7], v[164:167], v[184:187], v[100:103]
	v_mfma_f32_16x16x32_bf16 v[184:187], v[168:171], v[188:191], v[4:7]
	v_mfma_f32_16x16x32_bf16 v[4:7], v[120:123], v[192:195], v[16:19]
	v_mfma_f32_16x16x32_bf16 v[188:191], v[124:127], v[196:199], v[4:7]
	v_mfma_f32_16x16x32_bf16 v[4:7], v[164:167], v[192:195], v[20:23]
	v_mfma_f32_16x16x32_bf16 v[164:167], v[168:171], v[196:199], v[4:7]
	s_setprio 0
	s_barrier
	s_nop 4
	ds_read_b128 v[4:7], v137
	ds_read_b128 v[60:63], v137 offset:1024
	ds_read_b128 v[168:171], v137 offset:2048
	ds_read_b128 v[192:195], v137 offset:3072
	ds_read_b128 v[196:199], v138
	ds_read_b128 v[208:211], v138 offset:1024
	ds_read_b128 v[212:215], v138 offset:2048
	ds_read_b128 v[216:219], v138 offset:3072
	s_add_u32 s34, s34, 0x10000
	s_addc_u32 s35, s35, 0
	s_mov_b32 m0, s48
	v_lshl_add_u64 v[32:33], s[34:35], 0, v[130:131]
	ds_read_b128 v[16:19], v136 offset:32768
	ds_read_b128 v[20:23], v136 offset:33792
	ds_read_b128 v[104:107], v136 offset:34816
	ds_read_b128 v[220:223], v136 offset:35840
	ds_read_b128 v[224:227], v136 offset:36864
	ds_read_b128 v[228:231], v136 offset:37888
	ds_read_b128 v[232:235], v136 offset:38912
	ds_read_b128 v[236:239], v136 offset:39936
	global_load_lds_dwordx4 v[32:33], off
	v_lshl_add_u64 v[32:33], s[34:35], 0, v[128:129]
	s_mov_b32 m0, s49
	s_nop 0
	global_load_lds_dwordx4 v[32:33], off
	s_waitcnt vmcnt(8)
	s_cmp_lt_u32 s3, 4
	s_cbranch_scc1 .Lgls_18
	s_waitcnt lgkmcnt(0)
; #define PG8_STAGE(bufoff, gbase, voff) do { _Pragma("unroll") for (int _i = 0; _i < 2; ++_i) \
;         __builtin_amdgcn_global_load_lds((const unsigned*)((const char*)(gbase) + (voff)[_i]), (PG8_LAS unsigned*)(lds + (bufoff) + ldsw + _i * 8192), 16, 0, 0); } while (0)
; #define PG8_LDA(dst, b, h) do { _Pragma("unroll") for (int m = 0; m < 4; ++m) _Pragma("unroll") for (int k = 0; k < 2; ++k) dst[m][k] = *(const PG8_LAS bf16x8*)(lds + PG8_SA(b, h) + aoff + m * 2048 + k * 1024); } while (0)
; #define PG8_MMA(ai, bj, At, Bt) do { __builtin_amdgcn_s_setprio(1); _Pragma("unroll") for (int m = 0; m < 4; ++m) _Pragma("unroll") for (int n = 0; n < 2; ++n) _Pragma("unroll") for (int k = 0; k < 2; ++k) \
;         acc[ai][bj][m][n] = mma16<F16>(Bt[n][k], At[m][k], acc[ai][bj][m][n]); __builtin_amdgcn_s_setprio(0); } while (0)
; #define PG8_WAIT_V(n) asm volatile("s_waitcnt vmcnt(" #n ")" ::: "memory")
; #define PG8_WAIT_L(n) asm volatile("s_waitcnt lgkmcnt(" #n ")" ::: "memory")
; #define PG8_BAR __builtin_amdgcn_s_barrier()
; #define PG8_SCHED __builtin_amdgcn_sched_barrier(0)
; template <class Epi, class Sched, bool ALIGN_EPI = false, bool SP2 = false, bool F16 = false>
; __device__ __forceinline__ void gemm_phase(PG8_LAS unsigned char* lds, const Gemm g, const Sched& S, const Epi& E, const int wid_in) {
;     ...
;             PG8_WAIT_V(8); PG8_WAIT_L(0); PG8_BAR; PG8_MMA(0, 0, At, B0); PG8_MMA(0, 1, At, B1); PG8_BAR; PG8_SCHED;
;             PG8_LDA(At, 1, 1); PG8_STAGE(PG8_SB(1, 0), b3, voffB); PG8_STAGE(PG8_SB(1, 1), b3 + hstep, voffB); PG8_STAGE(PG8_SA(1, 0), a3, voffA);
;             PG8_WAIT_V(8); PG8_WAIT_L(0); PG8_BAR; PG8_MMA(1, 0, At, B0); PG8_MMA(1, 1, At, B1); PG8_BAR; PG8_SCHED;
;     ...
;         if constexpr (ALIGN_EPI) { if (wr == 0) PG8_BAR; }
.Lgls_18:
	s_barrier
	s_setprio 1
	s_waitcnt lgkmcnt(0)
	v_mfma_f32_16x16x32_bf16 v[32:35], v[4:7], v[16:19], v[64:67]
	v_mfma_f32_16x16x32_bf16 v[116:119], v[60:63], v[20:23], v[32:35]
	v_mfma_f32_16x16x32_bf16 v[32:35], v[168:171], v[16:19], v[68:71]
	v_mfma_f32_16x16x32_bf16 v[112:115], v[192:195], v[20:23], v[32:35]
	v_mfma_f32_16x16x32_bf16 v[32:35], v[4:7], v[104:107], v[72:75]
	v_mfma_f32_16x16x32_bf16 v[100:103], v[60:63], v[220:223], v[32:35]
	v_mfma_f32_16x16x32_bf16 v[32:35], v[168:171], v[104:107], v[76:79]
	v_mfma_f32_16x16x32_bf16 v[96:99], v[192:195], v[220:223], v[32:35]
	v_mfma_f32_16x16x32_bf16 v[32:35], v[4:7], v[224:227], v[80:83]
	v_mfma_f32_16x16x32_bf16 v[68:71], v[60:63], v[228:231], v[32:35]
	v_mfma_f32_16x16x32_bf16 v[32:35], v[168:171], v[224:227], v[84:87]
	v_mfma_f32_16x16x32_bf16 v[64:67], v[192:195], v[228:231], v[32:35]
	v_mfma_f32_16x16x32_bf16 v[32:35], v[4:7], v[232:235], v[88:91]
	v_mfma_f32_16x16x32_bf16 v[36:39], v[60:63], v[236:239], v[32:35]
	v_mfma_f32_16x16x32_bf16 v[32:35], v[168:171], v[232:235], v[92:95]
	v_mfma_f32_16x16x32_bf16 v[32:35], v[192:195], v[236:239], v[32:35]
	s_setprio 0
	s_setprio 1
	v_mfma_f32_16x16x32_bf16 v[72:75], v[196:199], v[16:19], v[204:207]
	v_mfma_f32_16x16x32_bf16 v[16:19], v[212:215], v[16:19], v[172:175]
	v_mfma_f32_16x16x32_bf16 v[120:123], v[216:219], v[20:23], v[16:19]
	v_mfma_f32_16x16x32_bf16 v[16:19], v[196:199], v[104:107], v[176:179]
	v_mfma_f32_16x16x32_bf16 v[108:111], v[208:211], v[220:223], v[16:19]
	v_mfma_f32_16x16x32_bf16 v[16:19], v[212:215], v[104:107], v[40:43]
	v_mfma_f32_16x16x32_bf16 v[104:107], v[216:219], v[220:223], v[16:19]
	v_mfma_f32_16x16x32_bf16 v[16:19], v[196:199], v[224:227], v[44:47]
	v_mfma_f32_16x16x32_bf16 v[80:83], v[208:211], v[228:231], v[16:19]
	v_mfma_f32_16x16x32_bf16 v[16:19], v[212:215], v[224:227], v[48:51]
	v_mfma_f32_16x16x32_bf16 v[124:127], v[208:211], v[20:23], v[72:75]
	v_mfma_f32_16x16x32_bf16 v[72:75], v[216:219], v[228:231], v[16:19]
	v_mfma_f32_16x16x32_bf16 v[16:19], v[196:199], v[232:235], v[52:55]
	v_mfma_f32_16x16x32_bf16 v[48:51], v[208:211], v[236:239], v[16:19]
	v_mfma_f32_16x16x32_bf16 v[16:19], v[212:215], v[232:235], v[56:59]
	v_mfma_f32_16x16x32_bf16 v[40:43], v[216:219], v[236:239], v[16:19]
	s_setprio 0
	s_barrier
	s_mov_b32 m0, s55
	s_nop 3
	v_lshl_add_u64 v[16:17], v[240:241], 0, s[20:21]
	s_add_u32 s30, s30, 0x10080
	ds_read_b128 v[56:59], v136 offset:49152
	ds_read_b128 v[88:91], v136 offset:50176
	ds_read_b128 v[172:175], v136 offset:51200
	ds_read_b128 v[176:179], v136 offset:52224
	ds_read_b128 v[204:207], v136 offset:53248
	ds_read_b128 v[220:223], v136 offset:54272
	ds_read_b128 v[224:227], v136 offset:55296
	ds_read_b128 v[228:231], v136 offset:56320
	global_load_lds_dwordx4 v[16:17], off
	v_lshl_add_u64 v[16:17], v[242:243], 0, s[20:21]
	s_mov_b32 m0, s58
	s_addc_u32 s31, s31, 0
	global_load_lds_dwordx4 v[16:17], off
	v_lshl_add_u64 v[16:17], s[30:31], 0, v[130:131]
	s_mov_b32 m0, s59
	s_nop 0
	global_load_lds_dwordx4 v[16:17], off
	v_lshl_add_u64 v[16:17], s[30:31], 0, v[128:129]
	s_mov_b32 m0, s60
	s_nop 0
	global_load_lds_dwordx4 v[16:17], off
	v_lshl_add_u64 v[16:17], v[244:245], 0, s[20:21]
	s_mov_b32 m0, s75
	s_nop 0
	global_load_lds_dwordx4 v[16:17], off
	v_lshl_add_u64 v[16:17], v[246:247], 0, s[20:21]
	s_mov_b32 m0, s14
	s_nop 0
	global_load_lds_dwordx4 v[16:17], off
	s_waitcnt vmcnt(8)
	s_cmp_lt_u32 s3, 4
	s_cbranch_scc1 .Lgls_19
	s_waitcnt lgkmcnt(0)
.Lgls_19:
	s_barrier
	s_setprio 1
	s_waitcnt lgkmcnt(0)
	v_mfma_f32_16x16x32_bf16 v[16:19], v[4:7], v[56:59], v[140:143]
	v_mfma_f32_16x16x32_bf16 v[84:87], v[60:63], v[88:91], v[16:19]
	v_mfma_f32_16x16x32_bf16 v[16:19], v[168:171], v[56:59], v[144:147]
	v_mfma_f32_16x16x32_bf16 v[76:79], v[192:195], v[88:91], v[16:19]
	v_mfma_f32_16x16x32_bf16 v[16:19], v[4:7], v[172:175], v[148:151]
	v_mfma_f32_16x16x32_bf16 v[52:55], v[60:63], v[176:179], v[16:19]
	v_mfma_f32_16x16x32_bf16 v[16:19], v[168:171], v[172:175], v[152:155]
	v_mfma_f32_16x16x32_bf16 v[44:47], v[192:195], v[176:179], v[16:19]
	v_mfma_f32_16x16x32_bf16 v[16:19], v[4:7], v[204:207], v[156:159]
	v_mfma_f32_16x16x32_bf16 v[0:3], v[4:7], v[224:227], v[0:3]
	v_mfma_f32_16x16x32_bf16 v[20:23], v[60:63], v[220:223], v[16:19]
	v_mfma_f32_16x16x32_bf16 v[16:19], v[168:171], v[204:207], v[160:163]
	v_mfma_f32_16x16x32_bf16 v[4:7], v[60:63], v[228:231], v[0:3]
	v_mfma_f32_16x16x32_bf16 v[0:3], v[168:171], v[224:227], v[200:203]
	v_mfma_f32_16x16x32_bf16 v[16:19], v[192:195], v[220:223], v[16:19]
	v_mfma_f32_16x16x32_bf16 v[0:3], v[192:195], v[228:231], v[0:3]
	s_setprio 0
	s_setprio 1
	v_mfma_f32_16x16x32_bf16 v[8:11], v[196:199], v[56:59], v[8:11]
	v_mfma_f32_16x16x32_bf16 v[92:95], v[208:211], v[88:91], v[8:11]
	v_mfma_f32_16x16x32_bf16 v[8:11], v[212:215], v[56:59], v[12:15]
	v_mfma_f32_16x16x32_bf16 v[88:91], v[216:219], v[88:91], v[8:11]
	v_mfma_f32_16x16x32_bf16 v[8:11], v[196:199], v[172:175], v[24:27]
	v_mfma_f32_16x16x32_bf16 v[60:63], v[208:211], v[176:179], v[8:11]
	v_mfma_f32_16x16x32_bf16 v[8:11], v[212:215], v[172:175], v[28:31]
	v_mfma_f32_16x16x32_bf16 v[56:59], v[216:219], v[176:179], v[8:11]
	v_mfma_f32_16x16x32_bf16 v[8:11], v[196:199], v[204:207], v[180:183]
	v_mfma_f32_16x16x32_bf16 v[28:31], v[208:211], v[220:223], v[8:11]
	v_mfma_f32_16x16x32_bf16 v[8:11], v[212:215], v[204:207], v[184:187]
	v_mfma_f32_16x16x32_bf16 v[24:27], v[216:219], v[220:223], v[8:11]
	v_mfma_f32_16x16x32_bf16 v[8:11], v[196:199], v[224:227], v[188:191]
	v_mfma_f32_16x16x32_bf16 v[12:15], v[208:211], v[228:231], v[8:11]
	v_mfma_f32_16x16x32_bf16 v[8:11], v[212:215], v[224:227], v[164:167]
	v_mfma_f32_16x16x32_bf16 v[8:11], v[216:219], v[228:231], v[8:11]
	s_setprio 0
	s_barrier
	s_and_b64 vcc, exec, s[8:9]
	s_cbranch_vccnz .LBB0_622
	s_barrier

; #define PG8_STAGE(bufoff, gbase, voff) do { _Pragma("unroll") for (int _i = 0; _i < 2; ++_i) \
;         __builtin_amdgcn_global_load_lds((const unsigned*)((const char*)(gbase) + (voff)[_i]), (PG8_LAS unsigned*)(lds + (bufoff) + ldsw + _i * 8192), 16, 0, 0); } while (0)
; #define PG8_LDA(dst, b, h) do { _Pragma("unroll") for (int m = 0; m < 4; ++m) _Pragma("unroll") for (int k = 0; k < 2; ++k) dst[m][k] = *(const PG8_LAS bf16x8*)(lds + PG8_SA(b, h) + aoff + m * 2048 + k * 1024); } while (0)
; #define PG8_LDB(dst, b, h) do { _Pragma("unroll") for (int n = 0; n < 2; ++n) _Pragma("unroll") for (int k = 0; k < 2; ++k) dst[n][k] = *(const PG8_LAS bf16x8*)(lds + PG8_SB(b, h) + boff + n * 2048 + k * 1024); } while (0)
; #define PG8_MMA(ai, bj, At, Bt) do { __builtin_amdgcn_s_setprio(1); _Pragma("unroll") for (int m = 0; m < 4; ++m) _Pragma("unroll") for (int n = 0; n < 2; ++n) _Pragma("unroll") for (int k = 0; k < 2; ++k) \
;         acc[ai][bj][m][n] = mma16<F16>(Bt[n][k], At[m][k], acc[ai][bj][m][n]); __builtin_amdgcn_s_setprio(0); } while (0)
; #define PG8_WAIT_V(n) asm volatile("s_waitcnt vmcnt(" #n ")" ::: "memory")
; #define PG8_WAIT_L(n) asm volatile("s_waitcnt lgkmcnt(" #n ")" ::: "memory")
; template <class Epi, class Sched, bool ALIGN_EPI = false, bool SP2 = false, bool F16 = false>
; __device__ __forceinline__ void gemm_phase(PG8_LAS unsigned char* lds, const Gemm g, const Sched& S, const Epi& E, const int wid_in) {
;     ...
;             const bool last = (t == nt - 2);
;             const char* a1 = cA + (size_t)(t + 1) * kstep;
;             const char* a2 = last ? nA : cA + (size_t)(t + 2) * kstep; const char* b2 = last ? nB : cB + (size_t)(t + 2) * kstep;
;             const char* a3 = a2 + kstep; const char* b3 = b2 + kstep;
;             if (last && has_next) S.a_ready(nxt);
;             if constexpr (SP2) {
;             PG8_LDB(B0, 0, 0); PG8_LDB(B1, 0, 1); PG8_SCHED; PG8_LDA(At, 0, 0); PG8_STAGE(PG8_SA(1, 1), a1 + hstep, voffA);
;             PG8_WAIT_V(8); PG8_WAIT_L(0); PG8_BAR; PG8_MMA(0, 0, At, B0); PG8_MMA(0, 1, At, B1); PG8_BAR; PG8_SCHED;
;             PG8_LDA(At, 0, 1); PG8_STAGE(PG8_SB(0, 0), b2, voffB); PG8_STAGE(PG8_SB(0, 1), b2 + hstep, voffB); PG8_STAGE(PG8_SA(0, 0), a2, voffA);
;             PG8_WAIT_V(8); PG8_WAIT_L(0); PG8_BAR; PG8_MMA(1, 0, At, B0); PG8_MMA(1, 1, At, B1); PG8_BAR; PG8_SCHED;
.LBB0_716:
	ds_read_b128 v[128:131], v189
	ds_read_b128 v[132:135], v189 offset:1024
	ds_read_b128 v[136:139], v189 offset:2048
	ds_read_b128 v[140:143], v189 offset:3072
	ds_read_b128 v[144:147], v190
	ds_read_b128 v[148:151], v190 offset:1024
	ds_read_b128 v[168:171], v190 offset:2048
	ds_read_b128 v[172:175], v190 offset:3072
	s_add_u32 s30, s28, 0x100
	s_addc_u32 s31, s29, 0
	s_cmp_eq_u32 s60, 40
	s_cselect_b32 s37, s11, s31
	s_cselect_b32 s36, s10, s30
	s_cselect_b32 s35, s27, s59
	s_cselect_b32 s34, s26, s43
	v_lshl_add_u64 v[184:185], s[28:29], 0, v[160:161]
	s_add_i32 m0, s74, 0xc000
	ds_read_b128 v[176:179], v191
	ds_read_b128 v[180:183], v191 offset:1024
	ds_read_b128 v[192:195], v191 offset:2048
	ds_read_b128 v[196:199], v191 offset:3072
	ds_read_b128 v[200:203], v191 offset:4096
	ds_read_b128 v[204:207], v191 offset:5120
	ds_read_b128 v[208:211], v191 offset:6144
	ds_read_b128 v[212:215], v191 offset:7168
	global_load_lds_dwordx4 v[184:185], off
	v_lshl_add_u64 v[184:185], s[28:29], 0, v[162:163]
	s_add_i32 m0, s74, 0xe000
	s_nop 0
	global_load_lds_dwordx4 v[184:185], off
	s_waitcnt vmcnt(8)
	s_cmp_lt_u32 s3, 4
	s_cbranch_scc1 .Lgls_20
	s_waitcnt lgkmcnt(0)
.Lgls_20:
	s_barrier
	s_setprio 1
	s_waitcnt lgkmcnt(0)
	v_mfma_f32_16x16x32_bf16 v[124:127], v[128:131], v[176:179], v[124:127]
	v_mfma_f32_16x16x32_bf16 v[120:123], v[136:139], v[176:179], v[120:123]
	v_mfma_f32_16x16x32_bf16 v[108:111], v[128:131], v[192:195], v[108:111]
	v_mfma_f32_16x16x32_bf16 v[104:107], v[136:139], v[192:195], v[104:107]
	v_mfma_f32_16x16x32_bf16 v[92:95], v[128:131], v[200:203], v[92:95]
	v_mfma_f32_16x16x32_bf16 v[88:91], v[136:139], v[200:203], v[88:91]
	v_mfma_f32_16x16x32_bf16 v[76:79], v[128:131], v[208:211], v[76:79]
	v_mfma_f32_16x16x32_bf16 v[72:75], v[136:139], v[208:211], v[72:75]
	v_mfma_f32_16x16x32_bf16 v[124:127], v[132:135], v[180:183], v[124:127]
	v_mfma_f32_16x16x32_bf16 v[120:123], v[140:143], v[180:183], v[120:123]
	v_mfma_f32_16x16x32_bf16 v[108:111], v[132:135], v[196:199], v[108:111]
	v_mfma_f32_16x16x32_bf16 v[104:107], v[140:143], v[196:199], v[104:107]
	v_mfma_f32_16x16x32_bf16 v[92:95], v[132:135], v[204:207], v[92:95]
	v_mfma_f32_16x16x32_bf16 v[88:91], v[140:143], v[204:207], v[88:91]
	v_mfma_f32_16x16x32_bf16 v[76:79], v[132:135], v[212:215], v[76:79]
	v_mfma_f32_16x16x32_bf16 v[72:75], v[140:143], v[212:215], v[72:75]
	s_setprio 0
	s_setprio 1
	v_mfma_f32_16x16x32_bf16 v[116:119], v[144:147], v[176:179], v[116:119]
	v_mfma_f32_16x16x32_bf16 v[112:115], v[168:171], v[176:179], v[112:115]
	v_mfma_f32_16x16x32_bf16 v[100:103], v[144:147], v[192:195], v[100:103]
	v_mfma_f32_16x16x32_bf16 v[96:99], v[168:171], v[192:195], v[96:99]
	v_mfma_f32_16x16x32_bf16 v[84:87], v[144:147], v[200:203], v[84:87]
	v_mfma_f32_16x16x32_bf16 v[80:83], v[168:171], v[200:203], v[80:83]
	v_mfma_f32_16x16x32_bf16 v[68:71], v[144:147], v[208:211], v[68:71]
	v_mfma_f32_16x16x32_bf16 v[64:67], v[168:171], v[208:211], v[64:67]
	v_mfma_f32_16x16x32_bf16 v[116:119], v[148:151], v[180:183], v[116:119]
	v_mfma_f32_16x16x32_bf16 v[112:115], v[172:175], v[180:183], v[112:115]
	v_mfma_f32_16x16x32_bf16 v[100:103], v[148:151], v[196:199], v[100:103]
	v_mfma_f32_16x16x32_bf16 v[96:99], v[172:175], v[196:199], v[96:99]
	v_mfma_f32_16x16x32_bf16 v[84:87], v[148:151], v[204:207], v[84:87]
	v_mfma_f32_16x16x32_bf16 v[80:83], v[172:175], v[204:207], v[80:83]
	v_mfma_f32_16x16x32_bf16 v[68:71], v[148:151], v[212:215], v[68:71]
	v_mfma_f32_16x16x32_bf16 v[64:67], v[172:175], v[212:215], v[64:67]
	s_setprio 0
	s_barrier
	s_add_i32 s28, s52, s68
	v_lshl_add_u64 v[184:185], s[34:35], 0, v[154:155]
	s_mov_b32 m0, s28
	ds_read_b128 v[176:179], v191 offset:16384
	ds_read_b128 v[180:183], v191 offset:17408
	ds_read_b128 v[192:195], v191 offset:18432
	ds_read_b128 v[196:199], v191 offset:19456
	ds_read_b128 v[200:203], v191 offset:20480
	ds_read_b128 v[204:207], v191 offset:21504
	ds_read_b128 v[208:211], v191 offset:22528
	ds_read_b128 v[212:215], v191 offset:23552
	global_load_lds_dwordx4 v[184:185], off
	s_add_i32 m0, s28, 0x2000
	s_add_u32 s28, s34, 0xb0000
	v_lshl_add_u64 v[216:217], s[34:35], 0, v[158:159]
	s_addc_u32 s29, s35, 0
	s_add_i32 s61, s53, s68
	global_load_lds_dwordx4 v[216:217], off
	v_lshl_add_u64 v[218:219], s[28:29], 0, v[154:155]
	s_mov_b32 m0, s61
	v_lshl_add_u64 v[220:221], s[36:37], 0, v[156:157]
	global_load_lds_dwordx4 v[218:219], off
	v_lshl_add_u64 v[218:219], s[28:29], 0, v[158:159]
	s_add_i32 m0, s61, 0x2000
	s_nop 0
	global_load_lds_dwordx4 v[218:219], off
	v_lshl_add_u64 v[218:219], s[36:37], 0, v[152:153]
	s_mov_b32 m0, s74
	s_nop 0
	global_load_lds_dwordx4 v[218:219], off
	s_mov_b32 m0, s45
	s_nop 0
	global_load_lds_dwordx4 v[220:221], off
	s_waitcnt vmcnt(8)
	s_cmp_lt_u32 s3, 4
	s_cbranch_scc1 .Lgls_21
	s_waitcnt lgkmcnt(0)
; #define PG8_STAGE(bufoff, gbase, voff) do { _Pragma("unroll") for (int _i = 0; _i < 2; ++_i) \
;         __builtin_amdgcn_global_load_lds((const unsigned*)((const char*)(gbase) + (voff)[_i]), (PG8_LAS unsigned*)(lds + (bufoff) + ldsw + _i * 8192), 16, 0, 0); } while (0)
; #define PG8_LDA(dst, b, h) do { _Pragma("unroll") for (int m = 0; m < 4; ++m) _Pragma("unroll") for (int k = 0; k < 2; ++k) dst[m][k] = *(const PG8_LAS bf16x8*)(lds + PG8_SA(b, h) + aoff + m * 2048 + k * 1024); } while (0)
; #define PG8_LDB(dst, b, h) do { _Pragma("unroll") for (int n = 0; n < 2; ++n) _Pragma("unroll") for (int k = 0; k < 2; ++k) dst[n][k] = *(const PG8_LAS bf16x8*)(lds + PG8_SB(b, h) + boff + n * 2048 + k * 1024); } while (0)
; #define PG8_MMA(ai, bj, At, Bt) do { __builtin_amdgcn_s_setprio(1); _Pragma("unroll") for (int m = 0; m < 4; ++m) _Pragma("unroll") for (int n = 0; n < 2; ++n) _Pragma("unroll") for (int k = 0; k < 2; ++k) \
;         acc[ai][bj][m][n] = mma16<F16>(Bt[n][k], At[m][k], acc[ai][bj][m][n]); __builtin_amdgcn_s_setprio(0); } while (0)
; #define PG8_WAIT_V(n) asm volatile("s_waitcnt vmcnt(" #n ")" ::: "memory")
; #define PG8_WAIT_L(n) asm volatile("s_waitcnt lgkmcnt(" #n ")" ::: "memory")
; #define PG8_BAR __builtin_amdgcn_s_barrier()
; #define PG8_SCHED __builtin_amdgcn_sched_barrier(0)
; template <class Epi, class Sched, bool ALIGN_EPI = false, bool SP2 = false, bool F16 = false>
; __device__ __forceinline__ void gemm_phase(PG8_LAS unsigned char* lds, const Gemm g, const Sched& S, const Epi& E, const int wid_in) {
;     ...
;             PG8_WAIT_V(8); PG8_WAIT_L(0); PG8_BAR; PG8_MMA(1, 0, At, B0); PG8_MMA(1, 1, At, B1); PG8_BAR; PG8_SCHED;
;             PG8_LDB(B0, 1, 0); PG8_LDB(B1, 1, 1); PG8_SCHED; PG8_LDA(At, 1, 0); PG8_STAGE(PG8_SA(0, 1), a2 + hstep, voffA);
;             PG8_WAIT_V(8); PG8_WAIT_L(0); PG8_BAR; PG8_MMA(0, 0, At, B0); PG8_MMA(0, 1, At, B1); PG8_BAR; PG8_SCHED;
.Lgls_21:
	s_barrier
	s_setprio 1
	s_waitcnt lgkmcnt(0)
	v_mfma_f32_16x16x32_bf16 v[60:63], v[128:131], v[176:179], v[60:63]
	v_mfma_f32_16x16x32_bf16 v[56:59], v[136:139], v[176:179], v[56:59]
	v_mfma_f32_16x16x32_bf16 v[44:47], v[128:131], v[192:195], v[44:47]
	v_mfma_f32_16x16x32_bf16 v[40:43], v[136:139], v[192:195], v[40:43]
	v_mfma_f32_16x16x32_bf16 v[28:31], v[128:131], v[200:203], v[28:31]
	v_mfma_f32_16x16x32_bf16 v[24:27], v[136:139], v[200:203], v[24:27]
	v_mfma_f32_16x16x32_bf16 v[12:15], v[128:131], v[208:211], v[12:15]
	v_mfma_f32_16x16x32_bf16 v[8:11], v[136:139], v[208:211], v[8:11]
	v_mfma_f32_16x16x32_bf16 v[60:63], v[132:135], v[180:183], v[60:63]
	v_mfma_f32_16x16x32_bf16 v[56:59], v[140:143], v[180:183], v[56:59]
	v_mfma_f32_16x16x32_bf16 v[44:47], v[132:135], v[196:199], v[44:47]
	v_mfma_f32_16x16x32_bf16 v[40:43], v[140:143], v[196:199], v[40:43]
	v_mfma_f32_16x16x32_bf16 v[28:31], v[132:135], v[204:207], v[28:31]
	v_mfma_f32_16x16x32_bf16 v[24:27], v[140:143], v[204:207], v[24:27]
	v_mfma_f32_16x16x32_bf16 v[12:15], v[132:135], v[212:215], v[12:15]
	v_mfma_f32_16x16x32_bf16 v[8:11], v[140:143], v[212:215], v[8:11]
	s_setprio 0
	s_setprio 1
	v_mfma_f32_16x16x32_bf16 v[52:55], v[144:147], v[176:179], v[52:55]
	v_mfma_f32_16x16x32_bf16 v[48:51], v[168:171], v[176:179], v[48:51]
	v_mfma_f32_16x16x32_bf16 v[36:39], v[144:147], v[192:195], v[36:39]
	v_mfma_f32_16x16x32_bf16 v[32:35], v[168:171], v[192:195], v[32:35]
	v_mfma_f32_16x16x32_bf16 v[20:23], v[144:147], v[200:203], v[20:23]
	v_mfma_f32_16x16x32_bf16 v[16:19], v[168:171], v[200:203], v[16:19]
	v_mfma_f32_16x16x32_bf16 v[4:7], v[144:147], v[208:211], v[4:7]
	v_mfma_f32_16x16x32_bf16 v[0:3], v[168:171], v[208:211], v[0:3]
	v_mfma_f32_16x16x32_bf16 v[52:55], v[148:151], v[180:183], v[52:55]
	v_mfma_f32_16x16x32_bf16 v[48:51], v[172:175], v[180:183], v[48:51]
	v_mfma_f32_16x16x32_bf16 v[36:39], v[148:151], v[196:199], v[36:39]
	v_mfma_f32_16x16x32_bf16 v[32:35], v[172:175], v[196:199], v[32:35]
	v_mfma_f32_16x16x32_bf16 v[20:23], v[148:151], v[204:207], v[20:23]
	v_mfma_f32_16x16x32_bf16 v[16:19], v[172:175], v[204:207], v[16:19]
	v_mfma_f32_16x16x32_bf16 v[4:7], v[148:151], v[212:215], v[4:7]
	v_mfma_f32_16x16x32_bf16 v[0:3], v[172:175], v[212:215], v[0:3]
	s_setprio 0
	s_barrier
	s_add_i32 s61, 0, 0x18000
	s_add_i32 s62, 0, 0x1c000
	v_add_u32_e32 v140, s61, v188
	v_add_u32_e32 v172, s62, v188
	ds_read_b128 v[128:131], v140
	ds_read_b128 v[132:135], v140 offset:1024
	ds_read_b128 v[136:139], v140 offset:2048
	ds_read_b128 v[140:143], v140 offset:3072
	ds_read_b128 v[144:147], v172
	ds_read_b128 v[148:151], v172 offset:1024
	ds_read_b128 v[168:171], v172 offset:2048
	ds_read_b128 v[172:175], v172 offset:3072
	s_add_u32 s28, s36, 0xb0000
	s_addc_u32 s29, s37, 0
	s_mov_b32 m0, s46
	v_lshl_add_u64 v[222:223], s[28:29], 0, v[152:153]
	ds_read_b128 v[176:179], v191 offset:32768
	ds_read_b128 v[180:183], v191 offset:33792
	ds_read_b128 v[192:195], v191 offset:34816
	ds_read_b128 v[196:199], v191 offset:35840
	ds_read_b128 v[200:203], v191 offset:36864
	ds_read_b128 v[204:207], v191 offset:37888
	ds_read_b128 v[208:211], v191 offset:38912
	ds_read_b128 v[212:215], v191 offset:39936
	global_load_lds_dwordx4 v[222:223], off
	v_lshl_add_u64 v[222:223], s[28:29], 0, v[156:157]
	s_mov_b32 m0, s47
	s_nop 0
	global_load_lds_dwordx4 v[222:223], off
	s_waitcnt vmcnt(8)
	s_cmp_lt_u32 s3, 4
	s_cbranch_scc1 .Lgls_22
	s_waitcnt lgkmcnt(0)
; #define PG8_STAGE(bufoff, gbase, voff) do { _Pragma("unroll") for (int _i = 0; _i < 2; ++_i) \
;         __builtin_amdgcn_global_load_lds((const unsigned*)((const char*)(gbase) + (voff)[_i]), (PG8_LAS unsigned*)(lds + (bufoff) + ldsw + _i * 8192), 16, 0, 0); } while (0)
; #define PG8_LDA(dst, b, h) do { _Pragma("unroll") for (int m = 0; m < 4; ++m) _Pragma("unroll") for (int k = 0; k < 2; ++k) dst[m][k] = *(const PG8_LAS bf16x8*)(lds + PG8_SA(b, h) + aoff + m * 2048 + k * 1024); } while (0)
; #define PG8_MMA(ai, bj, At, Bt) do { __builtin_amdgcn_s_setprio(1); _Pragma("unroll") for (int m = 0; m < 4; ++m) _Pragma("unroll") for (int n = 0; n < 2; ++n) _Pragma("unroll") for (int k = 0; k < 2; ++k) \
;         acc[ai][bj][m][n] = mma16<F16>(Bt[n][k], At[m][k], acc[ai][bj][m][n]); __builtin_amdgcn_s_setprio(0); } while (0)
; #define PG8_WAIT_V(n) asm volatile("s_waitcnt vmcnt(" #n ")" ::: "memory")
; #define PG8_WAIT_L(n) asm volatile("s_waitcnt lgkmcnt(" #n ")" ::: "memory")
; #define PG8_BAR __builtin_amdgcn_s_barrier()
; #define PG8_SCHED __builtin_amdgcn_sched_barrier(0)
; template <class Epi, class Sched, bool ALIGN_EPI = false, bool SP2 = false, bool F16 = false>
; __device__ __forceinline__ void gemm_phase(PG8_LAS unsigned char* lds, const Gemm g, const Sched& S, const Epi& E, const int wid_in) {
;     ...
;             PG8_WAIT_V(8); PG8_WAIT_L(0); PG8_BAR; PG8_MMA(0, 0, At, B0); PG8_MMA(0, 1, At, B1); PG8_BAR; PG8_SCHED;
;             PG8_LDA(At, 1, 1); PG8_STAGE(PG8_SB(1, 0), b3, voffB); PG8_STAGE(PG8_SB(1, 1), b3 + hstep, voffB); PG8_STAGE(PG8_SA(1, 0), a3, voffA);
;             PG8_WAIT_V(8); PG8_WAIT_L(0); PG8_BAR; PG8_MMA(1, 0, At, B0); PG8_MMA(1, 1, At, B1); PG8_BAR; PG8_SCHED;
;     ...
;         if constexpr (ALIGN_EPI) { if (wr == 0) PG8_BAR; }
.Lgls_22:
	s_barrier
	s_setprio 1
	s_waitcnt lgkmcnt(0)
	v_mfma_f32_16x16x32_bf16 v[124:127], v[128:131], v[176:179], v[124:127]
	v_mfma_f32_16x16x32_bf16 v[120:123], v[136:139], v[176:179], v[120:123]
	v_mfma_f32_16x16x32_bf16 v[108:111], v[128:131], v[192:195], v[108:111]
	v_mfma_f32_16x16x32_bf16 v[104:107], v[136:139], v[192:195], v[104:107]
	v_mfma_f32_16x16x32_bf16 v[92:95], v[128:131], v[200:203], v[92:95]
	v_mfma_f32_16x16x32_bf16 v[88:91], v[136:139], v[200:203], v[88:91]
	v_mfma_f32_16x16x32_bf16 v[76:79], v[128:131], v[208:211], v[76:79]
	v_mfma_f32_16x16x32_bf16 v[72:75], v[136:139], v[208:211], v[72:75]
	v_mfma_f32_16x16x32_bf16 v[124:127], v[132:135], v[180:183], v[124:127]
	v_mfma_f32_16x16x32_bf16 v[120:123], v[140:143], v[180:183], v[120:123]
	v_mfma_f32_16x16x32_bf16 v[108:111], v[132:135], v[196:199], v[108:111]
	v_mfma_f32_16x16x32_bf16 v[104:107], v[140:143], v[196:199], v[104:107]
	v_mfma_f32_16x16x32_bf16 v[92:95], v[132:135], v[204:207], v[92:95]
	v_mfma_f32_16x16x32_bf16 v[88:91], v[140:143], v[204:207], v[88:91]
	v_mfma_f32_16x16x32_bf16 v[76:79], v[132:135], v[212:215], v[76:79]
	v_mfma_f32_16x16x32_bf16 v[72:75], v[140:143], v[212:215], v[72:75]
	s_setprio 0
	s_setprio 1
	v_mfma_f32_16x16x32_bf16 v[116:119], v[144:147], v[176:179], v[116:119]
	v_mfma_f32_16x16x32_bf16 v[112:115], v[168:171], v[176:179], v[112:115]
	v_mfma_f32_16x16x32_bf16 v[100:103], v[144:147], v[192:195], v[100:103]
	v_mfma_f32_16x16x32_bf16 v[96:99], v[168:171], v[192:195], v[96:99]
	v_mfma_f32_16x16x32_bf16 v[84:87], v[144:147], v[200:203], v[84:87]
	v_mfma_f32_16x16x32_bf16 v[80:83], v[168:171], v[200:203], v[80:83]
	v_mfma_f32_16x16x32_bf16 v[68:71], v[144:147], v[208:211], v[68:71]
	v_mfma_f32_16x16x32_bf16 v[64:67], v[168:171], v[208:211], v[64:67]
	v_mfma_f32_16x16x32_bf16 v[116:119], v[148:151], v[180:183], v[116:119]
	v_mfma_f32_16x16x32_bf16 v[112:115], v[172:175], v[180:183], v[112:115]
	v_mfma_f32_16x16x32_bf16 v[100:103], v[148:151], v[196:199], v[100:103]
	v_mfma_f32_16x16x32_bf16 v[96:99], v[172:175], v[196:199], v[96:99]
	v_mfma_f32_16x16x32_bf16 v[84:87], v[148:151], v[204:207], v[84:87]
	v_mfma_f32_16x16x32_bf16 v[80:83], v[172:175], v[204:207], v[80:83]
	v_mfma_f32_16x16x32_bf16 v[68:71], v[148:151], v[212:215], v[68:71]
	v_mfma_f32_16x16x32_bf16 v[64:67], v[172:175], v[212:215], v[64:67]
	s_setprio 0
	s_barrier
	s_add_i32 s28, s61, s68
	v_lshl_add_u64 v[184:185], v[184:185], 0, s[24:25]
	s_mov_b32 m0, s28
	ds_read_b128 v[176:179], v191 offset:49152
	ds_read_b128 v[180:183], v191 offset:50176
	ds_read_b128 v[192:195], v191 offset:51200
	ds_read_b128 v[196:199], v191 offset:52224
	ds_read_b128 v[200:203], v191 offset:53248
	ds_read_b128 v[204:207], v191 offset:54272
	ds_read_b128 v[208:211], v191 offset:55296
	ds_read_b128 v[212:215], v191 offset:56320
	global_load_lds_dwordx4 v[184:185], off
	s_add_i32 m0, s28, 0x2000
	s_add_u32 s28, s34, 0xb0080
	v_lshl_add_u64 v[184:185], v[216:217], 0, s[24:25]
	s_addc_u32 s29, s35, 0
	s_add_i32 s34, s62, s68
	global_load_lds_dwordx4 v[184:185], off
	v_lshl_add_u64 v[184:185], s[28:29], 0, v[154:155]
	s_mov_b32 m0, s34
	s_nop 0
	global_load_lds_dwordx4 v[184:185], off
	v_lshl_add_u64 v[184:185], s[28:29], 0, v[158:159]
	s_add_i32 m0, s34, 0x2000
	s_nop 0
	global_load_lds_dwordx4 v[184:185], off
	v_lshl_add_u64 v[184:185], v[218:219], 0, s[24:25]
	s_mov_b32 m0, s75
	s_nop 0
	global_load_lds_dwordx4 v[184:185], off
	v_lshl_add_u64 v[184:185], v[220:221], 0, s[24:25]
	s_mov_b32 m0, s48
	s_nop 0
	global_load_lds_dwordx4 v[184:185], off
	s_waitcnt vmcnt(8)
	s_cmp_lt_u32 s3, 4
	s_cbranch_scc1 .Lgls_23
	s_waitcnt lgkmcnt(0)
.Lgls_23:
	s_barrier
	s_setprio 1
	s_waitcnt lgkmcnt(0)
	v_mfma_f32_16x16x32_bf16 v[60:63], v[128:131], v[176:179], v[60:63]
	v_mfma_f32_16x16x32_bf16 v[56:59], v[136:139], v[176:179], v[56:59]
	v_mfma_f32_16x16x32_bf16 v[44:47], v[128:131], v[192:195], v[44:47]
	v_mfma_f32_16x16x32_bf16 v[40:43], v[136:139], v[192:195], v[40:43]
	v_mfma_f32_16x16x32_bf16 v[28:31], v[128:131], v[200:203], v[28:31]
	v_mfma_f32_16x16x32_bf16 v[24:27], v[136:139], v[200:203], v[24:27]
	v_mfma_f32_16x16x32_bf16 v[12:15], v[128:131], v[208:211], v[12:15]
	v_mfma_f32_16x16x32_bf16 v[8:11], v[136:139], v[208:211], v[8:11]
	v_mfma_f32_16x16x32_bf16 v[60:63], v[132:135], v[180:183], v[60:63]
	v_mfma_f32_16x16x32_bf16 v[56:59], v[140:143], v[180:183], v[56:59]
	v_mfma_f32_16x16x32_bf16 v[44:47], v[132:135], v[196:199], v[44:47]
	v_mfma_f32_16x16x32_bf16 v[40:43], v[140:143], v[196:199], v[40:43]
	v_mfma_f32_16x16x32_bf16 v[28:31], v[132:135], v[204:207], v[28:31]
	v_mfma_f32_16x16x32_bf16 v[24:27], v[140:143], v[204:207], v[24:27]
	v_mfma_f32_16x16x32_bf16 v[12:15], v[132:135], v[212:215], v[12:15]
	v_mfma_f32_16x16x32_bf16 v[8:11], v[140:143], v[212:215], v[8:11]
	s_setprio 0
	s_setprio 1
	v_mfma_f32_16x16x32_bf16 v[52:55], v[144:147], v[176:179], v[52:55]
	v_mfma_f32_16x16x32_bf16 v[48:51], v[168:171], v[176:179], v[48:51]
	v_mfma_f32_16x16x32_bf16 v[36:39], v[144:147], v[192:195], v[36:39]
	v_mfma_f32_16x16x32_bf16 v[32:35], v[168:171], v[192:195], v[32:35]
	v_mfma_f32_16x16x32_bf16 v[20:23], v[144:147], v[200:203], v[20:23]
	v_mfma_f32_16x16x32_bf16 v[16:19], v[168:171], v[200:203], v[16:19]
	v_mfma_f32_16x16x32_bf16 v[4:7], v[144:147], v[208:211], v[4:7]
	v_mfma_f32_16x16x32_bf16 v[0:3], v[168:171], v[208:211], v[0:3]
	v_mfma_f32_16x16x32_bf16 v[52:55], v[148:151], v[180:183], v[52:55]
	v_mfma_f32_16x16x32_bf16 v[48:51], v[172:175], v[180:183], v[48:51]
	v_mfma_f32_16x16x32_bf16 v[36:39], v[148:151], v[196:199], v[36:39]
	v_mfma_f32_16x16x32_bf16 v[32:35], v[172:175], v[196:199], v[32:35]
	v_mfma_f32_16x16x32_bf16 v[20:23], v[148:151], v[204:207], v[20:23]
	v_mfma_f32_16x16x32_bf16 v[16:19], v[172:175], v[204:207], v[16:19]
	v_mfma_f32_16x16x32_bf16 v[4:7], v[148:151], v[212:215], v[4:7]
	v_mfma_f32_16x16x32_bf16 v[0:3], v[172:175], v[212:215], v[0:3]
	s_setprio 0
	s_barrier
	s_add_i32 s60, s60, 2
	s_add_u32 s43, s43, 0x100
	s_addc_u32 s59, s59, 0
	s_cmp_gt_u32 s60, 41
	s_mov_b64 s[28:29], s[30:31]
	s_cbranch_scc0 .LBB0_716
	s_and_b64 vcc, exec, s[16:17]
	s_cbranch_vccz .LBB0_719
	s_barrier

; #define PG8_STAGE(bufoff, gbase, voff) do { _Pragma("unroll") for (int _i = 0; _i < 2; ++_i) \
;         __builtin_amdgcn_global_load_lds((const unsigned*)((const char*)(gbase) + (voff)[_i]), (PG8_LAS unsigned*)(lds + (bufoff) + ldsw + _i * 8192), 16, 0, 0); } while (0)
; #define PG8_LDA(dst, b, h) do { _Pragma("unroll") for (int m = 0; m < 4; ++m) _Pragma("unroll") for (int k = 0; k < 2; ++k) dst[m][k] = *(const PG8_LAS bf16x8*)(lds + PG8_SA(b, h) + aoff + m * 2048 + k * 1024); } while (0)
; #define PG8_LDB(dst, b, h) do { _Pragma("unroll") for (int n = 0; n < 2; ++n) _Pragma("unroll") for (int k = 0; k < 2; ++k) dst[n][k] = *(const PG8_LAS bf16x8*)(lds + PG8_SB(b, h) + boff + n * 2048 + k * 1024); } while (0)
; #define PG8_MMA(ai, bj, At, Bt) do { __builtin_amdgcn_s_setprio(1); _Pragma("unroll") for (int m = 0; m < 4; ++m) _Pragma("unroll") for (int n = 0; n < 2; ++n) _Pragma("unroll") for (int k = 0; k < 2; ++k) \
;         acc[ai][bj][m][n] = mma16<F16>(Bt[n][k], At[m][k], acc[ai][bj][m][n]); __builtin_amdgcn_s_setprio(0); } while (0)
; #define PG8_WAIT_V(n) asm volatile("s_waitcnt vmcnt(" #n ")" ::: "memory")
; #define PG8_WAIT_L(n) asm volatile("s_waitcnt lgkmcnt(" #n ")" ::: "memory")
; template <class Epi, class Sched, bool ALIGN_EPI = false, bool SP2 = false, bool F16 = false>
; __device__ __forceinline__ void gemm_phase(PG8_LAS unsigned char* lds, const Gemm g, const Sched& S, const Epi& E, const int wid_in) {
;     ...
;             const bool last = (t == nt - 2);
;             const char* a1 = cA + (size_t)(t + 1) * kstep;
;             const char* a2 = last ? nA : cA + (size_t)(t + 2) * kstep; const char* b2 = last ? nB : cB + (size_t)(t + 2) * kstep;
;             const char* a3 = a2 + kstep; const char* b3 = b2 + kstep;
;             if (last && has_next) S.a_ready(nxt);
;             if constexpr (SP2) {
;             PG8_LDB(B0, 0, 0); PG8_LDB(B1, 0, 1); PG8_SCHED; PG8_LDA(At, 0, 0); PG8_STAGE(PG8_SA(1, 1), a1 + hstep, voffA);
;             PG8_WAIT_V(8); PG8_WAIT_L(0); PG8_BAR; PG8_MMA(0, 0, At, B0); PG8_MMA(0, 1, At, B1); PG8_BAR; PG8_SCHED;
;             PG8_LDA(At, 0, 1); PG8_STAGE(PG8_SB(0, 0), b2, voffB); PG8_STAGE(PG8_SB(0, 1), b2 + hstep, voffB); PG8_STAGE(PG8_SA(0, 0), a2, voffA);
;             PG8_WAIT_V(8); PG8_WAIT_L(0); PG8_BAR; PG8_MMA(1, 0, At, B0); PG8_MMA(1, 1, At, B1); PG8_BAR; PG8_SCHED;
.LBB0_812:
	ds_read_b128 v[112:115], v235
	ds_read_b128 v[116:119], v235 offset:1024
	ds_read_b128 v[128:131], v235 offset:2048
	ds_read_b128 v[132:135], v235 offset:3072
	ds_read_b128 v[144:147], v236
	ds_read_b128 v[148:151], v236 offset:1024
	ds_read_b128 v[152:155], v236 offset:2048
	ds_read_b128 v[156:159], v236 offset:3072
	s_add_u32 s43, s46, 0xfffc0080
	s_addc_u32 s45, s47, -1
	s_cmp_eq_u32 s42, 12
	s_cselect_b32 s51, s14, s45
	s_cselect_b32 s50, s15, s43
	s_cselect_b32 s49, s29, s41
	s_cselect_b32 s48, s31, s40
	v_lshl_add_u64 v[192:193], s[46:47], 0, v[204:205]
	s_add_i32 m0, s74, 0xc000
	ds_read_b128 v[160:163], v237
	ds_read_b128 v[164:167], v237 offset:1024
	ds_read_b128 v[168:171], v237 offset:2048
	ds_read_b128 v[172:175], v237 offset:3072
	ds_read_b128 v[176:179], v237 offset:4096
	ds_read_b128 v[180:183], v237 offset:5120
	ds_read_b128 v[184:187], v237 offset:6144
	ds_read_b128 v[188:191], v237 offset:7168
	global_load_lds_dwordx4 v[192:193], off
	v_lshl_add_u64 v[192:193], s[46:47], 0, v[206:207]
	s_add_i32 m0, s74, 0xe000
	s_nop 0
	global_load_lds_dwordx4 v[192:193], off
	s_waitcnt vmcnt(8)
	s_cmp_lt_u32 s3, 4
	s_cbranch_scc1 .Lgls_24
	s_waitcnt lgkmcnt(0)
.Lgls_24:
	s_barrier
	s_setprio 1
	s_waitcnt lgkmcnt(0)
	v_mfma_f32_16x16x32_f16 v[140:143], v[112:115], v[160:163], v[140:143]
	v_mfma_f32_16x16x32_f16 v[136:139], v[128:131], v[160:163], v[136:139]
	v_mfma_f32_16x16x32_f16 v[108:111], v[112:115], v[168:171], v[108:111]
	v_mfma_f32_16x16x32_f16 v[104:107], v[128:131], v[168:171], v[104:107]
	v_mfma_f32_16x16x32_f16 v[92:95], v[112:115], v[176:179], v[92:95]
	v_mfma_f32_16x16x32_f16 v[88:91], v[128:131], v[176:179], v[88:91]
	v_mfma_f32_16x16x32_f16 v[76:79], v[112:115], v[184:187], v[76:79]
	v_mfma_f32_16x16x32_f16 v[72:75], v[128:131], v[184:187], v[72:75]
	v_mfma_f32_16x16x32_f16 v[140:143], v[116:119], v[164:167], v[140:143]
	v_mfma_f32_16x16x32_f16 v[136:139], v[132:135], v[164:167], v[136:139]
	v_mfma_f32_16x16x32_f16 v[108:111], v[116:119], v[172:175], v[108:111]
	v_mfma_f32_16x16x32_f16 v[104:107], v[132:135], v[172:175], v[104:107]
	v_mfma_f32_16x16x32_f16 v[92:95], v[116:119], v[180:183], v[92:95]
	v_mfma_f32_16x16x32_f16 v[88:91], v[132:135], v[180:183], v[88:91]
	v_mfma_f32_16x16x32_f16 v[76:79], v[116:119], v[188:191], v[76:79]
	v_mfma_f32_16x16x32_f16 v[72:75], v[132:135], v[188:191], v[72:75]
	s_setprio 0
	s_setprio 1
	v_mfma_f32_16x16x32_f16 v[124:127], v[144:147], v[160:163], v[124:127]
	v_mfma_f32_16x16x32_f16 v[120:123], v[152:155], v[160:163], v[120:123]
	v_mfma_f32_16x16x32_f16 v[100:103], v[144:147], v[168:171], v[100:103]
	v_mfma_f32_16x16x32_f16 v[96:99], v[152:155], v[168:171], v[96:99]
	v_mfma_f32_16x16x32_f16 v[84:87], v[144:147], v[176:179], v[84:87]
	v_mfma_f32_16x16x32_f16 v[80:83], v[152:155], v[176:179], v[80:83]
	v_mfma_f32_16x16x32_f16 v[68:71], v[144:147], v[184:187], v[68:71]
	v_mfma_f32_16x16x32_f16 v[64:67], v[152:155], v[184:187], v[64:67]
	v_mfma_f32_16x16x32_f16 v[124:127], v[148:151], v[164:167], v[124:127]
	v_mfma_f32_16x16x32_f16 v[120:123], v[156:159], v[164:167], v[120:123]
	v_mfma_f32_16x16x32_f16 v[100:103], v[148:151], v[172:175], v[100:103]
	v_mfma_f32_16x16x32_f16 v[96:99], v[156:159], v[172:175], v[96:99]
	v_mfma_f32_16x16x32_f16 v[84:87], v[148:151], v[180:183], v[84:87]
	v_mfma_f32_16x16x32_f16 v[80:83], v[156:159], v[180:183], v[80:83]
	v_mfma_f32_16x16x32_f16 v[68:71], v[148:151], v[188:191], v[68:71]
	v_mfma_f32_16x16x32_f16 v[64:67], v[156:159], v[188:191], v[64:67]
	s_setprio 0
	s_barrier
	s_add_i32 s43, s64, s68
	v_lshl_add_u64 v[192:193], s[48:49], 0, v[198:199]
	s_mov_b32 m0, s43
	ds_read_b128 v[160:163], v237 offset:16384
	ds_read_b128 v[164:167], v237 offset:17408
	ds_read_b128 v[168:171], v237 offset:18432
	ds_read_b128 v[172:175], v237 offset:19456
	ds_read_b128 v[176:179], v237 offset:20480
	ds_read_b128 v[180:183], v237 offset:21504
	ds_read_b128 v[184:187], v237 offset:22528
	ds_read_b128 v[188:191], v237 offset:23552
	global_load_lds_dwordx4 v[192:193], off
	s_add_i32 m0, s43, 0x2000
	s_add_u32 s86, s48, 0x40000
	v_lshl_add_u64 v[194:195], s[48:49], 0, v[202:203]
	s_addc_u32 s87, s49, 0
	s_add_i32 s43, s65, s68
	global_load_lds_dwordx4 v[194:195], off
	v_lshl_add_u64 v[212:213], s[86:87], 0, v[198:199]
	s_mov_b32 m0, s43
	v_lshl_add_u64 v[214:215], s[50:51], 0, v[200:201]
	global_load_lds_dwordx4 v[212:213], off
	v_lshl_add_u64 v[212:213], s[86:87], 0, v[202:203]
	s_add_i32 m0, s43, 0x2000
	s_nop 0
	global_load_lds_dwordx4 v[212:213], off
	v_lshl_add_u64 v[212:213], s[50:51], 0, v[196:197]
	s_mov_b32 m0, s74
	s_nop 0
	global_load_lds_dwordx4 v[212:213], off
	s_mov_b32 m0, s55
	s_nop 0
	global_load_lds_dwordx4 v[214:215], off
	s_waitcnt vmcnt(8)
	s_cmp_lt_u32 s3, 4
	s_cbranch_scc1 .Lgls_25
	s_waitcnt lgkmcnt(0)
; #define PG8_STAGE(bufoff, gbase, voff) do { _Pragma("unroll") for (int _i = 0; _i < 2; ++_i) \
;         __builtin_amdgcn_global_load_lds((const unsigned*)((const char*)(gbase) + (voff)[_i]), (PG8_LAS unsigned*)(lds + (bufoff) + ldsw + _i * 8192), 16, 0, 0); } while (0)
; #define PG8_LDA(dst, b, h) do { _Pragma("unroll") for (int m = 0; m < 4; ++m) _Pragma("unroll") for (int k = 0; k < 2; ++k) dst[m][k] = *(const PG8_LAS bf16x8*)(lds + PG8_SA(b, h) + aoff + m * 2048 + k * 1024); } while (0)
; #define PG8_LDB(dst, b, h) do { _Pragma("unroll") for (int n = 0; n < 2; ++n) _Pragma("unroll") for (int k = 0; k < 2; ++k) dst[n][k] = *(const PG8_LAS bf16x8*)(lds + PG8_SB(b, h) + boff + n * 2048 + k * 1024); } while (0)
; #define PG8_MMA(ai, bj, At, Bt) do { __builtin_amdgcn_s_setprio(1); _Pragma("unroll") for (int m = 0; m < 4; ++m) _Pragma("unroll") for (int n = 0; n < 2; ++n) _Pragma("unroll") for (int k = 0; k < 2; ++k) \
;         acc[ai][bj][m][n] = mma16<F16>(Bt[n][k], At[m][k], acc[ai][bj][m][n]); __builtin_amdgcn_s_setprio(0); } while (0)
; #define PG8_WAIT_V(n) asm volatile("s_waitcnt vmcnt(" #n ")" ::: "memory")
; #define PG8_WAIT_L(n) asm volatile("s_waitcnt lgkmcnt(" #n ")" ::: "memory")
; #define PG8_BAR __builtin_amdgcn_s_barrier()
; #define PG8_SCHED __builtin_amdgcn_sched_barrier(0)
; template <class Epi, class Sched, bool ALIGN_EPI = false, bool SP2 = false, bool F16 = false>
; __device__ __forceinline__ void gemm_phase(PG8_LAS unsigned char* lds, const Gemm g, const Sched& S, const Epi& E, const int wid_in) {
;     ...
;             PG8_WAIT_V(8); PG8_WAIT_L(0); PG8_BAR; PG8_MMA(1, 0, At, B0); PG8_MMA(1, 1, At, B1); PG8_BAR; PG8_SCHED;
;             PG8_LDB(B0, 1, 0); PG8_LDB(B1, 1, 1); PG8_SCHED; PG8_LDA(At, 1, 0); PG8_STAGE(PG8_SA(0, 1), a2 + hstep, voffA);
;             PG8_WAIT_V(8); PG8_WAIT_L(0); PG8_BAR; PG8_MMA(0, 0, At, B0); PG8_MMA(0, 1, At, B1); PG8_BAR; PG8_SCHED;
.Lgls_25:
	s_barrier
	s_setprio 1
	s_waitcnt lgkmcnt(0)
	v_mfma_f32_16x16x32_f16 v[60:63], v[112:115], v[160:163], v[60:63]
	v_mfma_f32_16x16x32_f16 v[56:59], v[128:131], v[160:163], v[56:59]
	v_mfma_f32_16x16x32_f16 v[44:47], v[112:115], v[168:171], v[44:47]
	v_mfma_f32_16x16x32_f16 v[40:43], v[128:131], v[168:171], v[40:43]
	v_mfma_f32_16x16x32_f16 v[28:31], v[112:115], v[176:179], v[28:31]
	v_mfma_f32_16x16x32_f16 v[24:27], v[128:131], v[176:179], v[24:27]
	v_mfma_f32_16x16x32_f16 v[12:15], v[112:115], v[184:187], v[12:15]
	v_mfma_f32_16x16x32_f16 v[8:11], v[128:131], v[184:187], v[8:11]
	v_mfma_f32_16x16x32_f16 v[60:63], v[116:119], v[164:167], v[60:63]
	v_mfma_f32_16x16x32_f16 v[56:59], v[132:135], v[164:167], v[56:59]
	v_mfma_f32_16x16x32_f16 v[44:47], v[116:119], v[172:175], v[44:47]
	v_mfma_f32_16x16x32_f16 v[40:43], v[132:135], v[172:175], v[40:43]
	v_mfma_f32_16x16x32_f16 v[28:31], v[116:119], v[180:183], v[28:31]
	v_mfma_f32_16x16x32_f16 v[24:27], v[132:135], v[180:183], v[24:27]
	v_mfma_f32_16x16x32_f16 v[12:15], v[116:119], v[188:191], v[12:15]
	v_mfma_f32_16x16x32_f16 v[8:11], v[132:135], v[188:191], v[8:11]
	s_setprio 0
	s_setprio 1
	v_mfma_f32_16x16x32_f16 v[52:55], v[144:147], v[160:163], v[52:55]
	v_mfma_f32_16x16x32_f16 v[48:51], v[152:155], v[160:163], v[48:51]
	v_mfma_f32_16x16x32_f16 v[36:39], v[144:147], v[168:171], v[36:39]
	v_mfma_f32_16x16x32_f16 v[32:35], v[152:155], v[168:171], v[32:35]
	v_mfma_f32_16x16x32_f16 v[20:23], v[144:147], v[176:179], v[20:23]
	v_mfma_f32_16x16x32_f16 v[16:19], v[152:155], v[176:179], v[16:19]
	v_mfma_f32_16x16x32_f16 v[4:7], v[144:147], v[184:187], v[4:7]
	v_mfma_f32_16x16x32_f16 v[0:3], v[152:155], v[184:187], v[0:3]
	v_mfma_f32_16x16x32_f16 v[52:55], v[148:151], v[164:167], v[52:55]
	v_mfma_f32_16x16x32_f16 v[48:51], v[156:159], v[164:167], v[48:51]
	v_mfma_f32_16x16x32_f16 v[36:39], v[148:151], v[172:175], v[36:39]
	v_mfma_f32_16x16x32_f16 v[32:35], v[156:159], v[172:175], v[32:35]
	v_mfma_f32_16x16x32_f16 v[20:23], v[148:151], v[180:183], v[20:23]
	v_mfma_f32_16x16x32_f16 v[16:19], v[156:159], v[180:183], v[16:19]
	v_mfma_f32_16x16x32_f16 v[4:7], v[148:151], v[188:191], v[4:7]
	v_mfma_f32_16x16x32_f16 v[0:3], v[156:159], v[188:191], v[0:3]
	s_setprio 0
	s_barrier
	s_add_i32 s43, 0, 0x18000
	s_add_i32 s45, 0, 0x1c000
	v_add_u32_e32 v132, s43, v234
	v_add_u32_e32 v156, s45, v234
	ds_read_b128 v[112:115], v132
	ds_read_b128 v[116:119], v132 offset:1024
	ds_read_b128 v[128:131], v132 offset:2048
	ds_read_b128 v[132:135], v132 offset:3072
	ds_read_b128 v[144:147], v156
	ds_read_b128 v[148:151], v156 offset:1024
	ds_read_b128 v[152:155], v156 offset:2048
	ds_read_b128 v[156:159], v156 offset:3072
	s_add_u32 s50, s50, 0x40000
	s_addc_u32 s51, s51, 0
	s_mov_b32 m0, s58
	v_lshl_add_u64 v[216:217], s[50:51], 0, v[196:197]
	ds_read_b128 v[160:163], v237 offset:32768
	ds_read_b128 v[164:167], v237 offset:33792
	ds_read_b128 v[168:171], v237 offset:34816
	ds_read_b128 v[172:175], v237 offset:35840
	ds_read_b128 v[176:179], v237 offset:36864
	ds_read_b128 v[180:183], v237 offset:37888
	ds_read_b128 v[184:187], v237 offset:38912
	ds_read_b128 v[188:191], v237 offset:39936
	global_load_lds_dwordx4 v[216:217], off
	v_lshl_add_u64 v[216:217], s[50:51], 0, v[200:201]
	s_mov_b32 m0, s59
	s_nop 0
	global_load_lds_dwordx4 v[216:217], off
	s_waitcnt vmcnt(8)
	s_cmp_lt_u32 s3, 4
	s_cbranch_scc1 .Lgls_26
	s_waitcnt lgkmcnt(0)
; #define PG8_STAGE(bufoff, gbase, voff) do { _Pragma("unroll") for (int _i = 0; _i < 2; ++_i) \
;         __builtin_amdgcn_global_load_lds((const unsigned*)((const char*)(gbase) + (voff)[_i]), (PG8_LAS unsigned*)(lds + (bufoff) + ldsw + _i * 8192), 16, 0, 0); } while (0)
; #define PG8_LDA(dst, b, h) do { _Pragma("unroll") for (int m = 0; m < 4; ++m) _Pragma("unroll") for (int k = 0; k < 2; ++k) dst[m][k] = *(const PG8_LAS bf16x8*)(lds + PG8_SA(b, h) + aoff + m * 2048 + k * 1024); } while (0)
; #define PG8_MMA(ai, bj, At, Bt) do { __builtin_amdgcn_s_setprio(1); _Pragma("unroll") for (int m = 0; m < 4; ++m) _Pragma("unroll") for (int n = 0; n < 2; ++n) _Pragma("unroll") for (int k = 0; k < 2; ++k) \
;         acc[ai][bj][m][n] = mma16<F16>(Bt[n][k], At[m][k], acc[ai][bj][m][n]); __builtin_amdgcn_s_setprio(0); } while (0)
; #define PG8_WAIT_V(n) asm volatile("s_waitcnt vmcnt(" #n ")" ::: "memory")
; #define PG8_WAIT_L(n) asm volatile("s_waitcnt lgkmcnt(" #n ")" ::: "memory")
; #define PG8_BAR __builtin_amdgcn_s_barrier()
; #define PG8_SCHED __builtin_amdgcn_sched_barrier(0)
; template <class Epi, class Sched, bool ALIGN_EPI = false, bool SP2 = false, bool F16 = false>
; __device__ __forceinline__ void gemm_phase(PG8_LAS unsigned char* lds, const Gemm g, const Sched& S, const Epi& E, const int wid_in) {
;     ...
;             PG8_WAIT_V(8); PG8_WAIT_L(0); PG8_BAR; PG8_MMA(0, 0, At, B0); PG8_MMA(0, 1, At, B1); PG8_BAR; PG8_SCHED;
;             PG8_LDA(At, 1, 1); PG8_STAGE(PG8_SB(1, 0), b3, voffB); PG8_STAGE(PG8_SB(1, 1), b3 + hstep, voffB); PG8_STAGE(PG8_SA(1, 0), a3, voffA);
;             PG8_WAIT_V(8); PG8_WAIT_L(0); PG8_BAR; PG8_MMA(1, 0, At, B0); PG8_MMA(1, 1, At, B1); PG8_BAR; PG8_SCHED;
;     ...
;         if constexpr (ALIGN_EPI) { if (wr == 0) PG8_BAR; }
.Lgls_26:
	s_barrier
	s_setprio 1
	s_waitcnt lgkmcnt(0)
	v_mfma_f32_16x16x32_f16 v[140:143], v[112:115], v[160:163], v[140:143]
	v_mfma_f32_16x16x32_f16 v[136:139], v[128:131], v[160:163], v[136:139]
	v_mfma_f32_16x16x32_f16 v[108:111], v[112:115], v[168:171], v[108:111]
	v_mfma_f32_16x16x32_f16 v[104:107], v[128:131], v[168:171], v[104:107]
	v_mfma_f32_16x16x32_f16 v[92:95], v[112:115], v[176:179], v[92:95]
	v_mfma_f32_16x16x32_f16 v[88:91], v[128:131], v[176:179], v[88:91]
	v_mfma_f32_16x16x32_f16 v[76:79], v[112:115], v[184:187], v[76:79]
	v_mfma_f32_16x16x32_f16 v[72:75], v[128:131], v[184:187], v[72:75]
	v_mfma_f32_16x16x32_f16 v[140:143], v[116:119], v[164:167], v[140:143]
	v_mfma_f32_16x16x32_f16 v[136:139], v[132:135], v[164:167], v[136:139]
	v_mfma_f32_16x16x32_f16 v[108:111], v[116:119], v[172:175], v[108:111]
	v_mfma_f32_16x16x32_f16 v[104:107], v[132:135], v[172:175], v[104:107]
	v_mfma_f32_16x16x32_f16 v[92:95], v[116:119], v[180:183], v[92:95]
	v_mfma_f32_16x16x32_f16 v[88:91], v[132:135], v[180:183], v[88:91]
	v_mfma_f32_16x16x32_f16 v[76:79], v[116:119], v[188:191], v[76:79]
	v_mfma_f32_16x16x32_f16 v[72:75], v[132:135], v[188:191], v[72:75]
	s_setprio 0
	s_setprio 1
	v_mfma_f32_16x16x32_f16 v[124:127], v[144:147], v[160:163], v[124:127]
	v_mfma_f32_16x16x32_f16 v[120:123], v[152:155], v[160:163], v[120:123]
	v_mfma_f32_16x16x32_f16 v[100:103], v[144:147], v[168:171], v[100:103]
	v_mfma_f32_16x16x32_f16 v[96:99], v[152:155], v[168:171], v[96:99]
	v_mfma_f32_16x16x32_f16 v[84:87], v[144:147], v[176:179], v[84:87]
	v_mfma_f32_16x16x32_f16 v[80:83], v[152:155], v[176:179], v[80:83]
	v_mfma_f32_16x16x32_f16 v[68:71], v[144:147], v[184:187], v[68:71]
	v_mfma_f32_16x16x32_f16 v[64:67], v[152:155], v[184:187], v[64:67]
	v_mfma_f32_16x16x32_f16 v[124:127], v[148:151], v[164:167], v[124:127]
	v_mfma_f32_16x16x32_f16 v[120:123], v[156:159], v[164:167], v[120:123]
	v_mfma_f32_16x16x32_f16 v[100:103], v[148:151], v[172:175], v[100:103]
	v_mfma_f32_16x16x32_f16 v[96:99], v[156:159], v[172:175], v[96:99]
	v_mfma_f32_16x16x32_f16 v[84:87], v[148:151], v[180:183], v[84:87]
	v_mfma_f32_16x16x32_f16 v[80:83], v[156:159], v[180:183], v[80:83]
	v_mfma_f32_16x16x32_f16 v[68:71], v[148:151], v[188:191], v[68:71]
	v_mfma_f32_16x16x32_f16 v[64:67], v[156:159], v[188:191], v[64:67]
	s_setprio 0
	s_barrier
	s_add_i32 s43, s43, s68
	v_lshl_add_u64 v[192:193], v[192:193], 0, s[26:27]
	s_mov_b32 m0, s43
	ds_read_b128 v[160:163], v237 offset:49152
	ds_read_b128 v[164:167], v237 offset:50176
	ds_read_b128 v[168:171], v237 offset:51200
	ds_read_b128 v[172:175], v237 offset:52224
	ds_read_b128 v[176:179], v237 offset:53248
	ds_read_b128 v[180:183], v237 offset:54272
	ds_read_b128 v[184:187], v237 offset:55296
	ds_read_b128 v[188:191], v237 offset:56320
	global_load_lds_dwordx4 v[192:193], off
	s_add_i32 m0, s43, 0x2000
	s_add_u32 s48, s48, 0x40080
	v_lshl_add_u64 v[192:193], v[194:195], 0, s[26:27]
	s_addc_u32 s49, s49, 0
	s_add_i32 s43, s45, s68
	global_load_lds_dwordx4 v[192:193], off
	v_lshl_add_u64 v[192:193], s[48:49], 0, v[198:199]
	s_mov_b32 m0, s43
	s_nop 0
	global_load_lds_dwordx4 v[192:193], off
	v_lshl_add_u64 v[192:193], s[48:49], 0, v[202:203]
	s_add_i32 m0, s43, 0x2000
	s_nop 0
	global_load_lds_dwordx4 v[192:193], off
	v_lshl_add_u64 v[192:193], v[212:213], 0, s[26:27]
	s_mov_b32 m0, s75
	s_nop 0
	global_load_lds_dwordx4 v[192:193], off
	v_lshl_add_u64 v[192:193], v[214:215], 0, s[26:27]
	s_mov_b32 m0, s60
	s_nop 0
	global_load_lds_dwordx4 v[192:193], off
	s_waitcnt vmcnt(8)
	s_cmp_lt_u32 s3, 4
	s_cbranch_scc1 .Lgls_27
	s_waitcnt lgkmcnt(0)
.Lgls_27:
	s_barrier
	s_setprio 1
	s_waitcnt lgkmcnt(0)
	v_mfma_f32_16x16x32_f16 v[60:63], v[112:115], v[160:163], v[60:63]
	v_mfma_f32_16x16x32_f16 v[56:59], v[128:131], v[160:163], v[56:59]
	v_mfma_f32_16x16x32_f16 v[44:47], v[112:115], v[168:171], v[44:47]
	v_mfma_f32_16x16x32_f16 v[40:43], v[128:131], v[168:171], v[40:43]
	v_mfma_f32_16x16x32_f16 v[28:31], v[112:115], v[176:179], v[28:31]
	v_mfma_f32_16x16x32_f16 v[24:27], v[128:131], v[176:179], v[24:27]
	v_mfma_f32_16x16x32_f16 v[12:15], v[112:115], v[184:187], v[12:15]
	v_mfma_f32_16x16x32_f16 v[8:11], v[128:131], v[184:187], v[8:11]
	v_mfma_f32_16x16x32_f16 v[60:63], v[116:119], v[164:167], v[60:63]
	v_mfma_f32_16x16x32_f16 v[56:59], v[132:135], v[164:167], v[56:59]
	v_mfma_f32_16x16x32_f16 v[44:47], v[116:119], v[172:175], v[44:47]
	v_mfma_f32_16x16x32_f16 v[40:43], v[132:135], v[172:175], v[40:43]
	v_mfma_f32_16x16x32_f16 v[28:31], v[116:119], v[180:183], v[28:31]
	v_mfma_f32_16x16x32_f16 v[24:27], v[132:135], v[180:183], v[24:27]
	v_mfma_f32_16x16x32_f16 v[12:15], v[116:119], v[188:191], v[12:15]
	v_mfma_f32_16x16x32_f16 v[8:11], v[132:135], v[188:191], v[8:11]
	s_setprio 0
	s_setprio 1
	v_mfma_f32_16x16x32_f16 v[52:55], v[144:147], v[160:163], v[52:55]
	v_mfma_f32_16x16x32_f16 v[48:51], v[152:155], v[160:163], v[48:51]
	v_mfma_f32_16x16x32_f16 v[36:39], v[144:147], v[168:171], v[36:39]
	v_mfma_f32_16x16x32_f16 v[32:35], v[152:155], v[168:171], v[32:35]
	v_mfma_f32_16x16x32_f16 v[20:23], v[144:147], v[176:179], v[20:23]
	v_mfma_f32_16x16x32_f16 v[16:19], v[152:155], v[176:179], v[16:19]
	v_mfma_f32_16x16x32_f16 v[4:7], v[144:147], v[184:187], v[4:7]
	v_mfma_f32_16x16x32_f16 v[0:3], v[152:155], v[184:187], v[0:3]
	v_mfma_f32_16x16x32_f16 v[52:55], v[148:151], v[164:167], v[52:55]
	v_mfma_f32_16x16x32_f16 v[48:51], v[156:159], v[164:167], v[48:51]
	v_mfma_f32_16x16x32_f16 v[36:39], v[148:151], v[172:175], v[36:39]
	v_mfma_f32_16x16x32_f16 v[32:35], v[156:159], v[172:175], v[32:35]
	v_mfma_f32_16x16x32_f16 v[20:23], v[148:151], v[180:183], v[20:23]
	v_mfma_f32_16x16x32_f16 v[16:19], v[156:159], v[180:183], v[16:19]
	v_mfma_f32_16x16x32_f16 v[4:7], v[148:151], v[188:191], v[4:7]
	v_mfma_f32_16x16x32_f16 v[0:3], v[156:159], v[188:191], v[0:3]
	s_setprio 0
	s_barrier
	s_add_i32 s42, s42, 2
	s_add_u32 s46, s46, 0x100
	s_addc_u32 s47, s47, 0
	s_add_u32 s40, s40, 0x100
	s_addc_u32 s41, s41, 0
	s_cmp_gt_u32 s42, 13
	s_cbranch_scc0 .LBB0_812
	s_and_b64 vcc, exec, s[16:17]
	s_cbranch_vccz .LBB0_815
	s_barrier

; #define PG8_STAGE(bufoff, gbase, voff) do { _Pragma("unroll") for (int _i = 0; _i < 2; ++_i) \
;         __builtin_amdgcn_global_load_lds((const unsigned*)((const char*)(gbase) + (voff)[_i]), (PG8_LAS unsigned*)(lds + (bufoff) + ldsw + _i * 8192), 16, 0, 0); } while (0)
; #define PG8_LDA(dst, b, h) do { _Pragma("unroll") for (int m = 0; m < 4; ++m) _Pragma("unroll") for (int k = 0; k < 2; ++k) dst[m][k] = *(const PG8_LAS bf16x8*)(lds + PG8_SA(b, h) + aoff + m * 2048 + k * 1024); } while (0)
; #define PG8_LDB(dst, b, h) do { _Pragma("unroll") for (int n = 0; n < 2; ++n) _Pragma("unroll") for (int k = 0; k < 2; ++k) dst[n][k] = *(const PG8_LAS bf16x8*)(lds + PG8_SB(b, h) + boff + n * 2048 + k * 1024); } while (0)
; #define PG8_MMA(ai, bj, At, Bt) do { __builtin_amdgcn_s_setprio(1); _Pragma("unroll") for (int m = 0; m < 4; ++m) _Pragma("unroll") for (int n = 0; n < 2; ++n) _Pragma("unroll") for (int k = 0; k < 2; ++k) \
;         acc[ai][bj][m][n] = mma16<F16>(Bt[n][k], At[m][k], acc[ai][bj][m][n]); __builtin_amdgcn_s_setprio(0); } while (0)
; #define PG8_WAIT_V(n) asm volatile("s_waitcnt vmcnt(" #n ")" ::: "memory")
; #define PG8_WAIT_L(n) asm volatile("s_waitcnt lgkmcnt(" #n ")" ::: "memory")
; template <class Epi, class Sched, bool ALIGN_EPI = false, bool SP2 = false, bool F16 = false>
; __device__ __forceinline__ void gemm_phase(PG8_LAS unsigned char* lds, const Gemm g, const Sched& S, const Epi& E, const int wid_in) {
;     ...
;             const bool last = (t == nt - 2);
;             const char* a1 = cA + (size_t)(t + 1) * kstep;
;             const char* a2 = last ? nA : cA + (size_t)(t + 2) * kstep; const char* b2 = last ? nB : cB + (size_t)(t + 2) * kstep;
;             const char* a3 = a2 + kstep; const char* b3 = b2 + kstep;
;             if (last && has_next) S.a_ready(nxt);
;             if constexpr (SP2) {
;             PG8_LDB(B0, 0, 0); PG8_LDB(B1, 0, 1); PG8_SCHED; PG8_LDA(At, 0, 0); PG8_STAGE(PG8_SA(1, 1), a1 + hstep, voffA);
;             PG8_WAIT_V(8); PG8_WAIT_L(0); PG8_BAR; PG8_MMA(0, 0, At, B0); PG8_MMA(0, 1, At, B1); PG8_BAR; PG8_SCHED;
;             PG8_LDA(At, 0, 1); PG8_STAGE(PG8_SB(0, 0), b2, voffB); PG8_STAGE(PG8_SB(0, 1), b2 + hstep, voffB); PG8_STAGE(PG8_SA(0, 0), a2, voffA);
;             PG8_WAIT_V(8); PG8_WAIT_L(0); PG8_BAR; PG8_MMA(1, 0, At, B0); PG8_MMA(1, 1, At, B1); PG8_BAR; PG8_SCHED;
.LBB0_902:
	ds_read_b128 v[128:131], v183
	ds_read_b128 v[132:135], v183 offset:1024
	ds_read_b128 v[136:139], v183 offset:2048
	ds_read_b128 v[140:143], v183 offset:3072
	ds_read_b128 v[144:147], v184
	ds_read_b128 v[148:151], v184 offset:1024
	ds_read_b128 v[152:155], v184 offset:2048
	ds_read_b128 v[174:177], v184 offset:3072
	s_add_u32 s48, s46, 0xfffc0080
	s_addc_u32 s49, s47, -1
	s_cmp_eq_u32 s52, 12
	s_cselect_b32 s51, s11, s49
	s_cselect_b32 s50, s13, s48
	s_cselect_b32 s49, s31, s43
	s_cselect_b32 s48, s35, s42
	v_lshl_add_u64 v[178:179], s[46:47], 0, v[166:167]
	s_add_i32 m0, s74, 0xc000
	ds_read_b128 v[188:191], v185
	ds_read_b128 v[192:195], v185 offset:1024
	ds_read_b128 v[196:199], v185 offset:2048
	ds_read_b128 v[200:203], v185 offset:3072
	ds_read_b128 v[204:207], v185 offset:4096
	ds_read_b128 v[208:211], v185 offset:5120
	ds_read_b128 v[212:215], v185 offset:6144
	ds_read_b128 v[216:219], v185 offset:7168
	global_load_lds_dwordx4 v[178:179], off
	v_lshl_add_u64 v[178:179], s[46:47], 0, v[168:169]
	s_add_i32 m0, s74, 0xe000
	s_nop 0
	global_load_lds_dwordx4 v[178:179], off
	s_waitcnt vmcnt(8)
	s_cmp_lt_u32 s3, 4
	s_cbranch_scc1 .Lgls_28
	s_waitcnt lgkmcnt(0)
.Lgls_28:
	s_barrier
	s_setprio 1
	s_waitcnt lgkmcnt(0)
	v_mfma_f32_16x16x32_f16 v[124:127], v[128:131], v[188:191], v[124:127]
	v_mfma_f32_16x16x32_f16 v[120:123], v[136:139], v[188:191], v[120:123]
	v_mfma_f32_16x16x32_f16 v[108:111], v[128:131], v[196:199], v[108:111]
	v_mfma_f32_16x16x32_f16 v[104:107], v[136:139], v[196:199], v[104:107]
	v_mfma_f32_16x16x32_f16 v[92:95], v[128:131], v[204:207], v[92:95]
	v_mfma_f32_16x16x32_f16 v[88:91], v[136:139], v[204:207], v[88:91]
	v_mfma_f32_16x16x32_f16 v[76:79], v[128:131], v[212:215], v[76:79]
	v_mfma_f32_16x16x32_f16 v[72:75], v[136:139], v[212:215], v[72:75]
	v_mfma_f32_16x16x32_f16 v[124:127], v[132:135], v[192:195], v[124:127]
	v_mfma_f32_16x16x32_f16 v[120:123], v[140:143], v[192:195], v[120:123]
	v_mfma_f32_16x16x32_f16 v[108:111], v[132:135], v[200:203], v[108:111]
	v_mfma_f32_16x16x32_f16 v[104:107], v[140:143], v[200:203], v[104:107]
	v_mfma_f32_16x16x32_f16 v[92:95], v[132:135], v[208:211], v[92:95]
	v_mfma_f32_16x16x32_f16 v[88:91], v[140:143], v[208:211], v[88:91]
	v_mfma_f32_16x16x32_f16 v[76:79], v[132:135], v[216:219], v[76:79]
	v_mfma_f32_16x16x32_f16 v[72:75], v[140:143], v[216:219], v[72:75]
	s_setprio 0
	s_setprio 1
	v_mfma_f32_16x16x32_f16 v[116:119], v[144:147], v[188:191], v[116:119]
	v_mfma_f32_16x16x32_f16 v[112:115], v[152:155], v[188:191], v[112:115]
	v_mfma_f32_16x16x32_f16 v[100:103], v[144:147], v[196:199], v[100:103]
	v_mfma_f32_16x16x32_f16 v[96:99], v[152:155], v[196:199], v[96:99]
	v_mfma_f32_16x16x32_f16 v[84:87], v[144:147], v[204:207], v[84:87]
	v_mfma_f32_16x16x32_f16 v[80:83], v[152:155], v[204:207], v[80:83]
	v_mfma_f32_16x16x32_f16 v[68:71], v[144:147], v[212:215], v[68:71]
	v_mfma_f32_16x16x32_f16 v[64:67], v[152:155], v[212:215], v[64:67]
	v_mfma_f32_16x16x32_f16 v[116:119], v[148:151], v[192:195], v[116:119]
	v_mfma_f32_16x16x32_f16 v[112:115], v[174:177], v[192:195], v[112:115]
	v_mfma_f32_16x16x32_f16 v[100:103], v[148:151], v[200:203], v[100:103]
	v_mfma_f32_16x16x32_f16 v[96:99], v[174:177], v[200:203], v[96:99]
	v_mfma_f32_16x16x32_f16 v[84:87], v[148:151], v[208:211], v[84:87]
	v_mfma_f32_16x16x32_f16 v[80:83], v[174:177], v[208:211], v[80:83]
	v_mfma_f32_16x16x32_f16 v[68:71], v[148:151], v[216:219], v[68:71]
	v_mfma_f32_16x16x32_f16 v[64:67], v[174:177], v[216:219], v[64:67]
	s_setprio 0
	s_barrier
	s_add_i32 s53, s40, s68
	v_lshl_add_u64 v[178:179], s[48:49], 0, v[158:159]
	s_mov_b32 m0, s53
	ds_read_b128 v[188:191], v185 offset:16384
	ds_read_b128 v[192:195], v185 offset:17408
	ds_read_b128 v[196:199], v185 offset:18432
	ds_read_b128 v[200:203], v185 offset:19456
	ds_read_b128 v[204:207], v185 offset:20480
	ds_read_b128 v[208:211], v185 offset:21504
	ds_read_b128 v[212:215], v185 offset:22528
	ds_read_b128 v[216:219], v185 offset:23552
	global_load_lds_dwordx4 v[178:179], off
	s_add_i32 m0, s53, 0x2000
	s_add_u32 s54, s48, 0x40000
	v_lshl_add_u64 v[220:221], s[48:49], 0, v[162:163]
	s_addc_u32 s55, s49, 0
	s_add_i32 s53, s41, s68
	global_load_lds_dwordx4 v[220:221], off
	v_lshl_add_u64 v[222:223], s[54:55], 0, v[158:159]
	s_mov_b32 m0, s53
	v_lshl_add_u64 v[224:225], s[50:51], 0, v[160:161]
	global_load_lds_dwordx4 v[222:223], off
	v_lshl_add_u64 v[222:223], s[54:55], 0, v[162:163]
	s_add_i32 m0, s53, 0x2000
	s_nop 0
	global_load_lds_dwordx4 v[222:223], off
	v_lshl_add_u64 v[222:223], s[50:51], 0, v[156:157]
	s_mov_b32 m0, s74
	s_nop 0
	global_load_lds_dwordx4 v[222:223], off
	s_mov_b32 m0, s65
	s_nop 0
	global_load_lds_dwordx4 v[224:225], off
	s_waitcnt vmcnt(8)
	s_cmp_lt_u32 s3, 4
	s_cbranch_scc1 .Lgls_29
	s_waitcnt lgkmcnt(0)
; #define PG8_STAGE(bufoff, gbase, voff) do { _Pragma("unroll") for (int _i = 0; _i < 2; ++_i) \
;         __builtin_amdgcn_global_load_lds((const unsigned*)((const char*)(gbase) + (voff)[_i]), (PG8_LAS unsigned*)(lds + (bufoff) + ldsw + _i * 8192), 16, 0, 0); } while (0)
; #define PG8_LDA(dst, b, h) do { _Pragma("unroll") for (int m = 0; m < 4; ++m) _Pragma("unroll") for (int k = 0; k < 2; ++k) dst[m][k] = *(const PG8_LAS bf16x8*)(lds + PG8_SA(b, h) + aoff + m * 2048 + k * 1024); } while (0)
; #define PG8_LDB(dst, b, h) do { _Pragma("unroll") for (int n = 0; n < 2; ++n) _Pragma("unroll") for (int k = 0; k < 2; ++k) dst[n][k] = *(const PG8_LAS bf16x8*)(lds + PG8_SB(b, h) + boff + n * 2048 + k * 1024); } while (0)
; #define PG8_MMA(ai, bj, At, Bt) do { __builtin_amdgcn_s_setprio(1); _Pragma("unroll") for (int m = 0; m < 4; ++m) _Pragma("unroll") for (int n = 0; n < 2; ++n) _Pragma("unroll") for (int k = 0; k < 2; ++k) \
;         acc[ai][bj][m][n] = mma16<F16>(Bt[n][k], At[m][k], acc[ai][bj][m][n]); __builtin_amdgcn_s_setprio(0); } while (0)
; #define PG8_WAIT_V(n) asm volatile("s_waitcnt vmcnt(" #n ")" ::: "memory")
; #define PG8_WAIT_L(n) asm volatile("s_waitcnt lgkmcnt(" #n ")" ::: "memory")
; #define PG8_BAR __builtin_amdgcn_s_barrier()
; #define PG8_SCHED __builtin_amdgcn_sched_barrier(0)
; template <class Epi, class Sched, bool ALIGN_EPI = false, bool SP2 = false, bool F16 = false>
; __device__ __forceinline__ void gemm_phase(PG8_LAS unsigned char* lds, const Gemm g, const Sched& S, const Epi& E, const int wid_in) {
;     ...
;             PG8_WAIT_V(8); PG8_WAIT_L(0); PG8_BAR; PG8_MMA(1, 0, At, B0); PG8_MMA(1, 1, At, B1); PG8_BAR; PG8_SCHED;
;             PG8_LDB(B0, 1, 0); PG8_LDB(B1, 1, 1); PG8_SCHED; PG8_LDA(At, 1, 0); PG8_STAGE(PG8_SA(0, 1), a2 + hstep, voffA);
;             PG8_WAIT_V(8); PG8_WAIT_L(0); PG8_BAR; PG8_MMA(0, 0, At, B0); PG8_MMA(0, 1, At, B1); PG8_BAR; PG8_SCHED;
.Lgls_29:
	s_barrier
	s_setprio 1
	s_waitcnt lgkmcnt(0)
	v_mfma_f32_16x16x32_f16 v[60:63], v[128:131], v[188:191], v[60:63]
	v_mfma_f32_16x16x32_f16 v[56:59], v[136:139], v[188:191], v[56:59]
	v_mfma_f32_16x16x32_f16 v[44:47], v[128:131], v[196:199], v[44:47]
	v_mfma_f32_16x16x32_f16 v[40:43], v[136:139], v[196:199], v[40:43]
	v_mfma_f32_16x16x32_f16 v[28:31], v[128:131], v[204:207], v[28:31]
	v_mfma_f32_16x16x32_f16 v[24:27], v[136:139], v[204:207], v[24:27]
	v_mfma_f32_16x16x32_f16 v[12:15], v[128:131], v[212:215], v[12:15]
	v_mfma_f32_16x16x32_f16 v[8:11], v[136:139], v[212:215], v[8:11]
	v_mfma_f32_16x16x32_f16 v[60:63], v[132:135], v[192:195], v[60:63]
	v_mfma_f32_16x16x32_f16 v[56:59], v[140:143], v[192:195], v[56:59]
	v_mfma_f32_16x16x32_f16 v[44:47], v[132:135], v[200:203], v[44:47]
	v_mfma_f32_16x16x32_f16 v[40:43], v[140:143], v[200:203], v[40:43]
	v_mfma_f32_16x16x32_f16 v[28:31], v[132:135], v[208:211], v[28:31]
	v_mfma_f32_16x16x32_f16 v[24:27], v[140:143], v[208:211], v[24:27]
	v_mfma_f32_16x16x32_f16 v[12:15], v[132:135], v[216:219], v[12:15]
	v_mfma_f32_16x16x32_f16 v[8:11], v[140:143], v[216:219], v[8:11]
	s_setprio 0
	s_setprio 1
	v_mfma_f32_16x16x32_f16 v[52:55], v[144:147], v[188:191], v[52:55]
	v_mfma_f32_16x16x32_f16 v[48:51], v[152:155], v[188:191], v[48:51]
	v_mfma_f32_16x16x32_f16 v[36:39], v[144:147], v[196:199], v[36:39]
	v_mfma_f32_16x16x32_f16 v[32:35], v[152:155], v[196:199], v[32:35]
	v_mfma_f32_16x16x32_f16 v[20:23], v[144:147], v[204:207], v[20:23]
	v_mfma_f32_16x16x32_f16 v[16:19], v[152:155], v[204:207], v[16:19]
	v_mfma_f32_16x16x32_f16 v[4:7], v[144:147], v[212:215], v[4:7]
	v_mfma_f32_16x16x32_f16 v[0:3], v[152:155], v[212:215], v[0:3]
	v_mfma_f32_16x16x32_f16 v[52:55], v[148:151], v[192:195], v[52:55]
	v_mfma_f32_16x16x32_f16 v[48:51], v[174:177], v[192:195], v[48:51]
	v_mfma_f32_16x16x32_f16 v[36:39], v[148:151], v[200:203], v[36:39]
	v_mfma_f32_16x16x32_f16 v[32:35], v[174:177], v[200:203], v[32:35]
	v_mfma_f32_16x16x32_f16 v[20:23], v[148:151], v[208:211], v[20:23]
	v_mfma_f32_16x16x32_f16 v[16:19], v[174:177], v[208:211], v[16:19]
	v_mfma_f32_16x16x32_f16 v[4:7], v[148:151], v[216:219], v[4:7]
	v_mfma_f32_16x16x32_f16 v[0:3], v[174:177], v[216:219], v[0:3]
	s_setprio 0
	s_barrier
	s_add_i32 s53, 0, 0x18000
	s_add_i32 s54, 0, 0x1c000
	v_add_u32_e32 v140, s53, v182
	v_add_u32_e32 v165, s54, v182
	ds_read_b128 v[128:131], v140
	ds_read_b128 v[132:135], v140 offset:1024
	ds_read_b128 v[136:139], v140 offset:2048
	ds_read_b128 v[140:143], v140 offset:3072
	ds_read_b128 v[144:147], v165
	ds_read_b128 v[148:151], v165 offset:1024
	ds_read_b128 v[152:155], v165 offset:2048
	ds_read_b128 v[174:177], v165 offset:3072
	s_add_u32 s50, s50, 0x40000
	s_addc_u32 s51, s51, 0
	s_mov_b32 m0, s66
	v_lshl_add_u64 v[226:227], s[50:51], 0, v[156:157]
	ds_read_b128 v[188:191], v185 offset:32768
	ds_read_b128 v[192:195], v185 offset:33792
	ds_read_b128 v[196:199], v185 offset:34816
	ds_read_b128 v[200:203], v185 offset:35840
	ds_read_b128 v[204:207], v185 offset:36864
	ds_read_b128 v[208:211], v185 offset:37888
	ds_read_b128 v[212:215], v185 offset:38912
	ds_read_b128 v[216:219], v185 offset:39936
	global_load_lds_dwordx4 v[226:227], off
	v_lshl_add_u64 v[226:227], s[50:51], 0, v[160:161]
	s_mov_b32 m0, s67
	s_nop 0
	global_load_lds_dwordx4 v[226:227], off
	s_waitcnt vmcnt(8)
	s_cmp_lt_u32 s3, 4
	s_cbranch_scc1 .Lgls_30
	s_waitcnt lgkmcnt(0)
; #define PG8_STAGE(bufoff, gbase, voff) do { _Pragma("unroll") for (int _i = 0; _i < 2; ++_i) \
;         __builtin_amdgcn_global_load_lds((const unsigned*)((const char*)(gbase) + (voff)[_i]), (PG8_LAS unsigned*)(lds + (bufoff) + ldsw + _i * 8192), 16, 0, 0); } while (0)
; #define PG8_LDA(dst, b, h) do { _Pragma("unroll") for (int m = 0; m < 4; ++m) _Pragma("unroll") for (int k = 0; k < 2; ++k) dst[m][k] = *(const PG8_LAS bf16x8*)(lds + PG8_SA(b, h) + aoff + m * 2048 + k * 1024); } while (0)
; #define PG8_MMA(ai, bj, At, Bt) do { __builtin_amdgcn_s_setprio(1); _Pragma("unroll") for (int m = 0; m < 4; ++m) _Pragma("unroll") for (int n = 0; n < 2; ++n) _Pragma("unroll") for (int k = 0; k < 2; ++k) \
;         acc[ai][bj][m][n] = mma16<F16>(Bt[n][k], At[m][k], acc[ai][bj][m][n]); __builtin_amdgcn_s_setprio(0); } while (0)
; #define PG8_WAIT_V(n) asm volatile("s_waitcnt vmcnt(" #n ")" ::: "memory")
; #define PG8_WAIT_L(n) asm volatile("s_waitcnt lgkmcnt(" #n ")" ::: "memory")
; #define PG8_BAR __builtin_amdgcn_s_barrier()
; #define PG8_SCHED __builtin_amdgcn_sched_barrier(0)
; template <class Epi, class Sched, bool ALIGN_EPI = false, bool SP2 = false, bool F16 = false>
; __device__ __forceinline__ void gemm_phase(PG8_LAS unsigned char* lds, const Gemm g, const Sched& S, const Epi& E, const int wid_in) {
;     ...
;             PG8_WAIT_V(8); PG8_WAIT_L(0); PG8_BAR; PG8_MMA(0, 0, At, B0); PG8_MMA(0, 1, At, B1); PG8_BAR; PG8_SCHED;
;             PG8_LDA(At, 1, 1); PG8_STAGE(PG8_SB(1, 0), b3, voffB); PG8_STAGE(PG8_SB(1, 1), b3 + hstep, voffB); PG8_STAGE(PG8_SA(1, 0), a3, voffA);
;             PG8_WAIT_V(8); PG8_WAIT_L(0); PG8_BAR; PG8_MMA(1, 0, At, B0); PG8_MMA(1, 1, At, B1); PG8_BAR; PG8_SCHED;
;     ...
;         if constexpr (ALIGN_EPI) { if (wr == 0) PG8_BAR; }
.Lgls_30:
	s_barrier
	s_setprio 1
	s_waitcnt lgkmcnt(0)
	v_mfma_f32_16x16x32_f16 v[124:127], v[128:131], v[188:191], v[124:127]
	v_mfma_f32_16x16x32_f16 v[120:123], v[136:139], v[188:191], v[120:123]
	v_mfma_f32_16x16x32_f16 v[108:111], v[128:131], v[196:199], v[108:111]
	v_mfma_f32_16x16x32_f16 v[104:107], v[136:139], v[196:199], v[104:107]
	v_mfma_f32_16x16x32_f16 v[92:95], v[128:131], v[204:207], v[92:95]
	v_mfma_f32_16x16x32_f16 v[88:91], v[136:139], v[204:207], v[88:91]
	v_mfma_f32_16x16x32_f16 v[76:79], v[128:131], v[212:215], v[76:79]
	v_mfma_f32_16x16x32_f16 v[72:75], v[136:139], v[212:215], v[72:75]
	v_mfma_f32_16x16x32_f16 v[124:127], v[132:135], v[192:195], v[124:127]
	v_mfma_f32_16x16x32_f16 v[120:123], v[140:143], v[192:195], v[120:123]
	v_mfma_f32_16x16x32_f16 v[108:111], v[132:135], v[200:203], v[108:111]
	v_mfma_f32_16x16x32_f16 v[104:107], v[140:143], v[200:203], v[104:107]
	v_mfma_f32_16x16x32_f16 v[92:95], v[132:135], v[208:211], v[92:95]
	v_mfma_f32_16x16x32_f16 v[88:91], v[140:143], v[208:211], v[88:91]
	v_mfma_f32_16x16x32_f16 v[76:79], v[132:135], v[216:219], v[76:79]
	v_mfma_f32_16x16x32_f16 v[72:75], v[140:143], v[216:219], v[72:75]
	s_setprio 0
	s_setprio 1
	v_mfma_f32_16x16x32_f16 v[116:119], v[144:147], v[188:191], v[116:119]
	v_mfma_f32_16x16x32_f16 v[112:115], v[152:155], v[188:191], v[112:115]
	v_mfma_f32_16x16x32_f16 v[100:103], v[144:147], v[196:199], v[100:103]
	v_mfma_f32_16x16x32_f16 v[96:99], v[152:155], v[196:199], v[96:99]
	v_mfma_f32_16x16x32_f16 v[84:87], v[144:147], v[204:207], v[84:87]
	v_mfma_f32_16x16x32_f16 v[80:83], v[152:155], v[204:207], v[80:83]
	v_mfma_f32_16x16x32_f16 v[68:71], v[144:147], v[212:215], v[68:71]
	v_mfma_f32_16x16x32_f16 v[64:67], v[152:155], v[212:215], v[64:67]
	v_mfma_f32_16x16x32_f16 v[116:119], v[148:151], v[192:195], v[116:119]
	v_mfma_f32_16x16x32_f16 v[112:115], v[174:177], v[192:195], v[112:115]
	v_mfma_f32_16x16x32_f16 v[100:103], v[148:151], v[200:203], v[100:103]
	v_mfma_f32_16x16x32_f16 v[96:99], v[174:177], v[200:203], v[96:99]
	v_mfma_f32_16x16x32_f16 v[84:87], v[148:151], v[208:211], v[84:87]
	v_mfma_f32_16x16x32_f16 v[80:83], v[174:177], v[208:211], v[80:83]
	v_mfma_f32_16x16x32_f16 v[68:71], v[148:151], v[216:219], v[68:71]
	v_mfma_f32_16x16x32_f16 v[64:67], v[174:177], v[216:219], v[64:67]
	s_setprio 0
	s_barrier
	s_add_i32 s50, s53, s68
	v_lshl_add_u64 v[178:179], v[178:179], 0, s[20:21]
	s_mov_b32 m0, s50
	ds_read_b128 v[188:191], v185 offset:49152
	ds_read_b128 v[192:195], v185 offset:50176
	ds_read_b128 v[196:199], v185 offset:51200
	ds_read_b128 v[200:203], v185 offset:52224
	ds_read_b128 v[204:207], v185 offset:53248
	ds_read_b128 v[208:211], v185 offset:54272
	ds_read_b128 v[212:215], v185 offset:55296
	ds_read_b128 v[216:219], v185 offset:56320
	global_load_lds_dwordx4 v[178:179], off
	s_add_i32 m0, s50, 0x2000
	s_add_u32 s48, s48, 0x40080
	v_lshl_add_u64 v[178:179], v[220:221], 0, s[20:21]
	s_addc_u32 s49, s49, 0
	s_add_i32 s50, s54, s68
	global_load_lds_dwordx4 v[178:179], off
	v_lshl_add_u64 v[178:179], s[48:49], 0, v[158:159]
	s_mov_b32 m0, s50
	s_nop 0
	global_load_lds_dwordx4 v[178:179], off
	v_lshl_add_u64 v[178:179], s[48:49], 0, v[162:163]
	s_add_i32 m0, s50, 0x2000
	s_nop 0
	global_load_lds_dwordx4 v[178:179], off
	v_lshl_add_u64 v[178:179], v[222:223], 0, s[20:21]
	s_mov_b32 m0, s75
	s_nop 0
	global_load_lds_dwordx4 v[178:179], off
	v_lshl_add_u64 v[178:179], v[224:225], 0, s[20:21]
	s_mov_b32 m0, s89
	s_nop 0
	global_load_lds_dwordx4 v[178:179], off
	s_waitcnt vmcnt(8)
	s_cmp_lt_u32 s3, 4
	s_cbranch_scc1 .Lgls_31
	s_waitcnt lgkmcnt(0)
.Lgls_31:
	s_barrier
	s_setprio 1
	s_waitcnt lgkmcnt(0)
	v_mfma_f32_16x16x32_f16 v[60:63], v[128:131], v[188:191], v[60:63]
	v_mfma_f32_16x16x32_f16 v[56:59], v[136:139], v[188:191], v[56:59]
	v_mfma_f32_16x16x32_f16 v[44:47], v[128:131], v[196:199], v[44:47]
	v_mfma_f32_16x16x32_f16 v[40:43], v[136:139], v[196:199], v[40:43]
	v_mfma_f32_16x16x32_f16 v[28:31], v[128:131], v[204:207], v[28:31]
	v_mfma_f32_16x16x32_f16 v[24:27], v[136:139], v[204:207], v[24:27]
	v_mfma_f32_16x16x32_f16 v[12:15], v[128:131], v[212:215], v[12:15]
	v_mfma_f32_16x16x32_f16 v[8:11], v[136:139], v[212:215], v[8:11]
	v_mfma_f32_16x16x32_f16 v[60:63], v[132:135], v[192:195], v[60:63]
	v_mfma_f32_16x16x32_f16 v[56:59], v[140:143], v[192:195], v[56:59]
	v_mfma_f32_16x16x32_f16 v[44:47], v[132:135], v[200:203], v[44:47]
	v_mfma_f32_16x16x32_f16 v[40:43], v[140:143], v[200:203], v[40:43]
	v_mfma_f32_16x16x32_f16 v[28:31], v[132:135], v[208:211], v[28:31]
	v_mfma_f32_16x16x32_f16 v[24:27], v[140:143], v[208:211], v[24:27]
	v_mfma_f32_16x16x32_f16 v[12:15], v[132:135], v[216:219], v[12:15]
	v_mfma_f32_16x16x32_f16 v[8:11], v[140:143], v[216:219], v[8:11]
	s_setprio 0
	s_setprio 1
	v_mfma_f32_16x16x32_f16 v[52:55], v[144:147], v[188:191], v[52:55]
	v_mfma_f32_16x16x32_f16 v[48:51], v[152:155], v[188:191], v[48:51]
	v_mfma_f32_16x16x32_f16 v[36:39], v[144:147], v[196:199], v[36:39]
	v_mfma_f32_16x16x32_f16 v[32:35], v[152:155], v[196:199], v[32:35]
	v_mfma_f32_16x16x32_f16 v[20:23], v[144:147], v[204:207], v[20:23]
	v_mfma_f32_16x16x32_f16 v[16:19], v[152:155], v[204:207], v[16:19]
	v_mfma_f32_16x16x32_f16 v[4:7], v[144:147], v[212:215], v[4:7]
	v_mfma_f32_16x16x32_f16 v[0:3], v[152:155], v[212:215], v[0:3]
	v_mfma_f32_16x16x32_f16 v[52:55], v[148:151], v[192:195], v[52:55]
	v_mfma_f32_16x16x32_f16 v[48:51], v[174:177], v[192:195], v[48:51]
	v_mfma_f32_16x16x32_f16 v[36:39], v[148:151], v[200:203], v[36:39]
	v_mfma_f32_16x16x32_f16 v[32:35], v[174:177], v[200:203], v[32:35]
	v_mfma_f32_16x16x32_f16 v[20:23], v[148:151], v[208:211], v[20:23]
	v_mfma_f32_16x16x32_f16 v[16:19], v[174:177], v[208:211], v[16:19]
	v_mfma_f32_16x16x32_f16 v[4:7], v[148:151], v[216:219], v[4:7]
	v_mfma_f32_16x16x32_f16 v[0:3], v[174:177], v[216:219], v[0:3]
	s_setprio 0
	s_barrier
	s_add_i32 s52, s52, 2
	s_add_u32 s46, s46, 0x100
	s_addc_u32 s47, s47, 0
	s_add_u32 s42, s42, 0x100
	s_addc_u32 s43, s43, 0
	s_cmp_gt_u32 s52, 13
	s_cbranch_scc0 .LBB0_902
	s_and_b64 vcc, exec, s[16:17]
	s_cbranch_vccz .LBB0_905
	s_barrier

; #define PG8_STAGE(bufoff, gbase, voff) do { _Pragma("unroll") for (int _i = 0; _i < 2; ++_i) \
;         __builtin_amdgcn_global_load_lds((const unsigned*)((const char*)(gbase) + (voff)[_i]), (PG8_LAS unsigned*)(lds + (bufoff) + ldsw + _i * 8192), 16, 0, 0); } while (0)
; #define PG8_LDA(dst, b, h) do { _Pragma("unroll") for (int m = 0; m < 4; ++m) _Pragma("unroll") for (int k = 0; k < 2; ++k) dst[m][k] = *(const PG8_LAS bf16x8*)(lds + PG8_SA(b, h) + aoff + m * 2048 + k * 1024); } while (0)
; #define PG8_LDB(dst, b, h) do { _Pragma("unroll") for (int n = 0; n < 2; ++n) _Pragma("unroll") for (int k = 0; k < 2; ++k) dst[n][k] = *(const PG8_LAS bf16x8*)(lds + PG8_SB(b, h) + boff + n * 2048 + k * 1024); } while (0)
; #define PG8_MMA(ai, bj, At, Bt) do { __builtin_amdgcn_s_setprio(1); _Pragma("unroll") for (int m = 0; m < 4; ++m) _Pragma("unroll") for (int n = 0; n < 2; ++n) _Pragma("unroll") for (int k = 0; k < 2; ++k) \
;         acc[ai][bj][m][n] = mma16<F16>(Bt[n][k], At[m][k], acc[ai][bj][m][n]); __builtin_amdgcn_s_setprio(0); } while (0)
; #define PG8_WAIT_V(n) asm volatile("s_waitcnt vmcnt(" #n ")" ::: "memory")
; #define PG8_WAIT_L(n) asm volatile("s_waitcnt lgkmcnt(" #n ")" ::: "memory")
; template <class Epi, class Sched, bool ALIGN_EPI = false, bool SP2 = false, bool F16 = false>
; __device__ __forceinline__ void gemm_phase(PG8_LAS unsigned char* lds, const Gemm g, const Sched& S, const Epi& E, const int wid_in) {
;     ...
;             const bool last = (t == nt - 2);
;             const char* a1 = cA + (size_t)(t + 1) * kstep;
;             const char* a2 = last ? nA : cA + (size_t)(t + 2) * kstep; const char* b2 = last ? nB : cB + (size_t)(t + 2) * kstep;
;             const char* a3 = a2 + kstep; const char* b3 = b2 + kstep;
;             if (last && has_next) S.a_ready(nxt);
;             if constexpr (SP2) {
;             PG8_LDB(B0, 0, 0); PG8_LDB(B1, 0, 1); PG8_SCHED; PG8_LDA(At, 0, 0); PG8_STAGE(PG8_SA(1, 1), a1 + hstep, voffA);
;             PG8_WAIT_V(8); PG8_WAIT_L(0); PG8_BAR; PG8_MMA(0, 0, At, B0); PG8_MMA(0, 1, At, B1); PG8_BAR; PG8_SCHED;
;             PG8_LDA(At, 0, 1); PG8_STAGE(PG8_SB(0, 0), b2, voffB); PG8_STAGE(PG8_SB(0, 1), b2 + hstep, voffB); PG8_STAGE(PG8_SA(0, 0), a2, voffA);
;             PG8_WAIT_V(8); PG8_WAIT_L(0); PG8_BAR; PG8_MMA(1, 0, At, B0); PG8_MMA(1, 1, At, B1); PG8_BAR; PG8_SCHED;
.LBB0_1165:
	ds_read_b128 v[128:131], v189
	ds_read_b128 v[132:135], v189 offset:1024
	ds_read_b128 v[136:139], v189 offset:2048
	ds_read_b128 v[140:143], v189 offset:3072
	ds_read_b128 v[144:147], v190
	ds_read_b128 v[148:151], v190 offset:1024
	ds_read_b128 v[168:171], v190 offset:2048
	ds_read_b128 v[172:175], v190 offset:3072
	s_add_u32 s50, s48, 0xfffc0080
	s_addc_u32 s51, s49, -1
	s_cmp_eq_u32 s64, 12
	s_cselect_b32 s53, s35, s51
	s_cselect_b32 s52, s42, s50
	s_cselect_b32 s51, s31, s63
	s_cselect_b32 s50, s43, s47
	v_lshl_add_u64 v[184:185], s[48:49], 0, v[160:161]
	s_add_i32 m0, s74, 0xc000
	ds_read_b128 v[176:179], v191
	ds_read_b128 v[180:183], v191 offset:1024
	ds_read_b128 v[192:195], v191 offset:2048
	ds_read_b128 v[196:199], v191 offset:3072
	ds_read_b128 v[200:203], v191 offset:4096
	ds_read_b128 v[204:207], v191 offset:5120
	ds_read_b128 v[208:211], v191 offset:6144
	ds_read_b128 v[212:215], v191 offset:7168
	global_load_lds_dwordx4 v[184:185], off
	v_lshl_add_u64 v[184:185], s[48:49], 0, v[162:163]
	s_add_i32 m0, s74, 0xe000
	s_nop 0
	global_load_lds_dwordx4 v[184:185], off
	s_waitcnt vmcnt(8)
	s_cmp_lt_u32 s3, 4
	s_cbranch_scc1 .Lgls_32
	s_waitcnt lgkmcnt(0)
.Lgls_32:
	s_barrier
	s_setprio 1
	s_waitcnt lgkmcnt(0)
	v_mfma_f32_16x16x32_bf16 v[124:127], v[128:131], v[176:179], v[124:127]
	v_mfma_f32_16x16x32_bf16 v[120:123], v[136:139], v[176:179], v[120:123]
	v_mfma_f32_16x16x32_bf16 v[108:111], v[128:131], v[192:195], v[108:111]
	v_mfma_f32_16x16x32_bf16 v[104:107], v[136:139], v[192:195], v[104:107]
	v_mfma_f32_16x16x32_bf16 v[92:95], v[128:131], v[200:203], v[92:95]
	v_mfma_f32_16x16x32_bf16 v[88:91], v[136:139], v[200:203], v[88:91]
	v_mfma_f32_16x16x32_bf16 v[76:79], v[128:131], v[208:211], v[76:79]
	v_mfma_f32_16x16x32_bf16 v[72:75], v[136:139], v[208:211], v[72:75]
	v_mfma_f32_16x16x32_bf16 v[124:127], v[132:135], v[180:183], v[124:127]
	v_mfma_f32_16x16x32_bf16 v[120:123], v[140:143], v[180:183], v[120:123]
	v_mfma_f32_16x16x32_bf16 v[108:111], v[132:135], v[196:199], v[108:111]
	v_mfma_f32_16x16x32_bf16 v[104:107], v[140:143], v[196:199], v[104:107]
	v_mfma_f32_16x16x32_bf16 v[92:95], v[132:135], v[204:207], v[92:95]
	v_mfma_f32_16x16x32_bf16 v[88:91], v[140:143], v[204:207], v[88:91]
	v_mfma_f32_16x16x32_bf16 v[76:79], v[132:135], v[212:215], v[76:79]
	v_mfma_f32_16x16x32_bf16 v[72:75], v[140:143], v[212:215], v[72:75]
	s_setprio 0
	s_setprio 1
	v_mfma_f32_16x16x32_bf16 v[116:119], v[144:147], v[176:179], v[116:119]
	v_mfma_f32_16x16x32_bf16 v[112:115], v[168:171], v[176:179], v[112:115]
	v_mfma_f32_16x16x32_bf16 v[100:103], v[144:147], v[192:195], v[100:103]
	v_mfma_f32_16x16x32_bf16 v[96:99], v[168:171], v[192:195], v[96:99]
	v_mfma_f32_16x16x32_bf16 v[84:87], v[144:147], v[200:203], v[84:87]
	v_mfma_f32_16x16x32_bf16 v[80:83], v[168:171], v[200:203], v[80:83]
	v_mfma_f32_16x16x32_bf16 v[68:71], v[144:147], v[208:211], v[68:71]
	v_mfma_f32_16x16x32_bf16 v[64:67], v[168:171], v[208:211], v[64:67]
	v_mfma_f32_16x16x32_bf16 v[116:119], v[148:151], v[180:183], v[116:119]
	v_mfma_f32_16x16x32_bf16 v[112:115], v[172:175], v[180:183], v[112:115]
	v_mfma_f32_16x16x32_bf16 v[100:103], v[148:151], v[196:199], v[100:103]
	v_mfma_f32_16x16x32_bf16 v[96:99], v[172:175], v[196:199], v[96:99]
	v_mfma_f32_16x16x32_bf16 v[84:87], v[148:151], v[204:207], v[84:87]
	v_mfma_f32_16x16x32_bf16 v[80:83], v[172:175], v[204:207], v[80:83]
	v_mfma_f32_16x16x32_bf16 v[68:71], v[148:151], v[212:215], v[68:71]
	v_mfma_f32_16x16x32_bf16 v[64:67], v[172:175], v[212:215], v[64:67]
	s_setprio 0
	s_barrier
	s_add_i32 s65, s60, s68
	v_lshl_add_u64 v[184:185], s[50:51], 0, v[154:155]
	s_mov_b32 m0, s65
	ds_read_b128 v[176:179], v191 offset:16384
	ds_read_b128 v[180:183], v191 offset:17408
	ds_read_b128 v[192:195], v191 offset:18432
	ds_read_b128 v[196:199], v191 offset:19456
	ds_read_b128 v[200:203], v191 offset:20480
	ds_read_b128 v[204:207], v191 offset:21504
	ds_read_b128 v[208:211], v191 offset:22528
	ds_read_b128 v[212:215], v191 offset:23552
	global_load_lds_dwordx4 v[184:185], off
	s_add_i32 m0, s65, 0x2000
	s_add_u32 s66, s50, 0x40000
	v_lshl_add_u64 v[216:217], s[50:51], 0, v[158:159]
	s_addc_u32 s67, s51, 0
	s_add_i32 s65, s61, s68
	global_load_lds_dwordx4 v[216:217], off
	v_lshl_add_u64 v[218:219], s[66:67], 0, v[154:155]
	s_mov_b32 m0, s65
	v_lshl_add_u64 v[220:221], s[52:53], 0, v[156:157]
	global_load_lds_dwordx4 v[218:219], off
	v_lshl_add_u64 v[218:219], s[66:67], 0, v[158:159]
	s_add_i32 m0, s65, 0x2000
	s_nop 0
	global_load_lds_dwordx4 v[218:219], off
	v_lshl_add_u64 v[218:219], s[52:53], 0, v[152:153]
	s_mov_b32 m0, s74
	s_nop 0
	global_load_lds_dwordx4 v[218:219], off
	s_mov_b32 m0, s41
	s_nop 0
	global_load_lds_dwordx4 v[220:221], off
	s_waitcnt vmcnt(8)
	s_cmp_lt_u32 s3, 4
	s_cbranch_scc1 .Lgls_33
	s_waitcnt lgkmcnt(0)
; #define PG8_STAGE(bufoff, gbase, voff) do { _Pragma("unroll") for (int _i = 0; _i < 2; ++_i) \
;         __builtin_amdgcn_global_load_lds((const unsigned*)((const char*)(gbase) + (voff)[_i]), (PG8_LAS unsigned*)(lds + (bufoff) + ldsw + _i * 8192), 16, 0, 0); } while (0)
; #define PG8_LDA(dst, b, h) do { _Pragma("unroll") for (int m = 0; m < 4; ++m) _Pragma("unroll") for (int k = 0; k < 2; ++k) dst[m][k] = *(const PG8_LAS bf16x8*)(lds + PG8_SA(b, h) + aoff + m * 2048 + k * 1024); } while (0)
; #define PG8_LDB(dst, b, h) do { _Pragma("unroll") for (int n = 0; n < 2; ++n) _Pragma("unroll") for (int k = 0; k < 2; ++k) dst[n][k] = *(const PG8_LAS bf16x8*)(lds + PG8_SB(b, h) + boff + n * 2048 + k * 1024); } while (0)
; #define PG8_MMA(ai, bj, At, Bt) do { __builtin_amdgcn_s_setprio(1); _Pragma("unroll") for (int m = 0; m < 4; ++m) _Pragma("unroll") for (int n = 0; n < 2; ++n) _Pragma("unroll") for (int k = 0; k < 2; ++k) \
;         acc[ai][bj][m][n] = mma16<F16>(Bt[n][k], At[m][k], acc[ai][bj][m][n]); __builtin_amdgcn_s_setprio(0); } while (0)
; #define PG8_WAIT_V(n) asm volatile("s_waitcnt vmcnt(" #n ")" ::: "memory")
; #define PG8_WAIT_L(n) asm volatile("s_waitcnt lgkmcnt(" #n ")" ::: "memory")
; #define PG8_BAR __builtin_amdgcn_s_barrier()
; #define PG8_SCHED __builtin_amdgcn_sched_barrier(0)
; template <class Epi, class Sched, bool ALIGN_EPI = false, bool SP2 = false, bool F16 = false>
; __device__ __forceinline__ void gemm_phase(PG8_LAS unsigned char* lds, const Gemm g, const Sched& S, const Epi& E, const int wid_in) {
;     ...
;             PG8_WAIT_V(8); PG8_WAIT_L(0); PG8_BAR; PG8_MMA(1, 0, At, B0); PG8_MMA(1, 1, At, B1); PG8_BAR; PG8_SCHED;
;             PG8_LDB(B0, 1, 0); PG8_LDB(B1, 1, 1); PG8_SCHED; PG8_LDA(At, 1, 0); PG8_STAGE(PG8_SA(0, 1), a2 + hstep, voffA);
;             PG8_WAIT_V(8); PG8_WAIT_L(0); PG8_BAR; PG8_MMA(0, 0, At, B0); PG8_MMA(0, 1, At, B1); PG8_BAR; PG8_SCHED;
.Lgls_33:
	s_barrier
	s_setprio 1
	s_waitcnt lgkmcnt(0)
	v_mfma_f32_16x16x32_bf16 v[60:63], v[128:131], v[176:179], v[60:63]
	v_mfma_f32_16x16x32_bf16 v[56:59], v[136:139], v[176:179], v[56:59]
	v_mfma_f32_16x16x32_bf16 v[44:47], v[128:131], v[192:195], v[44:47]
	v_mfma_f32_16x16x32_bf16 v[40:43], v[136:139], v[192:195], v[40:43]
	v_mfma_f32_16x16x32_bf16 v[28:31], v[128:131], v[200:203], v[28:31]
	v_mfma_f32_16x16x32_bf16 v[24:27], v[136:139], v[200:203], v[24:27]
	v_mfma_f32_16x16x32_bf16 v[12:15], v[128:131], v[208:211], v[12:15]
	v_mfma_f32_16x16x32_bf16 v[8:11], v[136:139], v[208:211], v[8:11]
	v_mfma_f32_16x16x32_bf16 v[60:63], v[132:135], v[180:183], v[60:63]
	v_mfma_f32_16x16x32_bf16 v[56:59], v[140:143], v[180:183], v[56:59]
	v_mfma_f32_16x16x32_bf16 v[44:47], v[132:135], v[196:199], v[44:47]
	v_mfma_f32_16x16x32_bf16 v[40:43], v[140:143], v[196:199], v[40:43]
	v_mfma_f32_16x16x32_bf16 v[28:31], v[132:135], v[204:207], v[28:31]
	v_mfma_f32_16x16x32_bf16 v[24:27], v[140:143], v[204:207], v[24:27]
	v_mfma_f32_16x16x32_bf16 v[12:15], v[132:135], v[212:215], v[12:15]
	v_mfma_f32_16x16x32_bf16 v[8:11], v[140:143], v[212:215], v[8:11]
	s_setprio 0
	s_setprio 1
	v_mfma_f32_16x16x32_bf16 v[52:55], v[144:147], v[176:179], v[52:55]
	v_mfma_f32_16x16x32_bf16 v[48:51], v[168:171], v[176:179], v[48:51]
	v_mfma_f32_16x16x32_bf16 v[36:39], v[144:147], v[192:195], v[36:39]
	v_mfma_f32_16x16x32_bf16 v[32:35], v[168:171], v[192:195], v[32:35]
	v_mfma_f32_16x16x32_bf16 v[20:23], v[144:147], v[200:203], v[20:23]
	v_mfma_f32_16x16x32_bf16 v[16:19], v[168:171], v[200:203], v[16:19]
	v_mfma_f32_16x16x32_bf16 v[4:7], v[144:147], v[208:211], v[4:7]
	v_mfma_f32_16x16x32_bf16 v[0:3], v[168:171], v[208:211], v[0:3]
	v_mfma_f32_16x16x32_bf16 v[52:55], v[148:151], v[180:183], v[52:55]
	v_mfma_f32_16x16x32_bf16 v[48:51], v[172:175], v[180:183], v[48:51]
	v_mfma_f32_16x16x32_bf16 v[36:39], v[148:151], v[196:199], v[36:39]
	v_mfma_f32_16x16x32_bf16 v[32:35], v[172:175], v[196:199], v[32:35]
	v_mfma_f32_16x16x32_bf16 v[20:23], v[148:151], v[204:207], v[20:23]
	v_mfma_f32_16x16x32_bf16 v[16:19], v[172:175], v[204:207], v[16:19]
	v_mfma_f32_16x16x32_bf16 v[4:7], v[148:151], v[212:215], v[4:7]
	v_mfma_f32_16x16x32_bf16 v[0:3], v[172:175], v[212:215], v[0:3]
	s_setprio 0
	s_barrier
	s_add_i32 s65, 0, 0x18000
	s_add_i32 s66, 0, 0x1c000
	v_add_u32_e32 v140, s65, v188
	v_add_u32_e32 v172, s66, v188
	ds_read_b128 v[128:131], v140
	ds_read_b128 v[132:135], v140 offset:1024
	ds_read_b128 v[136:139], v140 offset:2048
	ds_read_b128 v[140:143], v140 offset:3072
	ds_read_b128 v[144:147], v172
	ds_read_b128 v[148:151], v172 offset:1024
	ds_read_b128 v[168:171], v172 offset:2048
	ds_read_b128 v[172:175], v172 offset:3072
	s_add_u32 s52, s52, 0x40000
	s_addc_u32 s53, s53, 0
	s_mov_b32 m0, s54
	v_lshl_add_u64 v[222:223], s[52:53], 0, v[152:153]
	ds_read_b128 v[176:179], v191 offset:32768
	ds_read_b128 v[180:183], v191 offset:33792
	ds_read_b128 v[192:195], v191 offset:34816
	ds_read_b128 v[196:199], v191 offset:35840
	ds_read_b128 v[200:203], v191 offset:36864
	ds_read_b128 v[204:207], v191 offset:37888
	ds_read_b128 v[208:211], v191 offset:38912
	ds_read_b128 v[212:215], v191 offset:39936
	global_load_lds_dwordx4 v[222:223], off
	v_lshl_add_u64 v[222:223], s[52:53], 0, v[156:157]
	s_mov_b32 m0, s55
	s_nop 0
	global_load_lds_dwordx4 v[222:223], off
	s_waitcnt vmcnt(8)
	s_cmp_lt_u32 s3, 4
	s_cbranch_scc1 .Lgls_34
	s_waitcnt lgkmcnt(0)
; #define PG8_STAGE(bufoff, gbase, voff) do { _Pragma("unroll") for (int _i = 0; _i < 2; ++_i) \
;         __builtin_amdgcn_global_load_lds((const unsigned*)((const char*)(gbase) + (voff)[_i]), (PG8_LAS unsigned*)(lds + (bufoff) + ldsw + _i * 8192), 16, 0, 0); } while (0)
; #define PG8_LDA(dst, b, h) do { _Pragma("unroll") for (int m = 0; m < 4; ++m) _Pragma("unroll") for (int k = 0; k < 2; ++k) dst[m][k] = *(const PG8_LAS bf16x8*)(lds + PG8_SA(b, h) + aoff + m * 2048 + k * 1024); } while (0)
; #define PG8_MMA(ai, bj, At, Bt) do { __builtin_amdgcn_s_setprio(1); _Pragma("unroll") for (int m = 0; m < 4; ++m) _Pragma("unroll") for (int n = 0; n < 2; ++n) _Pragma("unroll") for (int k = 0; k < 2; ++k) \
;         acc[ai][bj][m][n] = mma16<F16>(Bt[n][k], At[m][k], acc[ai][bj][m][n]); __builtin_amdgcn_s_setprio(0); } while (0)
; #define PG8_WAIT_V(n) asm volatile("s_waitcnt vmcnt(" #n ")" ::: "memory")
; #define PG8_WAIT_L(n) asm volatile("s_waitcnt lgkmcnt(" #n ")" ::: "memory")
; #define PG8_BAR __builtin_amdgcn_s_barrier()
; #define PG8_SCHED __builtin_amdgcn_sched_barrier(0)
; template <class Epi, class Sched, bool ALIGN_EPI = false, bool SP2 = false, bool F16 = false>
; __device__ __forceinline__ void gemm_phase(PG8_LAS unsigned char* lds, const Gemm g, const Sched& S, const Epi& E, const int wid_in) {
;     ...
;             PG8_WAIT_V(8); PG8_WAIT_L(0); PG8_BAR; PG8_MMA(0, 0, At, B0); PG8_MMA(0, 1, At, B1); PG8_BAR; PG8_SCHED;
;             PG8_LDA(At, 1, 1); PG8_STAGE(PG8_SB(1, 0), b3, voffB); PG8_STAGE(PG8_SB(1, 1), b3 + hstep, voffB); PG8_STAGE(PG8_SA(1, 0), a3, voffA);
;             PG8_WAIT_V(8); PG8_WAIT_L(0); PG8_BAR; PG8_MMA(1, 0, At, B0); PG8_MMA(1, 1, At, B1); PG8_BAR; PG8_SCHED;
;     ...
;         if constexpr (ALIGN_EPI) { if (wr == 0) PG8_BAR; }
.Lgls_34:
	s_barrier
	s_setprio 1
	s_waitcnt lgkmcnt(0)
	v_mfma_f32_16x16x32_bf16 v[124:127], v[128:131], v[176:179], v[124:127]
	v_mfma_f32_16x16x32_bf16 v[120:123], v[136:139], v[176:179], v[120:123]
	v_mfma_f32_16x16x32_bf16 v[108:111], v[128:131], v[192:195], v[108:111]
	v_mfma_f32_16x16x32_bf16 v[104:107], v[136:139], v[192:195], v[104:107]
	v_mfma_f32_16x16x32_bf16 v[92:95], v[128:131], v[200:203], v[92:95]
	v_mfma_f32_16x16x32_bf16 v[88:91], v[136:139], v[200:203], v[88:91]
	v_mfma_f32_16x16x32_bf16 v[76:79], v[128:131], v[208:211], v[76:79]
	v_mfma_f32_16x16x32_bf16 v[72:75], v[136:139], v[208:211], v[72:75]
	v_mfma_f32_16x16x32_bf16 v[124:127], v[132:135], v[180:183], v[124:127]
	v_mfma_f32_16x16x32_bf16 v[120:123], v[140:143], v[180:183], v[120:123]
	v_mfma_f32_16x16x32_bf16 v[108:111], v[132:135], v[196:199], v[108:111]
	v_mfma_f32_16x16x32_bf16 v[104:107], v[140:143], v[196:199], v[104:107]
	v_mfma_f32_16x16x32_bf16 v[92:95], v[132:135], v[204:207], v[92:95]
	v_mfma_f32_16x16x32_bf16 v[88:91], v[140:143], v[204:207], v[88:91]
	v_mfma_f32_16x16x32_bf16 v[76:79], v[132:135], v[212:215], v[76:79]
	v_mfma_f32_16x16x32_bf16 v[72:75], v[140:143], v[212:215], v[72:75]
	s_setprio 0
	s_setprio 1
	v_mfma_f32_16x16x32_bf16 v[116:119], v[144:147], v[176:179], v[116:119]
	v_mfma_f32_16x16x32_bf16 v[112:115], v[168:171], v[176:179], v[112:115]
	v_mfma_f32_16x16x32_bf16 v[100:103], v[144:147], v[192:195], v[100:103]
	v_mfma_f32_16x16x32_bf16 v[96:99], v[168:171], v[192:195], v[96:99]
	v_mfma_f32_16x16x32_bf16 v[84:87], v[144:147], v[200:203], v[84:87]
	v_mfma_f32_16x16x32_bf16 v[80:83], v[168:171], v[200:203], v[80:83]
	v_mfma_f32_16x16x32_bf16 v[68:71], v[144:147], v[208:211], v[68:71]
	v_mfma_f32_16x16x32_bf16 v[64:67], v[168:171], v[208:211], v[64:67]
	v_mfma_f32_16x16x32_bf16 v[116:119], v[148:151], v[180:183], v[116:119]
	v_mfma_f32_16x16x32_bf16 v[112:115], v[172:175], v[180:183], v[112:115]
	v_mfma_f32_16x16x32_bf16 v[100:103], v[148:151], v[196:199], v[100:103]
	v_mfma_f32_16x16x32_bf16 v[96:99], v[172:175], v[196:199], v[96:99]
	v_mfma_f32_16x16x32_bf16 v[84:87], v[148:151], v[204:207], v[84:87]
	v_mfma_f32_16x16x32_bf16 v[80:83], v[172:175], v[204:207], v[80:83]
	v_mfma_f32_16x16x32_bf16 v[68:71], v[148:151], v[212:215], v[68:71]
	v_mfma_f32_16x16x32_bf16 v[64:67], v[172:175], v[212:215], v[64:67]
	s_setprio 0
	s_barrier
	s_add_i32 s52, s65, s68
	v_lshl_add_u64 v[184:185], v[184:185], 0, s[28:29]
	s_mov_b32 m0, s52
	ds_read_b128 v[176:179], v191 offset:49152
	ds_read_b128 v[180:183], v191 offset:50176
	ds_read_b128 v[192:195], v191 offset:51200
	ds_read_b128 v[196:199], v191 offset:52224
	ds_read_b128 v[200:203], v191 offset:53248
	ds_read_b128 v[204:207], v191 offset:54272
	ds_read_b128 v[208:211], v191 offset:55296
	ds_read_b128 v[212:215], v191 offset:56320
	global_load_lds_dwordx4 v[184:185], off
	s_add_i32 m0, s52, 0x2000
	s_add_u32 s50, s50, 0x40080
	v_lshl_add_u64 v[184:185], v[216:217], 0, s[28:29]
	s_addc_u32 s51, s51, 0
	s_add_i32 s52, s66, s68
	global_load_lds_dwordx4 v[184:185], off
	v_lshl_add_u64 v[184:185], s[50:51], 0, v[154:155]
	s_mov_b32 m0, s52
	s_nop 0
	global_load_lds_dwordx4 v[184:185], off
	v_lshl_add_u64 v[184:185], s[50:51], 0, v[158:159]
	s_add_i32 m0, s52, 0x2000
	s_nop 0
	global_load_lds_dwordx4 v[184:185], off
	v_lshl_add_u64 v[184:185], v[218:219], 0, s[28:29]
	s_mov_b32 m0, s75
	s_nop 0
	global_load_lds_dwordx4 v[184:185], off
	v_lshl_add_u64 v[184:185], v[220:221], 0, s[28:29]
	s_mov_b32 m0, s56
	s_nop 0
	global_load_lds_dwordx4 v[184:185], off
	s_waitcnt vmcnt(8)
	s_cmp_lt_u32 s3, 4
	s_cbranch_scc1 .Lgls_35
	s_waitcnt lgkmcnt(0)
.Lgls_35:
	s_barrier
	s_setprio 1
	s_waitcnt lgkmcnt(0)
	v_mfma_f32_16x16x32_bf16 v[60:63], v[128:131], v[176:179], v[60:63]
	v_mfma_f32_16x16x32_bf16 v[56:59], v[136:139], v[176:179], v[56:59]
	v_mfma_f32_16x16x32_bf16 v[44:47], v[128:131], v[192:195], v[44:47]
	v_mfma_f32_16x16x32_bf16 v[40:43], v[136:139], v[192:195], v[40:43]
	v_mfma_f32_16x16x32_bf16 v[28:31], v[128:131], v[200:203], v[28:31]
	v_mfma_f32_16x16x32_bf16 v[24:27], v[136:139], v[200:203], v[24:27]
	v_mfma_f32_16x16x32_bf16 v[12:15], v[128:131], v[208:211], v[12:15]
	v_mfma_f32_16x16x32_bf16 v[8:11], v[136:139], v[208:211], v[8:11]
	v_mfma_f32_16x16x32_bf16 v[60:63], v[132:135], v[180:183], v[60:63]
	v_mfma_f32_16x16x32_bf16 v[56:59], v[140:143], v[180:183], v[56:59]
	v_mfma_f32_16x16x32_bf16 v[44:47], v[132:135], v[196:199], v[44:47]
	v_mfma_f32_16x16x32_bf16 v[40:43], v[140:143], v[196:199], v[40:43]
	v_mfma_f32_16x16x32_bf16 v[28:31], v[132:135], v[204:207], v[28:31]
	v_mfma_f32_16x16x32_bf16 v[24:27], v[140:143], v[204:207], v[24:27]
	v_mfma_f32_16x16x32_bf16 v[12:15], v[132:135], v[212:215], v[12:15]
	v_mfma_f32_16x16x32_bf16 v[8:11], v[140:143], v[212:215], v[8:11]
	s_setprio 0
	s_setprio 1
	v_mfma_f32_16x16x32_bf16 v[52:55], v[144:147], v[176:179], v[52:55]
	v_mfma_f32_16x16x32_bf16 v[48:51], v[168:171], v[176:179], v[48:51]
	v_mfma_f32_16x16x32_bf16 v[36:39], v[144:147], v[192:195], v[36:39]
	v_mfma_f32_16x16x32_bf16 v[32:35], v[168:171], v[192:195], v[32:35]
	v_mfma_f32_16x16x32_bf16 v[20:23], v[144:147], v[200:203], v[20:23]
	v_mfma_f32_16x16x32_bf16 v[16:19], v[168:171], v[200:203], v[16:19]
	v_mfma_f32_16x16x32_bf16 v[4:7], v[144:147], v[208:211], v[4:7]
	v_mfma_f32_16x16x32_bf16 v[0:3], v[168:171], v[208:211], v[0:3]
	v_mfma_f32_16x16x32_bf16 v[52:55], v[148:151], v[180:183], v[52:55]
	v_mfma_f32_16x16x32_bf16 v[48:51], v[172:175], v[180:183], v[48:51]
	v_mfma_f32_16x16x32_bf16 v[36:39], v[148:151], v[196:199], v[36:39]
	v_mfma_f32_16x16x32_bf16 v[32:35], v[172:175], v[196:199], v[32:35]
	v_mfma_f32_16x16x32_bf16 v[20:23], v[148:151], v[204:207], v[20:23]
	v_mfma_f32_16x16x32_bf16 v[16:19], v[172:175], v[204:207], v[16:19]
	v_mfma_f32_16x16x32_bf16 v[4:7], v[148:151], v[212:215], v[4:7]
	v_mfma_f32_16x16x32_bf16 v[0:3], v[172:175], v[212:215], v[0:3]
	s_setprio 0
	s_barrier
	s_add_i32 s64, s64, 2
	s_add_u32 s48, s48, 0x100
	s_addc_u32 s49, s49, 0
	s_add_u32 s47, s47, 0x100
	s_addc_u32 s63, s63, 0
	s_cmp_gt_u32 s64, 13
	s_cbranch_scc0 .LBB0_1165
	s_and_b64 vcc, exec, s[16:17]
	s_cbranch_vccz .LBB0_1168
	s_barrier

; #define PG8_STAGE(bufoff, gbase, voff) do { _Pragma("unroll") for (int _i = 0; _i < 2; ++_i) \
;         __builtin_amdgcn_global_load_lds((const unsigned*)((const char*)(gbase) + (voff)[_i]), (PG8_LAS unsigned*)(lds + (bufoff) + ldsw + _i * 8192), 16, 0, 0); } while (0)
; #define PG8_LDA(dst, b, h) do { _Pragma("unroll") for (int m = 0; m < 4; ++m) _Pragma("unroll") for (int k = 0; k < 2; ++k) dst[m][k] = *(const PG8_LAS bf16x8*)(lds + PG8_SA(b, h) + aoff + m * 2048 + k * 1024); } while (0)
; #define PG8_LDB(dst, b, h) do { _Pragma("unroll") for (int n = 0; n < 2; ++n) _Pragma("unroll") for (int k = 0; k < 2; ++k) dst[n][k] = *(const PG8_LAS bf16x8*)(lds + PG8_SB(b, h) + boff + n * 2048 + k * 1024); } while (0)
; #define PG8_MMA(ai, bj, At, Bt) do { __builtin_amdgcn_s_setprio(1); _Pragma("unroll") for (int m = 0; m < 4; ++m) _Pragma("unroll") for (int n = 0; n < 2; ++n) _Pragma("unroll") for (int k = 0; k < 2; ++k) \
;         acc[ai][bj][m][n] = mma16<F16>(Bt[n][k], At[m][k], acc[ai][bj][m][n]); __builtin_amdgcn_s_setprio(0); } while (0)
; #define PG8_WAIT_V(n) asm volatile("s_waitcnt vmcnt(" #n ")" ::: "memory")
; #define PG8_WAIT_L(n) asm volatile("s_waitcnt lgkmcnt(" #n ")" ::: "memory")
; template <class Epi, class Sched, bool ALIGN_EPI = false, bool SP2 = false, bool F16 = false>
; __device__ __forceinline__ void gemm_phase(PG8_LAS unsigned char* lds, const Gemm g, const Sched& S, const Epi& E, const int wid_in) {
;     ...
;             const bool last = (t == nt - 2);
;             const char* a1 = cA + (size_t)(t + 1) * kstep;
;             const char* a2 = last ? nA : cA + (size_t)(t + 2) * kstep; const char* b2 = last ? nB : cB + (size_t)(t + 2) * kstep;
;             const char* a3 = a2 + kstep; const char* b3 = b2 + kstep;
;             if (last && has_next) S.a_ready(nxt);
;             if constexpr (SP2) {
;             PG8_LDB(B0, 0, 0); PG8_LDB(B1, 0, 1); PG8_SCHED; PG8_LDA(At, 0, 0); PG8_STAGE(PG8_SA(1, 1), a1 + hstep, voffA);
;             PG8_WAIT_V(8); PG8_WAIT_L(0); PG8_BAR; PG8_MMA(0, 0, At, B0); PG8_MMA(0, 1, At, B1); PG8_BAR; PG8_SCHED;
;             PG8_LDA(At, 0, 1); PG8_STAGE(PG8_SB(0, 0), b2, voffB); PG8_STAGE(PG8_SB(0, 1), b2 + hstep, voffB); PG8_STAGE(PG8_SA(0, 0), a2, voffA);
;             PG8_WAIT_V(8); PG8_WAIT_L(0); PG8_BAR; PG8_MMA(1, 0, At, B0); PG8_MMA(1, 1, At, B1); PG8_BAR; PG8_SCHED;
.LBB0_1242:
	ds_read_b128 v[0:3], v193
	ds_read_b128 v[4:7], v193 offset:1024
	ds_read_b128 v[136:139], v193 offset:2048
	ds_read_b128 v[140:143], v193 offset:3072
	ds_read_b128 v[144:147], v194
	ds_read_b128 v[148:151], v194 offset:1024
	ds_read_b128 v[152:155], v194 offset:2048
	ds_read_b128 v[156:159], v194 offset:3072
	s_add_u32 s48, s46, 0xfffc0080
	s_addc_u32 s49, s47, -1
	s_cmp_eq_u32 s67, 12
	s_cselect_b32 s51, s29, s49
	s_cselect_b32 s50, s42, s48
	s_cselect_b32 s49, s27, s66
	s_cselect_b32 s48, s43, s45
	v_lshl_add_u64 v[188:189], s[46:47], 0, v[168:169]
	s_add_i32 m0, s74, 0xc000
	ds_read_b128 v[176:179], v195
	ds_read_b128 v[180:183], v195 offset:1024
	ds_read_b128 v[184:187], v195 offset:2048
	ds_read_b128 v[198:201], v195 offset:3072
	ds_read_b128 v[202:205], v195 offset:4096
	ds_read_b128 v[206:209], v195 offset:5120
	ds_read_b128 v[210:213], v195 offset:6144
	ds_read_b128 v[214:217], v195 offset:7168
	global_load_lds_dwordx4 v[188:189], off
	v_lshl_add_u64 v[188:189], s[46:47], 0, v[170:171]
	s_add_i32 m0, s74, 0xe000
	s_nop 0
	global_load_lds_dwordx4 v[188:189], off
	s_waitcnt vmcnt(8)
	s_cmp_lt_u32 s3, 4
	s_cbranch_scc1 .Lgls_36
	s_waitcnt lgkmcnt(0)
.Lgls_36:
	s_barrier
	s_setprio 1
	s_waitcnt lgkmcnt(0)
	v_mfma_f32_16x16x32_f16 v[132:135], v[0:3], v[176:179], v[132:135]
	v_mfma_f32_16x16x32_f16 v[128:131], v[136:139], v[176:179], v[128:131]
	v_mfma_f32_16x16x32_f16 v[116:119], v[0:3], v[184:187], v[116:119]
	v_mfma_f32_16x16x32_f16 v[112:115], v[136:139], v[184:187], v[112:115]
	v_mfma_f32_16x16x32_f16 v[100:103], v[0:3], v[202:205], v[100:103]
	v_mfma_f32_16x16x32_f16 v[96:99], v[136:139], v[202:205], v[96:99]
	v_mfma_f32_16x16x32_f16 v[84:87], v[0:3], v[210:213], v[84:87]
	v_mfma_f32_16x16x32_f16 v[80:83], v[136:139], v[210:213], v[80:83]
	v_mfma_f32_16x16x32_f16 v[132:135], v[4:7], v[180:183], v[132:135]
	v_mfma_f32_16x16x32_f16 v[128:131], v[140:143], v[180:183], v[128:131]
	v_mfma_f32_16x16x32_f16 v[116:119], v[4:7], v[198:201], v[116:119]
	v_mfma_f32_16x16x32_f16 v[112:115], v[140:143], v[198:201], v[112:115]
	v_mfma_f32_16x16x32_f16 v[100:103], v[4:7], v[206:209], v[100:103]
	v_mfma_f32_16x16x32_f16 v[96:99], v[140:143], v[206:209], v[96:99]
	v_mfma_f32_16x16x32_f16 v[84:87], v[4:7], v[214:217], v[84:87]
	v_mfma_f32_16x16x32_f16 v[80:83], v[140:143], v[214:217], v[80:83]
	s_setprio 0
	s_setprio 1
	v_mfma_f32_16x16x32_f16 v[124:127], v[144:147], v[176:179], v[124:127]
	v_mfma_f32_16x16x32_f16 v[120:123], v[152:155], v[176:179], v[120:123]
	v_mfma_f32_16x16x32_f16 v[108:111], v[144:147], v[184:187], v[108:111]
	v_mfma_f32_16x16x32_f16 v[104:107], v[152:155], v[184:187], v[104:107]
	v_mfma_f32_16x16x32_f16 v[92:95], v[144:147], v[202:205], v[92:95]
	v_mfma_f32_16x16x32_f16 v[88:91], v[152:155], v[202:205], v[88:91]
	v_mfma_f32_16x16x32_f16 v[76:79], v[144:147], v[210:213], v[76:79]
	v_mfma_f32_16x16x32_f16 v[72:75], v[152:155], v[210:213], v[72:75]
	v_mfma_f32_16x16x32_f16 v[124:127], v[148:151], v[180:183], v[124:127]
	v_mfma_f32_16x16x32_f16 v[120:123], v[156:159], v[180:183], v[120:123]
	v_mfma_f32_16x16x32_f16 v[108:111], v[148:151], v[198:201], v[108:111]
	v_mfma_f32_16x16x32_f16 v[104:107], v[156:159], v[198:201], v[104:107]
	v_mfma_f32_16x16x32_f16 v[92:95], v[148:151], v[206:209], v[92:95]
	v_mfma_f32_16x16x32_f16 v[88:91], v[156:159], v[206:209], v[88:91]
	v_mfma_f32_16x16x32_f16 v[76:79], v[148:151], v[214:217], v[76:79]
	v_mfma_f32_16x16x32_f16 v[72:75], v[156:159], v[214:217], v[72:75]
	s_setprio 0
	s_barrier
	s_add_i32 s76, s63, s68
	v_lshl_add_u64 v[188:189], s[48:49], 0, v[162:163]
	s_mov_b32 m0, s76
	ds_read_b128 v[176:179], v195 offset:16384
	ds_read_b128 v[180:183], v195 offset:17408
	ds_read_b128 v[184:187], v195 offset:18432
	ds_read_b128 v[198:201], v195 offset:19456
	ds_read_b128 v[202:205], v195 offset:20480
	ds_read_b128 v[206:209], v195 offset:21504
	ds_read_b128 v[210:213], v195 offset:22528
	ds_read_b128 v[214:217], v195 offset:23552
	global_load_lds_dwordx4 v[188:189], off
	s_add_i32 m0, s76, 0x2000
	s_add_u32 s90, s48, 0x40000
	v_lshl_add_u64 v[218:219], s[48:49], 0, v[166:167]
	s_addc_u32 s91, s49, 0
	s_add_i32 s76, s64, s68
	global_load_lds_dwordx4 v[218:219], off
	v_lshl_add_u64 v[220:221], s[90:91], 0, v[162:163]
	s_mov_b32 m0, s76
	v_lshl_add_u64 v[222:223], s[50:51], 0, v[164:165]
	global_load_lds_dwordx4 v[220:221], off
	v_lshl_add_u64 v[220:221], s[90:91], 0, v[166:167]
	s_add_i32 m0, s76, 0x2000
	s_nop 0
	global_load_lds_dwordx4 v[220:221], off
	v_lshl_add_u64 v[220:221], s[50:51], 0, v[160:161]
	s_mov_b32 m0, s74
	s_nop 0
	global_load_lds_dwordx4 v[220:221], off
	s_mov_b32 m0, s37
	s_nop 0
	global_load_lds_dwordx4 v[222:223], off
	s_waitcnt vmcnt(8)
	s_cmp_lt_u32 s3, 4
	s_cbranch_scc1 .Lgls_37
	s_waitcnt lgkmcnt(0)
; #define PG8_STAGE(bufoff, gbase, voff) do { _Pragma("unroll") for (int _i = 0; _i < 2; ++_i) \
;         __builtin_amdgcn_global_load_lds((const unsigned*)((const char*)(gbase) + (voff)[_i]), (PG8_LAS unsigned*)(lds + (bufoff) + ldsw + _i * 8192), 16, 0, 0); } while (0)
; #define PG8_LDA(dst, b, h) do { _Pragma("unroll") for (int m = 0; m < 4; ++m) _Pragma("unroll") for (int k = 0; k < 2; ++k) dst[m][k] = *(const PG8_LAS bf16x8*)(lds + PG8_SA(b, h) + aoff + m * 2048 + k * 1024); } while (0)
; #define PG8_LDB(dst, b, h) do { _Pragma("unroll") for (int n = 0; n < 2; ++n) _Pragma("unroll") for (int k = 0; k < 2; ++k) dst[n][k] = *(const PG8_LAS bf16x8*)(lds + PG8_SB(b, h) + boff + n * 2048 + k * 1024); } while (0)
; #define PG8_MMA(ai, bj, At, Bt) do { __builtin_amdgcn_s_setprio(1); _Pragma("unroll") for (int m = 0; m < 4; ++m) _Pragma("unroll") for (int n = 0; n < 2; ++n) _Pragma("unroll") for (int k = 0; k < 2; ++k) \
;         acc[ai][bj][m][n] = mma16<F16>(Bt[n][k], At[m][k], acc[ai][bj][m][n]); __builtin_amdgcn_s_setprio(0); } while (0)
; #define PG8_WAIT_V(n) asm volatile("s_waitcnt vmcnt(" #n ")" ::: "memory")
; #define PG8_WAIT_L(n) asm volatile("s_waitcnt lgkmcnt(" #n ")" ::: "memory")
; #define PG8_BAR __builtin_amdgcn_s_barrier()
; #define PG8_SCHED __builtin_amdgcn_sched_barrier(0)
; template <class Epi, class Sched, bool ALIGN_EPI = false, bool SP2 = false, bool F16 = false>
; __device__ __forceinline__ void gemm_phase(PG8_LAS unsigned char* lds, const Gemm g, const Sched& S, const Epi& E, const int wid_in) {
;     ...
;             PG8_WAIT_V(8); PG8_WAIT_L(0); PG8_BAR; PG8_MMA(1, 0, At, B0); PG8_MMA(1, 1, At, B1); PG8_BAR; PG8_SCHED;
;             PG8_LDB(B0, 1, 0); PG8_LDB(B1, 1, 1); PG8_SCHED; PG8_LDA(At, 1, 0); PG8_STAGE(PG8_SA(0, 1), a2 + hstep, voffA);
;             PG8_WAIT_V(8); PG8_WAIT_L(0); PG8_BAR; PG8_MMA(0, 0, At, B0); PG8_MMA(0, 1, At, B1); PG8_BAR; PG8_SCHED;
.Lgls_37:
	s_barrier
	s_setprio 1
	s_waitcnt lgkmcnt(0)
	v_mfma_f32_16x16x32_f16 v[68:71], v[0:3], v[176:179], v[68:71]
	v_mfma_f32_16x16x32_f16 v[64:67], v[136:139], v[176:179], v[64:67]
	v_mfma_f32_16x16x32_f16 v[52:55], v[0:3], v[184:187], v[52:55]
	v_mfma_f32_16x16x32_f16 v[48:51], v[136:139], v[184:187], v[48:51]
	v_mfma_f32_16x16x32_f16 v[36:39], v[0:3], v[202:205], v[36:39]
	v_mfma_f32_16x16x32_f16 v[32:35], v[136:139], v[202:205], v[32:35]
	v_mfma_f32_16x16x32_f16 v[0:3], v[0:3], v[210:213], v[20:23]
	v_mfma_f32_16x16x32_f16 v[68:71], v[4:7], v[180:183], v[68:71]
	v_mfma_f32_16x16x32_f16 v[64:67], v[140:143], v[180:183], v[64:67]
	v_mfma_f32_16x16x32_f16 v[52:55], v[4:7], v[198:201], v[52:55]
	v_mfma_f32_16x16x32_f16 v[48:51], v[140:143], v[198:201], v[48:51]
	v_mfma_f32_16x16x32_f16 v[36:39], v[4:7], v[206:209], v[36:39]
	v_mfma_f32_16x16x32_f16 v[32:35], v[140:143], v[206:209], v[32:35]
	v_mfma_f32_16x16x32_f16 v[0:3], v[4:7], v[214:217], v[0:3]
	v_mfma_f32_16x16x32_f16 v[4:7], v[136:139], v[210:213], v[16:19]
	v_mfma_f32_16x16x32_f16 v[4:7], v[140:143], v[214:217], v[4:7]
	s_setprio 0
	s_setprio 1
	v_mfma_f32_16x16x32_f16 v[16:19], v[144:147], v[176:179], v[60:63]
	v_mfma_f32_16x16x32_f16 v[60:63], v[148:151], v[180:183], v[16:19]
	v_mfma_f32_16x16x32_f16 v[16:19], v[152:155], v[176:179], v[56:59]
	v_mfma_f32_16x16x32_f16 v[56:59], v[156:159], v[180:183], v[16:19]
	v_mfma_f32_16x16x32_f16 v[16:19], v[144:147], v[184:187], v[44:47]
	v_mfma_f32_16x16x32_f16 v[44:47], v[148:151], v[198:201], v[16:19]
	v_mfma_f32_16x16x32_f16 v[16:19], v[152:155], v[184:187], v[40:43]
	v_mfma_f32_16x16x32_f16 v[40:43], v[156:159], v[198:201], v[16:19]
	v_mfma_f32_16x16x32_f16 v[16:19], v[144:147], v[202:205], v[28:31]
	v_mfma_f32_16x16x32_f16 v[28:31], v[148:151], v[206:209], v[16:19]
	v_mfma_f32_16x16x32_f16 v[16:19], v[152:155], v[202:205], v[24:27]
	v_mfma_f32_16x16x32_f16 v[12:15], v[144:147], v[210:213], v[12:15]
	v_mfma_f32_16x16x32_f16 v[8:11], v[152:155], v[210:213], v[8:11]
	v_mfma_f32_16x16x32_f16 v[24:27], v[156:159], v[206:209], v[16:19]
	v_mfma_f32_16x16x32_f16 v[12:15], v[148:151], v[214:217], v[12:15]
	v_mfma_f32_16x16x32_f16 v[8:11], v[156:159], v[214:217], v[8:11]
	s_setprio 0
	s_barrier
	s_add_i32 s76, 0, 0x18000
	s_add_i32 s83, 0, 0x1c000
	v_add_u32_e32 v140, s76, v192
	v_add_u32_e32 v156, s83, v192
	ds_read_b128 v[16:19], v140
	ds_read_b128 v[20:23], v140 offset:1024
	ds_read_b128 v[136:139], v140 offset:2048
	ds_read_b128 v[140:143], v140 offset:3072
	ds_read_b128 v[144:147], v156
	ds_read_b128 v[148:151], v156 offset:1024
	ds_read_b128 v[152:155], v156 offset:2048
	ds_read_b128 v[156:159], v156 offset:3072
	s_add_u32 s50, s50, 0x40000
	s_addc_u32 s51, s51, 0
	s_mov_b32 m0, s53
	v_lshl_add_u64 v[224:225], s[50:51], 0, v[160:161]
	ds_read_b128 v[176:179], v195 offset:32768
	ds_read_b128 v[180:183], v195 offset:33792
	ds_read_b128 v[184:187], v195 offset:34816
	ds_read_b128 v[198:201], v195 offset:35840
	ds_read_b128 v[202:205], v195 offset:36864
	ds_read_b128 v[206:209], v195 offset:37888
	ds_read_b128 v[210:213], v195 offset:38912
	ds_read_b128 v[214:217], v195 offset:39936
	global_load_lds_dwordx4 v[224:225], off
	v_lshl_add_u64 v[224:225], s[50:51], 0, v[164:165]
	s_mov_b32 m0, s54
	s_nop 0
	global_load_lds_dwordx4 v[224:225], off
	s_waitcnt vmcnt(8)
	s_cmp_lt_u32 s3, 4
	s_cbranch_scc1 .Lgls_38
	s_waitcnt lgkmcnt(0)
; #define PG8_STAGE(bufoff, gbase, voff) do { _Pragma("unroll") for (int _i = 0; _i < 2; ++_i) \
;         __builtin_amdgcn_global_load_lds((const unsigned*)((const char*)(gbase) + (voff)[_i]), (PG8_LAS unsigned*)(lds + (bufoff) + ldsw + _i * 8192), 16, 0, 0); } while (0)
; #define PG8_LDA(dst, b, h) do { _Pragma("unroll") for (int m = 0; m < 4; ++m) _Pragma("unroll") for (int k = 0; k < 2; ++k) dst[m][k] = *(const PG8_LAS bf16x8*)(lds + PG8_SA(b, h) + aoff + m * 2048 + k * 1024); } while (0)
; #define PG8_MMA(ai, bj, At, Bt) do { __builtin_amdgcn_s_setprio(1); _Pragma("unroll") for (int m = 0; m < 4; ++m) _Pragma("unroll") for (int n = 0; n < 2; ++n) _Pragma("unroll") for (int k = 0; k < 2; ++k) \
;         acc[ai][bj][m][n] = mma16<F16>(Bt[n][k], At[m][k], acc[ai][bj][m][n]); __builtin_amdgcn_s_setprio(0); } while (0)
; #define PG8_WAIT_V(n) asm volatile("s_waitcnt vmcnt(" #n ")" ::: "memory")
; #define PG8_WAIT_L(n) asm volatile("s_waitcnt lgkmcnt(" #n ")" ::: "memory")
; #define PG8_BAR __builtin_amdgcn_s_barrier()
; #define PG8_SCHED __builtin_amdgcn_sched_barrier(0)
; template <class Epi, class Sched, bool ALIGN_EPI = false, bool SP2 = false, bool F16 = false>
; __device__ __forceinline__ void gemm_phase(PG8_LAS unsigned char* lds, const Gemm g, const Sched& S, const Epi& E, const int wid_in) {
;     ...
;             PG8_WAIT_V(8); PG8_WAIT_L(0); PG8_BAR; PG8_MMA(0, 0, At, B0); PG8_MMA(0, 1, At, B1); PG8_BAR; PG8_SCHED;
;             PG8_LDA(At, 1, 1); PG8_STAGE(PG8_SB(1, 0), b3, voffB); PG8_STAGE(PG8_SB(1, 1), b3 + hstep, voffB); PG8_STAGE(PG8_SA(1, 0), a3, voffA);
;             PG8_WAIT_V(8); PG8_WAIT_L(0); PG8_BAR; PG8_MMA(1, 0, At, B0); PG8_MMA(1, 1, At, B1); PG8_BAR; PG8_SCHED;
;     ...
;         if constexpr (ALIGN_EPI) { if (wr == 0) PG8_BAR; }
.Lgls_38:
	s_barrier
	s_setprio 1
	s_waitcnt lgkmcnt(0)
	v_mfma_f32_16x16x32_f16 v[132:135], v[16:19], v[176:179], v[132:135]
	v_mfma_f32_16x16x32_f16 v[128:131], v[136:139], v[176:179], v[128:131]
	v_mfma_f32_16x16x32_f16 v[116:119], v[16:19], v[184:187], v[116:119]
	v_mfma_f32_16x16x32_f16 v[112:115], v[136:139], v[184:187], v[112:115]
	v_mfma_f32_16x16x32_f16 v[100:103], v[16:19], v[202:205], v[100:103]
	v_mfma_f32_16x16x32_f16 v[96:99], v[136:139], v[202:205], v[96:99]
	v_mfma_f32_16x16x32_f16 v[84:87], v[16:19], v[210:213], v[84:87]
	v_mfma_f32_16x16x32_f16 v[80:83], v[136:139], v[210:213], v[80:83]
	v_mfma_f32_16x16x32_f16 v[132:135], v[20:23], v[180:183], v[132:135]
	v_mfma_f32_16x16x32_f16 v[128:131], v[140:143], v[180:183], v[128:131]
	v_mfma_f32_16x16x32_f16 v[116:119], v[20:23], v[198:201], v[116:119]
	v_mfma_f32_16x16x32_f16 v[112:115], v[140:143], v[198:201], v[112:115]
	v_mfma_f32_16x16x32_f16 v[100:103], v[20:23], v[206:209], v[100:103]
	v_mfma_f32_16x16x32_f16 v[96:99], v[140:143], v[206:209], v[96:99]
	v_mfma_f32_16x16x32_f16 v[84:87], v[20:23], v[214:217], v[84:87]
	v_mfma_f32_16x16x32_f16 v[80:83], v[140:143], v[214:217], v[80:83]
	s_setprio 0
	s_setprio 1
	v_mfma_f32_16x16x32_f16 v[124:127], v[144:147], v[176:179], v[124:127]
	v_mfma_f32_16x16x32_f16 v[120:123], v[152:155], v[176:179], v[120:123]
	v_mfma_f32_16x16x32_f16 v[108:111], v[144:147], v[184:187], v[108:111]
	v_mfma_f32_16x16x32_f16 v[104:107], v[152:155], v[184:187], v[104:107]
	v_mfma_f32_16x16x32_f16 v[92:95], v[144:147], v[202:205], v[92:95]
	v_mfma_f32_16x16x32_f16 v[88:91], v[152:155], v[202:205], v[88:91]
	v_mfma_f32_16x16x32_f16 v[76:79], v[144:147], v[210:213], v[76:79]
	v_mfma_f32_16x16x32_f16 v[72:75], v[152:155], v[210:213], v[72:75]
	v_mfma_f32_16x16x32_f16 v[124:127], v[148:151], v[180:183], v[124:127]
	v_mfma_f32_16x16x32_f16 v[120:123], v[156:159], v[180:183], v[120:123]
	v_mfma_f32_16x16x32_f16 v[108:111], v[148:151], v[198:201], v[108:111]
	v_mfma_f32_16x16x32_f16 v[104:107], v[156:159], v[198:201], v[104:107]
	v_mfma_f32_16x16x32_f16 v[92:95], v[148:151], v[206:209], v[92:95]
	v_mfma_f32_16x16x32_f16 v[88:91], v[156:159], v[206:209], v[88:91]
	v_mfma_f32_16x16x32_f16 v[76:79], v[148:151], v[214:217], v[76:79]
	v_mfma_f32_16x16x32_f16 v[72:75], v[156:159], v[214:217], v[72:75]
	s_setprio 0
	s_barrier
	s_add_i32 s50, s76, s68
	v_lshl_add_u64 v[188:189], v[188:189], 0, s[24:25]
	s_mov_b32 m0, s50
	ds_read_b128 v[176:179], v195 offset:49152
	ds_read_b128 v[180:183], v195 offset:50176
	ds_read_b128 v[184:187], v195 offset:51200
	ds_read_b128 v[198:201], v195 offset:52224
	ds_read_b128 v[202:205], v195 offset:53248
	ds_read_b128 v[206:209], v195 offset:54272
	ds_read_b128 v[210:213], v195 offset:55296
	ds_read_b128 v[214:217], v195 offset:56320
	global_load_lds_dwordx4 v[188:189], off
	s_add_i32 m0, s50, 0x2000
	s_add_u32 s48, s48, 0x40080
	v_lshl_add_u64 v[188:189], v[218:219], 0, s[24:25]
	s_addc_u32 s49, s49, 0
	s_add_i32 s50, s83, s68
	global_load_lds_dwordx4 v[188:189], off
	v_lshl_add_u64 v[188:189], s[48:49], 0, v[162:163]
	s_mov_b32 m0, s50
	s_nop 0
	global_load_lds_dwordx4 v[188:189], off
	v_lshl_add_u64 v[188:189], s[48:49], 0, v[166:167]
	s_add_i32 m0, s50, 0x2000
	s_nop 0
	global_load_lds_dwordx4 v[188:189], off
	v_lshl_add_u64 v[188:189], v[220:221], 0, s[24:25]
	s_mov_b32 m0, s75
	s_nop 0
	global_load_lds_dwordx4 v[188:189], off
	v_lshl_add_u64 v[188:189], v[222:223], 0, s[24:25]
	s_mov_b32 m0, s57
	s_nop 0
	global_load_lds_dwordx4 v[188:189], off
	s_waitcnt vmcnt(8)
	s_cmp_lt_u32 s3, 4
	s_cbranch_scc1 .Lgls_39
	s_waitcnt lgkmcnt(0)
.Lgls_39:
	s_barrier
	s_setprio 1
	s_waitcnt lgkmcnt(0)
	v_mfma_f32_16x16x32_f16 v[68:71], v[16:19], v[176:179], v[68:71]
	v_mfma_f32_16x16x32_f16 v[52:55], v[16:19], v[184:187], v[52:55]
	v_mfma_f32_16x16x32_f16 v[36:39], v[16:19], v[202:205], v[36:39]
	v_mfma_f32_16x16x32_f16 v[0:3], v[16:19], v[210:213], v[0:3]
	v_mfma_f32_16x16x32_f16 v[68:71], v[20:23], v[180:183], v[68:71]
	v_mfma_f32_16x16x32_f16 v[64:67], v[136:139], v[176:179], v[64:67]
	v_mfma_f32_16x16x32_f16 v[52:55], v[20:23], v[198:201], v[52:55]
	v_mfma_f32_16x16x32_f16 v[48:51], v[136:139], v[184:187], v[48:51]
	v_mfma_f32_16x16x32_f16 v[36:39], v[20:23], v[206:209], v[36:39]
	v_mfma_f32_16x16x32_f16 v[32:35], v[136:139], v[202:205], v[32:35]
	v_mfma_f32_16x16x32_f16 v[20:23], v[20:23], v[214:217], v[0:3]
	v_mfma_f32_16x16x32_f16 v[0:3], v[136:139], v[210:213], v[4:7]
	v_mfma_f32_16x16x32_f16 v[64:67], v[140:143], v[180:183], v[64:67]
	v_mfma_f32_16x16x32_f16 v[48:51], v[140:143], v[198:201], v[48:51]
	v_mfma_f32_16x16x32_f16 v[32:35], v[140:143], v[206:209], v[32:35]
	v_mfma_f32_16x16x32_f16 v[16:19], v[140:143], v[214:217], v[0:3]
	s_setprio 0
	s_setprio 1
	v_mfma_f32_16x16x32_f16 v[0:3], v[144:147], v[176:179], v[60:63]
	v_mfma_f32_16x16x32_f16 v[60:63], v[148:151], v[180:183], v[0:3]
	v_mfma_f32_16x16x32_f16 v[0:3], v[152:155], v[176:179], v[56:59]
	v_mfma_f32_16x16x32_f16 v[56:59], v[156:159], v[180:183], v[0:3]
	v_mfma_f32_16x16x32_f16 v[0:3], v[144:147], v[184:187], v[44:47]
	v_mfma_f32_16x16x32_f16 v[44:47], v[148:151], v[198:201], v[0:3]
	v_mfma_f32_16x16x32_f16 v[0:3], v[152:155], v[184:187], v[40:43]
	v_mfma_f32_16x16x32_f16 v[40:43], v[156:159], v[198:201], v[0:3]
	v_mfma_f32_16x16x32_f16 v[0:3], v[144:147], v[202:205], v[28:31]
	v_mfma_f32_16x16x32_f16 v[28:31], v[148:151], v[206:209], v[0:3]
	v_mfma_f32_16x16x32_f16 v[0:3], v[152:155], v[202:205], v[24:27]
	v_mfma_f32_16x16x32_f16 v[24:27], v[156:159], v[206:209], v[0:3]
	v_mfma_f32_16x16x32_f16 v[0:3], v[144:147], v[210:213], v[12:15]
	v_mfma_f32_16x16x32_f16 v[12:15], v[148:151], v[214:217], v[0:3]
	v_mfma_f32_16x16x32_f16 v[0:3], v[152:155], v[210:213], v[8:11]
	v_mfma_f32_16x16x32_f16 v[8:11], v[156:159], v[214:217], v[0:3]
	s_setprio 0
	s_barrier
	s_add_i32 s67, s67, 2
	s_add_u32 s46, s46, 0x100
	s_addc_u32 s47, s47, 0
	s_add_u32 s45, s45, 0x100
	s_addc_u32 s66, s66, 0
	s_cmp_gt_u32 s67, 13
	s_cbranch_scc0 .LBB0_1242
	s_and_b64 vcc, exec, s[16:17]
	s_cbranch_vccz .LBB0_1245
	s_barrier

; #define PG8_STAGE(bufoff, gbase, voff) do { _Pragma("unroll") for (int _i = 0; _i < 2; ++_i) \
;         __builtin_amdgcn_global_load_lds((const unsigned*)((const char*)(gbase) + (voff)[_i]), (PG8_LAS unsigned*)(lds + (bufoff) + ldsw + _i * 8192), 16, 0, 0); } while (0)
; #define PG8_LDA(dst, b, h) do { _Pragma("unroll") for (int m = 0; m < 4; ++m) _Pragma("unroll") for (int k = 0; k < 2; ++k) dst[m][k] = *(const PG8_LAS bf16x8*)(lds + PG8_SA(b, h) + aoff + m * 2048 + k * 1024); } while (0)
; #define PG8_LDB(dst, b, h) do { _Pragma("unroll") for (int n = 0; n < 2; ++n) _Pragma("unroll") for (int k = 0; k < 2; ++k) dst[n][k] = *(const PG8_LAS bf16x8*)(lds + PG8_SB(b, h) + boff + n * 2048 + k * 1024); } while (0)
; #define PG8_WAIT_V(n) asm volatile("s_waitcnt vmcnt(" #n ")" ::: "memory")
; #define PG8_WAIT_L(n) asm volatile("s_waitcnt lgkmcnt(" #n ")" ::: "memory")
; #define PG8_BAR __builtin_amdgcn_s_barrier()
; #define PG8_SCHED __builtin_amdgcn_sched_barrier(0)
; template <class Epi, class Sched, bool ALIGN_EPI = false, bool SP2 = false, bool F16 = false>
; __device__ __forceinline__ void gemm_phase(PG8_LAS unsigned char* lds, const Gemm g, const Sched& S, const Epi& E, const int wid_in) {
;     ...
;         const bool has_next = S.next(ui + 1, nxt);
;         const char* nA = has_next ? (const char*)g.A + (size_t)nxt.pm * tstep : cA; const char* nB = has_next ? (const char*)g.Bt + (size_t)nxt.pn * tstep : cB;
;         for (int t = 0; t < nt; t += 2) {
;             const bool last = (t == nt - 2);
;             const char* a1 = cA + (size_t)(t + 1) * kstep;
;             const char* a2 = last ? nA : cA + (size_t)(t + 2) * kstep; const char* b2 = last ? nB : cB + (size_t)(t + 2) * kstep;
;             const char* a3 = a2 + kstep; const char* b3 = b2 + kstep;
;             if (last && has_next) S.a_ready(nxt);
;             if constexpr (SP2) {
;             PG8_LDB(B0, 0, 0); PG8_LDB(B1, 0, 1); PG8_SCHED; PG8_LDA(At, 0, 0); PG8_STAGE(PG8_SA(1, 1), a1 + hstep, voffA);
;             PG8_WAIT_V(8); PG8_WAIT_L(0); PG8_BAR; PG8_MMA(0, 0, At, B0); PG8_MMA(0, 1, At, B1); PG8_BAR; PG8_SCHED;
;             PG8_LDA(At, 0, 1); PG8_STAGE(PG8_SB(0, 0), b2, voffB); PG8_STAGE(PG8_SB(0, 1), b2 + hstep, voffB); PG8_STAGE(PG8_SA(0, 0), a2, voffA);
;             PG8_WAIT_V(8); PG8_WAIT_L(0); PG8_BAR; PG8_MMA(1, 0, At, B0); PG8_MMA(1, 1, At, B1); PG8_BAR; PG8_SCHED;
.LBB0_1277:
	s_mov_b64 s[48:49], s[10:11]
	s_add_i32 s10, s36, s19
	s_mov_b64 s[46:47], s[12:13]
	s_mov_b32 s12, s62
	s_mov_b32 s13, s61
	s_and_b32 s61, s10, 3
	s_ashr_i32 s62, s10, 2
	s_and_b64 s[10:11], s[30:31], exec
	s_cselect_b32 s12, s62, s12
	ds_read_b128 v[0:3], v134
	ds_read_b128 v[4:7], v134 offset:1024
	ds_read_b128 v[8:11], v134 offset:2048
	ds_read_b128 v[12:15], v134 offset:3072
	ds_read_b128 v[16:19], v135
	ds_read_b128 v[20:23], v135 offset:1024
	ds_read_b128 v[24:27], v135 offset:2048
	ds_read_b128 v[28:31], v135 offset:3072
	s_cselect_b32 s10, s61, s13
	s_ashr_i32 s13, s12, 31
	s_lshl_b64 s[12:13], s[12:13], 17
	s_add_u32 s12, s21, s12
	s_addc_u32 s13, s40, s13
	s_and_b64 s[36:37], s[30:31], exec
	s_cselect_b32 s45, s13, s47
	s_cselect_b32 s44, s12, s46
	s_ashr_i32 s11, s10, 31
	s_lshl_b64 s[10:11], s[10:11], 17
	s_add_u32 s10, s41, s10
	s_addc_u32 s11, s42, s11
	s_and_b64 s[36:37], s[30:31], exec
	s_cselect_b32 s37, s11, s49
	s_cselect_b32 s36, s10, s48
	s_add_u32 s64, s46, 0x10080
	s_addc_u32 s65, s47, 0
	s_mov_b32 m0, s15
	v_lshl_add_u64 v[64:65], s[64:65], 0, v[130:131]
	ds_read_b128 v[32:35], v136
	ds_read_b128 v[36:39], v136 offset:1024
	ds_read_b128 v[40:43], v136 offset:2048
	ds_read_b128 v[44:47], v136 offset:3072
	ds_read_b128 v[48:51], v136 offset:4096
	ds_read_b128 v[52:55], v136 offset:5120
	ds_read_b128 v[56:59], v136 offset:6144
	ds_read_b128 v[60:63], v136 offset:7168
	global_load_lds_dwordx4 v[64:65], off
	v_lshl_add_u64 v[64:65], s[64:65], 0, v[128:129]
	s_mov_b32 m0, s52
	s_nop 0
	global_load_lds_dwordx4 v[64:65], off
	s_waitcnt vmcnt(8)
	s_cmp_lt_u32 s3, 4
	s_cbranch_scc1 .Lgls_40
	s_waitcnt lgkmcnt(0)
.Lgls_40:
	s_barrier
	s_setprio 1
	s_waitcnt lgkmcnt(0)
	v_mfma_f32_16x16x32_bf16 v[64:67], v[0:3], v[32:35], 0
	v_mfma_f32_16x16x32_bf16 v[68:71], v[8:11], v[32:35], 0
	v_mfma_f32_16x16x32_bf16 v[72:75], v[0:3], v[40:43], 0
	v_mfma_f32_16x16x32_bf16 v[76:79], v[8:11], v[40:43], 0
	v_mfma_f32_16x16x32_bf16 v[80:83], v[0:3], v[48:51], 0
	v_mfma_f32_16x16x32_bf16 v[84:87], v[8:11], v[48:51], 0
	v_mfma_f32_16x16x32_bf16 v[88:91], v[0:3], v[56:59], 0
	v_mfma_f32_16x16x32_bf16 v[92:95], v[8:11], v[56:59], 0
	v_mfma_f32_16x16x32_bf16 v[64:67], v[4:7], v[36:39], v[64:67]
	v_mfma_f32_16x16x32_bf16 v[68:71], v[12:15], v[36:39], v[68:71]
	v_mfma_f32_16x16x32_bf16 v[72:75], v[4:7], v[44:47], v[72:75]
	v_mfma_f32_16x16x32_bf16 v[76:79], v[12:15], v[44:47], v[76:79]
	v_mfma_f32_16x16x32_bf16 v[80:83], v[4:7], v[52:55], v[80:83]
	v_mfma_f32_16x16x32_bf16 v[84:87], v[12:15], v[52:55], v[84:87]
	v_mfma_f32_16x16x32_bf16 v[88:91], v[4:7], v[60:63], v[88:91]
	v_mfma_f32_16x16x32_bf16 v[92:95], v[12:15], v[60:63], v[92:95]
	s_setprio 0
	s_setprio 1
	v_mfma_f32_16x16x32_bf16 v[96:99], v[16:19], v[32:35], 0
	v_mfma_f32_16x16x32_bf16 v[32:35], v[24:27], v[32:35], 0
	v_mfma_f32_16x16x32_bf16 v[96:99], v[20:23], v[36:39], v[96:99]
	v_mfma_f32_16x16x32_bf16 v[32:35], v[28:31], v[36:39], v[32:35]
	v_mfma_f32_16x16x32_bf16 v[36:39], v[16:19], v[40:43], 0
	v_mfma_f32_16x16x32_bf16 v[40:43], v[24:27], v[40:43], 0
	v_mfma_f32_16x16x32_bf16 v[36:39], v[20:23], v[44:47], v[36:39]
	v_mfma_f32_16x16x32_bf16 v[40:43], v[28:31], v[44:47], v[40:43]
	v_mfma_f32_16x16x32_bf16 v[44:47], v[16:19], v[48:51], 0
	v_mfma_f32_16x16x32_bf16 v[48:51], v[24:27], v[48:51], 0
	v_mfma_f32_16x16x32_bf16 v[44:47], v[20:23], v[52:55], v[44:47]
	v_mfma_f32_16x16x32_bf16 v[48:51], v[28:31], v[52:55], v[48:51]
	v_mfma_f32_16x16x32_bf16 v[52:55], v[16:19], v[56:59], 0
	v_mfma_f32_16x16x32_bf16 v[56:59], v[24:27], v[56:59], 0
	v_mfma_f32_16x16x32_bf16 v[52:55], v[20:23], v[60:63], v[52:55]
	v_mfma_f32_16x16x32_bf16 v[56:59], v[28:31], v[60:63], v[56:59]
	s_setprio 0
	s_barrier
	v_lshl_add_u64 v[204:205], s[48:49], 0, v[130:131]
	s_mov_b32 m0, s53
	v_lshl_add_u64 v[140:141], v[204:205], 0, s[26:27]
	v_lshl_add_u64 v[206:207], s[48:49], 0, v[128:129]
	s_add_u32 s64, s48, 0x10100
	ds_read_b128 v[60:63], v136 offset:16384
	ds_read_b128 v[100:103], v136 offset:17408
	ds_read_b128 v[104:107], v136 offset:18432
	ds_read_b128 v[108:111], v136 offset:19456
	ds_read_b128 v[112:115], v136 offset:20480
	ds_read_b128 v[116:119], v136 offset:21504
	ds_read_b128 v[120:123], v136 offset:22528
	ds_read_b128 v[124:127], v136 offset:23552
	global_load_lds_dwordx4 v[140:141], off
	v_lshl_add_u64 v[140:141], v[206:207], 0, s[26:27]
	s_mov_b32 m0, s54
	s_addc_u32 s65, s49, 0
	global_load_lds_dwordx4 v[140:141], off
	v_lshl_add_u64 v[140:141], s[64:65], 0, v[130:131]
	s_mov_b32 m0, s55
	v_lshl_add_u64 v[208:209], s[46:47], 0, v[130:131]
	global_load_lds_dwordx4 v[140:141], off
	v_lshl_add_u64 v[140:141], s[64:65], 0, v[128:129]
	s_mov_b32 m0, s56
	v_lshl_add_u64 v[210:211], s[46:47], 0, v[128:129]
	global_load_lds_dwordx4 v[140:141], off
	v_lshl_add_u64 v[140:141], v[208:209], 0, s[26:27]
	s_mov_b32 m0, s74
	s_nop 0
	global_load_lds_dwordx4 v[140:141], off
	v_lshl_add_u64 v[140:141], v[210:211], 0, s[26:27]
	s_mov_b32 m0, s43
	s_nop 0
	global_load_lds_dwordx4 v[140:141], off
	s_waitcnt vmcnt(8)
	s_cmp_lt_u32 s3, 4
	s_cbranch_scc1 .Lgls_41
	s_waitcnt lgkmcnt(0)
; #define PG8_STAGE(bufoff, gbase, voff) do { _Pragma("unroll") for (int _i = 0; _i < 2; ++_i) \
;         __builtin_amdgcn_global_load_lds((const unsigned*)((const char*)(gbase) + (voff)[_i]), (PG8_LAS unsigned*)(lds + (bufoff) + ldsw + _i * 8192), 16, 0, 0); } while (0)
; #define PG8_LDA(dst, b, h) do { _Pragma("unroll") for (int m = 0; m < 4; ++m) _Pragma("unroll") for (int k = 0; k < 2; ++k) dst[m][k] = *(const PG8_LAS bf16x8*)(lds + PG8_SA(b, h) + aoff + m * 2048 + k * 1024); } while (0)
; #define PG8_LDB(dst, b, h) do { _Pragma("unroll") for (int n = 0; n < 2; ++n) _Pragma("unroll") for (int k = 0; k < 2; ++k) dst[n][k] = *(const PG8_LAS bf16x8*)(lds + PG8_SB(b, h) + boff + n * 2048 + k * 1024); } while (0)
; #define PG8_MMA(ai, bj, At, Bt) do { __builtin_amdgcn_s_setprio(1); _Pragma("unroll") for (int m = 0; m < 4; ++m) _Pragma("unroll") for (int n = 0; n < 2; ++n) _Pragma("unroll") for (int k = 0; k < 2; ++k) \
;         acc[ai][bj][m][n] = mma16<F16>(Bt[n][k], At[m][k], acc[ai][bj][m][n]); __builtin_amdgcn_s_setprio(0); } while (0)
; #define PG8_WAIT_V(n) asm volatile("s_waitcnt vmcnt(" #n ")" ::: "memory")
; #define PG8_WAIT_L(n) asm volatile("s_waitcnt lgkmcnt(" #n ")" ::: "memory")
; #define PG8_BAR __builtin_amdgcn_s_barrier()
; #define PG8_SCHED __builtin_amdgcn_sched_barrier(0)
; template <class Epi, class Sched, bool ALIGN_EPI = false, bool SP2 = false, bool F16 = false>
; __device__ __forceinline__ void gemm_phase(PG8_LAS unsigned char* lds, const Gemm g, const Sched& S, const Epi& E, const int wid_in) {
;     ...
;             PG8_WAIT_V(8); PG8_WAIT_L(0); PG8_BAR; PG8_MMA(1, 0, At, B0); PG8_MMA(1, 1, At, B1); PG8_BAR; PG8_SCHED;
;             PG8_LDB(B0, 1, 0); PG8_LDB(B1, 1, 1); PG8_SCHED; PG8_LDA(At, 1, 0); PG8_STAGE(PG8_SA(0, 1), a2 + hstep, voffA);
;             PG8_WAIT_V(8); PG8_WAIT_L(0); PG8_BAR; PG8_MMA(0, 0, At, B0); PG8_MMA(0, 1, At, B1); PG8_BAR; PG8_SCHED;
;             PG8_LDA(At, 1, 1); PG8_STAGE(PG8_SB(1, 0), b3, voffB); PG8_STAGE(PG8_SB(1, 1), b3 + hstep, voffB); PG8_STAGE(PG8_SA(1, 0), a3, voffA);
;             PG8_WAIT_V(8); PG8_WAIT_L(0); PG8_BAR; PG8_MMA(1, 0, At, B0); PG8_MMA(1, 1, At, B1); PG8_BAR; PG8_SCHED;
.Lgls_41:
	s_barrier
	s_setprio 1
	s_waitcnt lgkmcnt(0)
	v_mfma_f32_16x16x32_bf16 v[140:143], v[0:3], v[60:63], 0
	v_mfma_f32_16x16x32_bf16 v[148:151], v[0:3], v[104:107], 0
	v_mfma_f32_16x16x32_bf16 v[156:159], v[0:3], v[112:115], 0
	v_mfma_f32_16x16x32_bf16 v[0:3], v[0:3], v[120:123], 0
	v_mfma_f32_16x16x32_bf16 v[140:143], v[4:7], v[100:103], v[140:143]
	v_mfma_f32_16x16x32_bf16 v[148:151], v[4:7], v[108:111], v[148:151]
	v_mfma_f32_16x16x32_bf16 v[156:159], v[4:7], v[116:119], v[156:159]
	v_mfma_f32_16x16x32_bf16 v[0:3], v[4:7], v[124:127], v[0:3]
	v_mfma_f32_16x16x32_bf16 v[4:7], v[8:11], v[120:123], 0
	v_mfma_f32_16x16x32_bf16 v[144:147], v[8:11], v[60:63], 0
	v_mfma_f32_16x16x32_bf16 v[152:155], v[8:11], v[104:107], 0
	v_mfma_f32_16x16x32_bf16 v[160:163], v[8:11], v[112:115], 0
	v_mfma_f32_16x16x32_bf16 v[4:7], v[12:15], v[124:127], v[4:7]
	v_mfma_f32_16x16x32_bf16 v[144:147], v[12:15], v[100:103], v[144:147]
	v_mfma_f32_16x16x32_bf16 v[152:155], v[12:15], v[108:111], v[152:155]
	v_mfma_f32_16x16x32_bf16 v[160:163], v[12:15], v[116:119], v[160:163]
	s_setprio 0
	s_setprio 1
	v_mfma_f32_16x16x32_bf16 v[8:11], v[16:19], v[60:63], 0
	v_mfma_f32_16x16x32_bf16 v[12:15], v[24:27], v[60:63], 0
	v_mfma_f32_16x16x32_bf16 v[8:11], v[20:23], v[100:103], v[8:11]
	v_mfma_f32_16x16x32_bf16 v[12:15], v[28:31], v[100:103], v[12:15]
	v_mfma_f32_16x16x32_bf16 v[60:63], v[16:19], v[104:107], 0
	v_mfma_f32_16x16x32_bf16 v[100:103], v[24:27], v[104:107], 0
	v_mfma_f32_16x16x32_bf16 v[104:107], v[16:19], v[112:115], 0
	v_mfma_f32_16x16x32_bf16 v[16:19], v[16:19], v[120:123], 0
	v_mfma_f32_16x16x32_bf16 v[60:63], v[20:23], v[108:111], v[60:63]
	v_mfma_f32_16x16x32_bf16 v[100:103], v[28:31], v[108:111], v[100:103]
	v_mfma_f32_16x16x32_bf16 v[104:107], v[20:23], v[116:119], v[104:107]
	v_mfma_f32_16x16x32_bf16 v[108:111], v[24:27], v[112:115], 0
	v_mfma_f32_16x16x32_bf16 v[16:19], v[20:23], v[124:127], v[16:19]
	v_mfma_f32_16x16x32_bf16 v[20:23], v[24:27], v[120:123], 0
	v_mfma_f32_16x16x32_bf16 v[108:111], v[28:31], v[116:119], v[108:111]
	v_mfma_f32_16x16x32_bf16 v[20:23], v[28:31], v[124:127], v[20:23]
	s_setprio 0
	s_barrier
	ds_read_b128 v[24:27], v137
	ds_read_b128 v[28:31], v137 offset:1024
	ds_read_b128 v[112:115], v137 offset:2048
	ds_read_b128 v[116:119], v137 offset:3072
	ds_read_b128 v[120:123], v138
	ds_read_b128 v[124:127], v138 offset:1024
	ds_read_b128 v[164:167], v138 offset:2048
	ds_read_b128 v[168:171], v138 offset:3072
	s_add_u32 s64, s46, 0x10100
	s_addc_u32 s65, s47, 0
	s_mov_b32 m0, s50
	v_lshl_add_u64 v[212:213], s[64:65], 0, v[130:131]
	ds_read_b128 v[172:175], v136 offset:32768
	ds_read_b128 v[176:179], v136 offset:33792
	ds_read_b128 v[180:183], v136 offset:34816
	ds_read_b128 v[184:187], v136 offset:35840
	ds_read_b128 v[188:191], v136 offset:36864
	ds_read_b128 v[192:195], v136 offset:37888
	ds_read_b128 v[196:199], v136 offset:38912
	ds_read_b128 v[200:203], v136 offset:39936
	global_load_lds_dwordx4 v[212:213], off
	v_lshl_add_u64 v[212:213], s[64:65], 0, v[128:129]
	s_mov_b32 m0, s51
	s_nop 0
	global_load_lds_dwordx4 v[212:213], off
	s_waitcnt vmcnt(8)
	s_cmp_lt_u32 s3, 4
	s_cbranch_scc1 .Lgls_42
	s_waitcnt lgkmcnt(0)
.Lgls_42:
	s_barrier
	s_setprio 1
	s_waitcnt lgkmcnt(0)
	v_mfma_f32_16x16x32_bf16 v[64:67], v[24:27], v[172:175], v[64:67]
	v_mfma_f32_16x16x32_bf16 v[68:71], v[112:115], v[172:175], v[68:71]
	v_mfma_f32_16x16x32_bf16 v[72:75], v[24:27], v[180:183], v[72:75]
	v_mfma_f32_16x16x32_bf16 v[76:79], v[112:115], v[180:183], v[76:79]
	v_mfma_f32_16x16x32_bf16 v[80:83], v[24:27], v[188:191], v[80:83]
	v_mfma_f32_16x16x32_bf16 v[84:87], v[112:115], v[188:191], v[84:87]
	v_mfma_f32_16x16x32_bf16 v[88:91], v[24:27], v[196:199], v[88:91]
	v_mfma_f32_16x16x32_bf16 v[92:95], v[112:115], v[196:199], v[92:95]
	v_mfma_f32_16x16x32_bf16 v[64:67], v[28:31], v[176:179], v[64:67]
	v_mfma_f32_16x16x32_bf16 v[68:71], v[116:119], v[176:179], v[68:71]
	v_mfma_f32_16x16x32_bf16 v[72:75], v[28:31], v[184:187], v[72:75]
	v_mfma_f32_16x16x32_bf16 v[76:79], v[116:119], v[184:187], v[76:79]
	v_mfma_f32_16x16x32_bf16 v[80:83], v[28:31], v[192:195], v[80:83]
	v_mfma_f32_16x16x32_bf16 v[84:87], v[116:119], v[192:195], v[84:87]
	v_mfma_f32_16x16x32_bf16 v[88:91], v[28:31], v[200:203], v[88:91]
	v_mfma_f32_16x16x32_bf16 v[92:95], v[116:119], v[200:203], v[92:95]
	s_setprio 0
	s_setprio 1
	v_mfma_f32_16x16x32_bf16 v[96:99], v[120:123], v[172:175], v[96:99]
	v_mfma_f32_16x16x32_bf16 v[32:35], v[164:167], v[172:175], v[32:35]
	v_mfma_f32_16x16x32_bf16 v[36:39], v[120:123], v[180:183], v[36:39]
	v_mfma_f32_16x16x32_bf16 v[40:43], v[164:167], v[180:183], v[40:43]
	v_mfma_f32_16x16x32_bf16 v[44:47], v[120:123], v[188:191], v[44:47]
	v_mfma_f32_16x16x32_bf16 v[48:51], v[164:167], v[188:191], v[48:51]
	v_mfma_f32_16x16x32_bf16 v[52:55], v[120:123], v[196:199], v[52:55]
	v_mfma_f32_16x16x32_bf16 v[56:59], v[164:167], v[196:199], v[56:59]
	v_mfma_f32_16x16x32_bf16 v[96:99], v[124:127], v[176:179], v[96:99]
	v_mfma_f32_16x16x32_bf16 v[32:35], v[168:171], v[176:179], v[32:35]
	v_mfma_f32_16x16x32_bf16 v[36:39], v[124:127], v[184:187], v[36:39]
	v_mfma_f32_16x16x32_bf16 v[40:43], v[168:171], v[184:187], v[40:43]
	v_mfma_f32_16x16x32_bf16 v[44:47], v[124:127], v[192:195], v[44:47]
	v_mfma_f32_16x16x32_bf16 v[48:51], v[168:171], v[192:195], v[48:51]
	v_mfma_f32_16x16x32_bf16 v[52:55], v[124:127], v[200:203], v[52:55]
	v_mfma_f32_16x16x32_bf16 v[56:59], v[168:171], v[200:203], v[56:59]
	s_setprio 0
	s_barrier
	s_mov_b32 m0, s57
	v_lshl_add_u64 v[204:205], v[204:205], 0, s[28:29]
	s_add_u32 s48, s48, 0x10180
	ds_read_b128 v[172:175], v136 offset:49152
	ds_read_b128 v[176:179], v136 offset:50176
	ds_read_b128 v[180:183], v136 offset:51200
	ds_read_b128 v[184:187], v136 offset:52224
	ds_read_b128 v[188:191], v136 offset:53248
	ds_read_b128 v[192:195], v136 offset:54272
	ds_read_b128 v[196:199], v136 offset:55296
	ds_read_b128 v[200:203], v136 offset:56320
	global_load_lds_dwordx4 v[204:205], off
	v_lshl_add_u64 v[204:205], v[206:207], 0, s[28:29]
	s_mov_b32 m0, s58
	s_addc_u32 s49, s49, 0
	global_load_lds_dwordx4 v[204:205], off
	v_lshl_add_u64 v[204:205], s[48:49], 0, v[130:131]
	s_mov_b32 m0, s59
	s_nop 0
	global_load_lds_dwordx4 v[204:205], off
	v_lshl_add_u64 v[204:205], s[48:49], 0, v[128:129]
	s_mov_b32 m0, s60
	s_nop 0
	global_load_lds_dwordx4 v[204:205], off
	v_lshl_add_u64 v[204:205], v[208:209], 0, s[28:29]
	s_mov_b32 m0, s75
	s_nop 0
	global_load_lds_dwordx4 v[204:205], off
	v_lshl_add_u64 v[204:205], v[210:211], 0, s[28:29]
	s_mov_b32 m0, s14
	s_nop 0
	global_load_lds_dwordx4 v[204:205], off
	s_waitcnt vmcnt(8)
	s_cmp_lt_u32 s3, 4
	s_cbranch_scc1 .Lgls_43
	s_waitcnt lgkmcnt(0)
; #define PG8_STAGE(bufoff, gbase, voff) do { _Pragma("unroll") for (int _i = 0; _i < 2; ++_i) \
;         __builtin_amdgcn_global_load_lds((const unsigned*)((const char*)(gbase) + (voff)[_i]), (PG8_LAS unsigned*)(lds + (bufoff) + ldsw + _i * 8192), 16, 0, 0); } while (0)
; #define PG8_LDA(dst, b, h) do { _Pragma("unroll") for (int m = 0; m < 4; ++m) _Pragma("unroll") for (int k = 0; k < 2; ++k) dst[m][k] = *(const PG8_LAS bf16x8*)(lds + PG8_SA(b, h) + aoff + m * 2048 + k * 1024); } while (0)
; #define PG8_LDB(dst, b, h) do { _Pragma("unroll") for (int n = 0; n < 2; ++n) _Pragma("unroll") for (int k = 0; k < 2; ++k) dst[n][k] = *(const PG8_LAS bf16x8*)(lds + PG8_SB(b, h) + boff + n * 2048 + k * 1024); } while (0)
; #define PG8_MMA(ai, bj, At, Bt) do { __builtin_amdgcn_s_setprio(1); _Pragma("unroll") for (int m = 0; m < 4; ++m) _Pragma("unroll") for (int n = 0; n < 2; ++n) _Pragma("unroll") for (int k = 0; k < 2; ++k) \
;         acc[ai][bj][m][n] = mma16<F16>(Bt[n][k], At[m][k], acc[ai][bj][m][n]); __builtin_amdgcn_s_setprio(0); } while (0)
; #define PG8_WAIT_V(n) asm volatile("s_waitcnt vmcnt(" #n ")" ::: "memory")
; template <class Epi, class Sched, bool ALIGN_EPI = false, bool SP2 = false, bool F16 = false>
; __device__ __forceinline__ void gemm_phase(PG8_LAS unsigned char* lds, const Gemm g, const Sched& S, const Epi& E, const int wid_in) {
;     ...
;             PG8_LDB(B0, 0, 0); PG8_LDB(B1, 0, 1); PG8_SCHED; PG8_LDA(At, 0, 0); PG8_STAGE(PG8_SA(1, 1), a1 + hstep, voffA);
;             PG8_WAIT_V(8); PG8_WAIT_L(0); PG8_BAR; PG8_MMA(0, 0, At, B0); PG8_MMA(0, 1, At, B1); PG8_BAR; PG8_SCHED;
;             PG8_LDA(At, 0, 1); PG8_STAGE(PG8_SB(0, 0), b2, voffB); PG8_STAGE(PG8_SB(0, 1), b2 + hstep, voffB); PG8_STAGE(PG8_SA(0, 0), a2, voffA);
;             PG8_WAIT_V(8); PG8_WAIT_L(0); PG8_BAR; PG8_MMA(1, 0, At, B0); PG8_MMA(1, 1, At, B1); PG8_BAR; PG8_SCHED;
;             PG8_LDB(B0, 1, 0); PG8_LDB(B1, 1, 1); PG8_SCHED; PG8_LDA(At, 1, 0); PG8_STAGE(PG8_SA(0, 1), a2 + hstep, voffA);
;             PG8_WAIT_V(8); PG8_WAIT_L(0); PG8_BAR; PG8_MMA(0, 0, At, B0); PG8_MMA(0, 1, At, B1); PG8_BAR; PG8_SCHED;
;             PG8_LDA(At, 1, 1); PG8_STAGE(PG8_SB(1, 0), b3, voffB); PG8_STAGE(PG8_SB(1, 1), b3 + hstep, voffB); PG8_STAGE(PG8_SA(1, 0), a3, voffA);
;             PG8_WAIT_V(8); PG8_WAIT_L(0); PG8_BAR; PG8_MMA(1, 0, At, B0); PG8_MMA(1, 1, At, B1); PG8_BAR; PG8_SCHED;
.Lgls_43:
	s_barrier
	s_setprio 1
	s_waitcnt lgkmcnt(0)
	v_mfma_f32_16x16x32_bf16 v[0:3], v[24:27], v[196:199], v[0:3]
	v_mfma_f32_16x16x32_bf16 v[4:7], v[112:115], v[196:199], v[4:7]
	v_mfma_f32_16x16x32_bf16 v[140:143], v[24:27], v[172:175], v[140:143]
	v_mfma_f32_16x16x32_bf16 v[144:147], v[112:115], v[172:175], v[144:147]
	v_mfma_f32_16x16x32_bf16 v[148:151], v[24:27], v[180:183], v[148:151]
	v_mfma_f32_16x16x32_bf16 v[152:155], v[112:115], v[180:183], v[152:155]
	v_mfma_f32_16x16x32_bf16 v[156:159], v[24:27], v[188:191], v[156:159]
	v_mfma_f32_16x16x32_bf16 v[160:163], v[112:115], v[188:191], v[160:163]
	v_mfma_f32_16x16x32_bf16 v[0:3], v[28:31], v[200:203], v[0:3]
	v_mfma_f32_16x16x32_bf16 v[4:7], v[116:119], v[200:203], v[4:7]
	v_mfma_f32_16x16x32_bf16 v[140:143], v[28:31], v[176:179], v[140:143]
	v_mfma_f32_16x16x32_bf16 v[144:147], v[116:119], v[176:179], v[144:147]
	v_mfma_f32_16x16x32_bf16 v[148:151], v[28:31], v[184:187], v[148:151]
	v_mfma_f32_16x16x32_bf16 v[152:155], v[116:119], v[184:187], v[152:155]
	v_mfma_f32_16x16x32_bf16 v[156:159], v[28:31], v[192:195], v[156:159]
	v_mfma_f32_16x16x32_bf16 v[160:163], v[116:119], v[192:195], v[160:163]
	s_setprio 0
	s_setprio 1
	v_mfma_f32_16x16x32_bf16 v[8:11], v[120:123], v[172:175], v[8:11]
	v_mfma_f32_16x16x32_bf16 v[12:15], v[164:167], v[172:175], v[12:15]
	v_mfma_f32_16x16x32_bf16 v[24:27], v[120:123], v[180:183], v[60:63]
	v_mfma_f32_16x16x32_bf16 v[28:31], v[164:167], v[180:183], v[100:103]
	v_mfma_f32_16x16x32_bf16 v[60:63], v[120:123], v[188:191], v[104:107]
	v_mfma_f32_16x16x32_bf16 v[100:103], v[164:167], v[188:191], v[108:111]
	v_mfma_f32_16x16x32_bf16 v[16:19], v[120:123], v[196:199], v[16:19]
	v_mfma_f32_16x16x32_bf16 v[20:23], v[164:167], v[196:199], v[20:23]
	v_mfma_f32_16x16x32_bf16 v[8:11], v[124:127], v[176:179], v[8:11]
	v_mfma_f32_16x16x32_bf16 v[12:15], v[168:171], v[176:179], v[12:15]
	v_mfma_f32_16x16x32_bf16 v[24:27], v[124:127], v[184:187], v[24:27]
	v_mfma_f32_16x16x32_bf16 v[28:31], v[168:171], v[184:187], v[28:31]
	v_mfma_f32_16x16x32_bf16 v[60:63], v[124:127], v[192:195], v[60:63]
	v_mfma_f32_16x16x32_bf16 v[100:103], v[168:171], v[192:195], v[100:103]
	v_mfma_f32_16x16x32_bf16 v[16:19], v[124:127], v[200:203], v[16:19]
	v_mfma_f32_16x16x32_bf16 v[20:23], v[168:171], v[200:203], v[20:23]
	s_setprio 0
	s_barrier
	ds_read_b128 v[104:107], v134
	ds_read_b128 v[108:111], v134 offset:1024
	ds_read_b128 v[112:115], v134 offset:2048
	ds_read_b128 v[116:119], v134 offset:3072
	ds_read_b128 v[120:123], v135
	ds_read_b128 v[124:127], v135 offset:1024
	ds_read_b128 v[164:167], v135 offset:2048
	ds_read_b128 v[168:171], v135 offset:3072
	s_add_u32 s46, s46, 0x10180
	s_addc_u32 s47, s47, 0
	s_mov_b32 m0, s15
	v_lshl_add_u64 v[204:205], s[46:47], 0, v[130:131]
	ds_read_b128 v[172:175], v136
	ds_read_b128 v[176:179], v136 offset:1024
	ds_read_b128 v[180:183], v136 offset:2048
	ds_read_b128 v[184:187], v136 offset:3072
	ds_read_b128 v[188:191], v136 offset:4096
	ds_read_b128 v[192:195], v136 offset:5120
	ds_read_b128 v[196:199], v136 offset:6144
	ds_read_b128 v[200:203], v136 offset:7168
	global_load_lds_dwordx4 v[204:205], off
	v_lshl_add_u64 v[204:205], s[46:47], 0, v[128:129]
	s_mov_b32 m0, s52
	s_nop 0
	global_load_lds_dwordx4 v[204:205], off
	s_waitcnt vmcnt(8)
	s_cmp_lt_u32 s3, 4
	s_cbranch_scc1 .Lgls_44
	s_waitcnt lgkmcnt(0)
.Lgls_44:
	s_barrier
	s_setprio 1
	s_waitcnt lgkmcnt(0)
	v_mfma_f32_16x16x32_bf16 v[64:67], v[104:107], v[172:175], v[64:67]
	v_mfma_f32_16x16x32_bf16 v[68:71], v[112:115], v[172:175], v[68:71]
	v_mfma_f32_16x16x32_bf16 v[72:75], v[104:107], v[180:183], v[72:75]
	v_mfma_f32_16x16x32_bf16 v[76:79], v[112:115], v[180:183], v[76:79]
	v_mfma_f32_16x16x32_bf16 v[80:83], v[104:107], v[188:191], v[80:83]
	v_mfma_f32_16x16x32_bf16 v[84:87], v[112:115], v[188:191], v[84:87]
	v_mfma_f32_16x16x32_bf16 v[88:91], v[104:107], v[196:199], v[88:91]
	v_mfma_f32_16x16x32_bf16 v[92:95], v[112:115], v[196:199], v[92:95]
	v_mfma_f32_16x16x32_bf16 v[64:67], v[108:111], v[176:179], v[64:67]
	v_mfma_f32_16x16x32_bf16 v[68:71], v[116:119], v[176:179], v[68:71]
	v_mfma_f32_16x16x32_bf16 v[72:75], v[108:111], v[184:187], v[72:75]
	v_mfma_f32_16x16x32_bf16 v[76:79], v[116:119], v[184:187], v[76:79]
	v_mfma_f32_16x16x32_bf16 v[80:83], v[108:111], v[192:195], v[80:83]
	v_mfma_f32_16x16x32_bf16 v[84:87], v[116:119], v[192:195], v[84:87]
	v_mfma_f32_16x16x32_bf16 v[88:91], v[108:111], v[200:203], v[88:91]
	v_mfma_f32_16x16x32_bf16 v[92:95], v[116:119], v[200:203], v[92:95]
	s_setprio 0
	s_setprio 1
	v_mfma_f32_16x16x32_bf16 v[32:35], v[164:167], v[172:175], v[32:35]
	v_mfma_f32_16x16x32_bf16 v[96:99], v[120:123], v[172:175], v[96:99]
	v_mfma_f32_16x16x32_bf16 v[172:175], v[168:171], v[176:179], v[32:35]
	v_mfma_f32_16x16x32_bf16 v[32:35], v[120:123], v[180:183], v[36:39]
	v_mfma_f32_16x16x32_bf16 v[204:207], v[124:127], v[176:179], v[96:99]
	v_mfma_f32_16x16x32_bf16 v[176:179], v[124:127], v[184:187], v[32:35]
	v_mfma_f32_16x16x32_bf16 v[32:35], v[164:167], v[180:183], v[40:43]
	v_mfma_f32_16x16x32_bf16 v[40:43], v[168:171], v[184:187], v[32:35]
	v_mfma_f32_16x16x32_bf16 v[32:35], v[120:123], v[188:191], v[44:47]
	v_mfma_f32_16x16x32_bf16 v[44:47], v[124:127], v[192:195], v[32:35]
	v_mfma_f32_16x16x32_bf16 v[32:35], v[164:167], v[188:191], v[48:51]
	v_mfma_f32_16x16x32_bf16 v[48:51], v[168:171], v[192:195], v[32:35]
	v_mfma_f32_16x16x32_bf16 v[32:35], v[120:123], v[196:199], v[52:55]
	v_mfma_f32_16x16x32_bf16 v[52:55], v[124:127], v[200:203], v[32:35]
	v_mfma_f32_16x16x32_bf16 v[32:35], v[164:167], v[196:199], v[56:59]
	v_mfma_f32_16x16x32_bf16 v[56:59], v[168:171], v[200:203], v[32:35]
	s_setprio 0
	s_barrier
	s_mov_b32 m0, s53
	v_lshl_add_u64 v[240:241], s[36:37], 0, v[130:131]
	s_add_u32 s46, s36, 0x10000
	s_nop 1
	ds_read_b128 v[32:35], v136 offset:16384
	ds_read_b128 v[36:39], v136 offset:17408
	ds_read_b128 v[96:99], v136 offset:18432
	ds_read_b128 v[180:183], v136 offset:19456
	ds_read_b128 v[184:187], v136 offset:20480
	ds_read_b128 v[188:191], v136 offset:21504
	ds_read_b128 v[192:195], v136 offset:22528
	ds_read_b128 v[196:199], v136 offset:23552
	global_load_lds_dwordx4 v[240:241], off
	v_lshl_add_u64 v[242:243], s[36:37], 0, v[128:129]
	s_mov_b32 m0, s54
	s_addc_u32 s47, s37, 0
	global_load_lds_dwordx4 v[242:243], off
	v_lshl_add_u64 v[200:201], s[46:47], 0, v[130:131]
	s_mov_b32 m0, s55
	v_lshl_add_u64 v[244:245], s[44:45], 0, v[130:131]
	global_load_lds_dwordx4 v[200:201], off
	v_lshl_add_u64 v[200:201], s[46:47], 0, v[128:129]
	s_mov_b32 m0, s56
	v_lshl_add_u64 v[246:247], s[44:45], 0, v[128:129]
	global_load_lds_dwordx4 v[200:201], off
	s_mov_b32 m0, s74
	s_nop 0
	global_load_lds_dwordx4 v[244:245], off
	s_mov_b32 m0, s43
	s_nop 0
	global_load_lds_dwordx4 v[246:247], off
	s_waitcnt vmcnt(8)
	s_cmp_lt_u32 s3, 4
	s_cbranch_scc1 .Lgls_45
	s_waitcnt lgkmcnt(0)
; #define PG8_STAGE(bufoff, gbase, voff) do { _Pragma("unroll") for (int _i = 0; _i < 2; ++_i) \
;         __builtin_amdgcn_global_load_lds((const unsigned*)((const char*)(gbase) + (voff)[_i]), (PG8_LAS unsigned*)(lds + (bufoff) + ldsw + _i * 8192), 16, 0, 0); } while (0)
; #define PG8_LDA(dst, b, h) do { _Pragma("unroll") for (int m = 0; m < 4; ++m) _Pragma("unroll") for (int k = 0; k < 2; ++k) dst[m][k] = *(const PG8_LAS bf16x8*)(lds + PG8_SA(b, h) + aoff + m * 2048 + k * 1024); } while (0)
; #define PG8_LDB(dst, b, h) do { _Pragma("unroll") for (int n = 0; n < 2; ++n) _Pragma("unroll") for (int k = 0; k < 2; ++k) dst[n][k] = *(const PG8_LAS bf16x8*)(lds + PG8_SB(b, h) + boff + n * 2048 + k * 1024); } while (0)
; #define PG8_MMA(ai, bj, At, Bt) do { __builtin_amdgcn_s_setprio(1); _Pragma("unroll") for (int m = 0; m < 4; ++m) _Pragma("unroll") for (int n = 0; n < 2; ++n) _Pragma("unroll") for (int k = 0; k < 2; ++k) \
;         acc[ai][bj][m][n] = mma16<F16>(Bt[n][k], At[m][k], acc[ai][bj][m][n]); __builtin_amdgcn_s_setprio(0); } while (0)
; #define PG8_WAIT_V(n) asm volatile("s_waitcnt vmcnt(" #n ")" ::: "memory")
; #define PG8_WAIT_L(n) asm volatile("s_waitcnt lgkmcnt(" #n ")" ::: "memory")
; #define PG8_BAR __builtin_amdgcn_s_barrier()
; #define PG8_SCHED __builtin_amdgcn_sched_barrier(0)
; template <class Epi, class Sched, bool ALIGN_EPI = false, bool SP2 = false, bool F16 = false>
; __device__ __forceinline__ void gemm_phase(PG8_LAS unsigned char* lds, const Gemm g, const Sched& S, const Epi& E, const int wid_in) {
;     ...
;             PG8_WAIT_V(8); PG8_WAIT_L(0); PG8_BAR; PG8_MMA(0, 0, At, B0); PG8_MMA(0, 1, At, B1); PG8_BAR; PG8_SCHED;
;             PG8_LDA(At, 0, 1); PG8_STAGE(PG8_SB(0, 0), b2, voffB); PG8_STAGE(PG8_SB(0, 1), b2 + hstep, voffB); PG8_STAGE(PG8_SA(0, 0), a2, voffA);
;             PG8_WAIT_V(8); PG8_WAIT_L(0); PG8_BAR; PG8_MMA(1, 0, At, B0); PG8_MMA(1, 1, At, B1); PG8_BAR; PG8_SCHED;
;             PG8_LDB(B0, 1, 0); PG8_LDB(B1, 1, 1); PG8_SCHED; PG8_LDA(At, 1, 0); PG8_STAGE(PG8_SA(0, 1), a2 + hstep, voffA);
;             PG8_WAIT_V(8); PG8_WAIT_L(0); PG8_BAR; PG8_MMA(0, 0, At, B0); PG8_MMA(0, 1, At, B1); PG8_BAR; PG8_SCHED;
;             PG8_LDA(At, 1, 1); PG8_STAGE(PG8_SB(1, 0), b3, voffB); PG8_STAGE(PG8_SB(1, 1), b3 + hstep, voffB); PG8_STAGE(PG8_SA(1, 0), a3, voffA);
.Lgls_45:
	s_barrier
	s_setprio 1
	s_waitcnt lgkmcnt(0)
	v_mfma_f32_16x16x32_bf16 v[0:3], v[104:107], v[192:195], v[0:3]
	v_mfma_f32_16x16x32_bf16 v[140:143], v[104:107], v[32:35], v[140:143]
	v_mfma_f32_16x16x32_bf16 v[144:147], v[112:115], v[32:35], v[144:147]
	v_mfma_f32_16x16x32_bf16 v[148:151], v[104:107], v[96:99], v[148:151]
	v_mfma_f32_16x16x32_bf16 v[152:155], v[112:115], v[96:99], v[152:155]
	v_mfma_f32_16x16x32_bf16 v[156:159], v[104:107], v[184:187], v[156:159]
	v_mfma_f32_16x16x32_bf16 v[160:163], v[112:115], v[184:187], v[160:163]
	v_mfma_f32_16x16x32_bf16 v[0:3], v[108:111], v[196:199], v[0:3]
	v_mfma_f32_16x16x32_bf16 v[4:7], v[112:115], v[192:195], v[4:7]
	v_mfma_f32_16x16x32_bf16 v[140:143], v[108:111], v[36:39], v[140:143]
	v_mfma_f32_16x16x32_bf16 v[144:147], v[116:119], v[36:39], v[144:147]
	v_mfma_f32_16x16x32_bf16 v[148:151], v[108:111], v[180:183], v[148:151]
	v_mfma_f32_16x16x32_bf16 v[152:155], v[116:119], v[180:183], v[152:155]
	v_mfma_f32_16x16x32_bf16 v[156:159], v[108:111], v[188:191], v[156:159]
	v_mfma_f32_16x16x32_bf16 v[160:163], v[116:119], v[188:191], v[160:163]
	v_mfma_f32_16x16x32_bf16 v[200:203], v[116:119], v[196:199], v[4:7]
	s_setprio 0
	s_setprio 1
	v_mfma_f32_16x16x32_bf16 v[4:7], v[120:123], v[32:35], v[8:11]
	v_mfma_f32_16x16x32_bf16 v[8:11], v[124:127], v[36:39], v[4:7]
	v_mfma_f32_16x16x32_bf16 v[4:7], v[164:167], v[32:35], v[12:15]
	v_mfma_f32_16x16x32_bf16 v[12:15], v[168:171], v[36:39], v[4:7]
	v_mfma_f32_16x16x32_bf16 v[4:7], v[120:123], v[96:99], v[24:27]
	v_mfma_f32_16x16x32_bf16 v[24:27], v[124:127], v[180:183], v[4:7]
	v_mfma_f32_16x16x32_bf16 v[4:7], v[164:167], v[96:99], v[28:31]
	v_mfma_f32_16x16x32_bf16 v[28:31], v[168:171], v[180:183], v[4:7]
	v_mfma_f32_16x16x32_bf16 v[4:7], v[120:123], v[184:187], v[60:63]
	v_mfma_f32_16x16x32_bf16 v[180:183], v[124:127], v[188:191], v[4:7]
	v_mfma_f32_16x16x32_bf16 v[4:7], v[164:167], v[184:187], v[100:103]
	v_mfma_f32_16x16x32_bf16 v[184:187], v[168:171], v[188:191], v[4:7]
	v_mfma_f32_16x16x32_bf16 v[4:7], v[120:123], v[192:195], v[16:19]
	v_mfma_f32_16x16x32_bf16 v[188:191], v[124:127], v[196:199], v[4:7]
	v_mfma_f32_16x16x32_bf16 v[4:7], v[164:167], v[192:195], v[20:23]
	v_mfma_f32_16x16x32_bf16 v[164:167], v[168:171], v[196:199], v[4:7]
	s_setprio 0
	s_barrier
	s_nop 4
	ds_read_b128 v[4:7], v137
	ds_read_b128 v[60:63], v137 offset:1024
	ds_read_b128 v[168:171], v137 offset:2048
	ds_read_b128 v[192:195], v137 offset:3072
	ds_read_b128 v[196:199], v138
	ds_read_b128 v[208:211], v138 offset:1024
	ds_read_b128 v[212:215], v138 offset:2048
	ds_read_b128 v[216:219], v138 offset:3072
	s_add_u32 s44, s44, 0x10000
	s_addc_u32 s45, s45, 0
	s_mov_b32 m0, s50
	v_lshl_add_u64 v[32:33], s[44:45], 0, v[130:131]
	ds_read_b128 v[16:19], v136 offset:32768
	ds_read_b128 v[20:23], v136 offset:33792
	ds_read_b128 v[104:107], v136 offset:34816
	ds_read_b128 v[220:223], v136 offset:35840
	ds_read_b128 v[224:227], v136 offset:36864
	ds_read_b128 v[228:231], v136 offset:37888
	ds_read_b128 v[232:235], v136 offset:38912
	ds_read_b128 v[236:239], v136 offset:39936
	global_load_lds_dwordx4 v[32:33], off
	v_lshl_add_u64 v[32:33], s[44:45], 0, v[128:129]
	s_mov_b32 m0, s51
	s_nop 0
	global_load_lds_dwordx4 v[32:33], off
	s_waitcnt vmcnt(8)
	s_cmp_lt_u32 s3, 4
	s_cbranch_scc1 .Lgls_46
	s_waitcnt lgkmcnt(0)
.Lgls_46:
	s_barrier
	s_setprio 1
	s_waitcnt lgkmcnt(0)
	v_mfma_f32_16x16x32_bf16 v[32:35], v[4:7], v[16:19], v[64:67]
	v_mfma_f32_16x16x32_bf16 v[116:119], v[60:63], v[20:23], v[32:35]
	v_mfma_f32_16x16x32_bf16 v[32:35], v[168:171], v[16:19], v[68:71]
	v_mfma_f32_16x16x32_bf16 v[112:115], v[192:195], v[20:23], v[32:35]
	v_mfma_f32_16x16x32_bf16 v[32:35], v[4:7], v[104:107], v[72:75]
	v_mfma_f32_16x16x32_bf16 v[100:103], v[60:63], v[220:223], v[32:35]
	v_mfma_f32_16x16x32_bf16 v[32:35], v[168:171], v[104:107], v[76:79]
	v_mfma_f32_16x16x32_bf16 v[96:99], v[192:195], v[220:223], v[32:35]
	v_mfma_f32_16x16x32_bf16 v[32:35], v[4:7], v[224:227], v[80:83]
	v_mfma_f32_16x16x32_bf16 v[68:71], v[60:63], v[228:231], v[32:35]
	v_mfma_f32_16x16x32_bf16 v[32:35], v[168:171], v[224:227], v[84:87]
	v_mfma_f32_16x16x32_bf16 v[64:67], v[192:195], v[228:231], v[32:35]
	v_mfma_f32_16x16x32_bf16 v[32:35], v[4:7], v[232:235], v[88:91]
	v_mfma_f32_16x16x32_bf16 v[36:39], v[60:63], v[236:239], v[32:35]
	v_mfma_f32_16x16x32_bf16 v[32:35], v[168:171], v[232:235], v[92:95]
	v_mfma_f32_16x16x32_bf16 v[32:35], v[192:195], v[236:239], v[32:35]
	s_setprio 0
	s_setprio 1
	v_mfma_f32_16x16x32_bf16 v[72:75], v[196:199], v[16:19], v[204:207]
	v_mfma_f32_16x16x32_bf16 v[16:19], v[212:215], v[16:19], v[172:175]
	v_mfma_f32_16x16x32_bf16 v[120:123], v[216:219], v[20:23], v[16:19]
	v_mfma_f32_16x16x32_bf16 v[16:19], v[196:199], v[104:107], v[176:179]
	v_mfma_f32_16x16x32_bf16 v[108:111], v[208:211], v[220:223], v[16:19]
	v_mfma_f32_16x16x32_bf16 v[16:19], v[212:215], v[104:107], v[40:43]
	v_mfma_f32_16x16x32_bf16 v[104:107], v[216:219], v[220:223], v[16:19]
	v_mfma_f32_16x16x32_bf16 v[16:19], v[196:199], v[224:227], v[44:47]
	v_mfma_f32_16x16x32_bf16 v[80:83], v[208:211], v[228:231], v[16:19]
	v_mfma_f32_16x16x32_bf16 v[16:19], v[212:215], v[224:227], v[48:51]
	v_mfma_f32_16x16x32_bf16 v[124:127], v[208:211], v[20:23], v[72:75]
	v_mfma_f32_16x16x32_bf16 v[72:75], v[216:219], v[228:231], v[16:19]
	v_mfma_f32_16x16x32_bf16 v[16:19], v[196:199], v[232:235], v[52:55]
	v_mfma_f32_16x16x32_bf16 v[48:51], v[208:211], v[236:239], v[16:19]
	v_mfma_f32_16x16x32_bf16 v[16:19], v[212:215], v[232:235], v[56:59]
	v_mfma_f32_16x16x32_bf16 v[40:43], v[216:219], v[236:239], v[16:19]
	s_setprio 0
	s_barrier
	s_mov_b32 m0, s57
	s_nop 3
	v_lshl_add_u64 v[16:17], v[240:241], 0, s[24:25]
	s_add_u32 s36, s36, 0x10080
	ds_read_b128 v[56:59], v136 offset:49152
	ds_read_b128 v[88:91], v136 offset:50176
	ds_read_b128 v[172:175], v136 offset:51200
	ds_read_b128 v[176:179], v136 offset:52224
	ds_read_b128 v[204:207], v136 offset:53248
	ds_read_b128 v[220:223], v136 offset:54272
	ds_read_b128 v[224:227], v136 offset:55296
	ds_read_b128 v[228:231], v136 offset:56320
	global_load_lds_dwordx4 v[16:17], off
	v_lshl_add_u64 v[16:17], v[242:243], 0, s[24:25]
	s_mov_b32 m0, s58
	s_addc_u32 s37, s37, 0
	global_load_lds_dwordx4 v[16:17], off
	v_lshl_add_u64 v[16:17], s[36:37], 0, v[130:131]
	s_mov_b32 m0, s59
	s_nop 0
	global_load_lds_dwordx4 v[16:17], off
	v_lshl_add_u64 v[16:17], s[36:37], 0, v[128:129]
	s_mov_b32 m0, s60
	s_nop 0
	global_load_lds_dwordx4 v[16:17], off
	v_lshl_add_u64 v[16:17], v[244:245], 0, s[24:25]
	s_mov_b32 m0, s75
	s_nop 0
	global_load_lds_dwordx4 v[16:17], off
	v_lshl_add_u64 v[16:17], v[246:247], 0, s[24:25]
	s_mov_b32 m0, s14
	s_nop 0
	global_load_lds_dwordx4 v[16:17], off
	s_waitcnt vmcnt(8)
	s_cmp_lt_u32 s3, 4
	s_cbranch_scc1 .Lgls_47
	s_waitcnt lgkmcnt(0)

; #define PG8_STAGE(bufoff, gbase, voff) do { _Pragma("unroll") for (int _i = 0; _i < 2; ++_i) \
;         __builtin_amdgcn_global_load_lds((const unsigned*)((const char*)(gbase) + (voff)[_i]), (PG8_LAS unsigned*)(lds + (bufoff) + ldsw + _i * 8192), 16, 0, 0); } while (0)
; #define PG8_LDA(dst, b, h) do { _Pragma("unroll") for (int m = 0; m < 4; ++m) _Pragma("unroll") for (int k = 0; k < 2; ++k) dst[m][k] = *(const PG8_LAS bf16x8*)(lds + PG8_SA(b, h) + aoff + m * 2048 + k * 1024); } while (0)
; #define PG8_LDB(dst, b, h) do { _Pragma("unroll") for (int n = 0; n < 2; ++n) _Pragma("unroll") for (int k = 0; k < 2; ++k) dst[n][k] = *(const PG8_LAS bf16x8*)(lds + PG8_SB(b, h) + boff + n * 2048 + k * 1024); } while (0)
; #define PG8_MMA(ai, bj, At, Bt) do { __builtin_amdgcn_s_setprio(1); _Pragma("unroll") for (int m = 0; m < 4; ++m) _Pragma("unroll") for (int n = 0; n < 2; ++n) _Pragma("unroll") for (int k = 0; k < 2; ++k) \
;         acc[ai][bj][m][n] = mma16<F16>(Bt[n][k], At[m][k], acc[ai][bj][m][n]); __builtin_amdgcn_s_setprio(0); } while (0)
; #define PG8_WAIT_V(n) asm volatile("s_waitcnt vmcnt(" #n ")" ::: "memory")
; #define PG8_WAIT_L(n) asm volatile("s_waitcnt lgkmcnt(" #n ")" ::: "memory")
; template <class Epi, class Sched, bool ALIGN_EPI = false, bool SP2 = false, bool F16 = false>
; __device__ __forceinline__ void gemm_phase(PG8_LAS unsigned char* lds, const Gemm g, const Sched& S, const Epi& E, const int wid_in) {
;     ...
;             const bool last = (t == nt - 2);
;             const char* a1 = cA + (size_t)(t + 1) * kstep;
;             const char* a2 = last ? nA : cA + (size_t)(t + 2) * kstep; const char* b2 = last ? nB : cB + (size_t)(t + 2) * kstep;
;             const char* a3 = a2 + kstep; const char* b3 = b2 + kstep;
;             if (last && has_next) S.a_ready(nxt);
;             if constexpr (SP2) {
;             PG8_LDB(B0, 0, 0); PG8_LDB(B1, 0, 1); PG8_SCHED; PG8_LDA(At, 0, 0); PG8_STAGE(PG8_SA(1, 1), a1 + hstep, voffA);
;             PG8_WAIT_V(8); PG8_WAIT_L(0); PG8_BAR; PG8_MMA(0, 0, At, B0); PG8_MMA(0, 1, At, B1); PG8_BAR; PG8_SCHED;
;             PG8_LDA(At, 0, 1); PG8_STAGE(PG8_SB(0, 0), b2, voffB); PG8_STAGE(PG8_SB(0, 1), b2 + hstep, voffB); PG8_STAGE(PG8_SA(0, 0), a2, voffA);
;             PG8_WAIT_V(8); PG8_WAIT_L(0); PG8_BAR; PG8_MMA(1, 0, At, B0); PG8_MMA(1, 1, At, B1); PG8_BAR; PG8_SCHED;
.LBB0_1373:
	ds_read_b128 v[128:131], v189
	ds_read_b128 v[132:135], v189 offset:1024
	ds_read_b128 v[136:139], v189 offset:2048
	ds_read_b128 v[140:143], v189 offset:3072
	ds_read_b128 v[144:147], v190
	ds_read_b128 v[148:151], v190 offset:1024
	ds_read_b128 v[168:171], v190 offset:2048
	ds_read_b128 v[172:175], v190 offset:3072
	s_add_u32 s44, s36, 0x100
	s_addc_u32 s45, s37, 0
	s_cmp_eq_u32 s62, 40
	s_cselect_b32 s49, s13, s45
	s_cselect_b32 s48, s12, s44
	s_cselect_b32 s47, s35, s61
	s_cselect_b32 s46, s34, s43
	v_lshl_add_u64 v[184:185], s[36:37], 0, v[160:161]
	s_add_i32 m0, s74, 0xc000
	ds_read_b128 v[176:179], v191
	ds_read_b128 v[180:183], v191 offset:1024
	ds_read_b128 v[192:195], v191 offset:2048
	ds_read_b128 v[196:199], v191 offset:3072
	ds_read_b128 v[200:203], v191 offset:4096
	ds_read_b128 v[204:207], v191 offset:5120
	ds_read_b128 v[208:211], v191 offset:6144
	ds_read_b128 v[212:215], v191 offset:7168
	global_load_lds_dwordx4 v[184:185], off
	v_lshl_add_u64 v[184:185], s[36:37], 0, v[162:163]
	s_add_i32 m0, s74, 0xe000
	s_nop 0
	global_load_lds_dwordx4 v[184:185], off
	s_waitcnt vmcnt(8)
	s_cmp_lt_u32 s3, 4
	s_cbranch_scc1 .Lgls_48
	s_waitcnt lgkmcnt(0)
.Lgls_48:
	s_barrier
	s_setprio 1
	s_waitcnt lgkmcnt(0)
	v_mfma_f32_16x16x32_bf16 v[124:127], v[128:131], v[176:179], v[124:127]
	v_mfma_f32_16x16x32_bf16 v[120:123], v[136:139], v[176:179], v[120:123]
	v_mfma_f32_16x16x32_bf16 v[108:111], v[128:131], v[192:195], v[108:111]
	v_mfma_f32_16x16x32_bf16 v[104:107], v[136:139], v[192:195], v[104:107]
	v_mfma_f32_16x16x32_bf16 v[92:95], v[128:131], v[200:203], v[92:95]
	v_mfma_f32_16x16x32_bf16 v[88:91], v[136:139], v[200:203], v[88:91]
	v_mfma_f32_16x16x32_bf16 v[76:79], v[128:131], v[208:211], v[76:79]
	v_mfma_f32_16x16x32_bf16 v[72:75], v[136:139], v[208:211], v[72:75]
	v_mfma_f32_16x16x32_bf16 v[124:127], v[132:135], v[180:183], v[124:127]
	v_mfma_f32_16x16x32_bf16 v[120:123], v[140:143], v[180:183], v[120:123]
	v_mfma_f32_16x16x32_bf16 v[108:111], v[132:135], v[196:199], v[108:111]
	v_mfma_f32_16x16x32_bf16 v[104:107], v[140:143], v[196:199], v[104:107]
	v_mfma_f32_16x16x32_bf16 v[92:95], v[132:135], v[204:207], v[92:95]
	v_mfma_f32_16x16x32_bf16 v[88:91], v[140:143], v[204:207], v[88:91]
	v_mfma_f32_16x16x32_bf16 v[76:79], v[132:135], v[212:215], v[76:79]
	v_mfma_f32_16x16x32_bf16 v[72:75], v[140:143], v[212:215], v[72:75]
	s_setprio 0
	s_setprio 1
	v_mfma_f32_16x16x32_bf16 v[116:119], v[144:147], v[176:179], v[116:119]
	v_mfma_f32_16x16x32_bf16 v[112:115], v[168:171], v[176:179], v[112:115]
	v_mfma_f32_16x16x32_bf16 v[100:103], v[144:147], v[192:195], v[100:103]
	v_mfma_f32_16x16x32_bf16 v[96:99], v[168:171], v[192:195], v[96:99]
	v_mfma_f32_16x16x32_bf16 v[84:87], v[144:147], v[200:203], v[84:87]
	v_mfma_f32_16x16x32_bf16 v[80:83], v[168:171], v[200:203], v[80:83]
	v_mfma_f32_16x16x32_bf16 v[68:71], v[144:147], v[208:211], v[68:71]
	v_mfma_f32_16x16x32_bf16 v[64:67], v[168:171], v[208:211], v[64:67]
	v_mfma_f32_16x16x32_bf16 v[116:119], v[148:151], v[180:183], v[116:119]
	v_mfma_f32_16x16x32_bf16 v[112:115], v[172:175], v[180:183], v[112:115]
	v_mfma_f32_16x16x32_bf16 v[100:103], v[148:151], v[196:199], v[100:103]
	v_mfma_f32_16x16x32_bf16 v[96:99], v[172:175], v[196:199], v[96:99]
	v_mfma_f32_16x16x32_bf16 v[84:87], v[148:151], v[204:207], v[84:87]
	v_mfma_f32_16x16x32_bf16 v[80:83], v[172:175], v[204:207], v[80:83]
	v_mfma_f32_16x16x32_bf16 v[68:71], v[148:151], v[212:215], v[68:71]
	v_mfma_f32_16x16x32_bf16 v[64:67], v[172:175], v[212:215], v[64:67]
	s_setprio 0
	s_barrier
	s_add_i32 s36, s56, s68
	v_lshl_add_u64 v[184:185], s[46:47], 0, v[154:155]
	s_mov_b32 m0, s36
	ds_read_b128 v[176:179], v191 offset:16384
	ds_read_b128 v[180:183], v191 offset:17408
	ds_read_b128 v[192:195], v191 offset:18432
	ds_read_b128 v[196:199], v191 offset:19456
	ds_read_b128 v[200:203], v191 offset:20480
	ds_read_b128 v[204:207], v191 offset:21504
	ds_read_b128 v[208:211], v191 offset:22528
	ds_read_b128 v[212:215], v191 offset:23552
	global_load_lds_dwordx4 v[184:185], off
	s_add_i32 m0, s36, 0x2000
	s_add_u32 s36, s46, 0xb0000
	v_lshl_add_u64 v[216:217], s[46:47], 0, v[158:159]
	s_addc_u32 s37, s47, 0
	s_add_i32 s63, s57, s68
	global_load_lds_dwordx4 v[216:217], off
	v_lshl_add_u64 v[218:219], s[36:37], 0, v[154:155]
	s_mov_b32 m0, s63
	v_lshl_add_u64 v[220:221], s[48:49], 0, v[156:157]
	global_load_lds_dwordx4 v[218:219], off
	v_lshl_add_u64 v[218:219], s[36:37], 0, v[158:159]
	s_add_i32 m0, s63, 0x2000
	s_nop 0
	global_load_lds_dwordx4 v[218:219], off
	v_lshl_add_u64 v[218:219], s[48:49], 0, v[152:153]
	s_mov_b32 m0, s74
	s_nop 0
	global_load_lds_dwordx4 v[218:219], off
	s_mov_b32 m0, s41
	s_nop 0
	global_load_lds_dwordx4 v[220:221], off
	s_waitcnt vmcnt(8)
	s_cmp_lt_u32 s3, 4
	s_cbranch_scc1 .Lgls_49
	s_waitcnt lgkmcnt(0)
; #define PG8_STAGE(bufoff, gbase, voff) do { _Pragma("unroll") for (int _i = 0; _i < 2; ++_i) \
;         __builtin_amdgcn_global_load_lds((const unsigned*)((const char*)(gbase) + (voff)[_i]), (PG8_LAS unsigned*)(lds + (bufoff) + ldsw + _i * 8192), 16, 0, 0); } while (0)
; #define PG8_LDA(dst, b, h) do { _Pragma("unroll") for (int m = 0; m < 4; ++m) _Pragma("unroll") for (int k = 0; k < 2; ++k) dst[m][k] = *(const PG8_LAS bf16x8*)(lds + PG8_SA(b, h) + aoff + m * 2048 + k * 1024); } while (0)
; #define PG8_LDB(dst, b, h) do { _Pragma("unroll") for (int n = 0; n < 2; ++n) _Pragma("unroll") for (int k = 0; k < 2; ++k) dst[n][k] = *(const PG8_LAS bf16x8*)(lds + PG8_SB(b, h) + boff + n * 2048 + k * 1024); } while (0)
; #define PG8_MMA(ai, bj, At, Bt) do { __builtin_amdgcn_s_setprio(1); _Pragma("unroll") for (int m = 0; m < 4; ++m) _Pragma("unroll") for (int n = 0; n < 2; ++n) _Pragma("unroll") for (int k = 0; k < 2; ++k) \
;         acc[ai][bj][m][n] = mma16<F16>(Bt[n][k], At[m][k], acc[ai][bj][m][n]); __builtin_amdgcn_s_setprio(0); } while (0)
; #define PG8_WAIT_V(n) asm volatile("s_waitcnt vmcnt(" #n ")" ::: "memory")
; #define PG8_WAIT_L(n) asm volatile("s_waitcnt lgkmcnt(" #n ")" ::: "memory")
; #define PG8_BAR __builtin_amdgcn_s_barrier()
; #define PG8_SCHED __builtin_amdgcn_sched_barrier(0)
; template <class Epi, class Sched, bool ALIGN_EPI = false, bool SP2 = false, bool F16 = false>
; __device__ __forceinline__ void gemm_phase(PG8_LAS unsigned char* lds, const Gemm g, const Sched& S, const Epi& E, const int wid_in) {
;     ...
;             PG8_LDA(At, 0, 1); PG8_STAGE(PG8_SB(0, 0), b2, voffB); PG8_STAGE(PG8_SB(0, 1), b2 + hstep, voffB); PG8_STAGE(PG8_SA(0, 0), a2, voffA);
;             PG8_WAIT_V(8); PG8_WAIT_L(0); PG8_BAR; PG8_MMA(1, 0, At, B0); PG8_MMA(1, 1, At, B1); PG8_BAR; PG8_SCHED;
;             PG8_LDB(B0, 1, 0); PG8_LDB(B1, 1, 1); PG8_SCHED; PG8_LDA(At, 1, 0); PG8_STAGE(PG8_SA(0, 1), a2 + hstep, voffA);
;             PG8_WAIT_V(8); PG8_WAIT_L(0); PG8_BAR; PG8_MMA(0, 0, At, B0); PG8_MMA(0, 1, At, B1); PG8_BAR; PG8_SCHED;
;             PG8_LDA(At, 1, 1); PG8_STAGE(PG8_SB(1, 0), b3, voffB); PG8_STAGE(PG8_SB(1, 1), b3 + hstep, voffB); PG8_STAGE(PG8_SA(1, 0), a3, voffA);
.Lgls_49:
	s_barrier
	s_setprio 1
	s_waitcnt lgkmcnt(0)
	v_mfma_f32_16x16x32_bf16 v[60:63], v[128:131], v[176:179], v[60:63]
	v_mfma_f32_16x16x32_bf16 v[56:59], v[136:139], v[176:179], v[56:59]
	v_mfma_f32_16x16x32_bf16 v[44:47], v[128:131], v[192:195], v[44:47]
	v_mfma_f32_16x16x32_bf16 v[40:43], v[136:139], v[192:195], v[40:43]
	v_mfma_f32_16x16x32_bf16 v[28:31], v[128:131], v[200:203], v[28:31]
	v_mfma_f32_16x16x32_bf16 v[24:27], v[136:139], v[200:203], v[24:27]
	v_mfma_f32_16x16x32_bf16 v[12:15], v[128:131], v[208:211], v[12:15]
	v_mfma_f32_16x16x32_bf16 v[8:11], v[136:139], v[208:211], v[8:11]
	v_mfma_f32_16x16x32_bf16 v[60:63], v[132:135], v[180:183], v[60:63]
	v_mfma_f32_16x16x32_bf16 v[56:59], v[140:143], v[180:183], v[56:59]
	v_mfma_f32_16x16x32_bf16 v[44:47], v[132:135], v[196:199], v[44:47]
	v_mfma_f32_16x16x32_bf16 v[40:43], v[140:143], v[196:199], v[40:43]
	v_mfma_f32_16x16x32_bf16 v[28:31], v[132:135], v[204:207], v[28:31]
	v_mfma_f32_16x16x32_bf16 v[24:27], v[140:143], v[204:207], v[24:27]
	v_mfma_f32_16x16x32_bf16 v[12:15], v[132:135], v[212:215], v[12:15]
	v_mfma_f32_16x16x32_bf16 v[8:11], v[140:143], v[212:215], v[8:11]
	s_setprio 0
	s_setprio 1
	v_mfma_f32_16x16x32_bf16 v[52:55], v[144:147], v[176:179], v[52:55]
	v_mfma_f32_16x16x32_bf16 v[48:51], v[168:171], v[176:179], v[48:51]
	v_mfma_f32_16x16x32_bf16 v[36:39], v[144:147], v[192:195], v[36:39]
	v_mfma_f32_16x16x32_bf16 v[32:35], v[168:171], v[192:195], v[32:35]
	v_mfma_f32_16x16x32_bf16 v[20:23], v[144:147], v[200:203], v[20:23]
	v_mfma_f32_16x16x32_bf16 v[16:19], v[168:171], v[200:203], v[16:19]
	v_mfma_f32_16x16x32_bf16 v[4:7], v[144:147], v[208:211], v[4:7]
	v_mfma_f32_16x16x32_bf16 v[0:3], v[168:171], v[208:211], v[0:3]
	v_mfma_f32_16x16x32_bf16 v[52:55], v[148:151], v[180:183], v[52:55]
	v_mfma_f32_16x16x32_bf16 v[48:51], v[172:175], v[180:183], v[48:51]
	v_mfma_f32_16x16x32_bf16 v[36:39], v[148:151], v[196:199], v[36:39]
	v_mfma_f32_16x16x32_bf16 v[32:35], v[172:175], v[196:199], v[32:35]
	v_mfma_f32_16x16x32_bf16 v[20:23], v[148:151], v[204:207], v[20:23]
	v_mfma_f32_16x16x32_bf16 v[16:19], v[172:175], v[204:207], v[16:19]
	v_mfma_f32_16x16x32_bf16 v[4:7], v[148:151], v[212:215], v[4:7]
	v_mfma_f32_16x16x32_bf16 v[0:3], v[172:175], v[212:215], v[0:3]
	s_setprio 0
	s_barrier
	s_add_i32 s63, 0, 0x18000
	s_add_i32 s64, 0, 0x1c000
	v_add_u32_e32 v140, s63, v188
	v_add_u32_e32 v172, s64, v188
	ds_read_b128 v[128:131], v140
	ds_read_b128 v[132:135], v140 offset:1024
	ds_read_b128 v[136:139], v140 offset:2048
	ds_read_b128 v[140:143], v140 offset:3072
	ds_read_b128 v[144:147], v172
	ds_read_b128 v[148:151], v172 offset:1024
	ds_read_b128 v[168:171], v172 offset:2048
	ds_read_b128 v[172:175], v172 offset:3072
	s_add_u32 s36, s48, 0xb0000
	s_addc_u32 s37, s49, 0
	s_mov_b32 m0, s50
	v_lshl_add_u64 v[222:223], s[36:37], 0, v[152:153]
	ds_read_b128 v[176:179], v191 offset:32768
	ds_read_b128 v[180:183], v191 offset:33792
	ds_read_b128 v[192:195], v191 offset:34816
	ds_read_b128 v[196:199], v191 offset:35840
	ds_read_b128 v[200:203], v191 offset:36864
	ds_read_b128 v[204:207], v191 offset:37888
	ds_read_b128 v[208:211], v191 offset:38912
	ds_read_b128 v[212:215], v191 offset:39936
	global_load_lds_dwordx4 v[222:223], off
	v_lshl_add_u64 v[222:223], s[36:37], 0, v[156:157]
	s_mov_b32 m0, s51
	s_nop 0
	global_load_lds_dwordx4 v[222:223], off
	s_waitcnt vmcnt(8)
	s_cmp_lt_u32 s3, 4
	s_cbranch_scc1 .Lgls_50
	s_waitcnt lgkmcnt(0)
; #define PG8_STAGE(bufoff, gbase, voff) do { _Pragma("unroll") for (int _i = 0; _i < 2; ++_i) \
;         __builtin_amdgcn_global_load_lds((const unsigned*)((const char*)(gbase) + (voff)[_i]), (PG8_LAS unsigned*)(lds + (bufoff) + ldsw + _i * 8192), 16, 0, 0); } while (0)
; #define PG8_LDA(dst, b, h) do { _Pragma("unroll") for (int m = 0; m < 4; ++m) _Pragma("unroll") for (int k = 0; k < 2; ++k) dst[m][k] = *(const PG8_LAS bf16x8*)(lds + PG8_SA(b, h) + aoff + m * 2048 + k * 1024); } while (0)
; #define PG8_WAIT_V(n) asm volatile("s_waitcnt vmcnt(" #n ")" ::: "memory")
; #define PG8_WAIT_L(n) asm volatile("s_waitcnt lgkmcnt(" #n ")" ::: "memory")
; template <class Epi, class Sched, bool ALIGN_EPI = false, bool SP2 = false, bool F16 = false>
; __device__ __forceinline__ void gemm_phase(PG8_LAS unsigned char* lds, const Gemm g, const Sched& S, const Epi& E, const int wid_in) {
;     ...
;         for (int t = 0; t < nt; t += 2) {
;             const bool last = (t == nt - 2);
;             const char* a1 = cA + (size_t)(t + 1) * kstep;
;             const char* a2 = last ? nA : cA + (size_t)(t + 2) * kstep; const char* b2 = last ? nB : cB + (size_t)(t + 2) * kstep;
;             const char* a3 = a2 + kstep; const char* b3 = b2 + kstep;
;             if (last && has_next) S.a_ready(nxt);
;             if constexpr (SP2) {
;             PG8_LDB(B0, 0, 0); PG8_LDB(B1, 0, 1); PG8_SCHED; PG8_LDA(At, 0, 0); PG8_STAGE(PG8_SA(1, 1), a1 + hstep, voffA);
;             PG8_WAIT_V(8); PG8_WAIT_L(0); PG8_BAR; PG8_MMA(0, 0, At, B0); PG8_MMA(0, 1, At, B1); PG8_BAR; PG8_SCHED;
;             PG8_LDA(At, 0, 1); PG8_STAGE(PG8_SB(0, 0), b2, voffB); PG8_STAGE(PG8_SB(0, 1), b2 + hstep, voffB); PG8_STAGE(PG8_SA(0, 0), a2, voffA);
;             PG8_WAIT_V(8); PG8_WAIT_L(0); PG8_BAR; PG8_MMA(1, 0, At, B0); PG8_MMA(1, 1, At, B1); PG8_BAR; PG8_SCHED;
;             PG8_LDB(B0, 1, 0); PG8_LDB(B1, 1, 1); PG8_SCHED; PG8_LDA(At, 1, 0); PG8_STAGE(PG8_SA(0, 1), a2 + hstep, voffA);
;             PG8_WAIT_V(8); PG8_WAIT_L(0); PG8_BAR; PG8_MMA(0, 0, At, B0); PG8_MMA(0, 1, At, B1); PG8_BAR; PG8_SCHED;
;             PG8_LDA(At, 1, 1); PG8_STAGE(PG8_SB(1, 0), b3, voffB); PG8_STAGE(PG8_SB(1, 1), b3 + hstep, voffB); PG8_STAGE(PG8_SA(1, 0), a3, voffA);
;             PG8_WAIT_V(8); PG8_WAIT_L(0); PG8_BAR; PG8_MMA(1, 0, At, B0); PG8_MMA(1, 1, At, B1); PG8_BAR; PG8_SCHED;
.Lgls_50:
	s_barrier
	s_setprio 1
	s_waitcnt lgkmcnt(0)
	v_mfma_f32_16x16x32_bf16 v[124:127], v[128:131], v[176:179], v[124:127]
	v_mfma_f32_16x16x32_bf16 v[120:123], v[136:139], v[176:179], v[120:123]
	v_mfma_f32_16x16x32_bf16 v[108:111], v[128:131], v[192:195], v[108:111]
	v_mfma_f32_16x16x32_bf16 v[104:107], v[136:139], v[192:195], v[104:107]
	v_mfma_f32_16x16x32_bf16 v[92:95], v[128:131], v[200:203], v[92:95]
	v_mfma_f32_16x16x32_bf16 v[88:91], v[136:139], v[200:203], v[88:91]
	v_mfma_f32_16x16x32_bf16 v[76:79], v[128:131], v[208:211], v[76:79]
	v_mfma_f32_16x16x32_bf16 v[72:75], v[136:139], v[208:211], v[72:75]
	v_mfma_f32_16x16x32_bf16 v[124:127], v[132:135], v[180:183], v[124:127]
	v_mfma_f32_16x16x32_bf16 v[120:123], v[140:143], v[180:183], v[120:123]
	v_mfma_f32_16x16x32_bf16 v[108:111], v[132:135], v[196:199], v[108:111]
	v_mfma_f32_16x16x32_bf16 v[104:107], v[140:143], v[196:199], v[104:107]
	v_mfma_f32_16x16x32_bf16 v[92:95], v[132:135], v[204:207], v[92:95]
	v_mfma_f32_16x16x32_bf16 v[88:91], v[140:143], v[204:207], v[88:91]
	v_mfma_f32_16x16x32_bf16 v[76:79], v[132:135], v[212:215], v[76:79]
	v_mfma_f32_16x16x32_bf16 v[72:75], v[140:143], v[212:215], v[72:75]
	s_setprio 0
	s_setprio 1
	v_mfma_f32_16x16x32_bf16 v[116:119], v[144:147], v[176:179], v[116:119]
	v_mfma_f32_16x16x32_bf16 v[112:115], v[168:171], v[176:179], v[112:115]
	v_mfma_f32_16x16x32_bf16 v[100:103], v[144:147], v[192:195], v[100:103]
	v_mfma_f32_16x16x32_bf16 v[96:99], v[168:171], v[192:195], v[96:99]
	v_mfma_f32_16x16x32_bf16 v[84:87], v[144:147], v[200:203], v[84:87]
	v_mfma_f32_16x16x32_bf16 v[80:83], v[168:171], v[200:203], v[80:83]
	v_mfma_f32_16x16x32_bf16 v[68:71], v[144:147], v[208:211], v[68:71]
	v_mfma_f32_16x16x32_bf16 v[64:67], v[168:171], v[208:211], v[64:67]
	v_mfma_f32_16x16x32_bf16 v[116:119], v[148:151], v[180:183], v[116:119]
	v_mfma_f32_16x16x32_bf16 v[112:115], v[172:175], v[180:183], v[112:115]
	v_mfma_f32_16x16x32_bf16 v[100:103], v[148:151], v[196:199], v[100:103]
	v_mfma_f32_16x16x32_bf16 v[96:99], v[172:175], v[196:199], v[96:99]
	v_mfma_f32_16x16x32_bf16 v[84:87], v[148:151], v[204:207], v[84:87]
	v_mfma_f32_16x16x32_bf16 v[80:83], v[172:175], v[204:207], v[80:83]
	v_mfma_f32_16x16x32_bf16 v[68:71], v[148:151], v[212:215], v[68:71]
	v_mfma_f32_16x16x32_bf16 v[64:67], v[172:175], v[212:215], v[64:67]
	s_setprio 0
	s_barrier
	s_add_i32 s36, s63, s68
	v_lshl_add_u64 v[184:185], v[184:185], 0, s[30:31]
	s_mov_b32 m0, s36
	ds_read_b128 v[176:179], v191 offset:49152
	ds_read_b128 v[180:183], v191 offset:50176
	ds_read_b128 v[192:195], v191 offset:51200
	ds_read_b128 v[196:199], v191 offset:52224
	ds_read_b128 v[200:203], v191 offset:53248
	ds_read_b128 v[204:207], v191 offset:54272
	ds_read_b128 v[208:211], v191 offset:55296
	ds_read_b128 v[212:215], v191 offset:56320
	global_load_lds_dwordx4 v[184:185], off
	s_add_i32 m0, s36, 0x2000
	s_add_u32 s36, s46, 0xb0080
	v_lshl_add_u64 v[184:185], v[216:217], 0, s[30:31]
	s_addc_u32 s37, s47, 0
	s_add_i32 s46, s64, s68
	global_load_lds_dwordx4 v[184:185], off
	v_lshl_add_u64 v[184:185], s[36:37], 0, v[154:155]
	s_mov_b32 m0, s46
	s_nop 0
	global_load_lds_dwordx4 v[184:185], off
	v_lshl_add_u64 v[184:185], s[36:37], 0, v[158:159]
	s_add_i32 m0, s46, 0x2000
	s_nop 0
	global_load_lds_dwordx4 v[184:185], off
	v_lshl_add_u64 v[184:185], v[218:219], 0, s[30:31]
	s_mov_b32 m0, s75
	s_nop 0
	global_load_lds_dwordx4 v[184:185], off
	v_lshl_add_u64 v[184:185], v[220:221], 0, s[30:31]
	s_mov_b32 m0, s52
	s_nop 0
	global_load_lds_dwordx4 v[184:185], off
	s_waitcnt vmcnt(8)
	s_cmp_lt_u32 s3, 4
	s_cbranch_scc1 .Lgls_51
	s_waitcnt lgkmcnt(0)
.Lgls_51:
	s_barrier
	s_setprio 1
	s_waitcnt lgkmcnt(0)
	v_mfma_f32_16x16x32_bf16 v[60:63], v[128:131], v[176:179], v[60:63]
	v_mfma_f32_16x16x32_bf16 v[56:59], v[136:139], v[176:179], v[56:59]
	v_mfma_f32_16x16x32_bf16 v[44:47], v[128:131], v[192:195], v[44:47]
	v_mfma_f32_16x16x32_bf16 v[40:43], v[136:139], v[192:195], v[40:43]
	v_mfma_f32_16x16x32_bf16 v[28:31], v[128:131], v[200:203], v[28:31]
	v_mfma_f32_16x16x32_bf16 v[24:27], v[136:139], v[200:203], v[24:27]
	v_mfma_f32_16x16x32_bf16 v[12:15], v[128:131], v[208:211], v[12:15]
	v_mfma_f32_16x16x32_bf16 v[8:11], v[136:139], v[208:211], v[8:11]
	v_mfma_f32_16x16x32_bf16 v[60:63], v[132:135], v[180:183], v[60:63]
	v_mfma_f32_16x16x32_bf16 v[56:59], v[140:143], v[180:183], v[56:59]
	v_mfma_f32_16x16x32_bf16 v[44:47], v[132:135], v[196:199], v[44:47]
	v_mfma_f32_16x16x32_bf16 v[40:43], v[140:143], v[196:199], v[40:43]
	v_mfma_f32_16x16x32_bf16 v[28:31], v[132:135], v[204:207], v[28:31]
	v_mfma_f32_16x16x32_bf16 v[24:27], v[140:143], v[204:207], v[24:27]
	v_mfma_f32_16x16x32_bf16 v[12:15], v[132:135], v[212:215], v[12:15]
	v_mfma_f32_16x16x32_bf16 v[8:11], v[140:143], v[212:215], v[8:11]
	s_setprio 0
	s_setprio 1
	v_mfma_f32_16x16x32_bf16 v[52:55], v[144:147], v[176:179], v[52:55]
	v_mfma_f32_16x16x32_bf16 v[48:51], v[168:171], v[176:179], v[48:51]
	v_mfma_f32_16x16x32_bf16 v[36:39], v[144:147], v[192:195], v[36:39]
	v_mfma_f32_16x16x32_bf16 v[32:35], v[168:171], v[192:195], v[32:35]
	v_mfma_f32_16x16x32_bf16 v[20:23], v[144:147], v[200:203], v[20:23]
	v_mfma_f32_16x16x32_bf16 v[16:19], v[168:171], v[200:203], v[16:19]
	v_mfma_f32_16x16x32_bf16 v[4:7], v[144:147], v[208:211], v[4:7]
	v_mfma_f32_16x16x32_bf16 v[0:3], v[168:171], v[208:211], v[0:3]
	v_mfma_f32_16x16x32_bf16 v[52:55], v[148:151], v[180:183], v[52:55]
	v_mfma_f32_16x16x32_bf16 v[48:51], v[172:175], v[180:183], v[48:51]
	v_mfma_f32_16x16x32_bf16 v[36:39], v[148:151], v[196:199], v[36:39]
	v_mfma_f32_16x16x32_bf16 v[32:35], v[172:175], v[196:199], v[32:35]
	v_mfma_f32_16x16x32_bf16 v[20:23], v[148:151], v[204:207], v[20:23]
	v_mfma_f32_16x16x32_bf16 v[16:19], v[172:175], v[204:207], v[16:19]
	v_mfma_f32_16x16x32_bf16 v[4:7], v[148:151], v[212:215], v[4:7]
	v_mfma_f32_16x16x32_bf16 v[0:3], v[172:175], v[212:215], v[0:3]
	s_setprio 0
	s_barrier
	s_add_i32 s62, s62, 2
	s_add_u32 s43, s43, 0x100
	s_addc_u32 s61, s61, 0
	s_cmp_gt_u32 s62, 41
	s_mov_b64 s[36:37], s[44:45]
	s_cbranch_scc0 .LBB0_1373
	s_and_b64 vcc, exec, s[16:17]
	s_cbranch_vccz .LBB0_1376
	s_barrier

; #define PG8_STAGE(bufoff, gbase, voff) do { _Pragma("unroll") for (int _i = 0; _i < 2; ++_i) \
;         __builtin_amdgcn_global_load_lds((const unsigned*)((const char*)(gbase) + (voff)[_i]), (PG8_LAS unsigned*)(lds + (bufoff) + ldsw + _i * 8192), 16, 0, 0); } while (0)
; #define PG8_LDA(dst, b, h) do { _Pragma("unroll") for (int m = 0; m < 4; ++m) _Pragma("unroll") for (int k = 0; k < 2; ++k) dst[m][k] = *(const PG8_LAS bf16x8*)(lds + PG8_SA(b, h) + aoff + m * 2048 + k * 1024); } while (0)
; #define PG8_LDB(dst, b, h) do { _Pragma("unroll") for (int n = 0; n < 2; ++n) _Pragma("unroll") for (int k = 0; k < 2; ++k) dst[n][k] = *(const PG8_LAS bf16x8*)(lds + PG8_SB(b, h) + boff + n * 2048 + k * 1024); } while (0)
; #define PG8_MMA(ai, bj, At, Bt) do { __builtin_amdgcn_s_setprio(1); _Pragma("unroll") for (int m = 0; m < 4; ++m) _Pragma("unroll") for (int n = 0; n < 2; ++n) _Pragma("unroll") for (int k = 0; k < 2; ++k) \
;         acc[ai][bj][m][n] = mma16<F16>(Bt[n][k], At[m][k], acc[ai][bj][m][n]); __builtin_amdgcn_s_setprio(0); } while (0)
; #define PG8_WAIT_V(n) asm volatile("s_waitcnt vmcnt(" #n ")" ::: "memory")
; #define PG8_WAIT_L(n) asm volatile("s_waitcnt lgkmcnt(" #n ")" ::: "memory")
; template <class Epi, class Sched, bool ALIGN_EPI = false, bool SP2 = false, bool F16 = false>
; __device__ __forceinline__ void gemm_phase(PG8_LAS unsigned char* lds, const Gemm g, const Sched& S, const Epi& E, const int wid_in) {
;     ...
;             const bool last = (t == nt - 2);
;             const char* a1 = cA + (size_t)(t + 1) * kstep;
;             const char* a2 = last ? nA : cA + (size_t)(t + 2) * kstep; const char* b2 = last ? nB : cB + (size_t)(t + 2) * kstep;
;             const char* a3 = a2 + kstep; const char* b3 = b2 + kstep;
;             if (last && has_next) S.a_ready(nxt);
;             if constexpr (SP2) {
;             PG8_LDB(B0, 0, 0); PG8_LDB(B1, 0, 1); PG8_SCHED; PG8_LDA(At, 0, 0); PG8_STAGE(PG8_SA(1, 1), a1 + hstep, voffA);
;             PG8_WAIT_V(8); PG8_WAIT_L(0); PG8_BAR; PG8_MMA(0, 0, At, B0); PG8_MMA(0, 1, At, B1); PG8_BAR; PG8_SCHED;
;             PG8_LDA(At, 0, 1); PG8_STAGE(PG8_SB(0, 0), b2, voffB); PG8_STAGE(PG8_SB(0, 1), b2 + hstep, voffB); PG8_STAGE(PG8_SA(0, 0), a2, voffA);
;             PG8_WAIT_V(8); PG8_WAIT_L(0); PG8_BAR; PG8_MMA(1, 0, At, B0); PG8_MMA(1, 1, At, B1); PG8_BAR; PG8_SCHED;
.LBB0_1469:
	ds_read_b128 v[112:115], v235
	ds_read_b128 v[116:119], v235 offset:1024
	ds_read_b128 v[128:131], v235 offset:2048
	ds_read_b128 v[132:135], v235 offset:3072
	ds_read_b128 v[144:147], v236
	ds_read_b128 v[148:151], v236 offset:1024
	ds_read_b128 v[152:155], v236 offset:2048
	ds_read_b128 v[156:159], v236 offset:3072
	s_add_u32 s45, s52, 0xfffc0080
	s_addc_u32 s51, s53, -1
	s_cmp_eq_u32 s43, 12
	s_cselect_b32 s57, s14, s51
	s_cselect_b32 s56, s15, s45
	s_cselect_b32 s55, s37, s42
	s_cselect_b32 s54, s40, s41
	v_lshl_add_u64 v[192:193], s[52:53], 0, v[204:205]
	s_add_i32 m0, s74, 0xc000
	ds_read_b128 v[160:163], v237
	ds_read_b128 v[164:167], v237 offset:1024
	ds_read_b128 v[168:171], v237 offset:2048
	ds_read_b128 v[172:175], v237 offset:3072
	ds_read_b128 v[176:179], v237 offset:4096
	ds_read_b128 v[180:183], v237 offset:5120
	ds_read_b128 v[184:187], v237 offset:6144
	ds_read_b128 v[188:191], v237 offset:7168
	global_load_lds_dwordx4 v[192:193], off
	v_lshl_add_u64 v[192:193], s[52:53], 0, v[206:207]
	s_add_i32 m0, s74, 0xe000
	s_nop 0
	global_load_lds_dwordx4 v[192:193], off
	s_waitcnt vmcnt(8)
	s_cmp_lt_u32 s3, 4
	s_cbranch_scc1 .Lgls_52
	s_waitcnt lgkmcnt(0)
.Lgls_52:
	s_barrier
	s_setprio 1
	s_waitcnt lgkmcnt(0)
	v_mfma_f32_16x16x32_f16 v[140:143], v[112:115], v[160:163], v[140:143]
	v_mfma_f32_16x16x32_f16 v[136:139], v[128:131], v[160:163], v[136:139]
	v_mfma_f32_16x16x32_f16 v[108:111], v[112:115], v[168:171], v[108:111]
	v_mfma_f32_16x16x32_f16 v[104:107], v[128:131], v[168:171], v[104:107]
	v_mfma_f32_16x16x32_f16 v[92:95], v[112:115], v[176:179], v[92:95]
	v_mfma_f32_16x16x32_f16 v[88:91], v[128:131], v[176:179], v[88:91]
	v_mfma_f32_16x16x32_f16 v[76:79], v[112:115], v[184:187], v[76:79]
	v_mfma_f32_16x16x32_f16 v[72:75], v[128:131], v[184:187], v[72:75]
	v_mfma_f32_16x16x32_f16 v[140:143], v[116:119], v[164:167], v[140:143]
	v_mfma_f32_16x16x32_f16 v[136:139], v[132:135], v[164:167], v[136:139]
	v_mfma_f32_16x16x32_f16 v[108:111], v[116:119], v[172:175], v[108:111]
	v_mfma_f32_16x16x32_f16 v[104:107], v[132:135], v[172:175], v[104:107]
	v_mfma_f32_16x16x32_f16 v[92:95], v[116:119], v[180:183], v[92:95]
	v_mfma_f32_16x16x32_f16 v[88:91], v[132:135], v[180:183], v[88:91]
	v_mfma_f32_16x16x32_f16 v[76:79], v[116:119], v[188:191], v[76:79]
	v_mfma_f32_16x16x32_f16 v[72:75], v[132:135], v[188:191], v[72:75]
	s_setprio 0
	s_setprio 1
	v_mfma_f32_16x16x32_f16 v[124:127], v[144:147], v[160:163], v[124:127]
	v_mfma_f32_16x16x32_f16 v[120:123], v[152:155], v[160:163], v[120:123]
	v_mfma_f32_16x16x32_f16 v[100:103], v[144:147], v[168:171], v[100:103]
	v_mfma_f32_16x16x32_f16 v[96:99], v[152:155], v[168:171], v[96:99]
	v_mfma_f32_16x16x32_f16 v[84:87], v[144:147], v[176:179], v[84:87]
	v_mfma_f32_16x16x32_f16 v[80:83], v[152:155], v[176:179], v[80:83]
	v_mfma_f32_16x16x32_f16 v[68:71], v[144:147], v[184:187], v[68:71]
	v_mfma_f32_16x16x32_f16 v[64:67], v[152:155], v[184:187], v[64:67]
	v_mfma_f32_16x16x32_f16 v[124:127], v[148:151], v[164:167], v[124:127]
	v_mfma_f32_16x16x32_f16 v[120:123], v[156:159], v[164:167], v[120:123]
	v_mfma_f32_16x16x32_f16 v[100:103], v[148:151], v[172:175], v[100:103]
	v_mfma_f32_16x16x32_f16 v[96:99], v[156:159], v[172:175], v[96:99]
	v_mfma_f32_16x16x32_f16 v[84:87], v[148:151], v[180:183], v[84:87]
	v_mfma_f32_16x16x32_f16 v[80:83], v[156:159], v[180:183], v[80:83]
	v_mfma_f32_16x16x32_f16 v[68:71], v[148:151], v[188:191], v[68:71]
	v_mfma_f32_16x16x32_f16 v[64:67], v[156:159], v[188:191], v[64:67]
	s_setprio 0
	s_barrier
	s_add_i32 s45, s66, s68
	v_lshl_add_u64 v[192:193], s[54:55], 0, v[198:199]
	s_mov_b32 m0, s45
	ds_read_b128 v[160:163], v237 offset:16384
	ds_read_b128 v[164:167], v237 offset:17408
	ds_read_b128 v[168:171], v237 offset:18432
	ds_read_b128 v[172:175], v237 offset:19456
	ds_read_b128 v[176:179], v237 offset:20480
	ds_read_b128 v[180:183], v237 offset:21504
	ds_read_b128 v[184:187], v237 offset:22528
	ds_read_b128 v[188:191], v237 offset:23552
	global_load_lds_dwordx4 v[192:193], off
	s_add_i32 m0, s45, 0x2000
	s_add_u32 s94, s54, 0x40000
	v_lshl_add_u64 v[194:195], s[54:55], 0, v[202:203]
	s_addc_u32 s95, s55, 0
	s_add_i32 s45, s67, s68
	global_load_lds_dwordx4 v[194:195], off
	v_lshl_add_u64 v[212:213], s[94:95], 0, v[198:199]
	s_mov_b32 m0, s45
	v_lshl_add_u64 v[214:215], s[56:57], 0, v[200:201]
	global_load_lds_dwordx4 v[212:213], off
	v_lshl_add_u64 v[212:213], s[94:95], 0, v[202:203]
	s_add_i32 m0, s45, 0x2000
	s_nop 0
	global_load_lds_dwordx4 v[212:213], off
	v_lshl_add_u64 v[212:213], s[56:57], 0, v[196:197]
	s_mov_b32 m0, s74
	s_nop 0
	global_load_lds_dwordx4 v[212:213], off
	s_mov_b32 m0, s59
	s_nop 0
	global_load_lds_dwordx4 v[214:215], off
	s_waitcnt vmcnt(8)
	s_cmp_lt_u32 s3, 4
	s_cbranch_scc1 .Lgls_53
	s_waitcnt lgkmcnt(0)
; #define PG8_STAGE(bufoff, gbase, voff) do { _Pragma("unroll") for (int _i = 0; _i < 2; ++_i) \
;         __builtin_amdgcn_global_load_lds((const unsigned*)((const char*)(gbase) + (voff)[_i]), (PG8_LAS unsigned*)(lds + (bufoff) + ldsw + _i * 8192), 16, 0, 0); } while (0)
; #define PG8_LDA(dst, b, h) do { _Pragma("unroll") for (int m = 0; m < 4; ++m) _Pragma("unroll") for (int k = 0; k < 2; ++k) dst[m][k] = *(const PG8_LAS bf16x8*)(lds + PG8_SA(b, h) + aoff + m * 2048 + k * 1024); } while (0)
; #define PG8_LDB(dst, b, h) do { _Pragma("unroll") for (int n = 0; n < 2; ++n) _Pragma("unroll") for (int k = 0; k < 2; ++k) dst[n][k] = *(const PG8_LAS bf16x8*)(lds + PG8_SB(b, h) + boff + n * 2048 + k * 1024); } while (0)
; #define PG8_MMA(ai, bj, At, Bt) do { __builtin_amdgcn_s_setprio(1); _Pragma("unroll") for (int m = 0; m < 4; ++m) _Pragma("unroll") for (int n = 0; n < 2; ++n) _Pragma("unroll") for (int k = 0; k < 2; ++k) \
;         acc[ai][bj][m][n] = mma16<F16>(Bt[n][k], At[m][k], acc[ai][bj][m][n]); __builtin_amdgcn_s_setprio(0); } while (0)
; #define PG8_WAIT_V(n) asm volatile("s_waitcnt vmcnt(" #n ")" ::: "memory")
; #define PG8_WAIT_L(n) asm volatile("s_waitcnt lgkmcnt(" #n ")" ::: "memory")
; #define PG8_BAR __builtin_amdgcn_s_barrier()
; #define PG8_SCHED __builtin_amdgcn_sched_barrier(0)
; template <class Epi, class Sched, bool ALIGN_EPI = false, bool SP2 = false, bool F16 = false>
; __device__ __forceinline__ void gemm_phase(PG8_LAS unsigned char* lds, const Gemm g, const Sched& S, const Epi& E, const int wid_in) {
;     ...
;             PG8_LDA(At, 0, 1); PG8_STAGE(PG8_SB(0, 0), b2, voffB); PG8_STAGE(PG8_SB(0, 1), b2 + hstep, voffB); PG8_STAGE(PG8_SA(0, 0), a2, voffA);
;             PG8_WAIT_V(8); PG8_WAIT_L(0); PG8_BAR; PG8_MMA(1, 0, At, B0); PG8_MMA(1, 1, At, B1); PG8_BAR; PG8_SCHED;
;             PG8_LDB(B0, 1, 0); PG8_LDB(B1, 1, 1); PG8_SCHED; PG8_LDA(At, 1, 0); PG8_STAGE(PG8_SA(0, 1), a2 + hstep, voffA);
;             PG8_WAIT_V(8); PG8_WAIT_L(0); PG8_BAR; PG8_MMA(0, 0, At, B0); PG8_MMA(0, 1, At, B1); PG8_BAR; PG8_SCHED;
;             PG8_LDA(At, 1, 1); PG8_STAGE(PG8_SB(1, 0), b3, voffB); PG8_STAGE(PG8_SB(1, 1), b3 + hstep, voffB); PG8_STAGE(PG8_SA(1, 0), a3, voffA);
.Lgls_53:
	s_barrier
	s_setprio 1
	s_waitcnt lgkmcnt(0)
	v_mfma_f32_16x16x32_f16 v[60:63], v[112:115], v[160:163], v[60:63]
	v_mfma_f32_16x16x32_f16 v[56:59], v[128:131], v[160:163], v[56:59]
	v_mfma_f32_16x16x32_f16 v[44:47], v[112:115], v[168:171], v[44:47]
	v_mfma_f32_16x16x32_f16 v[40:43], v[128:131], v[168:171], v[40:43]
	v_mfma_f32_16x16x32_f16 v[28:31], v[112:115], v[176:179], v[28:31]
	v_mfma_f32_16x16x32_f16 v[24:27], v[128:131], v[176:179], v[24:27]
	v_mfma_f32_16x16x32_f16 v[12:15], v[112:115], v[184:187], v[12:15]
	v_mfma_f32_16x16x32_f16 v[8:11], v[128:131], v[184:187], v[8:11]
	v_mfma_f32_16x16x32_f16 v[60:63], v[116:119], v[164:167], v[60:63]
	v_mfma_f32_16x16x32_f16 v[56:59], v[132:135], v[164:167], v[56:59]
	v_mfma_f32_16x16x32_f16 v[44:47], v[116:119], v[172:175], v[44:47]
	v_mfma_f32_16x16x32_f16 v[40:43], v[132:135], v[172:175], v[40:43]
	v_mfma_f32_16x16x32_f16 v[28:31], v[116:119], v[180:183], v[28:31]
	v_mfma_f32_16x16x32_f16 v[24:27], v[132:135], v[180:183], v[24:27]
	v_mfma_f32_16x16x32_f16 v[12:15], v[116:119], v[188:191], v[12:15]
	v_mfma_f32_16x16x32_f16 v[8:11], v[132:135], v[188:191], v[8:11]
	s_setprio 0
	s_setprio 1
	v_mfma_f32_16x16x32_f16 v[52:55], v[144:147], v[160:163], v[52:55]
	v_mfma_f32_16x16x32_f16 v[48:51], v[152:155], v[160:163], v[48:51]
	v_mfma_f32_16x16x32_f16 v[36:39], v[144:147], v[168:171], v[36:39]
	v_mfma_f32_16x16x32_f16 v[32:35], v[152:155], v[168:171], v[32:35]
	v_mfma_f32_16x16x32_f16 v[20:23], v[144:147], v[176:179], v[20:23]
	v_mfma_f32_16x16x32_f16 v[16:19], v[152:155], v[176:179], v[16:19]
	v_mfma_f32_16x16x32_f16 v[4:7], v[144:147], v[184:187], v[4:7]
	v_mfma_f32_16x16x32_f16 v[0:3], v[152:155], v[184:187], v[0:3]
	v_mfma_f32_16x16x32_f16 v[52:55], v[148:151], v[164:167], v[52:55]
	v_mfma_f32_16x16x32_f16 v[48:51], v[156:159], v[164:167], v[48:51]
	v_mfma_f32_16x16x32_f16 v[36:39], v[148:151], v[172:175], v[36:39]
	v_mfma_f32_16x16x32_f16 v[32:35], v[156:159], v[172:175], v[32:35]
	v_mfma_f32_16x16x32_f16 v[20:23], v[148:151], v[180:183], v[20:23]
	v_mfma_f32_16x16x32_f16 v[16:19], v[156:159], v[180:183], v[16:19]
	v_mfma_f32_16x16x32_f16 v[4:7], v[148:151], v[188:191], v[4:7]
	v_mfma_f32_16x16x32_f16 v[0:3], v[156:159], v[188:191], v[0:3]
	s_setprio 0
	s_barrier
	s_add_i32 s45, 0, 0x18000
	s_add_i32 s51, 0, 0x1c000
	v_add_u32_e32 v132, s45, v234
	v_add_u32_e32 v156, s51, v234
	ds_read_b128 v[112:115], v132
	ds_read_b128 v[116:119], v132 offset:1024
	ds_read_b128 v[128:131], v132 offset:2048
	ds_read_b128 v[132:135], v132 offset:3072
	ds_read_b128 v[144:147], v156
	ds_read_b128 v[148:151], v156 offset:1024
	ds_read_b128 v[152:155], v156 offset:2048
	ds_read_b128 v[156:159], v156 offset:3072
	s_add_u32 s56, s56, 0x40000
	s_addc_u32 s57, s57, 0
	s_mov_b32 m0, s60
	v_lshl_add_u64 v[216:217], s[56:57], 0, v[196:197]
	ds_read_b128 v[160:163], v237 offset:32768
	ds_read_b128 v[164:167], v237 offset:33792
	ds_read_b128 v[168:171], v237 offset:34816
	ds_read_b128 v[172:175], v237 offset:35840
	ds_read_b128 v[176:179], v237 offset:36864
	ds_read_b128 v[180:183], v237 offset:37888
	ds_read_b128 v[184:187], v237 offset:38912
	ds_read_b128 v[188:191], v237 offset:39936
	global_load_lds_dwordx4 v[216:217], off
	v_lshl_add_u64 v[216:217], s[56:57], 0, v[200:201]
	s_mov_b32 m0, s61
	s_nop 0
	global_load_lds_dwordx4 v[216:217], off
	s_waitcnt vmcnt(8)
	s_cmp_lt_u32 s3, 4
	s_cbranch_scc1 .Lgls_54
	s_waitcnt lgkmcnt(0)
; #define PG8_STAGE(bufoff, gbase, voff) do { _Pragma("unroll") for (int _i = 0; _i < 2; ++_i) \
;         __builtin_amdgcn_global_load_lds((const unsigned*)((const char*)(gbase) + (voff)[_i]), (PG8_LAS unsigned*)(lds + (bufoff) + ldsw + _i * 8192), 16, 0, 0); } while (0)
; #define PG8_LDA(dst, b, h) do { _Pragma("unroll") for (int m = 0; m < 4; ++m) _Pragma("unroll") for (int k = 0; k < 2; ++k) dst[m][k] = *(const PG8_LAS bf16x8*)(lds + PG8_SA(b, h) + aoff + m * 2048 + k * 1024); } while (0)
; #define PG8_MMA(ai, bj, At, Bt) do { __builtin_amdgcn_s_setprio(1); _Pragma("unroll") for (int m = 0; m < 4; ++m) _Pragma("unroll") for (int n = 0; n < 2; ++n) _Pragma("unroll") for (int k = 0; k < 2; ++k) \
;         acc[ai][bj][m][n] = mma16<F16>(Bt[n][k], At[m][k], acc[ai][bj][m][n]); __builtin_amdgcn_s_setprio(0); } while (0)
; #define PG8_WAIT_V(n) asm volatile("s_waitcnt vmcnt(" #n ")" ::: "memory")
; #define PG8_WAIT_L(n) asm volatile("s_waitcnt lgkmcnt(" #n ")" ::: "memory")
; #define PG8_BAR __builtin_amdgcn_s_barrier()
; #define PG8_SCHED __builtin_amdgcn_sched_barrier(0)
; template <class Epi, class Sched, bool ALIGN_EPI = false, bool SP2 = false, bool F16 = false>
; __device__ __forceinline__ void gemm_phase(PG8_LAS unsigned char* lds, const Gemm g, const Sched& S, const Epi& E, const int wid_in) {
;     ...
;         for (int t = 0; t < nt; t += 2) {
;     ...
;             PG8_LDA(At, 1, 1); PG8_STAGE(PG8_SB(1, 0), b3, voffB); PG8_STAGE(PG8_SB(1, 1), b3 + hstep, voffB); PG8_STAGE(PG8_SA(1, 0), a3, voffA);
;             PG8_WAIT_V(8); PG8_WAIT_L(0); PG8_BAR; PG8_MMA(1, 0, At, B0); PG8_MMA(1, 1, At, B1); PG8_BAR; PG8_SCHED;
.Lgls_54:
	s_barrier
	s_setprio 1
	s_waitcnt lgkmcnt(0)
	v_mfma_f32_16x16x32_f16 v[140:143], v[112:115], v[160:163], v[140:143]
	v_mfma_f32_16x16x32_f16 v[136:139], v[128:131], v[160:163], v[136:139]
	v_mfma_f32_16x16x32_f16 v[108:111], v[112:115], v[168:171], v[108:111]
	v_mfma_f32_16x16x32_f16 v[104:107], v[128:131], v[168:171], v[104:107]
	v_mfma_f32_16x16x32_f16 v[92:95], v[112:115], v[176:179], v[92:95]
	v_mfma_f32_16x16x32_f16 v[88:91], v[128:131], v[176:179], v[88:91]
	v_mfma_f32_16x16x32_f16 v[76:79], v[112:115], v[184:187], v[76:79]
	v_mfma_f32_16x16x32_f16 v[72:75], v[128:131], v[184:187], v[72:75]
	v_mfma_f32_16x16x32_f16 v[140:143], v[116:119], v[164:167], v[140:143]
	v_mfma_f32_16x16x32_f16 v[136:139], v[132:135], v[164:167], v[136:139]
	v_mfma_f32_16x16x32_f16 v[108:111], v[116:119], v[172:175], v[108:111]
	v_mfma_f32_16x16x32_f16 v[104:107], v[132:135], v[172:175], v[104:107]
	v_mfma_f32_16x16x32_f16 v[92:95], v[116:119], v[180:183], v[92:95]
	v_mfma_f32_16x16x32_f16 v[88:91], v[132:135], v[180:183], v[88:91]
	v_mfma_f32_16x16x32_f16 v[76:79], v[116:119], v[188:191], v[76:79]
	v_mfma_f32_16x16x32_f16 v[72:75], v[132:135], v[188:191], v[72:75]
	s_setprio 0
	s_setprio 1
	v_mfma_f32_16x16x32_f16 v[124:127], v[144:147], v[160:163], v[124:127]
	v_mfma_f32_16x16x32_f16 v[120:123], v[152:155], v[160:163], v[120:123]
	v_mfma_f32_16x16x32_f16 v[100:103], v[144:147], v[168:171], v[100:103]
	v_mfma_f32_16x16x32_f16 v[96:99], v[152:155], v[168:171], v[96:99]
	v_mfma_f32_16x16x32_f16 v[84:87], v[144:147], v[176:179], v[84:87]
	v_mfma_f32_16x16x32_f16 v[80:83], v[152:155], v[176:179], v[80:83]
	v_mfma_f32_16x16x32_f16 v[68:71], v[144:147], v[184:187], v[68:71]
	v_mfma_f32_16x16x32_f16 v[64:67], v[152:155], v[184:187], v[64:67]
	v_mfma_f32_16x16x32_f16 v[124:127], v[148:151], v[164:167], v[124:127]
	v_mfma_f32_16x16x32_f16 v[120:123], v[156:159], v[164:167], v[120:123]
	v_mfma_f32_16x16x32_f16 v[100:103], v[148:151], v[172:175], v[100:103]
	v_mfma_f32_16x16x32_f16 v[96:99], v[156:159], v[172:175], v[96:99]
	v_mfma_f32_16x16x32_f16 v[84:87], v[148:151], v[180:183], v[84:87]
	v_mfma_f32_16x16x32_f16 v[80:83], v[156:159], v[180:183], v[80:83]
	v_mfma_f32_16x16x32_f16 v[68:71], v[148:151], v[188:191], v[68:71]
	v_mfma_f32_16x16x32_f16 v[64:67], v[156:159], v[188:191], v[64:67]
	s_setprio 0
	s_barrier
	s_add_i32 s45, s45, s68
	v_lshl_add_u64 v[192:193], v[192:193], 0, s[34:35]
	s_mov_b32 m0, s45
	ds_read_b128 v[160:163], v237 offset:49152
	ds_read_b128 v[164:167], v237 offset:50176
	ds_read_b128 v[168:171], v237 offset:51200
	ds_read_b128 v[172:175], v237 offset:52224
	ds_read_b128 v[176:179], v237 offset:53248
	ds_read_b128 v[180:183], v237 offset:54272
	ds_read_b128 v[184:187], v237 offset:55296
	ds_read_b128 v[188:191], v237 offset:56320
	global_load_lds_dwordx4 v[192:193], off
	s_add_i32 m0, s45, 0x2000
	s_add_u32 s54, s54, 0x40080
	v_lshl_add_u64 v[192:193], v[194:195], 0, s[34:35]
	s_addc_u32 s55, s55, 0
	s_add_i32 s45, s51, s68
	global_load_lds_dwordx4 v[192:193], off
	v_lshl_add_u64 v[192:193], s[54:55], 0, v[198:199]
	s_mov_b32 m0, s45
	s_nop 0
	global_load_lds_dwordx4 v[192:193], off
	v_lshl_add_u64 v[192:193], s[54:55], 0, v[202:203]
	s_add_i32 m0, s45, 0x2000
	s_nop 0
	global_load_lds_dwordx4 v[192:193], off
	v_lshl_add_u64 v[192:193], v[212:213], 0, s[34:35]
	s_mov_b32 m0, s75
	s_nop 0
	global_load_lds_dwordx4 v[192:193], off
	v_lshl_add_u64 v[192:193], v[214:215], 0, s[34:35]
	s_mov_b32 m0, s62
	s_nop 0
	global_load_lds_dwordx4 v[192:193], off
	s_waitcnt vmcnt(8)
	s_cmp_lt_u32 s3, 4
	s_cbranch_scc1 .Lgls_55
	s_waitcnt lgkmcnt(0)
.Lgls_55:
	s_barrier
	s_setprio 1
	s_waitcnt lgkmcnt(0)
	v_mfma_f32_16x16x32_f16 v[60:63], v[112:115], v[160:163], v[60:63]
	v_mfma_f32_16x16x32_f16 v[56:59], v[128:131], v[160:163], v[56:59]
	v_mfma_f32_16x16x32_f16 v[44:47], v[112:115], v[168:171], v[44:47]
	v_mfma_f32_16x16x32_f16 v[40:43], v[128:131], v[168:171], v[40:43]
	v_mfma_f32_16x16x32_f16 v[28:31], v[112:115], v[176:179], v[28:31]
	v_mfma_f32_16x16x32_f16 v[24:27], v[128:131], v[176:179], v[24:27]
	v_mfma_f32_16x16x32_f16 v[12:15], v[112:115], v[184:187], v[12:15]
	v_mfma_f32_16x16x32_f16 v[8:11], v[128:131], v[184:187], v[8:11]
	v_mfma_f32_16x16x32_f16 v[60:63], v[116:119], v[164:167], v[60:63]
	v_mfma_f32_16x16x32_f16 v[56:59], v[132:135], v[164:167], v[56:59]
	v_mfma_f32_16x16x32_f16 v[44:47], v[116:119], v[172:175], v[44:47]
	v_mfma_f32_16x16x32_f16 v[40:43], v[132:135], v[172:175], v[40:43]
	v_mfma_f32_16x16x32_f16 v[28:31], v[116:119], v[180:183], v[28:31]
	v_mfma_f32_16x16x32_f16 v[24:27], v[132:135], v[180:183], v[24:27]
	v_mfma_f32_16x16x32_f16 v[12:15], v[116:119], v[188:191], v[12:15]
	v_mfma_f32_16x16x32_f16 v[8:11], v[132:135], v[188:191], v[8:11]
	s_setprio 0
	s_setprio 1
	v_mfma_f32_16x16x32_f16 v[52:55], v[144:147], v[160:163], v[52:55]
	v_mfma_f32_16x16x32_f16 v[48:51], v[152:155], v[160:163], v[48:51]
	v_mfma_f32_16x16x32_f16 v[36:39], v[144:147], v[168:171], v[36:39]
	v_mfma_f32_16x16x32_f16 v[32:35], v[152:155], v[168:171], v[32:35]
	v_mfma_f32_16x16x32_f16 v[20:23], v[144:147], v[176:179], v[20:23]
	v_mfma_f32_16x16x32_f16 v[16:19], v[152:155], v[176:179], v[16:19]
	v_mfma_f32_16x16x32_f16 v[4:7], v[144:147], v[184:187], v[4:7]
	v_mfma_f32_16x16x32_f16 v[0:3], v[152:155], v[184:187], v[0:3]
	v_mfma_f32_16x16x32_f16 v[52:55], v[148:151], v[164:167], v[52:55]
	v_mfma_f32_16x16x32_f16 v[48:51], v[156:159], v[164:167], v[48:51]
	v_mfma_f32_16x16x32_f16 v[36:39], v[148:151], v[172:175], v[36:39]
	v_mfma_f32_16x16x32_f16 v[32:35], v[156:159], v[172:175], v[32:35]
	v_mfma_f32_16x16x32_f16 v[20:23], v[148:151], v[180:183], v[20:23]
	v_mfma_f32_16x16x32_f16 v[16:19], v[156:159], v[180:183], v[16:19]
	v_mfma_f32_16x16x32_f16 v[4:7], v[148:151], v[188:191], v[4:7]
	v_mfma_f32_16x16x32_f16 v[0:3], v[156:159], v[188:191], v[0:3]
	s_setprio 0
	s_barrier
	s_add_i32 s43, s43, 2
	s_add_u32 s52, s52, 0x100
	s_addc_u32 s53, s53, 0
	s_add_u32 s41, s41, 0x100
	s_addc_u32 s42, s42, 0
	s_cmp_gt_u32 s43, 13
	s_cbranch_scc0 .LBB0_1469
	s_and_b64 vcc, exec, s[16:17]
	s_cbranch_vccz .LBB0_1472
	s_barrier

; #define PG8_STAGE(bufoff, gbase, voff) do { _Pragma("unroll") for (int _i = 0; _i < 2; ++_i) \
;         __builtin_amdgcn_global_load_lds((const unsigned*)((const char*)(gbase) + (voff)[_i]), (PG8_LAS unsigned*)(lds + (bufoff) + ldsw + _i * 8192), 16, 0, 0); } while (0)
; #define PG8_LDA(dst, b, h) do { _Pragma("unroll") for (int m = 0; m < 4; ++m) _Pragma("unroll") for (int k = 0; k < 2; ++k) dst[m][k] = *(const PG8_LAS bf16x8*)(lds + PG8_SA(b, h) + aoff + m * 2048 + k * 1024); } while (0)
; #define PG8_LDB(dst, b, h) do { _Pragma("unroll") for (int n = 0; n < 2; ++n) _Pragma("unroll") for (int k = 0; k < 2; ++k) dst[n][k] = *(const PG8_LAS bf16x8*)(lds + PG8_SB(b, h) + boff + n * 2048 + k * 1024); } while (0)
; #define PG8_MMA(ai, bj, At, Bt) do { __builtin_amdgcn_s_setprio(1); _Pragma("unroll") for (int m = 0; m < 4; ++m) _Pragma("unroll") for (int n = 0; n < 2; ++n) _Pragma("unroll") for (int k = 0; k < 2; ++k) \
;         acc[ai][bj][m][n] = mma16<F16>(Bt[n][k], At[m][k], acc[ai][bj][m][n]); __builtin_amdgcn_s_setprio(0); } while (0)
; #define PG8_WAIT_V(n) asm volatile("s_waitcnt vmcnt(" #n ")" ::: "memory")
; #define PG8_WAIT_L(n) asm volatile("s_waitcnt lgkmcnt(" #n ")" ::: "memory")
; template <class Epi, class Sched, bool ALIGN_EPI = false, bool SP2 = false, bool F16 = false>
; __device__ __forceinline__ void gemm_phase(PG8_LAS unsigned char* lds, const Gemm g, const Sched& S, const Epi& E, const int wid_in) {
;     ...
;             const bool last = (t == nt - 2);
;             const char* a1 = cA + (size_t)(t + 1) * kstep;
;             const char* a2 = last ? nA : cA + (size_t)(t + 2) * kstep; const char* b2 = last ? nB : cB + (size_t)(t + 2) * kstep;
;             const char* a3 = a2 + kstep; const char* b3 = b2 + kstep;
;             if (last && has_next) S.a_ready(nxt);
;             if constexpr (SP2) {
;             PG8_LDB(B0, 0, 0); PG8_LDB(B1, 0, 1); PG8_SCHED; PG8_LDA(At, 0, 0); PG8_STAGE(PG8_SA(1, 1), a1 + hstep, voffA);
;             PG8_WAIT_V(8); PG8_WAIT_L(0); PG8_BAR; PG8_MMA(0, 0, At, B0); PG8_MMA(0, 1, At, B1); PG8_BAR; PG8_SCHED;
;             PG8_LDA(At, 0, 1); PG8_STAGE(PG8_SB(0, 0), b2, voffB); PG8_STAGE(PG8_SB(0, 1), b2 + hstep, voffB); PG8_STAGE(PG8_SA(0, 0), a2, voffA);
;             PG8_WAIT_V(8); PG8_WAIT_L(0); PG8_BAR; PG8_MMA(1, 0, At, B0); PG8_MMA(1, 1, At, B1); PG8_BAR; PG8_SCHED;
.LBB0_1548:
	ds_read_b128 v[128:131], v184
	ds_read_b128 v[132:135], v184 offset:1024
	ds_read_b128 v[136:139], v184 offset:2048
	ds_read_b128 v[140:143], v184 offset:3072
	ds_read_b128 v[144:147], v185
	ds_read_b128 v[148:151], v185 offset:1024
	ds_read_b128 v[152:155], v185 offset:2048
	ds_read_b128 v[174:177], v185 offset:3072
	s_add_u32 s45, s50, 0xfffc0080
	s_addc_u32 s52, s51, -1
	s_cmp_eq_u32 s43, 12
	s_cselect_b32 s55, s13, s52
	s_cselect_b32 s54, s31, s45
	s_cselect_b32 s53, s37, s42
	s_cselect_b32 s52, s40, s41
	v_lshl_add_u64 v[178:179], s[50:51], 0, v[166:167]
	s_add_i32 m0, s74, 0xc000
	ds_read_b128 v[190:193], v186
	ds_read_b128 v[194:197], v186 offset:1024
	ds_read_b128 v[198:201], v186 offset:2048
	ds_read_b128 v[202:205], v186 offset:3072
	ds_read_b128 v[206:209], v186 offset:4096
	ds_read_b128 v[210:213], v186 offset:5120
	ds_read_b128 v[214:217], v186 offset:6144
	ds_read_b128 v[218:221], v186 offset:7168
	global_load_lds_dwordx4 v[178:179], off
	v_lshl_add_u64 v[178:179], s[50:51], 0, v[168:169]
	s_add_i32 m0, s74, 0xe000
	s_nop 0
	global_load_lds_dwordx4 v[178:179], off
	s_waitcnt vmcnt(8)
	s_cmp_lt_u32 s3, 4
	s_cbranch_scc1 .Lgls_56
	s_waitcnt lgkmcnt(0)
.Lgls_56:
	s_barrier
	s_setprio 1
	s_waitcnt lgkmcnt(0)
	v_mfma_f32_16x16x32_f16 v[124:127], v[128:131], v[190:193], v[124:127]
	v_mfma_f32_16x16x32_f16 v[120:123], v[136:139], v[190:193], v[120:123]
	v_mfma_f32_16x16x32_f16 v[108:111], v[128:131], v[198:201], v[108:111]
	v_mfma_f32_16x16x32_f16 v[104:107], v[136:139], v[198:201], v[104:107]
	v_mfma_f32_16x16x32_f16 v[92:95], v[128:131], v[206:209], v[92:95]
	v_mfma_f32_16x16x32_f16 v[88:91], v[136:139], v[206:209], v[88:91]
	v_mfma_f32_16x16x32_f16 v[76:79], v[128:131], v[214:217], v[76:79]
	v_mfma_f32_16x16x32_f16 v[72:75], v[136:139], v[214:217], v[72:75]
	v_mfma_f32_16x16x32_f16 v[124:127], v[132:135], v[194:197], v[124:127]
	v_mfma_f32_16x16x32_f16 v[120:123], v[140:143], v[194:197], v[120:123]
	v_mfma_f32_16x16x32_f16 v[108:111], v[132:135], v[202:205], v[108:111]
	v_mfma_f32_16x16x32_f16 v[104:107], v[140:143], v[202:205], v[104:107]
	v_mfma_f32_16x16x32_f16 v[92:95], v[132:135], v[210:213], v[92:95]
	v_mfma_f32_16x16x32_f16 v[88:91], v[140:143], v[210:213], v[88:91]
	v_mfma_f32_16x16x32_f16 v[76:79], v[132:135], v[218:221], v[76:79]
	v_mfma_f32_16x16x32_f16 v[72:75], v[140:143], v[218:221], v[72:75]
	s_setprio 0
	s_setprio 1
	v_mfma_f32_16x16x32_f16 v[116:119], v[144:147], v[190:193], v[116:119]
	v_mfma_f32_16x16x32_f16 v[112:115], v[152:155], v[190:193], v[112:115]
	v_mfma_f32_16x16x32_f16 v[100:103], v[144:147], v[198:201], v[100:103]
	v_mfma_f32_16x16x32_f16 v[96:99], v[152:155], v[198:201], v[96:99]
	v_mfma_f32_16x16x32_f16 v[84:87], v[144:147], v[206:209], v[84:87]
	v_mfma_f32_16x16x32_f16 v[80:83], v[152:155], v[206:209], v[80:83]
	v_mfma_f32_16x16x32_f16 v[68:71], v[144:147], v[214:217], v[68:71]
	v_mfma_f32_16x16x32_f16 v[64:67], v[152:155], v[214:217], v[64:67]
	v_mfma_f32_16x16x32_f16 v[116:119], v[148:151], v[194:197], v[116:119]
	v_mfma_f32_16x16x32_f16 v[112:115], v[174:177], v[194:197], v[112:115]
	v_mfma_f32_16x16x32_f16 v[100:103], v[148:151], v[202:205], v[100:103]
	v_mfma_f32_16x16x32_f16 v[96:99], v[174:177], v[202:205], v[96:99]
	v_mfma_f32_16x16x32_f16 v[84:87], v[148:151], v[210:213], v[84:87]
	v_mfma_f32_16x16x32_f16 v[80:83], v[174:177], v[210:213], v[80:83]
	v_mfma_f32_16x16x32_f16 v[68:71], v[148:151], v[218:221], v[68:71]
	v_mfma_f32_16x16x32_f16 v[64:67], v[174:177], v[218:221], v[64:67]
	s_setprio 0
	s_barrier
	s_add_i32 s45, s90, s68
	v_lshl_add_u64 v[178:179], s[52:53], 0, v[158:159]
	s_mov_b32 m0, s45
	ds_read_b128 v[190:193], v186 offset:16384
	ds_read_b128 v[194:197], v186 offset:17408
	ds_read_b128 v[198:201], v186 offset:18432
	ds_read_b128 v[202:205], v186 offset:19456
	ds_read_b128 v[206:209], v186 offset:20480
	ds_read_b128 v[210:213], v186 offset:21504
	ds_read_b128 v[214:217], v186 offset:22528
	ds_read_b128 v[218:221], v186 offset:23552
	global_load_lds_dwordx4 v[178:179], off
	s_add_i32 m0, s45, 0x2000
	s_add_u32 s56, s52, 0x40000
	v_lshl_add_u64 v[222:223], s[52:53], 0, v[162:163]
	s_addc_u32 s57, s53, 0
	s_add_i32 s45, s84, s68
	global_load_lds_dwordx4 v[222:223], off
	v_lshl_add_u64 v[224:225], s[56:57], 0, v[158:159]
	s_mov_b32 m0, s45
	v_lshl_add_u64 v[226:227], s[54:55], 0, v[160:161]
	global_load_lds_dwordx4 v[224:225], off
	v_lshl_add_u64 v[224:225], s[56:57], 0, v[162:163]
	s_add_i32 m0, s45, 0x2000
	s_nop 0
	global_load_lds_dwordx4 v[224:225], off
	v_lshl_add_u64 v[224:225], s[54:55], 0, v[156:157]
	s_mov_b32 m0, s74
	s_nop 0
	global_load_lds_dwordx4 v[224:225], off
	s_mov_b32 m0, s66
	s_nop 0
	global_load_lds_dwordx4 v[226:227], off
	s_waitcnt vmcnt(8)
	s_cmp_lt_u32 s3, 4
	s_cbranch_scc1 .Lgls_57
	s_waitcnt lgkmcnt(0)
; #define PG8_STAGE(bufoff, gbase, voff) do { _Pragma("unroll") for (int _i = 0; _i < 2; ++_i) \
;         __builtin_amdgcn_global_load_lds((const unsigned*)((const char*)(gbase) + (voff)[_i]), (PG8_LAS unsigned*)(lds + (bufoff) + ldsw + _i * 8192), 16, 0, 0); } while (0)
; #define PG8_LDA(dst, b, h) do { _Pragma("unroll") for (int m = 0; m < 4; ++m) _Pragma("unroll") for (int k = 0; k < 2; ++k) dst[m][k] = *(const PG8_LAS bf16x8*)(lds + PG8_SA(b, h) + aoff + m * 2048 + k * 1024); } while (0)
; #define PG8_LDB(dst, b, h) do { _Pragma("unroll") for (int n = 0; n < 2; ++n) _Pragma("unroll") for (int k = 0; k < 2; ++k) dst[n][k] = *(const PG8_LAS bf16x8*)(lds + PG8_SB(b, h) + boff + n * 2048 + k * 1024); } while (0)
; #define PG8_MMA(ai, bj, At, Bt) do { __builtin_amdgcn_s_setprio(1); _Pragma("unroll") for (int m = 0; m < 4; ++m) _Pragma("unroll") for (int n = 0; n < 2; ++n) _Pragma("unroll") for (int k = 0; k < 2; ++k) \
;         acc[ai][bj][m][n] = mma16<F16>(Bt[n][k], At[m][k], acc[ai][bj][m][n]); __builtin_amdgcn_s_setprio(0); } while (0)
; #define PG8_WAIT_V(n) asm volatile("s_waitcnt vmcnt(" #n ")" ::: "memory")
; #define PG8_WAIT_L(n) asm volatile("s_waitcnt lgkmcnt(" #n ")" ::: "memory")
; #define PG8_BAR __builtin_amdgcn_s_barrier()
; #define PG8_SCHED __builtin_amdgcn_sched_barrier(0)
; template <class Epi, class Sched, bool ALIGN_EPI = false, bool SP2 = false, bool F16 = false>
; __device__ __forceinline__ void gemm_phase(PG8_LAS unsigned char* lds, const Gemm g, const Sched& S, const Epi& E, const int wid_in) {
;     ...
;             PG8_LDA(At, 0, 1); PG8_STAGE(PG8_SB(0, 0), b2, voffB); PG8_STAGE(PG8_SB(0, 1), b2 + hstep, voffB); PG8_STAGE(PG8_SA(0, 0), a2, voffA);
;             PG8_WAIT_V(8); PG8_WAIT_L(0); PG8_BAR; PG8_MMA(1, 0, At, B0); PG8_MMA(1, 1, At, B1); PG8_BAR; PG8_SCHED;
;             PG8_LDB(B0, 1, 0); PG8_LDB(B1, 1, 1); PG8_SCHED; PG8_LDA(At, 1, 0); PG8_STAGE(PG8_SA(0, 1), a2 + hstep, voffA);
;             PG8_WAIT_V(8); PG8_WAIT_L(0); PG8_BAR; PG8_MMA(0, 0, At, B0); PG8_MMA(0, 1, At, B1); PG8_BAR; PG8_SCHED;
;             PG8_LDA(At, 1, 1); PG8_STAGE(PG8_SB(1, 0), b3, voffB); PG8_STAGE(PG8_SB(1, 1), b3 + hstep, voffB); PG8_STAGE(PG8_SA(1, 0), a3, voffA);
.Lgls_57:
	s_barrier
	s_setprio 1
	s_waitcnt lgkmcnt(0)
	v_mfma_f32_16x16x32_f16 v[60:63], v[128:131], v[190:193], v[60:63]
	v_mfma_f32_16x16x32_f16 v[56:59], v[136:139], v[190:193], v[56:59]
	v_mfma_f32_16x16x32_f16 v[44:47], v[128:131], v[198:201], v[44:47]
	v_mfma_f32_16x16x32_f16 v[40:43], v[136:139], v[198:201], v[40:43]
	v_mfma_f32_16x16x32_f16 v[28:31], v[128:131], v[206:209], v[28:31]
	v_mfma_f32_16x16x32_f16 v[24:27], v[136:139], v[206:209], v[24:27]
	v_mfma_f32_16x16x32_f16 v[12:15], v[128:131], v[214:217], v[12:15]
	v_mfma_f32_16x16x32_f16 v[8:11], v[136:139], v[214:217], v[8:11]
	v_mfma_f32_16x16x32_f16 v[60:63], v[132:135], v[194:197], v[60:63]
	v_mfma_f32_16x16x32_f16 v[56:59], v[140:143], v[194:197], v[56:59]
	v_mfma_f32_16x16x32_f16 v[44:47], v[132:135], v[202:205], v[44:47]
	v_mfma_f32_16x16x32_f16 v[40:43], v[140:143], v[202:205], v[40:43]
	v_mfma_f32_16x16x32_f16 v[28:31], v[132:135], v[210:213], v[28:31]
	v_mfma_f32_16x16x32_f16 v[24:27], v[140:143], v[210:213], v[24:27]
	v_mfma_f32_16x16x32_f16 v[12:15], v[132:135], v[218:221], v[12:15]
	v_mfma_f32_16x16x32_f16 v[8:11], v[140:143], v[218:221], v[8:11]
	s_setprio 0
	s_setprio 1
	v_mfma_f32_16x16x32_f16 v[52:55], v[144:147], v[190:193], v[52:55]
	v_mfma_f32_16x16x32_f16 v[48:51], v[152:155], v[190:193], v[48:51]
	v_mfma_f32_16x16x32_f16 v[36:39], v[144:147], v[198:201], v[36:39]
	v_mfma_f32_16x16x32_f16 v[32:35], v[152:155], v[198:201], v[32:35]
	v_mfma_f32_16x16x32_f16 v[20:23], v[144:147], v[206:209], v[20:23]
	v_mfma_f32_16x16x32_f16 v[16:19], v[152:155], v[206:209], v[16:19]
	v_mfma_f32_16x16x32_f16 v[4:7], v[144:147], v[214:217], v[4:7]
	v_mfma_f32_16x16x32_f16 v[0:3], v[152:155], v[214:217], v[0:3]
	v_mfma_f32_16x16x32_f16 v[52:55], v[148:151], v[194:197], v[52:55]
	v_mfma_f32_16x16x32_f16 v[48:51], v[174:177], v[194:197], v[48:51]
	v_mfma_f32_16x16x32_f16 v[36:39], v[148:151], v[202:205], v[36:39]
	v_mfma_f32_16x16x32_f16 v[32:35], v[174:177], v[202:205], v[32:35]
	v_mfma_f32_16x16x32_f16 v[20:23], v[148:151], v[210:213], v[20:23]
	v_mfma_f32_16x16x32_f16 v[16:19], v[174:177], v[210:213], v[16:19]
	v_mfma_f32_16x16x32_f16 v[4:7], v[148:151], v[218:221], v[4:7]
	v_mfma_f32_16x16x32_f16 v[0:3], v[174:177], v[218:221], v[0:3]
	s_setprio 0
	s_barrier
	s_add_i32 s45, 0, 0x18000
	s_add_i32 s56, 0, 0x1c000
	v_add_u32_e32 v140, s45, v183
	v_add_u32_e32 v165, s56, v183
	ds_read_b128 v[128:131], v140
	ds_read_b128 v[132:135], v140 offset:1024
	ds_read_b128 v[136:139], v140 offset:2048
	ds_read_b128 v[140:143], v140 offset:3072
	ds_read_b128 v[144:147], v165
	ds_read_b128 v[148:151], v165 offset:1024
	ds_read_b128 v[152:155], v165 offset:2048
	ds_read_b128 v[174:177], v165 offset:3072
	s_add_u32 s54, s54, 0x40000
	s_addc_u32 s55, s55, 0
	s_mov_b32 m0, s67
	v_lshl_add_u64 v[228:229], s[54:55], 0, v[156:157]
	ds_read_b128 v[190:193], v186 offset:32768
	ds_read_b128 v[194:197], v186 offset:33792
	ds_read_b128 v[198:201], v186 offset:34816
	ds_read_b128 v[202:205], v186 offset:35840
	ds_read_b128 v[206:209], v186 offset:36864
	ds_read_b128 v[210:213], v186 offset:37888
	ds_read_b128 v[214:217], v186 offset:38912
	ds_read_b128 v[218:221], v186 offset:39936
	global_load_lds_dwordx4 v[228:229], off
	v_lshl_add_u64 v[228:229], s[54:55], 0, v[160:161]
	s_mov_b32 m0, s91
	s_nop 0
	global_load_lds_dwordx4 v[228:229], off
	s_waitcnt vmcnt(8)
	s_cmp_lt_u32 s3, 4
	s_cbranch_scc1 .Lgls_58
	s_waitcnt lgkmcnt(0)
; #define PG8_STAGE(bufoff, gbase, voff) do { _Pragma("unroll") for (int _i = 0; _i < 2; ++_i) \
;         __builtin_amdgcn_global_load_lds((const unsigned*)((const char*)(gbase) + (voff)[_i]), (PG8_LAS unsigned*)(lds + (bufoff) + ldsw + _i * 8192), 16, 0, 0); } while (0)
; #define PG8_LDA(dst, b, h) do { _Pragma("unroll") for (int m = 0; m < 4; ++m) _Pragma("unroll") for (int k = 0; k < 2; ++k) dst[m][k] = *(const PG8_LAS bf16x8*)(lds + PG8_SA(b, h) + aoff + m * 2048 + k * 1024); } while (0)
; #define PG8_MMA(ai, bj, At, Bt) do { __builtin_amdgcn_s_setprio(1); _Pragma("unroll") for (int m = 0; m < 4; ++m) _Pragma("unroll") for (int n = 0; n < 2; ++n) _Pragma("unroll") for (int k = 0; k < 2; ++k) \
;         acc[ai][bj][m][n] = mma16<F16>(Bt[n][k], At[m][k], acc[ai][bj][m][n]); __builtin_amdgcn_s_setprio(0); } while (0)
; #define PG8_WAIT_V(n) asm volatile("s_waitcnt vmcnt(" #n ")" ::: "memory")
; #define PG8_WAIT_L(n) asm volatile("s_waitcnt lgkmcnt(" #n ")" ::: "memory")
; #define PG8_BAR __builtin_amdgcn_s_barrier()
; #define PG8_SCHED __builtin_amdgcn_sched_barrier(0)
; template <class Epi, class Sched, bool ALIGN_EPI = false, bool SP2 = false, bool F16 = false>
; __device__ __forceinline__ void gemm_phase(PG8_LAS unsigned char* lds, const Gemm g, const Sched& S, const Epi& E, const int wid_in) {
;     ...
;         for (int t = 0; t < nt; t += 2) {
;     ...
;             PG8_LDA(At, 1, 1); PG8_STAGE(PG8_SB(1, 0), b3, voffB); PG8_STAGE(PG8_SB(1, 1), b3 + hstep, voffB); PG8_STAGE(PG8_SA(1, 0), a3, voffA);
;             PG8_WAIT_V(8); PG8_WAIT_L(0); PG8_BAR; PG8_MMA(1, 0, At, B0); PG8_MMA(1, 1, At, B1); PG8_BAR; PG8_SCHED;
.Lgls_58:
	s_barrier
	s_setprio 1
	s_waitcnt lgkmcnt(0)
	v_mfma_f32_16x16x32_f16 v[124:127], v[128:131], v[190:193], v[124:127]
	v_mfma_f32_16x16x32_f16 v[120:123], v[136:139], v[190:193], v[120:123]
	v_mfma_f32_16x16x32_f16 v[108:111], v[128:131], v[198:201], v[108:111]
	v_mfma_f32_16x16x32_f16 v[104:107], v[136:139], v[198:201], v[104:107]
	v_mfma_f32_16x16x32_f16 v[92:95], v[128:131], v[206:209], v[92:95]
	v_mfma_f32_16x16x32_f16 v[88:91], v[136:139], v[206:209], v[88:91]
	v_mfma_f32_16x16x32_f16 v[76:79], v[128:131], v[214:217], v[76:79]
	v_mfma_f32_16x16x32_f16 v[72:75], v[136:139], v[214:217], v[72:75]
	v_mfma_f32_16x16x32_f16 v[124:127], v[132:135], v[194:197], v[124:127]
	v_mfma_f32_16x16x32_f16 v[120:123], v[140:143], v[194:197], v[120:123]
	v_mfma_f32_16x16x32_f16 v[108:111], v[132:135], v[202:205], v[108:111]
	v_mfma_f32_16x16x32_f16 v[104:107], v[140:143], v[202:205], v[104:107]
	v_mfma_f32_16x16x32_f16 v[92:95], v[132:135], v[210:213], v[92:95]
	v_mfma_f32_16x16x32_f16 v[88:91], v[140:143], v[210:213], v[88:91]
	v_mfma_f32_16x16x32_f16 v[76:79], v[132:135], v[218:221], v[76:79]
	v_mfma_f32_16x16x32_f16 v[72:75], v[140:143], v[218:221], v[72:75]
	s_setprio 0
	s_setprio 1
	v_mfma_f32_16x16x32_f16 v[116:119], v[144:147], v[190:193], v[116:119]
	v_mfma_f32_16x16x32_f16 v[112:115], v[152:155], v[190:193], v[112:115]
	v_mfma_f32_16x16x32_f16 v[100:103], v[144:147], v[198:201], v[100:103]
	v_mfma_f32_16x16x32_f16 v[96:99], v[152:155], v[198:201], v[96:99]
	v_mfma_f32_16x16x32_f16 v[84:87], v[144:147], v[206:209], v[84:87]
	v_mfma_f32_16x16x32_f16 v[80:83], v[152:155], v[206:209], v[80:83]
	v_mfma_f32_16x16x32_f16 v[68:71], v[144:147], v[214:217], v[68:71]
	v_mfma_f32_16x16x32_f16 v[64:67], v[152:155], v[214:217], v[64:67]
	v_mfma_f32_16x16x32_f16 v[116:119], v[148:151], v[194:197], v[116:119]
	v_mfma_f32_16x16x32_f16 v[112:115], v[174:177], v[194:197], v[112:115]
	v_mfma_f32_16x16x32_f16 v[100:103], v[148:151], v[202:205], v[100:103]
	v_mfma_f32_16x16x32_f16 v[96:99], v[174:177], v[202:205], v[96:99]
	v_mfma_f32_16x16x32_f16 v[84:87], v[148:151], v[210:213], v[84:87]
	v_mfma_f32_16x16x32_f16 v[80:83], v[174:177], v[210:213], v[80:83]
	v_mfma_f32_16x16x32_f16 v[68:71], v[148:151], v[218:221], v[68:71]
	v_mfma_f32_16x16x32_f16 v[64:67], v[174:177], v[218:221], v[64:67]
	s_setprio 0
	s_barrier
	s_add_i32 s45, s45, s68
	v_lshl_add_u64 v[178:179], v[178:179], 0, s[34:35]
	s_mov_b32 m0, s45
	ds_read_b128 v[190:193], v186 offset:49152
	ds_read_b128 v[194:197], v186 offset:50176
	ds_read_b128 v[198:201], v186 offset:51200
	ds_read_b128 v[202:205], v186 offset:52224
	ds_read_b128 v[206:209], v186 offset:53248
	ds_read_b128 v[210:213], v186 offset:54272
	ds_read_b128 v[214:217], v186 offset:55296
	ds_read_b128 v[218:221], v186 offset:56320
	global_load_lds_dwordx4 v[178:179], off
	s_add_i32 m0, s45, 0x2000
	s_add_u32 s52, s52, 0x40080
	v_lshl_add_u64 v[178:179], v[222:223], 0, s[34:35]
	s_addc_u32 s53, s53, 0
	s_add_i32 s45, s56, s68
	global_load_lds_dwordx4 v[178:179], off
	v_lshl_add_u64 v[178:179], s[52:53], 0, v[158:159]
	s_mov_b32 m0, s45
	s_nop 0
	global_load_lds_dwordx4 v[178:179], off
	v_lshl_add_u64 v[178:179], s[52:53], 0, v[162:163]
	s_add_i32 m0, s45, 0x2000
	s_nop 0
	global_load_lds_dwordx4 v[178:179], off
	v_lshl_add_u64 v[178:179], v[224:225], 0, s[34:35]
	s_mov_b32 m0, s75
	s_nop 0
	global_load_lds_dwordx4 v[178:179], off
	v_lshl_add_u64 v[178:179], v[226:227], 0, s[34:35]
	s_mov_b32 m0, s97
	s_nop 0
	global_load_lds_dwordx4 v[178:179], off
	s_waitcnt vmcnt(8)
	s_cmp_lt_u32 s3, 4
	s_cbranch_scc1 .Lgls_59
	s_waitcnt lgkmcnt(0)
.Lgls_59:
	s_barrier
	s_setprio 1
	s_waitcnt lgkmcnt(0)
	v_mfma_f32_16x16x32_f16 v[60:63], v[128:131], v[190:193], v[60:63]
	v_mfma_f32_16x16x32_f16 v[56:59], v[136:139], v[190:193], v[56:59]
	v_mfma_f32_16x16x32_f16 v[44:47], v[128:131], v[198:201], v[44:47]
	v_mfma_f32_16x16x32_f16 v[40:43], v[136:139], v[198:201], v[40:43]
	v_mfma_f32_16x16x32_f16 v[28:31], v[128:131], v[206:209], v[28:31]
	v_mfma_f32_16x16x32_f16 v[24:27], v[136:139], v[206:209], v[24:27]
	v_mfma_f32_16x16x32_f16 v[12:15], v[128:131], v[214:217], v[12:15]
	v_mfma_f32_16x16x32_f16 v[8:11], v[136:139], v[214:217], v[8:11]
	v_mfma_f32_16x16x32_f16 v[60:63], v[132:135], v[194:197], v[60:63]
	v_mfma_f32_16x16x32_f16 v[56:59], v[140:143], v[194:197], v[56:59]
	v_mfma_f32_16x16x32_f16 v[44:47], v[132:135], v[202:205], v[44:47]
	v_mfma_f32_16x16x32_f16 v[40:43], v[140:143], v[202:205], v[40:43]
	v_mfma_f32_16x16x32_f16 v[28:31], v[132:135], v[210:213], v[28:31]
	v_mfma_f32_16x16x32_f16 v[24:27], v[140:143], v[210:213], v[24:27]
	v_mfma_f32_16x16x32_f16 v[12:15], v[132:135], v[218:221], v[12:15]
	v_mfma_f32_16x16x32_f16 v[8:11], v[140:143], v[218:221], v[8:11]
	s_setprio 0
	s_setprio 1
	v_mfma_f32_16x16x32_f16 v[52:55], v[144:147], v[190:193], v[52:55]
	v_mfma_f32_16x16x32_f16 v[48:51], v[152:155], v[190:193], v[48:51]
	v_mfma_f32_16x16x32_f16 v[36:39], v[144:147], v[198:201], v[36:39]
	v_mfma_f32_16x16x32_f16 v[32:35], v[152:155], v[198:201], v[32:35]
	v_mfma_f32_16x16x32_f16 v[20:23], v[144:147], v[206:209], v[20:23]
	v_mfma_f32_16x16x32_f16 v[16:19], v[152:155], v[206:209], v[16:19]
	v_mfma_f32_16x16x32_f16 v[4:7], v[144:147], v[214:217], v[4:7]
	v_mfma_f32_16x16x32_f16 v[0:3], v[152:155], v[214:217], v[0:3]
	v_mfma_f32_16x16x32_f16 v[52:55], v[148:151], v[194:197], v[52:55]
	v_mfma_f32_16x16x32_f16 v[48:51], v[174:177], v[194:197], v[48:51]
	v_mfma_f32_16x16x32_f16 v[36:39], v[148:151], v[202:205], v[36:39]
	v_mfma_f32_16x16x32_f16 v[32:35], v[174:177], v[202:205], v[32:35]
	v_mfma_f32_16x16x32_f16 v[20:23], v[148:151], v[210:213], v[20:23]
	v_mfma_f32_16x16x32_f16 v[16:19], v[174:177], v[210:213], v[16:19]
	v_mfma_f32_16x16x32_f16 v[4:7], v[148:151], v[218:221], v[4:7]
	v_mfma_f32_16x16x32_f16 v[0:3], v[174:177], v[218:221], v[0:3]
	s_setprio 0
	s_barrier
	s_add_i32 s43, s43, 2
	s_add_u32 s50, s50, 0x100
	s_addc_u32 s51, s51, 0
	s_add_u32 s41, s41, 0x100
	s_addc_u32 s42, s42, 0
	s_cmp_gt_u32 s43, 13
	s_cbranch_scc0 .LBB0_1548
	s_and_b64 vcc, exec, s[16:17]
	s_cbranch_vccz .LBB0_1551
	s_barrier

; #define PG8_STAGE(bufoff, gbase, voff) do { _Pragma("unroll") for (int _i = 0; _i < 2; ++_i) \
;         __builtin_amdgcn_global_load_lds((const unsigned*)((const char*)(gbase) + (voff)[_i]), (PG8_LAS unsigned*)(lds + (bufoff) + ldsw + _i * 8192), 16, 0, 0); } while (0)
; #define PG8_LDA(dst, b, h) do { _Pragma("unroll") for (int m = 0; m < 4; ++m) _Pragma("unroll") for (int k = 0; k < 2; ++k) dst[m][k] = *(const PG8_LAS bf16x8*)(lds + PG8_SA(b, h) + aoff + m * 2048 + k * 1024); } while (0)
; #define PG8_LDB(dst, b, h) do { _Pragma("unroll") for (int n = 0; n < 2; ++n) _Pragma("unroll") for (int k = 0; k < 2; ++k) dst[n][k] = *(const PG8_LAS bf16x8*)(lds + PG8_SB(b, h) + boff + n * 2048 + k * 1024); } while (0)
; #define PG8_MMA(ai, bj, At, Bt) do { __builtin_amdgcn_s_setprio(1); _Pragma("unroll") for (int m = 0; m < 4; ++m) _Pragma("unroll") for (int n = 0; n < 2; ++n) _Pragma("unroll") for (int k = 0; k < 2; ++k) \
;         acc[ai][bj][m][n] = mma16<F16>(Bt[n][k], At[m][k], acc[ai][bj][m][n]); __builtin_amdgcn_s_setprio(0); } while (0)
; #define PG8_WAIT_V(n) asm volatile("s_waitcnt vmcnt(" #n ")" ::: "memory")
; #define PG8_WAIT_L(n) asm volatile("s_waitcnt lgkmcnt(" #n ")" ::: "memory")
; template <class Epi, class Sched, bool ALIGN_EPI = false, bool SP2 = false, bool F16 = false>
; __device__ __forceinline__ void gemm_phase(PG8_LAS unsigned char* lds, const Gemm g, const Sched& S, const Epi& E, const int wid_in) {
;     ...
;             const bool last = (t == nt - 2);
;             const char* a1 = cA + (size_t)(t + 1) * kstep;
;             const char* a2 = last ? nA : cA + (size_t)(t + 2) * kstep; const char* b2 = last ? nB : cB + (size_t)(t + 2) * kstep;
;             const char* a3 = a2 + kstep; const char* b3 = b2 + kstep;
;             if (last && has_next) S.a_ready(nxt);
;             if constexpr (SP2) {
;             PG8_LDB(B0, 0, 0); PG8_LDB(B1, 0, 1); PG8_SCHED; PG8_LDA(At, 0, 0); PG8_STAGE(PG8_SA(1, 1), a1 + hstep, voffA);
;             PG8_WAIT_V(8); PG8_WAIT_L(0); PG8_BAR; PG8_MMA(0, 0, At, B0); PG8_MMA(0, 1, At, B1); PG8_BAR; PG8_SCHED;
;             PG8_LDA(At, 0, 1); PG8_STAGE(PG8_SB(0, 0), b2, voffB); PG8_STAGE(PG8_SB(0, 1), b2 + hstep, voffB); PG8_STAGE(PG8_SA(0, 0), a2, voffA);
;             PG8_WAIT_V(8); PG8_WAIT_L(0); PG8_BAR; PG8_MMA(1, 0, At, B0); PG8_MMA(1, 1, At, B1); PG8_BAR; PG8_SCHED;
.LBB0_1832:
	ds_read_b128 v[128:131], v189
	ds_read_b128 v[132:135], v189 offset:1024
	ds_read_b128 v[136:139], v189 offset:2048
	ds_read_b128 v[140:143], v189 offset:3072
	ds_read_b128 v[144:147], v190
	ds_read_b128 v[148:151], v190 offset:1024
	ds_read_b128 v[168:171], v190 offset:2048
	ds_read_b128 v[172:175], v190 offset:3072
	s_add_u32 s50, s48, 0xfffc0080
	s_addc_u32 s51, s49, -1
	s_cmp_eq_u32 s61, 12
	s_cselect_b32 s53, s35, s51
	s_cselect_b32 s52, s42, s50
	s_cselect_b32 s51, s31, s60
	s_cselect_b32 s50, s43, s47
	s_mov_b32 m0, s91
	v_lshl_add_u64 v[184:185], s[48:49], 0, v[160:161]
	ds_read_b128 v[176:179], v191
	ds_read_b128 v[180:183], v191 offset:1024
	ds_read_b128 v[192:195], v191 offset:2048
	ds_read_b128 v[196:199], v191 offset:3072
	ds_read_b128 v[200:203], v191 offset:4096
	ds_read_b128 v[204:207], v191 offset:5120
	ds_read_b128 v[208:211], v191 offset:6144
	ds_read_b128 v[212:215], v191 offset:7168
	global_load_lds_dwordx4 v[184:185], off
	v_lshl_add_u64 v[184:185], s[48:49], 0, v[162:163]
	s_add_i32 m0, s74, 0xe000
	s_nop 0
	global_load_lds_dwordx4 v[184:185], off
	s_waitcnt vmcnt(8)
	s_cmp_lt_u32 s3, 4
	s_cbranch_scc1 .Lgls_60
	s_waitcnt lgkmcnt(0)
.Lgls_60:
	s_barrier
	s_setprio 1
	s_waitcnt lgkmcnt(0)
	v_mfma_f32_16x16x32_bf16 v[124:127], v[128:131], v[176:179], v[124:127]
	v_mfma_f32_16x16x32_bf16 v[120:123], v[136:139], v[176:179], v[120:123]
	v_mfma_f32_16x16x32_bf16 v[108:111], v[128:131], v[192:195], v[108:111]
	v_mfma_f32_16x16x32_bf16 v[104:107], v[136:139], v[192:195], v[104:107]
	v_mfma_f32_16x16x32_bf16 v[92:95], v[128:131], v[200:203], v[92:95]
	v_mfma_f32_16x16x32_bf16 v[88:91], v[136:139], v[200:203], v[88:91]
	v_mfma_f32_16x16x32_bf16 v[76:79], v[128:131], v[208:211], v[76:79]
	v_mfma_f32_16x16x32_bf16 v[72:75], v[136:139], v[208:211], v[72:75]
	v_mfma_f32_16x16x32_bf16 v[124:127], v[132:135], v[180:183], v[124:127]
	v_mfma_f32_16x16x32_bf16 v[120:123], v[140:143], v[180:183], v[120:123]
	v_mfma_f32_16x16x32_bf16 v[108:111], v[132:135], v[196:199], v[108:111]
	v_mfma_f32_16x16x32_bf16 v[104:107], v[140:143], v[196:199], v[104:107]
	v_mfma_f32_16x16x32_bf16 v[92:95], v[132:135], v[204:207], v[92:95]
	v_mfma_f32_16x16x32_bf16 v[88:91], v[140:143], v[204:207], v[88:91]
	v_mfma_f32_16x16x32_bf16 v[76:79], v[132:135], v[212:215], v[76:79]
	v_mfma_f32_16x16x32_bf16 v[72:75], v[140:143], v[212:215], v[72:75]
	s_setprio 0
	s_setprio 1
	v_mfma_f32_16x16x32_bf16 v[116:119], v[144:147], v[176:179], v[116:119]
	v_mfma_f32_16x16x32_bf16 v[112:115], v[168:171], v[176:179], v[112:115]
	v_mfma_f32_16x16x32_bf16 v[100:103], v[144:147], v[192:195], v[100:103]
	v_mfma_f32_16x16x32_bf16 v[96:99], v[168:171], v[192:195], v[96:99]
	v_mfma_f32_16x16x32_bf16 v[84:87], v[144:147], v[200:203], v[84:87]
	v_mfma_f32_16x16x32_bf16 v[80:83], v[168:171], v[200:203], v[80:83]
	v_mfma_f32_16x16x32_bf16 v[68:71], v[144:147], v[208:211], v[68:71]
	v_mfma_f32_16x16x32_bf16 v[64:67], v[168:171], v[208:211], v[64:67]
	v_mfma_f32_16x16x32_bf16 v[116:119], v[148:151], v[180:183], v[116:119]
	v_mfma_f32_16x16x32_bf16 v[112:115], v[172:175], v[180:183], v[112:115]
	v_mfma_f32_16x16x32_bf16 v[100:103], v[148:151], v[196:199], v[100:103]
	v_mfma_f32_16x16x32_bf16 v[96:99], v[172:175], v[196:199], v[96:99]
	v_mfma_f32_16x16x32_bf16 v[84:87], v[148:151], v[204:207], v[84:87]
	v_mfma_f32_16x16x32_bf16 v[80:83], v[172:175], v[204:207], v[80:83]
	v_mfma_f32_16x16x32_bf16 v[68:71], v[148:151], v[212:215], v[68:71]
	v_mfma_f32_16x16x32_bf16 v[64:67], v[172:175], v[212:215], v[64:67]
	s_setprio 0
	s_barrier
	s_add_i32 s62, s57, s68
	v_lshl_add_u64 v[184:185], s[50:51], 0, v[154:155]
	s_mov_b32 m0, s62
	ds_read_b128 v[176:179], v191 offset:16384
	ds_read_b128 v[180:183], v191 offset:17408
	ds_read_b128 v[192:195], v191 offset:18432
	ds_read_b128 v[196:199], v191 offset:19456
	ds_read_b128 v[200:203], v191 offset:20480
	ds_read_b128 v[204:207], v191 offset:21504
	ds_read_b128 v[208:211], v191 offset:22528
	ds_read_b128 v[212:215], v191 offset:23552
	global_load_lds_dwordx4 v[184:185], off
	s_add_i32 m0, s62, 0x2000
	s_add_u32 s62, s50, 0x40000
	v_lshl_add_u64 v[216:217], s[50:51], 0, v[158:159]
	s_addc_u32 s63, s51, 0
	s_add_i32 s64, s58, s68
	global_load_lds_dwordx4 v[216:217], off
	v_lshl_add_u64 v[218:219], s[62:63], 0, v[154:155]
	s_mov_b32 m0, s64
	v_lshl_add_u64 v[220:221], s[52:53], 0, v[156:157]
	global_load_lds_dwordx4 v[218:219], off
	v_lshl_add_u64 v[218:219], s[62:63], 0, v[158:159]
	s_add_i32 m0, s64, 0x2000
	s_nop 0
	global_load_lds_dwordx4 v[218:219], off
	v_lshl_add_u64 v[218:219], s[52:53], 0, v[152:153]
	s_mov_b32 m0, s74
	s_nop 0
	global_load_lds_dwordx4 v[218:219], off
	s_mov_b32 m0, s66
	s_nop 0
	global_load_lds_dwordx4 v[220:221], off
	s_waitcnt vmcnt(8)
	s_cmp_lt_u32 s3, 4
	s_cbranch_scc1 .Lgls_61
	s_waitcnt lgkmcnt(0)
; #define PG8_STAGE(bufoff, gbase, voff) do { _Pragma("unroll") for (int _i = 0; _i < 2; ++_i) \
;         __builtin_amdgcn_global_load_lds((const unsigned*)((const char*)(gbase) + (voff)[_i]), (PG8_LAS unsigned*)(lds + (bufoff) + ldsw + _i * 8192), 16, 0, 0); } while (0)
; #define PG8_LDA(dst, b, h) do { _Pragma("unroll") for (int m = 0; m < 4; ++m) _Pragma("unroll") for (int k = 0; k < 2; ++k) dst[m][k] = *(const PG8_LAS bf16x8*)(lds + PG8_SA(b, h) + aoff + m * 2048 + k * 1024); } while (0)
; #define PG8_LDB(dst, b, h) do { _Pragma("unroll") for (int n = 0; n < 2; ++n) _Pragma("unroll") for (int k = 0; k < 2; ++k) dst[n][k] = *(const PG8_LAS bf16x8*)(lds + PG8_SB(b, h) + boff + n * 2048 + k * 1024); } while (0)
; #define PG8_MMA(ai, bj, At, Bt) do { __builtin_amdgcn_s_setprio(1); _Pragma("unroll") for (int m = 0; m < 4; ++m) _Pragma("unroll") for (int n = 0; n < 2; ++n) _Pragma("unroll") for (int k = 0; k < 2; ++k) \
;         acc[ai][bj][m][n] = mma16<F16>(Bt[n][k], At[m][k], acc[ai][bj][m][n]); __builtin_amdgcn_s_setprio(0); } while (0)
; #define PG8_WAIT_V(n) asm volatile("s_waitcnt vmcnt(" #n ")" ::: "memory")
; #define PG8_WAIT_L(n) asm volatile("s_waitcnt lgkmcnt(" #n ")" ::: "memory")
; #define PG8_BAR __builtin_amdgcn_s_barrier()
; #define PG8_SCHED __builtin_amdgcn_sched_barrier(0)
; template <class Epi, class Sched, bool ALIGN_EPI = false, bool SP2 = false, bool F16 = false>
; __device__ __forceinline__ void gemm_phase(PG8_LAS unsigned char* lds, const Gemm g, const Sched& S, const Epi& E, const int wid_in) {
;     ...
;             PG8_LDA(At, 0, 1); PG8_STAGE(PG8_SB(0, 0), b2, voffB); PG8_STAGE(PG8_SB(0, 1), b2 + hstep, voffB); PG8_STAGE(PG8_SA(0, 0), a2, voffA);
;             PG8_WAIT_V(8); PG8_WAIT_L(0); PG8_BAR; PG8_MMA(1, 0, At, B0); PG8_MMA(1, 1, At, B1); PG8_BAR; PG8_SCHED;
;             PG8_LDB(B0, 1, 0); PG8_LDB(B1, 1, 1); PG8_SCHED; PG8_LDA(At, 1, 0); PG8_STAGE(PG8_SA(0, 1), a2 + hstep, voffA);
;             PG8_WAIT_V(8); PG8_WAIT_L(0); PG8_BAR; PG8_MMA(0, 0, At, B0); PG8_MMA(0, 1, At, B1); PG8_BAR; PG8_SCHED;
;             PG8_LDA(At, 1, 1); PG8_STAGE(PG8_SB(1, 0), b3, voffB); PG8_STAGE(PG8_SB(1, 1), b3 + hstep, voffB); PG8_STAGE(PG8_SA(1, 0), a3, voffA);
.Lgls_61:
	s_barrier
	s_setprio 1
	s_waitcnt lgkmcnt(0)
	v_mfma_f32_16x16x32_bf16 v[60:63], v[128:131], v[176:179], v[60:63]
	v_mfma_f32_16x16x32_bf16 v[56:59], v[136:139], v[176:179], v[56:59]
	v_mfma_f32_16x16x32_bf16 v[44:47], v[128:131], v[192:195], v[44:47]
	v_mfma_f32_16x16x32_bf16 v[40:43], v[136:139], v[192:195], v[40:43]
	v_mfma_f32_16x16x32_bf16 v[28:31], v[128:131], v[200:203], v[28:31]
	v_mfma_f32_16x16x32_bf16 v[24:27], v[136:139], v[200:203], v[24:27]
	v_mfma_f32_16x16x32_bf16 v[12:15], v[128:131], v[208:211], v[12:15]
	v_mfma_f32_16x16x32_bf16 v[8:11], v[136:139], v[208:211], v[8:11]
	v_mfma_f32_16x16x32_bf16 v[60:63], v[132:135], v[180:183], v[60:63]
	v_mfma_f32_16x16x32_bf16 v[56:59], v[140:143], v[180:183], v[56:59]
	v_mfma_f32_16x16x32_bf16 v[44:47], v[132:135], v[196:199], v[44:47]
	v_mfma_f32_16x16x32_bf16 v[40:43], v[140:143], v[196:199], v[40:43]
	v_mfma_f32_16x16x32_bf16 v[28:31], v[132:135], v[204:207], v[28:31]
	v_mfma_f32_16x16x32_bf16 v[24:27], v[140:143], v[204:207], v[24:27]
	v_mfma_f32_16x16x32_bf16 v[12:15], v[132:135], v[212:215], v[12:15]
	v_mfma_f32_16x16x32_bf16 v[8:11], v[140:143], v[212:215], v[8:11]
	s_setprio 0
	s_setprio 1
	v_mfma_f32_16x16x32_bf16 v[52:55], v[144:147], v[176:179], v[52:55]
	v_mfma_f32_16x16x32_bf16 v[48:51], v[168:171], v[176:179], v[48:51]
	v_mfma_f32_16x16x32_bf16 v[36:39], v[144:147], v[192:195], v[36:39]
	v_mfma_f32_16x16x32_bf16 v[32:35], v[168:171], v[192:195], v[32:35]
	v_mfma_f32_16x16x32_bf16 v[20:23], v[144:147], v[200:203], v[20:23]
	v_mfma_f32_16x16x32_bf16 v[16:19], v[168:171], v[200:203], v[16:19]
	v_mfma_f32_16x16x32_bf16 v[4:7], v[144:147], v[208:211], v[4:7]
	v_mfma_f32_16x16x32_bf16 v[0:3], v[168:171], v[208:211], v[0:3]
	v_mfma_f32_16x16x32_bf16 v[52:55], v[148:151], v[180:183], v[52:55]
	v_mfma_f32_16x16x32_bf16 v[48:51], v[172:175], v[180:183], v[48:51]
	v_mfma_f32_16x16x32_bf16 v[36:39], v[148:151], v[196:199], v[36:39]
	v_mfma_f32_16x16x32_bf16 v[32:35], v[172:175], v[196:199], v[32:35]
	v_mfma_f32_16x16x32_bf16 v[20:23], v[148:151], v[204:207], v[20:23]
	v_mfma_f32_16x16x32_bf16 v[16:19], v[172:175], v[204:207], v[16:19]
	v_mfma_f32_16x16x32_bf16 v[4:7], v[148:151], v[212:215], v[4:7]
	v_mfma_f32_16x16x32_bf16 v[0:3], v[172:175], v[212:215], v[0:3]
	s_setprio 0
	s_barrier
	s_add_i32 s62, 0, 0x18000
	s_add_i32 s63, 0, 0x1c000
	v_add_u32_e32 v140, s62, v188
	v_add_u32_e32 v172, s63, v188
	ds_read_b128 v[128:131], v140
	ds_read_b128 v[132:135], v140 offset:1024
	ds_read_b128 v[136:139], v140 offset:2048
	ds_read_b128 v[140:143], v140 offset:3072
	ds_read_b128 v[144:147], v172
	ds_read_b128 v[148:151], v172 offset:1024
	ds_read_b128 v[168:171], v172 offset:2048
	ds_read_b128 v[172:175], v172 offset:3072
	s_add_u32 s52, s52, 0x40000
	s_addc_u32 s53, s53, 0
	s_mov_b32 m0, s90
	v_lshl_add_u64 v[222:223], s[52:53], 0, v[152:153]
	ds_read_b128 v[176:179], v191 offset:32768
	ds_read_b128 v[180:183], v191 offset:33792
	ds_read_b128 v[192:195], v191 offset:34816
	ds_read_b128 v[196:199], v191 offset:35840
	ds_read_b128 v[200:203], v191 offset:36864
	ds_read_b128 v[204:207], v191 offset:37888
	ds_read_b128 v[208:211], v191 offset:38912
	ds_read_b128 v[212:215], v191 offset:39936
	global_load_lds_dwordx4 v[222:223], off
	v_lshl_add_u64 v[222:223], s[52:53], 0, v[156:157]
	s_mov_b32 m0, s41
	s_nop 0
	global_load_lds_dwordx4 v[222:223], off
	s_waitcnt vmcnt(8)
	s_cmp_lt_u32 s3, 4
	s_cbranch_scc1 .Lgls_62
	s_waitcnt lgkmcnt(0)
; #define PG8_STAGE(bufoff, gbase, voff) do { _Pragma("unroll") for (int _i = 0; _i < 2; ++_i) \
;         __builtin_amdgcn_global_load_lds((const unsigned*)((const char*)(gbase) + (voff)[_i]), (PG8_LAS unsigned*)(lds + (bufoff) + ldsw + _i * 8192), 16, 0, 0); } while (0)
; #define PG8_LDA(dst, b, h) do { _Pragma("unroll") for (int m = 0; m < 4; ++m) _Pragma("unroll") for (int k = 0; k < 2; ++k) dst[m][k] = *(const PG8_LAS bf16x8*)(lds + PG8_SA(b, h) + aoff + m * 2048 + k * 1024); } while (0)
; #define PG8_MMA(ai, bj, At, Bt) do { __builtin_amdgcn_s_setprio(1); _Pragma("unroll") for (int m = 0; m < 4; ++m) _Pragma("unroll") for (int n = 0; n < 2; ++n) _Pragma("unroll") for (int k = 0; k < 2; ++k) \
;         acc[ai][bj][m][n] = mma16<F16>(Bt[n][k], At[m][k], acc[ai][bj][m][n]); __builtin_amdgcn_s_setprio(0); } while (0)
; #define PG8_WAIT_V(n) asm volatile("s_waitcnt vmcnt(" #n ")" ::: "memory")
; #define PG8_WAIT_L(n) asm volatile("s_waitcnt lgkmcnt(" #n ")" ::: "memory")
; #define PG8_BAR __builtin_amdgcn_s_barrier()
; #define PG8_SCHED __builtin_amdgcn_sched_barrier(0)
; template <class Epi, class Sched, bool ALIGN_EPI = false, bool SP2 = false, bool F16 = false>
; __device__ __forceinline__ void gemm_phase(PG8_LAS unsigned char* lds, const Gemm g, const Sched& S, const Epi& E, const int wid_in) {
;     ...
;         for (int t = 0; t < nt; t += 2) {
;     ...
;             PG8_LDA(At, 1, 1); PG8_STAGE(PG8_SB(1, 0), b3, voffB); PG8_STAGE(PG8_SB(1, 1), b3 + hstep, voffB); PG8_STAGE(PG8_SA(1, 0), a3, voffA);
;             PG8_WAIT_V(8); PG8_WAIT_L(0); PG8_BAR; PG8_MMA(1, 0, At, B0); PG8_MMA(1, 1, At, B1); PG8_BAR; PG8_SCHED;
.Lgls_62:
	s_barrier
	s_setprio 1
	s_waitcnt lgkmcnt(0)
	v_mfma_f32_16x16x32_bf16 v[124:127], v[128:131], v[176:179], v[124:127]
	v_mfma_f32_16x16x32_bf16 v[120:123], v[136:139], v[176:179], v[120:123]
	v_mfma_f32_16x16x32_bf16 v[108:111], v[128:131], v[192:195], v[108:111]
	v_mfma_f32_16x16x32_bf16 v[104:107], v[136:139], v[192:195], v[104:107]
	v_mfma_f32_16x16x32_bf16 v[92:95], v[128:131], v[200:203], v[92:95]
	v_mfma_f32_16x16x32_bf16 v[88:91], v[136:139], v[200:203], v[88:91]
	v_mfma_f32_16x16x32_bf16 v[76:79], v[128:131], v[208:211], v[76:79]
	v_mfma_f32_16x16x32_bf16 v[72:75], v[136:139], v[208:211], v[72:75]
	v_mfma_f32_16x16x32_bf16 v[124:127], v[132:135], v[180:183], v[124:127]
	v_mfma_f32_16x16x32_bf16 v[120:123], v[140:143], v[180:183], v[120:123]
	v_mfma_f32_16x16x32_bf16 v[108:111], v[132:135], v[196:199], v[108:111]
	v_mfma_f32_16x16x32_bf16 v[104:107], v[140:143], v[196:199], v[104:107]
	v_mfma_f32_16x16x32_bf16 v[92:95], v[132:135], v[204:207], v[92:95]
	v_mfma_f32_16x16x32_bf16 v[88:91], v[140:143], v[204:207], v[88:91]
	v_mfma_f32_16x16x32_bf16 v[76:79], v[132:135], v[212:215], v[76:79]
	v_mfma_f32_16x16x32_bf16 v[72:75], v[140:143], v[212:215], v[72:75]
	s_setprio 0
	s_setprio 1
	v_mfma_f32_16x16x32_bf16 v[116:119], v[144:147], v[176:179], v[116:119]
	v_mfma_f32_16x16x32_bf16 v[112:115], v[168:171], v[176:179], v[112:115]
	v_mfma_f32_16x16x32_bf16 v[100:103], v[144:147], v[192:195], v[100:103]
	v_mfma_f32_16x16x32_bf16 v[96:99], v[168:171], v[192:195], v[96:99]
	v_mfma_f32_16x16x32_bf16 v[84:87], v[144:147], v[200:203], v[84:87]
	v_mfma_f32_16x16x32_bf16 v[80:83], v[168:171], v[200:203], v[80:83]
	v_mfma_f32_16x16x32_bf16 v[68:71], v[144:147], v[208:211], v[68:71]
	v_mfma_f32_16x16x32_bf16 v[64:67], v[168:171], v[208:211], v[64:67]
	v_mfma_f32_16x16x32_bf16 v[116:119], v[148:151], v[180:183], v[116:119]
	v_mfma_f32_16x16x32_bf16 v[112:115], v[172:175], v[180:183], v[112:115]
	v_mfma_f32_16x16x32_bf16 v[100:103], v[148:151], v[196:199], v[100:103]
	v_mfma_f32_16x16x32_bf16 v[96:99], v[172:175], v[196:199], v[96:99]
	v_mfma_f32_16x16x32_bf16 v[84:87], v[148:151], v[204:207], v[84:87]
	v_mfma_f32_16x16x32_bf16 v[80:83], v[172:175], v[204:207], v[80:83]
	v_mfma_f32_16x16x32_bf16 v[68:71], v[148:151], v[212:215], v[68:71]
	v_mfma_f32_16x16x32_bf16 v[64:67], v[172:175], v[212:215], v[64:67]
	s_setprio 0
	s_barrier
	s_add_i32 s52, s62, s68
	v_lshl_add_u64 v[184:185], v[184:185], 0, s[28:29]
	s_mov_b32 m0, s52
	ds_read_b128 v[176:179], v191 offset:49152
	ds_read_b128 v[180:183], v191 offset:50176
	ds_read_b128 v[192:195], v191 offset:51200
	ds_read_b128 v[196:199], v191 offset:52224
	ds_read_b128 v[200:203], v191 offset:53248
	ds_read_b128 v[204:207], v191 offset:54272
	ds_read_b128 v[208:211], v191 offset:55296
	ds_read_b128 v[212:215], v191 offset:56320
	global_load_lds_dwordx4 v[184:185], off
	s_add_i32 m0, s52, 0x2000
	s_add_u32 s50, s50, 0x40080
	v_lshl_add_u64 v[184:185], v[216:217], 0, s[28:29]
	s_addc_u32 s51, s51, 0
	s_add_i32 s52, s63, s68
	global_load_lds_dwordx4 v[184:185], off
	v_lshl_add_u64 v[184:185], s[50:51], 0, v[154:155]
	s_mov_b32 m0, s52
	s_nop 0
	global_load_lds_dwordx4 v[184:185], off
	v_lshl_add_u64 v[184:185], s[50:51], 0, v[158:159]
	s_add_i32 m0, s52, 0x2000
	s_nop 0
	global_load_lds_dwordx4 v[184:185], off
	v_lshl_add_u64 v[184:185], v[218:219], 0, s[28:29]
	s_mov_b32 m0, s75
	s_nop 0
	global_load_lds_dwordx4 v[184:185], off
	v_lshl_add_u64 v[184:185], v[220:221], 0, s[28:29]
	s_mov_b32 m0, s67
	s_nop 0
	global_load_lds_dwordx4 v[184:185], off
	s_waitcnt vmcnt(8)
	s_cmp_lt_u32 s3, 4
	s_cbranch_scc1 .Lgls_63
	s_waitcnt lgkmcnt(0)
.Lgls_63:
	s_barrier
	s_setprio 1
	s_waitcnt lgkmcnt(0)
	v_mfma_f32_16x16x32_bf16 v[60:63], v[128:131], v[176:179], v[60:63]
	v_mfma_f32_16x16x32_bf16 v[56:59], v[136:139], v[176:179], v[56:59]
	v_mfma_f32_16x16x32_bf16 v[44:47], v[128:131], v[192:195], v[44:47]
	v_mfma_f32_16x16x32_bf16 v[40:43], v[136:139], v[192:195], v[40:43]
	v_mfma_f32_16x16x32_bf16 v[28:31], v[128:131], v[200:203], v[28:31]
	v_mfma_f32_16x16x32_bf16 v[24:27], v[136:139], v[200:203], v[24:27]
	v_mfma_f32_16x16x32_bf16 v[12:15], v[128:131], v[208:211], v[12:15]
	v_mfma_f32_16x16x32_bf16 v[8:11], v[136:139], v[208:211], v[8:11]
	v_mfma_f32_16x16x32_bf16 v[60:63], v[132:135], v[180:183], v[60:63]
	v_mfma_f32_16x16x32_bf16 v[56:59], v[140:143], v[180:183], v[56:59]
	v_mfma_f32_16x16x32_bf16 v[44:47], v[132:135], v[196:199], v[44:47]
	v_mfma_f32_16x16x32_bf16 v[40:43], v[140:143], v[196:199], v[40:43]
	v_mfma_f32_16x16x32_bf16 v[28:31], v[132:135], v[204:207], v[28:31]
	v_mfma_f32_16x16x32_bf16 v[24:27], v[140:143], v[204:207], v[24:27]
	v_mfma_f32_16x16x32_bf16 v[12:15], v[132:135], v[212:215], v[12:15]
	v_mfma_f32_16x16x32_bf16 v[8:11], v[140:143], v[212:215], v[8:11]
	s_setprio 0
	s_setprio 1
	v_mfma_f32_16x16x32_bf16 v[52:55], v[144:147], v[176:179], v[52:55]
	v_mfma_f32_16x16x32_bf16 v[48:51], v[168:171], v[176:179], v[48:51]
	v_mfma_f32_16x16x32_bf16 v[36:39], v[144:147], v[192:195], v[36:39]
	v_mfma_f32_16x16x32_bf16 v[32:35], v[168:171], v[192:195], v[32:35]
	v_mfma_f32_16x16x32_bf16 v[20:23], v[144:147], v[200:203], v[20:23]
	v_mfma_f32_16x16x32_bf16 v[16:19], v[168:171], v[200:203], v[16:19]
	v_mfma_f32_16x16x32_bf16 v[4:7], v[144:147], v[208:211], v[4:7]
	v_mfma_f32_16x16x32_bf16 v[0:3], v[168:171], v[208:211], v[0:3]
	v_mfma_f32_16x16x32_bf16 v[52:55], v[148:151], v[180:183], v[52:55]
	v_mfma_f32_16x16x32_bf16 v[48:51], v[172:175], v[180:183], v[48:51]
	v_mfma_f32_16x16x32_bf16 v[36:39], v[148:151], v[196:199], v[36:39]
	v_mfma_f32_16x16x32_bf16 v[32:35], v[172:175], v[196:199], v[32:35]
	v_mfma_f32_16x16x32_bf16 v[20:23], v[148:151], v[204:207], v[20:23]
	v_mfma_f32_16x16x32_bf16 v[16:19], v[172:175], v[204:207], v[16:19]
	v_mfma_f32_16x16x32_bf16 v[4:7], v[148:151], v[212:215], v[4:7]
	v_mfma_f32_16x16x32_bf16 v[0:3], v[172:175], v[212:215], v[0:3]
	s_setprio 0
	s_barrier
	s_add_i32 s61, s61, 2
	s_add_u32 s48, s48, 0x100
	s_addc_u32 s49, s49, 0
	s_add_u32 s47, s47, 0x100
	s_addc_u32 s60, s60, 0
	s_cmp_gt_u32 s61, 13
	s_cbranch_scc0 .LBB0_1832
	s_and_b64 vcc, exec, s[16:17]
	s_cbranch_vccz .LBB0_1835
	s_barrier

; #define PG8_STAGE(bufoff, gbase, voff) do { _Pragma("unroll") for (int _i = 0; _i < 2; ++_i) \
;         __builtin_amdgcn_global_load_lds((const unsigned*)((const char*)(gbase) + (voff)[_i]), (PG8_LAS unsigned*)(lds + (bufoff) + ldsw + _i * 8192), 16, 0, 0); } while (0)
; #define PG8_LDA(dst, b, h) do { _Pragma("unroll") for (int m = 0; m < 4; ++m) _Pragma("unroll") for (int k = 0; k < 2; ++k) dst[m][k] = *(const PG8_LAS bf16x8*)(lds + PG8_SA(b, h) + aoff + m * 2048 + k * 1024); } while (0)
; #define PG8_LDB(dst, b, h) do { _Pragma("unroll") for (int n = 0; n < 2; ++n) _Pragma("unroll") for (int k = 0; k < 2; ++k) dst[n][k] = *(const PG8_LAS bf16x8*)(lds + PG8_SB(b, h) + boff + n * 2048 + k * 1024); } while (0)
; #define PG8_MMA(ai, bj, At, Bt) do { __builtin_amdgcn_s_setprio(1); _Pragma("unroll") for (int m = 0; m < 4; ++m) _Pragma("unroll") for (int n = 0; n < 2; ++n) _Pragma("unroll") for (int k = 0; k < 2; ++k) \
;         acc[ai][bj][m][n] = mma16<F16>(Bt[n][k], At[m][k], acc[ai][bj][m][n]); __builtin_amdgcn_s_setprio(0); } while (0)
; #define PG8_WAIT_V(n) asm volatile("s_waitcnt vmcnt(" #n ")" ::: "memory")
; #define PG8_WAIT_L(n) asm volatile("s_waitcnt lgkmcnt(" #n ")" ::: "memory")
; template <class Epi, class Sched, bool ALIGN_EPI = false, bool SP2 = false, bool F16 = false>
; __device__ __forceinline__ void gemm_phase(PG8_LAS unsigned char* lds, const Gemm g, const Sched& S, const Epi& E, const int wid_in) {
;     ...
;             const bool last = (t == nt - 2);
;             const char* a1 = cA + (size_t)(t + 1) * kstep;
;             const char* a2 = last ? nA : cA + (size_t)(t + 2) * kstep; const char* b2 = last ? nB : cB + (size_t)(t + 2) * kstep;
;             const char* a3 = a2 + kstep; const char* b3 = b2 + kstep;
;             if (last && has_next) S.a_ready(nxt);
;             if constexpr (SP2) {
;             PG8_LDB(B0, 0, 0); PG8_LDB(B1, 0, 1); PG8_SCHED; PG8_LDA(At, 0, 0); PG8_STAGE(PG8_SA(1, 1), a1 + hstep, voffA);
;             PG8_WAIT_V(8); PG8_WAIT_L(0); PG8_BAR; PG8_MMA(0, 0, At, B0); PG8_MMA(0, 1, At, B1); PG8_BAR; PG8_SCHED;
;             PG8_LDA(At, 0, 1); PG8_STAGE(PG8_SB(0, 0), b2, voffB); PG8_STAGE(PG8_SB(0, 1), b2 + hstep, voffB); PG8_STAGE(PG8_SA(0, 0), a2, voffA);
;             PG8_WAIT_V(8); PG8_WAIT_L(0); PG8_BAR; PG8_MMA(1, 0, At, B0); PG8_MMA(1, 1, At, B1); PG8_BAR; PG8_SCHED;
.LBB0_1909:
	ds_read_b128 v[0:3], v193
	ds_read_b128 v[4:7], v193 offset:1024
	ds_read_b128 v[136:139], v193 offset:2048
	ds_read_b128 v[140:143], v193 offset:3072
	ds_read_b128 v[144:147], v194
	ds_read_b128 v[148:151], v194 offset:1024
	ds_read_b128 v[152:155], v194 offset:2048
	ds_read_b128 v[156:159], v194 offset:3072
	s_add_u32 s48, s46, 0xfffc0080
	s_addc_u32 s49, s47, -1
	s_cmp_eq_u32 s64, 12
	s_cselect_b32 s51, s29, s49
	s_cselect_b32 s50, s42, s48
	s_cselect_b32 s49, s27, s63
	s_cselect_b32 s48, s43, s45
	s_mov_b32 m0, s91
	v_lshl_add_u64 v[188:189], s[46:47], 0, v[168:169]
	ds_read_b128 v[176:179], v195
	ds_read_b128 v[180:183], v195 offset:1024
	ds_read_b128 v[184:187], v195 offset:2048
	ds_read_b128 v[198:201], v195 offset:3072
	ds_read_b128 v[202:205], v195 offset:4096
	ds_read_b128 v[206:209], v195 offset:5120
	ds_read_b128 v[210:213], v195 offset:6144
	ds_read_b128 v[214:217], v195 offset:7168
	global_load_lds_dwordx4 v[188:189], off
	v_lshl_add_u64 v[188:189], s[46:47], 0, v[170:171]
	s_add_i32 m0, s74, 0xe000
	s_nop 0
	global_load_lds_dwordx4 v[188:189], off
	s_waitcnt vmcnt(8)
	s_cmp_lt_u32 s3, 4
	s_cbranch_scc1 .Lgls_64
	s_waitcnt lgkmcnt(0)
.Lgls_64:
	s_barrier
	s_setprio 1
	s_waitcnt lgkmcnt(0)
	v_mfma_f32_16x16x32_f16 v[132:135], v[0:3], v[176:179], v[132:135]
	v_mfma_f32_16x16x32_f16 v[128:131], v[136:139], v[176:179], v[128:131]
	v_mfma_f32_16x16x32_f16 v[116:119], v[0:3], v[184:187], v[116:119]
	v_mfma_f32_16x16x32_f16 v[112:115], v[136:139], v[184:187], v[112:115]
	v_mfma_f32_16x16x32_f16 v[100:103], v[0:3], v[202:205], v[100:103]
	v_mfma_f32_16x16x32_f16 v[96:99], v[136:139], v[202:205], v[96:99]
	v_mfma_f32_16x16x32_f16 v[84:87], v[0:3], v[210:213], v[84:87]
	v_mfma_f32_16x16x32_f16 v[80:83], v[136:139], v[210:213], v[80:83]
	v_mfma_f32_16x16x32_f16 v[132:135], v[4:7], v[180:183], v[132:135]
	v_mfma_f32_16x16x32_f16 v[128:131], v[140:143], v[180:183], v[128:131]
	v_mfma_f32_16x16x32_f16 v[116:119], v[4:7], v[198:201], v[116:119]
	v_mfma_f32_16x16x32_f16 v[112:115], v[140:143], v[198:201], v[112:115]
	v_mfma_f32_16x16x32_f16 v[100:103], v[4:7], v[206:209], v[100:103]
	v_mfma_f32_16x16x32_f16 v[96:99], v[140:143], v[206:209], v[96:99]
	v_mfma_f32_16x16x32_f16 v[84:87], v[4:7], v[214:217], v[84:87]
	v_mfma_f32_16x16x32_f16 v[80:83], v[140:143], v[214:217], v[80:83]
	s_setprio 0
	s_setprio 1
	v_mfma_f32_16x16x32_f16 v[124:127], v[144:147], v[176:179], v[124:127]
	v_mfma_f32_16x16x32_f16 v[120:123], v[152:155], v[176:179], v[120:123]
	v_mfma_f32_16x16x32_f16 v[108:111], v[144:147], v[184:187], v[108:111]
	v_mfma_f32_16x16x32_f16 v[104:107], v[152:155], v[184:187], v[104:107]
	v_mfma_f32_16x16x32_f16 v[92:95], v[144:147], v[202:205], v[92:95]
	v_mfma_f32_16x16x32_f16 v[88:91], v[152:155], v[202:205], v[88:91]
	v_mfma_f32_16x16x32_f16 v[76:79], v[144:147], v[210:213], v[76:79]
	v_mfma_f32_16x16x32_f16 v[72:75], v[152:155], v[210:213], v[72:75]
	v_mfma_f32_16x16x32_f16 v[124:127], v[148:151], v[180:183], v[124:127]
	v_mfma_f32_16x16x32_f16 v[120:123], v[156:159], v[180:183], v[120:123]
	v_mfma_f32_16x16x32_f16 v[108:111], v[148:151], v[198:201], v[108:111]
	v_mfma_f32_16x16x32_f16 v[104:107], v[156:159], v[198:201], v[104:107]
	v_mfma_f32_16x16x32_f16 v[92:95], v[148:151], v[206:209], v[92:95]
	v_mfma_f32_16x16x32_f16 v[88:91], v[156:159], v[206:209], v[88:91]
	v_mfma_f32_16x16x32_f16 v[76:79], v[148:151], v[214:217], v[76:79]
	v_mfma_f32_16x16x32_f16 v[72:75], v[156:159], v[214:217], v[72:75]
	s_setprio 0
	s_barrier
	s_add_i32 s65, s60, s68
	v_lshl_add_u64 v[188:189], s[48:49], 0, v[162:163]
	s_mov_b32 m0, s65
	ds_read_b128 v[176:179], v195 offset:16384
	ds_read_b128 v[180:183], v195 offset:17408
	ds_read_b128 v[184:187], v195 offset:18432
	ds_read_b128 v[198:201], v195 offset:19456
	ds_read_b128 v[202:205], v195 offset:20480
	ds_read_b128 v[206:209], v195 offset:21504
	ds_read_b128 v[210:213], v195 offset:22528
	ds_read_b128 v[214:217], v195 offset:23552
	global_load_lds_dwordx4 v[188:189], off
	s_add_i32 m0, s65, 0x2000
	s_add_u32 s84, s48, 0x40000
	v_lshl_add_u64 v[218:219], s[48:49], 0, v[166:167]
	s_addc_u32 s85, s49, 0
	s_add_i32 s65, s61, s68
	global_load_lds_dwordx4 v[218:219], off
	v_lshl_add_u64 v[220:221], s[84:85], 0, v[162:163]
	s_mov_b32 m0, s65
	v_lshl_add_u64 v[222:223], s[50:51], 0, v[164:165]
	global_load_lds_dwordx4 v[220:221], off
	v_lshl_add_u64 v[220:221], s[84:85], 0, v[166:167]
	s_add_i32 m0, s65, 0x2000
	s_nop 0
	global_load_lds_dwordx4 v[220:221], off
	v_lshl_add_u64 v[220:221], s[50:51], 0, v[160:161]
	s_mov_b32 m0, s74
	s_nop 0
	global_load_lds_dwordx4 v[220:221], off
	s_mov_b32 m0, s66
	s_nop 0
	global_load_lds_dwordx4 v[222:223], off
	s_waitcnt vmcnt(8)
	s_cmp_lt_u32 s3, 4
	s_cbranch_scc1 .Lgls_65
	s_waitcnt lgkmcnt(0)
; #define PG8_STAGE(bufoff, gbase, voff) do { _Pragma("unroll") for (int _i = 0; _i < 2; ++_i) \
;         __builtin_amdgcn_global_load_lds((const unsigned*)((const char*)(gbase) + (voff)[_i]), (PG8_LAS unsigned*)(lds + (bufoff) + ldsw + _i * 8192), 16, 0, 0); } while (0)
; #define PG8_LDA(dst, b, h) do { _Pragma("unroll") for (int m = 0; m < 4; ++m) _Pragma("unroll") for (int k = 0; k < 2; ++k) dst[m][k] = *(const PG8_LAS bf16x8*)(lds + PG8_SA(b, h) + aoff + m * 2048 + k * 1024); } while (0)
; #define PG8_LDB(dst, b, h) do { _Pragma("unroll") for (int n = 0; n < 2; ++n) _Pragma("unroll") for (int k = 0; k < 2; ++k) dst[n][k] = *(const PG8_LAS bf16x8*)(lds + PG8_SB(b, h) + boff + n * 2048 + k * 1024); } while (0)
; #define PG8_MMA(ai, bj, At, Bt) do { __builtin_amdgcn_s_setprio(1); _Pragma("unroll") for (int m = 0; m < 4; ++m) _Pragma("unroll") for (int n = 0; n < 2; ++n) _Pragma("unroll") for (int k = 0; k < 2; ++k) \
;         acc[ai][bj][m][n] = mma16<F16>(Bt[n][k], At[m][k], acc[ai][bj][m][n]); __builtin_amdgcn_s_setprio(0); } while (0)
; #define PG8_WAIT_V(n) asm volatile("s_waitcnt vmcnt(" #n ")" ::: "memory")
; #define PG8_WAIT_L(n) asm volatile("s_waitcnt lgkmcnt(" #n ")" ::: "memory")
; #define PG8_BAR __builtin_amdgcn_s_barrier()
; #define PG8_SCHED __builtin_amdgcn_sched_barrier(0)
; template <class Epi, class Sched, bool ALIGN_EPI = false, bool SP2 = false, bool F16 = false>
; __device__ __forceinline__ void gemm_phase(PG8_LAS unsigned char* lds, const Gemm g, const Sched& S, const Epi& E, const int wid_in) {
;     ...
;             PG8_LDA(At, 0, 1); PG8_STAGE(PG8_SB(0, 0), b2, voffB); PG8_STAGE(PG8_SB(0, 1), b2 + hstep, voffB); PG8_STAGE(PG8_SA(0, 0), a2, voffA);
;             PG8_WAIT_V(8); PG8_WAIT_L(0); PG8_BAR; PG8_MMA(1, 0, At, B0); PG8_MMA(1, 1, At, B1); PG8_BAR; PG8_SCHED;
;             PG8_LDB(B0, 1, 0); PG8_LDB(B1, 1, 1); PG8_SCHED; PG8_LDA(At, 1, 0); PG8_STAGE(PG8_SA(0, 1), a2 + hstep, voffA);
;             PG8_WAIT_V(8); PG8_WAIT_L(0); PG8_BAR; PG8_MMA(0, 0, At, B0); PG8_MMA(0, 1, At, B1); PG8_BAR; PG8_SCHED;
;             PG8_LDA(At, 1, 1); PG8_STAGE(PG8_SB(1, 0), b3, voffB); PG8_STAGE(PG8_SB(1, 1), b3 + hstep, voffB); PG8_STAGE(PG8_SA(1, 0), a3, voffA);
.Lgls_65:
	s_barrier
	s_setprio 1
	s_waitcnt lgkmcnt(0)
	v_mfma_f32_16x16x32_f16 v[68:71], v[0:3], v[176:179], v[68:71]
	v_mfma_f32_16x16x32_f16 v[64:67], v[136:139], v[176:179], v[64:67]
	v_mfma_f32_16x16x32_f16 v[52:55], v[0:3], v[184:187], v[52:55]
	v_mfma_f32_16x16x32_f16 v[48:51], v[136:139], v[184:187], v[48:51]
	v_mfma_f32_16x16x32_f16 v[36:39], v[0:3], v[202:205], v[36:39]
	v_mfma_f32_16x16x32_f16 v[32:35], v[136:139], v[202:205], v[32:35]
	v_mfma_f32_16x16x32_f16 v[0:3], v[0:3], v[210:213], v[20:23]
	v_mfma_f32_16x16x32_f16 v[68:71], v[4:7], v[180:183], v[68:71]
	v_mfma_f32_16x16x32_f16 v[64:67], v[140:143], v[180:183], v[64:67]
	v_mfma_f32_16x16x32_f16 v[52:55], v[4:7], v[198:201], v[52:55]
	v_mfma_f32_16x16x32_f16 v[48:51], v[140:143], v[198:201], v[48:51]
	v_mfma_f32_16x16x32_f16 v[36:39], v[4:7], v[206:209], v[36:39]
	v_mfma_f32_16x16x32_f16 v[32:35], v[140:143], v[206:209], v[32:35]
	v_mfma_f32_16x16x32_f16 v[0:3], v[4:7], v[214:217], v[0:3]
	v_mfma_f32_16x16x32_f16 v[4:7], v[136:139], v[210:213], v[16:19]
	v_mfma_f32_16x16x32_f16 v[4:7], v[140:143], v[214:217], v[4:7]
	s_setprio 0
	s_setprio 1
	v_mfma_f32_16x16x32_f16 v[16:19], v[144:147], v[176:179], v[60:63]
	v_mfma_f32_16x16x32_f16 v[60:63], v[148:151], v[180:183], v[16:19]
	v_mfma_f32_16x16x32_f16 v[16:19], v[152:155], v[176:179], v[56:59]
	v_mfma_f32_16x16x32_f16 v[56:59], v[156:159], v[180:183], v[16:19]
	v_mfma_f32_16x16x32_f16 v[16:19], v[144:147], v[184:187], v[44:47]
	v_mfma_f32_16x16x32_f16 v[44:47], v[148:151], v[198:201], v[16:19]
	v_mfma_f32_16x16x32_f16 v[16:19], v[152:155], v[184:187], v[40:43]
	v_mfma_f32_16x16x32_f16 v[40:43], v[156:159], v[198:201], v[16:19]
	v_mfma_f32_16x16x32_f16 v[16:19], v[144:147], v[202:205], v[28:31]
	v_mfma_f32_16x16x32_f16 v[28:31], v[148:151], v[206:209], v[16:19]
	v_mfma_f32_16x16x32_f16 v[16:19], v[152:155], v[202:205], v[24:27]
	v_mfma_f32_16x16x32_f16 v[12:15], v[144:147], v[210:213], v[12:15]
	v_mfma_f32_16x16x32_f16 v[8:11], v[152:155], v[210:213], v[8:11]
	v_mfma_f32_16x16x32_f16 v[24:27], v[156:159], v[206:209], v[16:19]
	v_mfma_f32_16x16x32_f16 v[12:15], v[148:151], v[214:217], v[12:15]
	v_mfma_f32_16x16x32_f16 v[8:11], v[156:159], v[214:217], v[8:11]
	s_setprio 0
	s_barrier
	s_add_i32 s65, 0, 0x18000
	s_add_i32 s76, 0, 0x1c000
	v_add_u32_e32 v140, s65, v192
	v_add_u32_e32 v156, s76, v192
	ds_read_b128 v[16:19], v140
	ds_read_b128 v[20:23], v140 offset:1024
	ds_read_b128 v[136:139], v140 offset:2048
	ds_read_b128 v[140:143], v140 offset:3072
	ds_read_b128 v[144:147], v156
	ds_read_b128 v[148:151], v156 offset:1024
	ds_read_b128 v[152:155], v156 offset:2048
	ds_read_b128 v[156:159], v156 offset:3072
	s_add_u32 s50, s50, 0x40000
	s_addc_u32 s51, s51, 0
	s_mov_b32 m0, s90
	v_lshl_add_u64 v[224:225], s[50:51], 0, v[160:161]
	ds_read_b128 v[176:179], v195 offset:32768
	ds_read_b128 v[180:183], v195 offset:33792
	ds_read_b128 v[184:187], v195 offset:34816
	ds_read_b128 v[198:201], v195 offset:35840
	ds_read_b128 v[202:205], v195 offset:36864
	ds_read_b128 v[206:209], v195 offset:37888
	ds_read_b128 v[210:213], v195 offset:38912
	ds_read_b128 v[214:217], v195 offset:39936
	global_load_lds_dwordx4 v[224:225], off
	v_lshl_add_u64 v[224:225], s[50:51], 0, v[164:165]
	s_mov_b32 m0, s37
	s_nop 0
	global_load_lds_dwordx4 v[224:225], off
	s_waitcnt vmcnt(8)
	s_cmp_lt_u32 s3, 4
	s_cbranch_scc1 .Lgls_66
	s_waitcnt lgkmcnt(0)
; #define PG8_STAGE(bufoff, gbase, voff) do { _Pragma("unroll") for (int _i = 0; _i < 2; ++_i) \
;         __builtin_amdgcn_global_load_lds((const unsigned*)((const char*)(gbase) + (voff)[_i]), (PG8_LAS unsigned*)(lds + (bufoff) + ldsw + _i * 8192), 16, 0, 0); } while (0)
; #define PG8_LDA(dst, b, h) do { _Pragma("unroll") for (int m = 0; m < 4; ++m) _Pragma("unroll") for (int k = 0; k < 2; ++k) dst[m][k] = *(const PG8_LAS bf16x8*)(lds + PG8_SA(b, h) + aoff + m * 2048 + k * 1024); } while (0)
; #define PG8_MMA(ai, bj, At, Bt) do { __builtin_amdgcn_s_setprio(1); _Pragma("unroll") for (int m = 0; m < 4; ++m) _Pragma("unroll") for (int n = 0; n < 2; ++n) _Pragma("unroll") for (int k = 0; k < 2; ++k) \
;         acc[ai][bj][m][n] = mma16<F16>(Bt[n][k], At[m][k], acc[ai][bj][m][n]); __builtin_amdgcn_s_setprio(0); } while (0)
; #define PG8_WAIT_V(n) asm volatile("s_waitcnt vmcnt(" #n ")" ::: "memory")
; #define PG8_WAIT_L(n) asm volatile("s_waitcnt lgkmcnt(" #n ")" ::: "memory")
; #define PG8_BAR __builtin_amdgcn_s_barrier()
; #define PG8_SCHED __builtin_amdgcn_sched_barrier(0)
; template <class Epi, class Sched, bool ALIGN_EPI = false, bool SP2 = false, bool F16 = false>
; __device__ __forceinline__ void gemm_phase(PG8_LAS unsigned char* lds, const Gemm g, const Sched& S, const Epi& E, const int wid_in) {
;     ...
;         for (int t = 0; t < nt; t += 2) {
;     ...
;             PG8_LDA(At, 1, 1); PG8_STAGE(PG8_SB(1, 0), b3, voffB); PG8_STAGE(PG8_SB(1, 1), b3 + hstep, voffB); PG8_STAGE(PG8_SA(1, 0), a3, voffA);
;             PG8_WAIT_V(8); PG8_WAIT_L(0); PG8_BAR; PG8_MMA(1, 0, At, B0); PG8_MMA(1, 1, At, B1); PG8_BAR; PG8_SCHED;
.Lgls_66:
	s_barrier
	s_setprio 1
	s_waitcnt lgkmcnt(0)
	v_mfma_f32_16x16x32_f16 v[132:135], v[16:19], v[176:179], v[132:135]
	v_mfma_f32_16x16x32_f16 v[128:131], v[136:139], v[176:179], v[128:131]
	v_mfma_f32_16x16x32_f16 v[116:119], v[16:19], v[184:187], v[116:119]
	v_mfma_f32_16x16x32_f16 v[112:115], v[136:139], v[184:187], v[112:115]
	v_mfma_f32_16x16x32_f16 v[100:103], v[16:19], v[202:205], v[100:103]
	v_mfma_f32_16x16x32_f16 v[96:99], v[136:139], v[202:205], v[96:99]
	v_mfma_f32_16x16x32_f16 v[84:87], v[16:19], v[210:213], v[84:87]
	v_mfma_f32_16x16x32_f16 v[80:83], v[136:139], v[210:213], v[80:83]
	v_mfma_f32_16x16x32_f16 v[132:135], v[20:23], v[180:183], v[132:135]
	v_mfma_f32_16x16x32_f16 v[128:131], v[140:143], v[180:183], v[128:131]
	v_mfma_f32_16x16x32_f16 v[116:119], v[20:23], v[198:201], v[116:119]
	v_mfma_f32_16x16x32_f16 v[112:115], v[140:143], v[198:201], v[112:115]
	v_mfma_f32_16x16x32_f16 v[100:103], v[20:23], v[206:209], v[100:103]
	v_mfma_f32_16x16x32_f16 v[96:99], v[140:143], v[206:209], v[96:99]
	v_mfma_f32_16x16x32_f16 v[84:87], v[20:23], v[214:217], v[84:87]
	v_mfma_f32_16x16x32_f16 v[80:83], v[140:143], v[214:217], v[80:83]
	s_setprio 0
	s_setprio 1
	v_mfma_f32_16x16x32_f16 v[124:127], v[144:147], v[176:179], v[124:127]
	v_mfma_f32_16x16x32_f16 v[120:123], v[152:155], v[176:179], v[120:123]
	v_mfma_f32_16x16x32_f16 v[108:111], v[144:147], v[184:187], v[108:111]
	v_mfma_f32_16x16x32_f16 v[104:107], v[152:155], v[184:187], v[104:107]
	v_mfma_f32_16x16x32_f16 v[92:95], v[144:147], v[202:205], v[92:95]
	v_mfma_f32_16x16x32_f16 v[88:91], v[152:155], v[202:205], v[88:91]
	v_mfma_f32_16x16x32_f16 v[76:79], v[144:147], v[210:213], v[76:79]
	v_mfma_f32_16x16x32_f16 v[72:75], v[152:155], v[210:213], v[72:75]
	v_mfma_f32_16x16x32_f16 v[124:127], v[148:151], v[180:183], v[124:127]
	v_mfma_f32_16x16x32_f16 v[120:123], v[156:159], v[180:183], v[120:123]
	v_mfma_f32_16x16x32_f16 v[108:111], v[148:151], v[198:201], v[108:111]
	v_mfma_f32_16x16x32_f16 v[104:107], v[156:159], v[198:201], v[104:107]
	v_mfma_f32_16x16x32_f16 v[92:95], v[148:151], v[206:209], v[92:95]
	v_mfma_f32_16x16x32_f16 v[88:91], v[156:159], v[206:209], v[88:91]
	v_mfma_f32_16x16x32_f16 v[76:79], v[148:151], v[214:217], v[76:79]
	v_mfma_f32_16x16x32_f16 v[72:75], v[156:159], v[214:217], v[72:75]
	s_setprio 0
	s_barrier
	s_add_i32 s50, s65, s68
	v_lshl_add_u64 v[188:189], v[188:189], 0, s[24:25]
	s_mov_b32 m0, s50
	ds_read_b128 v[176:179], v195 offset:49152
	ds_read_b128 v[180:183], v195 offset:50176
	ds_read_b128 v[184:187], v195 offset:51200
	ds_read_b128 v[198:201], v195 offset:52224
	ds_read_b128 v[202:205], v195 offset:53248
	ds_read_b128 v[206:209], v195 offset:54272
	ds_read_b128 v[210:213], v195 offset:55296
	ds_read_b128 v[214:217], v195 offset:56320
	global_load_lds_dwordx4 v[188:189], off
	s_add_i32 m0, s50, 0x2000
	s_add_u32 s48, s48, 0x40080
	v_lshl_add_u64 v[188:189], v[218:219], 0, s[24:25]
	s_addc_u32 s49, s49, 0
	s_add_i32 s50, s76, s68
	global_load_lds_dwordx4 v[188:189], off
	v_lshl_add_u64 v[188:189], s[48:49], 0, v[162:163]
	s_mov_b32 m0, s50
	s_nop 0
	global_load_lds_dwordx4 v[188:189], off
	v_lshl_add_u64 v[188:189], s[48:49], 0, v[166:167]
	s_add_i32 m0, s50, 0x2000
	s_nop 0
	global_load_lds_dwordx4 v[188:189], off
	v_lshl_add_u64 v[188:189], v[220:221], 0, s[24:25]
	s_mov_b32 m0, s75
	s_nop 0
	global_load_lds_dwordx4 v[188:189], off
	v_lshl_add_u64 v[188:189], v[222:223], 0, s[24:25]
	s_mov_b32 m0, s67
	s_nop 0
	global_load_lds_dwordx4 v[188:189], off
	s_waitcnt vmcnt(8)
	s_cmp_lt_u32 s3, 4
	s_cbranch_scc1 .Lgls_67
	s_waitcnt lgkmcnt(0)
.Lgls_67:
	s_barrier
	s_setprio 1
	s_waitcnt lgkmcnt(0)
	v_mfma_f32_16x16x32_f16 v[68:71], v[16:19], v[176:179], v[68:71]
	v_mfma_f32_16x16x32_f16 v[52:55], v[16:19], v[184:187], v[52:55]
	v_mfma_f32_16x16x32_f16 v[36:39], v[16:19], v[202:205], v[36:39]
	v_mfma_f32_16x16x32_f16 v[0:3], v[16:19], v[210:213], v[0:3]
	v_mfma_f32_16x16x32_f16 v[68:71], v[20:23], v[180:183], v[68:71]
	v_mfma_f32_16x16x32_f16 v[64:67], v[136:139], v[176:179], v[64:67]
	v_mfma_f32_16x16x32_f16 v[52:55], v[20:23], v[198:201], v[52:55]
	v_mfma_f32_16x16x32_f16 v[48:51], v[136:139], v[184:187], v[48:51]
	v_mfma_f32_16x16x32_f16 v[36:39], v[20:23], v[206:209], v[36:39]
	v_mfma_f32_16x16x32_f16 v[32:35], v[136:139], v[202:205], v[32:35]
	v_mfma_f32_16x16x32_f16 v[20:23], v[20:23], v[214:217], v[0:3]
	v_mfma_f32_16x16x32_f16 v[0:3], v[136:139], v[210:213], v[4:7]
	v_mfma_f32_16x16x32_f16 v[64:67], v[140:143], v[180:183], v[64:67]
	v_mfma_f32_16x16x32_f16 v[48:51], v[140:143], v[198:201], v[48:51]
	v_mfma_f32_16x16x32_f16 v[32:35], v[140:143], v[206:209], v[32:35]
	v_mfma_f32_16x16x32_f16 v[16:19], v[140:143], v[214:217], v[0:3]
	s_setprio 0
	s_setprio 1
	v_mfma_f32_16x16x32_f16 v[0:3], v[144:147], v[176:179], v[60:63]
	v_mfma_f32_16x16x32_f16 v[60:63], v[148:151], v[180:183], v[0:3]
	v_mfma_f32_16x16x32_f16 v[0:3], v[152:155], v[176:179], v[56:59]
	v_mfma_f32_16x16x32_f16 v[56:59], v[156:159], v[180:183], v[0:3]
	v_mfma_f32_16x16x32_f16 v[0:3], v[144:147], v[184:187], v[44:47]
	v_mfma_f32_16x16x32_f16 v[44:47], v[148:151], v[198:201], v[0:3]
	v_mfma_f32_16x16x32_f16 v[0:3], v[152:155], v[184:187], v[40:43]
	v_mfma_f32_16x16x32_f16 v[40:43], v[156:159], v[198:201], v[0:3]
	v_mfma_f32_16x16x32_f16 v[0:3], v[144:147], v[202:205], v[28:31]
	v_mfma_f32_16x16x32_f16 v[28:31], v[148:151], v[206:209], v[0:3]
	v_mfma_f32_16x16x32_f16 v[0:3], v[152:155], v[202:205], v[24:27]
	v_mfma_f32_16x16x32_f16 v[24:27], v[156:159], v[206:209], v[0:3]
	v_mfma_f32_16x16x32_f16 v[0:3], v[144:147], v[210:213], v[12:15]
	v_mfma_f32_16x16x32_f16 v[12:15], v[148:151], v[214:217], v[0:3]
	v_mfma_f32_16x16x32_f16 v[0:3], v[152:155], v[210:213], v[8:11]
	v_mfma_f32_16x16x32_f16 v[8:11], v[156:159], v[214:217], v[0:3]
	s_setprio 0
	s_barrier
	s_add_i32 s64, s64, 2
	s_add_u32 s46, s46, 0x100
	s_addc_u32 s47, s47, 0
	s_add_u32 s45, s45, 0x100
	s_addc_u32 s63, s63, 0
	s_cmp_gt_u32 s64, 13
	s_cbranch_scc0 .LBB0_1909
	s_and_b64 vcc, exec, s[16:17]
	s_cbranch_vccz .LBB0_1912
	s_barrier

; #define PG8_STAGE(bufoff, gbase, voff) do { _Pragma("unroll") for (int _i = 0; _i < 2; ++_i) \
;         __builtin_amdgcn_global_load_lds((const unsigned*)((const char*)(gbase) + (voff)[_i]), (PG8_LAS unsigned*)(lds + (bufoff) + ldsw + _i * 8192), 16, 0, 0); } while (0)
; #define PG8_LDA(dst, b, h) do { _Pragma("unroll") for (int m = 0; m < 4; ++m) _Pragma("unroll") for (int k = 0; k < 2; ++k) dst[m][k] = *(const PG8_LAS bf16x8*)(lds + PG8_SA(b, h) + aoff + m * 2048 + k * 1024); } while (0)
; #define PG8_LDB(dst, b, h) do { _Pragma("unroll") for (int n = 0; n < 2; ++n) _Pragma("unroll") for (int k = 0; k < 2; ++k) dst[n][k] = *(const PG8_LAS bf16x8*)(lds + PG8_SB(b, h) + boff + n * 2048 + k * 1024); } while (0)
; #define PG8_WAIT_V(n) asm volatile("s_waitcnt vmcnt(" #n ")" ::: "memory")
; #define PG8_WAIT_L(n) asm volatile("s_waitcnt lgkmcnt(" #n ")" ::: "memory")
; #define PG8_BAR __builtin_amdgcn_s_barrier()
; #define PG8_SCHED __builtin_amdgcn_sched_barrier(0)
; template <class Epi, class Sched, bool ALIGN_EPI = false, bool SP2 = false, bool F16 = false>
; __device__ __forceinline__ void gemm_phase(PG8_LAS unsigned char* lds, const Gemm g, const Sched& S, const Epi& E, const int wid_in) {
;     ...
;         const bool has_next = S.next(ui + 1, nxt);
;         const char* nA = has_next ? (const char*)g.A + (size_t)nxt.pm * tstep : cA; const char* nB = has_next ? (const char*)g.Bt + (size_t)nxt.pn * tstep : cB;
;         for (int t = 0; t < nt; t += 2) {
;             const bool last = (t == nt - 2);
;             const char* a1 = cA + (size_t)(t + 1) * kstep;
;             const char* a2 = last ? nA : cA + (size_t)(t + 2) * kstep; const char* b2 = last ? nB : cB + (size_t)(t + 2) * kstep;
;             const char* a3 = a2 + kstep; const char* b3 = b2 + kstep;
;             if (last && has_next) S.a_ready(nxt);
;             if constexpr (SP2) {
;             PG8_LDB(B0, 0, 0); PG8_LDB(B1, 0, 1); PG8_SCHED; PG8_LDA(At, 0, 0); PG8_STAGE(PG8_SA(1, 1), a1 + hstep, voffA);
;             PG8_WAIT_V(8); PG8_WAIT_L(0); PG8_BAR; PG8_MMA(0, 0, At, B0); PG8_MMA(0, 1, At, B1); PG8_BAR; PG8_SCHED;
;             PG8_LDA(At, 0, 1); PG8_STAGE(PG8_SB(0, 0), b2, voffB); PG8_STAGE(PG8_SB(0, 1), b2 + hstep, voffB); PG8_STAGE(PG8_SA(0, 0), a2, voffA);
;             PG8_WAIT_V(8); PG8_WAIT_L(0); PG8_BAR; PG8_MMA(1, 0, At, B0); PG8_MMA(1, 1, At, B1); PG8_BAR; PG8_SCHED;
.LBB0_1944:
	s_mov_b64 s[48:49], s[10:11]
	s_add_i32 s10, s36, s19
	s_mov_b64 s[46:47], s[12:13]
	s_mov_b32 s12, s58
	s_mov_b32 s13, s57
	s_and_b32 s57, s10, 3
	s_ashr_i32 s58, s10, 2
	s_and_b64 s[10:11], s[30:31], exec
	s_cselect_b32 s12, s58, s12
	ds_read_b128 v[0:3], v134
	ds_read_b128 v[4:7], v134 offset:1024
	ds_read_b128 v[8:11], v134 offset:2048
	ds_read_b128 v[12:15], v134 offset:3072
	ds_read_b128 v[16:19], v135
	ds_read_b128 v[20:23], v135 offset:1024
	ds_read_b128 v[24:27], v135 offset:2048
	ds_read_b128 v[28:31], v135 offset:3072
	s_cselect_b32 s10, s57, s13
	s_ashr_i32 s13, s12, 31
	s_lshl_b64 s[12:13], s[12:13], 17
	s_add_u32 s12, s21, s12
	s_addc_u32 s13, s40, s13
	s_and_b64 s[36:37], s[30:31], exec
	s_cselect_b32 s45, s13, s47
	s_cselect_b32 s44, s12, s46
	s_ashr_i32 s11, s10, 31
	s_lshl_b64 s[10:11], s[10:11], 17
	s_add_u32 s10, s41, s10
	s_addc_u32 s11, s42, s11
	s_and_b64 s[36:37], s[30:31], exec
	s_cselect_b32 s37, s11, s49
	s_cselect_b32 s36, s10, s48
	s_add_u32 s60, s46, 0x10080
	s_addc_u32 s61, s47, 0
	s_mov_b32 m0, s91
	v_lshl_add_u64 v[64:65], s[60:61], 0, v[130:131]
	ds_read_b128 v[32:35], v136
	ds_read_b128 v[36:39], v136 offset:1024
	ds_read_b128 v[40:43], v136 offset:2048
	ds_read_b128 v[44:47], v136 offset:3072
	ds_read_b128 v[48:51], v136 offset:4096
	ds_read_b128 v[52:55], v136 offset:5120
	ds_read_b128 v[56:59], v136 offset:6144
	ds_read_b128 v[60:63], v136 offset:7168
	global_load_lds_dwordx4 v[64:65], off
	v_lshl_add_u64 v[64:65], s[60:61], 0, v[128:129]
	s_mov_b32 m0, s14
	s_nop 0
	global_load_lds_dwordx4 v[64:65], off
	s_waitcnt vmcnt(8)
	s_cmp_lt_u32 s3, 4
	s_cbranch_scc1 .Lgls_68
	s_waitcnt lgkmcnt(0)
.Lgls_68:
	s_barrier
	s_setprio 1
	s_waitcnt lgkmcnt(0)
	v_mfma_f32_16x16x32_bf16 v[64:67], v[0:3], v[32:35], 0
	v_mfma_f32_16x16x32_bf16 v[68:71], v[8:11], v[32:35], 0
	v_mfma_f32_16x16x32_bf16 v[72:75], v[0:3], v[40:43], 0
	v_mfma_f32_16x16x32_bf16 v[76:79], v[8:11], v[40:43], 0
	v_mfma_f32_16x16x32_bf16 v[80:83], v[0:3], v[48:51], 0
	v_mfma_f32_16x16x32_bf16 v[84:87], v[8:11], v[48:51], 0
	v_mfma_f32_16x16x32_bf16 v[88:91], v[0:3], v[56:59], 0
	v_mfma_f32_16x16x32_bf16 v[92:95], v[8:11], v[56:59], 0
	v_mfma_f32_16x16x32_bf16 v[64:67], v[4:7], v[36:39], v[64:67]
	v_mfma_f32_16x16x32_bf16 v[68:71], v[12:15], v[36:39], v[68:71]
	v_mfma_f32_16x16x32_bf16 v[72:75], v[4:7], v[44:47], v[72:75]
	v_mfma_f32_16x16x32_bf16 v[76:79], v[12:15], v[44:47], v[76:79]
	v_mfma_f32_16x16x32_bf16 v[80:83], v[4:7], v[52:55], v[80:83]
	v_mfma_f32_16x16x32_bf16 v[84:87], v[12:15], v[52:55], v[84:87]
	v_mfma_f32_16x16x32_bf16 v[88:91], v[4:7], v[60:63], v[88:91]
	v_mfma_f32_16x16x32_bf16 v[92:95], v[12:15], v[60:63], v[92:95]
	s_setprio 0
	s_setprio 1
	v_mfma_f32_16x16x32_bf16 v[96:99], v[16:19], v[32:35], 0
	v_mfma_f32_16x16x32_bf16 v[32:35], v[24:27], v[32:35], 0
	v_mfma_f32_16x16x32_bf16 v[96:99], v[20:23], v[36:39], v[96:99]
	v_mfma_f32_16x16x32_bf16 v[32:35], v[28:31], v[36:39], v[32:35]
	v_mfma_f32_16x16x32_bf16 v[36:39], v[16:19], v[40:43], 0
	v_mfma_f32_16x16x32_bf16 v[40:43], v[24:27], v[40:43], 0
	v_mfma_f32_16x16x32_bf16 v[36:39], v[20:23], v[44:47], v[36:39]
	v_mfma_f32_16x16x32_bf16 v[40:43], v[28:31], v[44:47], v[40:43]
	v_mfma_f32_16x16x32_bf16 v[44:47], v[16:19], v[48:51], 0
	v_mfma_f32_16x16x32_bf16 v[48:51], v[24:27], v[48:51], 0
	v_mfma_f32_16x16x32_bf16 v[44:47], v[20:23], v[52:55], v[44:47]
	v_mfma_f32_16x16x32_bf16 v[48:51], v[28:31], v[52:55], v[48:51]
	v_mfma_f32_16x16x32_bf16 v[52:55], v[16:19], v[56:59], 0
	v_mfma_f32_16x16x32_bf16 v[56:59], v[24:27], v[56:59], 0
	v_mfma_f32_16x16x32_bf16 v[52:55], v[20:23], v[60:63], v[52:55]
	v_mfma_f32_16x16x32_bf16 v[56:59], v[28:31], v[60:63], v[56:59]
	s_setprio 0
	s_barrier
	v_lshl_add_u64 v[204:205], s[48:49], 0, v[130:131]
	s_mov_b32 m0, s15
	v_lshl_add_u64 v[140:141], v[204:205], 0, s[26:27]
	v_lshl_add_u64 v[206:207], s[48:49], 0, v[128:129]
	s_add_u32 s60, s48, 0x10100
	ds_read_b128 v[60:63], v136 offset:16384
	ds_read_b128 v[100:103], v136 offset:17408
	ds_read_b128 v[104:107], v136 offset:18432
	ds_read_b128 v[108:111], v136 offset:19456
	ds_read_b128 v[112:115], v136 offset:20480
	ds_read_b128 v[116:119], v136 offset:21504
	ds_read_b128 v[120:123], v136 offset:22528
	ds_read_b128 v[124:127], v136 offset:23552
	global_load_lds_dwordx4 v[140:141], off
	v_lshl_add_u64 v[140:141], v[206:207], 0, s[26:27]
	s_mov_b32 m0, s50
	s_addc_u32 s61, s49, 0
	global_load_lds_dwordx4 v[140:141], off
	v_lshl_add_u64 v[140:141], s[60:61], 0, v[130:131]
	s_mov_b32 m0, s51
	v_lshl_add_u64 v[208:209], s[46:47], 0, v[130:131]
	global_load_lds_dwordx4 v[140:141], off
	v_lshl_add_u64 v[140:141], s[60:61], 0, v[128:129]
	s_mov_b32 m0, s52
	v_lshl_add_u64 v[210:211], s[46:47], 0, v[128:129]
	global_load_lds_dwordx4 v[140:141], off
	v_lshl_add_u64 v[140:141], v[208:209], 0, s[26:27]
	s_mov_b32 m0, s74
	s_nop 0
	global_load_lds_dwordx4 v[140:141], off
	v_lshl_add_u64 v[140:141], v[210:211], 0, s[26:27]
	s_mov_b32 m0, s66
	s_nop 0
	global_load_lds_dwordx4 v[140:141], off
	s_waitcnt vmcnt(8)
	s_cmp_lt_u32 s3, 4
	s_cbranch_scc1 .Lgls_69
	s_waitcnt lgkmcnt(0)
; #define PG8_STAGE(bufoff, gbase, voff) do { _Pragma("unroll") for (int _i = 0; _i < 2; ++_i) \
;         __builtin_amdgcn_global_load_lds((const unsigned*)((const char*)(gbase) + (voff)[_i]), (PG8_LAS unsigned*)(lds + (bufoff) + ldsw + _i * 8192), 16, 0, 0); } while (0)
; #define PG8_LDA(dst, b, h) do { _Pragma("unroll") for (int m = 0; m < 4; ++m) _Pragma("unroll") for (int k = 0; k < 2; ++k) dst[m][k] = *(const PG8_LAS bf16x8*)(lds + PG8_SA(b, h) + aoff + m * 2048 + k * 1024); } while (0)
; #define PG8_LDB(dst, b, h) do { _Pragma("unroll") for (int n = 0; n < 2; ++n) _Pragma("unroll") for (int k = 0; k < 2; ++k) dst[n][k] = *(const PG8_LAS bf16x8*)(lds + PG8_SB(b, h) + boff + n * 2048 + k * 1024); } while (0)
; #define PG8_MMA(ai, bj, At, Bt) do { __builtin_amdgcn_s_setprio(1); _Pragma("unroll") for (int m = 0; m < 4; ++m) _Pragma("unroll") for (int n = 0; n < 2; ++n) _Pragma("unroll") for (int k = 0; k < 2; ++k) \
;         acc[ai][bj][m][n] = mma16<F16>(Bt[n][k], At[m][k], acc[ai][bj][m][n]); __builtin_amdgcn_s_setprio(0); } while (0)
; #define PG8_WAIT_V(n) asm volatile("s_waitcnt vmcnt(" #n ")" ::: "memory")
; #define PG8_WAIT_L(n) asm volatile("s_waitcnt lgkmcnt(" #n ")" ::: "memory")
; #define PG8_BAR __builtin_amdgcn_s_barrier()
; template <class Epi, class Sched, bool ALIGN_EPI = false, bool SP2 = false, bool F16 = false>
; __device__ __forceinline__ void gemm_phase(PG8_LAS unsigned char* lds, const Gemm g, const Sched& S, const Epi& E, const int wid_in) {
;     ...
;             PG8_WAIT_V(8); PG8_WAIT_L(0); PG8_BAR; PG8_MMA(0, 0, At, B0); PG8_MMA(0, 1, At, B1); PG8_BAR; PG8_SCHED;
;             PG8_LDA(At, 0, 1); PG8_STAGE(PG8_SB(0, 0), b2, voffB); PG8_STAGE(PG8_SB(0, 1), b2 + hstep, voffB); PG8_STAGE(PG8_SA(0, 0), a2, voffA);
;             PG8_WAIT_V(8); PG8_WAIT_L(0); PG8_BAR; PG8_MMA(1, 0, At, B0); PG8_MMA(1, 1, At, B1); PG8_BAR; PG8_SCHED;
;             PG8_LDB(B0, 1, 0); PG8_LDB(B1, 1, 1); PG8_SCHED; PG8_LDA(At, 1, 0); PG8_STAGE(PG8_SA(0, 1), a2 + hstep, voffA);
;             PG8_WAIT_V(8); PG8_WAIT_L(0); PG8_BAR; PG8_MMA(0, 0, At, B0); PG8_MMA(0, 1, At, B1); PG8_BAR; PG8_SCHED;
;             PG8_LDA(At, 1, 1); PG8_STAGE(PG8_SB(1, 0), b3, voffB); PG8_STAGE(PG8_SB(1, 1), b3 + hstep, voffB); PG8_STAGE(PG8_SA(1, 0), a3, voffA);
;             PG8_WAIT_V(8); PG8_WAIT_L(0); PG8_BAR; PG8_MMA(1, 0, At, B0); PG8_MMA(1, 1, At, B1); PG8_BAR; PG8_SCHED;
.Lgls_69:
	s_barrier
	s_setprio 1
	s_waitcnt lgkmcnt(0)
	v_mfma_f32_16x16x32_bf16 v[140:143], v[0:3], v[60:63], 0
	v_mfma_f32_16x16x32_bf16 v[148:151], v[0:3], v[104:107], 0
	v_mfma_f32_16x16x32_bf16 v[156:159], v[0:3], v[112:115], 0
	v_mfma_f32_16x16x32_bf16 v[0:3], v[0:3], v[120:123], 0
	v_mfma_f32_16x16x32_bf16 v[140:143], v[4:7], v[100:103], v[140:143]
	v_mfma_f32_16x16x32_bf16 v[148:151], v[4:7], v[108:111], v[148:151]
	v_mfma_f32_16x16x32_bf16 v[156:159], v[4:7], v[116:119], v[156:159]
	v_mfma_f32_16x16x32_bf16 v[0:3], v[4:7], v[124:127], v[0:3]
	v_mfma_f32_16x16x32_bf16 v[4:7], v[8:11], v[120:123], 0
	v_mfma_f32_16x16x32_bf16 v[144:147], v[8:11], v[60:63], 0
	v_mfma_f32_16x16x32_bf16 v[152:155], v[8:11], v[104:107], 0
	v_mfma_f32_16x16x32_bf16 v[160:163], v[8:11], v[112:115], 0
	v_mfma_f32_16x16x32_bf16 v[4:7], v[12:15], v[124:127], v[4:7]
	v_mfma_f32_16x16x32_bf16 v[144:147], v[12:15], v[100:103], v[144:147]
	v_mfma_f32_16x16x32_bf16 v[152:155], v[12:15], v[108:111], v[152:155]
	v_mfma_f32_16x16x32_bf16 v[160:163], v[12:15], v[116:119], v[160:163]
	s_setprio 0
	s_setprio 1
	v_mfma_f32_16x16x32_bf16 v[8:11], v[16:19], v[60:63], 0
	v_mfma_f32_16x16x32_bf16 v[12:15], v[24:27], v[60:63], 0
	v_mfma_f32_16x16x32_bf16 v[8:11], v[20:23], v[100:103], v[8:11]
	v_mfma_f32_16x16x32_bf16 v[12:15], v[28:31], v[100:103], v[12:15]
	v_mfma_f32_16x16x32_bf16 v[60:63], v[16:19], v[104:107], 0
	v_mfma_f32_16x16x32_bf16 v[100:103], v[24:27], v[104:107], 0
	v_mfma_f32_16x16x32_bf16 v[104:107], v[16:19], v[112:115], 0
	v_mfma_f32_16x16x32_bf16 v[16:19], v[16:19], v[120:123], 0
	v_mfma_f32_16x16x32_bf16 v[60:63], v[20:23], v[108:111], v[60:63]
	v_mfma_f32_16x16x32_bf16 v[100:103], v[28:31], v[108:111], v[100:103]
	v_mfma_f32_16x16x32_bf16 v[104:107], v[20:23], v[116:119], v[104:107]
	v_mfma_f32_16x16x32_bf16 v[108:111], v[24:27], v[112:115], 0
	v_mfma_f32_16x16x32_bf16 v[16:19], v[20:23], v[124:127], v[16:19]
	v_mfma_f32_16x16x32_bf16 v[20:23], v[24:27], v[120:123], 0
	v_mfma_f32_16x16x32_bf16 v[108:111], v[28:31], v[116:119], v[108:111]
	v_mfma_f32_16x16x32_bf16 v[20:23], v[28:31], v[124:127], v[20:23]
	s_setprio 0
	s_barrier
	ds_read_b128 v[24:27], v137
	ds_read_b128 v[28:31], v137 offset:1024
	ds_read_b128 v[112:115], v137 offset:2048
	ds_read_b128 v[116:119], v137 offset:3072
	ds_read_b128 v[120:123], v138
	ds_read_b128 v[124:127], v138 offset:1024
	ds_read_b128 v[164:167], v138 offset:2048
	ds_read_b128 v[168:171], v138 offset:3072
	s_add_u32 s60, s46, 0x10100
	s_addc_u32 s61, s47, 0
	s_mov_b32 m0, s90
	v_lshl_add_u64 v[212:213], s[60:61], 0, v[130:131]
	ds_read_b128 v[172:175], v136 offset:32768
	ds_read_b128 v[176:179], v136 offset:33792
	ds_read_b128 v[180:183], v136 offset:34816
	ds_read_b128 v[184:187], v136 offset:35840
	ds_read_b128 v[188:191], v136 offset:36864
	ds_read_b128 v[192:195], v136 offset:37888
	ds_read_b128 v[196:199], v136 offset:38912
	ds_read_b128 v[200:203], v136 offset:39936
	global_load_lds_dwordx4 v[212:213], off
	v_lshl_add_u64 v[212:213], s[60:61], 0, v[128:129]
	s_mov_b32 m0, s43
	s_nop 0
	global_load_lds_dwordx4 v[212:213], off
	s_waitcnt vmcnt(8)
	s_cmp_lt_u32 s3, 4
	s_cbranch_scc1 .Lgls_70
	s_waitcnt lgkmcnt(0)
.Lgls_70:
	s_barrier
	s_setprio 1
	s_waitcnt lgkmcnt(0)
	v_mfma_f32_16x16x32_bf16 v[64:67], v[24:27], v[172:175], v[64:67]
	v_mfma_f32_16x16x32_bf16 v[68:71], v[112:115], v[172:175], v[68:71]
	v_mfma_f32_16x16x32_bf16 v[72:75], v[24:27], v[180:183], v[72:75]
	v_mfma_f32_16x16x32_bf16 v[76:79], v[112:115], v[180:183], v[76:79]
	v_mfma_f32_16x16x32_bf16 v[80:83], v[24:27], v[188:191], v[80:83]
	v_mfma_f32_16x16x32_bf16 v[84:87], v[112:115], v[188:191], v[84:87]
	v_mfma_f32_16x16x32_bf16 v[88:91], v[24:27], v[196:199], v[88:91]
	v_mfma_f32_16x16x32_bf16 v[92:95], v[112:115], v[196:199], v[92:95]
	v_mfma_f32_16x16x32_bf16 v[64:67], v[28:31], v[176:179], v[64:67]
	v_mfma_f32_16x16x32_bf16 v[68:71], v[116:119], v[176:179], v[68:71]
	v_mfma_f32_16x16x32_bf16 v[72:75], v[28:31], v[184:187], v[72:75]
	v_mfma_f32_16x16x32_bf16 v[76:79], v[116:119], v[184:187], v[76:79]
	v_mfma_f32_16x16x32_bf16 v[80:83], v[28:31], v[192:195], v[80:83]
	v_mfma_f32_16x16x32_bf16 v[84:87], v[116:119], v[192:195], v[84:87]
	v_mfma_f32_16x16x32_bf16 v[88:91], v[28:31], v[200:203], v[88:91]
	v_mfma_f32_16x16x32_bf16 v[92:95], v[116:119], v[200:203], v[92:95]
	s_setprio 0
	s_setprio 1
	v_mfma_f32_16x16x32_bf16 v[96:99], v[120:123], v[172:175], v[96:99]
	v_mfma_f32_16x16x32_bf16 v[32:35], v[164:167], v[172:175], v[32:35]
	v_mfma_f32_16x16x32_bf16 v[36:39], v[120:123], v[180:183], v[36:39]
	v_mfma_f32_16x16x32_bf16 v[40:43], v[164:167], v[180:183], v[40:43]
	v_mfma_f32_16x16x32_bf16 v[44:47], v[120:123], v[188:191], v[44:47]
	v_mfma_f32_16x16x32_bf16 v[48:51], v[164:167], v[188:191], v[48:51]
	v_mfma_f32_16x16x32_bf16 v[52:55], v[120:123], v[196:199], v[52:55]
	v_mfma_f32_16x16x32_bf16 v[56:59], v[164:167], v[196:199], v[56:59]
	v_mfma_f32_16x16x32_bf16 v[96:99], v[124:127], v[176:179], v[96:99]
	v_mfma_f32_16x16x32_bf16 v[32:35], v[168:171], v[176:179], v[32:35]
	v_mfma_f32_16x16x32_bf16 v[36:39], v[124:127], v[184:187], v[36:39]
	v_mfma_f32_16x16x32_bf16 v[40:43], v[168:171], v[184:187], v[40:43]
	v_mfma_f32_16x16x32_bf16 v[44:47], v[124:127], v[192:195], v[44:47]
	v_mfma_f32_16x16x32_bf16 v[48:51], v[168:171], v[192:195], v[48:51]
	v_mfma_f32_16x16x32_bf16 v[52:55], v[124:127], v[200:203], v[52:55]
	v_mfma_f32_16x16x32_bf16 v[56:59], v[168:171], v[200:203], v[56:59]
	s_setprio 0
	s_barrier
	s_mov_b32 m0, s53
	v_lshl_add_u64 v[204:205], v[204:205], 0, s[28:29]
	s_add_u32 s48, s48, 0x10180
	ds_read_b128 v[172:175], v136 offset:49152
	ds_read_b128 v[176:179], v136 offset:50176
	ds_read_b128 v[180:183], v136 offset:51200
	ds_read_b128 v[184:187], v136 offset:52224
	ds_read_b128 v[188:191], v136 offset:53248
	ds_read_b128 v[192:195], v136 offset:54272
	ds_read_b128 v[196:199], v136 offset:55296
	ds_read_b128 v[200:203], v136 offset:56320
	global_load_lds_dwordx4 v[204:205], off
	v_lshl_add_u64 v[204:205], v[206:207], 0, s[28:29]
	s_mov_b32 m0, s54
	s_addc_u32 s49, s49, 0
	global_load_lds_dwordx4 v[204:205], off
	v_lshl_add_u64 v[204:205], s[48:49], 0, v[130:131]
	s_mov_b32 m0, s55
	s_nop 0
	global_load_lds_dwordx4 v[204:205], off
	v_lshl_add_u64 v[204:205], s[48:49], 0, v[128:129]
	s_mov_b32 m0, s56
	s_nop 0
	global_load_lds_dwordx4 v[204:205], off
	v_lshl_add_u64 v[204:205], v[208:209], 0, s[28:29]
	s_mov_b32 m0, s75
	s_nop 0
	global_load_lds_dwordx4 v[204:205], off
	v_lshl_add_u64 v[204:205], v[210:211], 0, s[28:29]
	s_mov_b32 m0, s67
	s_nop 0
	global_load_lds_dwordx4 v[204:205], off
	s_waitcnt vmcnt(8)
	s_cmp_lt_u32 s3, 4
	s_cbranch_scc1 .Lgls_71
	s_waitcnt lgkmcnt(0)
; #define PG8_STAGE(bufoff, gbase, voff) do { _Pragma("unroll") for (int _i = 0; _i < 2; ++_i) \
;         __builtin_amdgcn_global_load_lds((const unsigned*)((const char*)(gbase) + (voff)[_i]), (PG8_LAS unsigned*)(lds + (bufoff) + ldsw + _i * 8192), 16, 0, 0); } while (0)
; #define PG8_LDA(dst, b, h) do { _Pragma("unroll") for (int m = 0; m < 4; ++m) _Pragma("unroll") for (int k = 0; k < 2; ++k) dst[m][k] = *(const PG8_LAS bf16x8*)(lds + PG8_SA(b, h) + aoff + m * 2048 + k * 1024); } while (0)
; #define PG8_LDB(dst, b, h) do { _Pragma("unroll") for (int n = 0; n < 2; ++n) _Pragma("unroll") for (int k = 0; k < 2; ++k) dst[n][k] = *(const PG8_LAS bf16x8*)(lds + PG8_SB(b, h) + boff + n * 2048 + k * 1024); } while (0)
; #define PG8_MMA(ai, bj, At, Bt) do { __builtin_amdgcn_s_setprio(1); _Pragma("unroll") for (int m = 0; m < 4; ++m) _Pragma("unroll") for (int n = 0; n < 2; ++n) _Pragma("unroll") for (int k = 0; k < 2; ++k) \
;         acc[ai][bj][m][n] = mma16<F16>(Bt[n][k], At[m][k], acc[ai][bj][m][n]); __builtin_amdgcn_s_setprio(0); } while (0)
; #define PG8_WAIT_V(n) asm volatile("s_waitcnt vmcnt(" #n ")" ::: "memory")
; template <class Epi, class Sched, bool ALIGN_EPI = false, bool SP2 = false, bool F16 = false>
; __device__ __forceinline__ void gemm_phase(PG8_LAS unsigned char* lds, const Gemm g, const Sched& S, const Epi& E, const int wid_in) {
;     ...
;             PG8_LDB(B0, 0, 0); PG8_LDB(B1, 0, 1); PG8_SCHED; PG8_LDA(At, 0, 0); PG8_STAGE(PG8_SA(1, 1), a1 + hstep, voffA);
;             PG8_WAIT_V(8); PG8_WAIT_L(0); PG8_BAR; PG8_MMA(0, 0, At, B0); PG8_MMA(0, 1, At, B1); PG8_BAR; PG8_SCHED;
;             PG8_LDA(At, 0, 1); PG8_STAGE(PG8_SB(0, 0), b2, voffB); PG8_STAGE(PG8_SB(0, 1), b2 + hstep, voffB); PG8_STAGE(PG8_SA(0, 0), a2, voffA);
;             PG8_WAIT_V(8); PG8_WAIT_L(0); PG8_BAR; PG8_MMA(1, 0, At, B0); PG8_MMA(1, 1, At, B1); PG8_BAR; PG8_SCHED;
;             PG8_LDB(B0, 1, 0); PG8_LDB(B1, 1, 1); PG8_SCHED; PG8_LDA(At, 1, 0); PG8_STAGE(PG8_SA(0, 1), a2 + hstep, voffA);
;             PG8_WAIT_V(8); PG8_WAIT_L(0); PG8_BAR; PG8_MMA(0, 0, At, B0); PG8_MMA(0, 1, At, B1); PG8_BAR; PG8_SCHED;
;             PG8_LDA(At, 1, 1); PG8_STAGE(PG8_SB(1, 0), b3, voffB); PG8_STAGE(PG8_SB(1, 1), b3 + hstep, voffB); PG8_STAGE(PG8_SA(1, 0), a3, voffA);
;             PG8_WAIT_V(8); PG8_WAIT_L(0); PG8_BAR; PG8_MMA(1, 0, At, B0); PG8_MMA(1, 1, At, B1); PG8_BAR; PG8_SCHED;
.Lgls_71:
	s_barrier
	s_setprio 1
	s_waitcnt lgkmcnt(0)
	v_mfma_f32_16x16x32_bf16 v[0:3], v[24:27], v[196:199], v[0:3]
	v_mfma_f32_16x16x32_bf16 v[4:7], v[112:115], v[196:199], v[4:7]
	v_mfma_f32_16x16x32_bf16 v[140:143], v[24:27], v[172:175], v[140:143]
	v_mfma_f32_16x16x32_bf16 v[144:147], v[112:115], v[172:175], v[144:147]
	v_mfma_f32_16x16x32_bf16 v[148:151], v[24:27], v[180:183], v[148:151]
	v_mfma_f32_16x16x32_bf16 v[152:155], v[112:115], v[180:183], v[152:155]
	v_mfma_f32_16x16x32_bf16 v[156:159], v[24:27], v[188:191], v[156:159]
	v_mfma_f32_16x16x32_bf16 v[160:163], v[112:115], v[188:191], v[160:163]
	v_mfma_f32_16x16x32_bf16 v[0:3], v[28:31], v[200:203], v[0:3]
	v_mfma_f32_16x16x32_bf16 v[4:7], v[116:119], v[200:203], v[4:7]
	v_mfma_f32_16x16x32_bf16 v[140:143], v[28:31], v[176:179], v[140:143]
	v_mfma_f32_16x16x32_bf16 v[144:147], v[116:119], v[176:179], v[144:147]
	v_mfma_f32_16x16x32_bf16 v[148:151], v[28:31], v[184:187], v[148:151]
	v_mfma_f32_16x16x32_bf16 v[152:155], v[116:119], v[184:187], v[152:155]
	v_mfma_f32_16x16x32_bf16 v[156:159], v[28:31], v[192:195], v[156:159]
	v_mfma_f32_16x16x32_bf16 v[160:163], v[116:119], v[192:195], v[160:163]
	s_setprio 0
	s_setprio 1
	v_mfma_f32_16x16x32_bf16 v[8:11], v[120:123], v[172:175], v[8:11]
	v_mfma_f32_16x16x32_bf16 v[12:15], v[164:167], v[172:175], v[12:15]
	v_mfma_f32_16x16x32_bf16 v[24:27], v[120:123], v[180:183], v[60:63]
	v_mfma_f32_16x16x32_bf16 v[28:31], v[164:167], v[180:183], v[100:103]
	v_mfma_f32_16x16x32_bf16 v[60:63], v[120:123], v[188:191], v[104:107]
	v_mfma_f32_16x16x32_bf16 v[100:103], v[164:167], v[188:191], v[108:111]
	v_mfma_f32_16x16x32_bf16 v[16:19], v[120:123], v[196:199], v[16:19]
	v_mfma_f32_16x16x32_bf16 v[20:23], v[164:167], v[196:199], v[20:23]
	v_mfma_f32_16x16x32_bf16 v[8:11], v[124:127], v[176:179], v[8:11]
	v_mfma_f32_16x16x32_bf16 v[12:15], v[168:171], v[176:179], v[12:15]
	v_mfma_f32_16x16x32_bf16 v[24:27], v[124:127], v[184:187], v[24:27]
	v_mfma_f32_16x16x32_bf16 v[28:31], v[168:171], v[184:187], v[28:31]
	v_mfma_f32_16x16x32_bf16 v[60:63], v[124:127], v[192:195], v[60:63]
	v_mfma_f32_16x16x32_bf16 v[100:103], v[168:171], v[192:195], v[100:103]
	v_mfma_f32_16x16x32_bf16 v[16:19], v[124:127], v[200:203], v[16:19]
	v_mfma_f32_16x16x32_bf16 v[20:23], v[168:171], v[200:203], v[20:23]
	s_setprio 0
	s_barrier
	ds_read_b128 v[104:107], v134
	ds_read_b128 v[108:111], v134 offset:1024
	ds_read_b128 v[112:115], v134 offset:2048
	ds_read_b128 v[116:119], v134 offset:3072
	ds_read_b128 v[120:123], v135
	ds_read_b128 v[124:127], v135 offset:1024
	ds_read_b128 v[164:167], v135 offset:2048
	ds_read_b128 v[168:171], v135 offset:3072
	s_add_u32 s46, s46, 0x10180
	s_addc_u32 s47, s47, 0
	s_mov_b32 m0, s91
	v_lshl_add_u64 v[204:205], s[46:47], 0, v[130:131]
	ds_read_b128 v[172:175], v136
	ds_read_b128 v[176:179], v136 offset:1024
	ds_read_b128 v[180:183], v136 offset:2048
	ds_read_b128 v[184:187], v136 offset:3072
	ds_read_b128 v[188:191], v136 offset:4096
	ds_read_b128 v[192:195], v136 offset:5120
	ds_read_b128 v[196:199], v136 offset:6144
	ds_read_b128 v[200:203], v136 offset:7168
	global_load_lds_dwordx4 v[204:205], off
	v_lshl_add_u64 v[204:205], s[46:47], 0, v[128:129]
	s_mov_b32 m0, s14
	s_nop 0
	global_load_lds_dwordx4 v[204:205], off
	s_waitcnt vmcnt(8)
	s_cmp_lt_u32 s3, 4
	s_cbranch_scc1 .Lgls_72
	s_waitcnt lgkmcnt(0)
.Lgls_72:
	s_barrier
	s_setprio 1
	s_waitcnt lgkmcnt(0)
	v_mfma_f32_16x16x32_bf16 v[64:67], v[104:107], v[172:175], v[64:67]
	v_mfma_f32_16x16x32_bf16 v[68:71], v[112:115], v[172:175], v[68:71]
	v_mfma_f32_16x16x32_bf16 v[72:75], v[104:107], v[180:183], v[72:75]
	v_mfma_f32_16x16x32_bf16 v[76:79], v[112:115], v[180:183], v[76:79]
	v_mfma_f32_16x16x32_bf16 v[80:83], v[104:107], v[188:191], v[80:83]
	v_mfma_f32_16x16x32_bf16 v[84:87], v[112:115], v[188:191], v[84:87]
	v_mfma_f32_16x16x32_bf16 v[88:91], v[104:107], v[196:199], v[88:91]
	v_mfma_f32_16x16x32_bf16 v[92:95], v[112:115], v[196:199], v[92:95]
	v_mfma_f32_16x16x32_bf16 v[64:67], v[108:111], v[176:179], v[64:67]
	v_mfma_f32_16x16x32_bf16 v[68:71], v[116:119], v[176:179], v[68:71]
	v_mfma_f32_16x16x32_bf16 v[72:75], v[108:111], v[184:187], v[72:75]
	v_mfma_f32_16x16x32_bf16 v[76:79], v[116:119], v[184:187], v[76:79]
	v_mfma_f32_16x16x32_bf16 v[80:83], v[108:111], v[192:195], v[80:83]
	v_mfma_f32_16x16x32_bf16 v[84:87], v[116:119], v[192:195], v[84:87]
	v_mfma_f32_16x16x32_bf16 v[88:91], v[108:111], v[200:203], v[88:91]
	v_mfma_f32_16x16x32_bf16 v[92:95], v[116:119], v[200:203], v[92:95]
	s_setprio 0
	s_setprio 1
	v_mfma_f32_16x16x32_bf16 v[32:35], v[164:167], v[172:175], v[32:35]
	v_mfma_f32_16x16x32_bf16 v[96:99], v[120:123], v[172:175], v[96:99]
	v_mfma_f32_16x16x32_bf16 v[172:175], v[168:171], v[176:179], v[32:35]
	v_mfma_f32_16x16x32_bf16 v[32:35], v[120:123], v[180:183], v[36:39]
	v_mfma_f32_16x16x32_bf16 v[204:207], v[124:127], v[176:179], v[96:99]
	v_mfma_f32_16x16x32_bf16 v[176:179], v[124:127], v[184:187], v[32:35]
	v_mfma_f32_16x16x32_bf16 v[32:35], v[164:167], v[180:183], v[40:43]
	v_mfma_f32_16x16x32_bf16 v[40:43], v[168:171], v[184:187], v[32:35]
	v_mfma_f32_16x16x32_bf16 v[32:35], v[120:123], v[188:191], v[44:47]
	v_mfma_f32_16x16x32_bf16 v[44:47], v[124:127], v[192:195], v[32:35]
	v_mfma_f32_16x16x32_bf16 v[32:35], v[164:167], v[188:191], v[48:51]
	v_mfma_f32_16x16x32_bf16 v[48:51], v[168:171], v[192:195], v[32:35]
	v_mfma_f32_16x16x32_bf16 v[32:35], v[120:123], v[196:199], v[52:55]
	v_mfma_f32_16x16x32_bf16 v[52:55], v[124:127], v[200:203], v[32:35]
	v_mfma_f32_16x16x32_bf16 v[32:35], v[164:167], v[196:199], v[56:59]
	v_mfma_f32_16x16x32_bf16 v[56:59], v[168:171], v[200:203], v[32:35]
	s_setprio 0
	s_barrier
	s_mov_b32 m0, s15
	v_lshl_add_u64 v[240:241], s[36:37], 0, v[130:131]
	s_add_u32 s46, s36, 0x10000
	s_nop 1
	ds_read_b128 v[32:35], v136 offset:16384
	ds_read_b128 v[36:39], v136 offset:17408
	ds_read_b128 v[96:99], v136 offset:18432
	ds_read_b128 v[180:183], v136 offset:19456
	ds_read_b128 v[184:187], v136 offset:20480
	ds_read_b128 v[188:191], v136 offset:21504
	ds_read_b128 v[192:195], v136 offset:22528
	ds_read_b128 v[196:199], v136 offset:23552
	global_load_lds_dwordx4 v[240:241], off
	v_lshl_add_u64 v[242:243], s[36:37], 0, v[128:129]
	s_mov_b32 m0, s50
	s_addc_u32 s47, s37, 0
	global_load_lds_dwordx4 v[242:243], off
	v_lshl_add_u64 v[200:201], s[46:47], 0, v[130:131]
	s_mov_b32 m0, s51
	v_lshl_add_u64 v[244:245], s[44:45], 0, v[130:131]
	global_load_lds_dwordx4 v[200:201], off
	v_lshl_add_u64 v[200:201], s[46:47], 0, v[128:129]
	s_mov_b32 m0, s52
	v_lshl_add_u64 v[246:247], s[44:45], 0, v[128:129]
	global_load_lds_dwordx4 v[200:201], off
	s_mov_b32 m0, s74
	s_nop 0
	global_load_lds_dwordx4 v[244:245], off
	s_mov_b32 m0, s66
	s_nop 0
	global_load_lds_dwordx4 v[246:247], off
	s_waitcnt vmcnt(8)
	s_cmp_lt_u32 s3, 4
	s_cbranch_scc1 .Lgls_73
	s_waitcnt lgkmcnt(0)
; #define PG8_STAGE(bufoff, gbase, voff) do { _Pragma("unroll") for (int _i = 0; _i < 2; ++_i) \
;         __builtin_amdgcn_global_load_lds((const unsigned*)((const char*)(gbase) + (voff)[_i]), (PG8_LAS unsigned*)(lds + (bufoff) + ldsw + _i * 8192), 16, 0, 0); } while (0)
; #define PG8_LDA(dst, b, h) do { _Pragma("unroll") for (int m = 0; m < 4; ++m) _Pragma("unroll") for (int k = 0; k < 2; ++k) dst[m][k] = *(const PG8_LAS bf16x8*)(lds + PG8_SA(b, h) + aoff + m * 2048 + k * 1024); } while (0)
; #define PG8_LDB(dst, b, h) do { _Pragma("unroll") for (int n = 0; n < 2; ++n) _Pragma("unroll") for (int k = 0; k < 2; ++k) dst[n][k] = *(const PG8_LAS bf16x8*)(lds + PG8_SB(b, h) + boff + n * 2048 + k * 1024); } while (0)
; #define PG8_MMA(ai, bj, At, Bt) do { __builtin_amdgcn_s_setprio(1); _Pragma("unroll") for (int m = 0; m < 4; ++m) _Pragma("unroll") for (int n = 0; n < 2; ++n) _Pragma("unroll") for (int k = 0; k < 2; ++k) \
;         acc[ai][bj][m][n] = mma16<F16>(Bt[n][k], At[m][k], acc[ai][bj][m][n]); __builtin_amdgcn_s_setprio(0); } while (0)
; #define PG8_WAIT_V(n) asm volatile("s_waitcnt vmcnt(" #n ")" ::: "memory")
; #define PG8_WAIT_L(n) asm volatile("s_waitcnt lgkmcnt(" #n ")" ::: "memory")
; #define PG8_BAR __builtin_amdgcn_s_barrier()
; #define PG8_SCHED __builtin_amdgcn_sched_barrier(0)
; template <class Epi, class Sched, bool ALIGN_EPI = false, bool SP2 = false, bool F16 = false>
; __device__ __forceinline__ void gemm_phase(PG8_LAS unsigned char* lds, const Gemm g, const Sched& S, const Epi& E, const int wid_in) {
;     ...
;             PG8_WAIT_V(8); PG8_WAIT_L(0); PG8_BAR; PG8_MMA(0, 0, At, B0); PG8_MMA(0, 1, At, B1); PG8_BAR; PG8_SCHED;
;             PG8_LDA(At, 0, 1); PG8_STAGE(PG8_SB(0, 0), b2, voffB); PG8_STAGE(PG8_SB(0, 1), b2 + hstep, voffB); PG8_STAGE(PG8_SA(0, 0), a2, voffA);
;             PG8_WAIT_V(8); PG8_WAIT_L(0); PG8_BAR; PG8_MMA(1, 0, At, B0); PG8_MMA(1, 1, At, B1); PG8_BAR; PG8_SCHED;
;             PG8_LDB(B0, 1, 0); PG8_LDB(B1, 1, 1); PG8_SCHED; PG8_LDA(At, 1, 0); PG8_STAGE(PG8_SA(0, 1), a2 + hstep, voffA);
;             PG8_WAIT_V(8); PG8_WAIT_L(0); PG8_BAR; PG8_MMA(0, 0, At, B0); PG8_MMA(0, 1, At, B1); PG8_BAR; PG8_SCHED;
;             PG8_LDA(At, 1, 1); PG8_STAGE(PG8_SB(1, 0), b3, voffB); PG8_STAGE(PG8_SB(1, 1), b3 + hstep, voffB); PG8_STAGE(PG8_SA(1, 0), a3, voffA);
.Lgls_73:
	s_barrier
	s_setprio 1
	s_waitcnt lgkmcnt(0)
	v_mfma_f32_16x16x32_bf16 v[0:3], v[104:107], v[192:195], v[0:3]
	v_mfma_f32_16x16x32_bf16 v[140:143], v[104:107], v[32:35], v[140:143]
	v_mfma_f32_16x16x32_bf16 v[144:147], v[112:115], v[32:35], v[144:147]
	v_mfma_f32_16x16x32_bf16 v[148:151], v[104:107], v[96:99], v[148:151]
	v_mfma_f32_16x16x32_bf16 v[152:155], v[112:115], v[96:99], v[152:155]
	v_mfma_f32_16x16x32_bf16 v[156:159], v[104:107], v[184:187], v[156:159]
	v_mfma_f32_16x16x32_bf16 v[160:163], v[112:115], v[184:187], v[160:163]
	v_mfma_f32_16x16x32_bf16 v[0:3], v[108:111], v[196:199], v[0:3]
	v_mfma_f32_16x16x32_bf16 v[4:7], v[112:115], v[192:195], v[4:7]
	v_mfma_f32_16x16x32_bf16 v[140:143], v[108:111], v[36:39], v[140:143]
	v_mfma_f32_16x16x32_bf16 v[144:147], v[116:119], v[36:39], v[144:147]
	v_mfma_f32_16x16x32_bf16 v[148:151], v[108:111], v[180:183], v[148:151]
	v_mfma_f32_16x16x32_bf16 v[152:155], v[116:119], v[180:183], v[152:155]
	v_mfma_f32_16x16x32_bf16 v[156:159], v[108:111], v[188:191], v[156:159]
	v_mfma_f32_16x16x32_bf16 v[160:163], v[116:119], v[188:191], v[160:163]
	v_mfma_f32_16x16x32_bf16 v[200:203], v[116:119], v[196:199], v[4:7]
	s_setprio 0
	s_setprio 1
	v_mfma_f32_16x16x32_bf16 v[4:7], v[120:123], v[32:35], v[8:11]
	v_mfma_f32_16x16x32_bf16 v[8:11], v[124:127], v[36:39], v[4:7]
	v_mfma_f32_16x16x32_bf16 v[4:7], v[164:167], v[32:35], v[12:15]
	v_mfma_f32_16x16x32_bf16 v[12:15], v[168:171], v[36:39], v[4:7]
	v_mfma_f32_16x16x32_bf16 v[4:7], v[120:123], v[96:99], v[24:27]
	v_mfma_f32_16x16x32_bf16 v[24:27], v[124:127], v[180:183], v[4:7]
	v_mfma_f32_16x16x32_bf16 v[4:7], v[164:167], v[96:99], v[28:31]
	v_mfma_f32_16x16x32_bf16 v[28:31], v[168:171], v[180:183], v[4:7]
	v_mfma_f32_16x16x32_bf16 v[4:7], v[120:123], v[184:187], v[60:63]
	v_mfma_f32_16x16x32_bf16 v[180:183], v[124:127], v[188:191], v[4:7]
	v_mfma_f32_16x16x32_bf16 v[4:7], v[164:167], v[184:187], v[100:103]
	v_mfma_f32_16x16x32_bf16 v[184:187], v[168:171], v[188:191], v[4:7]
	v_mfma_f32_16x16x32_bf16 v[4:7], v[120:123], v[192:195], v[16:19]
	v_mfma_f32_16x16x32_bf16 v[188:191], v[124:127], v[196:199], v[4:7]
	v_mfma_f32_16x16x32_bf16 v[4:7], v[164:167], v[192:195], v[20:23]
	v_mfma_f32_16x16x32_bf16 v[164:167], v[168:171], v[196:199], v[4:7]
	s_setprio 0
	s_barrier
	s_nop 4
	ds_read_b128 v[4:7], v137
	ds_read_b128 v[60:63], v137 offset:1024
	ds_read_b128 v[168:171], v137 offset:2048
	ds_read_b128 v[192:195], v137 offset:3072
	ds_read_b128 v[196:199], v138
	ds_read_b128 v[208:211], v138 offset:1024
	ds_read_b128 v[212:215], v138 offset:2048
	ds_read_b128 v[216:219], v138 offset:3072
	s_add_u32 s44, s44, 0x10000
	s_addc_u32 s45, s45, 0
	s_mov_b32 m0, s90
	v_lshl_add_u64 v[32:33], s[44:45], 0, v[130:131]
	ds_read_b128 v[16:19], v136 offset:32768
	ds_read_b128 v[20:23], v136 offset:33792
	ds_read_b128 v[104:107], v136 offset:34816
	ds_read_b128 v[220:223], v136 offset:35840
	ds_read_b128 v[224:227], v136 offset:36864
	ds_read_b128 v[228:231], v136 offset:37888
	ds_read_b128 v[232:235], v136 offset:38912
	ds_read_b128 v[236:239], v136 offset:39936
	global_load_lds_dwordx4 v[32:33], off
	v_lshl_add_u64 v[32:33], s[44:45], 0, v[128:129]
	s_mov_b32 m0, s43
	s_nop 0
	global_load_lds_dwordx4 v[32:33], off
	s_waitcnt vmcnt(8)
	s_cmp_lt_u32 s3, 4
	s_cbranch_scc1 .Lgls_74
	s_waitcnt lgkmcnt(0)
.Lgls_74:
	s_barrier
	s_setprio 1
	s_waitcnt lgkmcnt(0)
	v_mfma_f32_16x16x32_bf16 v[32:35], v[4:7], v[16:19], v[64:67]
	v_mfma_f32_16x16x32_bf16 v[116:119], v[60:63], v[20:23], v[32:35]
	v_mfma_f32_16x16x32_bf16 v[32:35], v[168:171], v[16:19], v[68:71]
	v_mfma_f32_16x16x32_bf16 v[112:115], v[192:195], v[20:23], v[32:35]
	v_mfma_f32_16x16x32_bf16 v[32:35], v[4:7], v[104:107], v[72:75]
	v_mfma_f32_16x16x32_bf16 v[100:103], v[60:63], v[220:223], v[32:35]
	v_mfma_f32_16x16x32_bf16 v[32:35], v[168:171], v[104:107], v[76:79]
	v_mfma_f32_16x16x32_bf16 v[96:99], v[192:195], v[220:223], v[32:35]
	v_mfma_f32_16x16x32_bf16 v[32:35], v[4:7], v[224:227], v[80:83]
	v_mfma_f32_16x16x32_bf16 v[68:71], v[60:63], v[228:231], v[32:35]
	v_mfma_f32_16x16x32_bf16 v[32:35], v[168:171], v[224:227], v[84:87]
	v_mfma_f32_16x16x32_bf16 v[64:67], v[192:195], v[228:231], v[32:35]
	v_mfma_f32_16x16x32_bf16 v[32:35], v[4:7], v[232:235], v[88:91]
	v_mfma_f32_16x16x32_bf16 v[36:39], v[60:63], v[236:239], v[32:35]
	v_mfma_f32_16x16x32_bf16 v[32:35], v[168:171], v[232:235], v[92:95]
	v_mfma_f32_16x16x32_bf16 v[32:35], v[192:195], v[236:239], v[32:35]
	s_setprio 0
	s_setprio 1
	v_mfma_f32_16x16x32_bf16 v[72:75], v[196:199], v[16:19], v[204:207]
	v_mfma_f32_16x16x32_bf16 v[16:19], v[212:215], v[16:19], v[172:175]
	v_mfma_f32_16x16x32_bf16 v[120:123], v[216:219], v[20:23], v[16:19]
	v_mfma_f32_16x16x32_bf16 v[16:19], v[196:199], v[104:107], v[176:179]
	v_mfma_f32_16x16x32_bf16 v[108:111], v[208:211], v[220:223], v[16:19]
	v_mfma_f32_16x16x32_bf16 v[16:19], v[212:215], v[104:107], v[40:43]
	v_mfma_f32_16x16x32_bf16 v[104:107], v[216:219], v[220:223], v[16:19]
	v_mfma_f32_16x16x32_bf16 v[16:19], v[196:199], v[224:227], v[44:47]
	v_mfma_f32_16x16x32_bf16 v[80:83], v[208:211], v[228:231], v[16:19]
	v_mfma_f32_16x16x32_bf16 v[16:19], v[212:215], v[224:227], v[48:51]
	v_mfma_f32_16x16x32_bf16 v[124:127], v[208:211], v[20:23], v[72:75]
	v_mfma_f32_16x16x32_bf16 v[72:75], v[216:219], v[228:231], v[16:19]
	v_mfma_f32_16x16x32_bf16 v[16:19], v[196:199], v[232:235], v[52:55]
	v_mfma_f32_16x16x32_bf16 v[48:51], v[208:211], v[236:239], v[16:19]
	v_mfma_f32_16x16x32_bf16 v[16:19], v[212:215], v[232:235], v[56:59]
	v_mfma_f32_16x16x32_bf16 v[40:43], v[216:219], v[236:239], v[16:19]
	s_setprio 0
	s_barrier
	s_mov_b32 m0, s53
	s_nop 3
	v_lshl_add_u64 v[16:17], v[240:241], 0, s[24:25]
	s_add_u32 s36, s36, 0x10080
	ds_read_b128 v[56:59], v136 offset:49152
	ds_read_b128 v[88:91], v136 offset:50176
	ds_read_b128 v[172:175], v136 offset:51200
	ds_read_b128 v[176:179], v136 offset:52224
	ds_read_b128 v[204:207], v136 offset:53248
	ds_read_b128 v[220:223], v136 offset:54272
	ds_read_b128 v[224:227], v136 offset:55296
	ds_read_b128 v[228:231], v136 offset:56320
	global_load_lds_dwordx4 v[16:17], off
	v_lshl_add_u64 v[16:17], v[242:243], 0, s[24:25]
	s_mov_b32 m0, s54
	s_addc_u32 s37, s37, 0
	global_load_lds_dwordx4 v[16:17], off
	v_lshl_add_u64 v[16:17], s[36:37], 0, v[130:131]
	s_mov_b32 m0, s55
	s_nop 0
	global_load_lds_dwordx4 v[16:17], off
	v_lshl_add_u64 v[16:17], s[36:37], 0, v[128:129]
	s_mov_b32 m0, s56
	s_nop 0
	global_load_lds_dwordx4 v[16:17], off
	v_lshl_add_u64 v[16:17], v[244:245], 0, s[24:25]
	s_mov_b32 m0, s75
	s_nop 0
	global_load_lds_dwordx4 v[16:17], off
	v_lshl_add_u64 v[16:17], v[246:247], 0, s[24:25]
	s_mov_b32 m0, s67
	s_nop 0
	global_load_lds_dwordx4 v[16:17], off
	s_waitcnt vmcnt(8)
	s_cmp_lt_u32 s3, 4
	s_cbranch_scc1 .Lgls_75
	s_waitcnt lgkmcnt(0)

; #define PG8_STAGE(bufoff, gbase, voff) do { _Pragma("unroll") for (int _i = 0; _i < 2; ++_i) \
;         __builtin_amdgcn_global_load_lds((const unsigned*)((const char*)(gbase) + (voff)[_i]), (PG8_LAS unsigned*)(lds + (bufoff) + ldsw + _i * 8192), 16, 0, 0); } while (0)
; #define PG8_LDA(dst, b, h) do { _Pragma("unroll") for (int m = 0; m < 4; ++m) _Pragma("unroll") for (int k = 0; k < 2; ++k) dst[m][k] = *(const PG8_LAS bf16x8*)(lds + PG8_SA(b, h) + aoff + m * 2048 + k * 1024); } while (0)
; #define PG8_LDB(dst, b, h) do { _Pragma("unroll") for (int n = 0; n < 2; ++n) _Pragma("unroll") for (int k = 0; k < 2; ++k) dst[n][k] = *(const PG8_LAS bf16x8*)(lds + PG8_SB(b, h) + boff + n * 2048 + k * 1024); } while (0)
; #define PG8_MMA(ai, bj, At, Bt) do { __builtin_amdgcn_s_setprio(1); _Pragma("unroll") for (int m = 0; m < 4; ++m) _Pragma("unroll") for (int n = 0; n < 2; ++n) _Pragma("unroll") for (int k = 0; k < 2; ++k) \
;         acc[ai][bj][m][n] = mma16<F16>(Bt[n][k], At[m][k], acc[ai][bj][m][n]); __builtin_amdgcn_s_setprio(0); } while (0)
; #define PG8_WAIT_V(n) asm volatile("s_waitcnt vmcnt(" #n ")" ::: "memory")
; #define PG8_WAIT_L(n) asm volatile("s_waitcnt lgkmcnt(" #n ")" ::: "memory")
; template <class Epi, class Sched, bool ALIGN_EPI = false, bool SP2 = false, bool F16 = false>
; __device__ __forceinline__ void gemm_phase(PG8_LAS unsigned char* lds, const Gemm g, const Sched& S, const Epi& E, const int wid_in) {
;     ...
;             const bool last = (t == nt - 2);
;             const char* a1 = cA + (size_t)(t + 1) * kstep;
;             const char* a2 = last ? nA : cA + (size_t)(t + 2) * kstep; const char* b2 = last ? nB : cB + (size_t)(t + 2) * kstep;
;             const char* a3 = a2 + kstep; const char* b3 = b2 + kstep;
;             if (last && has_next) S.a_ready(nxt);
;             if constexpr (SP2) {
;             PG8_LDB(B0, 0, 0); PG8_LDB(B1, 0, 1); PG8_SCHED; PG8_LDA(At, 0, 0); PG8_STAGE(PG8_SA(1, 1), a1 + hstep, voffA);
;             PG8_WAIT_V(8); PG8_WAIT_L(0); PG8_BAR; PG8_MMA(0, 0, At, B0); PG8_MMA(0, 1, At, B1); PG8_BAR; PG8_SCHED;
;             PG8_LDA(At, 0, 1); PG8_STAGE(PG8_SB(0, 0), b2, voffB); PG8_STAGE(PG8_SB(0, 1), b2 + hstep, voffB); PG8_STAGE(PG8_SA(0, 0), a2, voffA);
;             PG8_WAIT_V(8); PG8_WAIT_L(0); PG8_BAR; PG8_MMA(1, 0, At, B0); PG8_MMA(1, 1, At, B1); PG8_BAR; PG8_SCHED;
.LBB0_2040:
	ds_read_b128 v[128:131], v189
	ds_read_b128 v[132:135], v189 offset:1024
	ds_read_b128 v[136:139], v189 offset:2048
	ds_read_b128 v[140:143], v189 offset:3072
	ds_read_b128 v[144:147], v190
	ds_read_b128 v[148:151], v190 offset:1024
	ds_read_b128 v[168:171], v190 offset:2048
	ds_read_b128 v[172:175], v190 offset:3072
	s_add_u32 s44, s36, 0x100
	s_addc_u32 s45, s37, 0
	s_cmp_eq_u32 s59, 40
	s_cselect_b32 s49, s13, s45
	s_cselect_b32 s48, s12, s44
	s_cselect_b32 s47, s35, s58
	s_cselect_b32 s46, s34, s43
	s_mov_b32 m0, s91
	v_lshl_add_u64 v[184:185], s[36:37], 0, v[160:161]
	ds_read_b128 v[176:179], v191
	ds_read_b128 v[180:183], v191 offset:1024
	ds_read_b128 v[192:195], v191 offset:2048
	ds_read_b128 v[196:199], v191 offset:3072
	ds_read_b128 v[200:203], v191 offset:4096
	ds_read_b128 v[204:207], v191 offset:5120
	ds_read_b128 v[208:211], v191 offset:6144
	ds_read_b128 v[212:215], v191 offset:7168
	global_load_lds_dwordx4 v[184:185], off
	v_lshl_add_u64 v[184:185], s[36:37], 0, v[162:163]
	s_add_i32 m0, s74, 0xe000
	s_nop 0
	global_load_lds_dwordx4 v[184:185], off
	s_waitcnt vmcnt(8)
	s_cmp_lt_u32 s3, 4
	s_cbranch_scc1 .Lgls_76
	s_waitcnt lgkmcnt(0)
.Lgls_76:
	s_barrier
	s_setprio 1
	s_waitcnt lgkmcnt(0)
	v_mfma_f32_16x16x32_bf16 v[124:127], v[128:131], v[176:179], v[124:127]
	v_mfma_f32_16x16x32_bf16 v[120:123], v[136:139], v[176:179], v[120:123]
	v_mfma_f32_16x16x32_bf16 v[108:111], v[128:131], v[192:195], v[108:111]
	v_mfma_f32_16x16x32_bf16 v[104:107], v[136:139], v[192:195], v[104:107]
	v_mfma_f32_16x16x32_bf16 v[92:95], v[128:131], v[200:203], v[92:95]
	v_mfma_f32_16x16x32_bf16 v[88:91], v[136:139], v[200:203], v[88:91]
	v_mfma_f32_16x16x32_bf16 v[76:79], v[128:131], v[208:211], v[76:79]
	v_mfma_f32_16x16x32_bf16 v[72:75], v[136:139], v[208:211], v[72:75]
	v_mfma_f32_16x16x32_bf16 v[124:127], v[132:135], v[180:183], v[124:127]
	v_mfma_f32_16x16x32_bf16 v[120:123], v[140:143], v[180:183], v[120:123]
	v_mfma_f32_16x16x32_bf16 v[108:111], v[132:135], v[196:199], v[108:111]
	v_mfma_f32_16x16x32_bf16 v[104:107], v[140:143], v[196:199], v[104:107]
	v_mfma_f32_16x16x32_bf16 v[92:95], v[132:135], v[204:207], v[92:95]
	v_mfma_f32_16x16x32_bf16 v[88:91], v[140:143], v[204:207], v[88:91]
	v_mfma_f32_16x16x32_bf16 v[76:79], v[132:135], v[212:215], v[76:79]
	v_mfma_f32_16x16x32_bf16 v[72:75], v[140:143], v[212:215], v[72:75]
	s_setprio 0
	s_setprio 1
	v_mfma_f32_16x16x32_bf16 v[116:119], v[144:147], v[176:179], v[116:119]
	v_mfma_f32_16x16x32_bf16 v[112:115], v[168:171], v[176:179], v[112:115]
	v_mfma_f32_16x16x32_bf16 v[100:103], v[144:147], v[192:195], v[100:103]
	v_mfma_f32_16x16x32_bf16 v[96:99], v[168:171], v[192:195], v[96:99]
	v_mfma_f32_16x16x32_bf16 v[84:87], v[144:147], v[200:203], v[84:87]
	v_mfma_f32_16x16x32_bf16 v[80:83], v[168:171], v[200:203], v[80:83]
	v_mfma_f32_16x16x32_bf16 v[68:71], v[144:147], v[208:211], v[68:71]
	v_mfma_f32_16x16x32_bf16 v[64:67], v[168:171], v[208:211], v[64:67]
	v_mfma_f32_16x16x32_bf16 v[116:119], v[148:151], v[180:183], v[116:119]
	v_mfma_f32_16x16x32_bf16 v[112:115], v[172:175], v[180:183], v[112:115]
	v_mfma_f32_16x16x32_bf16 v[100:103], v[148:151], v[196:199], v[100:103]
	v_mfma_f32_16x16x32_bf16 v[96:99], v[172:175], v[196:199], v[96:99]
	v_mfma_f32_16x16x32_bf16 v[84:87], v[148:151], v[204:207], v[84:87]
	v_mfma_f32_16x16x32_bf16 v[80:83], v[172:175], v[204:207], v[80:83]
	v_mfma_f32_16x16x32_bf16 v[68:71], v[148:151], v[212:215], v[68:71]
	v_mfma_f32_16x16x32_bf16 v[64:67], v[172:175], v[212:215], v[64:67]
	s_setprio 0
	s_barrier
	s_add_i32 s36, s53, s68
	v_lshl_add_u64 v[184:185], s[46:47], 0, v[154:155]
	s_mov_b32 m0, s36
	ds_read_b128 v[176:179], v191 offset:16384
	ds_read_b128 v[180:183], v191 offset:17408
	ds_read_b128 v[192:195], v191 offset:18432
	ds_read_b128 v[196:199], v191 offset:19456
	ds_read_b128 v[200:203], v191 offset:20480
	ds_read_b128 v[204:207], v191 offset:21504
	ds_read_b128 v[208:211], v191 offset:22528
	ds_read_b128 v[212:215], v191 offset:23552
	global_load_lds_dwordx4 v[184:185], off
	s_add_i32 m0, s36, 0x2000
	s_add_u32 s36, s46, 0xb0000
	v_lshl_add_u64 v[216:217], s[46:47], 0, v[158:159]
	s_addc_u32 s37, s47, 0
	s_add_i32 s60, s54, s68
	global_load_lds_dwordx4 v[216:217], off
	v_lshl_add_u64 v[218:219], s[36:37], 0, v[154:155]
	s_mov_b32 m0, s60
	v_lshl_add_u64 v[220:221], s[48:49], 0, v[156:157]
	global_load_lds_dwordx4 v[218:219], off
	v_lshl_add_u64 v[218:219], s[36:37], 0, v[158:159]
	s_add_i32 m0, s60, 0x2000
	s_nop 0
	global_load_lds_dwordx4 v[218:219], off
	v_lshl_add_u64 v[218:219], s[48:49], 0, v[152:153]
	s_mov_b32 m0, s74
	s_nop 0
	global_load_lds_dwordx4 v[218:219], off
	s_mov_b32 m0, s66
	s_nop 0
	global_load_lds_dwordx4 v[220:221], off
	s_waitcnt vmcnt(8)
	s_cmp_lt_u32 s3, 4
	s_cbranch_scc1 .Lgls_77
	s_waitcnt lgkmcnt(0)
; #define PG8_STAGE(bufoff, gbase, voff) do { _Pragma("unroll") for (int _i = 0; _i < 2; ++_i) \
;         __builtin_amdgcn_global_load_lds((const unsigned*)((const char*)(gbase) + (voff)[_i]), (PG8_LAS unsigned*)(lds + (bufoff) + ldsw + _i * 8192), 16, 0, 0); } while (0)
; #define PG8_LDA(dst, b, h) do { _Pragma("unroll") for (int m = 0; m < 4; ++m) _Pragma("unroll") for (int k = 0; k < 2; ++k) dst[m][k] = *(const PG8_LAS bf16x8*)(lds + PG8_SA(b, h) + aoff + m * 2048 + k * 1024); } while (0)
; #define PG8_LDB(dst, b, h) do { _Pragma("unroll") for (int n = 0; n < 2; ++n) _Pragma("unroll") for (int k = 0; k < 2; ++k) dst[n][k] = *(const PG8_LAS bf16x8*)(lds + PG8_SB(b, h) + boff + n * 2048 + k * 1024); } while (0)
; #define PG8_MMA(ai, bj, At, Bt) do { __builtin_amdgcn_s_setprio(1); _Pragma("unroll") for (int m = 0; m < 4; ++m) _Pragma("unroll") for (int n = 0; n < 2; ++n) _Pragma("unroll") for (int k = 0; k < 2; ++k) \
;         acc[ai][bj][m][n] = mma16<F16>(Bt[n][k], At[m][k], acc[ai][bj][m][n]); __builtin_amdgcn_s_setprio(0); } while (0)
; #define PG8_WAIT_V(n) asm volatile("s_waitcnt vmcnt(" #n ")" ::: "memory")
; #define PG8_WAIT_L(n) asm volatile("s_waitcnt lgkmcnt(" #n ")" ::: "memory")
; #define PG8_BAR __builtin_amdgcn_s_barrier()
; #define PG8_SCHED __builtin_amdgcn_sched_barrier(0)
; template <class Epi, class Sched, bool ALIGN_EPI = false, bool SP2 = false, bool F16 = false>
; __device__ __forceinline__ void gemm_phase(PG8_LAS unsigned char* lds, const Gemm g, const Sched& S, const Epi& E, const int wid_in) {
;     ...
;             PG8_LDA(At, 0, 1); PG8_STAGE(PG8_SB(0, 0), b2, voffB); PG8_STAGE(PG8_SB(0, 1), b2 + hstep, voffB); PG8_STAGE(PG8_SA(0, 0), a2, voffA);
;             PG8_WAIT_V(8); PG8_WAIT_L(0); PG8_BAR; PG8_MMA(1, 0, At, B0); PG8_MMA(1, 1, At, B1); PG8_BAR; PG8_SCHED;
;             PG8_LDB(B0, 1, 0); PG8_LDB(B1, 1, 1); PG8_SCHED; PG8_LDA(At, 1, 0); PG8_STAGE(PG8_SA(0, 1), a2 + hstep, voffA);
;             PG8_WAIT_V(8); PG8_WAIT_L(0); PG8_BAR; PG8_MMA(0, 0, At, B0); PG8_MMA(0, 1, At, B1); PG8_BAR; PG8_SCHED;
;             PG8_LDA(At, 1, 1); PG8_STAGE(PG8_SB(1, 0), b3, voffB); PG8_STAGE(PG8_SB(1, 1), b3 + hstep, voffB); PG8_STAGE(PG8_SA(1, 0), a3, voffA);
.Lgls_77:
	s_barrier
	s_setprio 1
	s_waitcnt lgkmcnt(0)
	v_mfma_f32_16x16x32_bf16 v[60:63], v[128:131], v[176:179], v[60:63]
	v_mfma_f32_16x16x32_bf16 v[56:59], v[136:139], v[176:179], v[56:59]
	v_mfma_f32_16x16x32_bf16 v[44:47], v[128:131], v[192:195], v[44:47]
	v_mfma_f32_16x16x32_bf16 v[40:43], v[136:139], v[192:195], v[40:43]
	v_mfma_f32_16x16x32_bf16 v[28:31], v[128:131], v[200:203], v[28:31]
	v_mfma_f32_16x16x32_bf16 v[24:27], v[136:139], v[200:203], v[24:27]
	v_mfma_f32_16x16x32_bf16 v[12:15], v[128:131], v[208:211], v[12:15]
	v_mfma_f32_16x16x32_bf16 v[8:11], v[136:139], v[208:211], v[8:11]
	v_mfma_f32_16x16x32_bf16 v[60:63], v[132:135], v[180:183], v[60:63]
	v_mfma_f32_16x16x32_bf16 v[56:59], v[140:143], v[180:183], v[56:59]
	v_mfma_f32_16x16x32_bf16 v[44:47], v[132:135], v[196:199], v[44:47]
	v_mfma_f32_16x16x32_bf16 v[40:43], v[140:143], v[196:199], v[40:43]
	v_mfma_f32_16x16x32_bf16 v[28:31], v[132:135], v[204:207], v[28:31]
	v_mfma_f32_16x16x32_bf16 v[24:27], v[140:143], v[204:207], v[24:27]
	v_mfma_f32_16x16x32_bf16 v[12:15], v[132:135], v[212:215], v[12:15]
	v_mfma_f32_16x16x32_bf16 v[8:11], v[140:143], v[212:215], v[8:11]
	s_setprio 0
	s_setprio 1
	v_mfma_f32_16x16x32_bf16 v[52:55], v[144:147], v[176:179], v[52:55]
	v_mfma_f32_16x16x32_bf16 v[48:51], v[168:171], v[176:179], v[48:51]
	v_mfma_f32_16x16x32_bf16 v[36:39], v[144:147], v[192:195], v[36:39]
	v_mfma_f32_16x16x32_bf16 v[32:35], v[168:171], v[192:195], v[32:35]
	v_mfma_f32_16x16x32_bf16 v[20:23], v[144:147], v[200:203], v[20:23]
	v_mfma_f32_16x16x32_bf16 v[16:19], v[168:171], v[200:203], v[16:19]
	v_mfma_f32_16x16x32_bf16 v[4:7], v[144:147], v[208:211], v[4:7]
	v_mfma_f32_16x16x32_bf16 v[0:3], v[168:171], v[208:211], v[0:3]
	v_mfma_f32_16x16x32_bf16 v[52:55], v[148:151], v[180:183], v[52:55]
	v_mfma_f32_16x16x32_bf16 v[48:51], v[172:175], v[180:183], v[48:51]
	v_mfma_f32_16x16x32_bf16 v[36:39], v[148:151], v[196:199], v[36:39]
	v_mfma_f32_16x16x32_bf16 v[32:35], v[172:175], v[196:199], v[32:35]
	v_mfma_f32_16x16x32_bf16 v[20:23], v[148:151], v[204:207], v[20:23]
	v_mfma_f32_16x16x32_bf16 v[16:19], v[172:175], v[204:207], v[16:19]
	v_mfma_f32_16x16x32_bf16 v[4:7], v[148:151], v[212:215], v[4:7]
	v_mfma_f32_16x16x32_bf16 v[0:3], v[172:175], v[212:215], v[0:3]
	s_setprio 0
	s_barrier
	s_add_i32 s60, 0, 0x18000
	s_add_i32 s61, 0, 0x1c000
	v_add_u32_e32 v140, s60, v188
	v_add_u32_e32 v172, s61, v188
	ds_read_b128 v[128:131], v140
	ds_read_b128 v[132:135], v140 offset:1024
	ds_read_b128 v[136:139], v140 offset:2048
	ds_read_b128 v[140:143], v140 offset:3072
	ds_read_b128 v[144:147], v172
	ds_read_b128 v[148:151], v172 offset:1024
	ds_read_b128 v[168:171], v172 offset:2048
	ds_read_b128 v[172:175], v172 offset:3072
	s_add_u32 s36, s48, 0xb0000
	s_addc_u32 s37, s49, 0
	s_mov_b32 m0, s90
	v_lshl_add_u64 v[222:223], s[36:37], 0, v[152:153]
	ds_read_b128 v[176:179], v191 offset:32768
	ds_read_b128 v[180:183], v191 offset:33792
	ds_read_b128 v[192:195], v191 offset:34816
	ds_read_b128 v[196:199], v191 offset:35840
	ds_read_b128 v[200:203], v191 offset:36864
	ds_read_b128 v[204:207], v191 offset:37888
	ds_read_b128 v[208:211], v191 offset:38912
	ds_read_b128 v[212:215], v191 offset:39936
	global_load_lds_dwordx4 v[222:223], off
	v_lshl_add_u64 v[222:223], s[36:37], 0, v[156:157]
	s_mov_b32 m0, s41
	s_nop 0
	global_load_lds_dwordx4 v[222:223], off
	s_waitcnt vmcnt(8)
	s_cmp_lt_u32 s3, 4
	s_cbranch_scc1 .Lgls_78
	s_waitcnt lgkmcnt(0)
; #define PG8_STAGE(bufoff, gbase, voff) do { _Pragma("unroll") for (int _i = 0; _i < 2; ++_i) \
;         __builtin_amdgcn_global_load_lds((const unsigned*)((const char*)(gbase) + (voff)[_i]), (PG8_LAS unsigned*)(lds + (bufoff) + ldsw + _i * 8192), 16, 0, 0); } while (0)
; #define PG8_LDA(dst, b, h) do { _Pragma("unroll") for (int m = 0; m < 4; ++m) _Pragma("unroll") for (int k = 0; k < 2; ++k) dst[m][k] = *(const PG8_LAS bf16x8*)(lds + PG8_SA(b, h) + aoff + m * 2048 + k * 1024); } while (0)
; #define PG8_LDB(dst, b, h) do { _Pragma("unroll") for (int n = 0; n < 2; ++n) _Pragma("unroll") for (int k = 0; k < 2; ++k) dst[n][k] = *(const PG8_LAS bf16x8*)(lds + PG8_SB(b, h) + boff + n * 2048 + k * 1024); } while (0)
; #define PG8_MMA(ai, bj, At, Bt) do { __builtin_amdgcn_s_setprio(1); _Pragma("unroll") for (int m = 0; m < 4; ++m) _Pragma("unroll") for (int n = 0; n < 2; ++n) _Pragma("unroll") for (int k = 0; k < 2; ++k) \
;         acc[ai][bj][m][n] = mma16<F16>(Bt[n][k], At[m][k], acc[ai][bj][m][n]); __builtin_amdgcn_s_setprio(0); } while (0)
; #define PG8_WAIT_V(n) asm volatile("s_waitcnt vmcnt(" #n ")" ::: "memory")
; #define PG8_WAIT_L(n) asm volatile("s_waitcnt lgkmcnt(" #n ")" ::: "memory")
; #define PG8_BAR __builtin_amdgcn_s_barrier()
; #define PG8_SCHED __builtin_amdgcn_sched_barrier(0)
; template <class Epi, class Sched, bool ALIGN_EPI = false, bool SP2 = false, bool F16 = false>
; __device__ __forceinline__ void gemm_phase(PG8_LAS unsigned char* lds, const Gemm g, const Sched& S, const Epi& E, const int wid_in) {
;     ...
;             PG8_LDB(B0, 1, 0); PG8_LDB(B1, 1, 1); PG8_SCHED; PG8_LDA(At, 1, 0); PG8_STAGE(PG8_SA(0, 1), a2 + hstep, voffA);
;             PG8_WAIT_V(8); PG8_WAIT_L(0); PG8_BAR; PG8_MMA(0, 0, At, B0); PG8_MMA(0, 1, At, B1); PG8_BAR; PG8_SCHED;
;             PG8_LDA(At, 1, 1); PG8_STAGE(PG8_SB(1, 0), b3, voffB); PG8_STAGE(PG8_SB(1, 1), b3 + hstep, voffB); PG8_STAGE(PG8_SA(1, 0), a3, voffA);
;             PG8_WAIT_V(8); PG8_WAIT_L(0); PG8_BAR; PG8_MMA(1, 0, At, B0); PG8_MMA(1, 1, At, B1); PG8_BAR; PG8_SCHED;
;     ...
;         if constexpr (ALIGN_EPI) { if (wr == 0) PG8_BAR; }
.Lgls_78:
	s_barrier
	s_setprio 1
	s_waitcnt lgkmcnt(0)
	v_mfma_f32_16x16x32_bf16 v[124:127], v[128:131], v[176:179], v[124:127]
	v_mfma_f32_16x16x32_bf16 v[120:123], v[136:139], v[176:179], v[120:123]
	v_mfma_f32_16x16x32_bf16 v[108:111], v[128:131], v[192:195], v[108:111]
	v_mfma_f32_16x16x32_bf16 v[104:107], v[136:139], v[192:195], v[104:107]
	v_mfma_f32_16x16x32_bf16 v[92:95], v[128:131], v[200:203], v[92:95]
	v_mfma_f32_16x16x32_bf16 v[88:91], v[136:139], v[200:203], v[88:91]
	v_mfma_f32_16x16x32_bf16 v[76:79], v[128:131], v[208:211], v[76:79]
	v_mfma_f32_16x16x32_bf16 v[72:75], v[136:139], v[208:211], v[72:75]
	v_mfma_f32_16x16x32_bf16 v[124:127], v[132:135], v[180:183], v[124:127]
	v_mfma_f32_16x16x32_bf16 v[120:123], v[140:143], v[180:183], v[120:123]
	v_mfma_f32_16x16x32_bf16 v[108:111], v[132:135], v[196:199], v[108:111]
	v_mfma_f32_16x16x32_bf16 v[104:107], v[140:143], v[196:199], v[104:107]
	v_mfma_f32_16x16x32_bf16 v[92:95], v[132:135], v[204:207], v[92:95]
	v_mfma_f32_16x16x32_bf16 v[88:91], v[140:143], v[204:207], v[88:91]
	v_mfma_f32_16x16x32_bf16 v[76:79], v[132:135], v[212:215], v[76:79]
	v_mfma_f32_16x16x32_bf16 v[72:75], v[140:143], v[212:215], v[72:75]
	s_setprio 0
	s_setprio 1
	v_mfma_f32_16x16x32_bf16 v[116:119], v[144:147], v[176:179], v[116:119]
	v_mfma_f32_16x16x32_bf16 v[112:115], v[168:171], v[176:179], v[112:115]
	v_mfma_f32_16x16x32_bf16 v[100:103], v[144:147], v[192:195], v[100:103]
	v_mfma_f32_16x16x32_bf16 v[96:99], v[168:171], v[192:195], v[96:99]
	v_mfma_f32_16x16x32_bf16 v[84:87], v[144:147], v[200:203], v[84:87]
	v_mfma_f32_16x16x32_bf16 v[80:83], v[168:171], v[200:203], v[80:83]
	v_mfma_f32_16x16x32_bf16 v[68:71], v[144:147], v[208:211], v[68:71]
	v_mfma_f32_16x16x32_bf16 v[64:67], v[168:171], v[208:211], v[64:67]
	v_mfma_f32_16x16x32_bf16 v[116:119], v[148:151], v[180:183], v[116:119]
	v_mfma_f32_16x16x32_bf16 v[112:115], v[172:175], v[180:183], v[112:115]
	v_mfma_f32_16x16x32_bf16 v[100:103], v[148:151], v[196:199], v[100:103]
	v_mfma_f32_16x16x32_bf16 v[96:99], v[172:175], v[196:199], v[96:99]
	v_mfma_f32_16x16x32_bf16 v[84:87], v[148:151], v[204:207], v[84:87]
	v_mfma_f32_16x16x32_bf16 v[80:83], v[172:175], v[204:207], v[80:83]
	v_mfma_f32_16x16x32_bf16 v[68:71], v[148:151], v[212:215], v[68:71]
	v_mfma_f32_16x16x32_bf16 v[64:67], v[172:175], v[212:215], v[64:67]
	s_setprio 0
	s_barrier
	s_add_i32 s36, s60, s68
	v_lshl_add_u64 v[184:185], v[184:185], 0, s[30:31]
	s_mov_b32 m0, s36
	ds_read_b128 v[176:179], v191 offset:49152
	ds_read_b128 v[180:183], v191 offset:50176
	ds_read_b128 v[192:195], v191 offset:51200
	ds_read_b128 v[196:199], v191 offset:52224
	ds_read_b128 v[200:203], v191 offset:53248
	ds_read_b128 v[204:207], v191 offset:54272
	ds_read_b128 v[208:211], v191 offset:55296
	ds_read_b128 v[212:215], v191 offset:56320
	global_load_lds_dwordx4 v[184:185], off
	s_add_i32 m0, s36, 0x2000
	s_add_u32 s36, s46, 0xb0080
	v_lshl_add_u64 v[184:185], v[216:217], 0, s[30:31]
	s_addc_u32 s37, s47, 0
	s_add_i32 s46, s61, s68
	global_load_lds_dwordx4 v[184:185], off
	v_lshl_add_u64 v[184:185], s[36:37], 0, v[154:155]
	s_mov_b32 m0, s46
	s_nop 0
	global_load_lds_dwordx4 v[184:185], off
	v_lshl_add_u64 v[184:185], s[36:37], 0, v[158:159]
	s_add_i32 m0, s46, 0x2000
	s_nop 0
	global_load_lds_dwordx4 v[184:185], off
	v_lshl_add_u64 v[184:185], v[218:219], 0, s[30:31]
	s_mov_b32 m0, s75
	s_nop 0
	global_load_lds_dwordx4 v[184:185], off
	v_lshl_add_u64 v[184:185], v[220:221], 0, s[30:31]
	s_mov_b32 m0, s67
	s_nop 0
	global_load_lds_dwordx4 v[184:185], off
	s_waitcnt vmcnt(8)
	s_cmp_lt_u32 s3, 4
	s_cbranch_scc1 .Lgls_79
	s_waitcnt lgkmcnt(0)
.Lgls_79:
	s_barrier
	s_setprio 1
	s_waitcnt lgkmcnt(0)
	v_mfma_f32_16x16x32_bf16 v[60:63], v[128:131], v[176:179], v[60:63]
	v_mfma_f32_16x16x32_bf16 v[56:59], v[136:139], v[176:179], v[56:59]
	v_mfma_f32_16x16x32_bf16 v[44:47], v[128:131], v[192:195], v[44:47]
	v_mfma_f32_16x16x32_bf16 v[40:43], v[136:139], v[192:195], v[40:43]
	v_mfma_f32_16x16x32_bf16 v[28:31], v[128:131], v[200:203], v[28:31]
	v_mfma_f32_16x16x32_bf16 v[24:27], v[136:139], v[200:203], v[24:27]
	v_mfma_f32_16x16x32_bf16 v[12:15], v[128:131], v[208:211], v[12:15]
	v_mfma_f32_16x16x32_bf16 v[8:11], v[136:139], v[208:211], v[8:11]
	v_mfma_f32_16x16x32_bf16 v[60:63], v[132:135], v[180:183], v[60:63]
	v_mfma_f32_16x16x32_bf16 v[56:59], v[140:143], v[180:183], v[56:59]
	v_mfma_f32_16x16x32_bf16 v[44:47], v[132:135], v[196:199], v[44:47]
	v_mfma_f32_16x16x32_bf16 v[40:43], v[140:143], v[196:199], v[40:43]
	v_mfma_f32_16x16x32_bf16 v[28:31], v[132:135], v[204:207], v[28:31]
	v_mfma_f32_16x16x32_bf16 v[24:27], v[140:143], v[204:207], v[24:27]
	v_mfma_f32_16x16x32_bf16 v[12:15], v[132:135], v[212:215], v[12:15]
	v_mfma_f32_16x16x32_bf16 v[8:11], v[140:143], v[212:215], v[8:11]
	s_setprio 0
	s_setprio 1
	v_mfma_f32_16x16x32_bf16 v[52:55], v[144:147], v[176:179], v[52:55]
	v_mfma_f32_16x16x32_bf16 v[48:51], v[168:171], v[176:179], v[48:51]
	v_mfma_f32_16x16x32_bf16 v[36:39], v[144:147], v[192:195], v[36:39]
	v_mfma_f32_16x16x32_bf16 v[32:35], v[168:171], v[192:195], v[32:35]
	v_mfma_f32_16x16x32_bf16 v[20:23], v[144:147], v[200:203], v[20:23]
	v_mfma_f32_16x16x32_bf16 v[16:19], v[168:171], v[200:203], v[16:19]
	v_mfma_f32_16x16x32_bf16 v[4:7], v[144:147], v[208:211], v[4:7]
	v_mfma_f32_16x16x32_bf16 v[0:3], v[168:171], v[208:211], v[0:3]
	v_mfma_f32_16x16x32_bf16 v[52:55], v[148:151], v[180:183], v[52:55]
	v_mfma_f32_16x16x32_bf16 v[48:51], v[172:175], v[180:183], v[48:51]
	v_mfma_f32_16x16x32_bf16 v[36:39], v[148:151], v[196:199], v[36:39]
	v_mfma_f32_16x16x32_bf16 v[32:35], v[172:175], v[196:199], v[32:35]
	v_mfma_f32_16x16x32_bf16 v[20:23], v[148:151], v[204:207], v[20:23]
	v_mfma_f32_16x16x32_bf16 v[16:19], v[172:175], v[204:207], v[16:19]
	v_mfma_f32_16x16x32_bf16 v[4:7], v[148:151], v[212:215], v[4:7]
	v_mfma_f32_16x16x32_bf16 v[0:3], v[172:175], v[212:215], v[0:3]
	s_setprio 0
	s_barrier
	s_add_i32 s59, s59, 2
	s_add_u32 s43, s43, 0x100
	s_addc_u32 s58, s58, 0
	s_cmp_gt_u32 s59, 41
	s_mov_b64 s[36:37], s[44:45]
	s_cbranch_scc0 .LBB0_2040
	s_and_b64 vcc, exec, s[16:17]
	s_cbranch_vccz .LBB0_2043
	s_barrier

; #define PG8_STAGE(bufoff, gbase, voff) do { _Pragma("unroll") for (int _i = 0; _i < 2; ++_i) \
;         __builtin_amdgcn_global_load_lds((const unsigned*)((const char*)(gbase) + (voff)[_i]), (PG8_LAS unsigned*)(lds + (bufoff) + ldsw + _i * 8192), 16, 0, 0); } while (0)
; #define PG8_LDA(dst, b, h) do { _Pragma("unroll") for (int m = 0; m < 4; ++m) _Pragma("unroll") for (int k = 0; k < 2; ++k) dst[m][k] = *(const PG8_LAS bf16x8*)(lds + PG8_SA(b, h) + aoff + m * 2048 + k * 1024); } while (0)
; #define PG8_LDB(dst, b, h) do { _Pragma("unroll") for (int n = 0; n < 2; ++n) _Pragma("unroll") for (int k = 0; k < 2; ++k) dst[n][k] = *(const PG8_LAS bf16x8*)(lds + PG8_SB(b, h) + boff + n * 2048 + k * 1024); } while (0)
; #define PG8_MMA(ai, bj, At, Bt) do { __builtin_amdgcn_s_setprio(1); _Pragma("unroll") for (int m = 0; m < 4; ++m) _Pragma("unroll") for (int n = 0; n < 2; ++n) _Pragma("unroll") for (int k = 0; k < 2; ++k) \
;         acc[ai][bj][m][n] = mma16<F16>(Bt[n][k], At[m][k], acc[ai][bj][m][n]); __builtin_amdgcn_s_setprio(0); } while (0)
; #define PG8_WAIT_V(n) asm volatile("s_waitcnt vmcnt(" #n ")" ::: "memory")
; #define PG8_WAIT_L(n) asm volatile("s_waitcnt lgkmcnt(" #n ")" ::: "memory")
; #define PG8_BAR __builtin_amdgcn_s_barrier()
; #define PG8_SCHED __builtin_amdgcn_sched_barrier(0)
; template <class Epi, class Sched, bool ALIGN_EPI = false, bool SP2 = false, bool F16 = false>
; __device__ __forceinline__ void gemm_phase(PG8_LAS unsigned char* lds, const Gemm g, const Sched& S, const Epi& E, const int wid_in) {
;     ...
;         for (int t = 0; t < nt; t += 2) {
;             const bool last = (t == nt - 2);
;             const char* a1 = cA + (size_t)(t + 1) * kstep;
;             const char* a2 = last ? nA : cA + (size_t)(t + 2) * kstep; const char* b2 = last ? nB : cB + (size_t)(t + 2) * kstep;
;             const char* a3 = a2 + kstep; const char* b3 = b2 + kstep;
;             if (last && has_next) S.a_ready(nxt);
;             if constexpr (SP2) {
;             PG8_LDB(B0, 0, 0); PG8_LDB(B1, 0, 1); PG8_SCHED; PG8_LDA(At, 0, 0); PG8_STAGE(PG8_SA(1, 1), a1 + hstep, voffA);
;             PG8_WAIT_V(8); PG8_WAIT_L(0); PG8_BAR; PG8_MMA(0, 0, At, B0); PG8_MMA(0, 1, At, B1); PG8_BAR; PG8_SCHED;
;             PG8_LDA(At, 0, 1); PG8_STAGE(PG8_SB(0, 0), b2, voffB); PG8_STAGE(PG8_SB(0, 1), b2 + hstep, voffB); PG8_STAGE(PG8_SA(0, 0), a2, voffA);
.LBB0_2136:
	ds_read_b128 v[112:115], v235
	ds_read_b128 v[116:119], v235 offset:1024
	ds_read_b128 v[128:131], v235 offset:2048
	ds_read_b128 v[132:135], v235 offset:3072
	ds_read_b128 v[144:147], v236
	ds_read_b128 v[148:151], v236 offset:1024
	ds_read_b128 v[152:155], v236 offset:2048
	ds_read_b128 v[156:159], v236 offset:3072
	s_add_u32 s45, s52, 0xfffc0080
	s_addc_u32 s51, s53, -1
	s_cmp_eq_u32 s43, 12
	s_cselect_b32 s57, s14, s51
	s_cselect_b32 s56, s15, s45
	s_cselect_b32 s55, s37, s42
	s_cselect_b32 s54, s40, s41
	s_mov_b32 m0, s91
	v_lshl_add_u64 v[192:193], s[52:53], 0, v[204:205]
	ds_read_b128 v[160:163], v237
	ds_read_b128 v[164:167], v237 offset:1024
	ds_read_b128 v[168:171], v237 offset:2048
	ds_read_b128 v[172:175], v237 offset:3072
	ds_read_b128 v[176:179], v237 offset:4096
	ds_read_b128 v[180:183], v237 offset:5120
	ds_read_b128 v[184:187], v237 offset:6144
	ds_read_b128 v[188:191], v237 offset:7168
	global_load_lds_dwordx4 v[192:193], off
	v_lshl_add_u64 v[192:193], s[52:53], 0, v[206:207]
	s_add_i32 m0, s74, 0xe000
	s_nop 0
	global_load_lds_dwordx4 v[192:193], off
	s_waitcnt vmcnt(8)
	s_cmp_lt_u32 s3, 4
	s_cbranch_scc1 .Lgls_80
	s_waitcnt lgkmcnt(0)
.Lgls_80:
	s_barrier
	s_setprio 1
	s_waitcnt lgkmcnt(0)
	v_mfma_f32_16x16x32_f16 v[140:143], v[112:115], v[160:163], v[140:143]
	v_mfma_f32_16x16x32_f16 v[136:139], v[128:131], v[160:163], v[136:139]
	v_mfma_f32_16x16x32_f16 v[108:111], v[112:115], v[168:171], v[108:111]
	v_mfma_f32_16x16x32_f16 v[104:107], v[128:131], v[168:171], v[104:107]
	v_mfma_f32_16x16x32_f16 v[92:95], v[112:115], v[176:179], v[92:95]
	v_mfma_f32_16x16x32_f16 v[88:91], v[128:131], v[176:179], v[88:91]
	v_mfma_f32_16x16x32_f16 v[76:79], v[112:115], v[184:187], v[76:79]
	v_mfma_f32_16x16x32_f16 v[72:75], v[128:131], v[184:187], v[72:75]
	v_mfma_f32_16x16x32_f16 v[140:143], v[116:119], v[164:167], v[140:143]
	v_mfma_f32_16x16x32_f16 v[136:139], v[132:135], v[164:167], v[136:139]
	v_mfma_f32_16x16x32_f16 v[108:111], v[116:119], v[172:175], v[108:111]
	v_mfma_f32_16x16x32_f16 v[104:107], v[132:135], v[172:175], v[104:107]
	v_mfma_f32_16x16x32_f16 v[92:95], v[116:119], v[180:183], v[92:95]
	v_mfma_f32_16x16x32_f16 v[88:91], v[132:135], v[180:183], v[88:91]
	v_mfma_f32_16x16x32_f16 v[76:79], v[116:119], v[188:191], v[76:79]
	v_mfma_f32_16x16x32_f16 v[72:75], v[132:135], v[188:191], v[72:75]
	s_setprio 0
	s_setprio 1
	v_mfma_f32_16x16x32_f16 v[124:127], v[144:147], v[160:163], v[124:127]
	v_mfma_f32_16x16x32_f16 v[120:123], v[152:155], v[160:163], v[120:123]
	v_mfma_f32_16x16x32_f16 v[100:103], v[144:147], v[168:171], v[100:103]
	v_mfma_f32_16x16x32_f16 v[96:99], v[152:155], v[168:171], v[96:99]
	v_mfma_f32_16x16x32_f16 v[84:87], v[144:147], v[176:179], v[84:87]
	v_mfma_f32_16x16x32_f16 v[80:83], v[152:155], v[176:179], v[80:83]
	v_mfma_f32_16x16x32_f16 v[68:71], v[144:147], v[184:187], v[68:71]
	v_mfma_f32_16x16x32_f16 v[64:67], v[152:155], v[184:187], v[64:67]
	v_mfma_f32_16x16x32_f16 v[124:127], v[148:151], v[164:167], v[124:127]
	v_mfma_f32_16x16x32_f16 v[120:123], v[156:159], v[164:167], v[120:123]
	v_mfma_f32_16x16x32_f16 v[100:103], v[148:151], v[172:175], v[100:103]
	v_mfma_f32_16x16x32_f16 v[96:99], v[156:159], v[172:175], v[96:99]
	v_mfma_f32_16x16x32_f16 v[84:87], v[148:151], v[180:183], v[84:87]
	v_mfma_f32_16x16x32_f16 v[80:83], v[156:159], v[180:183], v[80:83]
	v_mfma_f32_16x16x32_f16 v[68:71], v[148:151], v[188:191], v[68:71]
	v_mfma_f32_16x16x32_f16 v[64:67], v[156:159], v[188:191], v[64:67]
	s_setprio 0
	s_barrier
	s_add_i32 s45, s63, s68
	v_lshl_add_u64 v[192:193], s[54:55], 0, v[198:199]
	s_mov_b32 m0, s45
	ds_read_b128 v[160:163], v237 offset:16384
	ds_read_b128 v[164:167], v237 offset:17408
	ds_read_b128 v[168:171], v237 offset:18432
	ds_read_b128 v[172:175], v237 offset:19456
	ds_read_b128 v[176:179], v237 offset:20480
	ds_read_b128 v[180:183], v237 offset:21504
	ds_read_b128 v[184:187], v237 offset:22528
	ds_read_b128 v[188:191], v237 offset:23552
	global_load_lds_dwordx4 v[192:193], off
	s_add_i32 m0, s45, 0x2000
	s_add_u32 s84, s54, 0x40000
	v_lshl_add_u64 v[194:195], s[54:55], 0, v[202:203]
	s_addc_u32 s85, s55, 0
	s_add_i32 s45, s64, s68
	global_load_lds_dwordx4 v[194:195], off
	v_lshl_add_u64 v[212:213], s[84:85], 0, v[198:199]
	s_mov_b32 m0, s45
	v_lshl_add_u64 v[214:215], s[56:57], 0, v[200:201]
	global_load_lds_dwordx4 v[212:213], off
	v_lshl_add_u64 v[212:213], s[84:85], 0, v[202:203]
	s_add_i32 m0, s45, 0x2000
	s_nop 0
	global_load_lds_dwordx4 v[212:213], off
	v_lshl_add_u64 v[212:213], s[56:57], 0, v[196:197]
	s_mov_b32 m0, s74
	s_nop 0
	global_load_lds_dwordx4 v[212:213], off
	s_mov_b32 m0, s66
	s_nop 0
	global_load_lds_dwordx4 v[214:215], off
	s_waitcnt vmcnt(8)
	s_cmp_lt_u32 s3, 4
	s_cbranch_scc1 .Lgls_81
	s_waitcnt lgkmcnt(0)
; #define PG8_STAGE(bufoff, gbase, voff) do { _Pragma("unroll") for (int _i = 0; _i < 2; ++_i) \
;         __builtin_amdgcn_global_load_lds((const unsigned*)((const char*)(gbase) + (voff)[_i]), (PG8_LAS unsigned*)(lds + (bufoff) + ldsw + _i * 8192), 16, 0, 0); } while (0)
; #define PG8_LDA(dst, b, h) do { _Pragma("unroll") for (int m = 0; m < 4; ++m) _Pragma("unroll") for (int k = 0; k < 2; ++k) dst[m][k] = *(const PG8_LAS bf16x8*)(lds + PG8_SA(b, h) + aoff + m * 2048 + k * 1024); } while (0)
; #define PG8_LDB(dst, b, h) do { _Pragma("unroll") for (int n = 0; n < 2; ++n) _Pragma("unroll") for (int k = 0; k < 2; ++k) dst[n][k] = *(const PG8_LAS bf16x8*)(lds + PG8_SB(b, h) + boff + n * 2048 + k * 1024); } while (0)
; #define PG8_MMA(ai, bj, At, Bt) do { __builtin_amdgcn_s_setprio(1); _Pragma("unroll") for (int m = 0; m < 4; ++m) _Pragma("unroll") for (int n = 0; n < 2; ++n) _Pragma("unroll") for (int k = 0; k < 2; ++k) \
;         acc[ai][bj][m][n] = mma16<F16>(Bt[n][k], At[m][k], acc[ai][bj][m][n]); __builtin_amdgcn_s_setprio(0); } while (0)
; #define PG8_WAIT_V(n) asm volatile("s_waitcnt vmcnt(" #n ")" ::: "memory")
; #define PG8_WAIT_L(n) asm volatile("s_waitcnt lgkmcnt(" #n ")" ::: "memory")
; #define PG8_BAR __builtin_amdgcn_s_barrier()
; #define PG8_SCHED __builtin_amdgcn_sched_barrier(0)
; template <class Epi, class Sched, bool ALIGN_EPI = false, bool SP2 = false, bool F16 = false>
; __device__ __forceinline__ void gemm_phase(PG8_LAS unsigned char* lds, const Gemm g, const Sched& S, const Epi& E, const int wid_in) {
;     ...
;             PG8_WAIT_V(8); PG8_WAIT_L(0); PG8_BAR; PG8_MMA(1, 0, At, B0); PG8_MMA(1, 1, At, B1); PG8_BAR; PG8_SCHED;
;             PG8_LDB(B0, 1, 0); PG8_LDB(B1, 1, 1); PG8_SCHED; PG8_LDA(At, 1, 0); PG8_STAGE(PG8_SA(0, 1), a2 + hstep, voffA);
;             PG8_WAIT_V(8); PG8_WAIT_L(0); PG8_BAR; PG8_MMA(0, 0, At, B0); PG8_MMA(0, 1, At, B1); PG8_BAR; PG8_SCHED;
;             PG8_LDA(At, 1, 1); PG8_STAGE(PG8_SB(1, 0), b3, voffB); PG8_STAGE(PG8_SB(1, 1), b3 + hstep, voffB); PG8_STAGE(PG8_SA(1, 0), a3, voffA);
;             PG8_WAIT_V(8); PG8_WAIT_L(0); PG8_BAR; PG8_MMA(1, 0, At, B0); PG8_MMA(1, 1, At, B1); PG8_BAR; PG8_SCHED;
.Lgls_81:
	s_barrier
	s_setprio 1
	s_waitcnt lgkmcnt(0)
	v_mfma_f32_16x16x32_f16 v[60:63], v[112:115], v[160:163], v[60:63]
	v_mfma_f32_16x16x32_f16 v[56:59], v[128:131], v[160:163], v[56:59]
	v_mfma_f32_16x16x32_f16 v[44:47], v[112:115], v[168:171], v[44:47]
	v_mfma_f32_16x16x32_f16 v[40:43], v[128:131], v[168:171], v[40:43]
	v_mfma_f32_16x16x32_f16 v[28:31], v[112:115], v[176:179], v[28:31]
	v_mfma_f32_16x16x32_f16 v[24:27], v[128:131], v[176:179], v[24:27]
	v_mfma_f32_16x16x32_f16 v[12:15], v[112:115], v[184:187], v[12:15]
	v_mfma_f32_16x16x32_f16 v[8:11], v[128:131], v[184:187], v[8:11]
	v_mfma_f32_16x16x32_f16 v[60:63], v[116:119], v[164:167], v[60:63]
	v_mfma_f32_16x16x32_f16 v[56:59], v[132:135], v[164:167], v[56:59]
	v_mfma_f32_16x16x32_f16 v[44:47], v[116:119], v[172:175], v[44:47]
	v_mfma_f32_16x16x32_f16 v[40:43], v[132:135], v[172:175], v[40:43]
	v_mfma_f32_16x16x32_f16 v[28:31], v[116:119], v[180:183], v[28:31]
	v_mfma_f32_16x16x32_f16 v[24:27], v[132:135], v[180:183], v[24:27]
	v_mfma_f32_16x16x32_f16 v[12:15], v[116:119], v[188:191], v[12:15]
	v_mfma_f32_16x16x32_f16 v[8:11], v[132:135], v[188:191], v[8:11]
	s_setprio 0
	s_setprio 1
	v_mfma_f32_16x16x32_f16 v[52:55], v[144:147], v[160:163], v[52:55]
	v_mfma_f32_16x16x32_f16 v[48:51], v[152:155], v[160:163], v[48:51]
	v_mfma_f32_16x16x32_f16 v[36:39], v[144:147], v[168:171], v[36:39]
	v_mfma_f32_16x16x32_f16 v[32:35], v[152:155], v[168:171], v[32:35]
	v_mfma_f32_16x16x32_f16 v[20:23], v[144:147], v[176:179], v[20:23]
	v_mfma_f32_16x16x32_f16 v[16:19], v[152:155], v[176:179], v[16:19]
	v_mfma_f32_16x16x32_f16 v[4:7], v[144:147], v[184:187], v[4:7]
	v_mfma_f32_16x16x32_f16 v[0:3], v[152:155], v[184:187], v[0:3]
	v_mfma_f32_16x16x32_f16 v[52:55], v[148:151], v[164:167], v[52:55]
	v_mfma_f32_16x16x32_f16 v[48:51], v[156:159], v[164:167], v[48:51]
	v_mfma_f32_16x16x32_f16 v[36:39], v[148:151], v[172:175], v[36:39]
	v_mfma_f32_16x16x32_f16 v[32:35], v[156:159], v[172:175], v[32:35]
	v_mfma_f32_16x16x32_f16 v[20:23], v[148:151], v[180:183], v[20:23]
	v_mfma_f32_16x16x32_f16 v[16:19], v[156:159], v[180:183], v[16:19]
	v_mfma_f32_16x16x32_f16 v[4:7], v[148:151], v[188:191], v[4:7]
	v_mfma_f32_16x16x32_f16 v[0:3], v[156:159], v[188:191], v[0:3]
	s_setprio 0
	s_barrier
	s_add_i32 s45, 0, 0x18000
	s_add_i32 s51, 0, 0x1c000
	v_add_u32_e32 v132, s45, v234
	v_add_u32_e32 v156, s51, v234
	ds_read_b128 v[112:115], v132
	ds_read_b128 v[116:119], v132 offset:1024
	ds_read_b128 v[128:131], v132 offset:2048
	ds_read_b128 v[132:135], v132 offset:3072
	ds_read_b128 v[144:147], v156
	ds_read_b128 v[148:151], v156 offset:1024
	ds_read_b128 v[152:155], v156 offset:2048
	ds_read_b128 v[156:159], v156 offset:3072
	s_add_u32 s56, s56, 0x40000
	s_addc_u32 s57, s57, 0
	s_mov_b32 m0, s90
	v_lshl_add_u64 v[216:217], s[56:57], 0, v[196:197]
	ds_read_b128 v[160:163], v237 offset:32768
	ds_read_b128 v[164:167], v237 offset:33792
	ds_read_b128 v[168:171], v237 offset:34816
	ds_read_b128 v[172:175], v237 offset:35840
	ds_read_b128 v[176:179], v237 offset:36864
	ds_read_b128 v[180:183], v237 offset:37888
	ds_read_b128 v[184:187], v237 offset:38912
	ds_read_b128 v[188:191], v237 offset:39936
	global_load_lds_dwordx4 v[216:217], off
	v_lshl_add_u64 v[216:217], s[56:57], 0, v[200:201]
	s_mov_b32 m0, s59
	s_nop 0
	global_load_lds_dwordx4 v[216:217], off
	s_waitcnt vmcnt(8)
	s_cmp_lt_u32 s3, 4
	s_cbranch_scc1 .Lgls_82
	s_waitcnt lgkmcnt(0)
.Lgls_82:
	s_barrier
	s_setprio 1
	s_waitcnt lgkmcnt(0)
	v_mfma_f32_16x16x32_f16 v[140:143], v[112:115], v[160:163], v[140:143]
	v_mfma_f32_16x16x32_f16 v[136:139], v[128:131], v[160:163], v[136:139]
	v_mfma_f32_16x16x32_f16 v[108:111], v[112:115], v[168:171], v[108:111]
	v_mfma_f32_16x16x32_f16 v[104:107], v[128:131], v[168:171], v[104:107]
	v_mfma_f32_16x16x32_f16 v[92:95], v[112:115], v[176:179], v[92:95]
	v_mfma_f32_16x16x32_f16 v[88:91], v[128:131], v[176:179], v[88:91]
	v_mfma_f32_16x16x32_f16 v[76:79], v[112:115], v[184:187], v[76:79]
	v_mfma_f32_16x16x32_f16 v[72:75], v[128:131], v[184:187], v[72:75]
	v_mfma_f32_16x16x32_f16 v[140:143], v[116:119], v[164:167], v[140:143]
	v_mfma_f32_16x16x32_f16 v[136:139], v[132:135], v[164:167], v[136:139]
	v_mfma_f32_16x16x32_f16 v[108:111], v[116:119], v[172:175], v[108:111]
	v_mfma_f32_16x16x32_f16 v[104:107], v[132:135], v[172:175], v[104:107]
	v_mfma_f32_16x16x32_f16 v[92:95], v[116:119], v[180:183], v[92:95]
	v_mfma_f32_16x16x32_f16 v[88:91], v[132:135], v[180:183], v[88:91]
	v_mfma_f32_16x16x32_f16 v[76:79], v[116:119], v[188:191], v[76:79]
	v_mfma_f32_16x16x32_f16 v[72:75], v[132:135], v[188:191], v[72:75]
	s_setprio 0
	s_setprio 1
	v_mfma_f32_16x16x32_f16 v[124:127], v[144:147], v[160:163], v[124:127]
	v_mfma_f32_16x16x32_f16 v[120:123], v[152:155], v[160:163], v[120:123]
	v_mfma_f32_16x16x32_f16 v[100:103], v[144:147], v[168:171], v[100:103]
	v_mfma_f32_16x16x32_f16 v[96:99], v[152:155], v[168:171], v[96:99]
	v_mfma_f32_16x16x32_f16 v[84:87], v[144:147], v[176:179], v[84:87]
	v_mfma_f32_16x16x32_f16 v[80:83], v[152:155], v[176:179], v[80:83]
	v_mfma_f32_16x16x32_f16 v[68:71], v[144:147], v[184:187], v[68:71]
	v_mfma_f32_16x16x32_f16 v[64:67], v[152:155], v[184:187], v[64:67]
	v_mfma_f32_16x16x32_f16 v[124:127], v[148:151], v[164:167], v[124:127]
	v_mfma_f32_16x16x32_f16 v[120:123], v[156:159], v[164:167], v[120:123]
	v_mfma_f32_16x16x32_f16 v[100:103], v[148:151], v[172:175], v[100:103]
	v_mfma_f32_16x16x32_f16 v[96:99], v[156:159], v[172:175], v[96:99]
	v_mfma_f32_16x16x32_f16 v[84:87], v[148:151], v[180:183], v[84:87]
	v_mfma_f32_16x16x32_f16 v[80:83], v[156:159], v[180:183], v[80:83]
	v_mfma_f32_16x16x32_f16 v[68:71], v[148:151], v[188:191], v[68:71]
	v_mfma_f32_16x16x32_f16 v[64:67], v[156:159], v[188:191], v[64:67]
	s_setprio 0
	s_barrier
	s_add_i32 s45, s45, s68
	v_lshl_add_u64 v[192:193], v[192:193], 0, s[34:35]
	s_mov_b32 m0, s45
	ds_read_b128 v[160:163], v237 offset:49152
	ds_read_b128 v[164:167], v237 offset:50176
	ds_read_b128 v[168:171], v237 offset:51200
	ds_read_b128 v[172:175], v237 offset:52224
	ds_read_b128 v[176:179], v237 offset:53248
	ds_read_b128 v[180:183], v237 offset:54272
	ds_read_b128 v[184:187], v237 offset:55296
	ds_read_b128 v[188:191], v237 offset:56320
	global_load_lds_dwordx4 v[192:193], off
	s_add_i32 m0, s45, 0x2000
	s_add_u32 s54, s54, 0x40080
	v_lshl_add_u64 v[192:193], v[194:195], 0, s[34:35]
	s_addc_u32 s55, s55, 0
	s_add_i32 s45, s51, s68
	global_load_lds_dwordx4 v[192:193], off
	v_lshl_add_u64 v[192:193], s[54:55], 0, v[198:199]
	s_mov_b32 m0, s45
	s_nop 0
	global_load_lds_dwordx4 v[192:193], off
	v_lshl_add_u64 v[192:193], s[54:55], 0, v[202:203]
	s_add_i32 m0, s45, 0x2000
	s_nop 0
	global_load_lds_dwordx4 v[192:193], off
	v_lshl_add_u64 v[192:193], v[212:213], 0, s[34:35]
	s_mov_b32 m0, s75
	s_nop 0
	global_load_lds_dwordx4 v[192:193], off
	v_lshl_add_u64 v[192:193], v[214:215], 0, s[34:35]
	s_mov_b32 m0, s67
	s_nop 0
	global_load_lds_dwordx4 v[192:193], off
	s_waitcnt vmcnt(8)
	s_cmp_lt_u32 s3, 4
	s_cbranch_scc1 .Lgls_83
	s_waitcnt lgkmcnt(0)

; #define PG8_STAGE(bufoff, gbase, voff) do { _Pragma("unroll") for (int _i = 0; _i < 2; ++_i) \
;         __builtin_amdgcn_global_load_lds((const unsigned*)((const char*)(gbase) + (voff)[_i]), (PG8_LAS unsigned*)(lds + (bufoff) + ldsw + _i * 8192), 16, 0, 0); } while (0)
; #define PG8_LDA(dst, b, h) do { _Pragma("unroll") for (int m = 0; m < 4; ++m) _Pragma("unroll") for (int k = 0; k < 2; ++k) dst[m][k] = *(const PG8_LAS bf16x8*)(lds + PG8_SA(b, h) + aoff + m * 2048 + k * 1024); } while (0)
; #define PG8_LDB(dst, b, h) do { _Pragma("unroll") for (int n = 0; n < 2; ++n) _Pragma("unroll") for (int k = 0; k < 2; ++k) dst[n][k] = *(const PG8_LAS bf16x8*)(lds + PG8_SB(b, h) + boff + n * 2048 + k * 1024); } while (0)
; #define PG8_MMA(ai, bj, At, Bt) do { __builtin_amdgcn_s_setprio(1); _Pragma("unroll") for (int m = 0; m < 4; ++m) _Pragma("unroll") for (int n = 0; n < 2; ++n) _Pragma("unroll") for (int k = 0; k < 2; ++k) \
;         acc[ai][bj][m][n] = mma16<F16>(Bt[n][k], At[m][k], acc[ai][bj][m][n]); __builtin_amdgcn_s_setprio(0); } while (0)
; #define PG8_WAIT_V(n) asm volatile("s_waitcnt vmcnt(" #n ")" ::: "memory")
; #define PG8_WAIT_L(n) asm volatile("s_waitcnt lgkmcnt(" #n ")" ::: "memory")
; #define PG8_BAR __builtin_amdgcn_s_barrier()
; #define PG8_SCHED __builtin_amdgcn_sched_barrier(0)
; template <class Epi, class Sched, bool ALIGN_EPI = false, bool SP2 = false, bool F16 = false>
; __device__ __forceinline__ void gemm_phase(PG8_LAS unsigned char* lds, const Gemm g, const Sched& S, const Epi& E, const int wid_in) {
;     ...
;         for (int t = 0; t < nt; t += 2) {
;             const bool last = (t == nt - 2);
;             const char* a1 = cA + (size_t)(t + 1) * kstep;
;             const char* a2 = last ? nA : cA + (size_t)(t + 2) * kstep; const char* b2 = last ? nB : cB + (size_t)(t + 2) * kstep;
;             const char* a3 = a2 + kstep; const char* b3 = b2 + kstep;
;             if (last && has_next) S.a_ready(nxt);
;             if constexpr (SP2) {
;             PG8_LDB(B0, 0, 0); PG8_LDB(B1, 0, 1); PG8_SCHED; PG8_LDA(At, 0, 0); PG8_STAGE(PG8_SA(1, 1), a1 + hstep, voffA);
;             PG8_WAIT_V(8); PG8_WAIT_L(0); PG8_BAR; PG8_MMA(0, 0, At, B0); PG8_MMA(0, 1, At, B1); PG8_BAR; PG8_SCHED;
;             PG8_LDA(At, 0, 1); PG8_STAGE(PG8_SB(0, 0), b2, voffB); PG8_STAGE(PG8_SB(0, 1), b2 + hstep, voffB); PG8_STAGE(PG8_SA(0, 0), a2, voffA);
.LBB0_2226:
	ds_read_b128 v[128:131], v183
	ds_read_b128 v[132:135], v183 offset:1024
	ds_read_b128 v[136:139], v183 offset:2048
	ds_read_b128 v[140:143], v183 offset:3072
	ds_read_b128 v[144:147], v184
	ds_read_b128 v[148:151], v184 offset:1024
	ds_read_b128 v[152:155], v184 offset:2048
	ds_read_b128 v[174:177], v184 offset:3072
	s_add_u32 s43, s48, 0xfffc0080
	s_addc_u32 s50, s49, -1
	s_cmp_eq_u32 s42, 12
	s_cselect_b32 s53, s13, s50
	s_cselect_b32 s52, s23, s43
	s_cselect_b32 s51, s35, s41
	s_cselect_b32 s50, s37, s40
	s_mov_b32 m0, s91
	v_lshl_add_u64 v[178:179], s[48:49], 0, v[166:167]
	ds_read_b128 v[188:191], v185
	ds_read_b128 v[192:195], v185 offset:1024
	ds_read_b128 v[196:199], v185 offset:2048
	ds_read_b128 v[200:203], v185 offset:3072
	ds_read_b128 v[204:207], v185 offset:4096
	ds_read_b128 v[208:211], v185 offset:5120
	ds_read_b128 v[212:215], v185 offset:6144
	ds_read_b128 v[216:219], v185 offset:7168
	global_load_lds_dwordx4 v[178:179], off
	v_lshl_add_u64 v[178:179], s[48:49], 0, v[168:169]
	s_add_i32 m0, s74, 0xe000
	s_nop 0
	global_load_lds_dwordx4 v[178:179], off
	s_waitcnt vmcnt(8)
	s_cmp_lt_u32 s3, 4
	s_cbranch_scc1 .Lgls_84
	s_waitcnt lgkmcnt(0)
.Lgls_84:
	s_barrier
	s_setprio 1
	s_waitcnt lgkmcnt(0)
	v_mfma_f32_16x16x32_f16 v[124:127], v[128:131], v[188:191], v[124:127]
	v_mfma_f32_16x16x32_f16 v[120:123], v[136:139], v[188:191], v[120:123]
	v_mfma_f32_16x16x32_f16 v[108:111], v[128:131], v[196:199], v[108:111]
	v_mfma_f32_16x16x32_f16 v[104:107], v[136:139], v[196:199], v[104:107]
	v_mfma_f32_16x16x32_f16 v[92:95], v[128:131], v[204:207], v[92:95]
	v_mfma_f32_16x16x32_f16 v[88:91], v[136:139], v[204:207], v[88:91]
	v_mfma_f32_16x16x32_f16 v[76:79], v[128:131], v[212:215], v[76:79]
	v_mfma_f32_16x16x32_f16 v[72:75], v[136:139], v[212:215], v[72:75]
	v_mfma_f32_16x16x32_f16 v[124:127], v[132:135], v[192:195], v[124:127]
	v_mfma_f32_16x16x32_f16 v[120:123], v[140:143], v[192:195], v[120:123]
	v_mfma_f32_16x16x32_f16 v[108:111], v[132:135], v[200:203], v[108:111]
	v_mfma_f32_16x16x32_f16 v[104:107], v[140:143], v[200:203], v[104:107]
	v_mfma_f32_16x16x32_f16 v[92:95], v[132:135], v[208:211], v[92:95]
	v_mfma_f32_16x16x32_f16 v[88:91], v[140:143], v[208:211], v[88:91]
	v_mfma_f32_16x16x32_f16 v[76:79], v[132:135], v[216:219], v[76:79]
	v_mfma_f32_16x16x32_f16 v[72:75], v[140:143], v[216:219], v[72:75]
	s_setprio 0
	s_setprio 1
	v_mfma_f32_16x16x32_f16 v[116:119], v[144:147], v[188:191], v[116:119]
	v_mfma_f32_16x16x32_f16 v[112:115], v[152:155], v[188:191], v[112:115]
	v_mfma_f32_16x16x32_f16 v[100:103], v[144:147], v[196:199], v[100:103]
	v_mfma_f32_16x16x32_f16 v[96:99], v[152:155], v[196:199], v[96:99]
	v_mfma_f32_16x16x32_f16 v[84:87], v[144:147], v[204:207], v[84:87]
	v_mfma_f32_16x16x32_f16 v[80:83], v[152:155], v[204:207], v[80:83]
	v_mfma_f32_16x16x32_f16 v[68:71], v[144:147], v[212:215], v[68:71]
	v_mfma_f32_16x16x32_f16 v[64:67], v[152:155], v[212:215], v[64:67]
	v_mfma_f32_16x16x32_f16 v[116:119], v[148:151], v[192:195], v[116:119]
	v_mfma_f32_16x16x32_f16 v[112:115], v[174:177], v[192:195], v[112:115]
	v_mfma_f32_16x16x32_f16 v[100:103], v[148:151], v[200:203], v[100:103]
	v_mfma_f32_16x16x32_f16 v[96:99], v[174:177], v[200:203], v[96:99]
	v_mfma_f32_16x16x32_f16 v[84:87], v[148:151], v[208:211], v[84:87]
	v_mfma_f32_16x16x32_f16 v[80:83], v[174:177], v[208:211], v[80:83]
	v_mfma_f32_16x16x32_f16 v[68:71], v[148:151], v[216:219], v[68:71]
	v_mfma_f32_16x16x32_f16 v[64:67], v[174:177], v[216:219], v[64:67]
	s_setprio 0
	s_barrier
	s_add_i32 s43, s84, s68
	v_lshl_add_u64 v[178:179], s[50:51], 0, v[158:159]
	s_mov_b32 m0, s43
	ds_read_b128 v[188:191], v185 offset:16384
	ds_read_b128 v[192:195], v185 offset:17408
	ds_read_b128 v[196:199], v185 offset:18432
	ds_read_b128 v[200:203], v185 offset:19456
	ds_read_b128 v[204:207], v185 offset:20480
	ds_read_b128 v[208:211], v185 offset:21504
	ds_read_b128 v[212:215], v185 offset:22528
	ds_read_b128 v[216:219], v185 offset:23552
	global_load_lds_dwordx4 v[178:179], off
	s_add_i32 m0, s43, 0x2000
	s_add_u32 s54, s50, 0x40000
	v_lshl_add_u64 v[220:221], s[50:51], 0, v[162:163]
	s_addc_u32 s55, s51, 0
	s_add_i32 s43, s93, s68
	global_load_lds_dwordx4 v[220:221], off
	v_lshl_add_u64 v[222:223], s[54:55], 0, v[158:159]
	s_mov_b32 m0, s43
	v_lshl_add_u64 v[224:225], s[52:53], 0, v[160:161]
	global_load_lds_dwordx4 v[222:223], off
	v_lshl_add_u64 v[222:223], s[54:55], 0, v[162:163]
	s_add_i32 m0, s43, 0x2000
	s_nop 0
	global_load_lds_dwordx4 v[222:223], off
	v_lshl_add_u64 v[222:223], s[52:53], 0, v[156:157]
	s_mov_b32 m0, s74
	s_nop 0
	global_load_lds_dwordx4 v[222:223], off
	s_mov_b32 m0, s66
	s_nop 0
	global_load_lds_dwordx4 v[224:225], off
	s_waitcnt vmcnt(8)
	s_cmp_lt_u32 s3, 4
	s_cbranch_scc1 .Lgls_85
	s_waitcnt lgkmcnt(0)
; #define PG8_STAGE(bufoff, gbase, voff) do { _Pragma("unroll") for (int _i = 0; _i < 2; ++_i) \
;         __builtin_amdgcn_global_load_lds((const unsigned*)((const char*)(gbase) + (voff)[_i]), (PG8_LAS unsigned*)(lds + (bufoff) + ldsw + _i * 8192), 16, 0, 0); } while (0)
; #define PG8_LDA(dst, b, h) do { _Pragma("unroll") for (int m = 0; m < 4; ++m) _Pragma("unroll") for (int k = 0; k < 2; ++k) dst[m][k] = *(const PG8_LAS bf16x8*)(lds + PG8_SA(b, h) + aoff + m * 2048 + k * 1024); } while (0)
; #define PG8_LDB(dst, b, h) do { _Pragma("unroll") for (int n = 0; n < 2; ++n) _Pragma("unroll") for (int k = 0; k < 2; ++k) dst[n][k] = *(const PG8_LAS bf16x8*)(lds + PG8_SB(b, h) + boff + n * 2048 + k * 1024); } while (0)
; #define PG8_MMA(ai, bj, At, Bt) do { __builtin_amdgcn_s_setprio(1); _Pragma("unroll") for (int m = 0; m < 4; ++m) _Pragma("unroll") for (int n = 0; n < 2; ++n) _Pragma("unroll") for (int k = 0; k < 2; ++k) \
;         acc[ai][bj][m][n] = mma16<F16>(Bt[n][k], At[m][k], acc[ai][bj][m][n]); __builtin_amdgcn_s_setprio(0); } while (0)
; #define PG8_WAIT_V(n) asm volatile("s_waitcnt vmcnt(" #n ")" ::: "memory")
; #define PG8_WAIT_L(n) asm volatile("s_waitcnt lgkmcnt(" #n ")" ::: "memory")
; #define PG8_BAR __builtin_amdgcn_s_barrier()
; #define PG8_SCHED __builtin_amdgcn_sched_barrier(0)
; template <class Epi, class Sched, bool ALIGN_EPI = false, bool SP2 = false, bool F16 = false>
; __device__ __forceinline__ void gemm_phase(PG8_LAS unsigned char* lds, const Gemm g, const Sched& S, const Epi& E, const int wid_in) {
;     ...
;             PG8_WAIT_V(8); PG8_WAIT_L(0); PG8_BAR; PG8_MMA(1, 0, At, B0); PG8_MMA(1, 1, At, B1); PG8_BAR; PG8_SCHED;
;             PG8_LDB(B0, 1, 0); PG8_LDB(B1, 1, 1); PG8_SCHED; PG8_LDA(At, 1, 0); PG8_STAGE(PG8_SA(0, 1), a2 + hstep, voffA);
;             PG8_WAIT_V(8); PG8_WAIT_L(0); PG8_BAR; PG8_MMA(0, 0, At, B0); PG8_MMA(0, 1, At, B1); PG8_BAR; PG8_SCHED;
.Lgls_85:
	s_barrier
	s_setprio 1
	s_waitcnt lgkmcnt(0)
	v_mfma_f32_16x16x32_f16 v[60:63], v[128:131], v[188:191], v[60:63]
	v_mfma_f32_16x16x32_f16 v[56:59], v[136:139], v[188:191], v[56:59]
	v_mfma_f32_16x16x32_f16 v[44:47], v[128:131], v[196:199], v[44:47]
	v_mfma_f32_16x16x32_f16 v[40:43], v[136:139], v[196:199], v[40:43]
	v_mfma_f32_16x16x32_f16 v[28:31], v[128:131], v[204:207], v[28:31]
	v_mfma_f32_16x16x32_f16 v[24:27], v[136:139], v[204:207], v[24:27]
	v_mfma_f32_16x16x32_f16 v[12:15], v[128:131], v[212:215], v[12:15]
	v_mfma_f32_16x16x32_f16 v[8:11], v[136:139], v[212:215], v[8:11]
	v_mfma_f32_16x16x32_f16 v[60:63], v[132:135], v[192:195], v[60:63]
	v_mfma_f32_16x16x32_f16 v[56:59], v[140:143], v[192:195], v[56:59]
	v_mfma_f32_16x16x32_f16 v[44:47], v[132:135], v[200:203], v[44:47]
	v_mfma_f32_16x16x32_f16 v[40:43], v[140:143], v[200:203], v[40:43]
	v_mfma_f32_16x16x32_f16 v[28:31], v[132:135], v[208:211], v[28:31]
	v_mfma_f32_16x16x32_f16 v[24:27], v[140:143], v[208:211], v[24:27]
	v_mfma_f32_16x16x32_f16 v[12:15], v[132:135], v[216:219], v[12:15]
	v_mfma_f32_16x16x32_f16 v[8:11], v[140:143], v[216:219], v[8:11]
	s_setprio 0
	s_setprio 1
	v_mfma_f32_16x16x32_f16 v[52:55], v[144:147], v[188:191], v[52:55]
	v_mfma_f32_16x16x32_f16 v[48:51], v[152:155], v[188:191], v[48:51]
	v_mfma_f32_16x16x32_f16 v[36:39], v[144:147], v[196:199], v[36:39]
	v_mfma_f32_16x16x32_f16 v[32:35], v[152:155], v[196:199], v[32:35]
	v_mfma_f32_16x16x32_f16 v[20:23], v[144:147], v[204:207], v[20:23]
	v_mfma_f32_16x16x32_f16 v[16:19], v[152:155], v[204:207], v[16:19]
	v_mfma_f32_16x16x32_f16 v[4:7], v[144:147], v[212:215], v[4:7]
	v_mfma_f32_16x16x32_f16 v[0:3], v[152:155], v[212:215], v[0:3]
	v_mfma_f32_16x16x32_f16 v[52:55], v[148:151], v[192:195], v[52:55]
	v_mfma_f32_16x16x32_f16 v[48:51], v[174:177], v[192:195], v[48:51]
	v_mfma_f32_16x16x32_f16 v[36:39], v[148:151], v[200:203], v[36:39]
	v_mfma_f32_16x16x32_f16 v[32:35], v[174:177], v[200:203], v[32:35]
	v_mfma_f32_16x16x32_f16 v[20:23], v[148:151], v[208:211], v[20:23]
	v_mfma_f32_16x16x32_f16 v[16:19], v[174:177], v[208:211], v[16:19]
	v_mfma_f32_16x16x32_f16 v[4:7], v[148:151], v[216:219], v[4:7]
	v_mfma_f32_16x16x32_f16 v[0:3], v[174:177], v[216:219], v[0:3]
	s_setprio 0
	s_barrier
	s_add_i32 s43, 0, 0x18000
	s_add_i32 s54, 0, 0x1c000
	v_add_u32_e32 v140, s43, v182
	v_add_u32_e32 v165, s54, v182
	ds_read_b128 v[128:131], v140
	ds_read_b128 v[132:135], v140 offset:1024
	ds_read_b128 v[136:139], v140 offset:2048
	ds_read_b128 v[140:143], v140 offset:3072
	ds_read_b128 v[144:147], v165
	ds_read_b128 v[148:151], v165 offset:1024
	ds_read_b128 v[152:155], v165 offset:2048
	ds_read_b128 v[174:177], v165 offset:3072
	s_add_u32 s52, s52, 0x40000
	s_addc_u32 s53, s53, 0
	s_mov_b32 m0, s90
	v_lshl_add_u64 v[226:227], s[52:53], 0, v[156:157]
	ds_read_b128 v[188:191], v185 offset:32768
	ds_read_b128 v[192:195], v185 offset:33792
	ds_read_b128 v[196:199], v185 offset:34816
	ds_read_b128 v[200:203], v185 offset:35840
	ds_read_b128 v[204:207], v185 offset:36864
	ds_read_b128 v[208:211], v185 offset:37888
	ds_read_b128 v[212:215], v185 offset:38912
	ds_read_b128 v[216:219], v185 offset:39936
	global_load_lds_dwordx4 v[226:227], off
	v_lshl_add_u64 v[226:227], s[52:53], 0, v[160:161]
	s_mov_b32 m0, s63
	s_nop 0
	global_load_lds_dwordx4 v[226:227], off
	s_waitcnt vmcnt(8)
	s_cmp_lt_u32 s3, 4
	s_cbranch_scc1 .Lgls_86
	s_waitcnt lgkmcnt(0)
; #define PG8_STAGE(bufoff, gbase, voff) do { _Pragma("unroll") for (int _i = 0; _i < 2; ++_i) \
;         __builtin_amdgcn_global_load_lds((const unsigned*)((const char*)(gbase) + (voff)[_i]), (PG8_LAS unsigned*)(lds + (bufoff) + ldsw + _i * 8192), 16, 0, 0); } while (0)
; #define PG8_LDA(dst, b, h) do { _Pragma("unroll") for (int m = 0; m < 4; ++m) _Pragma("unroll") for (int k = 0; k < 2; ++k) dst[m][k] = *(const PG8_LAS bf16x8*)(lds + PG8_SA(b, h) + aoff + m * 2048 + k * 1024); } while (0)
; #define PG8_MMA(ai, bj, At, Bt) do { __builtin_amdgcn_s_setprio(1); _Pragma("unroll") for (int m = 0; m < 4; ++m) _Pragma("unroll") for (int n = 0; n < 2; ++n) _Pragma("unroll") for (int k = 0; k < 2; ++k) \
;         acc[ai][bj][m][n] = mma16<F16>(Bt[n][k], At[m][k], acc[ai][bj][m][n]); __builtin_amdgcn_s_setprio(0); } while (0)
; #define PG8_WAIT_V(n) asm volatile("s_waitcnt vmcnt(" #n ")" ::: "memory")
; #define PG8_WAIT_L(n) asm volatile("s_waitcnt lgkmcnt(" #n ")" ::: "memory")
; #define PG8_BAR __builtin_amdgcn_s_barrier()
; #define PG8_SCHED __builtin_amdgcn_sched_barrier(0)
; template <class Epi, class Sched, bool ALIGN_EPI = false, bool SP2 = false, bool F16 = false>
; __device__ __forceinline__ void gemm_phase(PG8_LAS unsigned char* lds, const Gemm g, const Sched& S, const Epi& E, const int wid_in) {
;     ...
;             PG8_WAIT_V(8); PG8_WAIT_L(0); PG8_BAR; PG8_MMA(0, 0, At, B0); PG8_MMA(0, 1, At, B1); PG8_BAR; PG8_SCHED;
;             PG8_LDA(At, 1, 1); PG8_STAGE(PG8_SB(1, 0), b3, voffB); PG8_STAGE(PG8_SB(1, 1), b3 + hstep, voffB); PG8_STAGE(PG8_SA(1, 0), a3, voffA);
;             PG8_WAIT_V(8); PG8_WAIT_L(0); PG8_BAR; PG8_MMA(1, 0, At, B0); PG8_MMA(1, 1, At, B1); PG8_BAR; PG8_SCHED;
;     ...
;         if constexpr (ALIGN_EPI) { if (wr == 0) PG8_BAR; }
.Lgls_86:
	s_barrier
	s_setprio 1
	s_waitcnt lgkmcnt(0)
	v_mfma_f32_16x16x32_f16 v[124:127], v[128:131], v[188:191], v[124:127]
	v_mfma_f32_16x16x32_f16 v[120:123], v[136:139], v[188:191], v[120:123]
	v_mfma_f32_16x16x32_f16 v[108:111], v[128:131], v[196:199], v[108:111]
	v_mfma_f32_16x16x32_f16 v[104:107], v[136:139], v[196:199], v[104:107]
	v_mfma_f32_16x16x32_f16 v[92:95], v[128:131], v[204:207], v[92:95]
	v_mfma_f32_16x16x32_f16 v[88:91], v[136:139], v[204:207], v[88:91]
	v_mfma_f32_16x16x32_f16 v[76:79], v[128:131], v[212:215], v[76:79]
	v_mfma_f32_16x16x32_f16 v[72:75], v[136:139], v[212:215], v[72:75]
	v_mfma_f32_16x16x32_f16 v[124:127], v[132:135], v[192:195], v[124:127]
	v_mfma_f32_16x16x32_f16 v[120:123], v[140:143], v[192:195], v[120:123]
	v_mfma_f32_16x16x32_f16 v[108:111], v[132:135], v[200:203], v[108:111]
	v_mfma_f32_16x16x32_f16 v[104:107], v[140:143], v[200:203], v[104:107]
	v_mfma_f32_16x16x32_f16 v[92:95], v[132:135], v[208:211], v[92:95]
	v_mfma_f32_16x16x32_f16 v[88:91], v[140:143], v[208:211], v[88:91]
	v_mfma_f32_16x16x32_f16 v[76:79], v[132:135], v[216:219], v[76:79]
	v_mfma_f32_16x16x32_f16 v[72:75], v[140:143], v[216:219], v[72:75]
	s_setprio 0
	s_setprio 1
	v_mfma_f32_16x16x32_f16 v[116:119], v[144:147], v[188:191], v[116:119]
	v_mfma_f32_16x16x32_f16 v[112:115], v[152:155], v[188:191], v[112:115]
	v_mfma_f32_16x16x32_f16 v[100:103], v[144:147], v[196:199], v[100:103]
	v_mfma_f32_16x16x32_f16 v[96:99], v[152:155], v[196:199], v[96:99]
	v_mfma_f32_16x16x32_f16 v[84:87], v[144:147], v[204:207], v[84:87]
	v_mfma_f32_16x16x32_f16 v[80:83], v[152:155], v[204:207], v[80:83]
	v_mfma_f32_16x16x32_f16 v[68:71], v[144:147], v[212:215], v[68:71]
	v_mfma_f32_16x16x32_f16 v[64:67], v[152:155], v[212:215], v[64:67]
	v_mfma_f32_16x16x32_f16 v[116:119], v[148:151], v[192:195], v[116:119]
	v_mfma_f32_16x16x32_f16 v[112:115], v[174:177], v[192:195], v[112:115]
	v_mfma_f32_16x16x32_f16 v[100:103], v[148:151], v[200:203], v[100:103]
	v_mfma_f32_16x16x32_f16 v[96:99], v[174:177], v[200:203], v[96:99]
	v_mfma_f32_16x16x32_f16 v[84:87], v[148:151], v[208:211], v[84:87]
	v_mfma_f32_16x16x32_f16 v[80:83], v[174:177], v[208:211], v[80:83]
	v_mfma_f32_16x16x32_f16 v[68:71], v[148:151], v[216:219], v[68:71]
	v_mfma_f32_16x16x32_f16 v[64:67], v[174:177], v[216:219], v[64:67]
	s_setprio 0
	s_barrier
	s_add_i32 s43, s43, s68
	v_lshl_add_u64 v[178:179], v[178:179], 0, s[26:27]
	s_mov_b32 m0, s43
	ds_read_b128 v[188:191], v185 offset:49152
	ds_read_b128 v[192:195], v185 offset:50176
	ds_read_b128 v[196:199], v185 offset:51200
	ds_read_b128 v[200:203], v185 offset:52224
	ds_read_b128 v[204:207], v185 offset:53248
	ds_read_b128 v[208:211], v185 offset:54272
	ds_read_b128 v[212:215], v185 offset:55296
	ds_read_b128 v[216:219], v185 offset:56320
	global_load_lds_dwordx4 v[178:179], off
	s_add_i32 m0, s43, 0x2000
	s_add_u32 s50, s50, 0x40080
	v_lshl_add_u64 v[178:179], v[220:221], 0, s[26:27]
	s_addc_u32 s51, s51, 0
	s_add_i32 s43, s54, s68
	global_load_lds_dwordx4 v[178:179], off
	v_lshl_add_u64 v[178:179], s[50:51], 0, v[158:159]
	s_mov_b32 m0, s43
	s_nop 0
	global_load_lds_dwordx4 v[178:179], off
	v_lshl_add_u64 v[178:179], s[50:51], 0, v[162:163]
	s_add_i32 m0, s43, 0x2000
	s_nop 0
	global_load_lds_dwordx4 v[178:179], off
	v_lshl_add_u64 v[178:179], v[222:223], 0, s[26:27]
	s_mov_b32 m0, s75
	s_nop 0
	global_load_lds_dwordx4 v[178:179], off
	v_lshl_add_u64 v[178:179], v[224:225], 0, s[26:27]
	s_mov_b32 m0, s67
	s_nop 0
	global_load_lds_dwordx4 v[178:179], off
	s_waitcnt vmcnt(8)
	s_cmp_lt_u32 s3, 4
	s_cbranch_scc1 .Lgls_87
	s_waitcnt lgkmcnt(0)
.Lgls_87:
	s_barrier
	s_setprio 1
	s_waitcnt lgkmcnt(0)
	v_mfma_f32_16x16x32_f16 v[60:63], v[128:131], v[188:191], v[60:63]
	v_mfma_f32_16x16x32_f16 v[56:59], v[136:139], v[188:191], v[56:59]
	v_mfma_f32_16x16x32_f16 v[44:47], v[128:131], v[196:199], v[44:47]
	v_mfma_f32_16x16x32_f16 v[40:43], v[136:139], v[196:199], v[40:43]
	v_mfma_f32_16x16x32_f16 v[28:31], v[128:131], v[204:207], v[28:31]
	v_mfma_f32_16x16x32_f16 v[24:27], v[136:139], v[204:207], v[24:27]
	v_mfma_f32_16x16x32_f16 v[12:15], v[128:131], v[212:215], v[12:15]
	v_mfma_f32_16x16x32_f16 v[8:11], v[136:139], v[212:215], v[8:11]
	v_mfma_f32_16x16x32_f16 v[60:63], v[132:135], v[192:195], v[60:63]
	v_mfma_f32_16x16x32_f16 v[56:59], v[140:143], v[192:195], v[56:59]
	v_mfma_f32_16x16x32_f16 v[44:47], v[132:135], v[200:203], v[44:47]
	v_mfma_f32_16x16x32_f16 v[40:43], v[140:143], v[200:203], v[40:43]
	v_mfma_f32_16x16x32_f16 v[28:31], v[132:135], v[208:211], v[28:31]
	v_mfma_f32_16x16x32_f16 v[24:27], v[140:143], v[208:211], v[24:27]
	v_mfma_f32_16x16x32_f16 v[12:15], v[132:135], v[216:219], v[12:15]
	v_mfma_f32_16x16x32_f16 v[8:11], v[140:143], v[216:219], v[8:11]
	s_setprio 0
	s_setprio 1
	v_mfma_f32_16x16x32_f16 v[52:55], v[144:147], v[188:191], v[52:55]
	v_mfma_f32_16x16x32_f16 v[48:51], v[152:155], v[188:191], v[48:51]
	v_mfma_f32_16x16x32_f16 v[36:39], v[144:147], v[196:199], v[36:39]
	v_mfma_f32_16x16x32_f16 v[32:35], v[152:155], v[196:199], v[32:35]
	v_mfma_f32_16x16x32_f16 v[20:23], v[144:147], v[204:207], v[20:23]
	v_mfma_f32_16x16x32_f16 v[16:19], v[152:155], v[204:207], v[16:19]
	v_mfma_f32_16x16x32_f16 v[4:7], v[144:147], v[212:215], v[4:7]
	v_mfma_f32_16x16x32_f16 v[0:3], v[152:155], v[212:215], v[0:3]
	v_mfma_f32_16x16x32_f16 v[52:55], v[148:151], v[192:195], v[52:55]
	v_mfma_f32_16x16x32_f16 v[48:51], v[174:177], v[192:195], v[48:51]
	v_mfma_f32_16x16x32_f16 v[36:39], v[148:151], v[200:203], v[36:39]
	v_mfma_f32_16x16x32_f16 v[32:35], v[174:177], v[200:203], v[32:35]
	v_mfma_f32_16x16x32_f16 v[20:23], v[148:151], v[208:211], v[20:23]
	v_mfma_f32_16x16x32_f16 v[16:19], v[174:177], v[208:211], v[16:19]
	v_mfma_f32_16x16x32_f16 v[4:7], v[148:151], v[216:219], v[4:7]
	v_mfma_f32_16x16x32_f16 v[0:3], v[174:177], v[216:219], v[0:3]
	s_setprio 0
	s_barrier
	s_add_i32 s42, s42, 2
	s_add_u32 s48, s48, 0x100
	s_addc_u32 s49, s49, 0
	s_add_u32 s40, s40, 0x100
	s_addc_u32 s41, s41, 0
	s_cmp_gt_u32 s42, 13
	s_cbranch_scc0 .LBB0_2226
	s_and_b64 vcc, exec, s[16:17]
	s_cbranch_vccz .LBB0_2229
	s_barrier

; #define PG8_STAGE(bufoff, gbase, voff) do { _Pragma("unroll") for (int _i = 0; _i < 2; ++_i) \
;         __builtin_amdgcn_global_load_lds((const unsigned*)((const char*)(gbase) + (voff)[_i]), (PG8_LAS unsigned*)(lds + (bufoff) + ldsw + _i * 8192), 16, 0, 0); } while (0)
; #define PG8_LDA(dst, b, h) do { _Pragma("unroll") for (int m = 0; m < 4; ++m) _Pragma("unroll") for (int k = 0; k < 2; ++k) dst[m][k] = *(const PG8_LAS bf16x8*)(lds + PG8_SA(b, h) + aoff + m * 2048 + k * 1024); } while (0)
; #define PG8_LDB(dst, b, h) do { _Pragma("unroll") for (int n = 0; n < 2; ++n) _Pragma("unroll") for (int k = 0; k < 2; ++k) dst[n][k] = *(const PG8_LAS bf16x8*)(lds + PG8_SB(b, h) + boff + n * 2048 + k * 1024); } while (0)
; #define PG8_MMA(ai, bj, At, Bt) do { __builtin_amdgcn_s_setprio(1); _Pragma("unroll") for (int m = 0; m < 4; ++m) _Pragma("unroll") for (int n = 0; n < 2; ++n) _Pragma("unroll") for (int k = 0; k < 2; ++k) \
;         acc[ai][bj][m][n] = mma16<F16>(Bt[n][k], At[m][k], acc[ai][bj][m][n]); __builtin_amdgcn_s_setprio(0); } while (0)
; #define PG8_WAIT_V(n) asm volatile("s_waitcnt vmcnt(" #n ")" ::: "memory")
; #define PG8_WAIT_L(n) asm volatile("s_waitcnt lgkmcnt(" #n ")" ::: "memory")
; #define PG8_BAR __builtin_amdgcn_s_barrier()
; #define PG8_SCHED __builtin_amdgcn_sched_barrier(0)
; template <class Epi, class Sched, bool ALIGN_EPI = false, bool SP2 = false, bool F16 = false>
; __device__ __forceinline__ void gemm_phase(PG8_LAS unsigned char* lds, const Gemm g, const Sched& S, const Epi& E, const int wid_in) {
;     ...
;         for (int t = 0; t < nt; t += 2) {
;             const bool last = (t == nt - 2);
;             const char* a1 = cA + (size_t)(t + 1) * kstep;
;             const char* a2 = last ? nA : cA + (size_t)(t + 2) * kstep; const char* b2 = last ? nB : cB + (size_t)(t + 2) * kstep;
;             const char* a3 = a2 + kstep; const char* b3 = b2 + kstep;
;             if (last && has_next) S.a_ready(nxt);
;             if constexpr (SP2) {
;             PG8_LDB(B0, 0, 0); PG8_LDB(B1, 0, 1); PG8_SCHED; PG8_LDA(At, 0, 0); PG8_STAGE(PG8_SA(1, 1), a1 + hstep, voffA);
;             PG8_WAIT_V(8); PG8_WAIT_L(0); PG8_BAR; PG8_MMA(0, 0, At, B0); PG8_MMA(0, 1, At, B1); PG8_BAR; PG8_SCHED;
;             PG8_LDA(At, 0, 1); PG8_STAGE(PG8_SB(0, 0), b2, voffB); PG8_STAGE(PG8_SB(0, 1), b2 + hstep, voffB); PG8_STAGE(PG8_SA(0, 0), a2, voffA);
.LBB0_2489:
	ds_read_b128 v[128:131], v189
	ds_read_b128 v[132:135], v189 offset:1024
	ds_read_b128 v[136:139], v189 offset:2048
	ds_read_b128 v[140:143], v189 offset:3072
	ds_read_b128 v[144:147], v190
	ds_read_b128 v[148:151], v190 offset:1024
	ds_read_b128 v[168:171], v190 offset:2048
	ds_read_b128 v[172:175], v190 offset:3072
	s_add_u32 s44, s42, 0xfffc0080
	s_addc_u32 s45, s43, -1
	s_cmp_eq_u32 s59, 12
	s_cselect_b32 s47, s29, s45
	s_cselect_b32 s46, s37, s44
	s_cselect_b32 s45, s27, s58
	s_cselect_b32 s44, s56, s57
	s_mov_b32 m0, s91
	v_lshl_add_u64 v[184:185], s[42:43], 0, v[160:161]
	ds_read_b128 v[176:179], v191
	ds_read_b128 v[180:183], v191 offset:1024
	ds_read_b128 v[192:195], v191 offset:2048
	ds_read_b128 v[196:199], v191 offset:3072
	ds_read_b128 v[200:203], v191 offset:4096
	ds_read_b128 v[204:207], v191 offset:5120
	ds_read_b128 v[208:211], v191 offset:6144
	ds_read_b128 v[212:215], v191 offset:7168
	global_load_lds_dwordx4 v[184:185], off
	v_lshl_add_u64 v[184:185], s[42:43], 0, v[162:163]
	s_add_i32 m0, s74, 0xe000
	s_nop 0
	global_load_lds_dwordx4 v[184:185], off
	s_waitcnt vmcnt(8)
	s_cmp_lt_u32 s3, 4
	s_cbranch_scc1 .Lgls_88
	s_waitcnt lgkmcnt(0)
.Lgls_88:
	s_barrier
	s_setprio 1
	s_waitcnt lgkmcnt(0)
	v_mfma_f32_16x16x32_bf16 v[124:127], v[128:131], v[176:179], v[124:127]
	v_mfma_f32_16x16x32_bf16 v[120:123], v[136:139], v[176:179], v[120:123]
	v_mfma_f32_16x16x32_bf16 v[108:111], v[128:131], v[192:195], v[108:111]
	v_mfma_f32_16x16x32_bf16 v[104:107], v[136:139], v[192:195], v[104:107]
	v_mfma_f32_16x16x32_bf16 v[92:95], v[128:131], v[200:203], v[92:95]
	v_mfma_f32_16x16x32_bf16 v[88:91], v[136:139], v[200:203], v[88:91]
	v_mfma_f32_16x16x32_bf16 v[76:79], v[128:131], v[208:211], v[76:79]
	v_mfma_f32_16x16x32_bf16 v[72:75], v[136:139], v[208:211], v[72:75]
	v_mfma_f32_16x16x32_bf16 v[124:127], v[132:135], v[180:183], v[124:127]
	v_mfma_f32_16x16x32_bf16 v[120:123], v[140:143], v[180:183], v[120:123]
	v_mfma_f32_16x16x32_bf16 v[108:111], v[132:135], v[196:199], v[108:111]
	v_mfma_f32_16x16x32_bf16 v[104:107], v[140:143], v[196:199], v[104:107]
	v_mfma_f32_16x16x32_bf16 v[92:95], v[132:135], v[204:207], v[92:95]
	v_mfma_f32_16x16x32_bf16 v[88:91], v[140:143], v[204:207], v[88:91]
	v_mfma_f32_16x16x32_bf16 v[76:79], v[132:135], v[212:215], v[76:79]
	v_mfma_f32_16x16x32_bf16 v[72:75], v[140:143], v[212:215], v[72:75]
	s_setprio 0
	s_setprio 1
	v_mfma_f32_16x16x32_bf16 v[116:119], v[144:147], v[176:179], v[116:119]
	v_mfma_f32_16x16x32_bf16 v[112:115], v[168:171], v[176:179], v[112:115]
	v_mfma_f32_16x16x32_bf16 v[100:103], v[144:147], v[192:195], v[100:103]
	v_mfma_f32_16x16x32_bf16 v[96:99], v[168:171], v[192:195], v[96:99]
	v_mfma_f32_16x16x32_bf16 v[84:87], v[144:147], v[200:203], v[84:87]
	v_mfma_f32_16x16x32_bf16 v[80:83], v[168:171], v[200:203], v[80:83]
	v_mfma_f32_16x16x32_bf16 v[68:71], v[144:147], v[208:211], v[68:71]
	v_mfma_f32_16x16x32_bf16 v[64:67], v[168:171], v[208:211], v[64:67]
	v_mfma_f32_16x16x32_bf16 v[116:119], v[148:151], v[180:183], v[116:119]
	v_mfma_f32_16x16x32_bf16 v[112:115], v[172:175], v[180:183], v[112:115]
	v_mfma_f32_16x16x32_bf16 v[100:103], v[148:151], v[196:199], v[100:103]
	v_mfma_f32_16x16x32_bf16 v[96:99], v[172:175], v[196:199], v[96:99]
	v_mfma_f32_16x16x32_bf16 v[84:87], v[148:151], v[204:207], v[84:87]
	v_mfma_f32_16x16x32_bf16 v[80:83], v[172:175], v[204:207], v[80:83]
	v_mfma_f32_16x16x32_bf16 v[68:71], v[148:151], v[212:215], v[68:71]
	v_mfma_f32_16x16x32_bf16 v[64:67], v[172:175], v[212:215], v[64:67]
	s_setprio 0
	s_barrier
	s_add_i32 s60, s53, s68
	v_lshl_add_u64 v[184:185], s[44:45], 0, v[154:155]
	s_mov_b32 m0, s60
	ds_read_b128 v[176:179], v191 offset:16384
	ds_read_b128 v[180:183], v191 offset:17408
	ds_read_b128 v[192:195], v191 offset:18432
	ds_read_b128 v[196:199], v191 offset:19456
	ds_read_b128 v[200:203], v191 offset:20480
	ds_read_b128 v[204:207], v191 offset:21504
	ds_read_b128 v[208:211], v191 offset:22528
	ds_read_b128 v[212:215], v191 offset:23552
	global_load_lds_dwordx4 v[184:185], off
	s_add_i32 m0, s60, 0x2000
	s_add_u32 s60, s44, 0x40000
	v_lshl_add_u64 v[216:217], s[44:45], 0, v[158:159]
	s_addc_u32 s61, s45, 0
	s_add_i32 s62, s54, s68
	global_load_lds_dwordx4 v[216:217], off
	v_lshl_add_u64 v[218:219], s[60:61], 0, v[154:155]
	s_mov_b32 m0, s62
	v_lshl_add_u64 v[220:221], s[46:47], 0, v[156:157]
	global_load_lds_dwordx4 v[218:219], off
	v_lshl_add_u64 v[218:219], s[60:61], 0, v[158:159]
	s_add_i32 m0, s62, 0x2000
	s_nop 0
	global_load_lds_dwordx4 v[218:219], off
	v_lshl_add_u64 v[218:219], s[46:47], 0, v[152:153]
	s_mov_b32 m0, s74
	s_nop 0
	global_load_lds_dwordx4 v[218:219], off
	s_mov_b32 m0, s66
	s_nop 0
	global_load_lds_dwordx4 v[220:221], off
	s_waitcnt vmcnt(8)
	s_cmp_lt_u32 s3, 4
	s_cbranch_scc1 .Lgls_89
	s_waitcnt lgkmcnt(0)
; #define PG8_STAGE(bufoff, gbase, voff) do { _Pragma("unroll") for (int _i = 0; _i < 2; ++_i) \
;         __builtin_amdgcn_global_load_lds((const unsigned*)((const char*)(gbase) + (voff)[_i]), (PG8_LAS unsigned*)(lds + (bufoff) + ldsw + _i * 8192), 16, 0, 0); } while (0)
; #define PG8_LDA(dst, b, h) do { _Pragma("unroll") for (int m = 0; m < 4; ++m) _Pragma("unroll") for (int k = 0; k < 2; ++k) dst[m][k] = *(const PG8_LAS bf16x8*)(lds + PG8_SA(b, h) + aoff + m * 2048 + k * 1024); } while (0)
; #define PG8_LDB(dst, b, h) do { _Pragma("unroll") for (int n = 0; n < 2; ++n) _Pragma("unroll") for (int k = 0; k < 2; ++k) dst[n][k] = *(const PG8_LAS bf16x8*)(lds + PG8_SB(b, h) + boff + n * 2048 + k * 1024); } while (0)
; #define PG8_MMA(ai, bj, At, Bt) do { __builtin_amdgcn_s_setprio(1); _Pragma("unroll") for (int m = 0; m < 4; ++m) _Pragma("unroll") for (int n = 0; n < 2; ++n) _Pragma("unroll") for (int k = 0; k < 2; ++k) \
;         acc[ai][bj][m][n] = mma16<F16>(Bt[n][k], At[m][k], acc[ai][bj][m][n]); __builtin_amdgcn_s_setprio(0); } while (0)
; #define PG8_WAIT_V(n) asm volatile("s_waitcnt vmcnt(" #n ")" ::: "memory")
; #define PG8_WAIT_L(n) asm volatile("s_waitcnt lgkmcnt(" #n ")" ::: "memory")
; #define PG8_BAR __builtin_amdgcn_s_barrier()
; #define PG8_SCHED __builtin_amdgcn_sched_barrier(0)
; template <class Epi, class Sched, bool ALIGN_EPI = false, bool SP2 = false, bool F16 = false>
; __device__ __forceinline__ void gemm_phase(PG8_LAS unsigned char* lds, const Gemm g, const Sched& S, const Epi& E, const int wid_in) {
;     ...
;             PG8_WAIT_V(8); PG8_WAIT_L(0); PG8_BAR; PG8_MMA(1, 0, At, B0); PG8_MMA(1, 1, At, B1); PG8_BAR; PG8_SCHED;
;             PG8_LDB(B0, 1, 0); PG8_LDB(B1, 1, 1); PG8_SCHED; PG8_LDA(At, 1, 0); PG8_STAGE(PG8_SA(0, 1), a2 + hstep, voffA);
;             PG8_WAIT_V(8); PG8_WAIT_L(0); PG8_BAR; PG8_MMA(0, 0, At, B0); PG8_MMA(0, 1, At, B1); PG8_BAR; PG8_SCHED;
.Lgls_89:
	s_barrier
	s_setprio 1
	s_waitcnt lgkmcnt(0)
	v_mfma_f32_16x16x32_bf16 v[60:63], v[128:131], v[176:179], v[60:63]
	v_mfma_f32_16x16x32_bf16 v[56:59], v[136:139], v[176:179], v[56:59]
	v_mfma_f32_16x16x32_bf16 v[44:47], v[128:131], v[192:195], v[44:47]
	v_mfma_f32_16x16x32_bf16 v[40:43], v[136:139], v[192:195], v[40:43]
	v_mfma_f32_16x16x32_bf16 v[28:31], v[128:131], v[200:203], v[28:31]
	v_mfma_f32_16x16x32_bf16 v[24:27], v[136:139], v[200:203], v[24:27]
	v_mfma_f32_16x16x32_bf16 v[12:15], v[128:131], v[208:211], v[12:15]
	v_mfma_f32_16x16x32_bf16 v[8:11], v[136:139], v[208:211], v[8:11]
	v_mfma_f32_16x16x32_bf16 v[60:63], v[132:135], v[180:183], v[60:63]
	v_mfma_f32_16x16x32_bf16 v[56:59], v[140:143], v[180:183], v[56:59]
	v_mfma_f32_16x16x32_bf16 v[44:47], v[132:135], v[196:199], v[44:47]
	v_mfma_f32_16x16x32_bf16 v[40:43], v[140:143], v[196:199], v[40:43]
	v_mfma_f32_16x16x32_bf16 v[28:31], v[132:135], v[204:207], v[28:31]
	v_mfma_f32_16x16x32_bf16 v[24:27], v[140:143], v[204:207], v[24:27]
	v_mfma_f32_16x16x32_bf16 v[12:15], v[132:135], v[212:215], v[12:15]
	v_mfma_f32_16x16x32_bf16 v[8:11], v[140:143], v[212:215], v[8:11]
	s_setprio 0
	s_setprio 1
	v_mfma_f32_16x16x32_bf16 v[52:55], v[144:147], v[176:179], v[52:55]
	v_mfma_f32_16x16x32_bf16 v[48:51], v[168:171], v[176:179], v[48:51]
	v_mfma_f32_16x16x32_bf16 v[36:39], v[144:147], v[192:195], v[36:39]
	v_mfma_f32_16x16x32_bf16 v[32:35], v[168:171], v[192:195], v[32:35]
	v_mfma_f32_16x16x32_bf16 v[20:23], v[144:147], v[200:203], v[20:23]
	v_mfma_f32_16x16x32_bf16 v[16:19], v[168:171], v[200:203], v[16:19]
	v_mfma_f32_16x16x32_bf16 v[4:7], v[144:147], v[208:211], v[4:7]
	v_mfma_f32_16x16x32_bf16 v[0:3], v[168:171], v[208:211], v[0:3]
	v_mfma_f32_16x16x32_bf16 v[52:55], v[148:151], v[180:183], v[52:55]
	v_mfma_f32_16x16x32_bf16 v[48:51], v[172:175], v[180:183], v[48:51]
	v_mfma_f32_16x16x32_bf16 v[36:39], v[148:151], v[196:199], v[36:39]
	v_mfma_f32_16x16x32_bf16 v[32:35], v[172:175], v[196:199], v[32:35]
	v_mfma_f32_16x16x32_bf16 v[20:23], v[148:151], v[204:207], v[20:23]
	v_mfma_f32_16x16x32_bf16 v[16:19], v[172:175], v[204:207], v[16:19]
	v_mfma_f32_16x16x32_bf16 v[4:7], v[148:151], v[212:215], v[4:7]
	v_mfma_f32_16x16x32_bf16 v[0:3], v[172:175], v[212:215], v[0:3]
	s_setprio 0
	s_barrier
	s_add_i32 s60, 0, 0x18000
	s_add_i32 s61, 0, 0x1c000
	v_add_u32_e32 v140, s60, v188
	v_add_u32_e32 v172, s61, v188
	ds_read_b128 v[128:131], v140
	ds_read_b128 v[132:135], v140 offset:1024
	ds_read_b128 v[136:139], v140 offset:2048
	ds_read_b128 v[140:143], v140 offset:3072
	ds_read_b128 v[144:147], v172
	ds_read_b128 v[148:151], v172 offset:1024
	ds_read_b128 v[168:171], v172 offset:2048
	ds_read_b128 v[172:175], v172 offset:3072
	s_add_u32 s46, s46, 0x40000
	s_addc_u32 s47, s47, 0
	s_mov_b32 m0, s90
	v_lshl_add_u64 v[222:223], s[46:47], 0, v[152:153]
	ds_read_b128 v[176:179], v191 offset:32768
	ds_read_b128 v[180:183], v191 offset:33792
	ds_read_b128 v[192:195], v191 offset:34816
	ds_read_b128 v[196:199], v191 offset:35840
	ds_read_b128 v[200:203], v191 offset:36864
	ds_read_b128 v[204:207], v191 offset:37888
	ds_read_b128 v[208:211], v191 offset:38912
	ds_read_b128 v[212:215], v191 offset:39936
	global_load_lds_dwordx4 v[222:223], off
	v_lshl_add_u64 v[222:223], s[46:47], 0, v[156:157]
	s_mov_b32 m0, s49
	s_nop 0
	global_load_lds_dwordx4 v[222:223], off
	s_waitcnt vmcnt(8)
	s_cmp_lt_u32 s3, 4
	s_cbranch_scc1 .Lgls_90
	s_waitcnt lgkmcnt(0)
; #define PG8_STAGE(bufoff, gbase, voff) do { _Pragma("unroll") for (int _i = 0; _i < 2; ++_i) \
;         __builtin_amdgcn_global_load_lds((const unsigned*)((const char*)(gbase) + (voff)[_i]), (PG8_LAS unsigned*)(lds + (bufoff) + ldsw + _i * 8192), 16, 0, 0); } while (0)
; #define PG8_LDA(dst, b, h) do { _Pragma("unroll") for (int m = 0; m < 4; ++m) _Pragma("unroll") for (int k = 0; k < 2; ++k) dst[m][k] = *(const PG8_LAS bf16x8*)(lds + PG8_SA(b, h) + aoff + m * 2048 + k * 1024); } while (0)
; #define PG8_MMA(ai, bj, At, Bt) do { __builtin_amdgcn_s_setprio(1); _Pragma("unroll") for (int m = 0; m < 4; ++m) _Pragma("unroll") for (int n = 0; n < 2; ++n) _Pragma("unroll") for (int k = 0; k < 2; ++k) \
;         acc[ai][bj][m][n] = mma16<F16>(Bt[n][k], At[m][k], acc[ai][bj][m][n]); __builtin_amdgcn_s_setprio(0); } while (0)
; #define PG8_WAIT_V(n) asm volatile("s_waitcnt vmcnt(" #n ")" ::: "memory")
; #define PG8_WAIT_L(n) asm volatile("s_waitcnt lgkmcnt(" #n ")" ::: "memory")
; #define PG8_BAR __builtin_amdgcn_s_barrier()
; #define PG8_SCHED __builtin_amdgcn_sched_barrier(0)
; template <class Epi, class Sched, bool ALIGN_EPI = false, bool SP2 = false, bool F16 = false>
; __device__ __forceinline__ void gemm_phase(PG8_LAS unsigned char* lds, const Gemm g, const Sched& S, const Epi& E, const int wid_in) {
;     ...
;             PG8_WAIT_V(8); PG8_WAIT_L(0); PG8_BAR; PG8_MMA(0, 0, At, B0); PG8_MMA(0, 1, At, B1); PG8_BAR; PG8_SCHED;
;             PG8_LDA(At, 1, 1); PG8_STAGE(PG8_SB(1, 0), b3, voffB); PG8_STAGE(PG8_SB(1, 1), b3 + hstep, voffB); PG8_STAGE(PG8_SA(1, 0), a3, voffA);
;             PG8_WAIT_V(8); PG8_WAIT_L(0); PG8_BAR; PG8_MMA(1, 0, At, B0); PG8_MMA(1, 1, At, B1); PG8_BAR; PG8_SCHED;
;     ...
;         if constexpr (ALIGN_EPI) { if (wr == 0) PG8_BAR; }
.Lgls_90:
	s_barrier
	s_setprio 1
	s_waitcnt lgkmcnt(0)
	v_mfma_f32_16x16x32_bf16 v[124:127], v[128:131], v[176:179], v[124:127]
	v_mfma_f32_16x16x32_bf16 v[120:123], v[136:139], v[176:179], v[120:123]
	v_mfma_f32_16x16x32_bf16 v[108:111], v[128:131], v[192:195], v[108:111]
	v_mfma_f32_16x16x32_bf16 v[104:107], v[136:139], v[192:195], v[104:107]
	v_mfma_f32_16x16x32_bf16 v[92:95], v[128:131], v[200:203], v[92:95]
	v_mfma_f32_16x16x32_bf16 v[88:91], v[136:139], v[200:203], v[88:91]
	v_mfma_f32_16x16x32_bf16 v[76:79], v[128:131], v[208:211], v[76:79]
	v_mfma_f32_16x16x32_bf16 v[72:75], v[136:139], v[208:211], v[72:75]
	v_mfma_f32_16x16x32_bf16 v[124:127], v[132:135], v[180:183], v[124:127]
	v_mfma_f32_16x16x32_bf16 v[120:123], v[140:143], v[180:183], v[120:123]
	v_mfma_f32_16x16x32_bf16 v[108:111], v[132:135], v[196:199], v[108:111]
	v_mfma_f32_16x16x32_bf16 v[104:107], v[140:143], v[196:199], v[104:107]
	v_mfma_f32_16x16x32_bf16 v[92:95], v[132:135], v[204:207], v[92:95]
	v_mfma_f32_16x16x32_bf16 v[88:91], v[140:143], v[204:207], v[88:91]
	v_mfma_f32_16x16x32_bf16 v[76:79], v[132:135], v[212:215], v[76:79]
	v_mfma_f32_16x16x32_bf16 v[72:75], v[140:143], v[212:215], v[72:75]
	s_setprio 0
	s_setprio 1
	v_mfma_f32_16x16x32_bf16 v[116:119], v[144:147], v[176:179], v[116:119]
	v_mfma_f32_16x16x32_bf16 v[112:115], v[168:171], v[176:179], v[112:115]
	v_mfma_f32_16x16x32_bf16 v[100:103], v[144:147], v[192:195], v[100:103]
	v_mfma_f32_16x16x32_bf16 v[96:99], v[168:171], v[192:195], v[96:99]
	v_mfma_f32_16x16x32_bf16 v[84:87], v[144:147], v[200:203], v[84:87]
	v_mfma_f32_16x16x32_bf16 v[80:83], v[168:171], v[200:203], v[80:83]
	v_mfma_f32_16x16x32_bf16 v[68:71], v[144:147], v[208:211], v[68:71]
	v_mfma_f32_16x16x32_bf16 v[64:67], v[168:171], v[208:211], v[64:67]
	v_mfma_f32_16x16x32_bf16 v[116:119], v[148:151], v[180:183], v[116:119]
	v_mfma_f32_16x16x32_bf16 v[112:115], v[172:175], v[180:183], v[112:115]
	v_mfma_f32_16x16x32_bf16 v[100:103], v[148:151], v[196:199], v[100:103]
	v_mfma_f32_16x16x32_bf16 v[96:99], v[172:175], v[196:199], v[96:99]
	v_mfma_f32_16x16x32_bf16 v[84:87], v[148:151], v[204:207], v[84:87]
	v_mfma_f32_16x16x32_bf16 v[80:83], v[172:175], v[204:207], v[80:83]
	v_mfma_f32_16x16x32_bf16 v[68:71], v[148:151], v[212:215], v[68:71]
	v_mfma_f32_16x16x32_bf16 v[64:67], v[172:175], v[212:215], v[64:67]
	s_setprio 0
	s_barrier
	s_add_i32 s46, s60, s68
	v_lshl_add_u64 v[184:185], v[184:185], 0, s[24:25]
	s_mov_b32 m0, s46
	ds_read_b128 v[176:179], v191 offset:49152
	ds_read_b128 v[180:183], v191 offset:50176
	ds_read_b128 v[192:195], v191 offset:51200
	ds_read_b128 v[196:199], v191 offset:52224
	ds_read_b128 v[200:203], v191 offset:53248
	ds_read_b128 v[204:207], v191 offset:54272
	ds_read_b128 v[208:211], v191 offset:55296
	ds_read_b128 v[212:215], v191 offset:56320
	global_load_lds_dwordx4 v[184:185], off
	s_add_i32 m0, s46, 0x2000
	s_add_u32 s44, s44, 0x40080
	v_lshl_add_u64 v[184:185], v[216:217], 0, s[24:25]
	s_addc_u32 s45, s45, 0
	s_add_i32 s46, s61, s68
	global_load_lds_dwordx4 v[184:185], off
	v_lshl_add_u64 v[184:185], s[44:45], 0, v[154:155]
	s_mov_b32 m0, s46
	s_nop 0
	global_load_lds_dwordx4 v[184:185], off
	v_lshl_add_u64 v[184:185], s[44:45], 0, v[158:159]
	s_add_i32 m0, s46, 0x2000
	s_nop 0
	global_load_lds_dwordx4 v[184:185], off
	v_lshl_add_u64 v[184:185], v[218:219], 0, s[24:25]
	s_mov_b32 m0, s75
	s_nop 0
	global_load_lds_dwordx4 v[184:185], off
	v_lshl_add_u64 v[184:185], v[220:221], 0, s[24:25]
	s_mov_b32 m0, s67
	s_nop 0
	global_load_lds_dwordx4 v[184:185], off
	s_waitcnt vmcnt(8)
	s_cmp_lt_u32 s3, 4
	s_cbranch_scc1 .Lgls_91
	s_waitcnt lgkmcnt(0)
.Lgls_91:
	s_barrier
	s_setprio 1
	s_waitcnt lgkmcnt(0)
	v_mfma_f32_16x16x32_bf16 v[60:63], v[128:131], v[176:179], v[60:63]
	v_mfma_f32_16x16x32_bf16 v[56:59], v[136:139], v[176:179], v[56:59]
	v_mfma_f32_16x16x32_bf16 v[44:47], v[128:131], v[192:195], v[44:47]
	v_mfma_f32_16x16x32_bf16 v[40:43], v[136:139], v[192:195], v[40:43]
	v_mfma_f32_16x16x32_bf16 v[28:31], v[128:131], v[200:203], v[28:31]
	v_mfma_f32_16x16x32_bf16 v[24:27], v[136:139], v[200:203], v[24:27]
	v_mfma_f32_16x16x32_bf16 v[12:15], v[128:131], v[208:211], v[12:15]
	v_mfma_f32_16x16x32_bf16 v[8:11], v[136:139], v[208:211], v[8:11]
	v_mfma_f32_16x16x32_bf16 v[60:63], v[132:135], v[180:183], v[60:63]
	v_mfma_f32_16x16x32_bf16 v[56:59], v[140:143], v[180:183], v[56:59]
	v_mfma_f32_16x16x32_bf16 v[44:47], v[132:135], v[196:199], v[44:47]
	v_mfma_f32_16x16x32_bf16 v[40:43], v[140:143], v[196:199], v[40:43]
	v_mfma_f32_16x16x32_bf16 v[28:31], v[132:135], v[204:207], v[28:31]
	v_mfma_f32_16x16x32_bf16 v[24:27], v[140:143], v[204:207], v[24:27]
	v_mfma_f32_16x16x32_bf16 v[12:15], v[132:135], v[212:215], v[12:15]
	v_mfma_f32_16x16x32_bf16 v[8:11], v[140:143], v[212:215], v[8:11]
	s_setprio 0
	s_setprio 1
	v_mfma_f32_16x16x32_bf16 v[52:55], v[144:147], v[176:179], v[52:55]
	v_mfma_f32_16x16x32_bf16 v[48:51], v[168:171], v[176:179], v[48:51]
	v_mfma_f32_16x16x32_bf16 v[36:39], v[144:147], v[192:195], v[36:39]
	v_mfma_f32_16x16x32_bf16 v[32:35], v[168:171], v[192:195], v[32:35]
	v_mfma_f32_16x16x32_bf16 v[20:23], v[144:147], v[200:203], v[20:23]
	v_mfma_f32_16x16x32_bf16 v[16:19], v[168:171], v[200:203], v[16:19]
	v_mfma_f32_16x16x32_bf16 v[4:7], v[144:147], v[208:211], v[4:7]
	v_mfma_f32_16x16x32_bf16 v[0:3], v[168:171], v[208:211], v[0:3]
	v_mfma_f32_16x16x32_bf16 v[52:55], v[148:151], v[180:183], v[52:55]
	v_mfma_f32_16x16x32_bf16 v[48:51], v[172:175], v[180:183], v[48:51]
	v_mfma_f32_16x16x32_bf16 v[36:39], v[148:151], v[196:199], v[36:39]
	v_mfma_f32_16x16x32_bf16 v[32:35], v[172:175], v[196:199], v[32:35]
	v_mfma_f32_16x16x32_bf16 v[20:23], v[148:151], v[204:207], v[20:23]
	v_mfma_f32_16x16x32_bf16 v[16:19], v[172:175], v[204:207], v[16:19]
	v_mfma_f32_16x16x32_bf16 v[4:7], v[148:151], v[212:215], v[4:7]
	v_mfma_f32_16x16x32_bf16 v[0:3], v[172:175], v[212:215], v[0:3]
	s_setprio 0
	s_barrier
	s_add_i32 s59, s59, 2
	s_add_u32 s42, s42, 0x100
	s_addc_u32 s43, s43, 0
	s_add_u32 s57, s57, 0x100
	s_addc_u32 s58, s58, 0
	s_cmp_gt_u32 s59, 13
	s_cbranch_scc0 .LBB0_2489
	s_and_b64 vcc, exec, s[16:17]
	s_cbranch_vccz .LBB0_2492
	s_barrier

; #define PG8_STAGE(bufoff, gbase, voff) do { _Pragma("unroll") for (int _i = 0; _i < 2; ++_i) \
;         __builtin_amdgcn_global_load_lds((const unsigned*)((const char*)(gbase) + (voff)[_i]), (PG8_LAS unsigned*)(lds + (bufoff) + ldsw + _i * 8192), 16, 0, 0); } while (0)
; #define PG8_LDA(dst, b, h) do { _Pragma("unroll") for (int m = 0; m < 4; ++m) _Pragma("unroll") for (int k = 0; k < 2; ++k) dst[m][k] = *(const PG8_LAS bf16x8*)(lds + PG8_SA(b, h) + aoff + m * 2048 + k * 1024); } while (0)
; #define PG8_LDB(dst, b, h) do { _Pragma("unroll") for (int n = 0; n < 2; ++n) _Pragma("unroll") for (int k = 0; k < 2; ++k) dst[n][k] = *(const PG8_LAS bf16x8*)(lds + PG8_SB(b, h) + boff + n * 2048 + k * 1024); } while (0)
; #define PG8_MMA(ai, bj, At, Bt) do { __builtin_amdgcn_s_setprio(1); _Pragma("unroll") for (int m = 0; m < 4; ++m) _Pragma("unroll") for (int n = 0; n < 2; ++n) _Pragma("unroll") for (int k = 0; k < 2; ++k) \
;         acc[ai][bj][m][n] = mma16<F16>(Bt[n][k], At[m][k], acc[ai][bj][m][n]); __builtin_amdgcn_s_setprio(0); } while (0)
; #define PG8_WAIT_V(n) asm volatile("s_waitcnt vmcnt(" #n ")" ::: "memory")
; #define PG8_WAIT_L(n) asm volatile("s_waitcnt lgkmcnt(" #n ")" ::: "memory")
; #define PG8_BAR __builtin_amdgcn_s_barrier()
; #define PG8_SCHED __builtin_amdgcn_sched_barrier(0)
; template <class Epi, class Sched, bool ALIGN_EPI = false, bool SP2 = false, bool F16 = false>
; __device__ __forceinline__ void gemm_phase(PG8_LAS unsigned char* lds, const Gemm g, const Sched& S, const Epi& E, const int wid_in) {
;     ...
;         for (int t = 0; t < nt; t += 2) {
;             const bool last = (t == nt - 2);
;             const char* a1 = cA + (size_t)(t + 1) * kstep;
;             const char* a2 = last ? nA : cA + (size_t)(t + 2) * kstep; const char* b2 = last ? nB : cB + (size_t)(t + 2) * kstep;
;             const char* a3 = a2 + kstep; const char* b3 = b2 + kstep;
;             if (last && has_next) S.a_ready(nxt);
;             if constexpr (SP2) {
;             PG8_LDB(B0, 0, 0); PG8_LDB(B1, 0, 1); PG8_SCHED; PG8_LDA(At, 0, 0); PG8_STAGE(PG8_SA(1, 1), a1 + hstep, voffA);
;             PG8_WAIT_V(8); PG8_WAIT_L(0); PG8_BAR; PG8_MMA(0, 0, At, B0); PG8_MMA(0, 1, At, B1); PG8_BAR; PG8_SCHED;
;             PG8_LDA(At, 0, 1); PG8_STAGE(PG8_SB(0, 0), b2, voffB); PG8_STAGE(PG8_SB(0, 1), b2 + hstep, voffB); PG8_STAGE(PG8_SA(0, 0), a2, voffA);
.LBB0_2566:
	ds_read_b128 v[0:3], v193
	ds_read_b128 v[4:7], v193 offset:1024
	ds_read_b128 v[136:139], v193 offset:2048
	ds_read_b128 v[140:143], v193 offset:3072
	ds_read_b128 v[144:147], v194
	ds_read_b128 v[148:151], v194 offset:1024
	ds_read_b128 v[152:155], v194 offset:2048
	ds_read_b128 v[156:159], v194 offset:3072
	s_add_u32 s42, s36, 0xfffc0080
	s_addc_u32 s43, s37, -1
	s_cmp_eq_u32 s62, 12
	s_cselect_b32 s45, s25, s43
	s_cselect_b32 s44, s35, s42
	s_cselect_b32 s43, s23, s61
	s_cselect_b32 s42, s59, s60
	s_mov_b32 m0, s91
	v_lshl_add_u64 v[188:189], s[36:37], 0, v[168:169]
	ds_read_b128 v[176:179], v195
	ds_read_b128 v[180:183], v195 offset:1024
	ds_read_b128 v[184:187], v195 offset:2048
	ds_read_b128 v[198:201], v195 offset:3072
	ds_read_b128 v[202:205], v195 offset:4096
	ds_read_b128 v[206:209], v195 offset:5120
	ds_read_b128 v[210:213], v195 offset:6144
	ds_read_b128 v[214:217], v195 offset:7168
	global_load_lds_dwordx4 v[188:189], off
	v_lshl_add_u64 v[188:189], s[36:37], 0, v[170:171]
	s_add_i32 m0, s74, 0xe000
	s_nop 0
	global_load_lds_dwordx4 v[188:189], off
	s_waitcnt vmcnt(8)
	s_cmp_lt_u32 s3, 4
	s_cbranch_scc1 .Lgls_92
	s_waitcnt lgkmcnt(0)
.Lgls_92:
	s_barrier
	s_setprio 1
	s_waitcnt lgkmcnt(0)
	v_mfma_f32_16x16x32_f16 v[132:135], v[0:3], v[176:179], v[132:135]
	v_mfma_f32_16x16x32_f16 v[128:131], v[136:139], v[176:179], v[128:131]
	v_mfma_f32_16x16x32_f16 v[116:119], v[0:3], v[184:187], v[116:119]
	v_mfma_f32_16x16x32_f16 v[112:115], v[136:139], v[184:187], v[112:115]
	v_mfma_f32_16x16x32_f16 v[100:103], v[0:3], v[202:205], v[100:103]
	v_mfma_f32_16x16x32_f16 v[96:99], v[136:139], v[202:205], v[96:99]
	v_mfma_f32_16x16x32_f16 v[84:87], v[0:3], v[210:213], v[84:87]
	v_mfma_f32_16x16x32_f16 v[80:83], v[136:139], v[210:213], v[80:83]
	v_mfma_f32_16x16x32_f16 v[132:135], v[4:7], v[180:183], v[132:135]
	v_mfma_f32_16x16x32_f16 v[128:131], v[140:143], v[180:183], v[128:131]
	v_mfma_f32_16x16x32_f16 v[116:119], v[4:7], v[198:201], v[116:119]
	v_mfma_f32_16x16x32_f16 v[112:115], v[140:143], v[198:201], v[112:115]
	v_mfma_f32_16x16x32_f16 v[100:103], v[4:7], v[206:209], v[100:103]
	v_mfma_f32_16x16x32_f16 v[96:99], v[140:143], v[206:209], v[96:99]
	v_mfma_f32_16x16x32_f16 v[84:87], v[4:7], v[214:217], v[84:87]
	v_mfma_f32_16x16x32_f16 v[80:83], v[140:143], v[214:217], v[80:83]
	s_setprio 0
	s_setprio 1
	v_mfma_f32_16x16x32_f16 v[124:127], v[144:147], v[176:179], v[124:127]
	v_mfma_f32_16x16x32_f16 v[120:123], v[152:155], v[176:179], v[120:123]
	v_mfma_f32_16x16x32_f16 v[108:111], v[144:147], v[184:187], v[108:111]
	v_mfma_f32_16x16x32_f16 v[104:107], v[152:155], v[184:187], v[104:107]
	v_mfma_f32_16x16x32_f16 v[92:95], v[144:147], v[202:205], v[92:95]
	v_mfma_f32_16x16x32_f16 v[88:91], v[152:155], v[202:205], v[88:91]
	v_mfma_f32_16x16x32_f16 v[76:79], v[144:147], v[210:213], v[76:79]
	v_mfma_f32_16x16x32_f16 v[72:75], v[152:155], v[210:213], v[72:75]
	v_mfma_f32_16x16x32_f16 v[124:127], v[148:151], v[180:183], v[124:127]
	v_mfma_f32_16x16x32_f16 v[120:123], v[156:159], v[180:183], v[120:123]
	v_mfma_f32_16x16x32_f16 v[108:111], v[148:151], v[198:201], v[108:111]
	v_mfma_f32_16x16x32_f16 v[104:107], v[156:159], v[198:201], v[104:107]
	v_mfma_f32_16x16x32_f16 v[92:95], v[148:151], v[206:209], v[92:95]
	v_mfma_f32_16x16x32_f16 v[88:91], v[156:159], v[206:209], v[88:91]
	v_mfma_f32_16x16x32_f16 v[76:79], v[148:151], v[214:217], v[76:79]
	v_mfma_f32_16x16x32_f16 v[72:75], v[156:159], v[214:217], v[72:75]
	s_setprio 0
	s_barrier
	s_add_i32 s63, s56, s68
	v_lshl_add_u64 v[188:189], s[42:43], 0, v[162:163]
	s_mov_b32 m0, s63
	ds_read_b128 v[176:179], v195 offset:16384
	ds_read_b128 v[180:183], v195 offset:17408
	ds_read_b128 v[184:187], v195 offset:18432
	ds_read_b128 v[198:201], v195 offset:19456
	ds_read_b128 v[202:205], v195 offset:20480
	ds_read_b128 v[206:209], v195 offset:21504
	ds_read_b128 v[210:213], v195 offset:22528
	ds_read_b128 v[214:217], v195 offset:23552
	global_load_lds_dwordx4 v[188:189], off
	s_add_i32 m0, s63, 0x2000
	s_add_u32 s64, s42, 0x40000
	v_lshl_add_u64 v[218:219], s[42:43], 0, v[166:167]
	s_addc_u32 s65, s43, 0
	s_add_i32 s63, s57, s68
	global_load_lds_dwordx4 v[218:219], off
	v_lshl_add_u64 v[220:221], s[64:65], 0, v[162:163]
	s_mov_b32 m0, s63
	v_lshl_add_u64 v[222:223], s[44:45], 0, v[164:165]
	global_load_lds_dwordx4 v[220:221], off
	v_lshl_add_u64 v[220:221], s[64:65], 0, v[166:167]
	s_add_i32 m0, s63, 0x2000
	s_nop 0
	global_load_lds_dwordx4 v[220:221], off
	v_lshl_add_u64 v[220:221], s[44:45], 0, v[160:161]
	s_mov_b32 m0, s74
	s_nop 0
	global_load_lds_dwordx4 v[220:221], off
	s_mov_b32 m0, s66
	s_nop 0
	global_load_lds_dwordx4 v[222:223], off
	s_waitcnt vmcnt(8)
	s_cmp_lt_u32 s3, 4
	s_cbranch_scc1 .Lgls_93
	s_waitcnt lgkmcnt(0)
; #define PG8_STAGE(bufoff, gbase, voff) do { _Pragma("unroll") for (int _i = 0; _i < 2; ++_i) \
;         __builtin_amdgcn_global_load_lds((const unsigned*)((const char*)(gbase) + (voff)[_i]), (PG8_LAS unsigned*)(lds + (bufoff) + ldsw + _i * 8192), 16, 0, 0); } while (0)
; #define PG8_LDA(dst, b, h) do { _Pragma("unroll") for (int m = 0; m < 4; ++m) _Pragma("unroll") for (int k = 0; k < 2; ++k) dst[m][k] = *(const PG8_LAS bf16x8*)(lds + PG8_SA(b, h) + aoff + m * 2048 + k * 1024); } while (0)
; #define PG8_LDB(dst, b, h) do { _Pragma("unroll") for (int n = 0; n < 2; ++n) _Pragma("unroll") for (int k = 0; k < 2; ++k) dst[n][k] = *(const PG8_LAS bf16x8*)(lds + PG8_SB(b, h) + boff + n * 2048 + k * 1024); } while (0)
; #define PG8_MMA(ai, bj, At, Bt) do { __builtin_amdgcn_s_setprio(1); _Pragma("unroll") for (int m = 0; m < 4; ++m) _Pragma("unroll") for (int n = 0; n < 2; ++n) _Pragma("unroll") for (int k = 0; k < 2; ++k) \
;         acc[ai][bj][m][n] = mma16<F16>(Bt[n][k], At[m][k], acc[ai][bj][m][n]); __builtin_amdgcn_s_setprio(0); } while (0)
; #define PG8_WAIT_V(n) asm volatile("s_waitcnt vmcnt(" #n ")" ::: "memory")
; #define PG8_WAIT_L(n) asm volatile("s_waitcnt lgkmcnt(" #n ")" ::: "memory")
; #define PG8_BAR __builtin_amdgcn_s_barrier()
; #define PG8_SCHED __builtin_amdgcn_sched_barrier(0)
; template <class Epi, class Sched, bool ALIGN_EPI = false, bool SP2 = false, bool F16 = false>
; __device__ __forceinline__ void gemm_phase(PG8_LAS unsigned char* lds, const Gemm g, const Sched& S, const Epi& E, const int wid_in) {
;     ...
;             PG8_WAIT_V(8); PG8_WAIT_L(0); PG8_BAR; PG8_MMA(1, 0, At, B0); PG8_MMA(1, 1, At, B1); PG8_BAR; PG8_SCHED;
;             PG8_LDB(B0, 1, 0); PG8_LDB(B1, 1, 1); PG8_SCHED; PG8_LDA(At, 1, 0); PG8_STAGE(PG8_SA(0, 1), a2 + hstep, voffA);
;             PG8_WAIT_V(8); PG8_WAIT_L(0); PG8_BAR; PG8_MMA(0, 0, At, B0); PG8_MMA(0, 1, At, B1); PG8_BAR; PG8_SCHED;
.Lgls_93:
	s_barrier
	s_setprio 1
	s_waitcnt lgkmcnt(0)
	v_mfma_f32_16x16x32_f16 v[68:71], v[0:3], v[176:179], v[68:71]
	v_mfma_f32_16x16x32_f16 v[64:67], v[136:139], v[176:179], v[64:67]
	v_mfma_f32_16x16x32_f16 v[52:55], v[0:3], v[184:187], v[52:55]
	v_mfma_f32_16x16x32_f16 v[48:51], v[136:139], v[184:187], v[48:51]
	v_mfma_f32_16x16x32_f16 v[36:39], v[0:3], v[202:205], v[36:39]
	v_mfma_f32_16x16x32_f16 v[32:35], v[136:139], v[202:205], v[32:35]
	v_mfma_f32_16x16x32_f16 v[0:3], v[0:3], v[210:213], v[20:23]
	v_mfma_f32_16x16x32_f16 v[68:71], v[4:7], v[180:183], v[68:71]
	v_mfma_f32_16x16x32_f16 v[64:67], v[140:143], v[180:183], v[64:67]
	v_mfma_f32_16x16x32_f16 v[52:55], v[4:7], v[198:201], v[52:55]
	v_mfma_f32_16x16x32_f16 v[48:51], v[140:143], v[198:201], v[48:51]
	v_mfma_f32_16x16x32_f16 v[36:39], v[4:7], v[206:209], v[36:39]
	v_mfma_f32_16x16x32_f16 v[32:35], v[140:143], v[206:209], v[32:35]
	v_mfma_f32_16x16x32_f16 v[0:3], v[4:7], v[214:217], v[0:3]
	v_mfma_f32_16x16x32_f16 v[4:7], v[136:139], v[210:213], v[16:19]
	v_mfma_f32_16x16x32_f16 v[4:7], v[140:143], v[214:217], v[4:7]
	s_setprio 0
	s_setprio 1
	v_mfma_f32_16x16x32_f16 v[16:19], v[144:147], v[176:179], v[60:63]
	v_mfma_f32_16x16x32_f16 v[60:63], v[148:151], v[180:183], v[16:19]
	v_mfma_f32_16x16x32_f16 v[16:19], v[152:155], v[176:179], v[56:59]
	v_mfma_f32_16x16x32_f16 v[56:59], v[156:159], v[180:183], v[16:19]
	v_mfma_f32_16x16x32_f16 v[16:19], v[144:147], v[184:187], v[44:47]
	v_mfma_f32_16x16x32_f16 v[44:47], v[148:151], v[198:201], v[16:19]
	v_mfma_f32_16x16x32_f16 v[16:19], v[152:155], v[184:187], v[40:43]
	v_mfma_f32_16x16x32_f16 v[40:43], v[156:159], v[198:201], v[16:19]
	v_mfma_f32_16x16x32_f16 v[16:19], v[144:147], v[202:205], v[28:31]
	v_mfma_f32_16x16x32_f16 v[28:31], v[148:151], v[206:209], v[16:19]
	v_mfma_f32_16x16x32_f16 v[16:19], v[152:155], v[202:205], v[24:27]
	v_mfma_f32_16x16x32_f16 v[12:15], v[144:147], v[210:213], v[12:15]
	v_mfma_f32_16x16x32_f16 v[8:11], v[152:155], v[210:213], v[8:11]
	v_mfma_f32_16x16x32_f16 v[24:27], v[156:159], v[206:209], v[16:19]
	v_mfma_f32_16x16x32_f16 v[12:15], v[148:151], v[214:217], v[12:15]
	v_mfma_f32_16x16x32_f16 v[8:11], v[156:159], v[214:217], v[8:11]
	s_setprio 0
	s_barrier
	s_add_i32 s63, 0, 0x18000
	s_add_i32 s64, 0, 0x1c000
	v_add_u32_e32 v140, s63, v192
	v_add_u32_e32 v156, s64, v192
	ds_read_b128 v[16:19], v140
	ds_read_b128 v[20:23], v140 offset:1024
	ds_read_b128 v[136:139], v140 offset:2048
	ds_read_b128 v[140:143], v140 offset:3072
	ds_read_b128 v[144:147], v156
	ds_read_b128 v[148:151], v156 offset:1024
	ds_read_b128 v[152:155], v156 offset:2048
	ds_read_b128 v[156:159], v156 offset:3072
	s_add_u32 s44, s44, 0x40000
	s_addc_u32 s45, s45, 0
	s_mov_b32 m0, s90
	v_lshl_add_u64 v[224:225], s[44:45], 0, v[160:161]
	ds_read_b128 v[176:179], v195 offset:32768
	ds_read_b128 v[180:183], v195 offset:33792
	ds_read_b128 v[184:187], v195 offset:34816
	ds_read_b128 v[198:201], v195 offset:35840
	ds_read_b128 v[202:205], v195 offset:36864
	ds_read_b128 v[206:209], v195 offset:37888
	ds_read_b128 v[210:213], v195 offset:38912
	ds_read_b128 v[214:217], v195 offset:39936
	global_load_lds_dwordx4 v[224:225], off
	v_lshl_add_u64 v[224:225], s[44:45], 0, v[164:165]
	s_mov_b32 m0, s31
	s_nop 0
	global_load_lds_dwordx4 v[224:225], off
	s_waitcnt vmcnt(8)
	s_cmp_lt_u32 s3, 4
	s_cbranch_scc1 .Lgls_94
	s_waitcnt lgkmcnt(0)
; #define PG8_STAGE(bufoff, gbase, voff) do { _Pragma("unroll") for (int _i = 0; _i < 2; ++_i) \
;         __builtin_amdgcn_global_load_lds((const unsigned*)((const char*)(gbase) + (voff)[_i]), (PG8_LAS unsigned*)(lds + (bufoff) + ldsw + _i * 8192), 16, 0, 0); } while (0)
; #define PG8_LDA(dst, b, h) do { _Pragma("unroll") for (int m = 0; m < 4; ++m) _Pragma("unroll") for (int k = 0; k < 2; ++k) dst[m][k] = *(const PG8_LAS bf16x8*)(lds + PG8_SA(b, h) + aoff + m * 2048 + k * 1024); } while (0)
; #define PG8_MMA(ai, bj, At, Bt) do { __builtin_amdgcn_s_setprio(1); _Pragma("unroll") for (int m = 0; m < 4; ++m) _Pragma("unroll") for (int n = 0; n < 2; ++n) _Pragma("unroll") for (int k = 0; k < 2; ++k) \
;         acc[ai][bj][m][n] = mma16<F16>(Bt[n][k], At[m][k], acc[ai][bj][m][n]); __builtin_amdgcn_s_setprio(0); } while (0)
; #define PG8_WAIT_V(n) asm volatile("s_waitcnt vmcnt(" #n ")" ::: "memory")
; #define PG8_WAIT_L(n) asm volatile("s_waitcnt lgkmcnt(" #n ")" ::: "memory")
; #define PG8_BAR __builtin_amdgcn_s_barrier()
; #define PG8_SCHED __builtin_amdgcn_sched_barrier(0)
; template <class Epi, class Sched, bool ALIGN_EPI = false, bool SP2 = false, bool F16 = false>
; __device__ __forceinline__ void gemm_phase(PG8_LAS unsigned char* lds, const Gemm g, const Sched& S, const Epi& E, const int wid_in) {
;     ...
;             PG8_WAIT_V(8); PG8_WAIT_L(0); PG8_BAR; PG8_MMA(0, 0, At, B0); PG8_MMA(0, 1, At, B1); PG8_BAR; PG8_SCHED;
;             PG8_LDA(At, 1, 1); PG8_STAGE(PG8_SB(1, 0), b3, voffB); PG8_STAGE(PG8_SB(1, 1), b3 + hstep, voffB); PG8_STAGE(PG8_SA(1, 0), a3, voffA);
;             PG8_WAIT_V(8); PG8_WAIT_L(0); PG8_BAR; PG8_MMA(1, 0, At, B0); PG8_MMA(1, 1, At, B1); PG8_BAR; PG8_SCHED;
;     ...
;         if constexpr (ALIGN_EPI) { if (wr == 0) PG8_BAR; }
.Lgls_94:
	s_barrier
	s_setprio 1
	s_waitcnt lgkmcnt(0)
	v_mfma_f32_16x16x32_f16 v[132:135], v[16:19], v[176:179], v[132:135]
	v_mfma_f32_16x16x32_f16 v[128:131], v[136:139], v[176:179], v[128:131]
	v_mfma_f32_16x16x32_f16 v[116:119], v[16:19], v[184:187], v[116:119]
	v_mfma_f32_16x16x32_f16 v[112:115], v[136:139], v[184:187], v[112:115]
	v_mfma_f32_16x16x32_f16 v[100:103], v[16:19], v[202:205], v[100:103]
	v_mfma_f32_16x16x32_f16 v[96:99], v[136:139], v[202:205], v[96:99]
	v_mfma_f32_16x16x32_f16 v[84:87], v[16:19], v[210:213], v[84:87]
	v_mfma_f32_16x16x32_f16 v[80:83], v[136:139], v[210:213], v[80:83]
	v_mfma_f32_16x16x32_f16 v[132:135], v[20:23], v[180:183], v[132:135]
	v_mfma_f32_16x16x32_f16 v[128:131], v[140:143], v[180:183], v[128:131]
	v_mfma_f32_16x16x32_f16 v[116:119], v[20:23], v[198:201], v[116:119]
	v_mfma_f32_16x16x32_f16 v[112:115], v[140:143], v[198:201], v[112:115]
	v_mfma_f32_16x16x32_f16 v[100:103], v[20:23], v[206:209], v[100:103]
	v_mfma_f32_16x16x32_f16 v[96:99], v[140:143], v[206:209], v[96:99]
	v_mfma_f32_16x16x32_f16 v[84:87], v[20:23], v[214:217], v[84:87]
	v_mfma_f32_16x16x32_f16 v[80:83], v[140:143], v[214:217], v[80:83]
	s_setprio 0
	s_setprio 1
	v_mfma_f32_16x16x32_f16 v[124:127], v[144:147], v[176:179], v[124:127]
	v_mfma_f32_16x16x32_f16 v[120:123], v[152:155], v[176:179], v[120:123]
	v_mfma_f32_16x16x32_f16 v[108:111], v[144:147], v[184:187], v[108:111]
	v_mfma_f32_16x16x32_f16 v[104:107], v[152:155], v[184:187], v[104:107]
	v_mfma_f32_16x16x32_f16 v[92:95], v[144:147], v[202:205], v[92:95]
	v_mfma_f32_16x16x32_f16 v[88:91], v[152:155], v[202:205], v[88:91]
	v_mfma_f32_16x16x32_f16 v[76:79], v[144:147], v[210:213], v[76:79]
	v_mfma_f32_16x16x32_f16 v[72:75], v[152:155], v[210:213], v[72:75]
	v_mfma_f32_16x16x32_f16 v[124:127], v[148:151], v[180:183], v[124:127]
	v_mfma_f32_16x16x32_f16 v[120:123], v[156:159], v[180:183], v[120:123]
	v_mfma_f32_16x16x32_f16 v[108:111], v[148:151], v[198:201], v[108:111]
	v_mfma_f32_16x16x32_f16 v[104:107], v[156:159], v[198:201], v[104:107]
	v_mfma_f32_16x16x32_f16 v[92:95], v[148:151], v[206:209], v[92:95]
	v_mfma_f32_16x16x32_f16 v[88:91], v[156:159], v[206:209], v[88:91]
	v_mfma_f32_16x16x32_f16 v[76:79], v[148:151], v[214:217], v[76:79]
	v_mfma_f32_16x16x32_f16 v[72:75], v[156:159], v[214:217], v[72:75]
	s_setprio 0
	s_barrier
	s_add_i32 s44, s63, s68
	v_lshl_add_u64 v[188:189], v[188:189], 0, s[20:21]
	s_mov_b32 m0, s44
	ds_read_b128 v[176:179], v195 offset:49152
	ds_read_b128 v[180:183], v195 offset:50176
	ds_read_b128 v[184:187], v195 offset:51200
	ds_read_b128 v[198:201], v195 offset:52224
	ds_read_b128 v[202:205], v195 offset:53248
	ds_read_b128 v[206:209], v195 offset:54272
	ds_read_b128 v[210:213], v195 offset:55296
	ds_read_b128 v[214:217], v195 offset:56320
	global_load_lds_dwordx4 v[188:189], off
	s_add_i32 m0, s44, 0x2000
	s_add_u32 s42, s42, 0x40080
	v_lshl_add_u64 v[188:189], v[218:219], 0, s[20:21]
	s_addc_u32 s43, s43, 0
	s_add_i32 s44, s64, s68
	global_load_lds_dwordx4 v[188:189], off
	v_lshl_add_u64 v[188:189], s[42:43], 0, v[162:163]
	s_mov_b32 m0, s44
	s_nop 0
	global_load_lds_dwordx4 v[188:189], off
	v_lshl_add_u64 v[188:189], s[42:43], 0, v[166:167]
	s_add_i32 m0, s44, 0x2000
	s_nop 0
	global_load_lds_dwordx4 v[188:189], off
	v_lshl_add_u64 v[188:189], v[220:221], 0, s[20:21]
	s_mov_b32 m0, s75
	s_nop 0
	global_load_lds_dwordx4 v[188:189], off
	v_lshl_add_u64 v[188:189], v[222:223], 0, s[20:21]
	s_mov_b32 m0, s67
	s_nop 0
	global_load_lds_dwordx4 v[188:189], off
	s_waitcnt vmcnt(8)
	s_cmp_lt_u32 s3, 4
	s_cbranch_scc1 .Lgls_95
	s_waitcnt lgkmcnt(0)
.Lgls_95:
	s_barrier
	s_setprio 1
	s_waitcnt lgkmcnt(0)
	v_mfma_f32_16x16x32_f16 v[68:71], v[16:19], v[176:179], v[68:71]
	v_mfma_f32_16x16x32_f16 v[52:55], v[16:19], v[184:187], v[52:55]
	v_mfma_f32_16x16x32_f16 v[36:39], v[16:19], v[202:205], v[36:39]
	v_mfma_f32_16x16x32_f16 v[0:3], v[16:19], v[210:213], v[0:3]
	v_mfma_f32_16x16x32_f16 v[68:71], v[20:23], v[180:183], v[68:71]
	v_mfma_f32_16x16x32_f16 v[64:67], v[136:139], v[176:179], v[64:67]
	v_mfma_f32_16x16x32_f16 v[52:55], v[20:23], v[198:201], v[52:55]
	v_mfma_f32_16x16x32_f16 v[48:51], v[136:139], v[184:187], v[48:51]
	v_mfma_f32_16x16x32_f16 v[36:39], v[20:23], v[206:209], v[36:39]
	v_mfma_f32_16x16x32_f16 v[32:35], v[136:139], v[202:205], v[32:35]
	v_mfma_f32_16x16x32_f16 v[20:23], v[20:23], v[214:217], v[0:3]
	v_mfma_f32_16x16x32_f16 v[0:3], v[136:139], v[210:213], v[4:7]
	v_mfma_f32_16x16x32_f16 v[64:67], v[140:143], v[180:183], v[64:67]
	v_mfma_f32_16x16x32_f16 v[48:51], v[140:143], v[198:201], v[48:51]
	v_mfma_f32_16x16x32_f16 v[32:35], v[140:143], v[206:209], v[32:35]
	v_mfma_f32_16x16x32_f16 v[16:19], v[140:143], v[214:217], v[0:3]
	s_setprio 0
	s_setprio 1
	v_mfma_f32_16x16x32_f16 v[0:3], v[144:147], v[176:179], v[60:63]
	v_mfma_f32_16x16x32_f16 v[60:63], v[148:151], v[180:183], v[0:3]
	v_mfma_f32_16x16x32_f16 v[0:3], v[152:155], v[176:179], v[56:59]
	v_mfma_f32_16x16x32_f16 v[56:59], v[156:159], v[180:183], v[0:3]
	v_mfma_f32_16x16x32_f16 v[0:3], v[144:147], v[184:187], v[44:47]
	v_mfma_f32_16x16x32_f16 v[44:47], v[148:151], v[198:201], v[0:3]
	v_mfma_f32_16x16x32_f16 v[0:3], v[152:155], v[184:187], v[40:43]
	v_mfma_f32_16x16x32_f16 v[40:43], v[156:159], v[198:201], v[0:3]
	v_mfma_f32_16x16x32_f16 v[0:3], v[144:147], v[202:205], v[28:31]
	v_mfma_f32_16x16x32_f16 v[28:31], v[148:151], v[206:209], v[0:3]
	v_mfma_f32_16x16x32_f16 v[0:3], v[152:155], v[202:205], v[24:27]
	v_mfma_f32_16x16x32_f16 v[24:27], v[156:159], v[206:209], v[0:3]
	v_mfma_f32_16x16x32_f16 v[0:3], v[144:147], v[210:213], v[12:15]
	v_mfma_f32_16x16x32_f16 v[12:15], v[148:151], v[214:217], v[0:3]
	v_mfma_f32_16x16x32_f16 v[0:3], v[152:155], v[210:213], v[8:11]
	v_mfma_f32_16x16x32_f16 v[8:11], v[156:159], v[214:217], v[0:3]
	s_setprio 0
	s_barrier
	s_add_i32 s62, s62, 2
	s_add_u32 s36, s36, 0x100
	s_addc_u32 s37, s37, 0
	s_add_u32 s60, s60, 0x100
	s_addc_u32 s61, s61, 0
	s_cmp_gt_u32 s62, 13
	s_cbranch_scc0 .LBB0_2566
	s_and_b64 vcc, exec, s[16:17]
	s_cbranch_vccz .LBB0_2569
	s_barrier

; #define PG8_STAGE(bufoff, gbase, voff) do { _Pragma("unroll") for (int _i = 0; _i < 2; ++_i) \
;         __builtin_amdgcn_global_load_lds((const unsigned*)((const char*)(gbase) + (voff)[_i]), (PG8_LAS unsigned*)(lds + (bufoff) + ldsw + _i * 8192), 16, 0, 0); } while (0)
; #define PG8_LDA(dst, b, h) do { _Pragma("unroll") for (int m = 0; m < 4; ++m) _Pragma("unroll") for (int k = 0; k < 2; ++k) dst[m][k] = *(const PG8_LAS bf16x8*)(lds + PG8_SA(b, h) + aoff + m * 2048 + k * 1024); } while (0)
; #define PG8_LDB(dst, b, h) do { _Pragma("unroll") for (int n = 0; n < 2; ++n) _Pragma("unroll") for (int k = 0; k < 2; ++k) dst[n][k] = *(const PG8_LAS bf16x8*)(lds + PG8_SB(b, h) + boff + n * 2048 + k * 1024); } while (0)
; #define PG8_MMA(ai, bj, At, Bt) do { __builtin_amdgcn_s_setprio(1); _Pragma("unroll") for (int m = 0; m < 4; ++m) _Pragma("unroll") for (int n = 0; n < 2; ++n) _Pragma("unroll") for (int k = 0; k < 2; ++k) \
;         acc[ai][bj][m][n] = mma16<F16>(Bt[n][k], At[m][k], acc[ai][bj][m][n]); __builtin_amdgcn_s_setprio(0); } while (0)
; template <class Epi, class Sched, bool ALIGN_EPI = false, bool SP2 = false, bool F16 = false>
; __device__ __forceinline__ void gemm_phase(PG8_LAS unsigned char* lds, const Gemm g, const Sched& S, const Epi& E, const int wid_in) {
;     ...
;         const bool has_next = S.next(ui + 1, nxt);
;         const char* nA = has_next ? (const char*)g.A + (size_t)nxt.pm * tstep : cA; const char* nB = has_next ? (const char*)g.Bt + (size_t)nxt.pn * tstep : cB;
;         for (int t = 0; t < nt; t += 2) {
;             const bool last = (t == nt - 2);
;             const char* a1 = cA + (size_t)(t + 1) * kstep;
;             const char* a2 = last ? nA : cA + (size_t)(t + 2) * kstep; const char* b2 = last ? nB : cB + (size_t)(t + 2) * kstep;
;             const char* a3 = a2 + kstep; const char* b3 = b2 + kstep;
;             if (last && has_next) S.a_ready(nxt);
;             if constexpr (SP2) {
;             PG8_LDB(B0, 0, 0); PG8_LDB(B1, 0, 1); PG8_SCHED; PG8_LDA(At, 0, 0); PG8_STAGE(PG8_SA(1, 1), a1 + hstep, voffA);
;             PG8_WAIT_V(8); PG8_WAIT_L(0); PG8_BAR; PG8_MMA(0, 0, At, B0); PG8_MMA(0, 1, At, B1); PG8_BAR; PG8_SCHED;
;             PG8_LDA(At, 0, 1); PG8_STAGE(PG8_SB(0, 0), b2, voffB); PG8_STAGE(PG8_SB(0, 1), b2 + hstep, voffB); PG8_STAGE(PG8_SA(0, 0), a2, voffA);
;     ...
;         cur = nxt; cA = nA; cB = nB; ++ui;
.LBB0_2601:
	s_mov_b64 s[42:43], s[10:11]
	s_add_i32 s10, s30, s40
	s_mov_b64 s[36:37], s[12:13]
	s_mov_b32 s12, s56
	s_mov_b32 s13, s55
	s_and_b32 s55, s10, 3
	s_ashr_i32 s56, s10, 2
	s_and_b64 s[10:11], s[26:27], exec
	s_cselect_b32 s12, s56, s12
	ds_read_b128 v[0:3], v134
	ds_read_b128 v[4:7], v134 offset:1024
	ds_read_b128 v[8:11], v134 offset:2048
	ds_read_b128 v[12:15], v134 offset:3072
	ds_read_b128 v[16:19], v135
	ds_read_b128 v[20:23], v135 offset:1024
	ds_read_b128 v[24:27], v135 offset:2048
	ds_read_b128 v[28:31], v135 offset:3072
	s_cselect_b32 s10, s55, s13
	s_ashr_i32 s13, s12, 31
	s_lshl_b64 s[12:13], s[12:13], 17
	s_add_u32 s12, s41, s12
	s_addc_u32 s13, s44, s13
	s_and_b64 s[30:31], s[26:27], exec
	s_cselect_b32 s35, s13, s37
	s_cselect_b32 s34, s12, s36
	s_ashr_i32 s11, s10, 31
	s_lshl_b64 s[10:11], s[10:11], 17
	s_add_u32 s10, s45, s10
	s_addc_u32 s11, s46, s11
	s_and_b64 s[30:31], s[26:27], exec
	s_cselect_b32 s31, s11, s43
	s_cselect_b32 s30, s10, s42
	s_add_u32 s58, s36, 0x10080
	s_addc_u32 s59, s37, 0
	s_mov_b32 m0, s91
	v_lshl_add_u64 v[64:65], s[58:59], 0, v[130:131]
	ds_read_b128 v[32:35], v136
	ds_read_b128 v[36:39], v136 offset:1024
	ds_read_b128 v[40:43], v136 offset:2048
	ds_read_b128 v[44:47], v136 offset:3072
	ds_read_b128 v[48:51], v136 offset:4096
	ds_read_b128 v[52:55], v136 offset:5120
	ds_read_b128 v[56:59], v136 offset:6144
	ds_read_b128 v[60:63], v136 offset:7168
	global_load_lds_dwordx4 v[64:65], off
	v_lshl_add_u64 v[64:65], s[58:59], 0, v[128:129]
	s_mov_b32 m0, s14
	s_nop 0
	global_load_lds_dwordx4 v[64:65], off
	s_waitcnt vmcnt(8)
	s_cmp_lt_u32 s3, 4
	s_cbranch_scc1 .Lgls_96
	s_waitcnt lgkmcnt(0)
.Lgls_96:
	s_barrier
	s_setprio 1
	s_waitcnt lgkmcnt(0)
	v_mfma_f32_16x16x32_bf16 v[64:67], v[0:3], v[32:35], 0
	v_mfma_f32_16x16x32_bf16 v[68:71], v[8:11], v[32:35], 0
	v_mfma_f32_16x16x32_bf16 v[72:75], v[0:3], v[40:43], 0
	v_mfma_f32_16x16x32_bf16 v[76:79], v[8:11], v[40:43], 0
	v_mfma_f32_16x16x32_bf16 v[80:83], v[0:3], v[48:51], 0
	v_mfma_f32_16x16x32_bf16 v[84:87], v[8:11], v[48:51], 0
	v_mfma_f32_16x16x32_bf16 v[88:91], v[0:3], v[56:59], 0
	v_mfma_f32_16x16x32_bf16 v[92:95], v[8:11], v[56:59], 0
	v_mfma_f32_16x16x32_bf16 v[64:67], v[4:7], v[36:39], v[64:67]
	v_mfma_f32_16x16x32_bf16 v[68:71], v[12:15], v[36:39], v[68:71]
	v_mfma_f32_16x16x32_bf16 v[72:75], v[4:7], v[44:47], v[72:75]
	v_mfma_f32_16x16x32_bf16 v[76:79], v[12:15], v[44:47], v[76:79]
	v_mfma_f32_16x16x32_bf16 v[80:83], v[4:7], v[52:55], v[80:83]
	v_mfma_f32_16x16x32_bf16 v[84:87], v[12:15], v[52:55], v[84:87]
	v_mfma_f32_16x16x32_bf16 v[88:91], v[4:7], v[60:63], v[88:91]
	v_mfma_f32_16x16x32_bf16 v[92:95], v[12:15], v[60:63], v[92:95]
	s_setprio 0
	s_setprio 1
	v_mfma_f32_16x16x32_bf16 v[96:99], v[16:19], v[32:35], 0
	v_mfma_f32_16x16x32_bf16 v[32:35], v[24:27], v[32:35], 0
	v_mfma_f32_16x16x32_bf16 v[96:99], v[20:23], v[36:39], v[96:99]
	v_mfma_f32_16x16x32_bf16 v[32:35], v[28:31], v[36:39], v[32:35]
	v_mfma_f32_16x16x32_bf16 v[36:39], v[16:19], v[40:43], 0
	v_mfma_f32_16x16x32_bf16 v[40:43], v[24:27], v[40:43], 0
	v_mfma_f32_16x16x32_bf16 v[36:39], v[20:23], v[44:47], v[36:39]
	v_mfma_f32_16x16x32_bf16 v[40:43], v[28:31], v[44:47], v[40:43]
	v_mfma_f32_16x16x32_bf16 v[44:47], v[16:19], v[48:51], 0
	v_mfma_f32_16x16x32_bf16 v[48:51], v[24:27], v[48:51], 0
	v_mfma_f32_16x16x32_bf16 v[44:47], v[20:23], v[52:55], v[44:47]
	v_mfma_f32_16x16x32_bf16 v[48:51], v[28:31], v[52:55], v[48:51]
	v_mfma_f32_16x16x32_bf16 v[52:55], v[16:19], v[56:59], 0
	v_mfma_f32_16x16x32_bf16 v[56:59], v[24:27], v[56:59], 0
	v_mfma_f32_16x16x32_bf16 v[52:55], v[20:23], v[60:63], v[52:55]
	v_mfma_f32_16x16x32_bf16 v[56:59], v[28:31], v[60:63], v[56:59]
	s_setprio 0
	s_barrier
	v_lshl_add_u64 v[204:205], s[42:43], 0, v[130:131]
	s_mov_b32 m0, s15
	v_lshl_add_u64 v[140:141], v[204:205], 0, s[22:23]
	v_lshl_add_u64 v[206:207], s[42:43], 0, v[128:129]
	s_add_u32 s58, s42, 0x10100
	ds_read_b128 v[60:63], v136 offset:16384
	ds_read_b128 v[100:103], v136 offset:17408
	ds_read_b128 v[104:107], v136 offset:18432
	ds_read_b128 v[108:111], v136 offset:19456
	ds_read_b128 v[112:115], v136 offset:20480
	ds_read_b128 v[116:119], v136 offset:21504
	ds_read_b128 v[120:123], v136 offset:22528
	ds_read_b128 v[124:127], v136 offset:23552
	global_load_lds_dwordx4 v[140:141], off
	v_lshl_add_u64 v[140:141], v[206:207], 0, s[22:23]
	s_mov_b32 m0, s48
	s_addc_u32 s59, s43, 0
	global_load_lds_dwordx4 v[140:141], off
	v_lshl_add_u64 v[140:141], s[58:59], 0, v[130:131]
	s_mov_b32 m0, s49
	v_lshl_add_u64 v[208:209], s[36:37], 0, v[130:131]
	global_load_lds_dwordx4 v[140:141], off
	v_lshl_add_u64 v[140:141], s[58:59], 0, v[128:129]
	s_mov_b32 m0, s50
	v_lshl_add_u64 v[210:211], s[36:37], 0, v[128:129]
	global_load_lds_dwordx4 v[140:141], off
	v_lshl_add_u64 v[140:141], v[208:209], 0, s[22:23]
	s_mov_b32 m0, s74
	s_nop 0
	global_load_lds_dwordx4 v[140:141], off
	v_lshl_add_u64 v[140:141], v[210:211], 0, s[22:23]
	s_mov_b32 m0, s66
	s_nop 0
	global_load_lds_dwordx4 v[140:141], off
	s_waitcnt vmcnt(8)
	s_cmp_lt_u32 s3, 4
	s_cbranch_scc1 .Lgls_97
	s_waitcnt lgkmcnt(0)
; #define PG8_STAGE(bufoff, gbase, voff) do { _Pragma("unroll") for (int _i = 0; _i < 2; ++_i) \
;         __builtin_amdgcn_global_load_lds((const unsigned*)((const char*)(gbase) + (voff)[_i]), (PG8_LAS unsigned*)(lds + (bufoff) + ldsw + _i * 8192), 16, 0, 0); } while (0)
; #define PG8_LDA(dst, b, h) do { _Pragma("unroll") for (int m = 0; m < 4; ++m) _Pragma("unroll") for (int k = 0; k < 2; ++k) dst[m][k] = *(const PG8_LAS bf16x8*)(lds + PG8_SA(b, h) + aoff + m * 2048 + k * 1024); } while (0)
; #define PG8_LDB(dst, b, h) do { _Pragma("unroll") for (int n = 0; n < 2; ++n) _Pragma("unroll") for (int k = 0; k < 2; ++k) dst[n][k] = *(const PG8_LAS bf16x8*)(lds + PG8_SB(b, h) + boff + n * 2048 + k * 1024); } while (0)
; #define PG8_MMA(ai, bj, At, Bt) do { __builtin_amdgcn_s_setprio(1); _Pragma("unroll") for (int m = 0; m < 4; ++m) _Pragma("unroll") for (int n = 0; n < 2; ++n) _Pragma("unroll") for (int k = 0; k < 2; ++k) \
;         acc[ai][bj][m][n] = mma16<F16>(Bt[n][k], At[m][k], acc[ai][bj][m][n]); __builtin_amdgcn_s_setprio(0); } while (0)
; #define PG8_WAIT_V(n) asm volatile("s_waitcnt vmcnt(" #n ")" ::: "memory")
; template <class Epi, class Sched, bool ALIGN_EPI = false, bool SP2 = false, bool F16 = false>
; __device__ __forceinline__ void gemm_phase(PG8_LAS unsigned char* lds, const Gemm g, const Sched& S, const Epi& E, const int wid_in) {
;     ...
;             PG8_LDB(B0, 0, 0); PG8_LDB(B1, 0, 1); PG8_SCHED; PG8_LDA(At, 0, 0); PG8_STAGE(PG8_SA(1, 1), a1 + hstep, voffA);
;             PG8_WAIT_V(8); PG8_WAIT_L(0); PG8_BAR; PG8_MMA(0, 0, At, B0); PG8_MMA(0, 1, At, B1); PG8_BAR; PG8_SCHED;
;             PG8_LDA(At, 0, 1); PG8_STAGE(PG8_SB(0, 0), b2, voffB); PG8_STAGE(PG8_SB(0, 1), b2 + hstep, voffB); PG8_STAGE(PG8_SA(0, 0), a2, voffA);
;             PG8_WAIT_V(8); PG8_WAIT_L(0); PG8_BAR; PG8_MMA(1, 0, At, B0); PG8_MMA(1, 1, At, B1); PG8_BAR; PG8_SCHED;
;             PG8_LDB(B0, 1, 0); PG8_LDB(B1, 1, 1); PG8_SCHED; PG8_LDA(At, 1, 0); PG8_STAGE(PG8_SA(0, 1), a2 + hstep, voffA);
;             PG8_WAIT_V(8); PG8_WAIT_L(0); PG8_BAR; PG8_MMA(0, 0, At, B0); PG8_MMA(0, 1, At, B1); PG8_BAR; PG8_SCHED;
;             PG8_LDA(At, 1, 1); PG8_STAGE(PG8_SB(1, 0), b3, voffB); PG8_STAGE(PG8_SB(1, 1), b3 + hstep, voffB); PG8_STAGE(PG8_SA(1, 0), a3, voffA);
;             PG8_WAIT_V(8); PG8_WAIT_L(0); PG8_BAR; PG8_MMA(1, 0, At, B0); PG8_MMA(1, 1, At, B1); PG8_BAR; PG8_SCHED;
.Lgls_97:
	s_barrier
	s_setprio 1
	s_waitcnt lgkmcnt(0)
	v_mfma_f32_16x16x32_bf16 v[140:143], v[0:3], v[60:63], 0
	v_mfma_f32_16x16x32_bf16 v[148:151], v[0:3], v[104:107], 0
	v_mfma_f32_16x16x32_bf16 v[156:159], v[0:3], v[112:115], 0
	v_mfma_f32_16x16x32_bf16 v[0:3], v[0:3], v[120:123], 0
	v_mfma_f32_16x16x32_bf16 v[140:143], v[4:7], v[100:103], v[140:143]
	v_mfma_f32_16x16x32_bf16 v[148:151], v[4:7], v[108:111], v[148:151]
	v_mfma_f32_16x16x32_bf16 v[156:159], v[4:7], v[116:119], v[156:159]
	v_mfma_f32_16x16x32_bf16 v[0:3], v[4:7], v[124:127], v[0:3]
	v_mfma_f32_16x16x32_bf16 v[4:7], v[8:11], v[120:123], 0
	v_mfma_f32_16x16x32_bf16 v[144:147], v[8:11], v[60:63], 0
	v_mfma_f32_16x16x32_bf16 v[152:155], v[8:11], v[104:107], 0
	v_mfma_f32_16x16x32_bf16 v[160:163], v[8:11], v[112:115], 0
	v_mfma_f32_16x16x32_bf16 v[4:7], v[12:15], v[124:127], v[4:7]
	v_mfma_f32_16x16x32_bf16 v[144:147], v[12:15], v[100:103], v[144:147]
	v_mfma_f32_16x16x32_bf16 v[152:155], v[12:15], v[108:111], v[152:155]
	v_mfma_f32_16x16x32_bf16 v[160:163], v[12:15], v[116:119], v[160:163]
	s_setprio 0
	s_setprio 1
	v_mfma_f32_16x16x32_bf16 v[8:11], v[16:19], v[60:63], 0
	v_mfma_f32_16x16x32_bf16 v[12:15], v[24:27], v[60:63], 0
	v_mfma_f32_16x16x32_bf16 v[8:11], v[20:23], v[100:103], v[8:11]
	v_mfma_f32_16x16x32_bf16 v[12:15], v[28:31], v[100:103], v[12:15]
	v_mfma_f32_16x16x32_bf16 v[60:63], v[16:19], v[104:107], 0
	v_mfma_f32_16x16x32_bf16 v[100:103], v[24:27], v[104:107], 0
	v_mfma_f32_16x16x32_bf16 v[104:107], v[16:19], v[112:115], 0
	v_mfma_f32_16x16x32_bf16 v[16:19], v[16:19], v[120:123], 0
	v_mfma_f32_16x16x32_bf16 v[60:63], v[20:23], v[108:111], v[60:63]
	v_mfma_f32_16x16x32_bf16 v[100:103], v[28:31], v[108:111], v[100:103]
	v_mfma_f32_16x16x32_bf16 v[104:107], v[20:23], v[116:119], v[104:107]
	v_mfma_f32_16x16x32_bf16 v[108:111], v[24:27], v[112:115], 0
	v_mfma_f32_16x16x32_bf16 v[16:19], v[20:23], v[124:127], v[16:19]
	v_mfma_f32_16x16x32_bf16 v[20:23], v[24:27], v[120:123], 0
	v_mfma_f32_16x16x32_bf16 v[108:111], v[28:31], v[116:119], v[108:111]
	v_mfma_f32_16x16x32_bf16 v[20:23], v[28:31], v[124:127], v[20:23]
	s_setprio 0
	s_barrier
	ds_read_b128 v[24:27], v137
	ds_read_b128 v[28:31], v137 offset:1024
	ds_read_b128 v[112:115], v137 offset:2048
	ds_read_b128 v[116:119], v137 offset:3072
	ds_read_b128 v[120:123], v138
	ds_read_b128 v[124:127], v138 offset:1024
	ds_read_b128 v[164:167], v138 offset:2048
	ds_read_b128 v[168:171], v138 offset:3072
	s_add_u32 s58, s36, 0x10100
	s_addc_u32 s59, s37, 0
	s_mov_b32 m0, s90
	v_lshl_add_u64 v[212:213], s[58:59], 0, v[130:131]
	ds_read_b128 v[172:175], v136 offset:32768
	ds_read_b128 v[176:179], v136 offset:33792
	ds_read_b128 v[180:183], v136 offset:34816
	ds_read_b128 v[184:187], v136 offset:35840
	ds_read_b128 v[188:191], v136 offset:36864
	ds_read_b128 v[192:195], v136 offset:37888
	ds_read_b128 v[196:199], v136 offset:38912
	ds_read_b128 v[200:203], v136 offset:39936
	global_load_lds_dwordx4 v[212:213], off
	v_lshl_add_u64 v[212:213], s[58:59], 0, v[128:129]
	s_mov_b32 m0, s47
	s_nop 0
	global_load_lds_dwordx4 v[212:213], off
	s_waitcnt vmcnt(8)
	s_cmp_lt_u32 s3, 4
	s_cbranch_scc1 .Lgls_98
	s_waitcnt lgkmcnt(0)
.Lgls_98:
	s_barrier
	s_setprio 1
	s_waitcnt lgkmcnt(0)
	v_mfma_f32_16x16x32_bf16 v[64:67], v[24:27], v[172:175], v[64:67]
	v_mfma_f32_16x16x32_bf16 v[68:71], v[112:115], v[172:175], v[68:71]
	v_mfma_f32_16x16x32_bf16 v[72:75], v[24:27], v[180:183], v[72:75]
	v_mfma_f32_16x16x32_bf16 v[76:79], v[112:115], v[180:183], v[76:79]
	v_mfma_f32_16x16x32_bf16 v[80:83], v[24:27], v[188:191], v[80:83]
	v_mfma_f32_16x16x32_bf16 v[84:87], v[112:115], v[188:191], v[84:87]
	v_mfma_f32_16x16x32_bf16 v[88:91], v[24:27], v[196:199], v[88:91]
	v_mfma_f32_16x16x32_bf16 v[92:95], v[112:115], v[196:199], v[92:95]
	v_mfma_f32_16x16x32_bf16 v[64:67], v[28:31], v[176:179], v[64:67]
	v_mfma_f32_16x16x32_bf16 v[68:71], v[116:119], v[176:179], v[68:71]
	v_mfma_f32_16x16x32_bf16 v[72:75], v[28:31], v[184:187], v[72:75]
	v_mfma_f32_16x16x32_bf16 v[76:79], v[116:119], v[184:187], v[76:79]
	v_mfma_f32_16x16x32_bf16 v[80:83], v[28:31], v[192:195], v[80:83]
	v_mfma_f32_16x16x32_bf16 v[84:87], v[116:119], v[192:195], v[84:87]
	v_mfma_f32_16x16x32_bf16 v[88:91], v[28:31], v[200:203], v[88:91]
	v_mfma_f32_16x16x32_bf16 v[92:95], v[116:119], v[200:203], v[92:95]
	s_setprio 0
	s_setprio 1
	v_mfma_f32_16x16x32_bf16 v[96:99], v[120:123], v[172:175], v[96:99]
	v_mfma_f32_16x16x32_bf16 v[32:35], v[164:167], v[172:175], v[32:35]
	v_mfma_f32_16x16x32_bf16 v[36:39], v[120:123], v[180:183], v[36:39]
	v_mfma_f32_16x16x32_bf16 v[40:43], v[164:167], v[180:183], v[40:43]
	v_mfma_f32_16x16x32_bf16 v[44:47], v[120:123], v[188:191], v[44:47]
	v_mfma_f32_16x16x32_bf16 v[48:51], v[164:167], v[188:191], v[48:51]
	v_mfma_f32_16x16x32_bf16 v[52:55], v[120:123], v[196:199], v[52:55]
	v_mfma_f32_16x16x32_bf16 v[56:59], v[164:167], v[196:199], v[56:59]
	v_mfma_f32_16x16x32_bf16 v[96:99], v[124:127], v[176:179], v[96:99]
	v_mfma_f32_16x16x32_bf16 v[32:35], v[168:171], v[176:179], v[32:35]
	v_mfma_f32_16x16x32_bf16 v[36:39], v[124:127], v[184:187], v[36:39]
	v_mfma_f32_16x16x32_bf16 v[40:43], v[168:171], v[184:187], v[40:43]
	v_mfma_f32_16x16x32_bf16 v[44:47], v[124:127], v[192:195], v[44:47]
	v_mfma_f32_16x16x32_bf16 v[48:51], v[168:171], v[192:195], v[48:51]
	v_mfma_f32_16x16x32_bf16 v[52:55], v[124:127], v[200:203], v[52:55]
	v_mfma_f32_16x16x32_bf16 v[56:59], v[168:171], v[200:203], v[56:59]
	s_setprio 0
	s_barrier
	s_mov_b32 m0, s51
	v_lshl_add_u64 v[204:205], v[204:205], 0, s[24:25]
	s_add_u32 s42, s42, 0x10180
	ds_read_b128 v[172:175], v136 offset:49152
	ds_read_b128 v[176:179], v136 offset:50176
	ds_read_b128 v[180:183], v136 offset:51200
	ds_read_b128 v[184:187], v136 offset:52224
	ds_read_b128 v[188:191], v136 offset:53248
	ds_read_b128 v[192:195], v136 offset:54272
	ds_read_b128 v[196:199], v136 offset:55296
	ds_read_b128 v[200:203], v136 offset:56320
	global_load_lds_dwordx4 v[204:205], off
	v_lshl_add_u64 v[204:205], v[206:207], 0, s[24:25]
	s_mov_b32 m0, s52
	s_addc_u32 s43, s43, 0
	global_load_lds_dwordx4 v[204:205], off
	v_lshl_add_u64 v[204:205], s[42:43], 0, v[130:131]
	s_mov_b32 m0, s53
	s_nop 0
	global_load_lds_dwordx4 v[204:205], off
	v_lshl_add_u64 v[204:205], s[42:43], 0, v[128:129]
	s_mov_b32 m0, s54
	s_nop 0
	global_load_lds_dwordx4 v[204:205], off
	v_lshl_add_u64 v[204:205], v[208:209], 0, s[24:25]
	s_mov_b32 m0, s75
	s_nop 0
	global_load_lds_dwordx4 v[204:205], off
	v_lshl_add_u64 v[204:205], v[210:211], 0, s[24:25]
	s_mov_b32 m0, s67
	s_nop 0
	global_load_lds_dwordx4 v[204:205], off
	s_waitcnt vmcnt(8)
	s_cmp_lt_u32 s3, 4
	s_cbranch_scc1 .Lgls_99
	s_waitcnt lgkmcnt(0)
; #define PG8_STAGE(bufoff, gbase, voff) do { _Pragma("unroll") for (int _i = 0; _i < 2; ++_i) \
;         __builtin_amdgcn_global_load_lds((const unsigned*)((const char*)(gbase) + (voff)[_i]), (PG8_LAS unsigned*)(lds + (bufoff) + ldsw + _i * 8192), 16, 0, 0); } while (0)
; #define PG8_LDA(dst, b, h) do { _Pragma("unroll") for (int m = 0; m < 4; ++m) _Pragma("unroll") for (int k = 0; k < 2; ++k) dst[m][k] = *(const PG8_LAS bf16x8*)(lds + PG8_SA(b, h) + aoff + m * 2048 + k * 1024); } while (0)
; #define PG8_LDB(dst, b, h) do { _Pragma("unroll") for (int n = 0; n < 2; ++n) _Pragma("unroll") for (int k = 0; k < 2; ++k) dst[n][k] = *(const PG8_LAS bf16x8*)(lds + PG8_SB(b, h) + boff + n * 2048 + k * 1024); } while (0)
; #define PG8_MMA(ai, bj, At, Bt) do { __builtin_amdgcn_s_setprio(1); _Pragma("unroll") for (int m = 0; m < 4; ++m) _Pragma("unroll") for (int n = 0; n < 2; ++n) _Pragma("unroll") for (int k = 0; k < 2; ++k) \
;         acc[ai][bj][m][n] = mma16<F16>(Bt[n][k], At[m][k], acc[ai][bj][m][n]); __builtin_amdgcn_s_setprio(0); } while (0)
; #define PG8_WAIT_V(n) asm volatile("s_waitcnt vmcnt(" #n ")" ::: "memory")
; #define PG8_WAIT_L(n) asm volatile("s_waitcnt lgkmcnt(" #n ")" ::: "memory")
; #define PG8_BAR __builtin_amdgcn_s_barrier()
; #define PG8_SCHED __builtin_amdgcn_sched_barrier(0)
; template <class Epi, class Sched, bool ALIGN_EPI = false, bool SP2 = false, bool F16 = false>
; __device__ __forceinline__ void gemm_phase(PG8_LAS unsigned char* lds, const Gemm g, const Sched& S, const Epi& E, const int wid_in) {
;     ...
;             PG8_LDB(B0, 0, 0); PG8_LDB(B1, 0, 1); PG8_SCHED; PG8_LDA(At, 0, 0); PG8_STAGE(PG8_SA(1, 1), a1 + hstep, voffA);
;             PG8_WAIT_V(8); PG8_WAIT_L(0); PG8_BAR; PG8_MMA(0, 0, At, B0); PG8_MMA(0, 1, At, B1); PG8_BAR; PG8_SCHED;
;             PG8_LDA(At, 0, 1); PG8_STAGE(PG8_SB(0, 0), b2, voffB); PG8_STAGE(PG8_SB(0, 1), b2 + hstep, voffB); PG8_STAGE(PG8_SA(0, 0), a2, voffA);
;             PG8_WAIT_V(8); PG8_WAIT_L(0); PG8_BAR; PG8_MMA(1, 0, At, B0); PG8_MMA(1, 1, At, B1); PG8_BAR; PG8_SCHED;
;             PG8_LDB(B0, 1, 0); PG8_LDB(B1, 1, 1); PG8_SCHED; PG8_LDA(At, 1, 0); PG8_STAGE(PG8_SA(0, 1), a2 + hstep, voffA);
;             PG8_WAIT_V(8); PG8_WAIT_L(0); PG8_BAR; PG8_MMA(0, 0, At, B0); PG8_MMA(0, 1, At, B1); PG8_BAR; PG8_SCHED;
.Lgls_99:
	s_barrier
	s_setprio 1
	s_waitcnt lgkmcnt(0)
	v_mfma_f32_16x16x32_bf16 v[0:3], v[24:27], v[196:199], v[0:3]
	v_mfma_f32_16x16x32_bf16 v[4:7], v[112:115], v[196:199], v[4:7]
	v_mfma_f32_16x16x32_bf16 v[140:143], v[24:27], v[172:175], v[140:143]
	v_mfma_f32_16x16x32_bf16 v[144:147], v[112:115], v[172:175], v[144:147]
	v_mfma_f32_16x16x32_bf16 v[148:151], v[24:27], v[180:183], v[148:151]
	v_mfma_f32_16x16x32_bf16 v[152:155], v[112:115], v[180:183], v[152:155]
	v_mfma_f32_16x16x32_bf16 v[156:159], v[24:27], v[188:191], v[156:159]
	v_mfma_f32_16x16x32_bf16 v[160:163], v[112:115], v[188:191], v[160:163]
	v_mfma_f32_16x16x32_bf16 v[0:3], v[28:31], v[200:203], v[0:3]
	v_mfma_f32_16x16x32_bf16 v[4:7], v[116:119], v[200:203], v[4:7]
	v_mfma_f32_16x16x32_bf16 v[140:143], v[28:31], v[176:179], v[140:143]
	v_mfma_f32_16x16x32_bf16 v[144:147], v[116:119], v[176:179], v[144:147]
	v_mfma_f32_16x16x32_bf16 v[148:151], v[28:31], v[184:187], v[148:151]
	v_mfma_f32_16x16x32_bf16 v[152:155], v[116:119], v[184:187], v[152:155]
	v_mfma_f32_16x16x32_bf16 v[156:159], v[28:31], v[192:195], v[156:159]
	v_mfma_f32_16x16x32_bf16 v[160:163], v[116:119], v[192:195], v[160:163]
	s_setprio 0
	s_setprio 1
	v_mfma_f32_16x16x32_bf16 v[8:11], v[120:123], v[172:175], v[8:11]
	v_mfma_f32_16x16x32_bf16 v[12:15], v[164:167], v[172:175], v[12:15]
	v_mfma_f32_16x16x32_bf16 v[24:27], v[120:123], v[180:183], v[60:63]
	v_mfma_f32_16x16x32_bf16 v[28:31], v[164:167], v[180:183], v[100:103]
	v_mfma_f32_16x16x32_bf16 v[60:63], v[120:123], v[188:191], v[104:107]
	v_mfma_f32_16x16x32_bf16 v[100:103], v[164:167], v[188:191], v[108:111]
	v_mfma_f32_16x16x32_bf16 v[16:19], v[120:123], v[196:199], v[16:19]
	v_mfma_f32_16x16x32_bf16 v[20:23], v[164:167], v[196:199], v[20:23]
	v_mfma_f32_16x16x32_bf16 v[8:11], v[124:127], v[176:179], v[8:11]
	v_mfma_f32_16x16x32_bf16 v[12:15], v[168:171], v[176:179], v[12:15]
	v_mfma_f32_16x16x32_bf16 v[24:27], v[124:127], v[184:187], v[24:27]
	v_mfma_f32_16x16x32_bf16 v[28:31], v[168:171], v[184:187], v[28:31]
	v_mfma_f32_16x16x32_bf16 v[60:63], v[124:127], v[192:195], v[60:63]
	v_mfma_f32_16x16x32_bf16 v[100:103], v[168:171], v[192:195], v[100:103]
	v_mfma_f32_16x16x32_bf16 v[16:19], v[124:127], v[200:203], v[16:19]
	v_mfma_f32_16x16x32_bf16 v[20:23], v[168:171], v[200:203], v[20:23]
	s_setprio 0
	s_barrier
	ds_read_b128 v[104:107], v134
	ds_read_b128 v[108:111], v134 offset:1024
	ds_read_b128 v[112:115], v134 offset:2048
	ds_read_b128 v[116:119], v134 offset:3072
	ds_read_b128 v[120:123], v135
	ds_read_b128 v[124:127], v135 offset:1024
	ds_read_b128 v[164:167], v135 offset:2048
	ds_read_b128 v[168:171], v135 offset:3072
	s_add_u32 s36, s36, 0x10180
	s_addc_u32 s37, s37, 0
	s_mov_b32 m0, s91
	v_lshl_add_u64 v[204:205], s[36:37], 0, v[130:131]
	ds_read_b128 v[172:175], v136
	ds_read_b128 v[176:179], v136 offset:1024
	ds_read_b128 v[180:183], v136 offset:2048
	ds_read_b128 v[184:187], v136 offset:3072
	ds_read_b128 v[188:191], v136 offset:4096
	ds_read_b128 v[192:195], v136 offset:5120
	ds_read_b128 v[196:199], v136 offset:6144
	ds_read_b128 v[200:203], v136 offset:7168
	global_load_lds_dwordx4 v[204:205], off
	v_lshl_add_u64 v[204:205], s[36:37], 0, v[128:129]
	s_mov_b32 m0, s14
	s_nop 0
	global_load_lds_dwordx4 v[204:205], off
	s_waitcnt vmcnt(8)
	s_cmp_lt_u32 s3, 4
	s_cbranch_scc1 .Lgls_100
	s_waitcnt lgkmcnt(0)
.Lgls_100:
	s_barrier
	s_setprio 1
	s_waitcnt lgkmcnt(0)
	v_mfma_f32_16x16x32_bf16 v[64:67], v[104:107], v[172:175], v[64:67]
	v_mfma_f32_16x16x32_bf16 v[68:71], v[112:115], v[172:175], v[68:71]
	v_mfma_f32_16x16x32_bf16 v[72:75], v[104:107], v[180:183], v[72:75]
	v_mfma_f32_16x16x32_bf16 v[76:79], v[112:115], v[180:183], v[76:79]
	v_mfma_f32_16x16x32_bf16 v[80:83], v[104:107], v[188:191], v[80:83]
	v_mfma_f32_16x16x32_bf16 v[84:87], v[112:115], v[188:191], v[84:87]
	v_mfma_f32_16x16x32_bf16 v[88:91], v[104:107], v[196:199], v[88:91]
	v_mfma_f32_16x16x32_bf16 v[92:95], v[112:115], v[196:199], v[92:95]
	v_mfma_f32_16x16x32_bf16 v[64:67], v[108:111], v[176:179], v[64:67]
	v_mfma_f32_16x16x32_bf16 v[68:71], v[116:119], v[176:179], v[68:71]
	v_mfma_f32_16x16x32_bf16 v[72:75], v[108:111], v[184:187], v[72:75]
	v_mfma_f32_16x16x32_bf16 v[76:79], v[116:119], v[184:187], v[76:79]
	v_mfma_f32_16x16x32_bf16 v[80:83], v[108:111], v[192:195], v[80:83]
	v_mfma_f32_16x16x32_bf16 v[84:87], v[116:119], v[192:195], v[84:87]
	v_mfma_f32_16x16x32_bf16 v[88:91], v[108:111], v[200:203], v[88:91]
	v_mfma_f32_16x16x32_bf16 v[92:95], v[116:119], v[200:203], v[92:95]
	s_setprio 0
	s_setprio 1
	v_mfma_f32_16x16x32_bf16 v[32:35], v[164:167], v[172:175], v[32:35]
	v_mfma_f32_16x16x32_bf16 v[96:99], v[120:123], v[172:175], v[96:99]
	v_mfma_f32_16x16x32_bf16 v[172:175], v[168:171], v[176:179], v[32:35]
	v_mfma_f32_16x16x32_bf16 v[32:35], v[120:123], v[180:183], v[36:39]
	v_mfma_f32_16x16x32_bf16 v[204:207], v[124:127], v[176:179], v[96:99]
	v_mfma_f32_16x16x32_bf16 v[176:179], v[124:127], v[184:187], v[32:35]
	v_mfma_f32_16x16x32_bf16 v[32:35], v[164:167], v[180:183], v[40:43]
	v_mfma_f32_16x16x32_bf16 v[40:43], v[168:171], v[184:187], v[32:35]
	v_mfma_f32_16x16x32_bf16 v[32:35], v[120:123], v[188:191], v[44:47]
	v_mfma_f32_16x16x32_bf16 v[44:47], v[124:127], v[192:195], v[32:35]
	v_mfma_f32_16x16x32_bf16 v[32:35], v[164:167], v[188:191], v[48:51]
	v_mfma_f32_16x16x32_bf16 v[48:51], v[168:171], v[192:195], v[32:35]
	v_mfma_f32_16x16x32_bf16 v[32:35], v[120:123], v[196:199], v[52:55]
	v_mfma_f32_16x16x32_bf16 v[52:55], v[124:127], v[200:203], v[32:35]
	v_mfma_f32_16x16x32_bf16 v[32:35], v[164:167], v[196:199], v[56:59]
	v_mfma_f32_16x16x32_bf16 v[56:59], v[168:171], v[200:203], v[32:35]
	s_setprio 0
	s_barrier
	s_mov_b32 m0, s15
	v_lshl_add_u64 v[240:241], s[30:31], 0, v[130:131]
	s_add_u32 s36, s30, 0x10000
	s_nop 1
	ds_read_b128 v[32:35], v136 offset:16384
	ds_read_b128 v[36:39], v136 offset:17408
	ds_read_b128 v[96:99], v136 offset:18432
	ds_read_b128 v[180:183], v136 offset:19456
	ds_read_b128 v[184:187], v136 offset:20480
	ds_read_b128 v[188:191], v136 offset:21504
	ds_read_b128 v[192:195], v136 offset:22528
	ds_read_b128 v[196:199], v136 offset:23552
	global_load_lds_dwordx4 v[240:241], off
	v_lshl_add_u64 v[242:243], s[30:31], 0, v[128:129]
	s_mov_b32 m0, s48
	s_addc_u32 s37, s31, 0
	global_load_lds_dwordx4 v[242:243], off
	v_lshl_add_u64 v[200:201], s[36:37], 0, v[130:131]
	s_mov_b32 m0, s49
	v_lshl_add_u64 v[244:245], s[34:35], 0, v[130:131]
	global_load_lds_dwordx4 v[200:201], off
	v_lshl_add_u64 v[200:201], s[36:37], 0, v[128:129]
	s_mov_b32 m0, s50
	v_lshl_add_u64 v[246:247], s[34:35], 0, v[128:129]
	global_load_lds_dwordx4 v[200:201], off
	s_mov_b32 m0, s74
	s_nop 0
	global_load_lds_dwordx4 v[244:245], off
	s_mov_b32 m0, s66
	s_nop 0
	global_load_lds_dwordx4 v[246:247], off
	s_waitcnt vmcnt(8)
	s_cmp_lt_u32 s3, 4
	s_cbranch_scc1 .Lgls_101
	s_waitcnt lgkmcnt(0)
; #define PG8_STAGE(bufoff, gbase, voff) do { _Pragma("unroll") for (int _i = 0; _i < 2; ++_i) \
;         __builtin_amdgcn_global_load_lds((const unsigned*)((const char*)(gbase) + (voff)[_i]), (PG8_LAS unsigned*)(lds + (bufoff) + ldsw + _i * 8192), 16, 0, 0); } while (0)
; #define PG8_LDA(dst, b, h) do { _Pragma("unroll") for (int m = 0; m < 4; ++m) _Pragma("unroll") for (int k = 0; k < 2; ++k) dst[m][k] = *(const PG8_LAS bf16x8*)(lds + PG8_SA(b, h) + aoff + m * 2048 + k * 1024); } while (0)
; #define PG8_LDB(dst, b, h) do { _Pragma("unroll") for (int n = 0; n < 2; ++n) _Pragma("unroll") for (int k = 0; k < 2; ++k) dst[n][k] = *(const PG8_LAS bf16x8*)(lds + PG8_SB(b, h) + boff + n * 2048 + k * 1024); } while (0)
; #define PG8_MMA(ai, bj, At, Bt) do { __builtin_amdgcn_s_setprio(1); _Pragma("unroll") for (int m = 0; m < 4; ++m) _Pragma("unroll") for (int n = 0; n < 2; ++n) _Pragma("unroll") for (int k = 0; k < 2; ++k) \
;         acc[ai][bj][m][n] = mma16<F16>(Bt[n][k], At[m][k], acc[ai][bj][m][n]); __builtin_amdgcn_s_setprio(0); } while (0)
; #define PG8_WAIT_V(n) asm volatile("s_waitcnt vmcnt(" #n ")" ::: "memory")
; #define PG8_WAIT_L(n) asm volatile("s_waitcnt lgkmcnt(" #n ")" ::: "memory")
; #define PG8_BAR __builtin_amdgcn_s_barrier()
; #define PG8_SCHED __builtin_amdgcn_sched_barrier(0)
; template <class Epi, class Sched, bool ALIGN_EPI = false, bool SP2 = false, bool F16 = false>
; __device__ __forceinline__ void gemm_phase(PG8_LAS unsigned char* lds, const Gemm g, const Sched& S, const Epi& E, const int wid_in) {
;     ...
;             PG8_WAIT_V(8); PG8_WAIT_L(0); PG8_BAR; PG8_MMA(1, 0, At, B0); PG8_MMA(1, 1, At, B1); PG8_BAR; PG8_SCHED;
;             PG8_LDB(B0, 1, 0); PG8_LDB(B1, 1, 1); PG8_SCHED; PG8_LDA(At, 1, 0); PG8_STAGE(PG8_SA(0, 1), a2 + hstep, voffA);
;             PG8_WAIT_V(8); PG8_WAIT_L(0); PG8_BAR; PG8_MMA(0, 0, At, B0); PG8_MMA(0, 1, At, B1); PG8_BAR; PG8_SCHED;
;             PG8_LDA(At, 1, 1); PG8_STAGE(PG8_SB(1, 0), b3, voffB); PG8_STAGE(PG8_SB(1, 1), b3 + hstep, voffB); PG8_STAGE(PG8_SA(1, 0), a3, voffA);
;             PG8_WAIT_V(8); PG8_WAIT_L(0); PG8_BAR; PG8_MMA(1, 0, At, B0); PG8_MMA(1, 1, At, B1); PG8_BAR; PG8_SCHED;
.Lgls_101:
	s_barrier
	s_setprio 1
	s_waitcnt lgkmcnt(0)
	v_mfma_f32_16x16x32_bf16 v[0:3], v[104:107], v[192:195], v[0:3]
	v_mfma_f32_16x16x32_bf16 v[140:143], v[104:107], v[32:35], v[140:143]
	v_mfma_f32_16x16x32_bf16 v[144:147], v[112:115], v[32:35], v[144:147]
	v_mfma_f32_16x16x32_bf16 v[148:151], v[104:107], v[96:99], v[148:151]
	v_mfma_f32_16x16x32_bf16 v[152:155], v[112:115], v[96:99], v[152:155]
	v_mfma_f32_16x16x32_bf16 v[156:159], v[104:107], v[184:187], v[156:159]
	v_mfma_f32_16x16x32_bf16 v[160:163], v[112:115], v[184:187], v[160:163]
	v_mfma_f32_16x16x32_bf16 v[0:3], v[108:111], v[196:199], v[0:3]
	v_mfma_f32_16x16x32_bf16 v[4:7], v[112:115], v[192:195], v[4:7]
	v_mfma_f32_16x16x32_bf16 v[140:143], v[108:111], v[36:39], v[140:143]
	v_mfma_f32_16x16x32_bf16 v[144:147], v[116:119], v[36:39], v[144:147]
	v_mfma_f32_16x16x32_bf16 v[148:151], v[108:111], v[180:183], v[148:151]
	v_mfma_f32_16x16x32_bf16 v[152:155], v[116:119], v[180:183], v[152:155]
	v_mfma_f32_16x16x32_bf16 v[156:159], v[108:111], v[188:191], v[156:159]
	v_mfma_f32_16x16x32_bf16 v[160:163], v[116:119], v[188:191], v[160:163]
	v_mfma_f32_16x16x32_bf16 v[200:203], v[116:119], v[196:199], v[4:7]
	s_setprio 0
	s_setprio 1
	v_mfma_f32_16x16x32_bf16 v[4:7], v[120:123], v[32:35], v[8:11]
	v_mfma_f32_16x16x32_bf16 v[8:11], v[124:127], v[36:39], v[4:7]
	v_mfma_f32_16x16x32_bf16 v[4:7], v[164:167], v[32:35], v[12:15]
	v_mfma_f32_16x16x32_bf16 v[12:15], v[168:171], v[36:39], v[4:7]
	v_mfma_f32_16x16x32_bf16 v[4:7], v[120:123], v[96:99], v[24:27]
	v_mfma_f32_16x16x32_bf16 v[24:27], v[124:127], v[180:183], v[4:7]
	v_mfma_f32_16x16x32_bf16 v[4:7], v[164:167], v[96:99], v[28:31]
	v_mfma_f32_16x16x32_bf16 v[28:31], v[168:171], v[180:183], v[4:7]
	v_mfma_f32_16x16x32_bf16 v[4:7], v[120:123], v[184:187], v[60:63]
	v_mfma_f32_16x16x32_bf16 v[180:183], v[124:127], v[188:191], v[4:7]
	v_mfma_f32_16x16x32_bf16 v[4:7], v[164:167], v[184:187], v[100:103]
	v_mfma_f32_16x16x32_bf16 v[184:187], v[168:171], v[188:191], v[4:7]
	v_mfma_f32_16x16x32_bf16 v[4:7], v[120:123], v[192:195], v[16:19]
	v_mfma_f32_16x16x32_bf16 v[188:191], v[124:127], v[196:199], v[4:7]
	v_mfma_f32_16x16x32_bf16 v[4:7], v[164:167], v[192:195], v[20:23]
	v_mfma_f32_16x16x32_bf16 v[164:167], v[168:171], v[196:199], v[4:7]
	s_setprio 0
	s_barrier
	s_nop 4
	ds_read_b128 v[4:7], v137
	ds_read_b128 v[60:63], v137 offset:1024
	ds_read_b128 v[168:171], v137 offset:2048
	ds_read_b128 v[192:195], v137 offset:3072
	ds_read_b128 v[196:199], v138
	ds_read_b128 v[208:211], v138 offset:1024
	ds_read_b128 v[212:215], v138 offset:2048
	ds_read_b128 v[216:219], v138 offset:3072
	s_add_u32 s34, s34, 0x10000
	s_addc_u32 s35, s35, 0
	s_mov_b32 m0, s90
	v_lshl_add_u64 v[32:33], s[34:35], 0, v[130:131]
	ds_read_b128 v[16:19], v136 offset:32768
	ds_read_b128 v[20:23], v136 offset:33792
	ds_read_b128 v[104:107], v136 offset:34816
	ds_read_b128 v[220:223], v136 offset:35840
	ds_read_b128 v[224:227], v136 offset:36864
	ds_read_b128 v[228:231], v136 offset:37888
	ds_read_b128 v[232:235], v136 offset:38912
	ds_read_b128 v[236:239], v136 offset:39936
	global_load_lds_dwordx4 v[32:33], off
	v_lshl_add_u64 v[32:33], s[34:35], 0, v[128:129]
	s_mov_b32 m0, s47
	s_nop 0
	global_load_lds_dwordx4 v[32:33], off
	s_waitcnt vmcnt(8)
	s_cmp_lt_u32 s3, 4
	s_cbranch_scc1 .Lgls_102
	s_waitcnt lgkmcnt(0)
.Lgls_102:
	s_barrier
	s_setprio 1
	s_waitcnt lgkmcnt(0)
	v_mfma_f32_16x16x32_bf16 v[32:35], v[4:7], v[16:19], v[64:67]
	v_mfma_f32_16x16x32_bf16 v[116:119], v[60:63], v[20:23], v[32:35]
	v_mfma_f32_16x16x32_bf16 v[32:35], v[168:171], v[16:19], v[68:71]
	v_mfma_f32_16x16x32_bf16 v[112:115], v[192:195], v[20:23], v[32:35]
	v_mfma_f32_16x16x32_bf16 v[32:35], v[4:7], v[104:107], v[72:75]
	v_mfma_f32_16x16x32_bf16 v[100:103], v[60:63], v[220:223], v[32:35]
	v_mfma_f32_16x16x32_bf16 v[32:35], v[168:171], v[104:107], v[76:79]
	v_mfma_f32_16x16x32_bf16 v[96:99], v[192:195], v[220:223], v[32:35]
	v_mfma_f32_16x16x32_bf16 v[32:35], v[4:7], v[224:227], v[80:83]
	v_mfma_f32_16x16x32_bf16 v[68:71], v[60:63], v[228:231], v[32:35]
	v_mfma_f32_16x16x32_bf16 v[32:35], v[168:171], v[224:227], v[84:87]
	v_mfma_f32_16x16x32_bf16 v[64:67], v[192:195], v[228:231], v[32:35]
	v_mfma_f32_16x16x32_bf16 v[32:35], v[4:7], v[232:235], v[88:91]
	v_mfma_f32_16x16x32_bf16 v[36:39], v[60:63], v[236:239], v[32:35]
	v_mfma_f32_16x16x32_bf16 v[32:35], v[168:171], v[232:235], v[92:95]
	v_mfma_f32_16x16x32_bf16 v[32:35], v[192:195], v[236:239], v[32:35]
	s_setprio 0
	s_setprio 1
	v_mfma_f32_16x16x32_bf16 v[72:75], v[196:199], v[16:19], v[204:207]
	v_mfma_f32_16x16x32_bf16 v[16:19], v[212:215], v[16:19], v[172:175]
	v_mfma_f32_16x16x32_bf16 v[120:123], v[216:219], v[20:23], v[16:19]
	v_mfma_f32_16x16x32_bf16 v[16:19], v[196:199], v[104:107], v[176:179]
	v_mfma_f32_16x16x32_bf16 v[108:111], v[208:211], v[220:223], v[16:19]
	v_mfma_f32_16x16x32_bf16 v[16:19], v[212:215], v[104:107], v[40:43]
	v_mfma_f32_16x16x32_bf16 v[104:107], v[216:219], v[220:223], v[16:19]
	v_mfma_f32_16x16x32_bf16 v[16:19], v[196:199], v[224:227], v[44:47]
	v_mfma_f32_16x16x32_bf16 v[80:83], v[208:211], v[228:231], v[16:19]
	v_mfma_f32_16x16x32_bf16 v[16:19], v[212:215], v[224:227], v[48:51]
	v_mfma_f32_16x16x32_bf16 v[124:127], v[208:211], v[20:23], v[72:75]
	v_mfma_f32_16x16x32_bf16 v[72:75], v[216:219], v[228:231], v[16:19]
	v_mfma_f32_16x16x32_bf16 v[16:19], v[196:199], v[232:235], v[52:55]
	v_mfma_f32_16x16x32_bf16 v[48:51], v[208:211], v[236:239], v[16:19]
	v_mfma_f32_16x16x32_bf16 v[16:19], v[212:215], v[232:235], v[56:59]
	v_mfma_f32_16x16x32_bf16 v[40:43], v[216:219], v[236:239], v[16:19]
	s_setprio 0
	s_barrier
	s_mov_b32 m0, s51
	s_nop 3
	v_lshl_add_u64 v[16:17], v[240:241], 0, s[20:21]
	s_add_u32 s30, s30, 0x10080
	ds_read_b128 v[56:59], v136 offset:49152
	ds_read_b128 v[88:91], v136 offset:50176
	ds_read_b128 v[172:175], v136 offset:51200
	ds_read_b128 v[176:179], v136 offset:52224
	ds_read_b128 v[204:207], v136 offset:53248
	ds_read_b128 v[220:223], v136 offset:54272
	ds_read_b128 v[224:227], v136 offset:55296
	ds_read_b128 v[228:231], v136 offset:56320
	global_load_lds_dwordx4 v[16:17], off
	v_lshl_add_u64 v[16:17], v[242:243], 0, s[20:21]
	s_mov_b32 m0, s52
	s_addc_u32 s31, s31, 0
	global_load_lds_dwordx4 v[16:17], off
	v_lshl_add_u64 v[16:17], s[30:31], 0, v[130:131]
	s_mov_b32 m0, s53
	s_nop 0
	global_load_lds_dwordx4 v[16:17], off
	v_lshl_add_u64 v[16:17], s[30:31], 0, v[128:129]
	s_mov_b32 m0, s54
	s_nop 0
	global_load_lds_dwordx4 v[16:17], off
	v_lshl_add_u64 v[16:17], v[244:245], 0, s[20:21]
	s_mov_b32 m0, s75
	s_nop 0
	global_load_lds_dwordx4 v[16:17], off
	v_lshl_add_u64 v[16:17], v[246:247], 0, s[20:21]
	s_mov_b32 m0, s67
	s_nop 0
	global_load_lds_dwordx4 v[16:17], off
	s_waitcnt vmcnt(8)
	s_cmp_lt_u32 s3, 4
	s_cbranch_scc1 .Lgls_103
	s_waitcnt lgkmcnt(0)

; #define PG8_STAGE(bufoff, gbase, voff) do { _Pragma("unroll") for (int _i = 0; _i < 2; ++_i) \
;         __builtin_amdgcn_global_load_lds((const unsigned*)((const char*)(gbase) + (voff)[_i]), (PG8_LAS unsigned*)(lds + (bufoff) + ldsw + _i * 8192), 16, 0, 0); } while (0)
; #define PG8_LDA(dst, b, h) do { _Pragma("unroll") for (int m = 0; m < 4; ++m) _Pragma("unroll") for (int k = 0; k < 2; ++k) dst[m][k] = *(const PG8_LAS bf16x8*)(lds + PG8_SA(b, h) + aoff + m * 2048 + k * 1024); } while (0)
; #define PG8_LDB(dst, b, h) do { _Pragma("unroll") for (int n = 0; n < 2; ++n) _Pragma("unroll") for (int k = 0; k < 2; ++k) dst[n][k] = *(const PG8_LAS bf16x8*)(lds + PG8_SB(b, h) + boff + n * 2048 + k * 1024); } while (0)
; #define PG8_MMA(ai, bj, At, Bt) do { __builtin_amdgcn_s_setprio(1); _Pragma("unroll") for (int m = 0; m < 4; ++m) _Pragma("unroll") for (int n = 0; n < 2; ++n) _Pragma("unroll") for (int k = 0; k < 2; ++k) \
;         acc[ai][bj][m][n] = mma16<F16>(Bt[n][k], At[m][k], acc[ai][bj][m][n]); __builtin_amdgcn_s_setprio(0); } while (0)
; #define PG8_WAIT_V(n) asm volatile("s_waitcnt vmcnt(" #n ")" ::: "memory")
; #define PG8_WAIT_L(n) asm volatile("s_waitcnt lgkmcnt(" #n ")" ::: "memory")
; #define PG8_BAR __builtin_amdgcn_s_barrier()
; #define PG8_SCHED __builtin_amdgcn_sched_barrier(0)
; template <class Epi, class Sched, bool ALIGN_EPI = false, bool SP2 = false, bool F16 = false>
; __device__ __forceinline__ void gemm_phase(PG8_LAS unsigned char* lds, const Gemm g, const Sched& S, const Epi& E, const int wid_in) {
;     ...
;         for (int t = 0; t < nt; t += 2) {
;             const bool last = (t == nt - 2);
;             const char* a1 = cA + (size_t)(t + 1) * kstep;
;             const char* a2 = last ? nA : cA + (size_t)(t + 2) * kstep; const char* b2 = last ? nB : cB + (size_t)(t + 2) * kstep;
;             const char* a3 = a2 + kstep; const char* b3 = b2 + kstep;
;             if (last && has_next) S.a_ready(nxt);
;             if constexpr (SP2) {
;             PG8_LDB(B0, 0, 0); PG8_LDB(B1, 0, 1); PG8_SCHED; PG8_LDA(At, 0, 0); PG8_STAGE(PG8_SA(1, 1), a1 + hstep, voffA);
;             PG8_WAIT_V(8); PG8_WAIT_L(0); PG8_BAR; PG8_MMA(0, 0, At, B0); PG8_MMA(0, 1, At, B1); PG8_BAR; PG8_SCHED;
;             PG8_LDA(At, 0, 1); PG8_STAGE(PG8_SB(0, 0), b2, voffB); PG8_STAGE(PG8_SB(0, 1), b2 + hstep, voffB); PG8_STAGE(PG8_SA(0, 0), a2, voffA);
.LBB0_2697:
	ds_read_b128 v[128:131], v189
	ds_read_b128 v[132:135], v189 offset:1024
	ds_read_b128 v[136:139], v189 offset:2048
	ds_read_b128 v[140:143], v189 offset:3072
	ds_read_b128 v[144:147], v190
	ds_read_b128 v[148:151], v190 offset:1024
	ds_read_b128 v[168:171], v190 offset:2048
	ds_read_b128 v[172:175], v190 offset:3072
	s_add_u32 s30, s28, 0x100
	s_addc_u32 s31, s29, 0
	s_cmp_eq_u32 s55, 40
	s_cselect_b32 s37, s11, s31
	s_cselect_b32 s36, s10, s30
	s_cselect_b32 s35, s27, s54
	s_cselect_b32 s34, s26, s53
	s_mov_b32 m0, s91
	v_lshl_add_u64 v[184:185], s[28:29], 0, v[160:161]
	ds_read_b128 v[176:179], v191
	ds_read_b128 v[180:183], v191 offset:1024
	ds_read_b128 v[192:195], v191 offset:2048
	ds_read_b128 v[196:199], v191 offset:3072
	ds_read_b128 v[200:203], v191 offset:4096
	ds_read_b128 v[204:207], v191 offset:5120
	ds_read_b128 v[208:211], v191 offset:6144
	ds_read_b128 v[212:215], v191 offset:7168
	global_load_lds_dwordx4 v[184:185], off
	v_lshl_add_u64 v[184:185], s[28:29], 0, v[162:163]
	s_add_i32 m0, s74, 0xe000
	s_nop 0
	global_load_lds_dwordx4 v[184:185], off
	s_waitcnt vmcnt(8)
	s_cmp_lt_u32 s3, 4
	s_cbranch_scc1 .Lgls_104
	s_waitcnt lgkmcnt(0)
.Lgls_104:
	s_barrier
	s_setprio 1
	s_waitcnt lgkmcnt(0)
	v_mfma_f32_16x16x32_bf16 v[124:127], v[128:131], v[176:179], v[124:127]
	v_mfma_f32_16x16x32_bf16 v[120:123], v[136:139], v[176:179], v[120:123]
	v_mfma_f32_16x16x32_bf16 v[108:111], v[128:131], v[192:195], v[108:111]
	v_mfma_f32_16x16x32_bf16 v[104:107], v[136:139], v[192:195], v[104:107]
	v_mfma_f32_16x16x32_bf16 v[92:95], v[128:131], v[200:203], v[92:95]
	v_mfma_f32_16x16x32_bf16 v[88:91], v[136:139], v[200:203], v[88:91]
	v_mfma_f32_16x16x32_bf16 v[76:79], v[128:131], v[208:211], v[76:79]
	v_mfma_f32_16x16x32_bf16 v[72:75], v[136:139], v[208:211], v[72:75]
	v_mfma_f32_16x16x32_bf16 v[124:127], v[132:135], v[180:183], v[124:127]
	v_mfma_f32_16x16x32_bf16 v[120:123], v[140:143], v[180:183], v[120:123]
	v_mfma_f32_16x16x32_bf16 v[108:111], v[132:135], v[196:199], v[108:111]
	v_mfma_f32_16x16x32_bf16 v[104:107], v[140:143], v[196:199], v[104:107]
	v_mfma_f32_16x16x32_bf16 v[92:95], v[132:135], v[204:207], v[92:95]
	v_mfma_f32_16x16x32_bf16 v[88:91], v[140:143], v[204:207], v[88:91]
	v_mfma_f32_16x16x32_bf16 v[76:79], v[132:135], v[212:215], v[76:79]
	v_mfma_f32_16x16x32_bf16 v[72:75], v[140:143], v[212:215], v[72:75]
	s_setprio 0
	s_setprio 1
	v_mfma_f32_16x16x32_bf16 v[116:119], v[144:147], v[176:179], v[116:119]
	v_mfma_f32_16x16x32_bf16 v[112:115], v[168:171], v[176:179], v[112:115]
	v_mfma_f32_16x16x32_bf16 v[100:103], v[144:147], v[192:195], v[100:103]
	v_mfma_f32_16x16x32_bf16 v[96:99], v[168:171], v[192:195], v[96:99]
	v_mfma_f32_16x16x32_bf16 v[84:87], v[144:147], v[200:203], v[84:87]
	v_mfma_f32_16x16x32_bf16 v[80:83], v[168:171], v[200:203], v[80:83]
	v_mfma_f32_16x16x32_bf16 v[68:71], v[144:147], v[208:211], v[68:71]
	v_mfma_f32_16x16x32_bf16 v[64:67], v[168:171], v[208:211], v[64:67]
	v_mfma_f32_16x16x32_bf16 v[116:119], v[148:151], v[180:183], v[116:119]
	v_mfma_f32_16x16x32_bf16 v[112:115], v[172:175], v[180:183], v[112:115]
	v_mfma_f32_16x16x32_bf16 v[100:103], v[148:151], v[196:199], v[100:103]
	v_mfma_f32_16x16x32_bf16 v[96:99], v[172:175], v[196:199], v[96:99]
	v_mfma_f32_16x16x32_bf16 v[84:87], v[148:151], v[204:207], v[84:87]
	v_mfma_f32_16x16x32_bf16 v[80:83], v[172:175], v[204:207], v[80:83]
	v_mfma_f32_16x16x32_bf16 v[68:71], v[148:151], v[212:215], v[68:71]
	v_mfma_f32_16x16x32_bf16 v[64:67], v[172:175], v[212:215], v[64:67]
	s_setprio 0
	s_barrier
	s_add_i32 s28, s47, s68
	v_lshl_add_u64 v[184:185], s[34:35], 0, v[154:155]
	s_mov_b32 m0, s28
	ds_read_b128 v[176:179], v191 offset:16384
	ds_read_b128 v[180:183], v191 offset:17408
	ds_read_b128 v[192:195], v191 offset:18432
	ds_read_b128 v[196:199], v191 offset:19456
	ds_read_b128 v[200:203], v191 offset:20480
	ds_read_b128 v[204:207], v191 offset:21504
	ds_read_b128 v[208:211], v191 offset:22528
	ds_read_b128 v[212:215], v191 offset:23552
	global_load_lds_dwordx4 v[184:185], off
	s_add_i32 m0, s28, 0x2000
	s_add_u32 s28, s34, 0xb0000
	v_lshl_add_u64 v[216:217], s[34:35], 0, v[158:159]
	s_addc_u32 s29, s35, 0
	s_add_i32 s56, s48, s68
	global_load_lds_dwordx4 v[216:217], off
	v_lshl_add_u64 v[218:219], s[28:29], 0, v[154:155]
	s_mov_b32 m0, s56
	v_lshl_add_u64 v[220:221], s[36:37], 0, v[156:157]
	global_load_lds_dwordx4 v[218:219], off
	v_lshl_add_u64 v[218:219], s[28:29], 0, v[158:159]
	s_add_i32 m0, s56, 0x2000
	s_nop 0
	global_load_lds_dwordx4 v[218:219], off
	v_lshl_add_u64 v[218:219], s[36:37], 0, v[152:153]
	s_mov_b32 m0, s74
	s_nop 0
	global_load_lds_dwordx4 v[218:219], off
	s_mov_b32 m0, s66
	s_nop 0
	global_load_lds_dwordx4 v[220:221], off
	s_waitcnt vmcnt(8)
	s_cmp_lt_u32 s3, 4
	s_cbranch_scc1 .Lgls_105
	s_waitcnt lgkmcnt(0)
; #define PG8_STAGE(bufoff, gbase, voff) do { _Pragma("unroll") for (int _i = 0; _i < 2; ++_i) \
;         __builtin_amdgcn_global_load_lds((const unsigned*)((const char*)(gbase) + (voff)[_i]), (PG8_LAS unsigned*)(lds + (bufoff) + ldsw + _i * 8192), 16, 0, 0); } while (0)
; #define PG8_LDA(dst, b, h) do { _Pragma("unroll") for (int m = 0; m < 4; ++m) _Pragma("unroll") for (int k = 0; k < 2; ++k) dst[m][k] = *(const PG8_LAS bf16x8*)(lds + PG8_SA(b, h) + aoff + m * 2048 + k * 1024); } while (0)
; #define PG8_LDB(dst, b, h) do { _Pragma("unroll") for (int n = 0; n < 2; ++n) _Pragma("unroll") for (int k = 0; k < 2; ++k) dst[n][k] = *(const PG8_LAS bf16x8*)(lds + PG8_SB(b, h) + boff + n * 2048 + k * 1024); } while (0)
; #define PG8_MMA(ai, bj, At, Bt) do { __builtin_amdgcn_s_setprio(1); _Pragma("unroll") for (int m = 0; m < 4; ++m) _Pragma("unroll") for (int n = 0; n < 2; ++n) _Pragma("unroll") for (int k = 0; k < 2; ++k) \
;         acc[ai][bj][m][n] = mma16<F16>(Bt[n][k], At[m][k], acc[ai][bj][m][n]); __builtin_amdgcn_s_setprio(0); } while (0)
; #define PG8_WAIT_V(n) asm volatile("s_waitcnt vmcnt(" #n ")" ::: "memory")
; #define PG8_WAIT_L(n) asm volatile("s_waitcnt lgkmcnt(" #n ")" ::: "memory")
; #define PG8_BAR __builtin_amdgcn_s_barrier()
; #define PG8_SCHED __builtin_amdgcn_sched_barrier(0)
; template <class Epi, class Sched, bool ALIGN_EPI = false, bool SP2 = false, bool F16 = false>
; __device__ __forceinline__ void gemm_phase(PG8_LAS unsigned char* lds, const Gemm g, const Sched& S, const Epi& E, const int wid_in) {
;     ...
;             PG8_WAIT_V(8); PG8_WAIT_L(0); PG8_BAR; PG8_MMA(1, 0, At, B0); PG8_MMA(1, 1, At, B1); PG8_BAR; PG8_SCHED;
;             PG8_LDB(B0, 1, 0); PG8_LDB(B1, 1, 1); PG8_SCHED; PG8_LDA(At, 1, 0); PG8_STAGE(PG8_SA(0, 1), a2 + hstep, voffA);
;             PG8_WAIT_V(8); PG8_WAIT_L(0); PG8_BAR; PG8_MMA(0, 0, At, B0); PG8_MMA(0, 1, At, B1); PG8_BAR; PG8_SCHED;
.Lgls_105:
	s_barrier
	s_setprio 1
	s_waitcnt lgkmcnt(0)
	v_mfma_f32_16x16x32_bf16 v[60:63], v[128:131], v[176:179], v[60:63]
	v_mfma_f32_16x16x32_bf16 v[56:59], v[136:139], v[176:179], v[56:59]
	v_mfma_f32_16x16x32_bf16 v[44:47], v[128:131], v[192:195], v[44:47]
	v_mfma_f32_16x16x32_bf16 v[40:43], v[136:139], v[192:195], v[40:43]
	v_mfma_f32_16x16x32_bf16 v[28:31], v[128:131], v[200:203], v[28:31]
	v_mfma_f32_16x16x32_bf16 v[24:27], v[136:139], v[200:203], v[24:27]
	v_mfma_f32_16x16x32_bf16 v[12:15], v[128:131], v[208:211], v[12:15]
	v_mfma_f32_16x16x32_bf16 v[8:11], v[136:139], v[208:211], v[8:11]
	v_mfma_f32_16x16x32_bf16 v[60:63], v[132:135], v[180:183], v[60:63]
	v_mfma_f32_16x16x32_bf16 v[56:59], v[140:143], v[180:183], v[56:59]
	v_mfma_f32_16x16x32_bf16 v[44:47], v[132:135], v[196:199], v[44:47]
	v_mfma_f32_16x16x32_bf16 v[40:43], v[140:143], v[196:199], v[40:43]
	v_mfma_f32_16x16x32_bf16 v[28:31], v[132:135], v[204:207], v[28:31]
	v_mfma_f32_16x16x32_bf16 v[24:27], v[140:143], v[204:207], v[24:27]
	v_mfma_f32_16x16x32_bf16 v[12:15], v[132:135], v[212:215], v[12:15]
	v_mfma_f32_16x16x32_bf16 v[8:11], v[140:143], v[212:215], v[8:11]
	s_setprio 0
	s_setprio 1
	v_mfma_f32_16x16x32_bf16 v[52:55], v[144:147], v[176:179], v[52:55]
	v_mfma_f32_16x16x32_bf16 v[48:51], v[168:171], v[176:179], v[48:51]
	v_mfma_f32_16x16x32_bf16 v[36:39], v[144:147], v[192:195], v[36:39]
	v_mfma_f32_16x16x32_bf16 v[32:35], v[168:171], v[192:195], v[32:35]
	v_mfma_f32_16x16x32_bf16 v[20:23], v[144:147], v[200:203], v[20:23]
	v_mfma_f32_16x16x32_bf16 v[16:19], v[168:171], v[200:203], v[16:19]
	v_mfma_f32_16x16x32_bf16 v[4:7], v[144:147], v[208:211], v[4:7]
	v_mfma_f32_16x16x32_bf16 v[0:3], v[168:171], v[208:211], v[0:3]
	v_mfma_f32_16x16x32_bf16 v[52:55], v[148:151], v[180:183], v[52:55]
	v_mfma_f32_16x16x32_bf16 v[48:51], v[172:175], v[180:183], v[48:51]
	v_mfma_f32_16x16x32_bf16 v[36:39], v[148:151], v[196:199], v[36:39]
	v_mfma_f32_16x16x32_bf16 v[32:35], v[172:175], v[196:199], v[32:35]
	v_mfma_f32_16x16x32_bf16 v[20:23], v[148:151], v[204:207], v[20:23]
	v_mfma_f32_16x16x32_bf16 v[16:19], v[172:175], v[204:207], v[16:19]
	v_mfma_f32_16x16x32_bf16 v[4:7], v[148:151], v[212:215], v[4:7]
	v_mfma_f32_16x16x32_bf16 v[0:3], v[172:175], v[212:215], v[0:3]
	s_setprio 0
	s_barrier
	s_add_i32 s56, 0, 0x18000
	s_add_i32 s57, 0, 0x1c000
	v_add_u32_e32 v140, s56, v188
	v_add_u32_e32 v172, s57, v188
	ds_read_b128 v[128:131], v140
	ds_read_b128 v[132:135], v140 offset:1024
	ds_read_b128 v[136:139], v140 offset:2048
	ds_read_b128 v[140:143], v140 offset:3072
	ds_read_b128 v[144:147], v172
	ds_read_b128 v[148:151], v172 offset:1024
	ds_read_b128 v[168:171], v172 offset:2048
	ds_read_b128 v[172:175], v172 offset:3072
	s_add_u32 s28, s36, 0xb0000
	s_addc_u32 s29, s37, 0
	s_mov_b32 m0, s90
	v_lshl_add_u64 v[222:223], s[28:29], 0, v[152:153]
	ds_read_b128 v[176:179], v191 offset:32768
	ds_read_b128 v[180:183], v191 offset:33792
	ds_read_b128 v[192:195], v191 offset:34816
	ds_read_b128 v[196:199], v191 offset:35840
	ds_read_b128 v[200:203], v191 offset:36864
	ds_read_b128 v[204:207], v191 offset:37888
	ds_read_b128 v[208:211], v191 offset:38912
	ds_read_b128 v[212:215], v191 offset:39936
	global_load_lds_dwordx4 v[222:223], off
	v_lshl_add_u64 v[222:223], s[28:29], 0, v[156:157]
	s_mov_b32 m0, s43
	s_nop 0
	global_load_lds_dwordx4 v[222:223], off
	s_waitcnt vmcnt(8)
	s_cmp_lt_u32 s3, 4
	s_cbranch_scc1 .Lgls_106
	s_waitcnt lgkmcnt(0)
; #define PG8_STAGE(bufoff, gbase, voff) do { _Pragma("unroll") for (int _i = 0; _i < 2; ++_i) \
;         __builtin_amdgcn_global_load_lds((const unsigned*)((const char*)(gbase) + (voff)[_i]), (PG8_LAS unsigned*)(lds + (bufoff) + ldsw + _i * 8192), 16, 0, 0); } while (0)
; #define PG8_LDA(dst, b, h) do { _Pragma("unroll") for (int m = 0; m < 4; ++m) _Pragma("unroll") for (int k = 0; k < 2; ++k) dst[m][k] = *(const PG8_LAS bf16x8*)(lds + PG8_SA(b, h) + aoff + m * 2048 + k * 1024); } while (0)
; #define PG8_MMA(ai, bj, At, Bt) do { __builtin_amdgcn_s_setprio(1); _Pragma("unroll") for (int m = 0; m < 4; ++m) _Pragma("unroll") for (int n = 0; n < 2; ++n) _Pragma("unroll") for (int k = 0; k < 2; ++k) \
;         acc[ai][bj][m][n] = mma16<F16>(Bt[n][k], At[m][k], acc[ai][bj][m][n]); __builtin_amdgcn_s_setprio(0); } while (0)
; #define PG8_WAIT_V(n) asm volatile("s_waitcnt vmcnt(" #n ")" ::: "memory")
; #define PG8_WAIT_L(n) asm volatile("s_waitcnt lgkmcnt(" #n ")" ::: "memory")
; #define PG8_BAR __builtin_amdgcn_s_barrier()
; #define PG8_SCHED __builtin_amdgcn_sched_barrier(0)
; template <class Epi, class Sched, bool ALIGN_EPI = false, bool SP2 = false, bool F16 = false>
; __device__ __forceinline__ void gemm_phase(PG8_LAS unsigned char* lds, const Gemm g, const Sched& S, const Epi& E, const int wid_in) {
;     ...
;             PG8_WAIT_V(8); PG8_WAIT_L(0); PG8_BAR; PG8_MMA(0, 0, At, B0); PG8_MMA(0, 1, At, B1); PG8_BAR; PG8_SCHED;
;             PG8_LDA(At, 1, 1); PG8_STAGE(PG8_SB(1, 0), b3, voffB); PG8_STAGE(PG8_SB(1, 1), b3 + hstep, voffB); PG8_STAGE(PG8_SA(1, 0), a3, voffA);
;             PG8_WAIT_V(8); PG8_WAIT_L(0); PG8_BAR; PG8_MMA(1, 0, At, B0); PG8_MMA(1, 1, At, B1); PG8_BAR; PG8_SCHED;
;     ...
;         if constexpr (ALIGN_EPI) { if (wr == 0) PG8_BAR; }
.Lgls_106:
	s_barrier
	s_setprio 1
	s_waitcnt lgkmcnt(0)
	v_mfma_f32_16x16x32_bf16 v[124:127], v[128:131], v[176:179], v[124:127]
	v_mfma_f32_16x16x32_bf16 v[120:123], v[136:139], v[176:179], v[120:123]
	v_mfma_f32_16x16x32_bf16 v[108:111], v[128:131], v[192:195], v[108:111]
	v_mfma_f32_16x16x32_bf16 v[104:107], v[136:139], v[192:195], v[104:107]
	v_mfma_f32_16x16x32_bf16 v[92:95], v[128:131], v[200:203], v[92:95]
	v_mfma_f32_16x16x32_bf16 v[88:91], v[136:139], v[200:203], v[88:91]
	v_mfma_f32_16x16x32_bf16 v[76:79], v[128:131], v[208:211], v[76:79]
	v_mfma_f32_16x16x32_bf16 v[72:75], v[136:139], v[208:211], v[72:75]
	v_mfma_f32_16x16x32_bf16 v[124:127], v[132:135], v[180:183], v[124:127]
	v_mfma_f32_16x16x32_bf16 v[120:123], v[140:143], v[180:183], v[120:123]
	v_mfma_f32_16x16x32_bf16 v[108:111], v[132:135], v[196:199], v[108:111]
	v_mfma_f32_16x16x32_bf16 v[104:107], v[140:143], v[196:199], v[104:107]
	v_mfma_f32_16x16x32_bf16 v[92:95], v[132:135], v[204:207], v[92:95]
	v_mfma_f32_16x16x32_bf16 v[88:91], v[140:143], v[204:207], v[88:91]
	v_mfma_f32_16x16x32_bf16 v[76:79], v[132:135], v[212:215], v[76:79]
	v_mfma_f32_16x16x32_bf16 v[72:75], v[140:143], v[212:215], v[72:75]
	s_setprio 0
	s_setprio 1
	v_mfma_f32_16x16x32_bf16 v[116:119], v[144:147], v[176:179], v[116:119]
	v_mfma_f32_16x16x32_bf16 v[112:115], v[168:171], v[176:179], v[112:115]
	v_mfma_f32_16x16x32_bf16 v[100:103], v[144:147], v[192:195], v[100:103]
	v_mfma_f32_16x16x32_bf16 v[96:99], v[168:171], v[192:195], v[96:99]
	v_mfma_f32_16x16x32_bf16 v[84:87], v[144:147], v[200:203], v[84:87]
	v_mfma_f32_16x16x32_bf16 v[80:83], v[168:171], v[200:203], v[80:83]
	v_mfma_f32_16x16x32_bf16 v[68:71], v[144:147], v[208:211], v[68:71]
	v_mfma_f32_16x16x32_bf16 v[64:67], v[168:171], v[208:211], v[64:67]
	v_mfma_f32_16x16x32_bf16 v[116:119], v[148:151], v[180:183], v[116:119]
	v_mfma_f32_16x16x32_bf16 v[112:115], v[172:175], v[180:183], v[112:115]
	v_mfma_f32_16x16x32_bf16 v[100:103], v[148:151], v[196:199], v[100:103]
	v_mfma_f32_16x16x32_bf16 v[96:99], v[172:175], v[196:199], v[96:99]
	v_mfma_f32_16x16x32_bf16 v[84:87], v[148:151], v[204:207], v[84:87]
	v_mfma_f32_16x16x32_bf16 v[80:83], v[172:175], v[204:207], v[80:83]
	v_mfma_f32_16x16x32_bf16 v[68:71], v[148:151], v[212:215], v[68:71]
	v_mfma_f32_16x16x32_bf16 v[64:67], v[172:175], v[212:215], v[64:67]
	s_setprio 0
	s_barrier
	s_add_i32 s28, s56, s68
	v_lshl_add_u64 v[184:185], v[184:185], 0, s[24:25]
	s_mov_b32 m0, s28
	ds_read_b128 v[176:179], v191 offset:49152
	ds_read_b128 v[180:183], v191 offset:50176
	ds_read_b128 v[192:195], v191 offset:51200
	ds_read_b128 v[196:199], v191 offset:52224
	ds_read_b128 v[200:203], v191 offset:53248
	ds_read_b128 v[204:207], v191 offset:54272
	ds_read_b128 v[208:211], v191 offset:55296
	ds_read_b128 v[212:215], v191 offset:56320
	global_load_lds_dwordx4 v[184:185], off
	s_add_i32 m0, s28, 0x2000
	s_add_u32 s28, s34, 0xb0080
	v_lshl_add_u64 v[184:185], v[216:217], 0, s[24:25]
	s_addc_u32 s29, s35, 0
	s_add_i32 s34, s57, s68
	global_load_lds_dwordx4 v[184:185], off
	v_lshl_add_u64 v[184:185], s[28:29], 0, v[154:155]
	s_mov_b32 m0, s34
	s_nop 0
	global_load_lds_dwordx4 v[184:185], off
	v_lshl_add_u64 v[184:185], s[28:29], 0, v[158:159]
	s_add_i32 m0, s34, 0x2000
	s_nop 0
	global_load_lds_dwordx4 v[184:185], off
	v_lshl_add_u64 v[184:185], v[218:219], 0, s[24:25]
	s_mov_b32 m0, s75
	s_nop 0
	global_load_lds_dwordx4 v[184:185], off
	v_lshl_add_u64 v[184:185], v[220:221], 0, s[24:25]
	s_mov_b32 m0, s67
	s_nop 0
	global_load_lds_dwordx4 v[184:185], off
	s_waitcnt vmcnt(8)
	s_cmp_lt_u32 s3, 4
	s_cbranch_scc1 .Lgls_107
	s_waitcnt lgkmcnt(0)
.Lgls_107:
	s_barrier
	s_setprio 1
	s_waitcnt lgkmcnt(0)
	v_mfma_f32_16x16x32_bf16 v[60:63], v[128:131], v[176:179], v[60:63]
	v_mfma_f32_16x16x32_bf16 v[56:59], v[136:139], v[176:179], v[56:59]
	v_mfma_f32_16x16x32_bf16 v[44:47], v[128:131], v[192:195], v[44:47]
	v_mfma_f32_16x16x32_bf16 v[40:43], v[136:139], v[192:195], v[40:43]
	v_mfma_f32_16x16x32_bf16 v[28:31], v[128:131], v[200:203], v[28:31]
	v_mfma_f32_16x16x32_bf16 v[24:27], v[136:139], v[200:203], v[24:27]
	v_mfma_f32_16x16x32_bf16 v[12:15], v[128:131], v[208:211], v[12:15]
	v_mfma_f32_16x16x32_bf16 v[8:11], v[136:139], v[208:211], v[8:11]
	v_mfma_f32_16x16x32_bf16 v[60:63], v[132:135], v[180:183], v[60:63]
	v_mfma_f32_16x16x32_bf16 v[56:59], v[140:143], v[180:183], v[56:59]
	v_mfma_f32_16x16x32_bf16 v[44:47], v[132:135], v[196:199], v[44:47]
	v_mfma_f32_16x16x32_bf16 v[40:43], v[140:143], v[196:199], v[40:43]
	v_mfma_f32_16x16x32_bf16 v[28:31], v[132:135], v[204:207], v[28:31]
	v_mfma_f32_16x16x32_bf16 v[24:27], v[140:143], v[204:207], v[24:27]
	v_mfma_f32_16x16x32_bf16 v[12:15], v[132:135], v[212:215], v[12:15]
	v_mfma_f32_16x16x32_bf16 v[8:11], v[140:143], v[212:215], v[8:11]
	s_setprio 0
	s_setprio 1
	v_mfma_f32_16x16x32_bf16 v[52:55], v[144:147], v[176:179], v[52:55]
	v_mfma_f32_16x16x32_bf16 v[48:51], v[168:171], v[176:179], v[48:51]
	v_mfma_f32_16x16x32_bf16 v[36:39], v[144:147], v[192:195], v[36:39]
	v_mfma_f32_16x16x32_bf16 v[32:35], v[168:171], v[192:195], v[32:35]
	v_mfma_f32_16x16x32_bf16 v[20:23], v[144:147], v[200:203], v[20:23]
	v_mfma_f32_16x16x32_bf16 v[16:19], v[168:171], v[200:203], v[16:19]
	v_mfma_f32_16x16x32_bf16 v[4:7], v[144:147], v[208:211], v[4:7]
	v_mfma_f32_16x16x32_bf16 v[0:3], v[168:171], v[208:211], v[0:3]
	v_mfma_f32_16x16x32_bf16 v[52:55], v[148:151], v[180:183], v[52:55]
	v_mfma_f32_16x16x32_bf16 v[48:51], v[172:175], v[180:183], v[48:51]
	v_mfma_f32_16x16x32_bf16 v[36:39], v[148:151], v[196:199], v[36:39]
	v_mfma_f32_16x16x32_bf16 v[32:35], v[172:175], v[196:199], v[32:35]
	v_mfma_f32_16x16x32_bf16 v[20:23], v[148:151], v[204:207], v[20:23]
	v_mfma_f32_16x16x32_bf16 v[16:19], v[172:175], v[204:207], v[16:19]
	v_mfma_f32_16x16x32_bf16 v[4:7], v[148:151], v[212:215], v[4:7]
	v_mfma_f32_16x16x32_bf16 v[0:3], v[172:175], v[212:215], v[0:3]
	s_setprio 0
	s_barrier
	s_add_i32 s55, s55, 2
	s_add_u32 s53, s53, 0x100
	s_addc_u32 s54, s54, 0
	s_cmp_gt_u32 s55, 41
	s_mov_b64 s[28:29], s[30:31]
	s_cbranch_scc0 .LBB0_2697
	s_and_b64 vcc, exec, s[16:17]
	s_cbranch_vccz .LBB0_2700
	s_barrier

; #define PG8_STAGE(bufoff, gbase, voff) do { _Pragma("unroll") for (int _i = 0; _i < 2; ++_i) \
;         __builtin_amdgcn_global_load_lds((const unsigned*)((const char*)(gbase) + (voff)[_i]), (PG8_LAS unsigned*)(lds + (bufoff) + ldsw + _i * 8192), 16, 0, 0); } while (0)
; #define PG8_LDA(dst, b, h) do { _Pragma("unroll") for (int m = 0; m < 4; ++m) _Pragma("unroll") for (int k = 0; k < 2; ++k) dst[m][k] = *(const PG8_LAS bf16x8*)(lds + PG8_SA(b, h) + aoff + m * 2048 + k * 1024); } while (0)
; #define PG8_LDB(dst, b, h) do { _Pragma("unroll") for (int n = 0; n < 2; ++n) _Pragma("unroll") for (int k = 0; k < 2; ++k) dst[n][k] = *(const PG8_LAS bf16x8*)(lds + PG8_SB(b, h) + boff + n * 2048 + k * 1024); } while (0)
; #define PG8_MMA(ai, bj, At, Bt) do { __builtin_amdgcn_s_setprio(1); _Pragma("unroll") for (int m = 0; m < 4; ++m) _Pragma("unroll") for (int n = 0; n < 2; ++n) _Pragma("unroll") for (int k = 0; k < 2; ++k) \
;         acc[ai][bj][m][n] = mma16<F16>(Bt[n][k], At[m][k], acc[ai][bj][m][n]); __builtin_amdgcn_s_setprio(0); } while (0)
; #define PG8_WAIT_V(n) asm volatile("s_waitcnt vmcnt(" #n ")" ::: "memory")
; #define PG8_WAIT_L(n) asm volatile("s_waitcnt lgkmcnt(" #n ")" ::: "memory")
; #define PG8_BAR __builtin_amdgcn_s_barrier()
; #define PG8_SCHED __builtin_amdgcn_sched_barrier(0)
; template <class Epi, class Sched, bool ALIGN_EPI = false, bool SP2 = false, bool F16 = false>
; __device__ __forceinline__ void gemm_phase(PG8_LAS unsigned char* lds, const Gemm g, const Sched& S, const Epi& E, const int wid_in) {
;     ...
;         for (int t = 0; t < nt; t += 2) {
;             const bool last = (t == nt - 2);
;             const char* a1 = cA + (size_t)(t + 1) * kstep;
;             const char* a2 = last ? nA : cA + (size_t)(t + 2) * kstep; const char* b2 = last ? nB : cB + (size_t)(t + 2) * kstep;
;             const char* a3 = a2 + kstep; const char* b3 = b2 + kstep;
;             if (last && has_next) S.a_ready(nxt);
;             if constexpr (SP2) {
;             PG8_LDB(B0, 0, 0); PG8_LDB(B1, 0, 1); PG8_SCHED; PG8_LDA(At, 0, 0); PG8_STAGE(PG8_SA(1, 1), a1 + hstep, voffA);
;             PG8_WAIT_V(8); PG8_WAIT_L(0); PG8_BAR; PG8_MMA(0, 0, At, B0); PG8_MMA(0, 1, At, B1); PG8_BAR; PG8_SCHED;
;             PG8_LDA(At, 0, 1); PG8_STAGE(PG8_SB(0, 0), b2, voffB); PG8_STAGE(PG8_SB(0, 1), b2 + hstep, voffB); PG8_STAGE(PG8_SA(0, 0), a2, voffA);
.LBB0_2793:
	ds_read_b128 v[112:115], v235
	ds_read_b128 v[116:119], v235 offset:1024
	ds_read_b128 v[128:131], v235 offset:2048
	ds_read_b128 v[132:135], v235 offset:3072
	ds_read_b128 v[144:147], v236
	ds_read_b128 v[148:151], v236 offset:1024
	ds_read_b128 v[152:155], v236 offset:2048
	ds_read_b128 v[156:159], v236 offset:3072
	s_add_u32 s44, s42, 0xfffc0080
	s_addc_u32 s45, s43, -1
	s_cmp_eq_u32 s59, 12
	s_cselect_b32 s47, s14, s45
	s_cselect_b32 s46, s15, s44
	s_cselect_b32 s45, s29, s58
	s_cselect_b32 s44, s31, s41
	s_mov_b32 m0, s91
	v_lshl_add_u64 v[192:193], s[42:43], 0, v[204:205]
	ds_read_b128 v[160:163], v237
	ds_read_b128 v[164:167], v237 offset:1024
	ds_read_b128 v[168:171], v237 offset:2048
	ds_read_b128 v[172:175], v237 offset:3072
	ds_read_b128 v[176:179], v237 offset:4096
	ds_read_b128 v[180:183], v237 offset:5120
	ds_read_b128 v[184:187], v237 offset:6144
	ds_read_b128 v[188:191], v237 offset:7168
	global_load_lds_dwordx4 v[192:193], off
	v_lshl_add_u64 v[192:193], s[42:43], 0, v[206:207]
	s_add_i32 m0, s74, 0xe000
	s_nop 0
	global_load_lds_dwordx4 v[192:193], off
	s_waitcnt vmcnt(8)
	s_cmp_lt_u32 s3, 4
	s_cbranch_scc1 .Lgls_108
	s_waitcnt lgkmcnt(0)
.Lgls_108:
	s_barrier
	s_setprio 1
	s_waitcnt lgkmcnt(0)
	v_mfma_f32_16x16x32_f16 v[140:143], v[112:115], v[160:163], v[140:143]
	v_mfma_f32_16x16x32_f16 v[136:139], v[128:131], v[160:163], v[136:139]
	v_mfma_f32_16x16x32_f16 v[108:111], v[112:115], v[168:171], v[108:111]
	v_mfma_f32_16x16x32_f16 v[104:107], v[128:131], v[168:171], v[104:107]
	v_mfma_f32_16x16x32_f16 v[92:95], v[112:115], v[176:179], v[92:95]
	v_mfma_f32_16x16x32_f16 v[88:91], v[128:131], v[176:179], v[88:91]
	v_mfma_f32_16x16x32_f16 v[76:79], v[112:115], v[184:187], v[76:79]
	v_mfma_f32_16x16x32_f16 v[72:75], v[128:131], v[184:187], v[72:75]
	v_mfma_f32_16x16x32_f16 v[140:143], v[116:119], v[164:167], v[140:143]
	v_mfma_f32_16x16x32_f16 v[136:139], v[132:135], v[164:167], v[136:139]
	v_mfma_f32_16x16x32_f16 v[108:111], v[116:119], v[172:175], v[108:111]
	v_mfma_f32_16x16x32_f16 v[104:107], v[132:135], v[172:175], v[104:107]
	v_mfma_f32_16x16x32_f16 v[92:95], v[116:119], v[180:183], v[92:95]
	v_mfma_f32_16x16x32_f16 v[88:91], v[132:135], v[180:183], v[88:91]
	v_mfma_f32_16x16x32_f16 v[76:79], v[116:119], v[188:191], v[76:79]
	v_mfma_f32_16x16x32_f16 v[72:75], v[132:135], v[188:191], v[72:75]
	s_setprio 0
	s_setprio 1
	v_mfma_f32_16x16x32_f16 v[124:127], v[144:147], v[160:163], v[124:127]
	v_mfma_f32_16x16x32_f16 v[120:123], v[152:155], v[160:163], v[120:123]
	v_mfma_f32_16x16x32_f16 v[100:103], v[144:147], v[168:171], v[100:103]
	v_mfma_f32_16x16x32_f16 v[96:99], v[152:155], v[168:171], v[96:99]
	v_mfma_f32_16x16x32_f16 v[84:87], v[144:147], v[176:179], v[84:87]
	v_mfma_f32_16x16x32_f16 v[80:83], v[152:155], v[176:179], v[80:83]
	v_mfma_f32_16x16x32_f16 v[68:71], v[144:147], v[184:187], v[68:71]
	v_mfma_f32_16x16x32_f16 v[64:67], v[152:155], v[184:187], v[64:67]
	v_mfma_f32_16x16x32_f16 v[124:127], v[148:151], v[164:167], v[124:127]
	v_mfma_f32_16x16x32_f16 v[120:123], v[156:159], v[164:167], v[120:123]
	v_mfma_f32_16x16x32_f16 v[100:103], v[148:151], v[172:175], v[100:103]
	v_mfma_f32_16x16x32_f16 v[96:99], v[156:159], v[172:175], v[96:99]
	v_mfma_f32_16x16x32_f16 v[84:87], v[148:151], v[180:183], v[84:87]
	v_mfma_f32_16x16x32_f16 v[80:83], v[156:159], v[180:183], v[80:83]
	v_mfma_f32_16x16x32_f16 v[68:71], v[148:151], v[188:191], v[68:71]
	v_mfma_f32_16x16x32_f16 v[64:67], v[156:159], v[188:191], v[64:67]
	s_setprio 0
	s_barrier
	s_add_i32 s60, s55, s68
	v_lshl_add_u64 v[192:193], s[44:45], 0, v[198:199]
	s_mov_b32 m0, s60
	ds_read_b128 v[160:163], v237 offset:16384
	ds_read_b128 v[164:167], v237 offset:17408
	ds_read_b128 v[168:171], v237 offset:18432
	ds_read_b128 v[172:175], v237 offset:19456
	ds_read_b128 v[176:179], v237 offset:20480
	ds_read_b128 v[180:183], v237 offset:21504
	ds_read_b128 v[184:187], v237 offset:22528
	ds_read_b128 v[188:191], v237 offset:23552
	global_load_lds_dwordx4 v[192:193], off
	s_add_i32 m0, s60, 0x2000
	s_add_u32 s60, s44, 0x40000
	v_lshl_add_u64 v[194:195], s[44:45], 0, v[202:203]
	s_addc_u32 s61, s45, 0
	s_add_i32 s62, s56, s68
	global_load_lds_dwordx4 v[194:195], off
	v_lshl_add_u64 v[212:213], s[60:61], 0, v[198:199]
	s_mov_b32 m0, s62
	v_lshl_add_u64 v[214:215], s[46:47], 0, v[200:201]
	global_load_lds_dwordx4 v[212:213], off
	v_lshl_add_u64 v[212:213], s[60:61], 0, v[202:203]
	s_add_i32 m0, s62, 0x2000
	s_nop 0
	global_load_lds_dwordx4 v[212:213], off
	v_lshl_add_u64 v[212:213], s[46:47], 0, v[196:197]
	s_mov_b32 m0, s74
	s_nop 0
	global_load_lds_dwordx4 v[212:213], off
	s_mov_b32 m0, s66
	s_nop 0
	global_load_lds_dwordx4 v[214:215], off
	s_waitcnt vmcnt(8)
	s_cmp_lt_u32 s3, 4
	s_cbranch_scc1 .Lgls_109
	s_waitcnt lgkmcnt(0)
; #define PG8_STAGE(bufoff, gbase, voff) do { _Pragma("unroll") for (int _i = 0; _i < 2; ++_i) \
;         __builtin_amdgcn_global_load_lds((const unsigned*)((const char*)(gbase) + (voff)[_i]), (PG8_LAS unsigned*)(lds + (bufoff) + ldsw + _i * 8192), 16, 0, 0); } while (0)
; #define PG8_LDA(dst, b, h) do { _Pragma("unroll") for (int m = 0; m < 4; ++m) _Pragma("unroll") for (int k = 0; k < 2; ++k) dst[m][k] = *(const PG8_LAS bf16x8*)(lds + PG8_SA(b, h) + aoff + m * 2048 + k * 1024); } while (0)
; #define PG8_LDB(dst, b, h) do { _Pragma("unroll") for (int n = 0; n < 2; ++n) _Pragma("unroll") for (int k = 0; k < 2; ++k) dst[n][k] = *(const PG8_LAS bf16x8*)(lds + PG8_SB(b, h) + boff + n * 2048 + k * 1024); } while (0)
; #define PG8_MMA(ai, bj, At, Bt) do { __builtin_amdgcn_s_setprio(1); _Pragma("unroll") for (int m = 0; m < 4; ++m) _Pragma("unroll") for (int n = 0; n < 2; ++n) _Pragma("unroll") for (int k = 0; k < 2; ++k) \
;         acc[ai][bj][m][n] = mma16<F16>(Bt[n][k], At[m][k], acc[ai][bj][m][n]); __builtin_amdgcn_s_setprio(0); } while (0)
; #define PG8_WAIT_V(n) asm volatile("s_waitcnt vmcnt(" #n ")" ::: "memory")
; #define PG8_WAIT_L(n) asm volatile("s_waitcnt lgkmcnt(" #n ")" ::: "memory")
; #define PG8_BAR __builtin_amdgcn_s_barrier()
; #define PG8_SCHED __builtin_amdgcn_sched_barrier(0)
; template <class Epi, class Sched, bool ALIGN_EPI = false, bool SP2 = false, bool F16 = false>
; __device__ __forceinline__ void gemm_phase(PG8_LAS unsigned char* lds, const Gemm g, const Sched& S, const Epi& E, const int wid_in) {
;     ...
;             PG8_WAIT_V(8); PG8_WAIT_L(0); PG8_BAR; PG8_MMA(1, 0, At, B0); PG8_MMA(1, 1, At, B1); PG8_BAR; PG8_SCHED;
;             PG8_LDB(B0, 1, 0); PG8_LDB(B1, 1, 1); PG8_SCHED; PG8_LDA(At, 1, 0); PG8_STAGE(PG8_SA(0, 1), a2 + hstep, voffA);
;             PG8_WAIT_V(8); PG8_WAIT_L(0); PG8_BAR; PG8_MMA(0, 0, At, B0); PG8_MMA(0, 1, At, B1); PG8_BAR; PG8_SCHED;
.Lgls_109:
	s_barrier
	s_setprio 1
	s_waitcnt lgkmcnt(0)
	v_mfma_f32_16x16x32_f16 v[60:63], v[112:115], v[160:163], v[60:63]
	v_mfma_f32_16x16x32_f16 v[56:59], v[128:131], v[160:163], v[56:59]
	v_mfma_f32_16x16x32_f16 v[44:47], v[112:115], v[168:171], v[44:47]
	v_mfma_f32_16x16x32_f16 v[40:43], v[128:131], v[168:171], v[40:43]
	v_mfma_f32_16x16x32_f16 v[28:31], v[112:115], v[176:179], v[28:31]
	v_mfma_f32_16x16x32_f16 v[24:27], v[128:131], v[176:179], v[24:27]
	v_mfma_f32_16x16x32_f16 v[12:15], v[112:115], v[184:187], v[12:15]
	v_mfma_f32_16x16x32_f16 v[8:11], v[128:131], v[184:187], v[8:11]
	v_mfma_f32_16x16x32_f16 v[60:63], v[116:119], v[164:167], v[60:63]
	v_mfma_f32_16x16x32_f16 v[56:59], v[132:135], v[164:167], v[56:59]
	v_mfma_f32_16x16x32_f16 v[44:47], v[116:119], v[172:175], v[44:47]
	v_mfma_f32_16x16x32_f16 v[40:43], v[132:135], v[172:175], v[40:43]
	v_mfma_f32_16x16x32_f16 v[28:31], v[116:119], v[180:183], v[28:31]
	v_mfma_f32_16x16x32_f16 v[24:27], v[132:135], v[180:183], v[24:27]
	v_mfma_f32_16x16x32_f16 v[12:15], v[116:119], v[188:191], v[12:15]
	v_mfma_f32_16x16x32_f16 v[8:11], v[132:135], v[188:191], v[8:11]
	s_setprio 0
	s_setprio 1
	v_mfma_f32_16x16x32_f16 v[52:55], v[144:147], v[160:163], v[52:55]
	v_mfma_f32_16x16x32_f16 v[48:51], v[152:155], v[160:163], v[48:51]
	v_mfma_f32_16x16x32_f16 v[36:39], v[144:147], v[168:171], v[36:39]
	v_mfma_f32_16x16x32_f16 v[32:35], v[152:155], v[168:171], v[32:35]
	v_mfma_f32_16x16x32_f16 v[20:23], v[144:147], v[176:179], v[20:23]
	v_mfma_f32_16x16x32_f16 v[16:19], v[152:155], v[176:179], v[16:19]
	v_mfma_f32_16x16x32_f16 v[4:7], v[144:147], v[184:187], v[4:7]
	v_mfma_f32_16x16x32_f16 v[0:3], v[152:155], v[184:187], v[0:3]
	v_mfma_f32_16x16x32_f16 v[52:55], v[148:151], v[164:167], v[52:55]
	v_mfma_f32_16x16x32_f16 v[48:51], v[156:159], v[164:167], v[48:51]
	v_mfma_f32_16x16x32_f16 v[36:39], v[148:151], v[172:175], v[36:39]
	v_mfma_f32_16x16x32_f16 v[32:35], v[156:159], v[172:175], v[32:35]
	v_mfma_f32_16x16x32_f16 v[20:23], v[148:151], v[180:183], v[20:23]
	v_mfma_f32_16x16x32_f16 v[16:19], v[156:159], v[180:183], v[16:19]
	v_mfma_f32_16x16x32_f16 v[4:7], v[148:151], v[188:191], v[4:7]
	v_mfma_f32_16x16x32_f16 v[0:3], v[156:159], v[188:191], v[0:3]
	s_setprio 0
	s_barrier
	s_add_i32 s60, 0, 0x18000
	s_add_i32 s61, 0, 0x1c000
	v_add_u32_e32 v132, s60, v234
	v_add_u32_e32 v156, s61, v234
	ds_read_b128 v[112:115], v132
	ds_read_b128 v[116:119], v132 offset:1024
	ds_read_b128 v[128:131], v132 offset:2048
	ds_read_b128 v[132:135], v132 offset:3072
	ds_read_b128 v[144:147], v156
	ds_read_b128 v[148:151], v156 offset:1024
	ds_read_b128 v[152:155], v156 offset:2048
	ds_read_b128 v[156:159], v156 offset:3072
	s_add_u32 s46, s46, 0x40000
	s_addc_u32 s47, s47, 0
	s_mov_b32 m0, s90
	v_lshl_add_u64 v[216:217], s[46:47], 0, v[196:197]
	ds_read_b128 v[160:163], v237 offset:32768
	ds_read_b128 v[164:167], v237 offset:33792
	ds_read_b128 v[168:171], v237 offset:34816
	ds_read_b128 v[172:175], v237 offset:35840
	ds_read_b128 v[176:179], v237 offset:36864
	ds_read_b128 v[180:183], v237 offset:37888
	ds_read_b128 v[184:187], v237 offset:38912
	ds_read_b128 v[188:191], v237 offset:39936
	global_load_lds_dwordx4 v[216:217], off
	v_lshl_add_u64 v[216:217], s[46:47], 0, v[200:201]
	s_mov_b32 m0, s51
	s_nop 0
	global_load_lds_dwordx4 v[216:217], off
	s_waitcnt vmcnt(8)
	s_cmp_lt_u32 s3, 4
	s_cbranch_scc1 .Lgls_110
	s_waitcnt lgkmcnt(0)
; #define PG8_STAGE(bufoff, gbase, voff) do { _Pragma("unroll") for (int _i = 0; _i < 2; ++_i) \
;         __builtin_amdgcn_global_load_lds((const unsigned*)((const char*)(gbase) + (voff)[_i]), (PG8_LAS unsigned*)(lds + (bufoff) + ldsw + _i * 8192), 16, 0, 0); } while (0)
; #define PG8_LDA(dst, b, h) do { _Pragma("unroll") for (int m = 0; m < 4; ++m) _Pragma("unroll") for (int k = 0; k < 2; ++k) dst[m][k] = *(const PG8_LAS bf16x8*)(lds + PG8_SA(b, h) + aoff + m * 2048 + k * 1024); } while (0)
; #define PG8_MMA(ai, bj, At, Bt) do { __builtin_amdgcn_s_setprio(1); _Pragma("unroll") for (int m = 0; m < 4; ++m) _Pragma("unroll") for (int n = 0; n < 2; ++n) _Pragma("unroll") for (int k = 0; k < 2; ++k) \
;         acc[ai][bj][m][n] = mma16<F16>(Bt[n][k], At[m][k], acc[ai][bj][m][n]); __builtin_amdgcn_s_setprio(0); } while (0)
; #define PG8_WAIT_V(n) asm volatile("s_waitcnt vmcnt(" #n ")" ::: "memory")
; #define PG8_WAIT_L(n) asm volatile("s_waitcnt lgkmcnt(" #n ")" ::: "memory")
; #define PG8_BAR __builtin_amdgcn_s_barrier()
; #define PG8_SCHED __builtin_amdgcn_sched_barrier(0)
; template <class Epi, class Sched, bool ALIGN_EPI = false, bool SP2 = false, bool F16 = false>
; __device__ __forceinline__ void gemm_phase(PG8_LAS unsigned char* lds, const Gemm g, const Sched& S, const Epi& E, const int wid_in) {
;     ...
;             PG8_WAIT_V(8); PG8_WAIT_L(0); PG8_BAR; PG8_MMA(0, 0, At, B0); PG8_MMA(0, 1, At, B1); PG8_BAR; PG8_SCHED;
;             PG8_LDA(At, 1, 1); PG8_STAGE(PG8_SB(1, 0), b3, voffB); PG8_STAGE(PG8_SB(1, 1), b3 + hstep, voffB); PG8_STAGE(PG8_SA(1, 0), a3, voffA);
;             PG8_WAIT_V(8); PG8_WAIT_L(0); PG8_BAR; PG8_MMA(1, 0, At, B0); PG8_MMA(1, 1, At, B1); PG8_BAR; PG8_SCHED;
;     ...
;         if constexpr (ALIGN_EPI) { if (wr == 0) PG8_BAR; }
.Lgls_110:
	s_barrier
	s_setprio 1
	s_waitcnt lgkmcnt(0)
	v_mfma_f32_16x16x32_f16 v[140:143], v[112:115], v[160:163], v[140:143]
	v_mfma_f32_16x16x32_f16 v[136:139], v[128:131], v[160:163], v[136:139]
	v_mfma_f32_16x16x32_f16 v[108:111], v[112:115], v[168:171], v[108:111]
	v_mfma_f32_16x16x32_f16 v[104:107], v[128:131], v[168:171], v[104:107]
	v_mfma_f32_16x16x32_f16 v[92:95], v[112:115], v[176:179], v[92:95]
	v_mfma_f32_16x16x32_f16 v[88:91], v[128:131], v[176:179], v[88:91]
	v_mfma_f32_16x16x32_f16 v[76:79], v[112:115], v[184:187], v[76:79]
	v_mfma_f32_16x16x32_f16 v[72:75], v[128:131], v[184:187], v[72:75]
	v_mfma_f32_16x16x32_f16 v[140:143], v[116:119], v[164:167], v[140:143]
	v_mfma_f32_16x16x32_f16 v[136:139], v[132:135], v[164:167], v[136:139]
	v_mfma_f32_16x16x32_f16 v[108:111], v[116:119], v[172:175], v[108:111]
	v_mfma_f32_16x16x32_f16 v[104:107], v[132:135], v[172:175], v[104:107]
	v_mfma_f32_16x16x32_f16 v[92:95], v[116:119], v[180:183], v[92:95]
	v_mfma_f32_16x16x32_f16 v[88:91], v[132:135], v[180:183], v[88:91]
	v_mfma_f32_16x16x32_f16 v[76:79], v[116:119], v[188:191], v[76:79]
	v_mfma_f32_16x16x32_f16 v[72:75], v[132:135], v[188:191], v[72:75]
	s_setprio 0
	s_setprio 1
	v_mfma_f32_16x16x32_f16 v[124:127], v[144:147], v[160:163], v[124:127]
	v_mfma_f32_16x16x32_f16 v[120:123], v[152:155], v[160:163], v[120:123]
	v_mfma_f32_16x16x32_f16 v[100:103], v[144:147], v[168:171], v[100:103]
	v_mfma_f32_16x16x32_f16 v[96:99], v[152:155], v[168:171], v[96:99]
	v_mfma_f32_16x16x32_f16 v[84:87], v[144:147], v[176:179], v[84:87]
	v_mfma_f32_16x16x32_f16 v[80:83], v[152:155], v[176:179], v[80:83]
	v_mfma_f32_16x16x32_f16 v[68:71], v[144:147], v[184:187], v[68:71]
	v_mfma_f32_16x16x32_f16 v[64:67], v[152:155], v[184:187], v[64:67]
	v_mfma_f32_16x16x32_f16 v[124:127], v[148:151], v[164:167], v[124:127]
	v_mfma_f32_16x16x32_f16 v[120:123], v[156:159], v[164:167], v[120:123]
	v_mfma_f32_16x16x32_f16 v[100:103], v[148:151], v[172:175], v[100:103]
	v_mfma_f32_16x16x32_f16 v[96:99], v[156:159], v[172:175], v[96:99]
	v_mfma_f32_16x16x32_f16 v[84:87], v[148:151], v[180:183], v[84:87]
	v_mfma_f32_16x16x32_f16 v[80:83], v[156:159], v[180:183], v[80:83]
	v_mfma_f32_16x16x32_f16 v[68:71], v[148:151], v[188:191], v[68:71]
	v_mfma_f32_16x16x32_f16 v[64:67], v[156:159], v[188:191], v[64:67]
	s_setprio 0
	s_barrier
	s_add_i32 s46, s60, s68
	v_lshl_add_u64 v[192:193], v[192:193], 0, s[26:27]
	s_mov_b32 m0, s46
	ds_read_b128 v[160:163], v237 offset:49152
	ds_read_b128 v[164:167], v237 offset:50176
	ds_read_b128 v[168:171], v237 offset:51200
	ds_read_b128 v[172:175], v237 offset:52224
	ds_read_b128 v[176:179], v237 offset:53248
	ds_read_b128 v[180:183], v237 offset:54272
	ds_read_b128 v[184:187], v237 offset:55296
	ds_read_b128 v[188:191], v237 offset:56320
	global_load_lds_dwordx4 v[192:193], off
	s_add_i32 m0, s46, 0x2000
	s_add_u32 s44, s44, 0x40080
	v_lshl_add_u64 v[192:193], v[194:195], 0, s[26:27]
	s_addc_u32 s45, s45, 0
	s_add_i32 s46, s61, s68
	global_load_lds_dwordx4 v[192:193], off
	v_lshl_add_u64 v[192:193], s[44:45], 0, v[198:199]
	s_mov_b32 m0, s46
	s_nop 0
	global_load_lds_dwordx4 v[192:193], off
	v_lshl_add_u64 v[192:193], s[44:45], 0, v[202:203]
	s_add_i32 m0, s46, 0x2000
	s_nop 0
	global_load_lds_dwordx4 v[192:193], off
	v_lshl_add_u64 v[192:193], v[212:213], 0, s[26:27]
	s_mov_b32 m0, s75
	s_nop 0
	global_load_lds_dwordx4 v[192:193], off
	v_lshl_add_u64 v[192:193], v[214:215], 0, s[26:27]
	s_mov_b32 m0, s67
	s_nop 0
	global_load_lds_dwordx4 v[192:193], off
	s_waitcnt vmcnt(8)
	s_cmp_lt_u32 s3, 4
	s_cbranch_scc1 .Lgls_111
	s_waitcnt lgkmcnt(0)
.Lgls_111:
	s_barrier
	s_setprio 1
	s_waitcnt lgkmcnt(0)
	v_mfma_f32_16x16x32_f16 v[60:63], v[112:115], v[160:163], v[60:63]
	v_mfma_f32_16x16x32_f16 v[56:59], v[128:131], v[160:163], v[56:59]
	v_mfma_f32_16x16x32_f16 v[44:47], v[112:115], v[168:171], v[44:47]
	v_mfma_f32_16x16x32_f16 v[40:43], v[128:131], v[168:171], v[40:43]
	v_mfma_f32_16x16x32_f16 v[28:31], v[112:115], v[176:179], v[28:31]
	v_mfma_f32_16x16x32_f16 v[24:27], v[128:131], v[176:179], v[24:27]
	v_mfma_f32_16x16x32_f16 v[12:15], v[112:115], v[184:187], v[12:15]
	v_mfma_f32_16x16x32_f16 v[8:11], v[128:131], v[184:187], v[8:11]
	v_mfma_f32_16x16x32_f16 v[60:63], v[116:119], v[164:167], v[60:63]
	v_mfma_f32_16x16x32_f16 v[56:59], v[132:135], v[164:167], v[56:59]
	v_mfma_f32_16x16x32_f16 v[44:47], v[116:119], v[172:175], v[44:47]
	v_mfma_f32_16x16x32_f16 v[40:43], v[132:135], v[172:175], v[40:43]
	v_mfma_f32_16x16x32_f16 v[28:31], v[116:119], v[180:183], v[28:31]
	v_mfma_f32_16x16x32_f16 v[24:27], v[132:135], v[180:183], v[24:27]
	v_mfma_f32_16x16x32_f16 v[12:15], v[116:119], v[188:191], v[12:15]
	v_mfma_f32_16x16x32_f16 v[8:11], v[132:135], v[188:191], v[8:11]
	s_setprio 0
	s_setprio 1
	v_mfma_f32_16x16x32_f16 v[52:55], v[144:147], v[160:163], v[52:55]
	v_mfma_f32_16x16x32_f16 v[48:51], v[152:155], v[160:163], v[48:51]
	v_mfma_f32_16x16x32_f16 v[36:39], v[144:147], v[168:171], v[36:39]
	v_mfma_f32_16x16x32_f16 v[32:35], v[152:155], v[168:171], v[32:35]
	v_mfma_f32_16x16x32_f16 v[20:23], v[144:147], v[176:179], v[20:23]
	v_mfma_f32_16x16x32_f16 v[16:19], v[152:155], v[176:179], v[16:19]
	v_mfma_f32_16x16x32_f16 v[4:7], v[144:147], v[184:187], v[4:7]
	v_mfma_f32_16x16x32_f16 v[0:3], v[152:155], v[184:187], v[0:3]
	v_mfma_f32_16x16x32_f16 v[52:55], v[148:151], v[164:167], v[52:55]
	v_mfma_f32_16x16x32_f16 v[48:51], v[156:159], v[164:167], v[48:51]
	v_mfma_f32_16x16x32_f16 v[36:39], v[148:151], v[172:175], v[36:39]
	v_mfma_f32_16x16x32_f16 v[32:35], v[156:159], v[172:175], v[32:35]
	v_mfma_f32_16x16x32_f16 v[20:23], v[148:151], v[180:183], v[20:23]
	v_mfma_f32_16x16x32_f16 v[16:19], v[156:159], v[180:183], v[16:19]
	v_mfma_f32_16x16x32_f16 v[4:7], v[148:151], v[188:191], v[4:7]
	v_mfma_f32_16x16x32_f16 v[0:3], v[156:159], v[188:191], v[0:3]
	s_setprio 0
	s_barrier
	s_add_i32 s59, s59, 2
	s_add_u32 s42, s42, 0x100
	s_addc_u32 s43, s43, 0
	s_add_u32 s41, s41, 0x100
	s_addc_u32 s58, s58, 0
	s_cmp_gt_u32 s59, 13
	s_cbranch_scc0 .LBB0_2793
	s_and_b64 vcc, exec, s[16:17]
	s_cbranch_vccz .LBB0_2796
	s_barrier
